# merge GEMM K-loop phases 2+3 and 6+7 into 32-MFMA segments (12 instead of 16 barriers per K-iteration), on top of static-prio v16
# baseline (speedup 1.0000x reference)
; #define PG8_STAGE(bufoff, gbase, voff) do { _Pragma("unroll") for (int _i = 0; _i < 2; ++_i) \
;         __builtin_amdgcn_global_load_lds((const unsigned*)((const char*)(gbase) + (voff)[_i]), (LAS unsigned*)(lds + (bufoff) + ldsw + _i * 8192), 16, 0, 0); } while (0)
; #define PG8_LDA(dst, b, h) do { _Pragma("unroll") for (int m = 0; m < 4; ++m) _Pragma("unroll") for (int k = 0; k < 2; ++k) dst[m][k] = *(const LAS bf16x8*)(lds + PG8_SA(b, h) + aoff + m * 2048 + k * 1024); } while (0)
; #define PG8_LDB(dst, b, h) do { _Pragma("unroll") for (int n = 0; n < 2; ++n) _Pragma("unroll") for (int k = 0; k < 2; ++k) dst[n][k] = *(const LAS bf16x8*)(lds + PG8_SB(b, h) + boff + n * 2048 + k * 1024); } while (0)
; #define PG8_WAIT_V(n) asm volatile("s_waitcnt vmcnt(" #n ")" ::: "memory")
; #define PG8_WAIT_L(n) asm volatile("s_waitcnt lgkmcnt(" #n ")" ::: "memory")
; #define PG8_BAR __builtin_amdgcn_s_barrier()
; #define PG8_SCHED __builtin_amdgcn_sched_barrier(0)
; template <class Epi>
; __device__ __forceinline__ void gemm_phase(LAS unsigned char* lds, const Gemm g, const StaticOrder& S, const Epi& E) {
;     ...
;             PG8_LDB(B0, 0, 0); PG8_SCHED; PG8_LDA(At, 0, 0); PG8_STAGE(PG8_SA(1, 1), a1 + hstep, voffA);
;             PG8_WAIT_L(8); PG8_BAR; PG8_WAIT_L(0); PG8_MMA(0, 0, At, B0); PG8_BAR; PG8_SCHED;
;             PG8_LDB(B1, 0, 1); PG8_STAGE(PG8_SB(0, 0), b2, voffB0);
;             PG8_BAR; PG8_WAIT_L(0); PG8_MMA(0, 1, At, B1); PG8_BAR;
;             PG8_LDA(At, 0, 1); PG8_STAGE(PG8_SA(0, 0), a2, voffA);
;             PG8_BAR; PG8_WAIT_L(0); PG8_MMA(1, 0, At, B0); PG8_BAR; PG8_SCHED;
;             PG8_STAGE(PG8_SB(0, 1), b2, voffB1);
;             PG8_WAIT_V(6); PG8_BAR; PG8_MMA(1, 1, At, B1); PG8_BAR;
;             PG8_LDB(B0, 1, 0); PG8_SCHED; PG8_LDA(At, 1, 0); PG8_STAGE(PG8_SA(0, 1), a2 + hstep, voffA);
;             PG8_WAIT_L(8); PG8_BAR; PG8_WAIT_L(0); PG8_MMA(0, 0, At, B0); PG8_BAR; PG8_SCHED;
;             PG8_LDB(B1, 1, 1); PG8_STAGE(PG8_SB(1, 0), b3, voffB0);
;             PG8_BAR; PG8_WAIT_L(0); PG8_MMA(0, 1, At, B1); PG8_BAR;
;             PG8_LDA(At, 1, 1); PG8_STAGE(PG8_SA(1, 0), a3, voffA);
;             PG8_BAR; PG8_WAIT_L(0); PG8_MMA(1, 0, At, B0); PG8_BAR; PG8_SCHED;
;             PG8_STAGE(PG8_SB(1, 1), b3, voffB1);
;             PG8_WAIT_V(6); PG8_BAR; PG8_MMA(1, 1, At, B1); PG8_BAR;
.LBB0_107:
	ds_read_b128 v[162:165], v158
	ds_read_b128 v[166:169], v158 offset:1024
	ds_read_b128 v[170:173], v158 offset:2048
	ds_read_b128 v[174:177], v158 offset:3072
	s_add_u32 s33, s34, 0xfff80080
	s_addc_u32 s36, s35, -1
	s_cmp_eq_u32 s63, 28
	s_cselect_b32 s37, s13, s36
	s_cselect_b32 s36, s59, s33
	s_cselect_b32 s39, s11, s62
	s_cselect_b32 s38, s60, s61
	v_lshl_add_u64 v[212:213], s[34:35], 0, v[140:141]
	s_add_i32 m0, s31, 0xc000
	ds_read_b128 v[178:181], v159
	ds_read_b128 v[182:185], v159 offset:1024
	ds_read_b128 v[186:189], v159 offset:2048
	ds_read_b128 v[190:193], v159 offset:3072
	ds_read_b128 v[194:197], v159 offset:4096
	ds_read_b128 v[198:201], v159 offset:5120
	ds_read_b128 v[204:207], v159 offset:6144
	ds_read_b128 v[208:211], v159 offset:7168
	global_load_lds_dwordx4 v[212:213], off
	v_lshl_add_u64 v[212:213], s[34:35], 0, v[142:143]
	s_add_i32 m0, s31, 0xe000
	s_nop 0
	global_load_lds_dwordx4 v[212:213], off
	s_waitcnt lgkmcnt(8)
	s_barrier
	s_waitcnt lgkmcnt(0)
	v_mfma_f32_16x16x32_bf16 v[124:127], v[162:165], v[178:181], v[124:127]
	v_mfma_f32_16x16x32_bf16 v[120:123], v[170:173], v[178:181], v[120:123]
	v_mfma_f32_16x16x32_bf16 v[108:111], v[162:165], v[186:189], v[108:111]
	v_mfma_f32_16x16x32_bf16 v[104:107], v[170:173], v[186:189], v[104:107]
	v_mfma_f32_16x16x32_bf16 v[92:95], v[162:165], v[194:197], v[92:95]
	v_mfma_f32_16x16x32_bf16 v[88:91], v[170:173], v[194:197], v[88:91]
	v_mfma_f32_16x16x32_bf16 v[76:79], v[162:165], v[204:207], v[76:79]
	v_mfma_f32_16x16x32_bf16 v[72:75], v[170:173], v[204:207], v[72:75]
	v_mfma_f32_16x16x32_bf16 v[124:127], v[166:169], v[182:185], v[124:127]
	v_mfma_f32_16x16x32_bf16 v[120:123], v[174:177], v[182:185], v[120:123]
	v_mfma_f32_16x16x32_bf16 v[108:111], v[166:169], v[190:193], v[108:111]
	v_mfma_f32_16x16x32_bf16 v[104:107], v[174:177], v[190:193], v[104:107]
	v_mfma_f32_16x16x32_bf16 v[92:95], v[166:169], v[198:201], v[92:95]
	v_mfma_f32_16x16x32_bf16 v[88:91], v[174:177], v[198:201], v[88:91]
	v_mfma_f32_16x16x32_bf16 v[76:79], v[166:169], v[208:211], v[76:79]
	v_mfma_f32_16x16x32_bf16 v[72:75], v[174:177], v[208:211], v[72:75]
	s_barrier
	s_add_i32 s33, s56, s44
	v_lshl_add_u64 v[228:229], s[38:39], 0, v[134:135]
	s_mov_b32 m0, s33
	ds_read_b128 v[212:215], v160
	ds_read_b128 v[216:219], v160 offset:1024
	ds_read_b128 v[220:223], v160 offset:2048
	ds_read_b128 v[224:227], v160 offset:3072
	global_load_lds_dwordx4 v[228:229], off
	v_lshl_add_u64 v[230:231], s[38:39], 0, v[128:129]
	s_add_i32 m0, s33, 0x2000
	s_nop 0
	global_load_lds_dwordx4 v[230:231], off
	s_waitcnt lgkmcnt(0)
	s_barrier
	s_waitcnt lgkmcnt(0)
	v_mfma_f32_16x16x32_bf16 v[116:119], v[212:215], v[178:181], v[116:119]
	v_mfma_f32_16x16x32_bf16 v[112:115], v[220:223], v[178:181], v[112:115]
	v_mfma_f32_16x16x32_bf16 v[100:103], v[212:215], v[186:189], v[100:103]
	v_mfma_f32_16x16x32_bf16 v[96:99], v[220:223], v[186:189], v[96:99]
	v_mfma_f32_16x16x32_bf16 v[84:87], v[212:215], v[194:197], v[84:87]
	v_mfma_f32_16x16x32_bf16 v[80:83], v[220:223], v[194:197], v[80:83]
	v_mfma_f32_16x16x32_bf16 v[68:71], v[212:215], v[204:207], v[68:71]
	v_mfma_f32_16x16x32_bf16 v[64:67], v[220:223], v[204:207], v[64:67]
	v_mfma_f32_16x16x32_bf16 v[116:119], v[216:219], v[182:185], v[116:119]
	v_mfma_f32_16x16x32_bf16 v[112:115], v[224:227], v[182:185], v[112:115]
	v_mfma_f32_16x16x32_bf16 v[100:103], v[216:219], v[190:193], v[100:103]
	v_mfma_f32_16x16x32_bf16 v[96:99], v[224:227], v[190:193], v[96:99]
	v_mfma_f32_16x16x32_bf16 v[84:87], v[216:219], v[198:201], v[84:87]
	v_mfma_f32_16x16x32_bf16 v[80:83], v[224:227], v[198:201], v[80:83]
	v_mfma_f32_16x16x32_bf16 v[68:71], v[216:219], v[208:211], v[68:71]
	v_mfma_f32_16x16x32_bf16 v[64:67], v[224:227], v[208:211], v[64:67]
	s_mov_b32 m0, s31
	v_lshl_add_u64 v[232:233], s[36:37], 0, v[138:139]
	s_barrier
	ds_read_b128 v[178:181], v159 offset:16384
	ds_read_b128 v[182:185], v159 offset:17408
	ds_read_b128 v[186:189], v159 offset:18432
	ds_read_b128 v[190:193], v159 offset:19456
	ds_read_b128 v[194:197], v159 offset:20480
	ds_read_b128 v[198:201], v159 offset:21504
	ds_read_b128 v[204:207], v159 offset:22528
	ds_read_b128 v[208:211], v159 offset:23552
	global_load_lds_dwordx4 v[232:233], off
	v_lshl_add_u64 v[234:235], s[36:37], 0, v[132:133]
	s_mov_b32 m0, s46
	s_nop 0
	global_load_lds_dwordx4 v[234:235], off
	s_add_i32 s33, s57, s44
	v_lshl_add_u64 v[236:237], s[38:39], 0, v[136:137]
	s_mov_b32 m0, s33
	v_lshl_add_u64 v[238:239], s[38:39], 0, v[130:131]
	global_load_lds_dwordx4 v[236:237], off
	s_add_i32 m0, s33, 0x2000
	s_nop 0
	global_load_lds_dwordx4 v[238:239], off
	s_waitcnt vmcnt(6)
	s_barrier
; #define PG8_STAGE(bufoff, gbase, voff) do { _Pragma("unroll") for (int _i = 0; _i < 2; ++_i) \
;         __builtin_amdgcn_global_load_lds((const unsigned*)((const char*)(gbase) + (voff)[_i]), (LAS unsigned*)(lds + (bufoff) + ldsw + _i * 8192), 16, 0, 0); } while (0)
; #define PG8_LDA(dst, b, h) do { _Pragma("unroll") for (int m = 0; m < 4; ++m) _Pragma("unroll") for (int k = 0; k < 2; ++k) dst[m][k] = *(const LAS bf16x8*)(lds + PG8_SA(b, h) + aoff + m * 2048 + k * 1024); } while (0)
; #define PG8_LDB(dst, b, h) do { _Pragma("unroll") for (int n = 0; n < 2; ++n) _Pragma("unroll") for (int k = 0; k < 2; ++k) dst[n][k] = *(const LAS bf16x8*)(lds + PG8_SB(b, h) + boff + n * 2048 + k * 1024); } while (0)
; #define PG8_WAIT_V(n) asm volatile("s_waitcnt vmcnt(" #n ")" ::: "memory")
; #define PG8_WAIT_L(n) asm volatile("s_waitcnt lgkmcnt(" #n ")" ::: "memory")
; #define PG8_BAR __builtin_amdgcn_s_barrier()
; #define PG8_SCHED __builtin_amdgcn_sched_barrier(0)
; template <class Epi>
; __device__ __forceinline__ void gemm_phase(LAS unsigned char* lds, const Gemm g, const StaticOrder& S, const Epi& E) {
;     ...
;             PG8_LDB(B0, 0, 0); PG8_SCHED; PG8_LDA(At, 0, 0); PG8_STAGE(PG8_SA(1, 1), a1 + hstep, voffA);
;             PG8_WAIT_L(8); PG8_BAR; PG8_WAIT_L(0); PG8_MMA(0, 0, At, B0); PG8_BAR; PG8_SCHED;
;             PG8_LDB(B1, 0, 1); PG8_STAGE(PG8_SB(0, 0), b2, voffB0);
;             PG8_BAR; PG8_WAIT_L(0); PG8_MMA(0, 1, At, B1); PG8_BAR;
;             PG8_LDA(At, 0, 1); PG8_STAGE(PG8_SA(0, 0), a2, voffA);
;             PG8_BAR; PG8_WAIT_L(0); PG8_MMA(1, 0, At, B0); PG8_BAR; PG8_SCHED;
;             PG8_STAGE(PG8_SB(0, 1), b2, voffB1);
;             PG8_WAIT_V(6); PG8_BAR; PG8_MMA(1, 1, At, B1); PG8_BAR;
;             PG8_LDB(B0, 1, 0); PG8_SCHED; PG8_LDA(At, 1, 0); PG8_STAGE(PG8_SA(0, 1), a2 + hstep, voffA);
;             PG8_WAIT_L(8); PG8_BAR; PG8_WAIT_L(0); PG8_MMA(0, 0, At, B0); PG8_BAR; PG8_SCHED;
;             PG8_LDB(B1, 1, 1); PG8_STAGE(PG8_SB(1, 0), b3, voffB0);
;             PG8_BAR; PG8_WAIT_L(0); PG8_MMA(0, 1, At, B1); PG8_BAR;
;             PG8_LDA(At, 1, 1); PG8_STAGE(PG8_SA(1, 0), a3, voffA);
;             PG8_BAR; PG8_WAIT_L(0); PG8_MMA(1, 0, At, B0); PG8_BAR; PG8_SCHED;
;             PG8_STAGE(PG8_SB(1, 1), b3, voffB1);
;             PG8_WAIT_V(6); PG8_BAR; PG8_MMA(1, 1, At, B1); PG8_BAR;
	s_waitcnt lgkmcnt(0)
	v_mfma_f32_16x16x32_bf16 v[60:63], v[162:165], v[178:181], v[60:63]
	v_mfma_f32_16x16x32_bf16 v[56:59], v[170:173], v[178:181], v[56:59]
	v_mfma_f32_16x16x32_bf16 v[44:47], v[162:165], v[186:189], v[44:47]
	v_mfma_f32_16x16x32_bf16 v[40:43], v[170:173], v[186:189], v[40:43]
	v_mfma_f32_16x16x32_bf16 v[28:31], v[162:165], v[194:197], v[28:31]
	v_mfma_f32_16x16x32_bf16 v[24:27], v[170:173], v[194:197], v[24:27]
	v_mfma_f32_16x16x32_bf16 v[12:15], v[162:165], v[204:207], v[12:15]
	v_mfma_f32_16x16x32_bf16 v[8:11], v[170:173], v[204:207], v[8:11]
	v_mfma_f32_16x16x32_bf16 v[60:63], v[166:169], v[182:185], v[60:63]
	v_mfma_f32_16x16x32_bf16 v[56:59], v[174:177], v[182:185], v[56:59]
	v_mfma_f32_16x16x32_bf16 v[44:47], v[166:169], v[190:193], v[44:47]
	v_mfma_f32_16x16x32_bf16 v[40:43], v[174:177], v[190:193], v[40:43]
	v_mfma_f32_16x16x32_bf16 v[28:31], v[166:169], v[198:201], v[28:31]
	v_mfma_f32_16x16x32_bf16 v[24:27], v[174:177], v[198:201], v[24:27]
	v_mfma_f32_16x16x32_bf16 v[12:15], v[166:169], v[208:211], v[12:15]
	v_mfma_f32_16x16x32_bf16 v[8:11], v[174:177], v[208:211], v[8:11]
	v_mfma_f32_16x16x32_bf16 v[52:55], v[212:215], v[178:181], v[52:55]
	v_mfma_f32_16x16x32_bf16 v[48:51], v[220:223], v[178:181], v[48:51]
	v_mfma_f32_16x16x32_bf16 v[36:39], v[212:215], v[186:189], v[36:39]
	v_mfma_f32_16x16x32_bf16 v[32:35], v[220:223], v[186:189], v[32:35]
	v_mfma_f32_16x16x32_bf16 v[20:23], v[212:215], v[194:197], v[20:23]
	v_mfma_f32_16x16x32_bf16 v[16:19], v[220:223], v[194:197], v[16:19]
	v_mfma_f32_16x16x32_bf16 v[4:7], v[212:215], v[204:207], v[4:7]
	v_mfma_f32_16x16x32_bf16 v[0:3], v[220:223], v[204:207], v[0:3]
	v_mfma_f32_16x16x32_bf16 v[52:55], v[216:219], v[182:185], v[52:55]
	v_mfma_f32_16x16x32_bf16 v[48:51], v[224:227], v[182:185], v[48:51]
	v_mfma_f32_16x16x32_bf16 v[36:39], v[216:219], v[190:193], v[36:39]
	v_mfma_f32_16x16x32_bf16 v[32:35], v[224:227], v[190:193], v[32:35]
	v_mfma_f32_16x16x32_bf16 v[20:23], v[216:219], v[198:201], v[20:23]
	v_mfma_f32_16x16x32_bf16 v[16:19], v[224:227], v[198:201], v[16:19]
	v_mfma_f32_16x16x32_bf16 v[4:7], v[216:219], v[208:211], v[4:7]
	v_mfma_f32_16x16x32_bf16 v[0:3], v[224:227], v[208:211], v[0:3]
	s_add_i32 s33, 0, 0x18000
	v_add_u32_e32 v161, s33, v148
	s_barrier
	ds_read_b128 v[162:165], v161
	ds_read_b128 v[166:169], v161 offset:1024
	ds_read_b128 v[170:173], v161 offset:2048
	ds_read_b128 v[174:177], v161 offset:3072
	s_add_u32 s36, s36, 0x80000
	s_addc_u32 s37, s37, 0
	s_mov_b32 m0, s47
	v_lshl_add_u64 v[212:213], s[36:37], 0, v[138:139]
	ds_read_b128 v[178:181], v159 offset:32768
	ds_read_b128 v[182:185], v159 offset:33792
	ds_read_b128 v[186:189], v159 offset:34816
	ds_read_b128 v[190:193], v159 offset:35840
	ds_read_b128 v[194:197], v159 offset:36864
	ds_read_b128 v[198:201], v159 offset:37888
	ds_read_b128 v[204:207], v159 offset:38912
	ds_read_b128 v[208:211], v159 offset:39936
	global_load_lds_dwordx4 v[212:213], off
	v_lshl_add_u64 v[212:213], s[36:37], 0, v[132:133]
	s_mov_b32 m0, s48
	s_nop 0
	global_load_lds_dwordx4 v[212:213], off
	s_waitcnt lgkmcnt(8)
	s_barrier
	s_waitcnt lgkmcnt(0)
	v_mfma_f32_16x16x32_bf16 v[124:127], v[162:165], v[178:181], v[124:127]
	v_mfma_f32_16x16x32_bf16 v[120:123], v[170:173], v[178:181], v[120:123]
	v_mfma_f32_16x16x32_bf16 v[108:111], v[162:165], v[186:189], v[108:111]
	v_mfma_f32_16x16x32_bf16 v[104:107], v[170:173], v[186:189], v[104:107]
	v_mfma_f32_16x16x32_bf16 v[92:95], v[162:165], v[194:197], v[92:95]
	v_mfma_f32_16x16x32_bf16 v[88:91], v[170:173], v[194:197], v[88:91]
	v_mfma_f32_16x16x32_bf16 v[76:79], v[162:165], v[204:207], v[76:79]
	v_mfma_f32_16x16x32_bf16 v[72:75], v[170:173], v[204:207], v[72:75]
	v_mfma_f32_16x16x32_bf16 v[124:127], v[166:169], v[182:185], v[124:127]
	v_mfma_f32_16x16x32_bf16 v[120:123], v[174:177], v[182:185], v[120:123]
	v_mfma_f32_16x16x32_bf16 v[108:111], v[166:169], v[190:193], v[108:111]
	v_mfma_f32_16x16x32_bf16 v[104:107], v[174:177], v[190:193], v[104:107]
	v_mfma_f32_16x16x32_bf16 v[92:95], v[166:169], v[198:201], v[92:95]
	v_mfma_f32_16x16x32_bf16 v[88:91], v[174:177], v[198:201], v[88:91]
	v_mfma_f32_16x16x32_bf16 v[76:79], v[166:169], v[208:211], v[76:79]
	v_mfma_f32_16x16x32_bf16 v[72:75], v[174:177], v[208:211], v[72:75]
	s_barrier
	s_add_i32 s36, 0, 0x1c000
	s_add_i32 s33, s33, s44
	v_add_u32_e32 v161, s36, v148
	v_lshl_add_u64 v[228:229], v[228:229], 0, s[8:9]
	s_mov_b32 m0, s33
	ds_read_b128 v[212:215], v161
	ds_read_b128 v[216:219], v161 offset:1024
	ds_read_b128 v[220:223], v161 offset:2048
	ds_read_b128 v[224:227], v161 offset:3072
	global_load_lds_dwordx4 v[228:229], off
	v_lshl_add_u64 v[228:229], v[230:231], 0, s[8:9]
	s_add_i32 m0, s33, 0x2000
	s_nop 0
	global_load_lds_dwordx4 v[228:229], off
	s_waitcnt lgkmcnt(0)
	s_barrier
	s_waitcnt lgkmcnt(0)
	v_mfma_f32_16x16x32_bf16 v[116:119], v[212:215], v[178:181], v[116:119]
	v_mfma_f32_16x16x32_bf16 v[112:115], v[220:223], v[178:181], v[112:115]
	v_mfma_f32_16x16x32_bf16 v[100:103], v[212:215], v[186:189], v[100:103]
	v_mfma_f32_16x16x32_bf16 v[96:99], v[220:223], v[186:189], v[96:99]
	v_mfma_f32_16x16x32_bf16 v[84:87], v[212:215], v[194:197], v[84:87]
	v_mfma_f32_16x16x32_bf16 v[80:83], v[220:223], v[194:197], v[80:83]
	v_mfma_f32_16x16x32_bf16 v[68:71], v[212:215], v[204:207], v[68:71]
	v_mfma_f32_16x16x32_bf16 v[64:67], v[220:223], v[204:207], v[64:67]
	v_mfma_f32_16x16x32_bf16 v[116:119], v[216:219], v[182:185], v[116:119]
	v_mfma_f32_16x16x32_bf16 v[112:115], v[224:227], v[182:185], v[112:115]
	v_mfma_f32_16x16x32_bf16 v[100:103], v[216:219], v[190:193], v[100:103]
	v_mfma_f32_16x16x32_bf16 v[96:99], v[224:227], v[190:193], v[96:99]
	v_mfma_f32_16x16x32_bf16 v[84:87], v[216:219], v[198:201], v[84:87]
	v_mfma_f32_16x16x32_bf16 v[80:83], v[224:227], v[198:201], v[80:83]
	v_mfma_f32_16x16x32_bf16 v[68:71], v[216:219], v[208:211], v[68:71]
	v_mfma_f32_16x16x32_bf16 v[64:67], v[224:227], v[208:211], v[64:67]
	s_mov_b32 m0, s51
	v_lshl_add_u64 v[228:229], v[232:233], 0, s[8:9]
	s_barrier
; __device__ __forceinline__ unsigned cvt_pk_bf16(float lo, float hi) { unsigned r; asm volatile("v_cvt_pk_bf16_f32 %0, %1, %2" : "=v"(r) : "v"(lo), "v"(hi)); return r; }
; #define PG8_STAGE(bufoff, gbase, voff) do { _Pragma("unroll") for (int _i = 0; _i < 2; ++_i) \
;         __builtin_amdgcn_global_load_lds((const unsigned*)((const char*)(gbase) + (voff)[_i]), (LAS unsigned*)(lds + (bufoff) + ldsw + _i * 8192), 16, 0, 0); } while (0)
; #define PG8_WAIT_V(n) asm volatile("s_waitcnt vmcnt(" #n ")" ::: "memory")
;     __device__ __forceinline__ void operator()(const f32x4 (&acc)[2][2][4][2], const Unit& u, int wr, int wc, int fr, int fq) const {
;     ...
;             for (int m = 0; m < 4; ++m) { const int row = row0 + ai * HALF + m * 16;
;                 const float rs = ssin ? __builtin_amdgcn_rsqf(ssin[row] * (1.f / D) + EPS) : 1.0f; float sq = 0.f; u32x4 w[2];
; #pragma unroll
;                 for (int bj = 0; bj < 2; ++bj) { f32x4 v0 = acc[ai][bj][m][0] * rs, v1 = acc[ai][bj][m][1] * rs;
;                     if (ACT == 1) {
; #pragma unroll
;                         for (int j = 0; j < 4; ++j) { const float a = fmaxf(v0[j], 0.f), b = fmaxf(v1[j], 0.f); v0[j] = a * a; v1[j] = b * b; } }
;                     sq += (v0[0] * v0[0] + v0[1] * v0[1]) + (v0[2] * v0[2] + v0[3] * v0[3]) + (v1[0] * v1[0] + v1[1] * v1[1]) + (v1[2] * v1[2] + v1[3] * v1[3]);
;                     w[bj].x = cvt_pk_bf16(v0[0], v0[1]); w[bj].y = cvt_pk_bf16(v0[2], v0[3]); w[bj].z = cvt_pk_bf16(v1[0], v1[1]); w[bj].w = cvt_pk_bf16(v1[2], v1[3]); }
;                 store_pair_lines(O, ldc, row, fr, col0, w[0], w[1]);
; template <class Epi>
; __device__ __forceinline__ void gemm_phase(LAS unsigned char* lds, const Gemm g, const StaticOrder& S, const Epi& E) {
;     ...
;             PG8_LDB(B0, 1, 0); PG8_SCHED; PG8_LDA(At, 1, 0); PG8_STAGE(PG8_SA(0, 1), a2 + hstep, voffA);
;             PG8_WAIT_L(8); PG8_BAR; PG8_WAIT_L(0); PG8_MMA(0, 0, At, B0); PG8_BAR; PG8_SCHED;
;             PG8_LDB(B1, 1, 1); PG8_STAGE(PG8_SB(1, 0), b3, voffB0);
;             PG8_BAR; PG8_WAIT_L(0); PG8_MMA(0, 1, At, B1); PG8_BAR;
;             PG8_LDA(At, 1, 1); PG8_STAGE(PG8_SA(1, 0), a3, voffA);
;             PG8_BAR; PG8_WAIT_L(0); PG8_MMA(1, 0, At, B0); PG8_BAR; PG8_SCHED;
;             PG8_STAGE(PG8_SB(1, 1), b3, voffB1);
;             PG8_WAIT_V(6); PG8_BAR; PG8_MMA(1, 1, At, B1); PG8_BAR;
;         }
	ds_read_b128 v[178:181], v159 offset:49152
	ds_read_b128 v[182:185], v159 offset:50176
	ds_read_b128 v[186:189], v159 offset:51200
	ds_read_b128 v[190:193], v159 offset:52224
	ds_read_b128 v[194:197], v159 offset:53248
	ds_read_b128 v[198:201], v159 offset:54272
	ds_read_b128 v[204:207], v159 offset:55296
	ds_read_b128 v[208:211], v159 offset:56320
	global_load_lds_dwordx4 v[228:229], off
	v_lshl_add_u64 v[228:229], v[234:235], 0, s[8:9]
	s_mov_b32 m0, s52
	s_nop 0
	global_load_lds_dwordx4 v[228:229], off
	s_add_i32 s33, s36, s44
	v_lshl_add_u64 v[250:251], v[236:237], 0, s[8:9]
	s_mov_b32 m0, s33
	s_nop 0
	global_load_lds_dwordx4 v[250:251], off
	v_lshl_add_u64 v[250:251], v[238:239], 0, s[8:9]
	s_add_i32 m0, s33, 0x2000
	s_nop 0
	global_load_lds_dwordx4 v[250:251], off
	s_waitcnt vmcnt(6)
	s_barrier
	s_waitcnt lgkmcnt(0)
	v_mfma_f32_16x16x32_bf16 v[60:63], v[162:165], v[178:181], v[60:63]
	v_mfma_f32_16x16x32_bf16 v[56:59], v[170:173], v[178:181], v[56:59]
	v_mfma_f32_16x16x32_bf16 v[44:47], v[162:165], v[186:189], v[44:47]
	v_mfma_f32_16x16x32_bf16 v[40:43], v[170:173], v[186:189], v[40:43]
	v_mfma_f32_16x16x32_bf16 v[28:31], v[162:165], v[194:197], v[28:31]
	v_mfma_f32_16x16x32_bf16 v[24:27], v[170:173], v[194:197], v[24:27]
	v_mfma_f32_16x16x32_bf16 v[12:15], v[162:165], v[204:207], v[12:15]
	v_mfma_f32_16x16x32_bf16 v[8:11], v[170:173], v[204:207], v[8:11]
	v_mfma_f32_16x16x32_bf16 v[60:63], v[166:169], v[182:185], v[60:63]
	v_mfma_f32_16x16x32_bf16 v[56:59], v[174:177], v[182:185], v[56:59]
	v_mfma_f32_16x16x32_bf16 v[44:47], v[166:169], v[190:193], v[44:47]
	v_mfma_f32_16x16x32_bf16 v[40:43], v[174:177], v[190:193], v[40:43]
	v_mfma_f32_16x16x32_bf16 v[28:31], v[166:169], v[198:201], v[28:31]
	v_mfma_f32_16x16x32_bf16 v[24:27], v[174:177], v[198:201], v[24:27]
	v_mfma_f32_16x16x32_bf16 v[12:15], v[166:169], v[208:211], v[12:15]
	v_mfma_f32_16x16x32_bf16 v[8:11], v[174:177], v[208:211], v[8:11]
	v_mfma_f32_16x16x32_bf16 v[52:55], v[212:215], v[178:181], v[52:55]
	v_mfma_f32_16x16x32_bf16 v[48:51], v[220:223], v[178:181], v[48:51]
	v_mfma_f32_16x16x32_bf16 v[36:39], v[212:215], v[186:189], v[36:39]
	v_mfma_f32_16x16x32_bf16 v[32:35], v[220:223], v[186:189], v[32:35]
	v_mfma_f32_16x16x32_bf16 v[20:23], v[212:215], v[194:197], v[20:23]
	v_mfma_f32_16x16x32_bf16 v[16:19], v[220:223], v[194:197], v[16:19]
	v_mfma_f32_16x16x32_bf16 v[4:7], v[212:215], v[204:207], v[4:7]
	v_mfma_f32_16x16x32_bf16 v[0:3], v[220:223], v[204:207], v[0:3]
	v_mfma_f32_16x16x32_bf16 v[52:55], v[216:219], v[182:185], v[52:55]
	v_mfma_f32_16x16x32_bf16 v[48:51], v[224:227], v[182:185], v[48:51]
	v_mfma_f32_16x16x32_bf16 v[36:39], v[216:219], v[190:193], v[36:39]
	v_mfma_f32_16x16x32_bf16 v[32:35], v[224:227], v[190:193], v[32:35]
	v_mfma_f32_16x16x32_bf16 v[20:23], v[216:219], v[198:201], v[20:23]
	v_mfma_f32_16x16x32_bf16 v[16:19], v[224:227], v[198:201], v[16:19]
	v_mfma_f32_16x16x32_bf16 v[4:7], v[216:219], v[208:211], v[4:7]
	v_mfma_f32_16x16x32_bf16 v[0:3], v[224:227], v[208:211], v[0:3]
	s_add_i32 s63, s63, 2
	s_add_u32 s34, s34, 0x100
	s_addc_u32 s35, s35, 0
	s_add_u32 s61, s61, 0x100
	s_addc_u32 s62, s62, 0
	s_cmp_gt_u32 s63, 29
	s_barrier
	s_cbranch_scc0 .LBB0_107
	s_lshl_b32 s11, s30, 8
	v_cvt_pk_bf16_f32 v124, v124, v125
	v_cvt_pk_bf16_f32 v125, v126, v127
	v_cvt_pk_bf16_f32 v120, v120, v121
	v_cvt_pk_bf16_f32 v121, v122, v123
	v_cvt_pk_bf16_f32 v122, v116, v117
	v_cvt_pk_bf16_f32 v119, v118, v119
	s_add_i32 s11, s11, s53
	v_cvt_pk_bf16_f32 v112, v112, v113
	v_cvt_pk_bf16_f32 v113, v114, v115
	v_mov_b32_dpp v118, v124 row_ror:8 row_mask:0xf bank_mask:0xf
	v_mov_b32_dpp v123, v125 row_ror:8 row_mask:0xf bank_mask:0xf
	v_mov_b32_dpp v114, v122 row_ror:8 row_mask:0xf bank_mask:0xf
	v_cndmask_b32_e64 v118, v122, v118, s[4:5]
	v_or_b32_e32 v122, s11, v149
	v_lshl_or_b32 v162, s58, 8, v157
	v_mov_b32_dpp v126, v120 row_ror:8 row_mask:0xf bank_mask:0xf
	v_mov_b32_dpp v127, v121 row_ror:8 row_mask:0xf bank_mask:0xf
	v_mov_b32_dpp v115, v119 row_ror:8 row_mask:0xf bank_mask:0xf
	v_mov_b32_dpp v116, v112 row_ror:8 row_mask:0xf bank_mask:0xf
	v_mov_b32_dpp v117, v113 row_ror:8 row_mask:0xf bank_mask:0xf
	v_cndmask_b32_e64 v119, v119, v123, s[4:5]
	v_ashrrev_i32_e32 v123, 31, v122
	v_ashrrev_i32_e32 v163, 31, v162
	v_cndmask_b32_e64 v116, v116, v120, s[4:5]
	v_cndmask_b32_e64 v117, v117, v121, s[4:5]
	v_cndmask_b32_e64 v120, v112, v126, s[4:5]
	v_cndmask_b32_e64 v121, v113, v127, s[4:5]
	v_lshlrev_b64 v[112:113], 13, v[122:123]
	v_cndmask_b32_e64 v114, v114, v124, s[4:5]
	v_cndmask_b32_e64 v115, v115, v125, s[4:5]
	v_lshl_add_u64 v[124:125], s[6:7], 0, v[112:113]
	v_lshlrev_b64 v[112:113], 1, v[162:163]
	v_lshl_add_u64 v[124:125], v[124:125], 0, v[112:113]
	global_store_dwordx4 v[124:125], v[114:117], off
	v_or_b32_e32 v161, s11, v147
	s_mov_b32 s58, s10
	v_or_b32_e32 v114, 8, v122
	v_ashrrev_i32_e32 v115, 31, v114
	v_lshlrev_b64 v[114:115], 13, v[114:115]
	v_lshl_add_u64 v[114:115], s[6:7], 0, v[114:115]
	v_lshl_add_u64 v[114:115], v[114:115], 0, v[112:113]
	global_store_dwordx4 v[114:115], v[118:121], off
	v_cvt_pk_bf16_f32 v108, v108, v109
	v_cvt_pk_bf16_f32 v109, v110, v111
	v_cvt_pk_bf16_f32 v104, v104, v105
	v_cvt_pk_bf16_f32 v105, v106, v107
	v_cvt_pk_bf16_f32 v100, v100, v101
	v_cvt_pk_bf16_f32 v101, v102, v103
	v_cvt_pk_bf16_f32 v102, v96, v97
	v_cvt_pk_bf16_f32 v103, v98, v99
	v_mov_b32_e32 v98, 0
	v_mov_b32_dpp v98, v102 row_ror:8 row_mask:0xf bank_mask:0xf
	v_mov_b32_dpp v110, v104 row_ror:8 row_mask:0xf bank_mask:0xf
	v_mov_b32_dpp v99, v103 row_ror:8 row_mask:0xf bank_mask:0xf
	v_cndmask_b32_e64 v98, v98, v104, s[4:5]
	v_add_u32_e32 v104, v150, v161
; __device__ __forceinline__ unsigned cvt_pk_bf16(float lo, float hi) { unsigned r; asm volatile("v_cvt_pk_bf16_f32 %0, %1, %2" : "=v"(r) : "v"(lo), "v"(hi)); return r; }
; __device__ __forceinline__ unsigned dpp_ror8(unsigned x) { return (unsigned)__builtin_amdgcn_update_dpp(0, (int)x, 0x128, 0xf, 0xf, false); }
; __device__ __forceinline__ void store_pair_lines(bf16_t* O, int ldc, int row, int fr, int col0, u32x4 wA, u32x4 wB) {
;     const u32x4 sA = {dpp_ror8(wA.x), dpp_ror8(wA.y), dpp_ror8(wA.z), dpp_ror8(wA.w)}, sB = {dpp_ror8(wB.x), dpp_ror8(wB.y), dpp_ror8(wB.z), dpp_ror8(wB.w)};
;     const bool lo = fr < 8;
;     const u32x4 o1 = lo ? wA : sB, o2 = lo ? sA : wB;
;     const int r1 = row - fr + (fr & 7), cb = col0 + (lo ? 0 : 8);
;     *(u32x4*)(O + (size_t)r1 * ldc + cb) = o1;
;     *(u32x4*)(O + (size_t)(r1 + 8) * ldc + cb) = o2;
; }
;     __device__ __forceinline__ void operator()(const f32x4 (&acc)[2][2][4][2], const Unit& u, int wr, int wc, int fr, int fq) const {
;     ...
;             for (int m = 0; m < 4; ++m) { const int row = row0 + ai * HALF + m * 16;
;                 const float rs = ssin ? __builtin_amdgcn_rsqf(ssin[row] * (1.f / D) + EPS) : 1.0f; float sq = 0.f; u32x4 w[2];
; #pragma unroll
;                 for (int bj = 0; bj < 2; ++bj) { f32x4 v0 = acc[ai][bj][m][0] * rs, v1 = acc[ai][bj][m][1] * rs;
;                     if (ACT == 1) {
; #pragma unroll
;                         for (int j = 0; j < 4; ++j) { const float a = fmaxf(v0[j], 0.f), b = fmaxf(v1[j], 0.f); v0[j] = a * a; v1[j] = b * b; } }
;                     sq += (v0[0] * v0[0] + v0[1] * v0[1]) + (v0[2] * v0[2] + v0[3] * v0[3]) + (v1[0] * v1[0] + v1[1] * v1[1]) + (v1[2] * v1[2] + v1[3] * v1[3]);
;                     w[bj].x = cvt_pk_bf16(v0[0], v0[1]); w[bj].y = cvt_pk_bf16(v0[2], v0[3]); w[bj].z = cvt_pk_bf16(v1[0], v1[1]); w[bj].w = cvt_pk_bf16(v1[2], v1[3]); }
;                 store_pair_lines(O, ldc, row, fr, col0, w[0], w[1]);
;                 if (ssout) { sq += __shfl_xor(sq, 16); sq += __shfl_xor(sq, 32); if (fq == 0) unsafeAtomicAdd(ssout + row, sq); } }
	v_mov_b32_dpp v111, v105 row_ror:8 row_mask:0xf bank_mask:0xf
	v_cndmask_b32_e64 v99, v99, v105, s[4:5]
	v_ashrrev_i32_e32 v105, 31, v104
	v_lshlrev_b64 v[104:105], 13, v[104:105]
	v_mov_b32_dpp v96, v100 row_ror:8 row_mask:0xf bank_mask:0xf
	v_mov_b32_dpp v97, v101 row_ror:8 row_mask:0xf bank_mask:0xf
	v_lshl_add_u64 v[104:105], s[6:7], 0, v[104:105]
	v_cndmask_b32_e64 v96, v96, v108, s[4:5]
	v_cndmask_b32_e64 v97, v97, v109, s[4:5]
	v_lshl_add_u64 v[104:105], v[104:105], 0, v[112:113]
	v_mov_b32_dpp v106, v108 row_ror:8 row_mask:0xf bank_mask:0xf
	v_mov_b32_dpp v107, v109 row_ror:8 row_mask:0xf bank_mask:0xf
	global_store_dwordx4 v[104:105], v[96:99], off
	v_cndmask_b32_e64 v100, v100, v106, s[4:5]
	v_cndmask_b32_e64 v101, v101, v107, s[4:5]
	v_add_co_u32_e32 v96, vcc, s49, v104
	v_cndmask_b32_e64 v102, v102, v110, s[4:5]
	v_cndmask_b32_e64 v103, v103, v111, s[4:5]
	v_addc_co_u32_e32 v97, vcc, 0, v105, vcc
	global_store_dwordx4 v[96:97], v[100:103], off
	v_cvt_pk_bf16_f32 v92, v92, v93
	v_cvt_pk_bf16_f32 v93, v94, v95
	v_cvt_pk_bf16_f32 v88, v88, v89
	v_cvt_pk_bf16_f32 v89, v90, v91
	v_cvt_pk_bf16_f32 v84, v84, v85
	v_cvt_pk_bf16_f32 v85, v86, v87
	v_cvt_pk_bf16_f32 v86, v80, v81
	v_cvt_pk_bf16_f32 v87, v82, v83
	v_mov_b32_e32 v82, 0
	v_mov_b32_dpp v82, v86 row_ror:8 row_mask:0xf bank_mask:0xf
	v_mov_b32_dpp v94, v88 row_ror:8 row_mask:0xf bank_mask:0xf
	v_mov_b32_dpp v83, v87 row_ror:8 row_mask:0xf bank_mask:0xf
	v_cndmask_b32_e64 v82, v82, v88, s[4:5]
	v_add_u32_e32 v88, v151, v161
	v_mov_b32_dpp v95, v89 row_ror:8 row_mask:0xf bank_mask:0xf
	v_cndmask_b32_e64 v83, v83, v89, s[4:5]
	v_ashrrev_i32_e32 v89, 31, v88
	v_lshlrev_b64 v[88:89], 13, v[88:89]
	v_mov_b32_dpp v80, v84 row_ror:8 row_mask:0xf bank_mask:0xf
	v_mov_b32_dpp v81, v85 row_ror:8 row_mask:0xf bank_mask:0xf
	v_lshl_add_u64 v[88:89], s[6:7], 0, v[88:89]
	v_cndmask_b32_e64 v80, v80, v92, s[4:5]
	v_cndmask_b32_e64 v81, v81, v93, s[4:5]
	v_lshl_add_u64 v[88:89], v[88:89], 0, v[112:113]
	v_mov_b32_dpp v90, v92 row_ror:8 row_mask:0xf bank_mask:0xf
	v_mov_b32_dpp v91, v93 row_ror:8 row_mask:0xf bank_mask:0xf
	global_store_dwordx4 v[88:89], v[80:83], off
	v_cndmask_b32_e64 v84, v84, v90, s[4:5]
	v_cndmask_b32_e64 v85, v85, v91, s[4:5]
	v_add_co_u32_e32 v80, vcc, s49, v88
	v_cndmask_b32_e64 v86, v86, v94, s[4:5]
	v_cndmask_b32_e64 v87, v87, v95, s[4:5]
	v_addc_co_u32_e32 v81, vcc, 0, v89, vcc
	global_store_dwordx4 v[80:81], v[84:87], off
	v_cvt_pk_bf16_f32 v76, v76, v77
	v_cvt_pk_bf16_f32 v77, v78, v79
	v_cvt_pk_bf16_f32 v72, v72, v73
	v_cvt_pk_bf16_f32 v73, v74, v75
	v_cvt_pk_bf16_f32 v68, v68, v69
	v_cvt_pk_bf16_f32 v69, v70, v71
	v_cvt_pk_bf16_f32 v70, v64, v65
	v_cvt_pk_bf16_f32 v71, v66, v67
	v_mov_b32_e32 v66, 0
	v_mov_b32_dpp v66, v70 row_ror:8 row_mask:0xf bank_mask:0xf
	v_mov_b32_dpp v78, v72 row_ror:8 row_mask:0xf bank_mask:0xf
	v_mov_b32_dpp v67, v71 row_ror:8 row_mask:0xf bank_mask:0xf
	v_cndmask_b32_e64 v66, v66, v72, s[4:5]
	v_add_u32_e32 v72, v152, v161
	v_mov_b32_dpp v79, v73 row_ror:8 row_mask:0xf bank_mask:0xf
	v_cndmask_b32_e64 v67, v67, v73, s[4:5]
	v_ashrrev_i32_e32 v73, 31, v72
	v_lshlrev_b64 v[72:73], 13, v[72:73]
	v_mov_b32_dpp v64, v68 row_ror:8 row_mask:0xf bank_mask:0xf
	v_mov_b32_dpp v65, v69 row_ror:8 row_mask:0xf bank_mask:0xf
	v_lshl_add_u64 v[72:73], s[6:7], 0, v[72:73]
	v_cndmask_b32_e64 v64, v64, v76, s[4:5]
	v_cndmask_b32_e64 v65, v65, v77, s[4:5]
	v_lshl_add_u64 v[72:73], v[72:73], 0, v[112:113]
	v_mov_b32_dpp v74, v76 row_ror:8 row_mask:0xf bank_mask:0xf
	v_mov_b32_dpp v75, v77 row_ror:8 row_mask:0xf bank_mask:0xf
	global_store_dwordx4 v[72:73], v[64:67], off
	v_cndmask_b32_e64 v68, v68, v74, s[4:5]
	v_cndmask_b32_e64 v69, v69, v75, s[4:5]
	v_add_co_u32_e32 v64, vcc, s49, v72
	v_cndmask_b32_e64 v70, v70, v78, s[4:5]
	v_cndmask_b32_e64 v71, v71, v79, s[4:5]
	v_addc_co_u32_e32 v65, vcc, 0, v73, vcc
	global_store_dwordx4 v[64:65], v[68:71], off
	v_cvt_pk_bf16_f32 v60, v60, v61
	v_cvt_pk_bf16_f32 v61, v62, v63
	v_cvt_pk_bf16_f32 v56, v56, v57
	v_cvt_pk_bf16_f32 v57, v58, v59
	v_cvt_pk_bf16_f32 v52, v52, v53
	v_cvt_pk_bf16_f32 v53, v54, v55
	v_cvt_pk_bf16_f32 v54, v48, v49
	v_cvt_pk_bf16_f32 v55, v50, v51
	v_mov_b32_e32 v50, 0
	v_mov_b32_dpp v50, v54 row_ror:8 row_mask:0xf bank_mask:0xf
	v_mov_b32_dpp v62, v56 row_ror:8 row_mask:0xf bank_mask:0xf
	v_mov_b32_dpp v51, v55 row_ror:8 row_mask:0xf bank_mask:0xf
	v_cndmask_b32_e64 v50, v50, v56, s[4:5]
	v_add_u32_e32 v56, v153, v161
	v_mov_b32_dpp v63, v57 row_ror:8 row_mask:0xf bank_mask:0xf
	v_cndmask_b32_e64 v51, v51, v57, s[4:5]
	v_ashrrev_i32_e32 v57, 31, v56
	v_lshlrev_b64 v[56:57], 13, v[56:57]
	v_mov_b32_dpp v48, v52 row_ror:8 row_mask:0xf bank_mask:0xf
	v_mov_b32_dpp v49, v53 row_ror:8 row_mask:0xf bank_mask:0xf
	v_lshl_add_u64 v[56:57], s[6:7], 0, v[56:57]
	v_cndmask_b32_e64 v48, v48, v60, s[4:5]
	v_cndmask_b32_e64 v49, v49, v61, s[4:5]
	v_lshl_add_u64 v[56:57], v[56:57], 0, v[112:113]
	v_mov_b32_dpp v58, v60 row_ror:8 row_mask:0xf bank_mask:0xf
; __device__ __forceinline__ unsigned cvt_pk_bf16(float lo, float hi) { unsigned r; asm volatile("v_cvt_pk_bf16_f32 %0, %1, %2" : "=v"(r) : "v"(lo), "v"(hi)); return r; }
; __device__ __forceinline__ unsigned dpp_ror8(unsigned x) { return (unsigned)__builtin_amdgcn_update_dpp(0, (int)x, 0x128, 0xf, 0xf, false); }
; __device__ __forceinline__ void store_pair_lines(bf16_t* O, int ldc, int row, int fr, int col0, u32x4 wA, u32x4 wB) {
;     const u32x4 sA = {dpp_ror8(wA.x), dpp_ror8(wA.y), dpp_ror8(wA.z), dpp_ror8(wA.w)}, sB = {dpp_ror8(wB.x), dpp_ror8(wB.y), dpp_ror8(wB.z), dpp_ror8(wB.w)};
;     const bool lo = fr < 8;
;     const u32x4 o1 = lo ? wA : sB, o2 = lo ? sA : wB;
;     const int r1 = row - fr + (fr & 7), cb = col0 + (lo ? 0 : 8);
;     *(u32x4*)(O + (size_t)r1 * ldc + cb) = o1;
;     *(u32x4*)(O + (size_t)(r1 + 8) * ldc + cb) = o2;
; }
;     __device__ __forceinline__ void operator()(const f32x4 (&acc)[2][2][4][2], const Unit& u, int wr, int wc, int fr, int fq) const {
;     ...
;             for (int m = 0; m < 4; ++m) { const int row = row0 + ai * HALF + m * 16;
;                 const float rs = ssin ? __builtin_amdgcn_rsqf(ssin[row] * (1.f / D) + EPS) : 1.0f; float sq = 0.f; u32x4 w[2];
; #pragma unroll
;                 for (int bj = 0; bj < 2; ++bj) { f32x4 v0 = acc[ai][bj][m][0] * rs, v1 = acc[ai][bj][m][1] * rs;
;                     if (ACT == 1) {
; #pragma unroll
;                         for (int j = 0; j < 4; ++j) { const float a = fmaxf(v0[j], 0.f), b = fmaxf(v1[j], 0.f); v0[j] = a * a; v1[j] = b * b; } }
;                     sq += (v0[0] * v0[0] + v0[1] * v0[1]) + (v0[2] * v0[2] + v0[3] * v0[3]) + (v1[0] * v1[0] + v1[1] * v1[1]) + (v1[2] * v1[2] + v1[3] * v1[3]);
;                     w[bj].x = cvt_pk_bf16(v0[0], v0[1]); w[bj].y = cvt_pk_bf16(v0[2], v0[3]); w[bj].z = cvt_pk_bf16(v1[0], v1[1]); w[bj].w = cvt_pk_bf16(v1[2], v1[3]); }
;                 store_pair_lines(O, ldc, row, fr, col0, w[0], w[1]);
;                 if (ssout) { sq += __shfl_xor(sq, 16); sq += __shfl_xor(sq, 32); if (fq == 0) unsafeAtomicAdd(ssout + row, sq); } }
	v_mov_b32_dpp v59, v61 row_ror:8 row_mask:0xf bank_mask:0xf
	global_store_dwordx4 v[56:57], v[48:51], off
	v_cndmask_b32_e64 v52, v52, v58, s[4:5]
	v_cndmask_b32_e64 v53, v53, v59, s[4:5]
	v_add_co_u32_e32 v48, vcc, s49, v56
	v_cndmask_b32_e64 v54, v54, v62, s[4:5]
	v_cndmask_b32_e64 v55, v55, v63, s[4:5]
	v_addc_co_u32_e32 v49, vcc, 0, v57, vcc
	global_store_dwordx4 v[48:49], v[52:55], off
	v_cvt_pk_bf16_f32 v44, v44, v45
	v_cvt_pk_bf16_f32 v45, v46, v47
	v_cvt_pk_bf16_f32 v40, v40, v41
	v_cvt_pk_bf16_f32 v41, v42, v43
	v_cvt_pk_bf16_f32 v36, v36, v37
	v_cvt_pk_bf16_f32 v37, v38, v39
	v_cvt_pk_bf16_f32 v38, v32, v33
	v_cvt_pk_bf16_f32 v39, v34, v35
	v_mov_b32_e32 v34, 0
	v_mov_b32_dpp v34, v38 row_ror:8 row_mask:0xf bank_mask:0xf
	v_mov_b32_dpp v46, v40 row_ror:8 row_mask:0xf bank_mask:0xf
	v_mov_b32_dpp v35, v39 row_ror:8 row_mask:0xf bank_mask:0xf
	v_cndmask_b32_e64 v34, v34, v40, s[4:5]
	v_add_u32_e32 v40, v154, v161
	v_mov_b32_dpp v47, v41 row_ror:8 row_mask:0xf bank_mask:0xf
	v_cndmask_b32_e64 v35, v35, v41, s[4:5]
	v_ashrrev_i32_e32 v41, 31, v40
	v_lshlrev_b64 v[40:41], 13, v[40:41]
	v_mov_b32_dpp v32, v36 row_ror:8 row_mask:0xf bank_mask:0xf
	v_mov_b32_dpp v33, v37 row_ror:8 row_mask:0xf bank_mask:0xf
	v_lshl_add_u64 v[40:41], s[6:7], 0, v[40:41]
	v_cndmask_b32_e64 v32, v32, v44, s[4:5]
	v_cndmask_b32_e64 v33, v33, v45, s[4:5]
	v_lshl_add_u64 v[40:41], v[40:41], 0, v[112:113]
	v_mov_b32_dpp v42, v44 row_ror:8 row_mask:0xf bank_mask:0xf
	v_mov_b32_dpp v43, v45 row_ror:8 row_mask:0xf bank_mask:0xf
	global_store_dwordx4 v[40:41], v[32:35], off
	v_cndmask_b32_e64 v36, v36, v42, s[4:5]
	v_cndmask_b32_e64 v37, v37, v43, s[4:5]
	v_add_co_u32_e32 v32, vcc, s49, v40
	v_cndmask_b32_e64 v38, v38, v46, s[4:5]
	v_cndmask_b32_e64 v39, v39, v47, s[4:5]
	v_addc_co_u32_e32 v33, vcc, 0, v41, vcc
	global_store_dwordx4 v[32:33], v[36:39], off
	v_cvt_pk_bf16_f32 v28, v28, v29
	v_cvt_pk_bf16_f32 v29, v30, v31
	v_cvt_pk_bf16_f32 v24, v24, v25
	v_cvt_pk_bf16_f32 v25, v26, v27
	v_cvt_pk_bf16_f32 v20, v20, v21
	v_cvt_pk_bf16_f32 v21, v22, v23
	v_cvt_pk_bf16_f32 v22, v16, v17
	v_cvt_pk_bf16_f32 v23, v18, v19
	v_mov_b32_e32 v18, 0
	v_mov_b32_dpp v18, v22 row_ror:8 row_mask:0xf bank_mask:0xf
	v_mov_b32_dpp v30, v24 row_ror:8 row_mask:0xf bank_mask:0xf
	v_mov_b32_dpp v19, v23 row_ror:8 row_mask:0xf bank_mask:0xf
	v_cndmask_b32_e64 v18, v18, v24, s[4:5]
	v_add_u32_e32 v24, v155, v161
	v_mov_b32_dpp v31, v25 row_ror:8 row_mask:0xf bank_mask:0xf
	v_cndmask_b32_e64 v19, v19, v25, s[4:5]
	v_ashrrev_i32_e32 v25, 31, v24
	v_lshlrev_b64 v[24:25], 13, v[24:25]
	v_mov_b32_dpp v16, v20 row_ror:8 row_mask:0xf bank_mask:0xf
	v_mov_b32_dpp v17, v21 row_ror:8 row_mask:0xf bank_mask:0xf
	v_lshl_add_u64 v[24:25], s[6:7], 0, v[24:25]
	v_cndmask_b32_e64 v16, v16, v28, s[4:5]
	v_cndmask_b32_e64 v17, v17, v29, s[4:5]
	v_lshl_add_u64 v[24:25], v[24:25], 0, v[112:113]
	v_mov_b32_dpp v26, v28 row_ror:8 row_mask:0xf bank_mask:0xf
	v_mov_b32_dpp v27, v29 row_ror:8 row_mask:0xf bank_mask:0xf
	global_store_dwordx4 v[24:25], v[16:19], off
	v_cndmask_b32_e64 v20, v20, v26, s[4:5]
	v_cndmask_b32_e64 v21, v21, v27, s[4:5]
	v_add_co_u32_e32 v16, vcc, s49, v24
	v_cndmask_b32_e64 v22, v22, v30, s[4:5]
	v_cndmask_b32_e64 v23, v23, v31, s[4:5]
	v_addc_co_u32_e32 v17, vcc, 0, v25, vcc
	global_store_dwordx4 v[16:17], v[20:23], off
	v_cvt_pk_bf16_f32 v12, v12, v13
	v_cvt_pk_bf16_f32 v13, v14, v15
	v_cvt_pk_bf16_f32 v8, v8, v9
	v_cvt_pk_bf16_f32 v9, v10, v11
	v_cvt_pk_bf16_f32 v4, v4, v5
	v_cvt_pk_bf16_f32 v5, v6, v7
	v_cvt_pk_bf16_f32 v6, v0, v1
	v_cvt_pk_bf16_f32 v7, v2, v3
	v_mov_b32_e32 v2, 0
	v_mov_b32_dpp v2, v6 row_ror:8 row_mask:0xf bank_mask:0xf
	v_mov_b32_dpp v14, v8 row_ror:8 row_mask:0xf bank_mask:0xf
	v_mov_b32_dpp v3, v7 row_ror:8 row_mask:0xf bank_mask:0xf
	v_cndmask_b32_e64 v2, v2, v8, s[4:5]
	v_add_u32_e32 v8, v156, v161
	v_mov_b32_dpp v15, v9 row_ror:8 row_mask:0xf bank_mask:0xf
	v_cndmask_b32_e64 v3, v3, v9, s[4:5]
	v_ashrrev_i32_e32 v9, 31, v8
	v_lshlrev_b64 v[8:9], 13, v[8:9]
	v_mov_b32_dpp v0, v4 row_ror:8 row_mask:0xf bank_mask:0xf
	v_mov_b32_dpp v1, v5 row_ror:8 row_mask:0xf bank_mask:0xf
	v_lshl_add_u64 v[8:9], s[6:7], 0, v[8:9]
	v_cndmask_b32_e64 v0, v0, v12, s[4:5]
	v_cndmask_b32_e64 v1, v1, v13, s[4:5]
	v_lshl_add_u64 v[8:9], v[8:9], 0, v[112:113]
	global_store_dwordx4 v[8:9], v[0:3], off
	v_mov_b32_dpp v10, v12 row_ror:8 row_mask:0xf bank_mask:0xf
	v_mov_b32_dpp v11, v13 row_ror:8 row_mask:0xf bank_mask:0xf
	v_add_co_u32_e32 v0, vcc, 0x10000, v8
	v_cndmask_b32_e64 v4, v4, v10, s[4:5]
	s_nop 0
	v_addc_co_u32_e32 v1, vcc, 0, v9, vcc
	v_cndmask_b32_e64 v5, v5, v11, s[4:5]
	v_cndmask_b32_e64 v6, v6, v14, s[4:5]
	v_cndmask_b32_e64 v7, v7, v15, s[4:5]
	s_and_b64 vcc, exec, s[18:19]
	s_mov_b32 s30, s12
	s_mov_b64 s[36:37], s[28:29]
	s_mov_b64 s[34:35], s[16:17]
	global_store_dwordx4 v[0:1], v[4:7], off
	s_cbranch_vccz .LBB0_103
	s_waitcnt vmcnt(0)
	s_cmpk_gt_u32 s27, 0xff
	s_cbranch_scc1 .LBB0_111
	s_barrier

; #define PG8_STAGE(bufoff, gbase, voff) do { _Pragma("unroll") for (int _i = 0; _i < 2; ++_i) \
;         __builtin_amdgcn_global_load_lds((const unsigned*)((const char*)(gbase) + (voff)[_i]), (LAS unsigned*)(lds + (bufoff) + ldsw + _i * 8192), 16, 0, 0); } while (0)
; #define PG8_LDA(dst, b, h) do { _Pragma("unroll") for (int m = 0; m < 4; ++m) _Pragma("unroll") for (int k = 0; k < 2; ++k) dst[m][k] = *(const LAS bf16x8*)(lds + PG8_SA(b, h) + aoff + m * 2048 + k * 1024); } while (0)
; #define PG8_LDB(dst, b, h) do { _Pragma("unroll") for (int n = 0; n < 2; ++n) _Pragma("unroll") for (int k = 0; k < 2; ++k) dst[n][k] = *(const LAS bf16x8*)(lds + PG8_SB(b, h) + boff + n * 2048 + k * 1024); } while (0)
; #define PG8_WAIT_V(n) asm volatile("s_waitcnt vmcnt(" #n ")" ::: "memory")
; #define PG8_WAIT_L(n) asm volatile("s_waitcnt lgkmcnt(" #n ")" ::: "memory")
; #define PG8_BAR __builtin_amdgcn_s_barrier()
; #define PG8_SCHED __builtin_amdgcn_sched_barrier(0)
; template <class Epi>
; __device__ __forceinline__ void gemm_phase(LAS unsigned char* lds, const Gemm g, const StaticOrder& S, const Epi& E) {
;     ...
;             PG8_LDB(B0, 0, 0); PG8_SCHED; PG8_LDA(At, 0, 0); PG8_STAGE(PG8_SA(1, 1), a1 + hstep, voffA);
;             PG8_WAIT_L(8); PG8_BAR; PG8_WAIT_L(0); PG8_MMA(0, 0, At, B0); PG8_BAR; PG8_SCHED;
;             PG8_LDB(B1, 0, 1); PG8_STAGE(PG8_SB(0, 0), b2, voffB0);
;             PG8_BAR; PG8_WAIT_L(0); PG8_MMA(0, 1, At, B1); PG8_BAR;
;             PG8_LDA(At, 0, 1); PG8_STAGE(PG8_SA(0, 0), a2, voffA);
;             PG8_BAR; PG8_WAIT_L(0); PG8_MMA(1, 0, At, B0); PG8_BAR; PG8_SCHED;
;             PG8_STAGE(PG8_SB(0, 1), b2, voffB1);
;             PG8_WAIT_V(6); PG8_BAR; PG8_MMA(1, 1, At, B1); PG8_BAR;
;             PG8_LDB(B0, 1, 0); PG8_SCHED; PG8_LDA(At, 1, 0); PG8_STAGE(PG8_SA(0, 1), a2 + hstep, voffA);
;             PG8_WAIT_L(8); PG8_BAR; PG8_WAIT_L(0); PG8_MMA(0, 0, At, B0); PG8_BAR; PG8_SCHED;
;             PG8_LDB(B1, 1, 1); PG8_STAGE(PG8_SB(1, 0), b3, voffB0);
;             PG8_BAR; PG8_WAIT_L(0); PG8_MMA(0, 1, At, B1); PG8_BAR;
;             PG8_LDA(At, 1, 1); PG8_STAGE(PG8_SA(1, 0), a3, voffA);
;             PG8_BAR; PG8_WAIT_L(0); PG8_MMA(1, 0, At, B0); PG8_BAR; PG8_SCHED;
;             PG8_STAGE(PG8_SB(1, 1), b3, voffB1);
;             PG8_WAIT_V(6); PG8_BAR; PG8_MMA(1, 1, At, B1); PG8_BAR;
.LBB0_234:
	ds_read_b128 v[160:163], v157
	ds_read_b128 v[164:167], v157 offset:1024
	ds_read_b128 v[168:171], v157 offset:2048
	ds_read_b128 v[172:175], v157 offset:3072
	s_add_u32 s33, s38, 0xfffe0080
	s_addc_u32 s40, s39, -1
	s_cmp_eq_u32 s68, 4
	s_cselect_b32 s41, s17, s40
	s_cselect_b32 s40, s64, s33
	s_cselect_b32 s43, s11, s67
	s_cselect_b32 s42, s65, s66
	v_lshl_add_u64 v[200:201], s[38:39], 0, v[140:141]
	s_add_i32 m0, s37, 0xc000
	ds_read_b128 v[176:179], v158
	ds_read_b128 v[180:183], v158 offset:1024
	ds_read_b128 v[184:187], v158 offset:2048
	ds_read_b128 v[188:191], v158 offset:3072
	ds_read_b128 v[192:195], v158 offset:4096
	ds_read_b128 v[196:199], v158 offset:5120
	ds_read_b128 v[204:207], v158 offset:6144
	ds_read_b128 v[208:211], v158 offset:7168
	global_load_lds_dwordx4 v[200:201], off
	v_lshl_add_u64 v[200:201], s[38:39], 0, v[142:143]
	s_add_i32 m0, s37, 0xe000
	s_nop 0
	global_load_lds_dwordx4 v[200:201], off
	s_waitcnt lgkmcnt(8)
	s_barrier
	s_waitcnt lgkmcnt(0)
	v_mfma_f32_16x16x32_bf16 v[124:127], v[160:163], v[176:179], v[124:127]
	v_mfma_f32_16x16x32_bf16 v[120:123], v[168:171], v[176:179], v[120:123]
	v_mfma_f32_16x16x32_bf16 v[108:111], v[160:163], v[184:187], v[108:111]
	v_mfma_f32_16x16x32_bf16 v[104:107], v[168:171], v[184:187], v[104:107]
	v_mfma_f32_16x16x32_bf16 v[92:95], v[160:163], v[192:195], v[92:95]
	v_mfma_f32_16x16x32_bf16 v[88:91], v[168:171], v[192:195], v[88:91]
	v_mfma_f32_16x16x32_bf16 v[76:79], v[160:163], v[204:207], v[76:79]
	v_mfma_f32_16x16x32_bf16 v[72:75], v[168:171], v[204:207], v[72:75]
	v_mfma_f32_16x16x32_bf16 v[124:127], v[164:167], v[180:183], v[124:127]
	v_mfma_f32_16x16x32_bf16 v[120:123], v[172:175], v[180:183], v[120:123]
	v_mfma_f32_16x16x32_bf16 v[108:111], v[164:167], v[188:191], v[108:111]
	v_mfma_f32_16x16x32_bf16 v[104:107], v[172:175], v[188:191], v[104:107]
	v_mfma_f32_16x16x32_bf16 v[92:95], v[164:167], v[196:199], v[92:95]
	v_mfma_f32_16x16x32_bf16 v[88:91], v[172:175], v[196:199], v[88:91]
	v_mfma_f32_16x16x32_bf16 v[76:79], v[164:167], v[208:211], v[76:79]
	v_mfma_f32_16x16x32_bf16 v[72:75], v[172:175], v[208:211], v[72:75]
	s_barrier
	s_add_i32 s33, s60, s49
	v_lshl_add_u64 v[200:201], s[42:43], 0, v[134:135]
	s_mov_b32 m0, s33
	ds_read_b128 v[212:215], v159
	ds_read_b128 v[216:219], v159 offset:1024
	ds_read_b128 v[220:223], v159 offset:2048
	ds_read_b128 v[224:227], v159 offset:3072
	global_load_lds_dwordx4 v[200:201], off
	v_lshl_add_u64 v[228:229], s[42:43], 0, v[128:129]
	s_add_i32 m0, s33, 0x2000
	s_nop 0
	global_load_lds_dwordx4 v[228:229], off
	s_waitcnt lgkmcnt(0)
	s_barrier
	s_waitcnt lgkmcnt(0)
	v_mfma_f32_16x16x32_bf16 v[116:119], v[212:215], v[176:179], v[116:119]
	v_mfma_f32_16x16x32_bf16 v[112:115], v[220:223], v[176:179], v[112:115]
	v_mfma_f32_16x16x32_bf16 v[100:103], v[212:215], v[184:187], v[100:103]
	v_mfma_f32_16x16x32_bf16 v[96:99], v[220:223], v[184:187], v[96:99]
	v_mfma_f32_16x16x32_bf16 v[84:87], v[212:215], v[192:195], v[84:87]
	v_mfma_f32_16x16x32_bf16 v[80:83], v[220:223], v[192:195], v[80:83]
	v_mfma_f32_16x16x32_bf16 v[68:71], v[212:215], v[204:207], v[68:71]
	v_mfma_f32_16x16x32_bf16 v[64:67], v[220:223], v[204:207], v[64:67]
	v_mfma_f32_16x16x32_bf16 v[116:119], v[216:219], v[180:183], v[116:119]
	v_mfma_f32_16x16x32_bf16 v[112:115], v[224:227], v[180:183], v[112:115]
	v_mfma_f32_16x16x32_bf16 v[100:103], v[216:219], v[188:191], v[100:103]
	v_mfma_f32_16x16x32_bf16 v[96:99], v[224:227], v[188:191], v[96:99]
	v_mfma_f32_16x16x32_bf16 v[84:87], v[216:219], v[196:199], v[84:87]
	v_mfma_f32_16x16x32_bf16 v[80:83], v[224:227], v[196:199], v[80:83]
	v_mfma_f32_16x16x32_bf16 v[68:71], v[216:219], v[208:211], v[68:71]
	v_mfma_f32_16x16x32_bf16 v[64:67], v[224:227], v[208:211], v[64:67]
	s_mov_b32 m0, s37
	v_lshl_add_u64 v[230:231], s[40:41], 0, v[138:139]
	s_barrier
	ds_read_b128 v[176:179], v158 offset:16384
	ds_read_b128 v[180:183], v158 offset:17408
	ds_read_b128 v[184:187], v158 offset:18432
	ds_read_b128 v[188:191], v158 offset:19456
	ds_read_b128 v[192:195], v158 offset:20480
	ds_read_b128 v[196:199], v158 offset:21504
	ds_read_b128 v[204:207], v158 offset:22528
	ds_read_b128 v[208:211], v158 offset:23552
	global_load_lds_dwordx4 v[230:231], off
	v_lshl_add_u64 v[232:233], s[40:41], 0, v[132:133]
	s_mov_b32 m0, s51
	s_nop 0
	global_load_lds_dwordx4 v[232:233], off
	s_add_i32 s33, s61, s49
	v_lshl_add_u64 v[234:235], s[42:43], 0, v[136:137]
	s_mov_b32 m0, s33
	v_lshl_add_u64 v[236:237], s[42:43], 0, v[130:131]
	global_load_lds_dwordx4 v[234:235], off
	s_add_i32 m0, s33, 0x2000
	s_nop 0
	global_load_lds_dwordx4 v[236:237], off
	s_waitcnt vmcnt(6)
	s_barrier
; #define PG8_STAGE(bufoff, gbase, voff) do { _Pragma("unroll") for (int _i = 0; _i < 2; ++_i) \
;         __builtin_amdgcn_global_load_lds((const unsigned*)((const char*)(gbase) + (voff)[_i]), (LAS unsigned*)(lds + (bufoff) + ldsw + _i * 8192), 16, 0, 0); } while (0)
; #define PG8_LDA(dst, b, h) do { _Pragma("unroll") for (int m = 0; m < 4; ++m) _Pragma("unroll") for (int k = 0; k < 2; ++k) dst[m][k] = *(const LAS bf16x8*)(lds + PG8_SA(b, h) + aoff + m * 2048 + k * 1024); } while (0)
; #define PG8_LDB(dst, b, h) do { _Pragma("unroll") for (int n = 0; n < 2; ++n) _Pragma("unroll") for (int k = 0; k < 2; ++k) dst[n][k] = *(const LAS bf16x8*)(lds + PG8_SB(b, h) + boff + n * 2048 + k * 1024); } while (0)
; #define PG8_WAIT_V(n) asm volatile("s_waitcnt vmcnt(" #n ")" ::: "memory")
; #define PG8_WAIT_L(n) asm volatile("s_waitcnt lgkmcnt(" #n ")" ::: "memory")
; #define PG8_BAR __builtin_amdgcn_s_barrier()
; #define PG8_SCHED __builtin_amdgcn_sched_barrier(0)
; template <class Epi>
; __device__ __forceinline__ void gemm_phase(LAS unsigned char* lds, const Gemm g, const StaticOrder& S, const Epi& E) {
;     ...
;             PG8_LDB(B0, 0, 0); PG8_SCHED; PG8_LDA(At, 0, 0); PG8_STAGE(PG8_SA(1, 1), a1 + hstep, voffA);
;             PG8_WAIT_L(8); PG8_BAR; PG8_WAIT_L(0); PG8_MMA(0, 0, At, B0); PG8_BAR; PG8_SCHED;
;             PG8_LDB(B1, 0, 1); PG8_STAGE(PG8_SB(0, 0), b2, voffB0);
;             PG8_BAR; PG8_WAIT_L(0); PG8_MMA(0, 1, At, B1); PG8_BAR;
;             PG8_LDA(At, 0, 1); PG8_STAGE(PG8_SA(0, 0), a2, voffA);
;             PG8_BAR; PG8_WAIT_L(0); PG8_MMA(1, 0, At, B0); PG8_BAR; PG8_SCHED;
;             PG8_STAGE(PG8_SB(0, 1), b2, voffB1);
;             PG8_WAIT_V(6); PG8_BAR; PG8_MMA(1, 1, At, B1); PG8_BAR;
;             PG8_LDB(B0, 1, 0); PG8_SCHED; PG8_LDA(At, 1, 0); PG8_STAGE(PG8_SA(0, 1), a2 + hstep, voffA);
;             PG8_WAIT_L(8); PG8_BAR; PG8_WAIT_L(0); PG8_MMA(0, 0, At, B0); PG8_BAR; PG8_SCHED;
;             PG8_LDB(B1, 1, 1); PG8_STAGE(PG8_SB(1, 0), b3, voffB0);
;             PG8_BAR; PG8_WAIT_L(0); PG8_MMA(0, 1, At, B1); PG8_BAR;
;             PG8_LDA(At, 1, 1); PG8_STAGE(PG8_SA(1, 0), a3, voffA);
;             PG8_BAR; PG8_WAIT_L(0); PG8_MMA(1, 0, At, B0); PG8_BAR; PG8_SCHED;
;             PG8_STAGE(PG8_SB(1, 1), b3, voffB1);
;             PG8_WAIT_V(6); PG8_BAR; PG8_MMA(1, 1, At, B1); PG8_BAR;
	s_waitcnt lgkmcnt(0)
	v_mfma_f32_16x16x32_bf16 v[60:63], v[160:163], v[176:179], v[60:63]
	v_mfma_f32_16x16x32_bf16 v[56:59], v[168:171], v[176:179], v[56:59]
	v_mfma_f32_16x16x32_bf16 v[44:47], v[160:163], v[184:187], v[44:47]
	v_mfma_f32_16x16x32_bf16 v[40:43], v[168:171], v[184:187], v[40:43]
	v_mfma_f32_16x16x32_bf16 v[28:31], v[160:163], v[192:195], v[28:31]
	v_mfma_f32_16x16x32_bf16 v[24:27], v[168:171], v[192:195], v[24:27]
	v_mfma_f32_16x16x32_bf16 v[12:15], v[160:163], v[204:207], v[12:15]
	v_mfma_f32_16x16x32_bf16 v[8:11], v[168:171], v[204:207], v[8:11]
	v_mfma_f32_16x16x32_bf16 v[60:63], v[164:167], v[180:183], v[60:63]
	v_mfma_f32_16x16x32_bf16 v[56:59], v[172:175], v[180:183], v[56:59]
	v_mfma_f32_16x16x32_bf16 v[44:47], v[164:167], v[188:191], v[44:47]
	v_mfma_f32_16x16x32_bf16 v[40:43], v[172:175], v[188:191], v[40:43]
	v_mfma_f32_16x16x32_bf16 v[28:31], v[164:167], v[196:199], v[28:31]
	v_mfma_f32_16x16x32_bf16 v[24:27], v[172:175], v[196:199], v[24:27]
	v_mfma_f32_16x16x32_bf16 v[12:15], v[164:167], v[208:211], v[12:15]
	v_mfma_f32_16x16x32_bf16 v[8:11], v[172:175], v[208:211], v[8:11]
	v_mfma_f32_16x16x32_bf16 v[52:55], v[212:215], v[176:179], v[52:55]
	v_mfma_f32_16x16x32_bf16 v[48:51], v[220:223], v[176:179], v[48:51]
	v_mfma_f32_16x16x32_bf16 v[36:39], v[212:215], v[184:187], v[36:39]
	v_mfma_f32_16x16x32_bf16 v[32:35], v[220:223], v[184:187], v[32:35]
	v_mfma_f32_16x16x32_bf16 v[20:23], v[212:215], v[192:195], v[20:23]
	v_mfma_f32_16x16x32_bf16 v[16:19], v[220:223], v[192:195], v[16:19]
	v_mfma_f32_16x16x32_bf16 v[4:7], v[212:215], v[204:207], v[4:7]
	v_mfma_f32_16x16x32_bf16 v[0:3], v[220:223], v[204:207], v[0:3]
	v_mfma_f32_16x16x32_bf16 v[52:55], v[216:219], v[180:183], v[52:55]
	v_mfma_f32_16x16x32_bf16 v[48:51], v[224:227], v[180:183], v[48:51]
	v_mfma_f32_16x16x32_bf16 v[36:39], v[216:219], v[188:191], v[36:39]
	v_mfma_f32_16x16x32_bf16 v[32:35], v[224:227], v[188:191], v[32:35]
	v_mfma_f32_16x16x32_bf16 v[20:23], v[216:219], v[196:199], v[20:23]
	v_mfma_f32_16x16x32_bf16 v[16:19], v[224:227], v[196:199], v[16:19]
	v_mfma_f32_16x16x32_bf16 v[4:7], v[216:219], v[208:211], v[4:7]
	v_mfma_f32_16x16x32_bf16 v[0:3], v[224:227], v[208:211], v[0:3]
	s_add_i32 s33, 0, 0x18000
	v_add_u32_e32 v172, s33, v147
	s_barrier
	ds_read_b128 v[160:163], v172
	ds_read_b128 v[164:167], v172 offset:1024
	ds_read_b128 v[168:171], v172 offset:2048
	ds_read_b128 v[172:175], v172 offset:3072
	s_add_u32 s40, s40, 0x20000
	s_addc_u32 s41, s41, 0
	s_mov_b32 m0, s52
	v_lshl_add_u64 v[212:213], s[40:41], 0, v[138:139]
	ds_read_b128 v[176:179], v158 offset:32768
	ds_read_b128 v[180:183], v158 offset:33792
	ds_read_b128 v[184:187], v158 offset:34816
	ds_read_b128 v[188:191], v158 offset:35840
	ds_read_b128 v[192:195], v158 offset:36864
	ds_read_b128 v[196:199], v158 offset:37888
	ds_read_b128 v[204:207], v158 offset:38912
	ds_read_b128 v[208:211], v158 offset:39936
	global_load_lds_dwordx4 v[212:213], off
	v_lshl_add_u64 v[212:213], s[40:41], 0, v[132:133]
	s_mov_b32 m0, s53
	s_nop 0
	global_load_lds_dwordx4 v[212:213], off
	s_waitcnt lgkmcnt(8)
	s_barrier
	s_waitcnt lgkmcnt(0)
	v_mfma_f32_16x16x32_bf16 v[124:127], v[160:163], v[176:179], v[124:127]
	v_mfma_f32_16x16x32_bf16 v[120:123], v[168:171], v[176:179], v[120:123]
	v_mfma_f32_16x16x32_bf16 v[108:111], v[160:163], v[184:187], v[108:111]
	v_mfma_f32_16x16x32_bf16 v[104:107], v[168:171], v[184:187], v[104:107]
	v_mfma_f32_16x16x32_bf16 v[92:95], v[160:163], v[192:195], v[92:95]
	v_mfma_f32_16x16x32_bf16 v[88:91], v[168:171], v[192:195], v[88:91]
	v_mfma_f32_16x16x32_bf16 v[76:79], v[160:163], v[204:207], v[76:79]
	v_mfma_f32_16x16x32_bf16 v[72:75], v[168:171], v[204:207], v[72:75]
	v_mfma_f32_16x16x32_bf16 v[124:127], v[164:167], v[180:183], v[124:127]
	v_mfma_f32_16x16x32_bf16 v[120:123], v[172:175], v[180:183], v[120:123]
	v_mfma_f32_16x16x32_bf16 v[108:111], v[164:167], v[188:191], v[108:111]
	v_mfma_f32_16x16x32_bf16 v[104:107], v[172:175], v[188:191], v[104:107]
	v_mfma_f32_16x16x32_bf16 v[92:95], v[164:167], v[196:199], v[92:95]
	v_mfma_f32_16x16x32_bf16 v[88:91], v[172:175], v[196:199], v[88:91]
	v_mfma_f32_16x16x32_bf16 v[76:79], v[164:167], v[208:211], v[76:79]
	v_mfma_f32_16x16x32_bf16 v[72:75], v[172:175], v[208:211], v[72:75]
	s_barrier
	s_add_i32 s40, 0, 0x1c000
	s_add_i32 s33, s33, s49
	v_add_u32_e32 v224, s40, v147
	v_lshl_add_u64 v[200:201], v[200:201], 0, s[8:9]
	s_mov_b32 m0, s33
	ds_read_b128 v[212:215], v224
	ds_read_b128 v[216:219], v224 offset:1024
	ds_read_b128 v[220:223], v224 offset:2048
	ds_read_b128 v[224:227], v224 offset:3072
	global_load_lds_dwordx4 v[200:201], off
	v_lshl_add_u64 v[200:201], v[228:229], 0, s[8:9]
	s_add_i32 m0, s33, 0x2000
	s_nop 0
	global_load_lds_dwordx4 v[200:201], off
	s_waitcnt lgkmcnt(0)
	s_barrier
	s_waitcnt lgkmcnt(0)
	v_mfma_f32_16x16x32_bf16 v[116:119], v[212:215], v[176:179], v[116:119]
	v_mfma_f32_16x16x32_bf16 v[112:115], v[220:223], v[176:179], v[112:115]
	v_mfma_f32_16x16x32_bf16 v[100:103], v[212:215], v[184:187], v[100:103]
	v_mfma_f32_16x16x32_bf16 v[96:99], v[220:223], v[184:187], v[96:99]
	v_mfma_f32_16x16x32_bf16 v[84:87], v[212:215], v[192:195], v[84:87]
	v_mfma_f32_16x16x32_bf16 v[80:83], v[220:223], v[192:195], v[80:83]
	v_mfma_f32_16x16x32_bf16 v[68:71], v[212:215], v[204:207], v[68:71]
	v_mfma_f32_16x16x32_bf16 v[64:67], v[220:223], v[204:207], v[64:67]
	v_mfma_f32_16x16x32_bf16 v[116:119], v[216:219], v[180:183], v[116:119]
	v_mfma_f32_16x16x32_bf16 v[112:115], v[224:227], v[180:183], v[112:115]
	v_mfma_f32_16x16x32_bf16 v[100:103], v[216:219], v[188:191], v[100:103]
	v_mfma_f32_16x16x32_bf16 v[96:99], v[224:227], v[188:191], v[96:99]
	v_mfma_f32_16x16x32_bf16 v[84:87], v[216:219], v[196:199], v[84:87]
	v_mfma_f32_16x16x32_bf16 v[80:83], v[224:227], v[196:199], v[80:83]
	v_mfma_f32_16x16x32_bf16 v[68:71], v[216:219], v[208:211], v[68:71]
	v_mfma_f32_16x16x32_bf16 v[64:67], v[224:227], v[208:211], v[64:67]
	s_mov_b32 m0, s55
	v_lshl_add_u64 v[200:201], v[230:231], 0, s[8:9]
	s_barrier
; __device__ __forceinline__ unsigned cvt_pk_bf16(float lo, float hi) { unsigned r; asm volatile("v_cvt_pk_bf16_f32 %0, %1, %2" : "=v"(r) : "v"(lo), "v"(hi)); return r; }
; #define PG8_STAGE(bufoff, gbase, voff) do { _Pragma("unroll") for (int _i = 0; _i < 2; ++_i) \
;         __builtin_amdgcn_global_load_lds((const unsigned*)((const char*)(gbase) + (voff)[_i]), (LAS unsigned*)(lds + (bufoff) + ldsw + _i * 8192), 16, 0, 0); } while (0)
; #define PG8_WAIT_V(n) asm volatile("s_waitcnt vmcnt(" #n ")" ::: "memory")
;     __device__ __forceinline__ void operator()(const f32x4 (&acc)[2][2][4][2], const Unit& u, int wr, int wc, int fr, int fq) const {
;     ...
;             for (int m = 0; m < 4; ++m) { const int row = row0 + ai * HALF + m * 16;
;                 const float rs = ssin ? __builtin_amdgcn_rsqf(ssin[row] * (1.f / D) + EPS) : 1.0f; float sq = 0.f; u32x4 w[2];
; #pragma unroll
;                 for (int bj = 0; bj < 2; ++bj) { f32x4 v0 = acc[ai][bj][m][0] * rs, v1 = acc[ai][bj][m][1] * rs;
;                     if (ACT == 1) {
; #pragma unroll
;                         for (int j = 0; j < 4; ++j) { const float a = fmaxf(v0[j], 0.f), b = fmaxf(v1[j], 0.f); v0[j] = a * a; v1[j] = b * b; } }
;                     sq += (v0[0] * v0[0] + v0[1] * v0[1]) + (v0[2] * v0[2] + v0[3] * v0[3]) + (v1[0] * v1[0] + v1[1] * v1[1]) + (v1[2] * v1[2] + v1[3] * v1[3]);
;                     w[bj].x = cvt_pk_bf16(v0[0], v0[1]); w[bj].y = cvt_pk_bf16(v0[2], v0[3]); w[bj].z = cvt_pk_bf16(v1[0], v1[1]); w[bj].w = cvt_pk_bf16(v1[2], v1[3]); }
;                 store_pair_lines(O, ldc, row, fr, col0, w[0], w[1]);
; template <class Epi>
; __device__ __forceinline__ void gemm_phase(LAS unsigned char* lds, const Gemm g, const StaticOrder& S, const Epi& E) {
;     ...
;             PG8_LDB(B0, 1, 0); PG8_SCHED; PG8_LDA(At, 1, 0); PG8_STAGE(PG8_SA(0, 1), a2 + hstep, voffA);
;             PG8_WAIT_L(8); PG8_BAR; PG8_WAIT_L(0); PG8_MMA(0, 0, At, B0); PG8_BAR; PG8_SCHED;
;             PG8_LDB(B1, 1, 1); PG8_STAGE(PG8_SB(1, 0), b3, voffB0);
;             PG8_BAR; PG8_WAIT_L(0); PG8_MMA(0, 1, At, B1); PG8_BAR;
;             PG8_LDA(At, 1, 1); PG8_STAGE(PG8_SA(1, 0), a3, voffA);
;             PG8_BAR; PG8_WAIT_L(0); PG8_MMA(1, 0, At, B0); PG8_BAR; PG8_SCHED;
;             PG8_STAGE(PG8_SB(1, 1), b3, voffB1);
;             PG8_WAIT_V(6); PG8_BAR; PG8_MMA(1, 1, At, B1); PG8_BAR;
;         }
	ds_read_b128 v[176:179], v158 offset:49152
	ds_read_b128 v[180:183], v158 offset:50176
	ds_read_b128 v[184:187], v158 offset:51200
	ds_read_b128 v[188:191], v158 offset:52224
	ds_read_b128 v[192:195], v158 offset:53248
	ds_read_b128 v[196:199], v158 offset:54272
	ds_read_b128 v[204:207], v158 offset:55296
	ds_read_b128 v[208:211], v158 offset:56320
	global_load_lds_dwordx4 v[200:201], off
	v_lshl_add_u64 v[200:201], v[232:233], 0, s[8:9]
	s_mov_b32 m0, s56
	s_nop 0
	global_load_lds_dwordx4 v[200:201], off
	s_add_i32 s33, s40, s49
	v_lshl_add_u64 v[250:251], v[234:235], 0, s[8:9]
	s_mov_b32 m0, s33
	s_nop 0
	global_load_lds_dwordx4 v[250:251], off
	v_lshl_add_u64 v[250:251], v[236:237], 0, s[8:9]
	s_add_i32 m0, s33, 0x2000
	s_nop 0
	global_load_lds_dwordx4 v[250:251], off
	s_waitcnt vmcnt(6)
	s_barrier
	s_waitcnt lgkmcnt(0)
	v_mfma_f32_16x16x32_bf16 v[60:63], v[160:163], v[176:179], v[60:63]
	v_mfma_f32_16x16x32_bf16 v[56:59], v[168:171], v[176:179], v[56:59]
	v_mfma_f32_16x16x32_bf16 v[44:47], v[160:163], v[184:187], v[44:47]
	v_mfma_f32_16x16x32_bf16 v[40:43], v[168:171], v[184:187], v[40:43]
	v_mfma_f32_16x16x32_bf16 v[28:31], v[160:163], v[192:195], v[28:31]
	v_mfma_f32_16x16x32_bf16 v[24:27], v[168:171], v[192:195], v[24:27]
	v_mfma_f32_16x16x32_bf16 v[12:15], v[160:163], v[204:207], v[12:15]
	v_mfma_f32_16x16x32_bf16 v[8:11], v[168:171], v[204:207], v[8:11]
	v_mfma_f32_16x16x32_bf16 v[60:63], v[164:167], v[180:183], v[60:63]
	v_mfma_f32_16x16x32_bf16 v[56:59], v[172:175], v[180:183], v[56:59]
	v_mfma_f32_16x16x32_bf16 v[44:47], v[164:167], v[188:191], v[44:47]
	v_mfma_f32_16x16x32_bf16 v[40:43], v[172:175], v[188:191], v[40:43]
	v_mfma_f32_16x16x32_bf16 v[28:31], v[164:167], v[196:199], v[28:31]
	v_mfma_f32_16x16x32_bf16 v[24:27], v[172:175], v[196:199], v[24:27]
	v_mfma_f32_16x16x32_bf16 v[12:15], v[164:167], v[208:211], v[12:15]
	v_mfma_f32_16x16x32_bf16 v[8:11], v[172:175], v[208:211], v[8:11]
	v_mfma_f32_16x16x32_bf16 v[52:55], v[212:215], v[176:179], v[52:55]
	v_mfma_f32_16x16x32_bf16 v[48:51], v[220:223], v[176:179], v[48:51]
	v_mfma_f32_16x16x32_bf16 v[36:39], v[212:215], v[184:187], v[36:39]
	v_mfma_f32_16x16x32_bf16 v[32:35], v[220:223], v[184:187], v[32:35]
	v_mfma_f32_16x16x32_bf16 v[20:23], v[212:215], v[192:195], v[20:23]
	v_mfma_f32_16x16x32_bf16 v[16:19], v[220:223], v[192:195], v[16:19]
	v_mfma_f32_16x16x32_bf16 v[4:7], v[212:215], v[204:207], v[4:7]
	v_mfma_f32_16x16x32_bf16 v[0:3], v[220:223], v[204:207], v[0:3]
	v_mfma_f32_16x16x32_bf16 v[52:55], v[216:219], v[180:183], v[52:55]
	v_mfma_f32_16x16x32_bf16 v[48:51], v[224:227], v[180:183], v[48:51]
	v_mfma_f32_16x16x32_bf16 v[36:39], v[216:219], v[188:191], v[36:39]
	v_mfma_f32_16x16x32_bf16 v[32:35], v[224:227], v[188:191], v[32:35]
	v_mfma_f32_16x16x32_bf16 v[20:23], v[216:219], v[196:199], v[20:23]
	v_mfma_f32_16x16x32_bf16 v[16:19], v[224:227], v[196:199], v[16:19]
	v_mfma_f32_16x16x32_bf16 v[4:7], v[216:219], v[208:211], v[4:7]
	v_mfma_f32_16x16x32_bf16 v[0:3], v[224:227], v[208:211], v[0:3]
	s_add_i32 s68, s68, 2
	s_add_u32 s38, s38, 0x100
	s_addc_u32 s39, s39, 0
	s_add_u32 s66, s66, 0x100
	s_addc_u32 s67, s67, 0
	s_cmp_gt_u32 s68, 5
	s_barrier
	s_cbranch_scc0 .LBB0_234
	s_lshl_b32 s11, s36, 8
	v_cvt_pk_bf16_f32 v124, v124, v125
	v_cvt_pk_bf16_f32 v125, v126, v127
	v_cvt_pk_bf16_f32 v120, v120, v121
	v_cvt_pk_bf16_f32 v121, v122, v123
	v_cvt_pk_bf16_f32 v122, v116, v117
	v_cvt_pk_bf16_f32 v123, v118, v119
	v_cvt_pk_bf16_f32 v112, v112, v113
	v_cvt_pk_bf16_f32 v113, v114, v115
	s_add_i32 s11, s11, s57
	v_lshl_or_b32 v162, s63, 8, v156
	v_mov_b32_dpp v114, v124 row_ror:8 row_mask:0xf bank_mask:0xf
	v_mov_b32_dpp v115, v125 row_ror:8 row_mask:0xf bank_mask:0xf
	v_mov_b32_dpp v126, v120 row_ror:8 row_mask:0xf bank_mask:0xf
	v_mov_b32_dpp v127, v121 row_ror:8 row_mask:0xf bank_mask:0xf
	v_mov_b32_dpp v118, v112 row_ror:8 row_mask:0xf bank_mask:0xf
	v_mov_b32_dpp v119, v113 row_ror:8 row_mask:0xf bank_mask:0xf
	v_ashrrev_i32_e32 v163, 31, v162
	v_mov_b32_dpp v116, v122 row_ror:8 row_mask:0xf bank_mask:0xf
	v_mov_b32_dpp v117, v123 row_ror:8 row_mask:0xf bank_mask:0xf
	v_cndmask_b32_e64 v118, v118, v120, s[4:5]
	v_cndmask_b32_e64 v119, v119, v121, s[4:5]
	v_cndmask_b32_e64 v120, v122, v114, s[4:5]
	v_cndmask_b32_e64 v121, v123, v115, s[4:5]
	v_cndmask_b32_e64 v122, v112, v126, s[4:5]
	v_cndmask_b32_e64 v123, v113, v127, s[4:5]
	v_or_b32_e32 v126, s11, v148
	v_mov_b64_e32 v[112:113], s[6:7]
	v_cndmask_b32_e64 v116, v116, v124, s[4:5]
	v_cndmask_b32_e64 v117, v117, v125, s[4:5]
	v_mad_i64_i32 v[124:125], s[38:39], v126, s62, v[112:113]
	v_lshlrev_b64 v[114:115], 1, v[162:163]
	v_lshl_add_u64 v[124:125], v[124:125], 0, v[114:115]
	global_store_dwordx4 v[124:125], v[116:119], off
	v_or_b32_e32 v160, s11, v146
	s_and_b64 vcc, exec, s[30:31]
	v_or_b32_e32 v116, 8, v126
	v_mad_i64_i32 v[116:117], s[38:39], v116, s62, v[112:113]
	v_lshl_add_u64 v[116:117], v[116:117], 0, v[114:115]
	global_store_dwordx4 v[116:117], v[120:123], off
	v_cvt_pk_bf16_f32 v108, v108, v109
	v_cvt_pk_bf16_f32 v109, v110, v111
	v_cvt_pk_bf16_f32 v104, v104, v105
	v_cvt_pk_bf16_f32 v105, v106, v107
	v_cvt_pk_bf16_f32 v100, v100, v101
	v_cvt_pk_bf16_f32 v101, v102, v103
	v_cvt_pk_bf16_f32 v102, v96, v97
	v_cvt_pk_bf16_f32 v103, v98, v99
	s_nop 0
	v_mov_b32_dpp v106, v108 row_ror:8 row_mask:0xf bank_mask:0xf
	v_mov_b32_dpp v96, v100 row_ror:8 row_mask:0xf bank_mask:0xf
	v_mov_b32_dpp v98, v102 row_ror:8 row_mask:0xf bank_mask:0xf
	v_mov_b32_dpp v99, v103 row_ror:8 row_mask:0xf bank_mask:0xf
	v_cndmask_b32_e64 v100, v100, v106, s[4:5]
	v_add_u32_e32 v106, v149, v160
	v_mov_b32_dpp v110, v104 row_ror:8 row_mask:0xf bank_mask:0xf
; __device__ __forceinline__ unsigned cvt_pk_bf16(float lo, float hi) { unsigned r; asm volatile("v_cvt_pk_bf16_f32 %0, %1, %2" : "=v"(r) : "v"(lo), "v"(hi)); return r; }
; __device__ __forceinline__ unsigned dpp_ror8(unsigned x) { return (unsigned)__builtin_amdgcn_update_dpp(0, (int)x, 0x128, 0xf, 0xf, false); }
; __device__ __forceinline__ void store_pair_lines(bf16_t* O, int ldc, int row, int fr, int col0, u32x4 wA, u32x4 wB) {
;     const u32x4 sA = {dpp_ror8(wA.x), dpp_ror8(wA.y), dpp_ror8(wA.z), dpp_ror8(wA.w)}, sB = {dpp_ror8(wB.x), dpp_ror8(wB.y), dpp_ror8(wB.z), dpp_ror8(wB.w)};
;     const bool lo = fr < 8;
;     const u32x4 o1 = lo ? wA : sB, o2 = lo ? sA : wB;
;     const int r1 = row - fr + (fr & 7), cb = col0 + (lo ? 0 : 8);
;     *(u32x4*)(O + (size_t)r1 * ldc + cb) = o1;
;     *(u32x4*)(O + (size_t)(r1 + 8) * ldc + cb) = o2;
; }
;     __device__ __forceinline__ void operator()(const f32x4 (&acc)[2][2][4][2], const Unit& u, int wr, int wc, int fr, int fq) const {
;     ...
;             for (int m = 0; m < 4; ++m) { const int row = row0 + ai * HALF + m * 16;
;                 const float rs = ssin ? __builtin_amdgcn_rsqf(ssin[row] * (1.f / D) + EPS) : 1.0f; float sq = 0.f; u32x4 w[2];
; #pragma unroll
;                 for (int bj = 0; bj < 2; ++bj) { f32x4 v0 = acc[ai][bj][m][0] * rs, v1 = acc[ai][bj][m][1] * rs;
;                     if (ACT == 1) {
; #pragma unroll
;                         for (int j = 0; j < 4; ++j) { const float a = fmaxf(v0[j], 0.f), b = fmaxf(v1[j], 0.f); v0[j] = a * a; v1[j] = b * b; } }
;                     sq += (v0[0] * v0[0] + v0[1] * v0[1]) + (v0[2] * v0[2] + v0[3] * v0[3]) + (v1[0] * v1[0] + v1[1] * v1[1]) + (v1[2] * v1[2] + v1[3] * v1[3]);
;                     w[bj].x = cvt_pk_bf16(v0[0], v0[1]); w[bj].y = cvt_pk_bf16(v0[2], v0[3]); w[bj].z = cvt_pk_bf16(v1[0], v1[1]); w[bj].w = cvt_pk_bf16(v1[2], v1[3]); }
;                 store_pair_lines(O, ldc, row, fr, col0, w[0], w[1]);
;                 if (ssout) { sq += __shfl_xor(sq, 16); sq += __shfl_xor(sq, 32); if (fq == 0) unsafeAtomicAdd(ssout + row, sq); } }
	v_mov_b32_dpp v111, v105 row_ror:8 row_mask:0xf bank_mask:0xf
	v_mov_b32_dpp v97, v101 row_ror:8 row_mask:0xf bank_mask:0xf
	v_cndmask_b32_e64 v98, v98, v104, s[4:5]
	v_cndmask_b32_e64 v99, v99, v105, s[4:5]
	v_mad_i64_i32 v[104:105], s[38:39], v106, s62, v[112:113]
	v_cndmask_b32_e64 v96, v96, v108, s[4:5]
	v_cndmask_b32_e64 v97, v97, v109, s[4:5]
	v_lshl_add_u64 v[104:105], v[104:105], 0, v[114:115]
	global_store_dwordx4 v[104:105], v[96:99], off
	v_cndmask_b32_e64 v102, v102, v110, s[4:5]
	v_mov_b32_dpp v107, v109 row_ror:8 row_mask:0xf bank_mask:0xf
	v_add_u32_e32 v96, 8, v106
	v_mad_i64_i32 v[96:97], s[38:39], v96, s62, v[112:113]
	v_cndmask_b32_e64 v101, v101, v107, s[4:5]
	v_cndmask_b32_e64 v103, v103, v111, s[4:5]
	v_lshl_add_u64 v[96:97], v[96:97], 0, v[114:115]
	global_store_dwordx4 v[96:97], v[100:103], off
	v_cvt_pk_bf16_f32 v92, v92, v93
	v_cvt_pk_bf16_f32 v93, v94, v95
	v_cvt_pk_bf16_f32 v88, v88, v89
	v_cvt_pk_bf16_f32 v89, v90, v91
	v_cvt_pk_bf16_f32 v84, v84, v85
	v_cvt_pk_bf16_f32 v85, v86, v87
	v_cvt_pk_bf16_f32 v86, v80, v81
	v_cvt_pk_bf16_f32 v87, v82, v83
	s_nop 0
	v_mov_b32_dpp v90, v92 row_ror:8 row_mask:0xf bank_mask:0xf
	v_mov_b32_dpp v80, v84 row_ror:8 row_mask:0xf bank_mask:0xf
	v_mov_b32_dpp v82, v86 row_ror:8 row_mask:0xf bank_mask:0xf
	v_mov_b32_dpp v83, v87 row_ror:8 row_mask:0xf bank_mask:0xf
	v_cndmask_b32_e64 v84, v84, v90, s[4:5]
	v_add_u32_e32 v90, v150, v160
	v_mov_b32_dpp v94, v88 row_ror:8 row_mask:0xf bank_mask:0xf
	v_mov_b32_dpp v95, v89 row_ror:8 row_mask:0xf bank_mask:0xf
	v_mov_b32_dpp v81, v85 row_ror:8 row_mask:0xf bank_mask:0xf
	v_cndmask_b32_e64 v82, v82, v88, s[4:5]
	v_cndmask_b32_e64 v83, v83, v89, s[4:5]
	v_mad_i64_i32 v[88:89], s[38:39], v90, s62, v[112:113]
	v_cndmask_b32_e64 v80, v80, v92, s[4:5]
	v_cndmask_b32_e64 v81, v81, v93, s[4:5]
	v_lshl_add_u64 v[88:89], v[88:89], 0, v[114:115]
	global_store_dwordx4 v[88:89], v[80:83], off
	v_cndmask_b32_e64 v86, v86, v94, s[4:5]
	v_mov_b32_dpp v91, v93 row_ror:8 row_mask:0xf bank_mask:0xf
	v_add_u32_e32 v80, 8, v90
	v_mad_i64_i32 v[80:81], s[38:39], v80, s62, v[112:113]
	v_cndmask_b32_e64 v85, v85, v91, s[4:5]
	v_cndmask_b32_e64 v87, v87, v95, s[4:5]
	v_lshl_add_u64 v[80:81], v[80:81], 0, v[114:115]
	global_store_dwordx4 v[80:81], v[84:87], off
	v_cvt_pk_bf16_f32 v76, v76, v77
	v_cvt_pk_bf16_f32 v77, v78, v79
	v_cvt_pk_bf16_f32 v72, v72, v73
	v_cvt_pk_bf16_f32 v73, v74, v75
	v_cvt_pk_bf16_f32 v68, v68, v69
	v_cvt_pk_bf16_f32 v69, v70, v71
	v_cvt_pk_bf16_f32 v70, v64, v65
	v_cvt_pk_bf16_f32 v71, v66, v67
	s_nop 0
	v_mov_b32_dpp v74, v76 row_ror:8 row_mask:0xf bank_mask:0xf
	v_mov_b32_dpp v64, v68 row_ror:8 row_mask:0xf bank_mask:0xf
	v_mov_b32_dpp v66, v70 row_ror:8 row_mask:0xf bank_mask:0xf
	v_mov_b32_dpp v67, v71 row_ror:8 row_mask:0xf bank_mask:0xf
	v_cndmask_b32_e64 v68, v68, v74, s[4:5]
	v_add_u32_e32 v74, v151, v160
	v_mov_b32_dpp v78, v72 row_ror:8 row_mask:0xf bank_mask:0xf
	v_mov_b32_dpp v79, v73 row_ror:8 row_mask:0xf bank_mask:0xf
	v_mov_b32_dpp v65, v69 row_ror:8 row_mask:0xf bank_mask:0xf
	v_cndmask_b32_e64 v66, v66, v72, s[4:5]
	v_cndmask_b32_e64 v67, v67, v73, s[4:5]
	v_mad_i64_i32 v[72:73], s[38:39], v74, s62, v[112:113]
	v_cndmask_b32_e64 v64, v64, v76, s[4:5]
	v_cndmask_b32_e64 v65, v65, v77, s[4:5]
	v_lshl_add_u64 v[72:73], v[72:73], 0, v[114:115]
	global_store_dwordx4 v[72:73], v[64:67], off
	v_cndmask_b32_e64 v70, v70, v78, s[4:5]
	v_mov_b32_dpp v75, v77 row_ror:8 row_mask:0xf bank_mask:0xf
	v_add_u32_e32 v64, 8, v74
	v_mad_i64_i32 v[64:65], s[38:39], v64, s62, v[112:113]
	v_cndmask_b32_e64 v69, v69, v75, s[4:5]
	v_cndmask_b32_e64 v71, v71, v79, s[4:5]
	v_lshl_add_u64 v[64:65], v[64:65], 0, v[114:115]
	global_store_dwordx4 v[64:65], v[68:71], off
	v_cvt_pk_bf16_f32 v60, v60, v61
	v_cvt_pk_bf16_f32 v61, v62, v63
	v_cvt_pk_bf16_f32 v56, v56, v57
	v_cvt_pk_bf16_f32 v57, v58, v59
	v_cvt_pk_bf16_f32 v52, v52, v53
	v_cvt_pk_bf16_f32 v53, v54, v55
	v_cvt_pk_bf16_f32 v54, v48, v49
	v_cvt_pk_bf16_f32 v55, v50, v51
	s_nop 0
	v_mov_b32_dpp v58, v60 row_ror:8 row_mask:0xf bank_mask:0xf
	v_mov_b32_dpp v48, v52 row_ror:8 row_mask:0xf bank_mask:0xf
	v_mov_b32_dpp v50, v54 row_ror:8 row_mask:0xf bank_mask:0xf
	v_mov_b32_dpp v51, v55 row_ror:8 row_mask:0xf bank_mask:0xf
	v_cndmask_b32_e64 v52, v52, v58, s[4:5]
	v_add_u32_e32 v58, v152, v160
	v_mov_b32_dpp v62, v56 row_ror:8 row_mask:0xf bank_mask:0xf
	v_mov_b32_dpp v63, v57 row_ror:8 row_mask:0xf bank_mask:0xf
	v_mov_b32_dpp v49, v53 row_ror:8 row_mask:0xf bank_mask:0xf
	v_cndmask_b32_e64 v50, v50, v56, s[4:5]
	v_cndmask_b32_e64 v51, v51, v57, s[4:5]
	v_mad_i64_i32 v[56:57], s[38:39], v58, s62, v[112:113]
	v_cndmask_b32_e64 v48, v48, v60, s[4:5]
	v_cndmask_b32_e64 v49, v49, v61, s[4:5]
	v_lshl_add_u64 v[56:57], v[56:57], 0, v[114:115]
	global_store_dwordx4 v[56:57], v[48:51], off
; __device__ __forceinline__ unsigned cvt_pk_bf16(float lo, float hi) { unsigned r; asm volatile("v_cvt_pk_bf16_f32 %0, %1, %2" : "=v"(r) : "v"(lo), "v"(hi)); return r; }
; __device__ __forceinline__ unsigned dpp_ror8(unsigned x) { return (unsigned)__builtin_amdgcn_update_dpp(0, (int)x, 0x128, 0xf, 0xf, false); }
; __device__ __forceinline__ void store_pair_lines(bf16_t* O, int ldc, int row, int fr, int col0, u32x4 wA, u32x4 wB) {
;     const u32x4 sA = {dpp_ror8(wA.x), dpp_ror8(wA.y), dpp_ror8(wA.z), dpp_ror8(wA.w)}, sB = {dpp_ror8(wB.x), dpp_ror8(wB.y), dpp_ror8(wB.z), dpp_ror8(wB.w)};
;     const bool lo = fr < 8;
;     const u32x4 o1 = lo ? wA : sB, o2 = lo ? sA : wB;
;     const int r1 = row - fr + (fr & 7), cb = col0 + (lo ? 0 : 8);
;     *(u32x4*)(O + (size_t)r1 * ldc + cb) = o1;
;     *(u32x4*)(O + (size_t)(r1 + 8) * ldc + cb) = o2;
; }
;     __device__ __forceinline__ void operator()(const f32x4 (&acc)[2][2][4][2], const Unit& u, int wr, int wc, int fr, int fq) const {
;     ...
;             for (int m = 0; m < 4; ++m) { const int row = row0 + ai * HALF + m * 16;
;                 const float rs = ssin ? __builtin_amdgcn_rsqf(ssin[row] * (1.f / D) + EPS) : 1.0f; float sq = 0.f; u32x4 w[2];
; #pragma unroll
;                 for (int bj = 0; bj < 2; ++bj) { f32x4 v0 = acc[ai][bj][m][0] * rs, v1 = acc[ai][bj][m][1] * rs;
;                     if (ACT == 1) {
; #pragma unroll
;                         for (int j = 0; j < 4; ++j) { const float a = fmaxf(v0[j], 0.f), b = fmaxf(v1[j], 0.f); v0[j] = a * a; v1[j] = b * b; } }
;                     sq += (v0[0] * v0[0] + v0[1] * v0[1]) + (v0[2] * v0[2] + v0[3] * v0[3]) + (v1[0] * v1[0] + v1[1] * v1[1]) + (v1[2] * v1[2] + v1[3] * v1[3]);
;                     w[bj].x = cvt_pk_bf16(v0[0], v0[1]); w[bj].y = cvt_pk_bf16(v0[2], v0[3]); w[bj].z = cvt_pk_bf16(v1[0], v1[1]); w[bj].w = cvt_pk_bf16(v1[2], v1[3]); }
;                 store_pair_lines(O, ldc, row, fr, col0, w[0], w[1]);
;                 if (ssout) { sq += __shfl_xor(sq, 16); sq += __shfl_xor(sq, 32); if (fq == 0) unsafeAtomicAdd(ssout + row, sq); } }
	v_cndmask_b32_e64 v54, v54, v62, s[4:5]
	v_mov_b32_dpp v59, v61 row_ror:8 row_mask:0xf bank_mask:0xf
	v_add_u32_e32 v48, 8, v58
	v_mad_i64_i32 v[48:49], s[38:39], v48, s62, v[112:113]
	v_cndmask_b32_e64 v53, v53, v59, s[4:5]
	v_cndmask_b32_e64 v55, v55, v63, s[4:5]
	v_lshl_add_u64 v[48:49], v[48:49], 0, v[114:115]
	global_store_dwordx4 v[48:49], v[52:55], off
	v_cvt_pk_bf16_f32 v44, v44, v45
	v_cvt_pk_bf16_f32 v45, v46, v47
	v_cvt_pk_bf16_f32 v40, v40, v41
	v_cvt_pk_bf16_f32 v41, v42, v43
	v_cvt_pk_bf16_f32 v36, v36, v37
	v_cvt_pk_bf16_f32 v37, v38, v39
	v_cvt_pk_bf16_f32 v38, v32, v33
	v_cvt_pk_bf16_f32 v39, v34, v35
	s_nop 0
	v_mov_b32_dpp v42, v44 row_ror:8 row_mask:0xf bank_mask:0xf
	v_mov_b32_dpp v32, v36 row_ror:8 row_mask:0xf bank_mask:0xf
	v_mov_b32_dpp v34, v38 row_ror:8 row_mask:0xf bank_mask:0xf
	v_mov_b32_dpp v35, v39 row_ror:8 row_mask:0xf bank_mask:0xf
	v_cndmask_b32_e64 v36, v36, v42, s[4:5]
	v_add_u32_e32 v42, v153, v160
	v_mov_b32_dpp v46, v40 row_ror:8 row_mask:0xf bank_mask:0xf
	v_mov_b32_dpp v47, v41 row_ror:8 row_mask:0xf bank_mask:0xf
	v_mov_b32_dpp v33, v37 row_ror:8 row_mask:0xf bank_mask:0xf
	v_cndmask_b32_e64 v34, v34, v40, s[4:5]
	v_cndmask_b32_e64 v35, v35, v41, s[4:5]
	v_mad_i64_i32 v[40:41], s[38:39], v42, s62, v[112:113]
	v_cndmask_b32_e64 v32, v32, v44, s[4:5]
	v_cndmask_b32_e64 v33, v33, v45, s[4:5]
	v_lshl_add_u64 v[40:41], v[40:41], 0, v[114:115]
	global_store_dwordx4 v[40:41], v[32:35], off
	v_cndmask_b32_e64 v38, v38, v46, s[4:5]
	v_mov_b32_dpp v43, v45 row_ror:8 row_mask:0xf bank_mask:0xf
	v_add_u32_e32 v32, 8, v42
	v_mad_i64_i32 v[32:33], s[38:39], v32, s62, v[112:113]
	v_cndmask_b32_e64 v37, v37, v43, s[4:5]
	v_cndmask_b32_e64 v39, v39, v47, s[4:5]
	v_lshl_add_u64 v[32:33], v[32:33], 0, v[114:115]
	global_store_dwordx4 v[32:33], v[36:39], off
	v_cvt_pk_bf16_f32 v28, v28, v29
	v_cvt_pk_bf16_f32 v29, v30, v31
	v_cvt_pk_bf16_f32 v24, v24, v25
	v_cvt_pk_bf16_f32 v25, v26, v27
	v_cvt_pk_bf16_f32 v20, v20, v21
	v_cvt_pk_bf16_f32 v21, v22, v23
	v_cvt_pk_bf16_f32 v22, v16, v17
	v_cvt_pk_bf16_f32 v23, v18, v19
	s_nop 0
	v_mov_b32_dpp v26, v28 row_ror:8 row_mask:0xf bank_mask:0xf
	v_mov_b32_dpp v16, v20 row_ror:8 row_mask:0xf bank_mask:0xf
	v_mov_b32_dpp v18, v22 row_ror:8 row_mask:0xf bank_mask:0xf
	v_mov_b32_dpp v19, v23 row_ror:8 row_mask:0xf bank_mask:0xf
	v_cndmask_b32_e64 v20, v20, v26, s[4:5]
	v_add_u32_e32 v26, v154, v160
	v_mov_b32_dpp v30, v24 row_ror:8 row_mask:0xf bank_mask:0xf
	v_mov_b32_dpp v31, v25 row_ror:8 row_mask:0xf bank_mask:0xf
	v_mov_b32_dpp v17, v21 row_ror:8 row_mask:0xf bank_mask:0xf
	v_cndmask_b32_e64 v18, v18, v24, s[4:5]
	v_cndmask_b32_e64 v19, v19, v25, s[4:5]
	v_mad_i64_i32 v[24:25], s[38:39], v26, s62, v[112:113]
	v_cndmask_b32_e64 v16, v16, v28, s[4:5]
	v_cndmask_b32_e64 v17, v17, v29, s[4:5]
	v_lshl_add_u64 v[24:25], v[24:25], 0, v[114:115]
	global_store_dwordx4 v[24:25], v[16:19], off
	v_cndmask_b32_e64 v22, v22, v30, s[4:5]
	v_mov_b32_dpp v27, v29 row_ror:8 row_mask:0xf bank_mask:0xf
	v_add_u32_e32 v16, 8, v26
	v_mad_i64_i32 v[16:17], s[38:39], v16, s62, v[112:113]
	v_cndmask_b32_e64 v21, v21, v27, s[4:5]
	v_cndmask_b32_e64 v23, v23, v31, s[4:5]
	v_lshl_add_u64 v[16:17], v[16:17], 0, v[114:115]
	global_store_dwordx4 v[16:17], v[20:23], off
	v_cvt_pk_bf16_f32 v12, v12, v13
	v_cvt_pk_bf16_f32 v13, v14, v15
	v_cvt_pk_bf16_f32 v8, v8, v9
	v_cvt_pk_bf16_f32 v9, v10, v11
	v_cvt_pk_bf16_f32 v4, v4, v5
	v_cvt_pk_bf16_f32 v5, v6, v7
	v_cvt_pk_bf16_f32 v6, v0, v1
	v_cvt_pk_bf16_f32 v7, v2, v3
	s_nop 0
	v_mov_b32_dpp v10, v12 row_ror:8 row_mask:0xf bank_mask:0xf
	v_mov_b32_dpp v0, v4 row_ror:8 row_mask:0xf bank_mask:0xf
	v_mov_b32_dpp v2, v6 row_ror:8 row_mask:0xf bank_mask:0xf
	v_mov_b32_dpp v3, v7 row_ror:8 row_mask:0xf bank_mask:0xf
	v_cndmask_b32_e64 v4, v4, v10, s[4:5]
	v_add_u32_e32 v10, v155, v160
	v_mov_b32_dpp v14, v8 row_ror:8 row_mask:0xf bank_mask:0xf
	v_mov_b32_dpp v15, v9 row_ror:8 row_mask:0xf bank_mask:0xf
	v_mov_b32_dpp v1, v5 row_ror:8 row_mask:0xf bank_mask:0xf
	v_cndmask_b32_e64 v2, v2, v8, s[4:5]
	v_cndmask_b32_e64 v3, v3, v9, s[4:5]
	v_mad_i64_i32 v[8:9], s[38:39], v10, s62, v[112:113]
	v_cndmask_b32_e64 v0, v0, v12, s[4:5]
	v_cndmask_b32_e64 v1, v1, v13, s[4:5]
	v_lshl_add_u64 v[8:9], v[8:9], 0, v[114:115]
	global_store_dwordx4 v[8:9], v[0:3], off
	v_cndmask_b32_e64 v6, v6, v14, s[4:5]
	v_mov_b32_dpp v11, v13 row_ror:8 row_mask:0xf bank_mask:0xf
	v_add_u32_e32 v0, 8, v10
	v_mad_i64_i32 v[0:1], s[38:39], v0, s62, v[112:113]
	v_cndmask_b32_e64 v5, v5, v11, s[4:5]
	v_cndmask_b32_e64 v7, v7, v15, s[4:5]
	v_lshl_add_u64 v[0:1], v[0:1], 0, v[114:115]
	s_mov_b32 s63, s10
	s_mov_b32 s36, s16
	s_mov_b64 s[40:41], s[34:35]
	s_mov_b64 s[38:39], s[18:19]
	global_store_dwordx4 v[0:1], v[4:7], off
	s_cbranch_vccz .LBB0_230
	s_waitcnt vmcnt(0)
	s_cmpk_gt_u32 s44, 0xff
	s_cbranch_scc1 .LBB0_238
	s_barrier

; #define PG8_STAGE(bufoff, gbase, voff) do { _Pragma("unroll") for (int _i = 0; _i < 2; ++_i) \
;         __builtin_amdgcn_global_load_lds((const unsigned*)((const char*)(gbase) + (voff)[_i]), (LAS unsigned*)(lds + (bufoff) + ldsw + _i * 8192), 16, 0, 0); } while (0)
; #define PG8_LDA(dst, b, h) do { _Pragma("unroll") for (int m = 0; m < 4; ++m) _Pragma("unroll") for (int k = 0; k < 2; ++k) dst[m][k] = *(const LAS bf16x8*)(lds + PG8_SA(b, h) + aoff + m * 2048 + k * 1024); } while (0)
; #define PG8_LDB(dst, b, h) do { _Pragma("unroll") for (int n = 0; n < 2; ++n) _Pragma("unroll") for (int k = 0; k < 2; ++k) dst[n][k] = *(const LAS bf16x8*)(lds + PG8_SB(b, h) + boff + n * 2048 + k * 1024); } while (0)
; #define PG8_MMA(ai, bj, At, Bt) do { __builtin_amdgcn_s_setprio(1); _Pragma("unroll") for (int m = 0; m < 4; ++m) _Pragma("unroll") for (int n = 0; n < 2; ++n) _Pragma("unroll") for (int k = 0; k < 2; ++k) \
;         acc[ai][bj][m][n] = __builtin_amdgcn_mfma_f32_16x16x32_bf16(Bt[n][k], At[m][k], acc[ai][bj][m][n], 0, 0, 0); __builtin_amdgcn_s_setprio(0); } while (0)
; #define PG8_WAIT_V(n) asm volatile("s_waitcnt vmcnt(" #n ")" ::: "memory")
; #define PG8_WAIT_L(n) asm volatile("s_waitcnt lgkmcnt(" #n ")" ::: "memory")
; #define PG8_BAR __builtin_amdgcn_s_barrier()
; #define PG8_SCHED __builtin_amdgcn_sched_barrier(0)
; template <class Epi>
; __device__ __forceinline__ void gemm_phase(LAS unsigned char* lds, const Gemm g, const StaticOrder& S, const Epi& E) {
;     ...
;             PG8_LDB(B0, 0, 0); PG8_SCHED; PG8_LDA(At, 0, 0); PG8_STAGE(PG8_SA(1, 1), a1 + hstep, voffA);
;             PG8_WAIT_L(8); PG8_BAR; PG8_WAIT_L(0); PG8_MMA(0, 0, At, B0); PG8_BAR; PG8_SCHED;
;             PG8_LDB(B1, 0, 1); PG8_STAGE(PG8_SB(0, 0), b2, voffB0);
;             PG8_BAR; PG8_WAIT_L(0); PG8_MMA(0, 1, At, B1); PG8_BAR;
;             PG8_LDA(At, 0, 1); PG8_STAGE(PG8_SA(0, 0), a2, voffA);
;             PG8_BAR; PG8_WAIT_L(0); PG8_MMA(1, 0, At, B0); PG8_BAR; PG8_SCHED;
;             PG8_STAGE(PG8_SB(0, 1), b2, voffB1);
;             PG8_WAIT_V(6); PG8_BAR; PG8_MMA(1, 1, At, B1); PG8_BAR;
.LBB0_613:
	ds_read_b128 v[146:149], v155
	ds_read_b128 v[158:161], v155 offset:1024
	ds_read_b128 v[162:165], v155 offset:2048
	ds_read_b128 v[166:169], v155 offset:3072
	s_add_u32 s33, s54, 0xfff80080
	s_addc_u32 s56, s55, -1
	s_cmp_eq_u32 s88, 28
	s_cselect_b32 s57, s43, s56
	s_cselect_b32 s56, s51, s33
	s_cselect_b32 s59, s41, s87
	s_cselect_b32 s58, s85, s86
	v_lshl_add_u64 v[204:205], s[54:55], 0, v[140:141]
	s_add_i32 m0, s53, 0xc000
	ds_read_b128 v[170:173], v156
	ds_read_b128 v[174:177], v156 offset:1024
	ds_read_b128 v[178:181], v156 offset:2048
	ds_read_b128 v[182:185], v156 offset:3072
	ds_read_b128 v[186:189], v156 offset:4096
	ds_read_b128 v[190:193], v156 offset:5120
	ds_read_b128 v[194:197], v156 offset:6144
	ds_read_b128 v[198:201], v156 offset:7168
	global_load_lds_dwordx4 v[204:205], off
	v_lshl_add_u64 v[204:205], s[54:55], 0, v[142:143]
	s_add_i32 m0, s53, 0xe000
	s_nop 0
	global_load_lds_dwordx4 v[204:205], off
	s_waitcnt lgkmcnt(8)
	s_barrier
	s_waitcnt lgkmcnt(0)
	v_mfma_f32_16x16x32_bf16 v[124:127], v[146:149], v[170:173], v[124:127]
	v_mfma_f32_16x16x32_bf16 v[120:123], v[162:165], v[170:173], v[120:123]
	v_mfma_f32_16x16x32_bf16 v[108:111], v[146:149], v[178:181], v[108:111]
	v_mfma_f32_16x16x32_bf16 v[104:107], v[162:165], v[178:181], v[104:107]
	v_mfma_f32_16x16x32_bf16 v[92:95], v[146:149], v[186:189], v[92:95]
	v_mfma_f32_16x16x32_bf16 v[88:91], v[162:165], v[186:189], v[88:91]
	v_mfma_f32_16x16x32_bf16 v[76:79], v[146:149], v[194:197], v[76:79]
	v_mfma_f32_16x16x32_bf16 v[72:75], v[162:165], v[194:197], v[72:75]
	v_mfma_f32_16x16x32_bf16 v[124:127], v[158:161], v[174:177], v[124:127]
	v_mfma_f32_16x16x32_bf16 v[120:123], v[166:169], v[174:177], v[120:123]
	v_mfma_f32_16x16x32_bf16 v[108:111], v[158:161], v[182:185], v[108:111]
	v_mfma_f32_16x16x32_bf16 v[104:107], v[166:169], v[182:185], v[104:107]
	v_mfma_f32_16x16x32_bf16 v[92:95], v[158:161], v[190:193], v[92:95]
	v_mfma_f32_16x16x32_bf16 v[88:91], v[166:169], v[190:193], v[88:91]
	v_mfma_f32_16x16x32_bf16 v[76:79], v[158:161], v[198:201], v[76:79]
	v_mfma_f32_16x16x32_bf16 v[72:75], v[166:169], v[198:201], v[72:75]
	s_barrier
	s_add_i32 s33, s79, s65
	v_lshl_add_u64 v[220:221], s[58:59], 0, v[130:131]
	s_mov_b32 m0, s33
	ds_read_b128 v[204:207], v157
	ds_read_b128 v[208:211], v157 offset:1024
	ds_read_b128 v[212:215], v157 offset:2048
	ds_read_b128 v[216:219], v157 offset:3072
	global_load_lds_dwordx4 v[220:221], off
	v_lshl_add_u64 v[222:223], s[58:59], 0, v[136:137]
	s_add_i32 m0, s33, 0x2000
	s_nop 0
	global_load_lds_dwordx4 v[222:223], off
	s_waitcnt lgkmcnt(0)
	s_barrier
	s_waitcnt lgkmcnt(0)
	v_mfma_f32_16x16x32_bf16 v[116:119], v[204:207], v[170:173], v[116:119]
	v_mfma_f32_16x16x32_bf16 v[112:115], v[212:215], v[170:173], v[112:115]
	v_mfma_f32_16x16x32_bf16 v[100:103], v[204:207], v[178:181], v[100:103]
	v_mfma_f32_16x16x32_bf16 v[96:99], v[212:215], v[178:181], v[96:99]
	v_mfma_f32_16x16x32_bf16 v[84:87], v[204:207], v[186:189], v[84:87]
	v_mfma_f32_16x16x32_bf16 v[80:83], v[212:215], v[186:189], v[80:83]
	v_mfma_f32_16x16x32_bf16 v[68:71], v[204:207], v[194:197], v[68:71]
	v_mfma_f32_16x16x32_bf16 v[64:67], v[212:215], v[194:197], v[64:67]
	v_mfma_f32_16x16x32_bf16 v[116:119], v[208:211], v[174:177], v[116:119]
	v_mfma_f32_16x16x32_bf16 v[112:115], v[216:219], v[174:177], v[112:115]
	v_mfma_f32_16x16x32_bf16 v[100:103], v[208:211], v[182:185], v[100:103]
	v_mfma_f32_16x16x32_bf16 v[96:99], v[216:219], v[182:185], v[96:99]
	v_mfma_f32_16x16x32_bf16 v[84:87], v[208:211], v[190:193], v[84:87]
	v_mfma_f32_16x16x32_bf16 v[80:83], v[216:219], v[190:193], v[80:83]
	v_mfma_f32_16x16x32_bf16 v[68:71], v[208:211], v[198:201], v[68:71]
	v_mfma_f32_16x16x32_bf16 v[64:67], v[216:219], v[198:201], v[64:67]
	s_mov_b32 m0, s53
	v_lshl_add_u64 v[224:225], s[56:57], 0, v[128:129]
	s_barrier
	ds_read_b128 v[170:173], v156 offset:16384
	ds_read_b128 v[174:177], v156 offset:17408
	ds_read_b128 v[178:181], v156 offset:18432
	ds_read_b128 v[182:185], v156 offset:19456
	ds_read_b128 v[186:189], v156 offset:20480
	ds_read_b128 v[190:193], v156 offset:21504
	ds_read_b128 v[194:197], v156 offset:22528
	ds_read_b128 v[198:201], v156 offset:23552
	global_load_lds_dwordx4 v[224:225], off
	v_lshl_add_u64 v[226:227], s[56:57], 0, v[134:135]
	s_mov_b32 m0, s66
	s_nop 0
	global_load_lds_dwordx4 v[226:227], off
	s_add_i32 s33, s80, s65
	v_lshl_add_u64 v[228:229], s[58:59], 0, v[132:133]
	s_mov_b32 m0, s33
	v_lshl_add_u64 v[230:231], s[58:59], 0, v[138:139]
	global_load_lds_dwordx4 v[228:229], off
	s_add_i32 m0, s33, 0x2000
	s_nop 0
	global_load_lds_dwordx4 v[230:231], off
	s_waitcnt vmcnt(6)
	s_barrier
; #define PG8_STAGE(bufoff, gbase, voff) do { _Pragma("unroll") for (int _i = 0; _i < 2; ++_i) \
;         __builtin_amdgcn_global_load_lds((const unsigned*)((const char*)(gbase) + (voff)[_i]), (LAS unsigned*)(lds + (bufoff) + ldsw + _i * 8192), 16, 0, 0); } while (0)
; #define PG8_LDA(dst, b, h) do { _Pragma("unroll") for (int m = 0; m < 4; ++m) _Pragma("unroll") for (int k = 0; k < 2; ++k) dst[m][k] = *(const LAS bf16x8*)(lds + PG8_SA(b, h) + aoff + m * 2048 + k * 1024); } while (0)
; #define PG8_LDB(dst, b, h) do { _Pragma("unroll") for (int n = 0; n < 2; ++n) _Pragma("unroll") for (int k = 0; k < 2; ++k) dst[n][k] = *(const LAS bf16x8*)(lds + PG8_SB(b, h) + boff + n * 2048 + k * 1024); } while (0)
; #define PG8_MMA(ai, bj, At, Bt) do { __builtin_amdgcn_s_setprio(1); _Pragma("unroll") for (int m = 0; m < 4; ++m) _Pragma("unroll") for (int n = 0; n < 2; ++n) _Pragma("unroll") for (int k = 0; k < 2; ++k) \
;         acc[ai][bj][m][n] = __builtin_amdgcn_mfma_f32_16x16x32_bf16(Bt[n][k], At[m][k], acc[ai][bj][m][n], 0, 0, 0); __builtin_amdgcn_s_setprio(0); } while (0)
; #define PG8_WAIT_V(n) asm volatile("s_waitcnt vmcnt(" #n ")" ::: "memory")
; #define PG8_WAIT_L(n) asm volatile("s_waitcnt lgkmcnt(" #n ")" ::: "memory")
; #define PG8_BAR __builtin_amdgcn_s_barrier()
; #define PG8_SCHED __builtin_amdgcn_sched_barrier(0)
; template <class Epi>
; __device__ __forceinline__ void gemm_phase(LAS unsigned char* lds, const Gemm g, const StaticOrder& S, const Epi& E) {
;     ...
;             PG8_BAR; PG8_WAIT_L(0); PG8_MMA(0, 1, At, B1); PG8_BAR;
;             PG8_LDA(At, 0, 1); PG8_STAGE(PG8_SA(0, 0), a2, voffA);
;             PG8_BAR; PG8_WAIT_L(0); PG8_MMA(1, 0, At, B0); PG8_BAR; PG8_SCHED;
;             PG8_STAGE(PG8_SB(0, 1), b2, voffB1);
;             PG8_WAIT_V(6); PG8_BAR; PG8_MMA(1, 1, At, B1); PG8_BAR;
;             PG8_LDB(B0, 1, 0); PG8_SCHED; PG8_LDA(At, 1, 0); PG8_STAGE(PG8_SA(0, 1), a2 + hstep, voffA);
;             PG8_WAIT_L(8); PG8_BAR; PG8_WAIT_L(0); PG8_MMA(0, 0, At, B0); PG8_BAR; PG8_SCHED;
;             PG8_LDB(B1, 1, 1); PG8_STAGE(PG8_SB(1, 0), b3, voffB0);
;             PG8_BAR; PG8_WAIT_L(0); PG8_MMA(0, 1, At, B1); PG8_BAR;
;             PG8_LDA(At, 1, 1); PG8_STAGE(PG8_SA(1, 0), a3, voffA);
;             PG8_BAR; PG8_WAIT_L(0); PG8_MMA(1, 0, At, B0); PG8_BAR; PG8_SCHED;
	s_waitcnt lgkmcnt(0)
	v_mfma_f32_16x16x32_bf16 v[60:63], v[146:149], v[170:173], v[60:63]
	v_mfma_f32_16x16x32_bf16 v[56:59], v[162:165], v[170:173], v[56:59]
	v_mfma_f32_16x16x32_bf16 v[44:47], v[146:149], v[178:181], v[44:47]
	v_mfma_f32_16x16x32_bf16 v[40:43], v[162:165], v[178:181], v[40:43]
	v_mfma_f32_16x16x32_bf16 v[28:31], v[146:149], v[186:189], v[28:31]
	v_mfma_f32_16x16x32_bf16 v[24:27], v[162:165], v[186:189], v[24:27]
	v_mfma_f32_16x16x32_bf16 v[12:15], v[146:149], v[194:197], v[12:15]
	v_mfma_f32_16x16x32_bf16 v[8:11], v[162:165], v[194:197], v[8:11]
	v_mfma_f32_16x16x32_bf16 v[60:63], v[158:161], v[174:177], v[60:63]
	v_mfma_f32_16x16x32_bf16 v[56:59], v[166:169], v[174:177], v[56:59]
	v_mfma_f32_16x16x32_bf16 v[44:47], v[158:161], v[182:185], v[44:47]
	v_mfma_f32_16x16x32_bf16 v[40:43], v[166:169], v[182:185], v[40:43]
	v_mfma_f32_16x16x32_bf16 v[28:31], v[158:161], v[190:193], v[28:31]
	v_mfma_f32_16x16x32_bf16 v[24:27], v[166:169], v[190:193], v[24:27]
	v_mfma_f32_16x16x32_bf16 v[12:15], v[158:161], v[198:201], v[12:15]
	v_mfma_f32_16x16x32_bf16 v[8:11], v[166:169], v[198:201], v[8:11]
	v_mfma_f32_16x16x32_bf16 v[52:55], v[204:207], v[170:173], v[52:55]
	v_mfma_f32_16x16x32_bf16 v[48:51], v[212:215], v[170:173], v[48:51]
	v_mfma_f32_16x16x32_bf16 v[36:39], v[204:207], v[178:181], v[36:39]
	v_mfma_f32_16x16x32_bf16 v[32:35], v[212:215], v[178:181], v[32:35]
	v_mfma_f32_16x16x32_bf16 v[20:23], v[204:207], v[186:189], v[20:23]
	v_mfma_f32_16x16x32_bf16 v[16:19], v[212:215], v[186:189], v[16:19]
	v_mfma_f32_16x16x32_bf16 v[4:7], v[204:207], v[194:197], v[4:7]
	v_mfma_f32_16x16x32_bf16 v[0:3], v[212:215], v[194:197], v[0:3]
	v_mfma_f32_16x16x32_bf16 v[52:55], v[208:211], v[174:177], v[52:55]
	v_mfma_f32_16x16x32_bf16 v[48:51], v[216:219], v[174:177], v[48:51]
	v_mfma_f32_16x16x32_bf16 v[36:39], v[208:211], v[182:185], v[36:39]
	v_mfma_f32_16x16x32_bf16 v[32:35], v[216:219], v[182:185], v[32:35]
	v_mfma_f32_16x16x32_bf16 v[20:23], v[208:211], v[190:193], v[20:23]
	v_mfma_f32_16x16x32_bf16 v[16:19], v[216:219], v[190:193], v[16:19]
	v_mfma_f32_16x16x32_bf16 v[4:7], v[208:211], v[198:201], v[4:7]
	v_mfma_f32_16x16x32_bf16 v[0:3], v[216:219], v[198:201], v[0:3]
	s_add_i32 s33, 0, 0x18000
	v_add_u32_e32 v166, s33, v151
	s_barrier
	ds_read_b128 v[146:149], v166
	ds_read_b128 v[158:161], v166 offset:1024
	ds_read_b128 v[162:165], v166 offset:2048
	ds_read_b128 v[166:169], v166 offset:3072
	s_add_u32 s56, s56, 0x80000
	s_addc_u32 s57, s57, 0
	s_mov_b32 m0, s67
	v_lshl_add_u64 v[204:205], s[56:57], 0, v[128:129]
	ds_read_b128 v[170:173], v156 offset:32768
	ds_read_b128 v[174:177], v156 offset:33792
	ds_read_b128 v[178:181], v156 offset:34816
	ds_read_b128 v[182:185], v156 offset:35840
	ds_read_b128 v[186:189], v156 offset:36864
	ds_read_b128 v[190:193], v156 offset:37888
	ds_read_b128 v[194:197], v156 offset:38912
	ds_read_b128 v[198:201], v156 offset:39936
	global_load_lds_dwordx4 v[204:205], off
	v_lshl_add_u64 v[204:205], s[56:57], 0, v[134:135]
	s_mov_b32 m0, s68
	s_nop 0
	global_load_lds_dwordx4 v[204:205], off
	s_waitcnt lgkmcnt(8)
	s_barrier
	s_waitcnt lgkmcnt(0)
	v_mfma_f32_16x16x32_bf16 v[124:127], v[146:149], v[170:173], v[124:127]
	v_mfma_f32_16x16x32_bf16 v[120:123], v[162:165], v[170:173], v[120:123]
	v_mfma_f32_16x16x32_bf16 v[108:111], v[146:149], v[178:181], v[108:111]
	v_mfma_f32_16x16x32_bf16 v[104:107], v[162:165], v[178:181], v[104:107]
	v_mfma_f32_16x16x32_bf16 v[92:95], v[146:149], v[186:189], v[92:95]
	v_mfma_f32_16x16x32_bf16 v[88:91], v[162:165], v[186:189], v[88:91]
	v_mfma_f32_16x16x32_bf16 v[76:79], v[146:149], v[194:197], v[76:79]
	v_mfma_f32_16x16x32_bf16 v[72:75], v[162:165], v[194:197], v[72:75]
	v_mfma_f32_16x16x32_bf16 v[124:127], v[158:161], v[174:177], v[124:127]
	v_mfma_f32_16x16x32_bf16 v[120:123], v[166:169], v[174:177], v[120:123]
	v_mfma_f32_16x16x32_bf16 v[108:111], v[158:161], v[182:185], v[108:111]
	v_mfma_f32_16x16x32_bf16 v[104:107], v[166:169], v[182:185], v[104:107]
	v_mfma_f32_16x16x32_bf16 v[92:95], v[158:161], v[190:193], v[92:95]
	v_mfma_f32_16x16x32_bf16 v[88:91], v[166:169], v[190:193], v[88:91]
	v_mfma_f32_16x16x32_bf16 v[76:79], v[158:161], v[198:201], v[76:79]
	v_mfma_f32_16x16x32_bf16 v[72:75], v[166:169], v[198:201], v[72:75]
	s_barrier
	s_add_i32 s56, 0, 0x1c000
	s_add_i32 s33, s33, s65
	v_add_u32_e32 v216, s56, v151
	v_lshl_add_u64 v[220:221], v[220:221], 0, s[36:37]
	s_mov_b32 m0, s33
	ds_read_b128 v[204:207], v216
	ds_read_b128 v[208:211], v216 offset:1024
	ds_read_b128 v[212:215], v216 offset:2048
	ds_read_b128 v[216:219], v216 offset:3072
	global_load_lds_dwordx4 v[220:221], off
	v_lshl_add_u64 v[220:221], v[222:223], 0, s[36:37]
	s_add_i32 m0, s33, 0x2000
	s_nop 0
	global_load_lds_dwordx4 v[220:221], off
	s_waitcnt lgkmcnt(0)
	s_barrier
	s_waitcnt lgkmcnt(0)
	v_mfma_f32_16x16x32_bf16 v[116:119], v[204:207], v[170:173], v[116:119]
	v_mfma_f32_16x16x32_bf16 v[112:115], v[212:215], v[170:173], v[112:115]
	v_mfma_f32_16x16x32_bf16 v[100:103], v[204:207], v[178:181], v[100:103]
	v_mfma_f32_16x16x32_bf16 v[96:99], v[212:215], v[178:181], v[96:99]
	v_mfma_f32_16x16x32_bf16 v[84:87], v[204:207], v[186:189], v[84:87]
	v_mfma_f32_16x16x32_bf16 v[80:83], v[212:215], v[186:189], v[80:83]
	v_mfma_f32_16x16x32_bf16 v[68:71], v[204:207], v[194:197], v[68:71]
	v_mfma_f32_16x16x32_bf16 v[64:67], v[212:215], v[194:197], v[64:67]
	v_mfma_f32_16x16x32_bf16 v[116:119], v[208:211], v[174:177], v[116:119]
	v_mfma_f32_16x16x32_bf16 v[112:115], v[216:219], v[174:177], v[112:115]
	v_mfma_f32_16x16x32_bf16 v[100:103], v[208:211], v[182:185], v[100:103]
	v_mfma_f32_16x16x32_bf16 v[96:99], v[216:219], v[182:185], v[96:99]
	v_mfma_f32_16x16x32_bf16 v[84:87], v[208:211], v[190:193], v[84:87]
	v_mfma_f32_16x16x32_bf16 v[80:83], v[216:219], v[190:193], v[80:83]
	v_mfma_f32_16x16x32_bf16 v[68:71], v[208:211], v[198:201], v[68:71]
	v_mfma_f32_16x16x32_bf16 v[64:67], v[216:219], v[198:201], v[64:67]
	s_mov_b32 m0, s72
	v_lshl_add_u64 v[220:221], v[224:225], 0, s[36:37]
	s_barrier
; #define PG8_STAGE(bufoff, gbase, voff) do { _Pragma("unroll") for (int _i = 0; _i < 2; ++_i) \
;         __builtin_amdgcn_global_load_lds((const unsigned*)((const char*)(gbase) + (voff)[_i]), (LAS unsigned*)(lds + (bufoff) + ldsw + _i * 8192), 16, 0, 0); } while (0)
; #define PG8_LDA(dst, b, h) do { _Pragma("unroll") for (int m = 0; m < 4; ++m) _Pragma("unroll") for (int k = 0; k < 2; ++k) dst[m][k] = *(const LAS bf16x8*)(lds + PG8_SA(b, h) + aoff + m * 2048 + k * 1024); } while (0)
; #define PG8_MMA(ai, bj, At, Bt) do { __builtin_amdgcn_s_setprio(1); _Pragma("unroll") for (int m = 0; m < 4; ++m) _Pragma("unroll") for (int n = 0; n < 2; ++n) _Pragma("unroll") for (int k = 0; k < 2; ++k) \
;         acc[ai][bj][m][n] = __builtin_amdgcn_mfma_f32_16x16x32_bf16(Bt[n][k], At[m][k], acc[ai][bj][m][n], 0, 0, 0); __builtin_amdgcn_s_setprio(0); } while (0)
; #define PG8_WAIT_V(n) asm volatile("s_waitcnt vmcnt(" #n ")" ::: "memory")
; #define PG8_WAIT_L(n) asm volatile("s_waitcnt lgkmcnt(" #n ")" ::: "memory")
; #define PG8_BAR __builtin_amdgcn_s_barrier()
; #define PG8_SCHED __builtin_amdgcn_sched_barrier(0)
; template <class Epi>
; __device__ __forceinline__ void gemm_phase(LAS unsigned char* lds, const Gemm g, const StaticOrder& S, const Epi& E) {
;     ...
;             PG8_LDA(At, 1, 1); PG8_STAGE(PG8_SA(1, 0), a3, voffA);
;             PG8_BAR; PG8_WAIT_L(0); PG8_MMA(1, 0, At, B0); PG8_BAR; PG8_SCHED;
;             PG8_STAGE(PG8_SB(1, 1), b3, voffB1);
;             PG8_WAIT_V(6); PG8_BAR; PG8_MMA(1, 1, At, B1); PG8_BAR;
;         }
	ds_read_b128 v[170:173], v156 offset:49152
	ds_read_b128 v[174:177], v156 offset:50176
	ds_read_b128 v[178:181], v156 offset:51200
	ds_read_b128 v[182:185], v156 offset:52224
	ds_read_b128 v[186:189], v156 offset:53248
	ds_read_b128 v[190:193], v156 offset:54272
	ds_read_b128 v[194:197], v156 offset:55296
	ds_read_b128 v[198:201], v156 offset:56320
	global_load_lds_dwordx4 v[220:221], off
	v_lshl_add_u64 v[220:221], v[226:227], 0, s[36:37]
	s_mov_b32 m0, s73
	s_nop 0
	global_load_lds_dwordx4 v[220:221], off
	s_add_i32 s33, s56, s65
	v_lshl_add_u64 v[250:251], v[228:229], 0, s[36:37]
	s_mov_b32 m0, s33
	s_nop 0
	global_load_lds_dwordx4 v[250:251], off
	v_lshl_add_u64 v[250:251], v[230:231], 0, s[36:37]
	s_add_i32 m0, s33, 0x2000
	s_nop 0
	global_load_lds_dwordx4 v[250:251], off
	s_waitcnt vmcnt(6)
	s_barrier
	s_waitcnt lgkmcnt(0)
	v_mfma_f32_16x16x32_bf16 v[60:63], v[146:149], v[170:173], v[60:63]
	v_mfma_f32_16x16x32_bf16 v[56:59], v[162:165], v[170:173], v[56:59]
	v_mfma_f32_16x16x32_bf16 v[44:47], v[146:149], v[178:181], v[44:47]
	v_mfma_f32_16x16x32_bf16 v[40:43], v[162:165], v[178:181], v[40:43]
	v_mfma_f32_16x16x32_bf16 v[28:31], v[146:149], v[186:189], v[28:31]
	v_mfma_f32_16x16x32_bf16 v[24:27], v[162:165], v[186:189], v[24:27]
	v_mfma_f32_16x16x32_bf16 v[12:15], v[146:149], v[194:197], v[12:15]
	v_mfma_f32_16x16x32_bf16 v[8:11], v[162:165], v[194:197], v[8:11]
	v_mfma_f32_16x16x32_bf16 v[60:63], v[158:161], v[174:177], v[60:63]
	v_mfma_f32_16x16x32_bf16 v[56:59], v[166:169], v[174:177], v[56:59]
	v_mfma_f32_16x16x32_bf16 v[44:47], v[158:161], v[182:185], v[44:47]
	v_mfma_f32_16x16x32_bf16 v[40:43], v[166:169], v[182:185], v[40:43]
	v_mfma_f32_16x16x32_bf16 v[28:31], v[158:161], v[190:193], v[28:31]
	v_mfma_f32_16x16x32_bf16 v[24:27], v[166:169], v[190:193], v[24:27]
	v_mfma_f32_16x16x32_bf16 v[12:15], v[158:161], v[198:201], v[12:15]
	v_mfma_f32_16x16x32_bf16 v[8:11], v[166:169], v[198:201], v[8:11]
	v_mfma_f32_16x16x32_bf16 v[52:55], v[204:207], v[170:173], v[52:55]
	v_mfma_f32_16x16x32_bf16 v[48:51], v[212:215], v[170:173], v[48:51]
	v_mfma_f32_16x16x32_bf16 v[36:39], v[204:207], v[178:181], v[36:39]
	v_mfma_f32_16x16x32_bf16 v[32:35], v[212:215], v[178:181], v[32:35]
	v_mfma_f32_16x16x32_bf16 v[20:23], v[204:207], v[186:189], v[20:23]
	v_mfma_f32_16x16x32_bf16 v[16:19], v[212:215], v[186:189], v[16:19]
	v_mfma_f32_16x16x32_bf16 v[4:7], v[204:207], v[194:197], v[4:7]
	v_mfma_f32_16x16x32_bf16 v[0:3], v[212:215], v[194:197], v[0:3]
	v_mfma_f32_16x16x32_bf16 v[52:55], v[208:211], v[174:177], v[52:55]
	v_mfma_f32_16x16x32_bf16 v[48:51], v[216:219], v[174:177], v[48:51]
	v_mfma_f32_16x16x32_bf16 v[36:39], v[208:211], v[182:185], v[36:39]
	v_mfma_f32_16x16x32_bf16 v[32:35], v[216:219], v[182:185], v[32:35]
	v_mfma_f32_16x16x32_bf16 v[20:23], v[208:211], v[190:193], v[20:23]
	v_mfma_f32_16x16x32_bf16 v[16:19], v[216:219], v[190:193], v[16:19]
	v_mfma_f32_16x16x32_bf16 v[4:7], v[208:211], v[198:201], v[4:7]
	v_mfma_f32_16x16x32_bf16 v[0:3], v[216:219], v[198:201], v[0:3]
	s_add_i32 s88, s88, 2
	s_add_u32 s54, s54, 0x100
	s_addc_u32 s55, s55, 0
	s_add_u32 s86, s86, 0x100
	s_addc_u32 s87, s87, 0
	s_cmp_gt_u32 s88, 29
	s_barrier
	s_cbranch_scc0 .LBB0_613
; __device__ __forceinline__ unsigned cvt_pk_bf16(float lo, float hi) { unsigned r; asm volatile("v_cvt_pk_bf16_f32 %0, %1, %2" : "=v"(r) : "v"(lo), "v"(hi)); return r; }
; __device__ __forceinline__ float bflo(unsigned w) { return __uint_as_float(w << 16); }
; __device__ __forceinline__ void store_pair_lines(bf16_t* O, int ldc, int row, int fr, int col0, u32x4 wA, u32x4 wB) {
;     const u32x4 sA = {dpp_ror8(wA.x), dpp_ror8(wA.y), dpp_ror8(wA.z), dpp_ror8(wA.w)}, sB = {dpp_ror8(wB.x), dpp_ror8(wB.y), dpp_ror8(wB.z), dpp_ror8(wB.w)};
;     const bool lo = fr < 8;
;     const u32x4 o1 = lo ? wA : sB, o2 = lo ? sA : wB;
;     const int r1 = row - fr + (fr & 7), cb = col0 + (lo ? 0 : 8);
;     *(u32x4*)(O + (size_t)r1 * ldc + cb) = o1;
;     *(u32x4*)(O + (size_t)(r1 + 8) * ldc + cb) = o2;
; }
;     __device__ __forceinline__ void operator()(const f32x4 (&acc)[2][2][4][2], const Unit& u, int wr, int wc, int fr, int fq) const {
;     ...
;             for (int m = 0; m < 4; ++m) { const int row = row0 + ai * HALF + m * 16; const size_t off = (size_t)row * D + col0; float sq = 0.f; u32x4 w[2];
;                 const float sc = rsin ? __builtin_amdgcn_rcpf(rsin[row] * (1.f / D) + EPS) : 1.0f;
;                 u32x4 rr[2]; if (R) load_pair_lines(R, D, row, fr, col0, rr[0], rr[1]);
; #pragma unroll
;                 for (int bj = 0; bj < 2; ++bj) { f32x4 r0, r1;
;                     if (R) { const u32x4 rw = rr[bj]; r0 = (f32x4){bflo(rw.x), bfhi(rw.x), bflo(rw.y), bfhi(rw.y)}; r1 = (f32x4){bflo(rw.z), bfhi(rw.z), bflo(rw.w), bfhi(rw.w)}; }
;                     else { const float* rp = (row < 8192 ? src_p + off : src_s + (off - (size_t)8192 * D)) + 8 * bj; r0 = *(const f32x4*)rp; r1 = *(const f32x4*)(rp + 4); }
;                     const f32x4 o0 = r0 + acc[ai][bj][m][0] * sc, o1 = r1 + acc[ai][bj][m][1] * sc;
;                     sq += (o0[0] * o0[0] + o0[1] * o0[1]) + (o0[2] * o0[2] + o0[3] * o0[3]) + (o1[0] * o1[0] + o1[1] * o1[1]) + (o1[2] * o1[2] + o1[3] * o1[3]);
;                     w[bj].x = cvt_pk_bf16(o0[0], o0[1]); w[bj].y = cvt_pk_bf16(o0[2], o0[3]); w[bj].z = cvt_pk_bf16(o1[0], o1[1]); w[bj].w = cvt_pk_bf16(o1[2], o1[3]); }
;                 store_pair_lines(O, D, row, fr, col0, w[0], w[1]);
;                 if (ssout) { sq += __shfl_xor(sq, 16); sq += __shfl_xor(sq, 32); if (fq == 0) unsafeAtomicAdd(ssout + row, sq); } }
	s_lshl_b32 s33, s52, 8
	s_add_i32 s33, s33, s74
	v_or_b32_e32 v146, s33, v150
	v_lshl_or_b32 v148, s50, 8, v154
	v_ashrrev_i32_e32 v147, 31, v146
	v_ashrrev_i32_e32 v149, 31, v148
	v_lshlrev_b64 v[158:159], 11, v[146:147]
	v_lshl_add_u64 v[158:159], v[158:159], 0, v[148:149]
	v_lshlrev_b64 v[158:159], 2, v[158:159]
	v_lshl_add_u64 v[160:161], s[16:17], 0, v[158:159]
	v_lshl_add_u64 v[158:159], s[18:19], 0, v[158:159]
	v_lshl_add_u64 v[158:159], v[158:159], 0, s[38:39]
	v_cmp_gt_i32_e32 vcc, s70, v146
	v_mov_b32_e32 v183, 0
	v_mov_b32_e32 v184, 0
	v_cndmask_b32_e32 v167, v159, v161, vcc
	v_cndmask_b32_e32 v166, v158, v160, vcc
	global_load_dwordx4 v[158:161], v[166:167], off
	global_load_dwordx4 v[162:165], v[166:167], off offset:16
	v_or_b32_e32 v188, 16, v146
	v_ashrrev_i32_e32 v189, 31, v188
	v_lshlrev_b64 v[190:191], 11, v[188:189]
	v_lshl_add_u64 v[190:191], v[190:191], 0, v[148:149]
	v_lshlrev_b64 v[190:191], 2, v[190:191]
	v_lshl_add_u64 v[192:193], s[16:17], 0, v[190:191]
	v_lshl_add_u64 v[190:191], s[18:19], 0, v[190:191]
	v_lshl_add_u64 v[190:191], v[190:191], 0, s[38:39]
	v_cmp_gt_i32_e32 vcc, s70, v188
	s_nop 1
	v_cndmask_b32_e32 v195, v191, v193, vcc
	v_cndmask_b32_e32 v194, v190, v192, vcc
	global_load_dwordx4 v[196:199], v[194:195], off
	global_load_dwordx4 v[204:207], v[194:195], off offset:16
	global_load_dwordx4 v[208:211], v[194:195], off offset:32
	global_load_dwordx4 v[212:215], v[194:195], off offset:48
	v_or_b32_e32 v188, 32, v146
	v_ashrrev_i32_e32 v189, 31, v188
	v_lshlrev_b64 v[190:191], 11, v[188:189]
	v_lshl_add_u64 v[190:191], v[190:191], 0, v[148:149]
	v_lshlrev_b64 v[190:191], 2, v[190:191]
	v_lshl_add_u64 v[192:193], s[16:17], 0, v[190:191]
	v_lshl_add_u64 v[190:191], s[18:19], 0, v[190:191]
	v_lshl_add_u64 v[190:191], v[190:191], 0, s[38:39]
	v_cmp_gt_i32_e32 vcc, s70, v188
	s_nop 1
	v_cndmask_b32_e32 v195, v191, v193, vcc
	v_cndmask_b32_e32 v194, v190, v192, vcc
	global_load_dwordx4 v[216:219], v[194:195], off
	global_load_dwordx4 v[220:223], v[194:195], off offset:16
	global_load_dwordx4 v[224:227], v[194:195], off offset:32
	global_load_dwordx4 v[228:231], v[194:195], off offset:48
	v_or_b32_e32 v188, 48, v146
	v_ashrrev_i32_e32 v189, 31, v188
	v_lshlrev_b64 v[190:191], 11, v[188:189]
	v_lshl_add_u64 v[190:191], v[190:191], 0, v[148:149]
	v_lshlrev_b64 v[190:191], 2, v[190:191]
	v_lshl_add_u64 v[192:193], s[16:17], 0, v[190:191]
	v_lshl_add_u64 v[190:191], s[18:19], 0, v[190:191]
	v_lshl_add_u64 v[190:191], v[190:191], 0, s[38:39]
	v_cmp_gt_i32_e32 vcc, s70, v188
	s_nop 1
	v_cndmask_b32_e32 v195, v191, v193, vcc
	v_cndmask_b32_e32 v194, v190, v192, vcc
	global_load_dwordx4 v[232:235], v[194:195], off
	global_load_dwordx4 v[236:239], v[194:195], off offset:16
	global_load_dwordx4 v[240:243], v[194:195], off offset:32
	global_load_dwordx4 v[244:247], v[194:195], off offset:48
	s_waitcnt vmcnt(12)
	v_pk_add_f32 v[168:169], v[126:127], v[160:161]
	v_pk_add_f32 v[170:171], v[124:125], v[158:159]
	v_pk_add_f32 v[164:165], v[122:123], v[164:165]
	v_pk_add_f32 v[162:163], v[120:121], v[162:163]
	v_cvt_pk_bf16_f32 v123, v170, v171
	v_cvt_pk_bf16_f32 v176, v168, v169
	v_mul_f32_e32 v171, v171, v171
	v_cvt_pk_bf16_f32 v177, v162, v163
	v_cvt_pk_bf16_f32 v178, v164, v165
	global_load_dwordx4 v[124:127], v[166:167], off offset:32
	global_load_dwordx4 v[158:161], v[166:167], off offset:48
	v_mul_f32_e32 v169, v169, v169
	v_and_b32_e32 v121, 64, v203
	v_mul_f32_e32 v163, v163, v163
	v_fmac_f32_e32 v171, v170, v170
	v_fmac_f32_e32 v169, v168, v168
	v_xor_b32_e32 v122, 16, v203
	v_add_u32_e32 v172, 64, v121
	v_mul_f32_e32 v165, v165, v165
	v_fmac_f32_e32 v163, v162, v162
	v_add_f32_e32 v162, v171, v169
	v_cmp_lt_i32_e32 vcc, v122, v172
	v_fmac_f32_e32 v165, v164, v164
	v_add_f32_e32 v162, v163, v162
	v_cndmask_b32_e32 v122, v203, v122, vcc
	v_add_f32_e32 v162, v165, v162
	v_xor_b32_e32 v167, 32, v203
	v_lshlrev_b32_e32 v122, 2, v122
	v_or_b32_e32 v166, s33, v152
	v_cmp_lt_i32_e32 vcc, v167, v172
	v_or_b32_e32 v120, v148, v153
	v_ashrrev_i32_e32 v121, 31, v120
	v_cndmask_b32_e32 v187, v203, v167, vcc
	v_ashrrev_i32_e32 v167, 31, v166
	v_or_b32_e32 v174, 8, v166
	v_lshlrev_b64 v[166:167], 12, v[166:167]
	v_lshlrev_b64 v[172:173], 1, v[120:121]
	v_lshl_add_u64 v[166:167], s[10:11], 0, v[166:167]
	v_lshl_add_u64 v[166:167], v[166:167], 0, v[172:173]
	v_ashrrev_i32_e32 v175, 31, v174
	v_mov_b32_dpp v179, v123 row_ror:8 row_mask:0xf bank_mask:0xf
	v_mov_b32_dpp v180, v176 row_ror:8 row_mask:0xf bank_mask:0xf
	v_mov_b32_dpp v181, v177 row_ror:8 row_mask:0xf bank_mask:0xf
	v_mov_b32_dpp v182, v178 row_ror:8 row_mask:0xf bank_mask:0xf
	s_waitcnt vmcnt(0)
	v_pk_add_f32 v[126:127], v[118:119], v[126:127]
	v_pk_add_f32 v[124:125], v[116:117], v[124:125]
	v_pk_add_f32 v[112:113], v[112:113], v[158:159]
	v_cvt_pk_bf16_f32 v116, v124, v125
	v_cvt_pk_bf16_f32 v117, v126, v127
	v_mul_f32_e32 v125, v125, v125
	v_mul_f32_e32 v127, v127, v127
	v_pk_add_f32 v[114:115], v[114:115], v[160:161]
	v_mul_f32_e32 v158, v113, v113
	v_fmac_f32_e32 v125, v124, v124
	v_fmac_f32_e32 v127, v126, v126
	v_cvt_pk_bf16_f32 v118, v112, v113
	v_cvt_pk_bf16_f32 v119, v114, v115
	v_mul_f32_e32 v115, v115, v115
	v_fmac_f32_e32 v158, v112, v112
	v_add_f32_e32 v112, v125, v127
	v_fmac_f32_e32 v115, v114, v114
	v_add_f32_e32 v112, v158, v112
	v_add_f32_e32 v112, v115, v112
	v_add_f32_e32 v124, v162, v112
	ds_bpermute_b32 v125, v122, v124
	v_mov_b32_dpp v183, v116 row_ror:8 row_mask:0xf bank_mask:0xf
	v_mov_b32_dpp v184, v117 row_ror:8 row_mask:0xf bank_mask:0xf
	v_mov_b32_dpp v185, v118 row_ror:8 row_mask:0xf bank_mask:0xf
	v_mov_b32_dpp v186, v119 row_ror:8 row_mask:0xf bank_mask:0xf
	v_cndmask_b32_e64 v113, v184, v176, s[6:7]
	v_cndmask_b32_e64 v115, v186, v178, s[6:7]
	v_cndmask_b32_e64 v112, v183, v123, s[6:7]
	v_cndmask_b32_e64 v114, v185, v177, s[6:7]
	global_store_dwordx4 v[166:167], v[112:115], off
	v_cndmask_b32_e64 v117, v117, v180, s[6:7]
	v_cndmask_b32_e64 v119, v119, v182, s[6:7]
	s_waitcnt lgkmcnt(0)
	v_add_f32_e32 v112, v124, v125
	v_lshlrev_b32_e32 v114, 2, v187
	ds_bpermute_b32 v113, v114, v112
	v_lshlrev_b64 v[124:125], 12, v[174:175]
	v_lshl_add_u64 v[124:125], s[10:11], 0, v[124:125]
	v_cndmask_b32_e64 v116, v116, v179, s[6:7]
	v_cndmask_b32_e64 v118, v118, v181, s[6:7]
	v_lshl_add_u64 v[124:125], v[124:125], 0, v[172:173]
	global_store_dwordx4 v[124:125], v[116:119], off
	s_and_saveexec_b64 s[50:51], s[8:9]
	s_cbranch_execz .LBB0_616
	s_waitcnt lgkmcnt(0)
	v_add_f32_e32 v115, v112, v113
	v_lshl_add_u64 v[112:113], v[146:147], 2, s[12:13]
	global_atomic_add_f32 v[112:113], v115, off

; #define PG8_STAGE(bufoff, gbase, voff) do { _Pragma("unroll") for (int _i = 0; _i < 2; ++_i) \
;         __builtin_amdgcn_global_load_lds((const unsigned*)((const char*)(gbase) + (voff)[_i]), (LAS unsigned*)(lds + (bufoff) + ldsw + _i * 8192), 16, 0, 0); } while (0)
; #define PG8_LDA(dst, b, h) do { _Pragma("unroll") for (int m = 0; m < 4; ++m) _Pragma("unroll") for (int k = 0; k < 2; ++k) dst[m][k] = *(const LAS bf16x8*)(lds + PG8_SA(b, h) + aoff + m * 2048 + k * 1024); } while (0)
; #define PG8_LDB(dst, b, h) do { _Pragma("unroll") for (int n = 0; n < 2; ++n) _Pragma("unroll") for (int k = 0; k < 2; ++k) dst[n][k] = *(const LAS bf16x8*)(lds + PG8_SB(b, h) + boff + n * 2048 + k * 1024); } while (0)
; #define PG8_MMA(ai, bj, At, Bt) do { __builtin_amdgcn_s_setprio(1); _Pragma("unroll") for (int m = 0; m < 4; ++m) _Pragma("unroll") for (int n = 0; n < 2; ++n) _Pragma("unroll") for (int k = 0; k < 2; ++k) \
;         acc[ai][bj][m][n] = __builtin_amdgcn_mfma_f32_16x16x32_bf16(Bt[n][k], At[m][k], acc[ai][bj][m][n], 0, 0, 0); __builtin_amdgcn_s_setprio(0); } while (0)
; #define PG8_WAIT_V(n) asm volatile("s_waitcnt vmcnt(" #n ")" ::: "memory")
; #define PG8_WAIT_L(n) asm volatile("s_waitcnt lgkmcnt(" #n ")" ::: "memory")
; #define PG8_BAR __builtin_amdgcn_s_barrier()
; #define PG8_SCHED __builtin_amdgcn_sched_barrier(0)
; template <class Epi>
; __device__ __forceinline__ void gemm_phase(LAS unsigned char* lds, const Gemm g, const StaticOrder& S, const Epi& E) {
;     ...
;             PG8_LDB(B0, 0, 0); PG8_SCHED; PG8_LDA(At, 0, 0); PG8_STAGE(PG8_SA(1, 1), a1 + hstep, voffA);
;             PG8_WAIT_L(8); PG8_BAR; PG8_WAIT_L(0); PG8_MMA(0, 0, At, B0); PG8_BAR; PG8_SCHED;
;             PG8_LDB(B1, 0, 1); PG8_STAGE(PG8_SB(0, 0), b2, voffB0);
;             PG8_BAR; PG8_WAIT_L(0); PG8_MMA(0, 1, At, B1); PG8_BAR;
;             PG8_LDA(At, 0, 1); PG8_STAGE(PG8_SA(0, 0), a2, voffA);
;             PG8_BAR; PG8_WAIT_L(0); PG8_MMA(1, 0, At, B0); PG8_BAR; PG8_SCHED;
;             PG8_STAGE(PG8_SB(0, 1), b2, voffB1);
;             PG8_WAIT_V(6); PG8_BAR; PG8_MMA(1, 1, At, B1); PG8_BAR;
.LBB0_733:
	ds_read_b128 v[160:163], v157
	ds_read_b128 v[164:167], v157 offset:1024
	ds_read_b128 v[168:171], v157 offset:2048
	ds_read_b128 v[172:175], v157 offset:3072
	s_add_u32 s33, s46, 0xfff80080
	s_addc_u32 s48, s47, -1
	s_cmp_eq_u32 s74, 28
	s_cselect_b32 s49, s37, s48
	s_cselect_b32 s48, s70, s33
	s_cselect_b32 s51, s19, s73
	s_cselect_b32 s50, s71, s72
	v_lshl_add_u64 v[200:201], s[46:47], 0, v[140:141]
	s_add_i32 m0, s45, 0xc000
	ds_read_b128 v[176:179], v158
	ds_read_b128 v[180:183], v158 offset:1024
	ds_read_b128 v[184:187], v158 offset:2048
	ds_read_b128 v[188:191], v158 offset:3072
	ds_read_b128 v[192:195], v158 offset:4096
	ds_read_b128 v[196:199], v158 offset:5120
	ds_read_b128 v[204:207], v158 offset:6144
	ds_read_b128 v[208:211], v158 offset:7168
	global_load_lds_dwordx4 v[200:201], off
	v_lshl_add_u64 v[200:201], s[46:47], 0, v[142:143]
	s_add_i32 m0, s45, 0xe000
	s_nop 0
	global_load_lds_dwordx4 v[200:201], off
	s_waitcnt lgkmcnt(8)
	s_barrier
	s_waitcnt lgkmcnt(0)
	v_mfma_f32_16x16x32_bf16 v[124:127], v[160:163], v[176:179], v[124:127]
	v_mfma_f32_16x16x32_bf16 v[120:123], v[168:171], v[176:179], v[120:123]
	v_mfma_f32_16x16x32_bf16 v[108:111], v[160:163], v[184:187], v[108:111]
	v_mfma_f32_16x16x32_bf16 v[104:107], v[168:171], v[184:187], v[104:107]
	v_mfma_f32_16x16x32_bf16 v[92:95], v[160:163], v[192:195], v[92:95]
	v_mfma_f32_16x16x32_bf16 v[88:91], v[168:171], v[192:195], v[88:91]
	v_mfma_f32_16x16x32_bf16 v[76:79], v[160:163], v[204:207], v[76:79]
	v_mfma_f32_16x16x32_bf16 v[72:75], v[168:171], v[204:207], v[72:75]
	v_mfma_f32_16x16x32_bf16 v[124:127], v[164:167], v[180:183], v[124:127]
	v_mfma_f32_16x16x32_bf16 v[120:123], v[172:175], v[180:183], v[120:123]
	v_mfma_f32_16x16x32_bf16 v[108:111], v[164:167], v[188:191], v[108:111]
	v_mfma_f32_16x16x32_bf16 v[104:107], v[172:175], v[188:191], v[104:107]
	v_mfma_f32_16x16x32_bf16 v[92:95], v[164:167], v[196:199], v[92:95]
	v_mfma_f32_16x16x32_bf16 v[88:91], v[172:175], v[196:199], v[88:91]
	v_mfma_f32_16x16x32_bf16 v[76:79], v[164:167], v[208:211], v[76:79]
	v_mfma_f32_16x16x32_bf16 v[72:75], v[172:175], v[208:211], v[72:75]
	s_barrier
	s_add_i32 s33, s66, s56
	v_lshl_add_u64 v[200:201], s[50:51], 0, v[130:131]
	s_mov_b32 m0, s33
	ds_read_b128 v[212:215], v159
	ds_read_b128 v[216:219], v159 offset:1024
	ds_read_b128 v[220:223], v159 offset:2048
	ds_read_b128 v[224:227], v159 offset:3072
	global_load_lds_dwordx4 v[200:201], off
	v_lshl_add_u64 v[228:229], s[50:51], 0, v[136:137]
	s_add_i32 m0, s33, 0x2000
	s_nop 0
	global_load_lds_dwordx4 v[228:229], off
	s_waitcnt lgkmcnt(0)
	s_barrier
	s_waitcnt lgkmcnt(0)
	v_mfma_f32_16x16x32_bf16 v[116:119], v[212:215], v[176:179], v[116:119]
	v_mfma_f32_16x16x32_bf16 v[112:115], v[220:223], v[176:179], v[112:115]
	v_mfma_f32_16x16x32_bf16 v[100:103], v[212:215], v[184:187], v[100:103]
	v_mfma_f32_16x16x32_bf16 v[96:99], v[220:223], v[184:187], v[96:99]
	v_mfma_f32_16x16x32_bf16 v[84:87], v[212:215], v[192:195], v[84:87]
	v_mfma_f32_16x16x32_bf16 v[80:83], v[220:223], v[192:195], v[80:83]
	v_mfma_f32_16x16x32_bf16 v[68:71], v[212:215], v[204:207], v[68:71]
	v_mfma_f32_16x16x32_bf16 v[64:67], v[220:223], v[204:207], v[64:67]
	v_mfma_f32_16x16x32_bf16 v[116:119], v[216:219], v[180:183], v[116:119]
	v_mfma_f32_16x16x32_bf16 v[112:115], v[224:227], v[180:183], v[112:115]
	v_mfma_f32_16x16x32_bf16 v[100:103], v[216:219], v[188:191], v[100:103]
	v_mfma_f32_16x16x32_bf16 v[96:99], v[224:227], v[188:191], v[96:99]
	v_mfma_f32_16x16x32_bf16 v[84:87], v[216:219], v[196:199], v[84:87]
	v_mfma_f32_16x16x32_bf16 v[80:83], v[224:227], v[196:199], v[80:83]
	v_mfma_f32_16x16x32_bf16 v[68:71], v[216:219], v[208:211], v[68:71]
	v_mfma_f32_16x16x32_bf16 v[64:67], v[224:227], v[208:211], v[64:67]
	s_mov_b32 m0, s45
	v_lshl_add_u64 v[230:231], s[48:49], 0, v[128:129]
	s_barrier
	ds_read_b128 v[176:179], v158 offset:16384
	ds_read_b128 v[180:183], v158 offset:17408
	ds_read_b128 v[184:187], v158 offset:18432
	ds_read_b128 v[188:191], v158 offset:19456
	ds_read_b128 v[192:195], v158 offset:20480
	ds_read_b128 v[196:199], v158 offset:21504
	ds_read_b128 v[204:207], v158 offset:22528
	ds_read_b128 v[208:211], v158 offset:23552
	global_load_lds_dwordx4 v[230:231], off
	v_lshl_add_u64 v[232:233], s[48:49], 0, v[134:135]
	s_mov_b32 m0, s57
	s_nop 0
	global_load_lds_dwordx4 v[232:233], off
	s_add_i32 s33, s67, s56
	v_lshl_add_u64 v[234:235], s[50:51], 0, v[132:133]
	s_mov_b32 m0, s33
	v_lshl_add_u64 v[236:237], s[50:51], 0, v[138:139]
	global_load_lds_dwordx4 v[234:235], off
	s_add_i32 m0, s33, 0x2000
	s_nop 0
	global_load_lds_dwordx4 v[236:237], off
	s_waitcnt vmcnt(6)
	s_barrier
; #define PG8_STAGE(bufoff, gbase, voff) do { _Pragma("unroll") for (int _i = 0; _i < 2; ++_i) \
;         __builtin_amdgcn_global_load_lds((const unsigned*)((const char*)(gbase) + (voff)[_i]), (LAS unsigned*)(lds + (bufoff) + ldsw + _i * 8192), 16, 0, 0); } while (0)
; #define PG8_LDA(dst, b, h) do { _Pragma("unroll") for (int m = 0; m < 4; ++m) _Pragma("unroll") for (int k = 0; k < 2; ++k) dst[m][k] = *(const LAS bf16x8*)(lds + PG8_SA(b, h) + aoff + m * 2048 + k * 1024); } while (0)
; #define PG8_LDB(dst, b, h) do { _Pragma("unroll") for (int n = 0; n < 2; ++n) _Pragma("unroll") for (int k = 0; k < 2; ++k) dst[n][k] = *(const LAS bf16x8*)(lds + PG8_SB(b, h) + boff + n * 2048 + k * 1024); } while (0)
; #define PG8_MMA(ai, bj, At, Bt) do { __builtin_amdgcn_s_setprio(1); _Pragma("unroll") for (int m = 0; m < 4; ++m) _Pragma("unroll") for (int n = 0; n < 2; ++n) _Pragma("unroll") for (int k = 0; k < 2; ++k) \
;         acc[ai][bj][m][n] = __builtin_amdgcn_mfma_f32_16x16x32_bf16(Bt[n][k], At[m][k], acc[ai][bj][m][n], 0, 0, 0); __builtin_amdgcn_s_setprio(0); } while (0)
; #define PG8_WAIT_V(n) asm volatile("s_waitcnt vmcnt(" #n ")" ::: "memory")
; #define PG8_WAIT_L(n) asm volatile("s_waitcnt lgkmcnt(" #n ")" ::: "memory")
; #define PG8_BAR __builtin_amdgcn_s_barrier()
; #define PG8_SCHED __builtin_amdgcn_sched_barrier(0)
; template <class Epi>
; __device__ __forceinline__ void gemm_phase(LAS unsigned char* lds, const Gemm g, const StaticOrder& S, const Epi& E) {
;     ...
;             PG8_WAIT_V(6); PG8_BAR; PG8_MMA(1, 1, At, B1); PG8_BAR;
;             PG8_LDB(B0, 1, 0); PG8_SCHED; PG8_LDA(At, 1, 0); PG8_STAGE(PG8_SA(0, 1), a2 + hstep, voffA);
;             PG8_WAIT_L(8); PG8_BAR; PG8_WAIT_L(0); PG8_MMA(0, 0, At, B0); PG8_BAR; PG8_SCHED;
;             PG8_LDB(B1, 1, 1); PG8_STAGE(PG8_SB(1, 0), b3, voffB0);
;             PG8_BAR; PG8_WAIT_L(0); PG8_MMA(0, 1, At, B1); PG8_BAR;
;             PG8_LDA(At, 1, 1); PG8_STAGE(PG8_SA(1, 0), a3, voffA);
;             PG8_BAR; PG8_WAIT_L(0); PG8_MMA(1, 0, At, B0); PG8_BAR; PG8_SCHED;
	s_waitcnt lgkmcnt(0)
	v_mfma_f32_16x16x32_bf16 v[60:63], v[160:163], v[176:179], v[60:63]
	v_mfma_f32_16x16x32_bf16 v[56:59], v[168:171], v[176:179], v[56:59]
	v_mfma_f32_16x16x32_bf16 v[44:47], v[160:163], v[184:187], v[44:47]
	v_mfma_f32_16x16x32_bf16 v[40:43], v[168:171], v[184:187], v[40:43]
	v_mfma_f32_16x16x32_bf16 v[28:31], v[160:163], v[192:195], v[28:31]
	v_mfma_f32_16x16x32_bf16 v[24:27], v[168:171], v[192:195], v[24:27]
	v_mfma_f32_16x16x32_bf16 v[12:15], v[160:163], v[204:207], v[12:15]
	v_mfma_f32_16x16x32_bf16 v[8:11], v[168:171], v[204:207], v[8:11]
	v_mfma_f32_16x16x32_bf16 v[60:63], v[164:167], v[180:183], v[60:63]
	v_mfma_f32_16x16x32_bf16 v[56:59], v[172:175], v[180:183], v[56:59]
	v_mfma_f32_16x16x32_bf16 v[44:47], v[164:167], v[188:191], v[44:47]
	v_mfma_f32_16x16x32_bf16 v[40:43], v[172:175], v[188:191], v[40:43]
	v_mfma_f32_16x16x32_bf16 v[28:31], v[164:167], v[196:199], v[28:31]
	v_mfma_f32_16x16x32_bf16 v[24:27], v[172:175], v[196:199], v[24:27]
	v_mfma_f32_16x16x32_bf16 v[12:15], v[164:167], v[208:211], v[12:15]
	v_mfma_f32_16x16x32_bf16 v[8:11], v[172:175], v[208:211], v[8:11]
	v_mfma_f32_16x16x32_bf16 v[52:55], v[212:215], v[176:179], v[52:55]
	v_mfma_f32_16x16x32_bf16 v[48:51], v[220:223], v[176:179], v[48:51]
	v_mfma_f32_16x16x32_bf16 v[36:39], v[212:215], v[184:187], v[36:39]
	v_mfma_f32_16x16x32_bf16 v[32:35], v[220:223], v[184:187], v[32:35]
	v_mfma_f32_16x16x32_bf16 v[20:23], v[212:215], v[192:195], v[20:23]
	v_mfma_f32_16x16x32_bf16 v[16:19], v[220:223], v[192:195], v[16:19]
	v_mfma_f32_16x16x32_bf16 v[4:7], v[212:215], v[204:207], v[4:7]
	v_mfma_f32_16x16x32_bf16 v[0:3], v[220:223], v[204:207], v[0:3]
	v_mfma_f32_16x16x32_bf16 v[52:55], v[216:219], v[180:183], v[52:55]
	v_mfma_f32_16x16x32_bf16 v[48:51], v[224:227], v[180:183], v[48:51]
	v_mfma_f32_16x16x32_bf16 v[36:39], v[216:219], v[188:191], v[36:39]
	v_mfma_f32_16x16x32_bf16 v[32:35], v[224:227], v[188:191], v[32:35]
	v_mfma_f32_16x16x32_bf16 v[20:23], v[216:219], v[196:199], v[20:23]
	v_mfma_f32_16x16x32_bf16 v[16:19], v[224:227], v[196:199], v[16:19]
	v_mfma_f32_16x16x32_bf16 v[4:7], v[216:219], v[208:211], v[4:7]
	v_mfma_f32_16x16x32_bf16 v[0:3], v[224:227], v[208:211], v[0:3]
	s_add_i32 s33, 0, 0x18000
	v_add_u32_e32 v172, s33, v147
	s_barrier
	ds_read_b128 v[160:163], v172
	ds_read_b128 v[164:167], v172 offset:1024
	ds_read_b128 v[168:171], v172 offset:2048
	ds_read_b128 v[172:175], v172 offset:3072
	s_add_u32 s48, s48, 0x80000
	s_addc_u32 s49, s49, 0
	s_mov_b32 m0, s58
	v_lshl_add_u64 v[212:213], s[48:49], 0, v[128:129]
	ds_read_b128 v[176:179], v158 offset:32768
	ds_read_b128 v[180:183], v158 offset:33792
	ds_read_b128 v[184:187], v158 offset:34816
	ds_read_b128 v[188:191], v158 offset:35840
	ds_read_b128 v[192:195], v158 offset:36864
	ds_read_b128 v[196:199], v158 offset:37888
	ds_read_b128 v[204:207], v158 offset:38912
	ds_read_b128 v[208:211], v158 offset:39936
	global_load_lds_dwordx4 v[212:213], off
	v_lshl_add_u64 v[212:213], s[48:49], 0, v[134:135]
	s_mov_b32 m0, s59
	s_nop 0
	global_load_lds_dwordx4 v[212:213], off
	s_waitcnt lgkmcnt(8)
	s_barrier
	s_waitcnt lgkmcnt(0)
	v_mfma_f32_16x16x32_bf16 v[124:127], v[160:163], v[176:179], v[124:127]
	v_mfma_f32_16x16x32_bf16 v[120:123], v[168:171], v[176:179], v[120:123]
	v_mfma_f32_16x16x32_bf16 v[108:111], v[160:163], v[184:187], v[108:111]
	v_mfma_f32_16x16x32_bf16 v[104:107], v[168:171], v[184:187], v[104:107]
	v_mfma_f32_16x16x32_bf16 v[92:95], v[160:163], v[192:195], v[92:95]
	v_mfma_f32_16x16x32_bf16 v[88:91], v[168:171], v[192:195], v[88:91]
	v_mfma_f32_16x16x32_bf16 v[76:79], v[160:163], v[204:207], v[76:79]
	v_mfma_f32_16x16x32_bf16 v[72:75], v[168:171], v[204:207], v[72:75]
	v_mfma_f32_16x16x32_bf16 v[124:127], v[164:167], v[180:183], v[124:127]
	v_mfma_f32_16x16x32_bf16 v[120:123], v[172:175], v[180:183], v[120:123]
	v_mfma_f32_16x16x32_bf16 v[108:111], v[164:167], v[188:191], v[108:111]
	v_mfma_f32_16x16x32_bf16 v[104:107], v[172:175], v[188:191], v[104:107]
	v_mfma_f32_16x16x32_bf16 v[92:95], v[164:167], v[196:199], v[92:95]
	v_mfma_f32_16x16x32_bf16 v[88:91], v[172:175], v[196:199], v[88:91]
	v_mfma_f32_16x16x32_bf16 v[76:79], v[164:167], v[208:211], v[76:79]
	v_mfma_f32_16x16x32_bf16 v[72:75], v[172:175], v[208:211], v[72:75]
	s_barrier
	s_add_i32 s48, 0, 0x1c000
	s_add_i32 s33, s33, s56
	v_add_u32_e32 v224, s48, v147
	v_lshl_add_u64 v[200:201], v[200:201], 0, s[16:17]
	s_mov_b32 m0, s33
	ds_read_b128 v[212:215], v224
	ds_read_b128 v[216:219], v224 offset:1024
	ds_read_b128 v[220:223], v224 offset:2048
	ds_read_b128 v[224:227], v224 offset:3072
	global_load_lds_dwordx4 v[200:201], off
	v_lshl_add_u64 v[200:201], v[228:229], 0, s[16:17]
	s_add_i32 m0, s33, 0x2000
	s_nop 0
	global_load_lds_dwordx4 v[200:201], off
	s_waitcnt lgkmcnt(0)
	s_barrier
	s_waitcnt lgkmcnt(0)
	v_mfma_f32_16x16x32_bf16 v[116:119], v[212:215], v[176:179], v[116:119]
	v_mfma_f32_16x16x32_bf16 v[112:115], v[220:223], v[176:179], v[112:115]
	v_mfma_f32_16x16x32_bf16 v[100:103], v[212:215], v[184:187], v[100:103]
	v_mfma_f32_16x16x32_bf16 v[96:99], v[220:223], v[184:187], v[96:99]
	v_mfma_f32_16x16x32_bf16 v[84:87], v[212:215], v[192:195], v[84:87]
	v_mfma_f32_16x16x32_bf16 v[80:83], v[220:223], v[192:195], v[80:83]
	v_mfma_f32_16x16x32_bf16 v[68:71], v[212:215], v[204:207], v[68:71]
	v_mfma_f32_16x16x32_bf16 v[64:67], v[220:223], v[204:207], v[64:67]
	v_mfma_f32_16x16x32_bf16 v[116:119], v[216:219], v[180:183], v[116:119]
	v_mfma_f32_16x16x32_bf16 v[112:115], v[224:227], v[180:183], v[112:115]
	v_mfma_f32_16x16x32_bf16 v[100:103], v[216:219], v[188:191], v[100:103]
	v_mfma_f32_16x16x32_bf16 v[96:99], v[224:227], v[188:191], v[96:99]
	v_mfma_f32_16x16x32_bf16 v[84:87], v[216:219], v[196:199], v[84:87]
	v_mfma_f32_16x16x32_bf16 v[80:83], v[224:227], v[196:199], v[80:83]
	v_mfma_f32_16x16x32_bf16 v[68:71], v[216:219], v[208:211], v[68:71]
	v_mfma_f32_16x16x32_bf16 v[64:67], v[224:227], v[208:211], v[64:67]
	s_mov_b32 m0, s61
	v_lshl_add_u64 v[200:201], v[230:231], 0, s[16:17]
	s_barrier
; __device__ __forceinline__ unsigned cvt_pk_bf16(float lo, float hi) { unsigned r; asm volatile("v_cvt_pk_bf16_f32 %0, %1, %2" : "=v"(r) : "v"(lo), "v"(hi)); return r; }
; #define PG8_STAGE(bufoff, gbase, voff) do { _Pragma("unroll") for (int _i = 0; _i < 2; ++_i) \
;         __builtin_amdgcn_global_load_lds((const unsigned*)((const char*)(gbase) + (voff)[_i]), (LAS unsigned*)(lds + (bufoff) + ldsw + _i * 8192), 16, 0, 0); } while (0)
; #define PG8_LDA(dst, b, h) do { _Pragma("unroll") for (int m = 0; m < 4; ++m) _Pragma("unroll") for (int k = 0; k < 2; ++k) dst[m][k] = *(const LAS bf16x8*)(lds + PG8_SA(b, h) + aoff + m * 2048 + k * 1024); } while (0)
; #define PG8_WAIT_V(n) asm volatile("s_waitcnt vmcnt(" #n ")" ::: "memory")
; #define PG8_WAIT_L(n) asm volatile("s_waitcnt lgkmcnt(" #n ")" ::: "memory")
; #define PG8_BAR __builtin_amdgcn_s_barrier()
;     __device__ __forceinline__ void operator()(const f32x4 (&acc)[2][2][4][2], const Unit& u, int wr, int wc, int fr, int fq) const {
;     ...
;             for (int m = 0; m < 4; ++m) { const int row = row0 + ai * HALF + m * 16;
;                 const float rs = ssin ? __builtin_amdgcn_rsqf(ssin[row] * (1.f / D) + EPS) : 1.0f; float sq = 0.f; u32x4 w[2];
; #pragma unroll
;                 for (int bj = 0; bj < 2; ++bj) { f32x4 v0 = acc[ai][bj][m][0] * rs, v1 = acc[ai][bj][m][1] * rs;
;                     if (ACT == 1) {
; #pragma unroll
;                         for (int j = 0; j < 4; ++j) { const float a = fmaxf(v0[j], 0.f), b = fmaxf(v1[j], 0.f); v0[j] = a * a; v1[j] = b * b; } }
;                     sq += (v0[0] * v0[0] + v0[1] * v0[1]) + (v0[2] * v0[2] + v0[3] * v0[3]) + (v1[0] * v1[0] + v1[1] * v1[1]) + (v1[2] * v1[2] + v1[3] * v1[3]);
;                     w[bj].x = cvt_pk_bf16(v0[0], v0[1]); w[bj].y = cvt_pk_bf16(v0[2], v0[3]); w[bj].z = cvt_pk_bf16(v1[0], v1[1]); w[bj].w = cvt_pk_bf16(v1[2], v1[3]); }
;                 store_pair_lines(O, ldc, row, fr, col0, w[0], w[1]);
; template <class Epi>
; __device__ __forceinline__ void gemm_phase(LAS unsigned char* lds, const Gemm g, const StaticOrder& S, const Epi& E) {
;     ...
;             PG8_LDA(At, 1, 1); PG8_STAGE(PG8_SA(1, 0), a3, voffA);
;             PG8_BAR; PG8_WAIT_L(0); PG8_MMA(1, 0, At, B0); PG8_BAR; PG8_SCHED;
;             PG8_STAGE(PG8_SB(1, 1), b3, voffB1);
;             PG8_WAIT_V(6); PG8_BAR; PG8_MMA(1, 1, At, B1); PG8_BAR;
;         }
	ds_read_b128 v[176:179], v158 offset:49152
	ds_read_b128 v[180:183], v158 offset:50176
	ds_read_b128 v[184:187], v158 offset:51200
	ds_read_b128 v[188:191], v158 offset:52224
	ds_read_b128 v[192:195], v158 offset:53248
	ds_read_b128 v[196:199], v158 offset:54272
	ds_read_b128 v[204:207], v158 offset:55296
	ds_read_b128 v[208:211], v158 offset:56320
	global_load_lds_dwordx4 v[200:201], off
	v_lshl_add_u64 v[200:201], v[232:233], 0, s[16:17]
	s_mov_b32 m0, s62
	s_nop 0
	global_load_lds_dwordx4 v[200:201], off
	s_add_i32 s33, s48, s56
	v_lshl_add_u64 v[250:251], v[234:235], 0, s[16:17]
	s_mov_b32 m0, s33
	s_nop 0
	global_load_lds_dwordx4 v[250:251], off
	v_lshl_add_u64 v[250:251], v[236:237], 0, s[16:17]
	s_add_i32 m0, s33, 0x2000
	s_nop 0
	global_load_lds_dwordx4 v[250:251], off
	s_waitcnt vmcnt(6)
	s_barrier
	s_waitcnt lgkmcnt(0)
	v_mfma_f32_16x16x32_bf16 v[60:63], v[160:163], v[176:179], v[60:63]
	v_mfma_f32_16x16x32_bf16 v[56:59], v[168:171], v[176:179], v[56:59]
	v_mfma_f32_16x16x32_bf16 v[44:47], v[160:163], v[184:187], v[44:47]
	v_mfma_f32_16x16x32_bf16 v[40:43], v[168:171], v[184:187], v[40:43]
	v_mfma_f32_16x16x32_bf16 v[28:31], v[160:163], v[192:195], v[28:31]
	v_mfma_f32_16x16x32_bf16 v[24:27], v[168:171], v[192:195], v[24:27]
	v_mfma_f32_16x16x32_bf16 v[12:15], v[160:163], v[204:207], v[12:15]
	v_mfma_f32_16x16x32_bf16 v[8:11], v[168:171], v[204:207], v[8:11]
	v_mfma_f32_16x16x32_bf16 v[60:63], v[164:167], v[180:183], v[60:63]
	v_mfma_f32_16x16x32_bf16 v[56:59], v[172:175], v[180:183], v[56:59]
	v_mfma_f32_16x16x32_bf16 v[44:47], v[164:167], v[188:191], v[44:47]
	v_mfma_f32_16x16x32_bf16 v[40:43], v[172:175], v[188:191], v[40:43]
	v_mfma_f32_16x16x32_bf16 v[28:31], v[164:167], v[196:199], v[28:31]
	v_mfma_f32_16x16x32_bf16 v[24:27], v[172:175], v[196:199], v[24:27]
	v_mfma_f32_16x16x32_bf16 v[12:15], v[164:167], v[208:211], v[12:15]
	v_mfma_f32_16x16x32_bf16 v[8:11], v[172:175], v[208:211], v[8:11]
	v_mfma_f32_16x16x32_bf16 v[52:55], v[212:215], v[176:179], v[52:55]
	v_mfma_f32_16x16x32_bf16 v[48:51], v[220:223], v[176:179], v[48:51]
	v_mfma_f32_16x16x32_bf16 v[36:39], v[212:215], v[184:187], v[36:39]
	v_mfma_f32_16x16x32_bf16 v[32:35], v[220:223], v[184:187], v[32:35]
	v_mfma_f32_16x16x32_bf16 v[20:23], v[212:215], v[192:195], v[20:23]
	v_mfma_f32_16x16x32_bf16 v[16:19], v[220:223], v[192:195], v[16:19]
	v_mfma_f32_16x16x32_bf16 v[4:7], v[212:215], v[204:207], v[4:7]
	v_mfma_f32_16x16x32_bf16 v[0:3], v[220:223], v[204:207], v[0:3]
	v_mfma_f32_16x16x32_bf16 v[52:55], v[216:219], v[180:183], v[52:55]
	v_mfma_f32_16x16x32_bf16 v[48:51], v[224:227], v[180:183], v[48:51]
	v_mfma_f32_16x16x32_bf16 v[36:39], v[216:219], v[188:191], v[36:39]
	v_mfma_f32_16x16x32_bf16 v[32:35], v[224:227], v[188:191], v[32:35]
	v_mfma_f32_16x16x32_bf16 v[20:23], v[216:219], v[196:199], v[20:23]
	v_mfma_f32_16x16x32_bf16 v[16:19], v[224:227], v[196:199], v[16:19]
	v_mfma_f32_16x16x32_bf16 v[4:7], v[216:219], v[208:211], v[4:7]
	v_mfma_f32_16x16x32_bf16 v[0:3], v[224:227], v[208:211], v[0:3]
	s_add_i32 s74, s74, 2
	s_add_u32 s46, s46, 0x100
	s_addc_u32 s47, s47, 0
	s_add_u32 s72, s72, 0x100
	s_addc_u32 s73, s73, 0
	s_cmp_gt_u32 s74, 29
	s_barrier
	s_cbranch_scc0 .LBB0_733
	v_max_f32_e32 v124, 0, v124
	v_max_f32_e32 v120, 0, v120
	v_max_f32_e32 v125, 0, v125
	v_max_f32_e32 v121, 0, v121
	v_max_f32_e32 v122, 0, v122
	v_max_f32_e32 v118, 0, v118
	v_max_f32_e32 v119, 0, v119
	v_mul_f32_e32 v124, v124, v124
	v_mul_f32_e32 v120, v120, v120
	v_mul_f32_e32 v125, v125, v125
	v_mul_f32_e32 v121, v121, v121
	v_max_f32_e32 v126, 0, v126
	v_mul_f32_e32 v122, v122, v122
	v_max_f32_e32 v127, 0, v127
	v_max_f32_e32 v123, 0, v123
	v_max_f32_e32 v116, 0, v116
	v_max_f32_e32 v112, 0, v112
	v_max_f32_e32 v117, 0, v117
	v_max_f32_e32 v113, 0, v113
	v_max_f32_e32 v114, 0, v114
	v_mul_f32_e32 v118, v118, v118
	v_mul_f32_e32 v119, v119, v119
	s_lshl_b32 s19, s44, 8
	v_mul_f32_e32 v126, v126, v126
	v_mul_f32_e32 v127, v127, v127
	v_mul_f32_e32 v123, v123, v123
	v_cvt_pk_bf16_f32 v124, v124, v125
	v_cvt_pk_bf16_f32 v125, v126, v127
	v_cvt_pk_bf16_f32 v120, v120, v121
	v_cvt_pk_bf16_f32 v121, v122, v123
	v_mul_f32_e32 v116, v116, v116
	v_mul_f32_e32 v112, v112, v112
	v_mul_f32_e32 v117, v117, v117
	v_mul_f32_e32 v113, v113, v113
	v_mul_f32_e32 v114, v114, v114
	v_max_f32_e32 v115, 0, v115
	v_cvt_pk_bf16_f32 v122, v116, v117
	v_cvt_pk_bf16_f32 v119, v118, v119
	s_add_i32 s19, s19, s63
	v_mul_f32_e32 v115, v115, v115
	v_cvt_pk_bf16_f32 v112, v112, v113
	v_cvt_pk_bf16_f32 v113, v114, v115
	v_mov_b32_dpp v118, v124 row_ror:8 row_mask:0xf bank_mask:0xf
	v_mov_b32_dpp v123, v125 row_ror:8 row_mask:0xf bank_mask:0xf
	v_mov_b32_dpp v114, v122 row_ror:8 row_mask:0xf bank_mask:0xf
	v_cndmask_b32_e64 v118, v122, v118, s[6:7]
	v_or_b32_e32 v122, s19, v148
	v_lshl_or_b32 v162, s69, 8, v156
	v_mov_b32_dpp v126, v120 row_ror:8 row_mask:0xf bank_mask:0xf
	v_mov_b32_dpp v127, v121 row_ror:8 row_mask:0xf bank_mask:0xf
	v_mov_b32_dpp v115, v119 row_ror:8 row_mask:0xf bank_mask:0xf
	v_mov_b32_dpp v116, v112 row_ror:8 row_mask:0xf bank_mask:0xf
	v_mov_b32_dpp v117, v113 row_ror:8 row_mask:0xf bank_mask:0xf
	v_cndmask_b32_e64 v119, v119, v123, s[6:7]
	v_ashrrev_i32_e32 v123, 31, v122
	v_ashrrev_i32_e32 v163, 31, v162
	v_cndmask_b32_e64 v116, v116, v120, s[6:7]
	v_cndmask_b32_e64 v117, v117, v121, s[6:7]
	v_cndmask_b32_e64 v120, v112, v126, s[6:7]
	v_cndmask_b32_e64 v121, v113, v127, s[6:7]
	v_lshlrev_b64 v[112:113], 14, v[122:123]
	v_cndmask_b32_e64 v114, v114, v124, s[6:7]
	v_cndmask_b32_e64 v115, v115, v125, s[6:7]
	v_lshl_add_u64 v[124:125], s[10:11], 0, v[112:113]
	v_lshlrev_b64 v[112:113], 1, v[162:163]
; __device__ __forceinline__ unsigned cvt_pk_bf16(float lo, float hi) { unsigned r; asm volatile("v_cvt_pk_bf16_f32 %0, %1, %2" : "=v"(r) : "v"(lo), "v"(hi)); return r; }
; __device__ __forceinline__ unsigned dpp_ror8(unsigned x) { return (unsigned)__builtin_amdgcn_update_dpp(0, (int)x, 0x128, 0xf, 0xf, false); }
; __device__ __forceinline__ void store_pair_lines(bf16_t* O, int ldc, int row, int fr, int col0, u32x4 wA, u32x4 wB) {
;     const u32x4 sA = {dpp_ror8(wA.x), dpp_ror8(wA.y), dpp_ror8(wA.z), dpp_ror8(wA.w)}, sB = {dpp_ror8(wB.x), dpp_ror8(wB.y), dpp_ror8(wB.z), dpp_ror8(wB.w)};
;     const bool lo = fr < 8;
;     const u32x4 o1 = lo ? wA : sB, o2 = lo ? sA : wB;
;     const int r1 = row - fr + (fr & 7), cb = col0 + (lo ? 0 : 8);
;     *(u32x4*)(O + (size_t)r1 * ldc + cb) = o1;
;     *(u32x4*)(O + (size_t)(r1 + 8) * ldc + cb) = o2;
; }
;     __device__ __forceinline__ void operator()(const f32x4 (&acc)[2][2][4][2], const Unit& u, int wr, int wc, int fr, int fq) const {
;     ...
;             for (int m = 0; m < 4; ++m) { const int row = row0 + ai * HALF + m * 16;
;                 const float rs = ssin ? __builtin_amdgcn_rsqf(ssin[row] * (1.f / D) + EPS) : 1.0f; float sq = 0.f; u32x4 w[2];
; #pragma unroll
;                 for (int bj = 0; bj < 2; ++bj) { f32x4 v0 = acc[ai][bj][m][0] * rs, v1 = acc[ai][bj][m][1] * rs;
;                     if (ACT == 1) {
; #pragma unroll
;                         for (int j = 0; j < 4; ++j) { const float a = fmaxf(v0[j], 0.f), b = fmaxf(v1[j], 0.f); v0[j] = a * a; v1[j] = b * b; } }
;                     sq += (v0[0] * v0[0] + v0[1] * v0[1]) + (v0[2] * v0[2] + v0[3] * v0[3]) + (v1[0] * v1[0] + v1[1] * v1[1]) + (v1[2] * v1[2] + v1[3] * v1[3]);
;                     w[bj].x = cvt_pk_bf16(v0[0], v0[1]); w[bj].y = cvt_pk_bf16(v0[2], v0[3]); w[bj].z = cvt_pk_bf16(v1[0], v1[1]); w[bj].w = cvt_pk_bf16(v1[2], v1[3]); }
;                 store_pair_lines(O, ldc, row, fr, col0, w[0], w[1]);
	v_lshl_add_u64 v[124:125], v[124:125], 0, v[112:113]
	global_store_dwordx4 v[124:125], v[114:117], off
	v_max_f32_e32 v108, v108, v108
	v_max_f32_e32 v104, v104, v104
	v_or_b32_e32 v114, 8, v122
	v_ashrrev_i32_e32 v115, 31, v114
	v_lshlrev_b64 v[114:115], 14, v[114:115]
	v_lshl_add_u64 v[114:115], s[10:11], 0, v[114:115]
	v_max_f32_e32 v108, 0, v108
	v_max_f32_e32 v104, 0, v104
	v_max_f32_e32 v109, 0, v109
	v_max_f32_e32 v105, 0, v105
	v_max_f32_e32 v100, 0, v100
	v_max_f32_e32 v101, 0, v101
	v_max_f32_e32 v102, 0, v102
	v_max_f32_e32 v98, 0, v98
	v_max_f32_e32 v103, 0, v103
	v_lshl_add_u64 v[114:115], v[114:115], 0, v[112:113]
	v_mul_f32_e32 v108, v108, v108
	v_mul_f32_e32 v104, v104, v104
	v_mul_f32_e32 v109, v109, v109
	v_mul_f32_e32 v105, v105, v105
	v_max_f32_e32 v110, 0, v110
	v_max_f32_e32 v106, 0, v106
	v_max_f32_e32 v111, 0, v111
	v_max_f32_e32 v107, 0, v107
	v_max_f32_e32 v96, 0, v96
	v_mul_f32_e32 v100, v100, v100
	v_max_f32_e32 v97, 0, v97
	v_mul_f32_e32 v101, v101, v101
	v_mul_f32_e32 v102, v102, v102
	v_mul_f32_e32 v98, v98, v98
	v_max_f32_e32 v99, 0, v99
	v_mul_f32_e32 v103, v103, v103
	global_store_dwordx4 v[114:115], v[118:121], off
	v_mul_f32_e32 v110, v110, v110
	v_mul_f32_e32 v106, v106, v106
	v_mul_f32_e32 v111, v111, v111
	v_mul_f32_e32 v107, v107, v107
	v_cvt_pk_bf16_f32 v108, v108, v109
	v_cvt_pk_bf16_f32 v109, v110, v111
	v_cvt_pk_bf16_f32 v104, v104, v105
	v_cvt_pk_bf16_f32 v105, v106, v107
	v_mul_f32_e32 v96, v96, v96
	v_mul_f32_e32 v97, v97, v97
	v_mul_f32_e32 v99, v99, v99
	v_cvt_pk_bf16_f32 v100, v100, v101
	v_cvt_pk_bf16_f32 v101, v102, v103
	v_cvt_pk_bf16_f32 v102, v96, v97
	v_cvt_pk_bf16_f32 v103, v98, v99
	v_or_b32_e32 v160, s19, v146
	v_mov_b32_dpp v98, v102 row_ror:8 row_mask:0xf bank_mask:0xf
	v_mov_b32_dpp v110, v104 row_ror:8 row_mask:0xf bank_mask:0xf
	v_mov_b32_dpp v99, v103 row_ror:8 row_mask:0xf bank_mask:0xf
	v_cndmask_b32_e64 v98, v98, v104, s[6:7]
	v_add_u32_e32 v104, v149, v160
	v_mov_b32_dpp v111, v105 row_ror:8 row_mask:0xf bank_mask:0xf
	v_cndmask_b32_e64 v99, v99, v105, s[6:7]
	v_ashrrev_i32_e32 v105, 31, v104
	v_lshlrev_b64 v[104:105], 14, v[104:105]
	v_mov_b32_dpp v96, v100 row_ror:8 row_mask:0xf bank_mask:0xf
	v_mov_b32_dpp v97, v101 row_ror:8 row_mask:0xf bank_mask:0xf
	v_lshl_add_u64 v[104:105], s[10:11], 0, v[104:105]
	v_cndmask_b32_e64 v96, v96, v108, s[6:7]
	v_cndmask_b32_e64 v97, v97, v109, s[6:7]
	v_lshl_add_u64 v[104:105], v[104:105], 0, v[112:113]
	v_mov_b32_dpp v106, v108 row_ror:8 row_mask:0xf bank_mask:0xf
	v_mov_b32_dpp v107, v109 row_ror:8 row_mask:0xf bank_mask:0xf
	global_store_dwordx4 v[104:105], v[96:99], off
	v_max_f32_e32 v92, 0, v92
	v_max_f32_e32 v88, 0, v88
	v_add_co_u32_e32 v96, vcc, s68, v104
	v_max_f32_e32 v93, 0, v93
	v_max_f32_e32 v89, 0, v89
	v_max_f32_e32 v84, 0, v84
	v_max_f32_e32 v85, 0, v85
	v_max_f32_e32 v86, 0, v86
	v_max_f32_e32 v82, 0, v82
	v_max_f32_e32 v87, 0, v87
	v_cndmask_b32_e64 v100, v100, v106, s[6:7]
	v_cndmask_b32_e64 v101, v101, v107, s[6:7]
	v_cndmask_b32_e64 v102, v102, v110, s[6:7]
	v_cndmask_b32_e64 v103, v103, v111, s[6:7]
	v_addc_co_u32_e32 v97, vcc, 0, v105, vcc
	v_mul_f32_e32 v92, v92, v92
	v_mul_f32_e32 v88, v88, v88
	v_mul_f32_e32 v93, v93, v93
	v_mul_f32_e32 v89, v89, v89
	v_max_f32_e32 v94, 0, v94
	v_max_f32_e32 v90, 0, v90
	v_max_f32_e32 v95, 0, v95
	v_max_f32_e32 v91, 0, v91
	v_max_f32_e32 v80, 0, v80
	v_mul_f32_e32 v84, v84, v84
	v_max_f32_e32 v81, 0, v81
	v_mul_f32_e32 v85, v85, v85
	v_mul_f32_e32 v86, v86, v86
	v_mul_f32_e32 v82, v82, v82
	v_max_f32_e32 v83, 0, v83
	v_mul_f32_e32 v87, v87, v87
	global_store_dwordx4 v[96:97], v[100:103], off
	v_mul_f32_e32 v94, v94, v94
	v_mul_f32_e32 v90, v90, v90
	v_mul_f32_e32 v95, v95, v95
	v_mul_f32_e32 v91, v91, v91
	v_cvt_pk_bf16_f32 v92, v92, v93
	v_cvt_pk_bf16_f32 v93, v94, v95
	v_cvt_pk_bf16_f32 v88, v88, v89
	v_cvt_pk_bf16_f32 v89, v90, v91
	v_mul_f32_e32 v80, v80, v80
	v_mul_f32_e32 v81, v81, v81
	v_mul_f32_e32 v83, v83, v83
	v_cvt_pk_bf16_f32 v84, v84, v85
	v_cvt_pk_bf16_f32 v85, v86, v87
	v_cvt_pk_bf16_f32 v86, v80, v81
	v_cvt_pk_bf16_f32 v87, v82, v83
	v_mov_b32_e32 v82, 0
	v_mov_b32_dpp v82, v86 row_ror:8 row_mask:0xf bank_mask:0xf
	v_mov_b32_dpp v94, v88 row_ror:8 row_mask:0xf bank_mask:0xf
	v_mov_b32_dpp v83, v87 row_ror:8 row_mask:0xf bank_mask:0xf
	v_cndmask_b32_e64 v82, v82, v88, s[6:7]
	v_add_u32_e32 v88, v150, v160
	v_mov_b32_dpp v95, v89 row_ror:8 row_mask:0xf bank_mask:0xf
	v_cndmask_b32_e64 v83, v83, v89, s[6:7]
	v_ashrrev_i32_e32 v89, 31, v88
	v_lshlrev_b64 v[88:89], 14, v[88:89]
	v_mov_b32_dpp v80, v84 row_ror:8 row_mask:0xf bank_mask:0xf
	v_mov_b32_dpp v81, v85 row_ror:8 row_mask:0xf bank_mask:0xf
	v_lshl_add_u64 v[88:89], s[10:11], 0, v[88:89]
	v_cndmask_b32_e64 v80, v80, v92, s[6:7]
	v_cndmask_b32_e64 v81, v81, v93, s[6:7]
	v_lshl_add_u64 v[88:89], v[88:89], 0, v[112:113]
	v_mov_b32_dpp v90, v92 row_ror:8 row_mask:0xf bank_mask:0xf
	v_mov_b32_dpp v91, v93 row_ror:8 row_mask:0xf bank_mask:0xf
	global_store_dwordx4 v[88:89], v[80:83], off
	v_max_f32_e32 v76, 0, v76
	v_max_f32_e32 v72, 0, v72
	v_add_co_u32_e32 v80, vcc, s68, v88
	v_max_f32_e32 v77, 0, v77
	v_max_f32_e32 v73, 0, v73
	v_max_f32_e32 v68, 0, v68
	v_max_f32_e32 v69, 0, v69
	v_max_f32_e32 v70, 0, v70
	v_max_f32_e32 v66, 0, v66
	v_max_f32_e32 v71, 0, v71
	v_cndmask_b32_e64 v84, v84, v90, s[6:7]
	v_cndmask_b32_e64 v85, v85, v91, s[6:7]
	v_cndmask_b32_e64 v86, v86, v94, s[6:7]
	v_cndmask_b32_e64 v87, v87, v95, s[6:7]
	v_addc_co_u32_e32 v81, vcc, 0, v89, vcc
	v_mul_f32_e32 v76, v76, v76
	v_mul_f32_e32 v72, v72, v72
	v_mul_f32_e32 v77, v77, v77
	v_mul_f32_e32 v73, v73, v73
	v_max_f32_e32 v78, 0, v78
; __device__ __forceinline__ unsigned cvt_pk_bf16(float lo, float hi) { unsigned r; asm volatile("v_cvt_pk_bf16_f32 %0, %1, %2" : "=v"(r) : "v"(lo), "v"(hi)); return r; }
; __device__ __forceinline__ unsigned dpp_ror8(unsigned x) { return (unsigned)__builtin_amdgcn_update_dpp(0, (int)x, 0x128, 0xf, 0xf, false); }
; __device__ __forceinline__ void store_pair_lines(bf16_t* O, int ldc, int row, int fr, int col0, u32x4 wA, u32x4 wB) {
;     const u32x4 sA = {dpp_ror8(wA.x), dpp_ror8(wA.y), dpp_ror8(wA.z), dpp_ror8(wA.w)}, sB = {dpp_ror8(wB.x), dpp_ror8(wB.y), dpp_ror8(wB.z), dpp_ror8(wB.w)};
;     const bool lo = fr < 8;
;     const u32x4 o1 = lo ? wA : sB, o2 = lo ? sA : wB;
;     const int r1 = row - fr + (fr & 7), cb = col0 + (lo ? 0 : 8);
;     *(u32x4*)(O + (size_t)r1 * ldc + cb) = o1;
;     *(u32x4*)(O + (size_t)(r1 + 8) * ldc + cb) = o2;
; }
;     __device__ __forceinline__ void operator()(const f32x4 (&acc)[2][2][4][2], const Unit& u, int wr, int wc, int fr, int fq) const {
;     ...
;             for (int m = 0; m < 4; ++m) { const int row = row0 + ai * HALF + m * 16;
;                 const float rs = ssin ? __builtin_amdgcn_rsqf(ssin[row] * (1.f / D) + EPS) : 1.0f; float sq = 0.f; u32x4 w[2];
; #pragma unroll
;                 for (int bj = 0; bj < 2; ++bj) { f32x4 v0 = acc[ai][bj][m][0] * rs, v1 = acc[ai][bj][m][1] * rs;
;                     if (ACT == 1) {
; #pragma unroll
;                         for (int j = 0; j < 4; ++j) { const float a = fmaxf(v0[j], 0.f), b = fmaxf(v1[j], 0.f); v0[j] = a * a; v1[j] = b * b; } }
;                     sq += (v0[0] * v0[0] + v0[1] * v0[1]) + (v0[2] * v0[2] + v0[3] * v0[3]) + (v1[0] * v1[0] + v1[1] * v1[1]) + (v1[2] * v1[2] + v1[3] * v1[3]);
;                     w[bj].x = cvt_pk_bf16(v0[0], v0[1]); w[bj].y = cvt_pk_bf16(v0[2], v0[3]); w[bj].z = cvt_pk_bf16(v1[0], v1[1]); w[bj].w = cvt_pk_bf16(v1[2], v1[3]); }
;                 store_pair_lines(O, ldc, row, fr, col0, w[0], w[1]);
	v_max_f32_e32 v74, 0, v74
	v_max_f32_e32 v79, 0, v79
	v_max_f32_e32 v75, 0, v75
	v_max_f32_e32 v64, 0, v64
	v_mul_f32_e32 v68, v68, v68
	v_max_f32_e32 v65, 0, v65
	v_mul_f32_e32 v69, v69, v69
	v_mul_f32_e32 v70, v70, v70
	v_mul_f32_e32 v66, v66, v66
	v_max_f32_e32 v67, 0, v67
	v_mul_f32_e32 v71, v71, v71
	global_store_dwordx4 v[80:81], v[84:87], off
	v_mul_f32_e32 v78, v78, v78
	v_mul_f32_e32 v74, v74, v74
	v_mul_f32_e32 v79, v79, v79
	v_mul_f32_e32 v75, v75, v75
	v_cvt_pk_bf16_f32 v76, v76, v77
	v_cvt_pk_bf16_f32 v77, v78, v79
	v_cvt_pk_bf16_f32 v72, v72, v73
	v_cvt_pk_bf16_f32 v73, v74, v75
	v_mul_f32_e32 v64, v64, v64
	v_mul_f32_e32 v65, v65, v65
	v_mul_f32_e32 v67, v67, v67
	v_cvt_pk_bf16_f32 v68, v68, v69
	v_cvt_pk_bf16_f32 v69, v70, v71
	v_cvt_pk_bf16_f32 v70, v64, v65
	v_cvt_pk_bf16_f32 v71, v66, v67
	v_mov_b32_e32 v66, 0
	v_mov_b32_dpp v66, v70 row_ror:8 row_mask:0xf bank_mask:0xf
	v_mov_b32_dpp v78, v72 row_ror:8 row_mask:0xf bank_mask:0xf
	v_mov_b32_dpp v67, v71 row_ror:8 row_mask:0xf bank_mask:0xf
	v_cndmask_b32_e64 v66, v66, v72, s[6:7]
	v_add_u32_e32 v72, v151, v160
	v_mov_b32_dpp v79, v73 row_ror:8 row_mask:0xf bank_mask:0xf
	v_cndmask_b32_e64 v67, v67, v73, s[6:7]
	v_ashrrev_i32_e32 v73, 31, v72
	v_lshlrev_b64 v[72:73], 14, v[72:73]
	v_mov_b32_dpp v64, v68 row_ror:8 row_mask:0xf bank_mask:0xf
	v_mov_b32_dpp v65, v69 row_ror:8 row_mask:0xf bank_mask:0xf
	v_lshl_add_u64 v[72:73], s[10:11], 0, v[72:73]
	v_cndmask_b32_e64 v64, v64, v76, s[6:7]
	v_cndmask_b32_e64 v65, v65, v77, s[6:7]
	v_lshl_add_u64 v[72:73], v[72:73], 0, v[112:113]
	v_mov_b32_dpp v74, v76 row_ror:8 row_mask:0xf bank_mask:0xf
	v_mov_b32_dpp v75, v77 row_ror:8 row_mask:0xf bank_mask:0xf
	global_store_dwordx4 v[72:73], v[64:67], off
	v_max_f32_e32 v60, 0, v60
	v_max_f32_e32 v56, 0, v56
	v_add_co_u32_e32 v64, vcc, s68, v72
	v_max_f32_e32 v61, 0, v61
	v_max_f32_e32 v57, 0, v57
	v_max_f32_e32 v52, 0, v52
	v_max_f32_e32 v53, 0, v53
	v_max_f32_e32 v54, 0, v54
	v_max_f32_e32 v50, 0, v50
	v_max_f32_e32 v55, 0, v55
	v_cndmask_b32_e64 v68, v68, v74, s[6:7]
	v_cndmask_b32_e64 v69, v69, v75, s[6:7]
	v_cndmask_b32_e64 v70, v70, v78, s[6:7]
	v_cndmask_b32_e64 v71, v71, v79, s[6:7]
	v_addc_co_u32_e32 v65, vcc, 0, v73, vcc
	v_mul_f32_e32 v60, v60, v60
	v_mul_f32_e32 v56, v56, v56
	v_mul_f32_e32 v61, v61, v61
	v_mul_f32_e32 v57, v57, v57
	v_max_f32_e32 v62, 0, v62
	v_max_f32_e32 v58, 0, v58
	v_max_f32_e32 v63, 0, v63
	v_max_f32_e32 v59, 0, v59
	v_max_f32_e32 v48, 0, v48
	v_mul_f32_e32 v52, v52, v52
	v_max_f32_e32 v49, 0, v49
	v_mul_f32_e32 v53, v53, v53
	v_mul_f32_e32 v54, v54, v54
	v_mul_f32_e32 v50, v50, v50
	v_max_f32_e32 v51, 0, v51
	v_mul_f32_e32 v55, v55, v55
	global_store_dwordx4 v[64:65], v[68:71], off
	v_mul_f32_e32 v62, v62, v62
	v_mul_f32_e32 v58, v58, v58
	v_mul_f32_e32 v63, v63, v63
	v_mul_f32_e32 v59, v59, v59
	v_cvt_pk_bf16_f32 v60, v60, v61
	v_cvt_pk_bf16_f32 v61, v62, v63
	v_cvt_pk_bf16_f32 v56, v56, v57
	v_cvt_pk_bf16_f32 v57, v58, v59
	v_mul_f32_e32 v48, v48, v48
	v_mul_f32_e32 v49, v49, v49
	v_mul_f32_e32 v51, v51, v51
	v_cvt_pk_bf16_f32 v52, v52, v53
	v_cvt_pk_bf16_f32 v53, v54, v55
	v_cvt_pk_bf16_f32 v54, v48, v49
	v_cvt_pk_bf16_f32 v55, v50, v51
	v_mov_b32_e32 v50, 0
	v_mov_b32_dpp v50, v54 row_ror:8 row_mask:0xf bank_mask:0xf
	v_mov_b32_dpp v62, v56 row_ror:8 row_mask:0xf bank_mask:0xf
	v_mov_b32_dpp v51, v55 row_ror:8 row_mask:0xf bank_mask:0xf
	v_cndmask_b32_e64 v50, v50, v56, s[6:7]
	v_add_u32_e32 v56, v152, v160
	v_mov_b32_dpp v63, v57 row_ror:8 row_mask:0xf bank_mask:0xf
	v_cndmask_b32_e64 v51, v51, v57, s[6:7]
	v_ashrrev_i32_e32 v57, 31, v56
	v_lshlrev_b64 v[56:57], 14, v[56:57]
	v_mov_b32_dpp v48, v52 row_ror:8 row_mask:0xf bank_mask:0xf
	v_mov_b32_dpp v49, v53 row_ror:8 row_mask:0xf bank_mask:0xf
	v_lshl_add_u64 v[56:57], s[10:11], 0, v[56:57]
	v_cndmask_b32_e64 v48, v48, v60, s[6:7]
	v_cndmask_b32_e64 v49, v49, v61, s[6:7]
	v_lshl_add_u64 v[56:57], v[56:57], 0, v[112:113]
	v_mov_b32_dpp v58, v60 row_ror:8 row_mask:0xf bank_mask:0xf
	v_mov_b32_dpp v59, v61 row_ror:8 row_mask:0xf bank_mask:0xf
	global_store_dwordx4 v[56:57], v[48:51], off
	v_max_f32_e32 v44, 0, v44
	v_max_f32_e32 v40, 0, v40
	v_add_co_u32_e32 v48, vcc, s68, v56
	v_max_f32_e32 v45, 0, v45
	v_max_f32_e32 v41, 0, v41
	v_max_f32_e32 v36, 0, v36
	v_max_f32_e32 v37, 0, v37
	v_max_f32_e32 v38, 0, v38
	v_max_f32_e32 v34, 0, v34
	v_max_f32_e32 v39, 0, v39
	v_cndmask_b32_e64 v52, v52, v58, s[6:7]
	v_cndmask_b32_e64 v53, v53, v59, s[6:7]
	v_cndmask_b32_e64 v54, v54, v62, s[6:7]
	v_cndmask_b32_e64 v55, v55, v63, s[6:7]
	v_addc_co_u32_e32 v49, vcc, 0, v57, vcc
	v_mul_f32_e32 v44, v44, v44
	v_mul_f32_e32 v40, v40, v40
	v_mul_f32_e32 v45, v45, v45
	v_mul_f32_e32 v41, v41, v41
	v_max_f32_e32 v46, 0, v46
	v_max_f32_e32 v42, 0, v42
	v_max_f32_e32 v47, 0, v47
	v_max_f32_e32 v43, 0, v43
	v_max_f32_e32 v32, 0, v32
	v_mul_f32_e32 v36, v36, v36
	v_max_f32_e32 v33, 0, v33
	v_mul_f32_e32 v37, v37, v37
	v_mul_f32_e32 v38, v38, v38
	v_mul_f32_e32 v34, v34, v34
	v_max_f32_e32 v35, 0, v35
	v_mul_f32_e32 v39, v39, v39
	global_store_dwordx4 v[48:49], v[52:55], off
	v_mul_f32_e32 v46, v46, v46
	v_mul_f32_e32 v42, v42, v42
	v_mul_f32_e32 v47, v47, v47
	v_mul_f32_e32 v43, v43, v43
	v_cvt_pk_bf16_f32 v44, v44, v45
	v_cvt_pk_bf16_f32 v45, v46, v47
	v_cvt_pk_bf16_f32 v40, v40, v41
	v_cvt_pk_bf16_f32 v41, v42, v43
	v_mul_f32_e32 v32, v32, v32
	v_mul_f32_e32 v33, v33, v33
	v_mul_f32_e32 v35, v35, v35
	v_cvt_pk_bf16_f32 v36, v36, v37
	v_cvt_pk_bf16_f32 v37, v38, v39
	v_cvt_pk_bf16_f32 v38, v32, v33
	v_cvt_pk_bf16_f32 v39, v34, v35
	v_mov_b32_e32 v34, 0
	v_mov_b32_dpp v34, v38 row_ror:8 row_mask:0xf bank_mask:0xf
; __device__ __forceinline__ unsigned cvt_pk_bf16(float lo, float hi) { unsigned r; asm volatile("v_cvt_pk_bf16_f32 %0, %1, %2" : "=v"(r) : "v"(lo), "v"(hi)); return r; }
; #define PG8_WAIT_V(n) asm volatile("s_waitcnt vmcnt(" #n ")" ::: "memory")
; #define PG8_BAR __builtin_amdgcn_s_barrier()
;     __device__ __forceinline__ void operator()(const f32x4 (&acc)[2][2][4][2], const Unit& u, int wr, int wc, int fr, int fq) const {
;     ...
;             for (int m = 0; m < 4; ++m) { const int row = row0 + ai * HALF + m * 16;
;                 const float rs = ssin ? __builtin_amdgcn_rsqf(ssin[row] * (1.f / D) + EPS) : 1.0f; float sq = 0.f; u32x4 w[2];
; #pragma unroll
;                 for (int bj = 0; bj < 2; ++bj) { f32x4 v0 = acc[ai][bj][m][0] * rs, v1 = acc[ai][bj][m][1] * rs;
;                     if (ACT == 1) {
; #pragma unroll
;                         for (int j = 0; j < 4; ++j) { const float a = fmaxf(v0[j], 0.f), b = fmaxf(v1[j], 0.f); v0[j] = a * a; v1[j] = b * b; } }
;                     sq += (v0[0] * v0[0] + v0[1] * v0[1]) + (v0[2] * v0[2] + v0[3] * v0[3]) + (v1[0] * v1[0] + v1[1] * v1[1]) + (v1[2] * v1[2] + v1[3] * v1[3]);
;                     w[bj].x = cvt_pk_bf16(v0[0], v0[1]); w[bj].y = cvt_pk_bf16(v0[2], v0[3]); w[bj].z = cvt_pk_bf16(v1[0], v1[1]); w[bj].w = cvt_pk_bf16(v1[2], v1[3]); }
;                 store_pair_lines(O, ldc, row, fr, col0, w[0], w[1]);
; template <class Epi>
; __device__ __forceinline__ void gemm_phase(LAS unsigned char* lds, const Gemm g, const StaticOrder& S, const Epi& E) {
;     ...
;         E(acc, cur, wr, wc, fr, fq);
;         if (!has_next) break;
; #pragma unroll
;         for (int a = 0; a < 2; ++a)
; #pragma unroll
;             for (int b = 0; b < 2; ++b)
; #pragma unroll
;                 for (int m = 0; m < 4; ++m)
; #pragma unroll
;                     for (int n = 0; n < 2; ++n) acc[a][b][m][n] = (f32x4){0.f, 0.f, 0.f, 0.f};
;         cur = nxt; cA = nA; cB = nB; ++ui;
;     }
;     PG8_WAIT_V(0);
;     if (wr == 0) PG8_BAR;
;     PG8_BAR;
	v_mov_b32_dpp v46, v40 row_ror:8 row_mask:0xf bank_mask:0xf
	v_mov_b32_dpp v35, v39 row_ror:8 row_mask:0xf bank_mask:0xf
	v_cndmask_b32_e64 v34, v34, v40, s[6:7]
	v_add_u32_e32 v40, v153, v160
	v_mov_b32_dpp v47, v41 row_ror:8 row_mask:0xf bank_mask:0xf
	v_cndmask_b32_e64 v35, v35, v41, s[6:7]
	v_ashrrev_i32_e32 v41, 31, v40
	v_lshlrev_b64 v[40:41], 14, v[40:41]
	v_mov_b32_dpp v32, v36 row_ror:8 row_mask:0xf bank_mask:0xf
	v_mov_b32_dpp v33, v37 row_ror:8 row_mask:0xf bank_mask:0xf
	v_lshl_add_u64 v[40:41], s[10:11], 0, v[40:41]
	v_cndmask_b32_e64 v32, v32, v44, s[6:7]
	v_cndmask_b32_e64 v33, v33, v45, s[6:7]
	v_lshl_add_u64 v[40:41], v[40:41], 0, v[112:113]
	v_mov_b32_dpp v42, v44 row_ror:8 row_mask:0xf bank_mask:0xf
	v_mov_b32_dpp v43, v45 row_ror:8 row_mask:0xf bank_mask:0xf
	global_store_dwordx4 v[40:41], v[32:35], off
	v_max_f32_e32 v28, 0, v28
	v_max_f32_e32 v24, 0, v24
	v_add_co_u32_e32 v32, vcc, s68, v40
	v_max_f32_e32 v29, 0, v29
	v_max_f32_e32 v25, 0, v25
	v_max_f32_e32 v20, 0, v20
	v_max_f32_e32 v21, 0, v21
	v_max_f32_e32 v22, 0, v22
	v_max_f32_e32 v18, 0, v18
	v_max_f32_e32 v23, 0, v23
	v_cndmask_b32_e64 v36, v36, v42, s[6:7]
	v_cndmask_b32_e64 v37, v37, v43, s[6:7]
	v_cndmask_b32_e64 v38, v38, v46, s[6:7]
	v_cndmask_b32_e64 v39, v39, v47, s[6:7]
	v_addc_co_u32_e32 v33, vcc, 0, v41, vcc
	v_mul_f32_e32 v28, v28, v28
	v_mul_f32_e32 v24, v24, v24
	v_mul_f32_e32 v29, v29, v29
	v_mul_f32_e32 v25, v25, v25
	v_max_f32_e32 v30, 0, v30
	v_max_f32_e32 v26, 0, v26
	v_max_f32_e32 v31, 0, v31
	v_max_f32_e32 v27, 0, v27
	v_max_f32_e32 v16, 0, v16
	v_mul_f32_e32 v20, v20, v20
	v_max_f32_e32 v17, 0, v17
	v_mul_f32_e32 v21, v21, v21
	v_mul_f32_e32 v22, v22, v22
	v_mul_f32_e32 v18, v18, v18
	v_max_f32_e32 v19, 0, v19
	v_mul_f32_e32 v23, v23, v23
	global_store_dwordx4 v[32:33], v[36:39], off
	v_mul_f32_e32 v30, v30, v30
	v_mul_f32_e32 v26, v26, v26
	v_mul_f32_e32 v31, v31, v31
	v_mul_f32_e32 v27, v27, v27
	v_cvt_pk_bf16_f32 v28, v28, v29
	v_cvt_pk_bf16_f32 v29, v30, v31
	v_cvt_pk_bf16_f32 v24, v24, v25
	v_cvt_pk_bf16_f32 v25, v26, v27
	v_mul_f32_e32 v16, v16, v16
	v_mul_f32_e32 v17, v17, v17
	v_mul_f32_e32 v19, v19, v19
	v_cvt_pk_bf16_f32 v20, v20, v21
	v_cvt_pk_bf16_f32 v21, v22, v23
	v_cvt_pk_bf16_f32 v22, v16, v17
	v_cvt_pk_bf16_f32 v23, v18, v19
	v_mov_b32_e32 v18, 0
	v_mov_b32_dpp v18, v22 row_ror:8 row_mask:0xf bank_mask:0xf
	v_mov_b32_dpp v30, v24 row_ror:8 row_mask:0xf bank_mask:0xf
	v_mov_b32_dpp v19, v23 row_ror:8 row_mask:0xf bank_mask:0xf
	v_cndmask_b32_e64 v18, v18, v24, s[6:7]
	v_add_u32_e32 v24, v154, v160
	v_mov_b32_dpp v31, v25 row_ror:8 row_mask:0xf bank_mask:0xf
	v_cndmask_b32_e64 v19, v19, v25, s[6:7]
	v_ashrrev_i32_e32 v25, 31, v24
	v_lshlrev_b64 v[24:25], 14, v[24:25]
	v_mov_b32_dpp v16, v20 row_ror:8 row_mask:0xf bank_mask:0xf
	v_mov_b32_dpp v17, v21 row_ror:8 row_mask:0xf bank_mask:0xf
	v_lshl_add_u64 v[24:25], s[10:11], 0, v[24:25]
	v_cndmask_b32_e64 v16, v16, v28, s[6:7]
	v_cndmask_b32_e64 v17, v17, v29, s[6:7]
	v_lshl_add_u64 v[24:25], v[24:25], 0, v[112:113]
	v_mov_b32_dpp v26, v28 row_ror:8 row_mask:0xf bank_mask:0xf
	v_mov_b32_dpp v27, v29 row_ror:8 row_mask:0xf bank_mask:0xf
	global_store_dwordx4 v[24:25], v[16:19], off
	v_max_f32_e32 v12, 0, v12
	v_max_f32_e32 v8, 0, v8
	v_add_co_u32_e32 v16, vcc, s68, v24
	v_max_f32_e32 v13, 0, v13
	v_max_f32_e32 v9, 0, v9
	v_max_f32_e32 v4, 0, v4
	v_max_f32_e32 v5, 0, v5
	v_max_f32_e32 v6, 0, v6
	v_max_f32_e32 v2, 0, v2
	v_max_f32_e32 v7, 0, v7
	v_cndmask_b32_e64 v20, v20, v26, s[6:7]
	v_cndmask_b32_e64 v21, v21, v27, s[6:7]
	v_cndmask_b32_e64 v22, v22, v30, s[6:7]
	v_cndmask_b32_e64 v23, v23, v31, s[6:7]
	v_addc_co_u32_e32 v17, vcc, 0, v25, vcc
	v_mul_f32_e32 v12, v12, v12
	v_mul_f32_e32 v8, v8, v8
	v_mul_f32_e32 v13, v13, v13
	v_mul_f32_e32 v9, v9, v9
	v_max_f32_e32 v14, 0, v14
	v_max_f32_e32 v10, 0, v10
	v_max_f32_e32 v15, 0, v15
	v_max_f32_e32 v11, 0, v11
	v_max_f32_e32 v0, 0, v0
	v_mul_f32_e32 v4, v4, v4
	v_max_f32_e32 v1, 0, v1
	v_mul_f32_e32 v5, v5, v5
	v_mul_f32_e32 v6, v6, v6
	v_mul_f32_e32 v2, v2, v2
	v_max_f32_e32 v3, 0, v3
	v_mul_f32_e32 v7, v7, v7
	global_store_dwordx4 v[16:17], v[20:23], off
	v_mul_f32_e32 v14, v14, v14
	v_mul_f32_e32 v10, v10, v10
	v_mul_f32_e32 v15, v15, v15
	v_mul_f32_e32 v11, v11, v11
	v_cvt_pk_bf16_f32 v12, v12, v13
	v_cvt_pk_bf16_f32 v13, v14, v15
	v_cvt_pk_bf16_f32 v8, v8, v9
	v_cvt_pk_bf16_f32 v9, v10, v11
	v_mul_f32_e32 v0, v0, v0
	v_mul_f32_e32 v1, v1, v1
	v_mul_f32_e32 v3, v3, v3
	v_cvt_pk_bf16_f32 v4, v4, v5
	v_cvt_pk_bf16_f32 v5, v6, v7
	v_cvt_pk_bf16_f32 v6, v0, v1
	v_cvt_pk_bf16_f32 v7, v2, v3
	v_mov_b32_e32 v2, 0
	v_mov_b32_dpp v2, v6 row_ror:8 row_mask:0xf bank_mask:0xf
	v_mov_b32_dpp v14, v8 row_ror:8 row_mask:0xf bank_mask:0xf
	v_mov_b32_dpp v3, v7 row_ror:8 row_mask:0xf bank_mask:0xf
	v_cndmask_b32_e64 v2, v2, v8, s[6:7]
	v_add_u32_e32 v8, v155, v160
	v_mov_b32_dpp v15, v9 row_ror:8 row_mask:0xf bank_mask:0xf
	v_cndmask_b32_e64 v3, v3, v9, s[6:7]
	v_ashrrev_i32_e32 v9, 31, v8
	v_lshlrev_b64 v[8:9], 14, v[8:9]
	v_mov_b32_dpp v0, v4 row_ror:8 row_mask:0xf bank_mask:0xf
	v_mov_b32_dpp v1, v5 row_ror:8 row_mask:0xf bank_mask:0xf
	v_lshl_add_u64 v[8:9], s[10:11], 0, v[8:9]
	v_cndmask_b32_e64 v0, v0, v12, s[6:7]
	v_cndmask_b32_e64 v1, v1, v13, s[6:7]
	v_lshl_add_u64 v[8:9], v[8:9], 0, v[112:113]
	global_store_dwordx4 v[8:9], v[0:3], off
	v_mov_b32_dpp v10, v12 row_ror:8 row_mask:0xf bank_mask:0xf
	v_mov_b32_dpp v11, v13 row_ror:8 row_mask:0xf bank_mask:0xf
	v_add_co_u32_e32 v0, vcc, 0x20000, v8
	v_cndmask_b32_e64 v4, v4, v10, s[6:7]
	s_nop 0
	v_addc_co_u32_e32 v1, vcc, 0, v9, vcc
	v_cndmask_b32_e64 v5, v5, v11, s[6:7]
	v_cndmask_b32_e64 v6, v6, v14, s[6:7]
	v_cndmask_b32_e64 v7, v7, v15, s[6:7]
	s_and_b64 vcc, exec, s[40:41]
	s_mov_b32 s69, s18
	s_mov_b32 s44, s36
	s_mov_b64 s[48:49], s[42:43]
	s_mov_b64 s[46:47], s[38:39]
	global_store_dwordx4 v[0:1], v[4:7], off
	s_cbranch_vccz .LBB0_725
	s_waitcnt vmcnt(0)
	s_cmpk_gt_u32 s52, 0xff
	s_cbranch_scc1 .LBB0_737
	s_barrier

; #define PG8_STAGE(bufoff, gbase, voff) do { _Pragma("unroll") for (int _i = 0; _i < 2; ++_i) \
;         __builtin_amdgcn_global_load_lds((const unsigned*)((const char*)(gbase) + (voff)[_i]), (LAS unsigned*)(lds + (bufoff) + ldsw + _i * 8192), 16, 0, 0); } while (0)
; #define PG8_LDA(dst, b, h) do { _Pragma("unroll") for (int m = 0; m < 4; ++m) _Pragma("unroll") for (int k = 0; k < 2; ++k) dst[m][k] = *(const LAS bf16x8*)(lds + PG8_SA(b, h) + aoff + m * 2048 + k * 1024); } while (0)
; #define PG8_LDB(dst, b, h) do { _Pragma("unroll") for (int n = 0; n < 2; ++n) _Pragma("unroll") for (int k = 0; k < 2; ++k) dst[n][k] = *(const LAS bf16x8*)(lds + PG8_SB(b, h) + boff + n * 2048 + k * 1024); } while (0)
; #define PG8_MMA(ai, bj, At, Bt) do { __builtin_amdgcn_s_setprio(1); _Pragma("unroll") for (int m = 0; m < 4; ++m) _Pragma("unroll") for (int n = 0; n < 2; ++n) _Pragma("unroll") for (int k = 0; k < 2; ++k) \
;         acc[ai][bj][m][n] = __builtin_amdgcn_mfma_f32_16x16x32_bf16(Bt[n][k], At[m][k], acc[ai][bj][m][n], 0, 0, 0); __builtin_amdgcn_s_setprio(0); } while (0)
; #define PG8_WAIT_V(n) asm volatile("s_waitcnt vmcnt(" #n ")" ::: "memory")
; #define PG8_WAIT_L(n) asm volatile("s_waitcnt lgkmcnt(" #n ")" ::: "memory")
; #define PG8_BAR __builtin_amdgcn_s_barrier()
; #define PG8_SCHED __builtin_amdgcn_sched_barrier(0)
; template <class Epi>
; __device__ __forceinline__ void gemm_phase(LAS unsigned char* lds, const Gemm g, const StaticOrder& S, const Epi& E) {
;     ...
;             PG8_LDB(B0, 0, 0); PG8_SCHED; PG8_LDA(At, 0, 0); PG8_STAGE(PG8_SA(1, 1), a1 + hstep, voffA);
;             PG8_WAIT_L(8); PG8_BAR; PG8_WAIT_L(0); PG8_MMA(0, 0, At, B0); PG8_BAR; PG8_SCHED;
;             PG8_LDB(B1, 0, 1); PG8_STAGE(PG8_SB(0, 0), b2, voffB0);
;             PG8_BAR; PG8_WAIT_L(0); PG8_MMA(0, 1, At, B1); PG8_BAR;
;             PG8_LDA(At, 0, 1); PG8_STAGE(PG8_SA(0, 0), a2, voffA);
;             PG8_BAR; PG8_WAIT_L(0); PG8_MMA(1, 0, At, B0); PG8_BAR; PG8_SCHED;
;             PG8_STAGE(PG8_SB(0, 1), b2, voffB1);
;             PG8_WAIT_V(6); PG8_BAR; PG8_MMA(1, 1, At, B1); PG8_BAR;
.LBB0_806:
	ds_read_b128 v[146:149], v156
	ds_read_b128 v[160:163], v156 offset:1024
	ds_read_b128 v[164:167], v156 offset:2048
	ds_read_b128 v[168:171], v156 offset:3072
	s_add_u32 s33, s50, 0xffe00080
	s_addc_u32 s52, s51, -1
	s_cmpk_eq_i32 s80, 0x7c
	s_cselect_b32 s53, s41, s52
	s_cselect_b32 s52, s75, s33
	s_cselect_b32 s55, s39, s79
	s_cselect_b32 s54, s77, s78
	v_lshl_add_u64 v[150:151], s[50:51], 0, v[140:141]
	s_add_i32 m0, s49, 0xc000
	ds_read_b128 v[172:175], v157
	ds_read_b128 v[176:179], v157 offset:1024
	ds_read_b128 v[180:183], v157 offset:2048
	ds_read_b128 v[184:187], v157 offset:3072
	ds_read_b128 v[188:191], v157 offset:4096
	ds_read_b128 v[192:195], v157 offset:5120
	ds_read_b128 v[196:199], v157 offset:6144
	ds_read_b128 v[204:207], v157 offset:7168
	global_load_lds_dwordx4 v[150:151], off
	v_lshl_add_u64 v[150:151], s[50:51], 0, v[142:143]
	s_add_i32 m0, s49, 0xe000
	s_nop 0
	global_load_lds_dwordx4 v[150:151], off
	s_waitcnt lgkmcnt(8)
	s_barrier
	s_waitcnt lgkmcnt(0)
	v_mfma_f32_16x16x32_bf16 v[124:127], v[146:149], v[172:175], v[124:127]
	v_mfma_f32_16x16x32_bf16 v[120:123], v[164:167], v[172:175], v[120:123]
	v_mfma_f32_16x16x32_bf16 v[108:111], v[146:149], v[180:183], v[108:111]
	v_mfma_f32_16x16x32_bf16 v[104:107], v[164:167], v[180:183], v[104:107]
	v_mfma_f32_16x16x32_bf16 v[92:95], v[146:149], v[188:191], v[92:95]
	v_mfma_f32_16x16x32_bf16 v[88:91], v[164:167], v[188:191], v[88:91]
	v_mfma_f32_16x16x32_bf16 v[76:79], v[146:149], v[196:199], v[76:79]
	v_mfma_f32_16x16x32_bf16 v[72:75], v[164:167], v[196:199], v[72:75]
	v_mfma_f32_16x16x32_bf16 v[124:127], v[160:163], v[176:179], v[124:127]
	v_mfma_f32_16x16x32_bf16 v[120:123], v[168:171], v[176:179], v[120:123]
	v_mfma_f32_16x16x32_bf16 v[108:111], v[160:163], v[184:187], v[108:111]
	v_mfma_f32_16x16x32_bf16 v[104:107], v[168:171], v[184:187], v[104:107]
	v_mfma_f32_16x16x32_bf16 v[92:95], v[160:163], v[192:195], v[92:95]
	v_mfma_f32_16x16x32_bf16 v[88:91], v[168:171], v[192:195], v[88:91]
	v_mfma_f32_16x16x32_bf16 v[76:79], v[160:163], v[204:207], v[76:79]
	v_mfma_f32_16x16x32_bf16 v[72:75], v[168:171], v[204:207], v[72:75]
	s_barrier
	s_add_i32 s33, s72, s62
	v_lshl_add_u64 v[150:151], s[54:55], 0, v[130:131]
	s_mov_b32 m0, s33
	ds_read_b128 v[208:211], v158
	ds_read_b128 v[212:215], v158 offset:1024
	ds_read_b128 v[216:219], v158 offset:2048
	ds_read_b128 v[220:223], v158 offset:3072
	global_load_lds_dwordx4 v[150:151], off
	v_lshl_add_u64 v[200:201], s[54:55], 0, v[136:137]
	s_add_i32 m0, s33, 0x2000
	s_nop 0
	global_load_lds_dwordx4 v[200:201], off
	s_waitcnt lgkmcnt(0)
	s_barrier
	s_waitcnt lgkmcnt(0)
	v_mfma_f32_16x16x32_bf16 v[116:119], v[208:211], v[172:175], v[116:119]
	v_mfma_f32_16x16x32_bf16 v[112:115], v[216:219], v[172:175], v[112:115]
	v_mfma_f32_16x16x32_bf16 v[100:103], v[208:211], v[180:183], v[100:103]
	v_mfma_f32_16x16x32_bf16 v[96:99], v[216:219], v[180:183], v[96:99]
	v_mfma_f32_16x16x32_bf16 v[84:87], v[208:211], v[188:191], v[84:87]
	v_mfma_f32_16x16x32_bf16 v[80:83], v[216:219], v[188:191], v[80:83]
	v_mfma_f32_16x16x32_bf16 v[68:71], v[208:211], v[196:199], v[68:71]
	v_mfma_f32_16x16x32_bf16 v[64:67], v[216:219], v[196:199], v[64:67]
	v_mfma_f32_16x16x32_bf16 v[116:119], v[212:215], v[176:179], v[116:119]
	v_mfma_f32_16x16x32_bf16 v[112:115], v[220:223], v[176:179], v[112:115]
	v_mfma_f32_16x16x32_bf16 v[100:103], v[212:215], v[184:187], v[100:103]
	v_mfma_f32_16x16x32_bf16 v[96:99], v[220:223], v[184:187], v[96:99]
	v_mfma_f32_16x16x32_bf16 v[84:87], v[212:215], v[192:195], v[84:87]
	v_mfma_f32_16x16x32_bf16 v[80:83], v[220:223], v[192:195], v[80:83]
	v_mfma_f32_16x16x32_bf16 v[68:71], v[212:215], v[204:207], v[68:71]
	v_mfma_f32_16x16x32_bf16 v[64:67], v[220:223], v[204:207], v[64:67]
	s_mov_b32 m0, s49
	v_lshl_add_u64 v[224:225], s[52:53], 0, v[128:129]
	s_barrier
	ds_read_b128 v[172:175], v157 offset:16384
	ds_read_b128 v[176:179], v157 offset:17408
	ds_read_b128 v[180:183], v157 offset:18432
	ds_read_b128 v[184:187], v157 offset:19456
	ds_read_b128 v[188:191], v157 offset:20480
	ds_read_b128 v[192:195], v157 offset:21504
	ds_read_b128 v[196:199], v157 offset:22528
	ds_read_b128 v[204:207], v157 offset:23552
	global_load_lds_dwordx4 v[224:225], off
	v_lshl_add_u64 v[226:227], s[52:53], 0, v[134:135]
	s_mov_b32 m0, s63
	s_nop 0
	global_load_lds_dwordx4 v[226:227], off
	s_add_i32 s33, s73, s62
	v_lshl_add_u64 v[228:229], s[54:55], 0, v[132:133]
	s_mov_b32 m0, s33
	v_lshl_add_u64 v[230:231], s[54:55], 0, v[138:139]
	global_load_lds_dwordx4 v[228:229], off
	s_add_i32 m0, s33, 0x2000
	s_nop 0
	global_load_lds_dwordx4 v[230:231], off
	s_waitcnt vmcnt(6)
	s_barrier
; #define PG8_STAGE(bufoff, gbase, voff) do { _Pragma("unroll") for (int _i = 0; _i < 2; ++_i) \
;         __builtin_amdgcn_global_load_lds((const unsigned*)((const char*)(gbase) + (voff)[_i]), (LAS unsigned*)(lds + (bufoff) + ldsw + _i * 8192), 16, 0, 0); } while (0)
; #define PG8_LDA(dst, b, h) do { _Pragma("unroll") for (int m = 0; m < 4; ++m) _Pragma("unroll") for (int k = 0; k < 2; ++k) dst[m][k] = *(const LAS bf16x8*)(lds + PG8_SA(b, h) + aoff + m * 2048 + k * 1024); } while (0)
; #define PG8_LDB(dst, b, h) do { _Pragma("unroll") for (int n = 0; n < 2; ++n) _Pragma("unroll") for (int k = 0; k < 2; ++k) dst[n][k] = *(const LAS bf16x8*)(lds + PG8_SB(b, h) + boff + n * 2048 + k * 1024); } while (0)
; #define PG8_MMA(ai, bj, At, Bt) do { __builtin_amdgcn_s_setprio(1); _Pragma("unroll") for (int m = 0; m < 4; ++m) _Pragma("unroll") for (int n = 0; n < 2; ++n) _Pragma("unroll") for (int k = 0; k < 2; ++k) \
;         acc[ai][bj][m][n] = __builtin_amdgcn_mfma_f32_16x16x32_bf16(Bt[n][k], At[m][k], acc[ai][bj][m][n], 0, 0, 0); __builtin_amdgcn_s_setprio(0); } while (0)
; #define PG8_WAIT_V(n) asm volatile("s_waitcnt vmcnt(" #n ")" ::: "memory")
; #define PG8_WAIT_L(n) asm volatile("s_waitcnt lgkmcnt(" #n ")" ::: "memory")
; #define PG8_BAR __builtin_amdgcn_s_barrier()
; #define PG8_SCHED __builtin_amdgcn_sched_barrier(0)
; template <class Epi>
; __device__ __forceinline__ void gemm_phase(LAS unsigned char* lds, const Gemm g, const StaticOrder& S, const Epi& E) {
;     ...
;             PG8_WAIT_V(6); PG8_BAR; PG8_MMA(1, 1, At, B1); PG8_BAR;
;             PG8_LDB(B0, 1, 0); PG8_SCHED; PG8_LDA(At, 1, 0); PG8_STAGE(PG8_SA(0, 1), a2 + hstep, voffA);
;             PG8_WAIT_L(8); PG8_BAR; PG8_WAIT_L(0); PG8_MMA(0, 0, At, B0); PG8_BAR; PG8_SCHED;
;             PG8_LDB(B1, 1, 1); PG8_STAGE(PG8_SB(1, 0), b3, voffB0);
;             PG8_BAR; PG8_WAIT_L(0); PG8_MMA(0, 1, At, B1); PG8_BAR;
;             PG8_LDA(At, 1, 1); PG8_STAGE(PG8_SA(1, 0), a3, voffA);
;             PG8_BAR; PG8_WAIT_L(0); PG8_MMA(1, 0, At, B0); PG8_BAR; PG8_SCHED;
	s_waitcnt lgkmcnt(0)
	v_mfma_f32_16x16x32_bf16 v[60:63], v[146:149], v[172:175], v[60:63]
	v_mfma_f32_16x16x32_bf16 v[56:59], v[164:167], v[172:175], v[56:59]
	v_mfma_f32_16x16x32_bf16 v[44:47], v[146:149], v[180:183], v[44:47]
	v_mfma_f32_16x16x32_bf16 v[40:43], v[164:167], v[180:183], v[40:43]
	v_mfma_f32_16x16x32_bf16 v[28:31], v[146:149], v[188:191], v[28:31]
	v_mfma_f32_16x16x32_bf16 v[24:27], v[164:167], v[188:191], v[24:27]
	v_mfma_f32_16x16x32_bf16 v[12:15], v[146:149], v[196:199], v[12:15]
	v_mfma_f32_16x16x32_bf16 v[8:11], v[164:167], v[196:199], v[8:11]
	v_mfma_f32_16x16x32_bf16 v[60:63], v[160:163], v[176:179], v[60:63]
	v_mfma_f32_16x16x32_bf16 v[56:59], v[168:171], v[176:179], v[56:59]
	v_mfma_f32_16x16x32_bf16 v[44:47], v[160:163], v[184:187], v[44:47]
	v_mfma_f32_16x16x32_bf16 v[40:43], v[168:171], v[184:187], v[40:43]
	v_mfma_f32_16x16x32_bf16 v[28:31], v[160:163], v[192:195], v[28:31]
	v_mfma_f32_16x16x32_bf16 v[24:27], v[168:171], v[192:195], v[24:27]
	v_mfma_f32_16x16x32_bf16 v[12:15], v[160:163], v[204:207], v[12:15]
	v_mfma_f32_16x16x32_bf16 v[8:11], v[168:171], v[204:207], v[8:11]
	v_mfma_f32_16x16x32_bf16 v[52:55], v[208:211], v[172:175], v[52:55]
	v_mfma_f32_16x16x32_bf16 v[48:51], v[216:219], v[172:175], v[48:51]
	v_mfma_f32_16x16x32_bf16 v[36:39], v[208:211], v[180:183], v[36:39]
	v_mfma_f32_16x16x32_bf16 v[32:35], v[216:219], v[180:183], v[32:35]
	v_mfma_f32_16x16x32_bf16 v[20:23], v[208:211], v[188:191], v[20:23]
	v_mfma_f32_16x16x32_bf16 v[16:19], v[216:219], v[188:191], v[16:19]
	v_mfma_f32_16x16x32_bf16 v[4:7], v[208:211], v[196:199], v[4:7]
	v_mfma_f32_16x16x32_bf16 v[0:3], v[216:219], v[196:199], v[0:3]
	v_mfma_f32_16x16x32_bf16 v[52:55], v[212:215], v[176:179], v[52:55]
	v_mfma_f32_16x16x32_bf16 v[48:51], v[220:223], v[176:179], v[48:51]
	v_mfma_f32_16x16x32_bf16 v[36:39], v[212:215], v[184:187], v[36:39]
	v_mfma_f32_16x16x32_bf16 v[32:35], v[220:223], v[184:187], v[32:35]
	v_mfma_f32_16x16x32_bf16 v[20:23], v[212:215], v[192:195], v[20:23]
	v_mfma_f32_16x16x32_bf16 v[16:19], v[220:223], v[192:195], v[16:19]
	v_mfma_f32_16x16x32_bf16 v[4:7], v[212:215], v[204:207], v[4:7]
	v_mfma_f32_16x16x32_bf16 v[0:3], v[220:223], v[204:207], v[0:3]
	s_add_i32 s33, 0, 0x18000
	v_add_u32_e32 v168, s33, v153
	s_barrier
	ds_read_b128 v[146:149], v168
	ds_read_b128 v[160:163], v168 offset:1024
	ds_read_b128 v[164:167], v168 offset:2048
	ds_read_b128 v[168:171], v168 offset:3072
	s_add_u32 s52, s52, 0x200000
	s_addc_u32 s53, s53, 0
	s_mov_b32 m0, s64
	v_lshl_add_u64 v[208:209], s[52:53], 0, v[128:129]
	ds_read_b128 v[172:175], v157 offset:32768
	ds_read_b128 v[176:179], v157 offset:33792
	ds_read_b128 v[180:183], v157 offset:34816
	ds_read_b128 v[184:187], v157 offset:35840
	ds_read_b128 v[188:191], v157 offset:36864
	ds_read_b128 v[192:195], v157 offset:37888
	ds_read_b128 v[196:199], v157 offset:38912
	ds_read_b128 v[204:207], v157 offset:39936
	global_load_lds_dwordx4 v[208:209], off
	v_lshl_add_u64 v[208:209], s[52:53], 0, v[134:135]
	s_mov_b32 m0, s65
	s_nop 0
	global_load_lds_dwordx4 v[208:209], off
	s_waitcnt lgkmcnt(8)
	s_barrier
	s_waitcnt lgkmcnt(0)
	v_mfma_f32_16x16x32_bf16 v[124:127], v[146:149], v[172:175], v[124:127]
	v_mfma_f32_16x16x32_bf16 v[120:123], v[164:167], v[172:175], v[120:123]
	v_mfma_f32_16x16x32_bf16 v[108:111], v[146:149], v[180:183], v[108:111]
	v_mfma_f32_16x16x32_bf16 v[104:107], v[164:167], v[180:183], v[104:107]
	v_mfma_f32_16x16x32_bf16 v[92:95], v[146:149], v[188:191], v[92:95]
	v_mfma_f32_16x16x32_bf16 v[88:91], v[164:167], v[188:191], v[88:91]
	v_mfma_f32_16x16x32_bf16 v[76:79], v[146:149], v[196:199], v[76:79]
	v_mfma_f32_16x16x32_bf16 v[72:75], v[164:167], v[196:199], v[72:75]
	v_mfma_f32_16x16x32_bf16 v[124:127], v[160:163], v[176:179], v[124:127]
	v_mfma_f32_16x16x32_bf16 v[120:123], v[168:171], v[176:179], v[120:123]
	v_mfma_f32_16x16x32_bf16 v[108:111], v[160:163], v[184:187], v[108:111]
	v_mfma_f32_16x16x32_bf16 v[104:107], v[168:171], v[184:187], v[104:107]
	v_mfma_f32_16x16x32_bf16 v[92:95], v[160:163], v[192:195], v[92:95]
	v_mfma_f32_16x16x32_bf16 v[88:91], v[168:171], v[192:195], v[88:91]
	v_mfma_f32_16x16x32_bf16 v[76:79], v[160:163], v[204:207], v[76:79]
	v_mfma_f32_16x16x32_bf16 v[72:75], v[168:171], v[204:207], v[72:75]
	s_barrier
	s_add_i32 s52, 0, 0x1c000
	s_add_i32 s33, s33, s62
	v_add_u32_e32 v220, s52, v153
	v_lshl_add_u64 v[150:151], v[150:151], 0, s[18:19]
	s_mov_b32 m0, s33
	ds_read_b128 v[208:211], v220
	ds_read_b128 v[212:215], v220 offset:1024
	ds_read_b128 v[216:219], v220 offset:2048
	ds_read_b128 v[220:223], v220 offset:3072
	global_load_lds_dwordx4 v[150:151], off
	v_lshl_add_u64 v[150:151], v[200:201], 0, s[18:19]
	s_add_i32 m0, s33, 0x2000
	s_nop 0
	global_load_lds_dwordx4 v[150:151], off
	s_waitcnt lgkmcnt(0)
	s_barrier
	s_waitcnt lgkmcnt(0)
	v_mfma_f32_16x16x32_bf16 v[116:119], v[208:211], v[172:175], v[116:119]
	v_mfma_f32_16x16x32_bf16 v[112:115], v[216:219], v[172:175], v[112:115]
	v_mfma_f32_16x16x32_bf16 v[100:103], v[208:211], v[180:183], v[100:103]
	v_mfma_f32_16x16x32_bf16 v[96:99], v[216:219], v[180:183], v[96:99]
	v_mfma_f32_16x16x32_bf16 v[84:87], v[208:211], v[188:191], v[84:87]
	v_mfma_f32_16x16x32_bf16 v[80:83], v[216:219], v[188:191], v[80:83]
	v_mfma_f32_16x16x32_bf16 v[68:71], v[208:211], v[196:199], v[68:71]
	v_mfma_f32_16x16x32_bf16 v[64:67], v[216:219], v[196:199], v[64:67]
	v_mfma_f32_16x16x32_bf16 v[116:119], v[212:215], v[176:179], v[116:119]
	v_mfma_f32_16x16x32_bf16 v[112:115], v[220:223], v[176:179], v[112:115]
	v_mfma_f32_16x16x32_bf16 v[100:103], v[212:215], v[184:187], v[100:103]
	v_mfma_f32_16x16x32_bf16 v[96:99], v[220:223], v[184:187], v[96:99]
	v_mfma_f32_16x16x32_bf16 v[84:87], v[212:215], v[192:195], v[84:87]
	v_mfma_f32_16x16x32_bf16 v[80:83], v[220:223], v[192:195], v[80:83]
	v_mfma_f32_16x16x32_bf16 v[68:71], v[212:215], v[204:207], v[68:71]
	v_mfma_f32_16x16x32_bf16 v[64:67], v[220:223], v[204:207], v[64:67]
	s_mov_b32 m0, s67
	v_lshl_add_u64 v[150:151], v[224:225], 0, s[18:19]
	s_barrier
; __device__ __forceinline__ float bflo(unsigned w) { return __uint_as_float(w << 16); }
; __device__ __forceinline__ float bfhi(unsigned w) { return __uint_as_float(w & 0xffff0000u); }
; __device__ __forceinline__ unsigned dpp_ror8(unsigned x) { return (unsigned)__builtin_amdgcn_update_dpp(0, (int)x, 0x128, 0xf, 0xf, false); }
; #define PG8_STAGE(bufoff, gbase, voff) do { _Pragma("unroll") for (int _i = 0; _i < 2; ++_i) \
;         __builtin_amdgcn_global_load_lds((const unsigned*)((const char*)(gbase) + (voff)[_i]), (LAS unsigned*)(lds + (bufoff) + ldsw + _i * 8192), 16, 0, 0); } while (0)
; #define PG8_WAIT_V(n) asm volatile("s_waitcnt vmcnt(" #n ")" ::: "memory")
; #define PG8_WAIT_L(n) asm volatile("s_waitcnt lgkmcnt(" #n ")" ::: "memory")
;     const bool lo = fr < 8;
;     const int r1 = row - fr + (fr & 7), cb = col0 + (lo ? 0 : boff);
;     const u32x4 l1 = *(const u32x4*)(P + (size_t)r1 * ld + cb), l2 = *(const u32x4*)(P + (size_t)(r1 + 8) * ld + cb);
;     const u32x4 s1 = {dpp_ror8(l1.x), dpp_ror8(l1.y), dpp_ror8(l1.z), dpp_ror8(l1.w)}, s2 = {dpp_ror8(l2.x), dpp_ror8(l2.y), dpp_ror8(l2.z), dpp_ror8(l2.w)};
;     wA = lo ? l1 : s2; wB = lo ? s1 : l2;
; }
;     __device__ __forceinline__ void operator()(const f32x4 (&acc)[2][2][4][2], const Unit& u, int wr, int wc, int fr, int fq) const {
;     ...
;             for (int m = 0; m < 4; ++m) { const int row = row0 + ai * HALF + m * 16; const size_t off = (size_t)row * D + col0; float sq = 0.f; u32x4 w[2];
;                 const float sc = rsin ? __builtin_amdgcn_rcpf(rsin[row] * (1.f / D) + EPS) : 1.0f;
;                 u32x4 rr[2]; if (R) load_pair_lines(R, D, row, fr, col0, rr[0], rr[1]);
; #pragma unroll
;                 for (int bj = 0; bj < 2; ++bj) { f32x4 r0, r1;
;                     if (R) { const u32x4 rw = rr[bj]; r0 = (f32x4){bflo(rw.x), bfhi(rw.x), bflo(rw.y), bfhi(rw.y)}; r1 = (f32x4){bflo(rw.z), bfhi(rw.z), bflo(rw.w), bfhi(rw.w)}; }
; template <class Epi>
; __device__ __forceinline__ void gemm_phase(LAS unsigned char* lds, const Gemm g, const StaticOrder& S, const Epi& E) {
;     ...
;             PG8_LDA(At, 1, 1); PG8_STAGE(PG8_SA(1, 0), a3, voffA);
;             PG8_BAR; PG8_WAIT_L(0); PG8_MMA(1, 0, At, B0); PG8_BAR; PG8_SCHED;
;             PG8_STAGE(PG8_SB(1, 1), b3, voffB1);
;             PG8_WAIT_V(6); PG8_BAR; PG8_MMA(1, 1, At, B1); PG8_BAR;
;         }
	ds_read_b128 v[172:175], v157 offset:49152
	ds_read_b128 v[176:179], v157 offset:50176
	ds_read_b128 v[180:183], v157 offset:51200
	ds_read_b128 v[184:187], v157 offset:52224
	ds_read_b128 v[188:191], v157 offset:53248
	ds_read_b128 v[192:195], v157 offset:54272
	ds_read_b128 v[196:199], v157 offset:55296
	ds_read_b128 v[204:207], v157 offset:56320
	global_load_lds_dwordx4 v[150:151], off
	v_lshl_add_u64 v[150:151], v[226:227], 0, s[18:19]
	s_mov_b32 m0, s68
	s_nop 0
	global_load_lds_dwordx4 v[150:151], off
	s_add_i32 s33, s52, s62
	v_lshl_add_u64 v[250:251], v[228:229], 0, s[18:19]
	s_mov_b32 m0, s33
	s_nop 0
	global_load_lds_dwordx4 v[250:251], off
	v_lshl_add_u64 v[250:251], v[230:231], 0, s[18:19]
	s_add_i32 m0, s33, 0x2000
	s_nop 0
	global_load_lds_dwordx4 v[250:251], off
	s_waitcnt vmcnt(6)
	s_barrier
	s_waitcnt lgkmcnt(0)
	v_mfma_f32_16x16x32_bf16 v[60:63], v[146:149], v[172:175], v[60:63]
	v_mfma_f32_16x16x32_bf16 v[56:59], v[164:167], v[172:175], v[56:59]
	v_mfma_f32_16x16x32_bf16 v[44:47], v[146:149], v[180:183], v[44:47]
	v_mfma_f32_16x16x32_bf16 v[40:43], v[164:167], v[180:183], v[40:43]
	v_mfma_f32_16x16x32_bf16 v[28:31], v[146:149], v[188:191], v[28:31]
	v_mfma_f32_16x16x32_bf16 v[24:27], v[164:167], v[188:191], v[24:27]
	v_mfma_f32_16x16x32_bf16 v[12:15], v[146:149], v[196:199], v[12:15]
	v_mfma_f32_16x16x32_bf16 v[8:11], v[164:167], v[196:199], v[8:11]
	v_mfma_f32_16x16x32_bf16 v[60:63], v[160:163], v[176:179], v[60:63]
	v_mfma_f32_16x16x32_bf16 v[56:59], v[168:171], v[176:179], v[56:59]
	v_mfma_f32_16x16x32_bf16 v[44:47], v[160:163], v[184:187], v[44:47]
	v_mfma_f32_16x16x32_bf16 v[40:43], v[168:171], v[184:187], v[40:43]
	v_mfma_f32_16x16x32_bf16 v[28:31], v[160:163], v[192:195], v[28:31]
	v_mfma_f32_16x16x32_bf16 v[24:27], v[168:171], v[192:195], v[24:27]
	v_mfma_f32_16x16x32_bf16 v[12:15], v[160:163], v[204:207], v[12:15]
	v_mfma_f32_16x16x32_bf16 v[8:11], v[168:171], v[204:207], v[8:11]
	v_mfma_f32_16x16x32_bf16 v[52:55], v[208:211], v[172:175], v[52:55]
	v_mfma_f32_16x16x32_bf16 v[48:51], v[216:219], v[172:175], v[48:51]
	v_mfma_f32_16x16x32_bf16 v[36:39], v[208:211], v[180:183], v[36:39]
	v_mfma_f32_16x16x32_bf16 v[32:35], v[216:219], v[180:183], v[32:35]
	v_mfma_f32_16x16x32_bf16 v[20:23], v[208:211], v[188:191], v[20:23]
	v_mfma_f32_16x16x32_bf16 v[16:19], v[216:219], v[188:191], v[16:19]
	v_mfma_f32_16x16x32_bf16 v[4:7], v[208:211], v[196:199], v[4:7]
	v_mfma_f32_16x16x32_bf16 v[0:3], v[216:219], v[196:199], v[0:3]
	v_mfma_f32_16x16x32_bf16 v[52:55], v[212:215], v[176:179], v[52:55]
	v_mfma_f32_16x16x32_bf16 v[48:51], v[220:223], v[176:179], v[48:51]
	v_mfma_f32_16x16x32_bf16 v[36:39], v[212:215], v[184:187], v[36:39]
	v_mfma_f32_16x16x32_bf16 v[32:35], v[220:223], v[184:187], v[32:35]
	v_mfma_f32_16x16x32_bf16 v[20:23], v[212:215], v[192:195], v[20:23]
	v_mfma_f32_16x16x32_bf16 v[16:19], v[220:223], v[192:195], v[16:19]
	v_mfma_f32_16x16x32_bf16 v[4:7], v[212:215], v[204:207], v[4:7]
	v_mfma_f32_16x16x32_bf16 v[0:3], v[220:223], v[204:207], v[0:3]
	s_add_i32 s80, s80, 2
	s_add_u32 s50, s50, 0x100
	s_addc_u32 s51, s51, 0
	s_add_u32 s78, s78, 0x100
	s_addc_u32 s79, s79, 0
	s_cmpk_gt_u32 s80, 0x7d
	s_barrier
	s_cbranch_scc0 .LBB0_806
	s_lshl_b32 s33, s48, 8
	s_add_i32 s33, s33, s69
	v_or_b32_e32 v164, s33, v154
	v_ashrrev_i32_e32 v165, 31, v164
	v_lshl_or_b32 v146, s74, 8, v155
	v_lshlrev_b64 v[168:169], 12, v[164:165]
	v_or_b32_e32 v164, 8, v164
	v_or_b32_e32 v150, s33, v152
	v_ashrrev_i32_e32 v147, 31, v146
	v_ashrrev_i32_e32 v165, 31, v164
	v_ashrrev_i32_e32 v151, 31, v150
	v_lshl_add_u64 v[160:161], s[16:17], 0, v[168:169]
	v_lshlrev_b64 v[146:147], 1, v[146:147]
	v_lshlrev_b64 v[170:171], 12, v[164:165]
	v_lshl_add_u64 v[148:149], v[150:151], 2, s[10:11]
	v_lshl_add_u64 v[160:161], v[160:161], 0, v[146:147]
	v_lshl_add_u64 v[164:165], s[16:17], 0, v[170:171]
	global_load_dword v151, v[148:149], off
	s_nop 0
	global_load_dwordx4 v[160:163], v[160:161], off
	v_lshl_add_u64 v[164:165], v[164:165], 0, v[146:147]
	global_load_dwordx4 v[164:167], v[164:165], off
	v_or_b32_e32 v190, 16, v150
	v_ashrrev_i32_e32 v191, 31, v190
	v_lshl_add_u64 v[192:193], v[190:191], 2, s[10:11]
	v_sub_u32_e32 v190, v190, v152
	v_add_u32_e32 v190, v190, v154
	v_ashrrev_i32_e32 v191, 31, v190
	v_lshlrev_b64 v[196:197], 12, v[190:191]
	v_lshl_add_u64 v[190:191], s[16:17], 0, v[196:197]
	v_lshl_add_u64 v[198:199], v[196:197], 0, s[36:37]
	v_lshl_add_u64 v[190:191], v[190:191], 0, v[146:147]
	v_lshl_add_u64 v[194:195], s[16:17], 0, v[198:199]
	global_load_dword v204, v[192:193], off
	global_load_dwordx4 v[208:211], v[190:191], off
	v_lshl_add_u64 v[194:195], v[194:195], 0, v[146:147]
	global_load_dwordx4 v[212:215], v[194:195], off
	v_or_b32_e32 v190, 32, v150
	v_ashrrev_i32_e32 v191, 31, v190
	v_lshl_add_u64 v[192:193], v[190:191], 2, s[10:11]
	v_sub_u32_e32 v190, v190, v152
	v_add_u32_e32 v190, v190, v154
	v_ashrrev_i32_e32 v191, 31, v190
	v_lshlrev_b64 v[196:197], 12, v[190:191]
	v_lshl_add_u64 v[190:191], s[16:17], 0, v[196:197]
	v_lshl_add_u64 v[198:199], v[196:197], 0, s[36:37]
	v_lshl_add_u64 v[190:191], v[190:191], 0, v[146:147]
	v_lshl_add_u64 v[194:195], s[16:17], 0, v[198:199]
	global_load_dword v205, v[192:193], off
	global_load_dwordx4 v[216:219], v[190:191], off
	v_lshl_add_u64 v[194:195], v[194:195], 0, v[146:147]
	global_load_dwordx4 v[220:223], v[194:195], off
	v_or_b32_e32 v190, 48, v150
	v_ashrrev_i32_e32 v191, 31, v190
	v_lshl_add_u64 v[192:193], v[190:191], 2, s[10:11]
	v_sub_u32_e32 v190, v190, v152
	v_add_u32_e32 v190, v190, v154
	v_ashrrev_i32_e32 v191, 31, v190
	v_lshlrev_b64 v[196:197], 12, v[190:191]
; __device__ __forceinline__ unsigned cvt_pk_bf16(float lo, float hi) { unsigned r; asm volatile("v_cvt_pk_bf16_f32 %0, %1, %2" : "=v"(r) : "v"(lo), "v"(hi)); return r; }
; __device__ __forceinline__ float bflo(unsigned w) { return __uint_as_float(w << 16); }
; __device__ __forceinline__ float bfhi(unsigned w) { return __uint_as_float(w & 0xffff0000u); }
; __device__ __forceinline__ unsigned dpp_ror8(unsigned x) { return (unsigned)__builtin_amdgcn_update_dpp(0, (int)x, 0x128, 0xf, 0xf, false); }
;     const bool lo = fr < 8;
;     const int r1 = row - fr + (fr & 7), cb = col0 + (lo ? 0 : boff);
;     const u32x4 l1 = *(const u32x4*)(P + (size_t)r1 * ld + cb), l2 = *(const u32x4*)(P + (size_t)(r1 + 8) * ld + cb);
;     const u32x4 s1 = {dpp_ror8(l1.x), dpp_ror8(l1.y), dpp_ror8(l1.z), dpp_ror8(l1.w)}, s2 = {dpp_ror8(l2.x), dpp_ror8(l2.y), dpp_ror8(l2.z), dpp_ror8(l2.w)};
;     wA = lo ? l1 : s2; wB = lo ? s1 : l2;
; }
;     __device__ __forceinline__ void operator()(const f32x4 (&acc)[2][2][4][2], const Unit& u, int wr, int wc, int fr, int fq) const {
;     ...
;             for (int m = 0; m < 4; ++m) { const int row = row0 + ai * HALF + m * 16; const size_t off = (size_t)row * D + col0; float sq = 0.f; u32x4 w[2];
;                 const float sc = rsin ? __builtin_amdgcn_rcpf(rsin[row] * (1.f / D) + EPS) : 1.0f;
;                 u32x4 rr[2]; if (R) load_pair_lines(R, D, row, fr, col0, rr[0], rr[1]);
; #pragma unroll
;                 for (int bj = 0; bj < 2; ++bj) { f32x4 r0, r1;
;                     if (R) { const u32x4 rw = rr[bj]; r0 = (f32x4){bflo(rw.x), bfhi(rw.x), bflo(rw.y), bfhi(rw.y)}; r1 = (f32x4){bflo(rw.z), bfhi(rw.z), bflo(rw.w), bfhi(rw.w)}; }
;                     else { const float* rp = (row < 8192 ? src_p + off : src_s + (off - (size_t)8192 * D)) + 8 * bj; r0 = *(const f32x4*)rp; r1 = *(const f32x4*)(rp + 4); }
;                     const f32x4 o0 = r0 + acc[ai][bj][m][0] * sc, o1 = r1 + acc[ai][bj][m][1] * sc;
;                     sq += (o0[0] * o0[0] + o0[1] * o0[1]) + (o0[2] * o0[2] + o0[3] * o0[3]) + (o1[0] * o1[0] + o1[1] * o1[1]) + (o1[2] * o1[2] + o1[3] * o1[3]);
;                     w[bj].x = cvt_pk_bf16(o0[0], o0[1]); w[bj].y = cvt_pk_bf16(o0[2], o0[3]); w[bj].z = cvt_pk_bf16(o1[0], o1[1]); w[bj].w = cvt_pk_bf16(o1[2], o1[3]); }
;                 store_pair_lines(O, D, row, fr, col0, w[0], w[1]);
	v_lshl_add_u64 v[190:191], s[16:17], 0, v[196:197]
	v_lshl_add_u64 v[198:199], v[196:197], 0, s[36:37]
	v_lshl_add_u64 v[190:191], v[190:191], 0, v[146:147]
	v_lshl_add_u64 v[194:195], s[16:17], 0, v[198:199]
	global_load_dword v206, v[192:193], off
	global_load_dwordx4 v[224:227], v[190:191], off
	v_lshl_add_u64 v[194:195], v[194:195], 0, v[146:147]
	global_load_dwordx4 v[228:231], v[194:195], off
	v_sub_u32_e32 v190, v150, v152
	v_add_u32_e32 v199, v190, v154
	v_add_u32_e32 v190, 0x80, v199
	v_ashrrev_i32_e32 v191, 31, v190
	v_lshlrev_b64 v[194:195], 12, v[190:191]
	v_lshl_add_u64 v[190:191], s[16:17], 0, v[194:195]
	v_lshl_add_u64 v[196:197], v[194:195], 0, s[36:37]
	v_lshl_add_u64 v[190:191], v[190:191], 0, v[146:147]
	v_lshl_add_u64 v[192:193], s[16:17], 0, v[196:197]
	global_load_dword v207, v[148:149], off offset:512
	global_load_dwordx4 v[232:235], v[190:191], off
	v_lshl_add_u64 v[192:193], v[192:193], 0, v[146:147]
	global_load_dwordx4 v[236:239], v[192:193], off
	v_sub_u32_e32 v198, v150, v152
	v_add_u32_e32 v201, v198, v154
	v_add_u32_e32 v190, 0x90, v201
	v_ashrrev_i32_e32 v191, 31, v190
	v_lshlrev_b64 v[194:195], 12, v[190:191]
	v_lshl_add_u64 v[190:191], s[16:17], 0, v[194:195]
	v_lshl_add_u64 v[196:197], v[194:195], 0, s[36:37]
	v_lshl_add_u64 v[190:191], v[190:191], 0, v[146:147]
	v_lshl_add_u64 v[192:193], s[16:17], 0, v[196:197]
	global_load_dword v240, v[148:149], off offset:576
	global_load_dwordx4 v[244:247], v[190:191], off
	v_lshl_add_u64 v[192:193], v[192:193], 0, v[146:147]
	global_load_dwordx4 v[248:251], v[192:193], off
	s_and_b64 vcc, exec, s[44:45]
	s_mov_b32 s74, s38
	s_mov_b32 s48, s40
	s_mov_b64 s[52:53], s[46:47]
	s_mov_b64 s[50:51], s[42:43]
	s_waitcnt vmcnt(15)
	v_fmamk_f32 v151, v151, 0x3a000000, v159
	v_rcp_f32_e32 v172, v151
	v_mov_b32_dpp v173, v160 row_ror:8 row_mask:0xf bank_mask:0xf
	v_mov_b32_dpp v174, v161 row_ror:8 row_mask:0xf bank_mask:0xf
	v_mov_b32_dpp v175, v162 row_ror:8 row_mask:0xf bank_mask:0xf
	v_mov_b32_dpp v177, v164 row_ror:8 row_mask:0xf bank_mask:0xf
	v_mov_b32_dpp v178, v165 row_ror:8 row_mask:0xf bank_mask:0xf
	v_mov_b32_dpp v179, v166 row_ror:8 row_mask:0xf bank_mask:0xf
	v_mov_b32_dpp v176, v163 row_ror:8 row_mask:0xf bank_mask:0xf
	v_mov_b32_dpp v180, v167 row_ror:8 row_mask:0xf bank_mask:0xf
	v_cndmask_b32_e64 v166, v166, v175, s[6:7]
	v_cndmask_b32_e64 v165, v165, v174, s[6:7]
	v_cndmask_b32_e64 v164, v164, v173, s[6:7]
	v_cndmask_b32_e64 v179, v179, v162, s[6:7]
	v_cndmask_b32_e64 v178, v178, v161, s[6:7]
	v_cndmask_b32_e64 v175, v177, v160, s[6:7]
	v_cndmask_b32_e64 v151, v167, v176, s[6:7]
	v_cndmask_b32_e64 v173, v180, v163, s[6:7]
	v_lshlrev_b32_e32 v160, 16, v164
	v_and_b32_e32 v161, 0xffff0000, v164
	v_lshlrev_b32_e32 v162, 16, v165
	v_and_b32_e32 v163, 0xffff0000, v165
	v_lshlrev_b32_e32 v174, 16, v175
	v_and_b32_e32 v175, 0xffff0000, v175
	v_lshlrev_b32_e32 v176, 16, v178
	v_and_b32_e32 v177, 0xffff0000, v178
	v_lshlrev_b32_e32 v178, 16, v179
	v_and_b32_e32 v179, 0xffff0000, v179
	v_lshlrev_b32_e32 v164, 16, v166
	v_and_b32_e32 v165, 0xffff0000, v166
	v_lshlrev_b32_e32 v166, 16, v151
	v_and_b32_e32 v167, 0xffff0000, v151
	v_lshlrev_b32_e32 v180, 16, v173
	v_and_b32_e32 v181, 0xffff0000, v173
	v_pk_fma_f32 v[118:119], v[118:119], v[172:173], v[162:163] op_sel_hi:[1,0,1]
	v_pk_fma_f32 v[116:117], v[116:117], v[172:173], v[160:161] op_sel_hi:[1,0,1]
	v_pk_fma_f32 v[124:125], v[124:125], v[172:173], v[174:175] op_sel_hi:[1,0,1]
	v_pk_fma_f32 v[120:121], v[120:121], v[172:173], v[178:179] op_sel_hi:[1,0,1]
	v_pk_fma_f32 v[114:115], v[114:115], v[172:173], v[166:167] op_sel_hi:[1,0,1]
	v_pk_fma_f32 v[112:113], v[112:113], v[172:173], v[164:165] op_sel_hi:[1,0,1]
	v_pk_fma_f32 v[126:127], v[126:127], v[172:173], v[176:177] op_sel_hi:[1,0,1]
	v_pk_fma_f32 v[122:123], v[122:123], v[172:173], v[180:181] op_sel_hi:[1,0,1]
	v_cvt_pk_bf16_f32 v124, v124, v125
	v_cvt_pk_bf16_f32 v125, v126, v127
	v_cvt_pk_bf16_f32 v120, v120, v121
	v_cvt_pk_bf16_f32 v121, v122, v123
	v_cvt_pk_bf16_f32 v116, v116, v117
	v_cvt_pk_bf16_f32 v117, v118, v119
	v_cvt_pk_bf16_f32 v118, v112, v113
	v_cvt_pk_bf16_f32 v119, v114, v115
	s_nop 0
	v_mov_b32_dpp v184, v120 row_ror:8 row_mask:0xf bank_mask:0xf
	v_mov_b32_dpp v185, v121 row_ror:8 row_mask:0xf bank_mask:0xf
	v_mov_b32_dpp v188, v118 row_ror:8 row_mask:0xf bank_mask:0xf
	v_mov_b32_dpp v189, v119 row_ror:8 row_mask:0xf bank_mask:0xf
	v_mov_b32_dpp v186, v116 row_ror:8 row_mask:0xf bank_mask:0xf
	v_mov_b32_dpp v187, v117 row_ror:8 row_mask:0xf bank_mask:0xf
	v_cndmask_b32_e64 v114, v188, v120, s[6:7]
	v_cndmask_b32_e64 v115, v189, v121, s[6:7]
	v_lshl_add_u64 v[120:121], s[8:9], 0, v[168:169]
	v_cndmask_b32_e64 v112, v186, v124, s[6:7]
	v_cndmask_b32_e64 v113, v187, v125, s[6:7]
	v_lshl_add_u64 v[120:121], v[120:121], 0, v[146:147]
	v_mov_b32_dpp v182, v124 row_ror:8 row_mask:0xf bank_mask:0xf
	v_mov_b32_dpp v183, v125 row_ror:8 row_mask:0xf bank_mask:0xf
	global_store_dwordx4 v[120:121], v[112:115], off
	v_cndmask_b32_e64 v116, v116, v182, s[6:7]
	v_cndmask_b32_e64 v117, v117, v183, s[6:7]
	v_lshl_add_u64 v[112:113], s[8:9], 0, v[170:171]
	v_cndmask_b32_e64 v118, v118, v184, s[6:7]
	v_cndmask_b32_e64 v119, v119, v185, s[6:7]
	v_lshl_add_u64 v[112:113], v[112:113], 0, v[146:147]
	global_store_dwordx4 v[112:113], v[116:119], off
	v_or_b32_e32 v112, 16, v150
	v_ashrrev_i32_e32 v113, 31, v112
	v_lshl_add_u64 v[114:115], v[112:113], 2, s[10:11]
	v_sub_u32_e32 v112, v112, v152
	v_add_u32_e32 v112, v112, v154
	v_ashrrev_i32_e32 v113, 31, v112
	v_lshlrev_b64 v[120:121], 12, v[112:113]
	v_lshl_add_u64 v[112:113], s[16:17], 0, v[120:121]
	v_lshl_add_u64 v[122:123], v[120:121], 0, s[36:37]
	v_lshl_add_u64 v[112:113], v[112:113], 0, v[146:147]
	v_lshl_add_u64 v[116:117], s[16:17], 0, v[122:123]
	s_waitcnt vmcnt(14)
; __device__ __forceinline__ unsigned cvt_pk_bf16(float lo, float hi) { unsigned r; asm volatile("v_cvt_pk_bf16_f32 %0, %1, %2" : "=v"(r) : "v"(lo), "v"(hi)); return r; }
; __device__ __forceinline__ float bflo(unsigned w) { return __uint_as_float(w << 16); }
; __device__ __forceinline__ float bfhi(unsigned w) { return __uint_as_float(w & 0xffff0000u); }
;     __device__ __forceinline__ void operator()(const f32x4 (&acc)[2][2][4][2], const Unit& u, int wr, int wc, int fr, int fq) const {
;     ...
;             for (int m = 0; m < 4; ++m) { const int row = row0 + ai * HALF + m * 16; const size_t off = (size_t)row * D + col0; float sq = 0.f; u32x4 w[2];
;                 const float sc = rsin ? __builtin_amdgcn_rcpf(rsin[row] * (1.f / D) + EPS) : 1.0f;
;                 u32x4 rr[2]; if (R) load_pair_lines(R, D, row, fr, col0, rr[0], rr[1]);
; #pragma unroll
;                 for (int bj = 0; bj < 2; ++bj) { f32x4 r0, r1;
;                     if (R) { const u32x4 rw = rr[bj]; r0 = (f32x4){bflo(rw.x), bfhi(rw.x), bflo(rw.y), bfhi(rw.y)}; r1 = (f32x4){bflo(rw.z), bfhi(rw.z), bflo(rw.w), bfhi(rw.w)}; }
;                     else { const float* rp = (row < 8192 ? src_p + off : src_s + (off - (size_t)8192 * D)) + 8 * bj; r0 = *(const f32x4*)rp; r1 = *(const f32x4*)(rp + 4); }
;                     const f32x4 o0 = r0 + acc[ai][bj][m][0] * sc, o1 = r1 + acc[ai][bj][m][1] * sc;
;                     sq += (o0[0] * o0[0] + o0[1] * o0[1]) + (o0[2] * o0[2] + o0[3] * o0[3]) + (o1[0] * o1[0] + o1[1] * o1[1]) + (o1[2] * o1[2] + o1[3] * o1[3]);
;                     w[bj].x = cvt_pk_bf16(o0[0], o0[1]); w[bj].y = cvt_pk_bf16(o0[2], o0[3]); w[bj].z = cvt_pk_bf16(o1[0], o1[1]); w[bj].w = cvt_pk_bf16(o1[2], o1[3]); }
;                 store_pair_lines(O, D, row, fr, col0, w[0], w[1]);
	s_nop 0
	v_mov_b32_e32 v124, v204
	s_nop 0
	v_mov_b64_e32 v[112:113], v[208:209]
	v_mov_b64_e32 v[114:115], v[210:211]
	v_lshl_add_u64 v[116:117], v[116:117], 0, v[146:147]
	v_mov_b64_e32 v[116:117], v[212:213]
	v_mov_b64_e32 v[118:119], v[214:215]
	s_nop 1
	v_sub_u32_e32 v198, v150, v152
	v_add_u32_e32 v201, v198, v154
	v_add_u32_e32 v190, 0xa0, v201
	v_ashrrev_i32_e32 v191, 31, v190
	v_lshlrev_b64 v[194:195], 12, v[190:191]
	v_lshl_add_u64 v[196:197], v[194:195], 0, s[36:37]
	global_load_dword v204, v[148:149], off offset:640
	v_lshl_add_u64 v[190:191], s[16:17], 0, v[194:195]
	v_lshl_add_u64 v[192:193], s[16:17], 0, v[196:197]
	v_lshl_add_u64 v[190:191], v[190:191], 0, v[146:147]
	v_lshl_add_u64 v[192:193], v[192:193], 0, v[146:147]
	global_load_dwordx4 v[208:211], v[190:191], off
	global_load_dwordx4 v[212:215], v[192:193], off
	v_fmamk_f32 v124, v124, 0x3a000000, v159
	v_rcp_f32_e32 v124, v124
	v_mov_b32_dpp v125, v112 row_ror:8 row_mask:0xf bank_mask:0xf
	v_mov_b32_dpp v126, v113 row_ror:8 row_mask:0xf bank_mask:0xf
	v_mov_b32_dpp v127, v114 row_ror:8 row_mask:0xf bank_mask:0xf
	v_mov_b32_dpp v151, v115 row_ror:8 row_mask:0xf bank_mask:0xf
	v_mov_b32_dpp v160, v116 row_ror:8 row_mask:0xf bank_mask:0xf
	v_mov_b32_dpp v161, v117 row_ror:8 row_mask:0xf bank_mask:0xf
	v_mov_b32_dpp v162, v118 row_ror:8 row_mask:0xf bank_mask:0xf
	v_mov_b32_dpp v163, v119 row_ror:8 row_mask:0xf bank_mask:0xf
	v_cndmask_b32_e64 v163, v163, v115, s[6:7]
	v_cndmask_b32_e64 v162, v162, v114, s[6:7]
	v_cndmask_b32_e64 v115, v161, v113, s[6:7]
	v_cndmask_b32_e64 v113, v160, v112, s[6:7]
	v_cndmask_b32_e64 v151, v119, v151, s[6:7]
	v_cndmask_b32_e64 v164, v118, v127, s[6:7]
	v_cndmask_b32_e64 v161, v117, v126, s[6:7]
	v_cndmask_b32_e64 v125, v116, v125, s[6:7]
	v_lshlrev_b32_e32 v112, 16, v113
	v_and_b32_e32 v113, 0xffff0000, v113
	v_lshlrev_b32_e32 v116, 16, v162
	v_and_b32_e32 v117, 0xffff0000, v162
	v_lshlrev_b32_e32 v118, 16, v163
	v_and_b32_e32 v119, 0xffff0000, v163
	v_lshlrev_b32_e32 v126, 16, v125
	v_and_b32_e32 v127, 0xffff0000, v125
	v_lshlrev_b32_e32 v160, 16, v161
	v_and_b32_e32 v161, 0xffff0000, v161
	v_lshlrev_b32_e32 v162, 16, v164
	v_and_b32_e32 v163, 0xffff0000, v164
	v_lshlrev_b32_e32 v164, 16, v151
	v_and_b32_e32 v165, 0xffff0000, v151
	v_lshlrev_b32_e32 v114, 16, v115
	v_and_b32_e32 v115, 0xffff0000, v115
	v_pk_fma_f32 v[108:109], v[108:109], v[124:125], v[112:113] op_sel_hi:[1,0,1]
	v_pk_fma_f32 v[104:105], v[104:105], v[124:125], v[116:117] op_sel_hi:[1,0,1]
	v_pk_fma_f32 v[102:103], v[102:103], v[124:125], v[160:161] op_sel_hi:[1,0,1]
	v_pk_fma_f32 v[100:101], v[100:101], v[124:125], v[126:127] op_sel_hi:[1,0,1]
	v_pk_fma_f32 v[98:99], v[98:99], v[124:125], v[164:165] op_sel_hi:[1,0,1]
	v_pk_fma_f32 v[110:111], v[110:111], v[124:125], v[114:115] op_sel_hi:[1,0,1]
	v_pk_fma_f32 v[106:107], v[106:107], v[124:125], v[118:119] op_sel_hi:[1,0,1]
	v_pk_fma_f32 v[96:97], v[96:97], v[124:125], v[162:163] op_sel_hi:[1,0,1]
	v_cvt_pk_bf16_f32 v108, v108, v109
	v_cvt_pk_bf16_f32 v109, v110, v111
	v_cvt_pk_bf16_f32 v104, v104, v105
	v_cvt_pk_bf16_f32 v105, v106, v107
	v_cvt_pk_bf16_f32 v100, v100, v101
	v_cvt_pk_bf16_f32 v101, v102, v103
	s_nop 0
	v_cvt_pk_bf16_f32 v102, v96, v97
	v_cvt_pk_bf16_f32 v103, v98, v99
	v_mov_b32_e32 v98, 0
	v_mov_b32_dpp v98, v102 row_ror:8 row_mask:0xf bank_mask:0xf
	v_mov_b32_dpp v99, v103 row_ror:8 row_mask:0xf bank_mask:0xf
	v_mov_b32_dpp v107, v104 row_ror:8 row_mask:0xf bank_mask:0xf
	v_mov_b32_dpp v110, v105 row_ror:8 row_mask:0xf bank_mask:0xf
	v_mov_b32_dpp v96, v100 row_ror:8 row_mask:0xf bank_mask:0xf
	v_mov_b32_dpp v97, v101 row_ror:8 row_mask:0xf bank_mask:0xf
	v_cndmask_b32_e64 v98, v98, v104, s[6:7]
	v_cndmask_b32_e64 v99, v99, v105, s[6:7]
	v_lshl_add_u64 v[104:105], s[8:9], 0, v[120:121]
	v_cndmask_b32_e64 v96, v96, v108, s[6:7]
	v_cndmask_b32_e64 v97, v97, v109, s[6:7]
	v_lshl_add_u64 v[104:105], v[104:105], 0, v[146:147]
	v_mov_b32_dpp v166, v108 row_ror:8 row_mask:0xf bank_mask:0xf
	v_mov_b32_dpp v106, v109 row_ror:8 row_mask:0xf bank_mask:0xf
	global_store_dwordx4 v[104:105], v[96:99], off
	v_cndmask_b32_e64 v100, v100, v166, s[6:7]
	v_cndmask_b32_e64 v101, v101, v106, s[6:7]
	v_lshl_add_u64 v[96:97], s[8:9], 0, v[122:123]
	v_cndmask_b32_e64 v102, v102, v107, s[6:7]
	v_cndmask_b32_e64 v103, v103, v110, s[6:7]
	v_lshl_add_u64 v[96:97], v[96:97], 0, v[146:147]
	global_store_dwordx4 v[96:97], v[100:103], off
	v_or_b32_e32 v96, 32, v150
	v_ashrrev_i32_e32 v97, 31, v96
	v_lshl_add_u64 v[98:99], v[96:97], 2, s[10:11]
	v_sub_u32_e32 v96, v96, v152
	v_add_u32_e32 v96, v96, v154
	v_ashrrev_i32_e32 v97, 31, v96
	v_lshlrev_b64 v[104:105], 12, v[96:97]
	v_lshl_add_u64 v[96:97], s[16:17], 0, v[104:105]
	v_lshl_add_u64 v[106:107], v[104:105], 0, s[36:37]
	v_lshl_add_u64 v[96:97], v[96:97], 0, v[146:147]
	v_lshl_add_u64 v[100:101], s[16:17], 0, v[106:107]
	s_waitcnt vmcnt(16)
; __device__ __forceinline__ unsigned cvt_pk_bf16(float lo, float hi) { unsigned r; asm volatile("v_cvt_pk_bf16_f32 %0, %1, %2" : "=v"(r) : "v"(lo), "v"(hi)); return r; }
; __device__ __forceinline__ float bflo(unsigned w) { return __uint_as_float(w << 16); }
; __device__ __forceinline__ float bfhi(unsigned w) { return __uint_as_float(w & 0xffff0000u); }
;     __device__ __forceinline__ void operator()(const f32x4 (&acc)[2][2][4][2], const Unit& u, int wr, int wc, int fr, int fq) const {
;     ...
;             for (int m = 0; m < 4; ++m) { const int row = row0 + ai * HALF + m * 16; const size_t off = (size_t)row * D + col0; float sq = 0.f; u32x4 w[2];
;                 const float sc = rsin ? __builtin_amdgcn_rcpf(rsin[row] * (1.f / D) + EPS) : 1.0f;
;                 u32x4 rr[2]; if (R) load_pair_lines(R, D, row, fr, col0, rr[0], rr[1]);
; #pragma unroll
;                 for (int bj = 0; bj < 2; ++bj) { f32x4 r0, r1;
;                     if (R) { const u32x4 rw = rr[bj]; r0 = (f32x4){bflo(rw.x), bfhi(rw.x), bflo(rw.y), bfhi(rw.y)}; r1 = (f32x4){bflo(rw.z), bfhi(rw.z), bflo(rw.w), bfhi(rw.w)}; }
;                     else { const float* rp = (row < 8192 ? src_p + off : src_s + (off - (size_t)8192 * D)) + 8 * bj; r0 = *(const f32x4*)rp; r1 = *(const f32x4*)(rp + 4); }
;                     const f32x4 o0 = r0 + acc[ai][bj][m][0] * sc, o1 = r1 + acc[ai][bj][m][1] * sc;
;                     sq += (o0[0] * o0[0] + o0[1] * o0[1]) + (o0[2] * o0[2] + o0[3] * o0[3]) + (o1[0] * o1[0] + o1[1] * o1[1]) + (o1[2] * o1[2] + o1[3] * o1[3]);
;                     w[bj].x = cvt_pk_bf16(o0[0], o0[1]); w[bj].y = cvt_pk_bf16(o0[2], o0[3]); w[bj].z = cvt_pk_bf16(o1[0], o1[1]); w[bj].w = cvt_pk_bf16(o1[2], o1[3]); }
;                 store_pair_lines(O, D, row, fr, col0, w[0], w[1]);
	s_nop 0
	v_mov_b32_e32 v108, v205
	s_nop 0
	v_mov_b64_e32 v[96:97], v[216:217]
	v_mov_b64_e32 v[98:99], v[218:219]
	v_lshl_add_u64 v[100:101], v[100:101], 0, v[146:147]
	v_mov_b64_e32 v[100:101], v[220:221]
	v_mov_b64_e32 v[102:103], v[222:223]
	s_nop 1
	v_sub_u32_e32 v198, v150, v152
	v_add_u32_e32 v201, v198, v154
	v_add_u32_e32 v190, 0xb0, v201
	v_ashrrev_i32_e32 v191, 31, v190
	v_lshlrev_b64 v[194:195], 12, v[190:191]
	v_lshl_add_u64 v[196:197], v[194:195], 0, s[36:37]
	global_load_dword v205, v[148:149], off offset:704
	v_lshl_add_u64 v[190:191], s[16:17], 0, v[194:195]
	v_lshl_add_u64 v[192:193], s[16:17], 0, v[196:197]
	v_lshl_add_u64 v[190:191], v[190:191], 0, v[146:147]
	v_lshl_add_u64 v[192:193], v[192:193], 0, v[146:147]
	global_load_dwordx4 v[216:219], v[190:191], off
	global_load_dwordx4 v[220:223], v[192:193], off
	v_fmamk_f32 v108, v108, 0x3a000000, v159
	v_rcp_f32_e32 v108, v108
	v_mov_b32_dpp v109, v96 row_ror:8 row_mask:0xf bank_mask:0xf
	v_mov_b32_dpp v113, v100 row_ror:8 row_mask:0xf bank_mask:0xf
	v_mov_b32_dpp v114, v101 row_ror:8 row_mask:0xf bank_mask:0xf
	v_mov_b32_dpp v115, v102 row_ror:8 row_mask:0xf bank_mask:0xf
	v_mov_b32_dpp v116, v103 row_ror:8 row_mask:0xf bank_mask:0xf
	v_mov_b32_dpp v110, v97 row_ror:8 row_mask:0xf bank_mask:0xf
	v_mov_b32_dpp v111, v98 row_ror:8 row_mask:0xf bank_mask:0xf
	v_mov_b32_dpp v112, v99 row_ror:8 row_mask:0xf bank_mask:0xf
	v_cndmask_b32_e64 v116, v116, v99, s[6:7]
	v_cndmask_b32_e64 v115, v115, v98, s[6:7]
	v_cndmask_b32_e64 v99, v114, v97, s[6:7]
	v_cndmask_b32_e64 v97, v113, v96, s[6:7]
	v_cndmask_b32_e64 v114, v103, v112, s[6:7]
	v_cndmask_b32_e64 v117, v102, v111, s[6:7]
	v_cndmask_b32_e64 v113, v101, v110, s[6:7]
	v_cndmask_b32_e64 v109, v100, v109, s[6:7]
	v_lshlrev_b32_e32 v96, 16, v97
	v_and_b32_e32 v97, 0xffff0000, v97
	v_lshlrev_b32_e32 v98, 16, v99
	v_and_b32_e32 v99, 0xffff0000, v99
	v_lshlrev_b32_e32 v100, 16, v115
	v_and_b32_e32 v101, 0xffff0000, v115
	v_lshlrev_b32_e32 v102, 16, v116
	v_and_b32_e32 v103, 0xffff0000, v116
	v_pk_fma_f32 v[94:95], v[94:95], v[108:109], v[98:99] op_sel_hi:[1,0,1]
	v_pk_fma_f32 v[92:93], v[92:93], v[108:109], v[96:97] op_sel_hi:[1,0,1]
	v_pk_fma_f32 v[90:91], v[90:91], v[108:109], v[102:103] op_sel_hi:[1,0,1]
	v_pk_fma_f32 v[88:89], v[88:89], v[108:109], v[100:101] op_sel_hi:[1,0,1]
	v_lshlrev_b32_e32 v110, 16, v109
	v_and_b32_e32 v111, 0xffff0000, v109
	v_lshlrev_b32_e32 v112, 16, v113
	v_and_b32_e32 v113, 0xffff0000, v113
	v_cvt_pk_bf16_f32 v92, v92, v93
	v_cvt_pk_bf16_f32 v93, v94, v95
	v_cvt_pk_bf16_f32 v94, v88, v89
	v_cvt_pk_bf16_f32 v95, v90, v91
	v_lshlrev_b32_e32 v88, 16, v117
	v_and_b32_e32 v89, 0xffff0000, v117
	v_lshlrev_b32_e32 v90, 16, v114
	v_and_b32_e32 v91, 0xffff0000, v114
	v_pk_fma_f32 v[86:87], v[86:87], v[108:109], v[112:113] op_sel_hi:[1,0,1]
	v_pk_fma_f32 v[84:85], v[84:85], v[108:109], v[110:111] op_sel_hi:[1,0,1]
	v_pk_fma_f32 v[82:83], v[82:83], v[108:109], v[90:91] op_sel_hi:[1,0,1]
	v_pk_fma_f32 v[80:81], v[80:81], v[108:109], v[88:89] op_sel_hi:[1,0,1]
	v_cvt_pk_bf16_f32 v84, v84, v85
	v_cvt_pk_bf16_f32 v85, v86, v87
	v_cvt_pk_bf16_f32 v86, v80, v81
	v_cvt_pk_bf16_f32 v87, v82, v83
	s_nop 0
	v_mov_b32_dpp v88, v92 row_ror:8 row_mask:0xf bank_mask:0xf
	v_mov_b32_dpp v89, v93 row_ror:8 row_mask:0xf bank_mask:0xf
	v_mov_b32_dpp v80, v84 row_ror:8 row_mask:0xf bank_mask:0xf
	v_mov_b32_dpp v81, v85 row_ror:8 row_mask:0xf bank_mask:0xf
	v_mov_b32_dpp v82, v86 row_ror:8 row_mask:0xf bank_mask:0xf
	v_mov_b32_dpp v83, v87 row_ror:8 row_mask:0xf bank_mask:0xf
	v_cndmask_b32_e64 v84, v84, v88, s[6:7]
	v_cndmask_b32_e64 v85, v85, v89, s[6:7]
	v_lshl_add_u64 v[88:89], s[8:9], 0, v[104:105]
	v_cndmask_b32_e64 v80, v80, v92, s[6:7]
	v_cndmask_b32_e64 v81, v81, v93, s[6:7]
	v_cndmask_b32_e64 v82, v82, v94, s[6:7]
	v_cndmask_b32_e64 v83, v83, v95, s[6:7]
	v_lshl_add_u64 v[88:89], v[88:89], 0, v[146:147]
	v_mov_b32_dpp v90, v94 row_ror:8 row_mask:0xf bank_mask:0xf
	v_mov_b32_dpp v91, v95 row_ror:8 row_mask:0xf bank_mask:0xf
	global_store_dwordx4 v[88:89], v[80:83], off
	v_cndmask_b32_e64 v86, v86, v90, s[6:7]
	v_cndmask_b32_e64 v87, v87, v91, s[6:7]
	v_lshl_add_u64 v[80:81], s[8:9], 0, v[106:107]
	v_lshl_add_u64 v[80:81], v[80:81], 0, v[146:147]
	global_store_dwordx4 v[80:81], v[84:87], off
	v_or_b32_e32 v80, 48, v150
	v_ashrrev_i32_e32 v81, 31, v80
	v_lshl_add_u64 v[82:83], v[80:81], 2, s[10:11]
	v_sub_u32_e32 v80, v80, v152
	v_add_u32_e32 v80, v80, v154
	v_ashrrev_i32_e32 v81, 31, v80
	v_lshlrev_b64 v[88:89], 12, v[80:81]
	v_lshl_add_u64 v[80:81], s[16:17], 0, v[88:89]
	v_lshl_add_u64 v[90:91], v[88:89], 0, s[36:37]
	v_lshl_add_u64 v[80:81], v[80:81], 0, v[146:147]
	v_lshl_add_u64 v[84:85], s[16:17], 0, v[90:91]
	s_waitcnt vmcnt(18)
; __device__ __forceinline__ unsigned cvt_pk_bf16(float lo, float hi) { unsigned r; asm volatile("v_cvt_pk_bf16_f32 %0, %1, %2" : "=v"(r) : "v"(lo), "v"(hi)); return r; }
; __device__ __forceinline__ float bflo(unsigned w) { return __uint_as_float(w << 16); }
; __device__ __forceinline__ float bfhi(unsigned w) { return __uint_as_float(w & 0xffff0000u); }
;     __device__ __forceinline__ void operator()(const f32x4 (&acc)[2][2][4][2], const Unit& u, int wr, int wc, int fr, int fq) const {
;     ...
;             for (int m = 0; m < 4; ++m) { const int row = row0 + ai * HALF + m * 16; const size_t off = (size_t)row * D + col0; float sq = 0.f; u32x4 w[2];
;                 const float sc = rsin ? __builtin_amdgcn_rcpf(rsin[row] * (1.f / D) + EPS) : 1.0f;
;                 u32x4 rr[2]; if (R) load_pair_lines(R, D, row, fr, col0, rr[0], rr[1]);
; #pragma unroll
;                 for (int bj = 0; bj < 2; ++bj) { f32x4 r0, r1;
;                     if (R) { const u32x4 rw = rr[bj]; r0 = (f32x4){bflo(rw.x), bfhi(rw.x), bflo(rw.y), bfhi(rw.y)}; r1 = (f32x4){bflo(rw.z), bfhi(rw.z), bflo(rw.w), bfhi(rw.w)}; }
;                     else { const float* rp = (row < 8192 ? src_p + off : src_s + (off - (size_t)8192 * D)) + 8 * bj; r0 = *(const f32x4*)rp; r1 = *(const f32x4*)(rp + 4); }
;                     const f32x4 o0 = r0 + acc[ai][bj][m][0] * sc, o1 = r1 + acc[ai][bj][m][1] * sc;
;                     sq += (o0[0] * o0[0] + o0[1] * o0[1]) + (o0[2] * o0[2] + o0[3] * o0[3]) + (o1[0] * o1[0] + o1[1] * o1[1]) + (o1[2] * o1[2] + o1[3] * o1[3]);
;                     w[bj].x = cvt_pk_bf16(o0[0], o0[1]); w[bj].y = cvt_pk_bf16(o0[2], o0[3]); w[bj].z = cvt_pk_bf16(o1[0], o1[1]); w[bj].w = cvt_pk_bf16(o1[2], o1[3]); }
;                 store_pair_lines(O, D, row, fr, col0, w[0], w[1]);
	s_nop 0
	v_mov_b32_e32 v92, v206
	s_nop 0
	v_mov_b64_e32 v[80:81], v[224:225]
	v_mov_b64_e32 v[82:83], v[226:227]
	v_lshl_add_u64 v[84:85], v[84:85], 0, v[146:147]
	v_mov_b64_e32 v[84:85], v[228:229]
	v_mov_b64_e32 v[86:87], v[230:231]
	s_nop 1
	v_fmamk_f32 v92, v92, 0x3a000000, v159
	v_rcp_f32_e32 v92, v92
	v_mov_b32_dpp v93, v80 row_ror:8 row_mask:0xf bank_mask:0xf
	v_mov_b32_dpp v97, v84 row_ror:8 row_mask:0xf bank_mask:0xf
	v_mov_b32_dpp v98, v85 row_ror:8 row_mask:0xf bank_mask:0xf
	v_mov_b32_dpp v99, v86 row_ror:8 row_mask:0xf bank_mask:0xf
	v_mov_b32_dpp v100, v87 row_ror:8 row_mask:0xf bank_mask:0xf
	v_mov_b32_dpp v94, v81 row_ror:8 row_mask:0xf bank_mask:0xf
	v_mov_b32_dpp v95, v82 row_ror:8 row_mask:0xf bank_mask:0xf
	v_mov_b32_dpp v96, v83 row_ror:8 row_mask:0xf bank_mask:0xf
	v_cndmask_b32_e64 v100, v100, v83, s[6:7]
	v_cndmask_b32_e64 v99, v99, v82, s[6:7]
	v_cndmask_b32_e64 v83, v98, v81, s[6:7]
	v_cndmask_b32_e64 v81, v97, v80, s[6:7]
	v_cndmask_b32_e64 v96, v87, v96, s[6:7]
	v_cndmask_b32_e64 v95, v86, v95, s[6:7]
	v_cndmask_b32_e64 v94, v85, v94, s[6:7]
	v_cndmask_b32_e64 v93, v84, v93, s[6:7]
	v_lshlrev_b32_e32 v80, 16, v81
	v_and_b32_e32 v81, 0xffff0000, v81
	v_lshlrev_b32_e32 v82, 16, v83
	v_and_b32_e32 v83, 0xffff0000, v83
	v_lshlrev_b32_e32 v84, 16, v99
	v_and_b32_e32 v85, 0xffff0000, v99
	v_lshlrev_b32_e32 v86, 16, v100
	v_and_b32_e32 v87, 0xffff0000, v100
	v_pk_fma_f32 v[78:79], v[78:79], v[92:93], v[82:83] op_sel_hi:[1,0,1]
	v_pk_fma_f32 v[76:77], v[76:77], v[92:93], v[80:81] op_sel_hi:[1,0,1]
	v_pk_fma_f32 v[74:75], v[74:75], v[92:93], v[86:87] op_sel_hi:[1,0,1]
	v_pk_fma_f32 v[72:73], v[72:73], v[92:93], v[84:85] op_sel_hi:[1,0,1]
	v_cvt_pk_bf16_f32 v80, v76, v77
	v_cvt_pk_bf16_f32 v81, v78, v79
	v_lshlrev_b32_e32 v76, 16, v95
	v_cvt_pk_bf16_f32 v82, v72, v73
	v_cvt_pk_bf16_f32 v83, v74, v75
	v_lshlrev_b32_e32 v72, 16, v93
	v_and_b32_e32 v73, 0xffff0000, v93
	v_lshlrev_b32_e32 v74, 16, v94
	v_and_b32_e32 v75, 0xffff0000, v94
	v_and_b32_e32 v77, 0xffff0000, v95
	v_lshlrev_b32_e32 v78, 16, v96
	v_and_b32_e32 v79, 0xffff0000, v96
	v_pk_fma_f32 v[70:71], v[70:71], v[92:93], v[74:75] op_sel_hi:[1,0,1]
	v_pk_fma_f32 v[68:69], v[68:69], v[92:93], v[72:73] op_sel_hi:[1,0,1]
	v_pk_fma_f32 v[66:67], v[66:67], v[92:93], v[78:79] op_sel_hi:[1,0,1]
	v_pk_fma_f32 v[64:65], v[64:65], v[92:93], v[76:77] op_sel_hi:[1,0,1]
	v_cvt_pk_bf16_f32 v68, v68, v69
	v_cvt_pk_bf16_f32 v69, v70, v71
	v_cvt_pk_bf16_f32 v70, v64, v65
	v_cvt_pk_bf16_f32 v71, v66, v67
	s_nop 0
	v_mov_b32_dpp v72, v80 row_ror:8 row_mask:0xf bank_mask:0xf
	v_mov_b32_dpp v73, v81 row_ror:8 row_mask:0xf bank_mask:0xf
	v_mov_b32_dpp v64, v68 row_ror:8 row_mask:0xf bank_mask:0xf
	v_mov_b32_dpp v65, v69 row_ror:8 row_mask:0xf bank_mask:0xf
	v_mov_b32_dpp v66, v70 row_ror:8 row_mask:0xf bank_mask:0xf
	v_mov_b32_dpp v67, v71 row_ror:8 row_mask:0xf bank_mask:0xf
	v_cndmask_b32_e64 v68, v68, v72, s[6:7]
	v_cndmask_b32_e64 v69, v69, v73, s[6:7]
	v_lshl_add_u64 v[72:73], s[8:9], 0, v[88:89]
	v_cndmask_b32_e64 v64, v64, v80, s[6:7]
	v_cndmask_b32_e64 v65, v65, v81, s[6:7]
	v_cndmask_b32_e64 v66, v66, v82, s[6:7]
	v_cndmask_b32_e64 v67, v67, v83, s[6:7]
	v_lshl_add_u64 v[72:73], v[72:73], 0, v[146:147]
	v_mov_b32_dpp v74, v82 row_ror:8 row_mask:0xf bank_mask:0xf
	v_mov_b32_dpp v75, v83 row_ror:8 row_mask:0xf bank_mask:0xf
	global_store_dwordx4 v[72:73], v[64:67], off
	v_cndmask_b32_e64 v70, v70, v74, s[6:7]
	v_cndmask_b32_e64 v71, v71, v75, s[6:7]
	v_lshl_add_u64 v[64:65], s[8:9], 0, v[90:91]
	v_lshl_add_u64 v[64:65], v[64:65], 0, v[146:147]
	global_store_dwordx4 v[64:65], v[68:71], off
	v_sub_u32_e32 v64, v150, v152
	v_add_u32_e32 v77, v64, v154
	v_add_u32_e32 v64, 0x80, v77
	v_ashrrev_i32_e32 v65, 31, v64
	v_lshlrev_b64 v[72:73], 12, v[64:65]
	v_lshl_add_u64 v[64:65], s[16:17], 0, v[72:73]
	v_lshl_add_u64 v[74:75], v[72:73], 0, s[36:37]
	v_lshl_add_u64 v[64:65], v[64:65], 0, v[146:147]
	v_lshl_add_u64 v[68:69], s[16:17], 0, v[74:75]
	s_waitcnt vmcnt(17)
	s_nop 0
	v_mov_b32_e32 v76, v207
	s_nop 0
	v_mov_b64_e32 v[64:65], v[232:233]
	v_mov_b64_e32 v[66:67], v[234:235]
	v_lshl_add_u64 v[68:69], v[68:69], 0, v[146:147]
	v_mov_b64_e32 v[68:69], v[236:237]
	v_mov_b64_e32 v[70:71], v[238:239]
	s_nop 1
	v_fmamk_f32 v76, v76, 0x3a000000, v159
	v_rcp_f32_e32 v76, v76
	v_mov_b32_dpp v78, v64 row_ror:8 row_mask:0xf bank_mask:0xf
	v_mov_b32_dpp v82, v68 row_ror:8 row_mask:0xf bank_mask:0xf
	v_mov_b32_dpp v83, v69 row_ror:8 row_mask:0xf bank_mask:0xf
	v_mov_b32_dpp v84, v70 row_ror:8 row_mask:0xf bank_mask:0xf
	v_mov_b32_dpp v85, v71 row_ror:8 row_mask:0xf bank_mask:0xf
	v_mov_b32_dpp v79, v65 row_ror:8 row_mask:0xf bank_mask:0xf
	v_mov_b32_dpp v80, v66 row_ror:8 row_mask:0xf bank_mask:0xf
	v_mov_b32_dpp v81, v67 row_ror:8 row_mask:0xf bank_mask:0xf
	v_cndmask_b32_e64 v85, v85, v67, s[6:7]
	v_cndmask_b32_e64 v84, v84, v66, s[6:7]
	v_cndmask_b32_e64 v67, v83, v65, s[6:7]
	v_cndmask_b32_e64 v65, v82, v64, s[6:7]
	v_cndmask_b32_e64 v81, v71, v81, s[6:7]
	v_cndmask_b32_e64 v80, v70, v80, s[6:7]
	v_cndmask_b32_e64 v79, v69, v79, s[6:7]
	v_cndmask_b32_e64 v78, v68, v78, s[6:7]
	v_lshlrev_b32_e32 v64, 16, v65
	v_and_b32_e32 v65, 0xffff0000, v65
	v_lshlrev_b32_e32 v66, 16, v67
	v_and_b32_e32 v67, 0xffff0000, v67
	v_lshlrev_b32_e32 v68, 16, v84
	v_and_b32_e32 v69, 0xffff0000, v84
	v_lshlrev_b32_e32 v70, 16, v85
	v_and_b32_e32 v71, 0xffff0000, v85
	v_pk_fma_f32 v[62:63], v[62:63], v[76:77], v[66:67] op_sel_hi:[1,0,1]
	v_pk_fma_f32 v[60:61], v[60:61], v[76:77], v[64:65] op_sel_hi:[1,0,1]
	v_pk_fma_f32 v[58:59], v[58:59], v[76:77], v[70:71] op_sel_hi:[1,0,1]
	v_pk_fma_f32 v[56:57], v[56:57], v[76:77], v[68:69] op_sel_hi:[1,0,1]
; __device__ __forceinline__ unsigned cvt_pk_bf16(float lo, float hi) { unsigned r; asm volatile("v_cvt_pk_bf16_f32 %0, %1, %2" : "=v"(r) : "v"(lo), "v"(hi)); return r; }
; __device__ __forceinline__ float bflo(unsigned w) { return __uint_as_float(w << 16); }
; __device__ __forceinline__ float bfhi(unsigned w) { return __uint_as_float(w & 0xffff0000u); }
;     __device__ __forceinline__ void operator()(const f32x4 (&acc)[2][2][4][2], const Unit& u, int wr, int wc, int fr, int fq) const {
;     ...
;             for (int m = 0; m < 4; ++m) { const int row = row0 + ai * HALF + m * 16; const size_t off = (size_t)row * D + col0; float sq = 0.f; u32x4 w[2];
;                 const float sc = rsin ? __builtin_amdgcn_rcpf(rsin[row] * (1.f / D) + EPS) : 1.0f;
;                 u32x4 rr[2]; if (R) load_pair_lines(R, D, row, fr, col0, rr[0], rr[1]);
; #pragma unroll
;                 for (int bj = 0; bj < 2; ++bj) { f32x4 r0, r1;
;                     if (R) { const u32x4 rw = rr[bj]; r0 = (f32x4){bflo(rw.x), bfhi(rw.x), bflo(rw.y), bfhi(rw.y)}; r1 = (f32x4){bflo(rw.z), bfhi(rw.z), bflo(rw.w), bfhi(rw.w)}; }
;                     else { const float* rp = (row < 8192 ? src_p + off : src_s + (off - (size_t)8192 * D)) + 8 * bj; r0 = *(const f32x4*)rp; r1 = *(const f32x4*)(rp + 4); }
;                     const f32x4 o0 = r0 + acc[ai][bj][m][0] * sc, o1 = r1 + acc[ai][bj][m][1] * sc;
;                     sq += (o0[0] * o0[0] + o0[1] * o0[1]) + (o0[2] * o0[2] + o0[3] * o0[3]) + (o1[0] * o1[0] + o1[1] * o1[1]) + (o1[2] * o1[2] + o1[3] * o1[3]);
;                     w[bj].x = cvt_pk_bf16(o0[0], o0[1]); w[bj].y = cvt_pk_bf16(o0[2], o0[3]); w[bj].z = cvt_pk_bf16(o1[0], o1[1]); w[bj].w = cvt_pk_bf16(o1[2], o1[3]); }
;                 store_pair_lines(O, D, row, fr, col0, w[0], w[1]);
	v_cvt_pk_bf16_f32 v64, v60, v61
	v_cvt_pk_bf16_f32 v65, v62, v63
	v_lshlrev_b32_e32 v60, 16, v80
	v_cvt_pk_bf16_f32 v66, v56, v57
	v_cvt_pk_bf16_f32 v67, v58, v59
	v_lshlrev_b32_e32 v56, 16, v78
	v_and_b32_e32 v57, 0xffff0000, v78
	v_lshlrev_b32_e32 v58, 16, v79
	v_and_b32_e32 v59, 0xffff0000, v79
	v_and_b32_e32 v61, 0xffff0000, v80
	v_lshlrev_b32_e32 v62, 16, v81
	v_and_b32_e32 v63, 0xffff0000, v81
	v_pk_fma_f32 v[54:55], v[54:55], v[76:77], v[58:59] op_sel_hi:[1,0,1]
	v_pk_fma_f32 v[52:53], v[52:53], v[76:77], v[56:57] op_sel_hi:[1,0,1]
	v_pk_fma_f32 v[50:51], v[50:51], v[76:77], v[62:63] op_sel_hi:[1,0,1]
	v_pk_fma_f32 v[48:49], v[48:49], v[76:77], v[60:61] op_sel_hi:[1,0,1]
	v_cvt_pk_bf16_f32 v52, v52, v53
	v_cvt_pk_bf16_f32 v53, v54, v55
	v_cvt_pk_bf16_f32 v54, v48, v49
	v_cvt_pk_bf16_f32 v55, v50, v51
	s_nop 0
	v_mov_b32_dpp v56, v64 row_ror:8 row_mask:0xf bank_mask:0xf
	v_mov_b32_dpp v57, v65 row_ror:8 row_mask:0xf bank_mask:0xf
	v_mov_b32_dpp v48, v52 row_ror:8 row_mask:0xf bank_mask:0xf
	v_mov_b32_dpp v49, v53 row_ror:8 row_mask:0xf bank_mask:0xf
	v_mov_b32_dpp v50, v54 row_ror:8 row_mask:0xf bank_mask:0xf
	v_mov_b32_dpp v51, v55 row_ror:8 row_mask:0xf bank_mask:0xf
	v_cndmask_b32_e64 v52, v52, v56, s[6:7]
	v_cndmask_b32_e64 v53, v53, v57, s[6:7]
	v_lshl_add_u64 v[56:57], s[8:9], 0, v[72:73]
	v_cndmask_b32_e64 v48, v48, v64, s[6:7]
	v_cndmask_b32_e64 v49, v49, v65, s[6:7]
	v_cndmask_b32_e64 v50, v50, v66, s[6:7]
	v_cndmask_b32_e64 v51, v51, v67, s[6:7]
	v_lshl_add_u64 v[56:57], v[56:57], 0, v[146:147]
	v_mov_b32_dpp v58, v66 row_ror:8 row_mask:0xf bank_mask:0xf
	v_mov_b32_dpp v59, v67 row_ror:8 row_mask:0xf bank_mask:0xf
	global_store_dwordx4 v[56:57], v[48:51], off
	v_cndmask_b32_e64 v54, v54, v58, s[6:7]
	v_cndmask_b32_e64 v55, v55, v59, s[6:7]
	v_lshl_add_u64 v[48:49], s[8:9], 0, v[74:75]
	v_lshl_add_u64 v[48:49], v[48:49], 0, v[146:147]
	global_store_dwordx4 v[48:49], v[52:55], off
	v_add_u32_e32 v48, 0x90, v77
	v_ashrrev_i32_e32 v49, 31, v48
	v_lshlrev_b64 v[56:57], 12, v[48:49]
	v_lshl_add_u64 v[48:49], s[16:17], 0, v[56:57]
	v_lshl_add_u64 v[58:59], v[56:57], 0, s[36:37]
	v_lshl_add_u64 v[48:49], v[48:49], 0, v[146:147]
	v_lshl_add_u64 v[52:53], s[16:17], 0, v[58:59]
	s_waitcnt vmcnt(16)
	s_nop 0
	v_mov_b32_e32 v60, v240
	s_nop 0
	v_mov_b64_e32 v[48:49], v[244:245]
	v_mov_b64_e32 v[50:51], v[246:247]
	v_lshl_add_u64 v[52:53], v[52:53], 0, v[146:147]
	v_mov_b64_e32 v[52:53], v[248:249]
	v_mov_b64_e32 v[54:55], v[250:251]
	s_nop 1
	v_fmamk_f32 v60, v60, 0x3a000000, v159
	v_rcp_f32_e32 v60, v60
	v_mov_b32_dpp v61, v48 row_ror:8 row_mask:0xf bank_mask:0xf
	v_mov_b32_dpp v65, v52 row_ror:8 row_mask:0xf bank_mask:0xf
	v_mov_b32_dpp v66, v53 row_ror:8 row_mask:0xf bank_mask:0xf
	v_mov_b32_dpp v67, v54 row_ror:8 row_mask:0xf bank_mask:0xf
	v_mov_b32_dpp v68, v55 row_ror:8 row_mask:0xf bank_mask:0xf
	v_mov_b32_dpp v62, v49 row_ror:8 row_mask:0xf bank_mask:0xf
	v_mov_b32_dpp v63, v50 row_ror:8 row_mask:0xf bank_mask:0xf
	v_mov_b32_dpp v64, v51 row_ror:8 row_mask:0xf bank_mask:0xf
	v_cndmask_b32_e64 v68, v68, v51, s[6:7]
	v_cndmask_b32_e64 v67, v67, v50, s[6:7]
	v_cndmask_b32_e64 v51, v66, v49, s[6:7]
	v_cndmask_b32_e64 v49, v65, v48, s[6:7]
	v_cndmask_b32_e64 v64, v55, v64, s[6:7]
	v_cndmask_b32_e64 v63, v54, v63, s[6:7]
	v_cndmask_b32_e64 v62, v53, v62, s[6:7]
	v_cndmask_b32_e64 v61, v52, v61, s[6:7]
	v_lshlrev_b32_e32 v48, 16, v49
	v_and_b32_e32 v49, 0xffff0000, v49
	v_lshlrev_b32_e32 v50, 16, v51
	v_and_b32_e32 v51, 0xffff0000, v51
	v_lshlrev_b32_e32 v52, 16, v67
	v_and_b32_e32 v53, 0xffff0000, v67
	v_lshlrev_b32_e32 v54, 16, v68
	v_and_b32_e32 v55, 0xffff0000, v68
	v_pk_fma_f32 v[46:47], v[46:47], v[60:61], v[50:51] op_sel_hi:[1,0,1]
	v_pk_fma_f32 v[44:45], v[44:45], v[60:61], v[48:49] op_sel_hi:[1,0,1]
	v_pk_fma_f32 v[42:43], v[42:43], v[60:61], v[54:55] op_sel_hi:[1,0,1]
	v_pk_fma_f32 v[40:41], v[40:41], v[60:61], v[52:53] op_sel_hi:[1,0,1]
	v_cvt_pk_bf16_f32 v48, v44, v45
	v_cvt_pk_bf16_f32 v49, v46, v47
	v_lshlrev_b32_e32 v44, 16, v63
	v_cvt_pk_bf16_f32 v50, v40, v41
	v_cvt_pk_bf16_f32 v51, v42, v43
	v_lshlrev_b32_e32 v40, 16, v61
	v_and_b32_e32 v41, 0xffff0000, v61
	v_lshlrev_b32_e32 v42, 16, v62
	v_and_b32_e32 v43, 0xffff0000, v62
	v_and_b32_e32 v45, 0xffff0000, v63
	v_lshlrev_b32_e32 v46, 16, v64
	v_and_b32_e32 v47, 0xffff0000, v64
	v_pk_fma_f32 v[38:39], v[38:39], v[60:61], v[42:43] op_sel_hi:[1,0,1]
	v_pk_fma_f32 v[36:37], v[36:37], v[60:61], v[40:41] op_sel_hi:[1,0,1]
	v_pk_fma_f32 v[34:35], v[34:35], v[60:61], v[46:47] op_sel_hi:[1,0,1]
	v_pk_fma_f32 v[32:33], v[32:33], v[60:61], v[44:45] op_sel_hi:[1,0,1]
	v_cvt_pk_bf16_f32 v36, v36, v37
	v_cvt_pk_bf16_f32 v37, v38, v39
	v_cvt_pk_bf16_f32 v38, v32, v33
	v_cvt_pk_bf16_f32 v39, v34, v35
	s_nop 0
	v_mov_b32_dpp v40, v48 row_ror:8 row_mask:0xf bank_mask:0xf
	v_mov_b32_dpp v41, v49 row_ror:8 row_mask:0xf bank_mask:0xf
	v_mov_b32_dpp v32, v36 row_ror:8 row_mask:0xf bank_mask:0xf
	v_mov_b32_dpp v33, v37 row_ror:8 row_mask:0xf bank_mask:0xf
	v_mov_b32_dpp v34, v38 row_ror:8 row_mask:0xf bank_mask:0xf
	v_mov_b32_dpp v35, v39 row_ror:8 row_mask:0xf bank_mask:0xf
	v_cndmask_b32_e64 v36, v36, v40, s[6:7]
	v_cndmask_b32_e64 v37, v37, v41, s[6:7]
	v_lshl_add_u64 v[40:41], s[8:9], 0, v[56:57]
	v_cndmask_b32_e64 v32, v32, v48, s[6:7]
	v_cndmask_b32_e64 v33, v33, v49, s[6:7]
	v_cndmask_b32_e64 v34, v34, v50, s[6:7]
	v_cndmask_b32_e64 v35, v35, v51, s[6:7]
	v_lshl_add_u64 v[40:41], v[40:41], 0, v[146:147]
	v_mov_b32_dpp v42, v50 row_ror:8 row_mask:0xf bank_mask:0xf
	v_mov_b32_dpp v43, v51 row_ror:8 row_mask:0xf bank_mask:0xf
	global_store_dwordx4 v[40:41], v[32:35], off
	v_cndmask_b32_e64 v38, v38, v42, s[6:7]
	v_cndmask_b32_e64 v39, v39, v43, s[6:7]
	v_lshl_add_u64 v[32:33], s[8:9], 0, v[58:59]
	v_lshl_add_u64 v[32:33], v[32:33], 0, v[146:147]
	global_store_dwordx4 v[32:33], v[36:39], off
	v_add_u32_e32 v32, 0xa0, v77
	v_ashrrev_i32_e32 v33, 31, v32
	v_lshlrev_b64 v[40:41], 12, v[32:33]
	v_lshl_add_u64 v[42:43], v[40:41], 0, s[36:37]
	s_waitcnt vmcnt(13)
; __device__ __forceinline__ unsigned cvt_pk_bf16(float lo, float hi) { unsigned r; asm volatile("v_cvt_pk_bf16_f32 %0, %1, %2" : "=v"(r) : "v"(lo), "v"(hi)); return r; }
; __device__ __forceinline__ float bflo(unsigned w) { return __uint_as_float(w << 16); }
; __device__ __forceinline__ float bfhi(unsigned w) { return __uint_as_float(w & 0xffff0000u); }
;     __device__ __forceinline__ void operator()(const f32x4 (&acc)[2][2][4][2], const Unit& u, int wr, int wc, int fr, int fq) const {
;     ...
;             for (int m = 0; m < 4; ++m) { const int row = row0 + ai * HALF + m * 16; const size_t off = (size_t)row * D + col0; float sq = 0.f; u32x4 w[2];
;                 const float sc = rsin ? __builtin_amdgcn_rcpf(rsin[row] * (1.f / D) + EPS) : 1.0f;
;                 u32x4 rr[2]; if (R) load_pair_lines(R, D, row, fr, col0, rr[0], rr[1]);
; #pragma unroll
;                 for (int bj = 0; bj < 2; ++bj) { f32x4 r0, r1;
;                     if (R) { const u32x4 rw = rr[bj]; r0 = (f32x4){bflo(rw.x), bfhi(rw.x), bflo(rw.y), bfhi(rw.y)}; r1 = (f32x4){bflo(rw.z), bfhi(rw.z), bflo(rw.w), bfhi(rw.w)}; }
;                     else { const float* rp = (row < 8192 ? src_p + off : src_s + (off - (size_t)8192 * D)) + 8 * bj; r0 = *(const f32x4*)rp; r1 = *(const f32x4*)(rp + 4); }
;                     const f32x4 o0 = r0 + acc[ai][bj][m][0] * sc, o1 = r1 + acc[ai][bj][m][1] * sc;
;                     sq += (o0[0] * o0[0] + o0[1] * o0[1]) + (o0[2] * o0[2] + o0[3] * o0[3]) + (o1[0] * o1[0] + o1[1] * o1[1]) + (o1[2] * o1[2] + o1[3] * o1[3]);
;                     w[bj].x = cvt_pk_bf16(o0[0], o0[1]); w[bj].y = cvt_pk_bf16(o0[2], o0[3]); w[bj].z = cvt_pk_bf16(o1[0], o1[1]); w[bj].w = cvt_pk_bf16(o1[2], o1[3]); }
;                 store_pair_lines(O, D, row, fr, col0, w[0], w[1]);
	s_nop 0
	v_mov_b32_e32 v44, v204
	v_lshl_add_u64 v[32:33], s[16:17], 0, v[40:41]
	v_lshl_add_u64 v[36:37], s[16:17], 0, v[42:43]
	v_lshl_add_u64 v[32:33], v[32:33], 0, v[146:147]
	v_lshl_add_u64 v[36:37], v[36:37], 0, v[146:147]
	v_mov_b64_e32 v[32:33], v[208:209]
	v_mov_b64_e32 v[34:35], v[210:211]
	v_mov_b64_e32 v[36:37], v[212:213]
	v_mov_b64_e32 v[38:39], v[214:215]
	s_nop 1
	v_fmamk_f32 v44, v44, 0x3a000000, v159
	v_rcp_f32_e32 v44, v44
	v_mov_b32_dpp v45, v32 row_ror:8 row_mask:0xf bank_mask:0xf
	v_mov_b32_dpp v46, v33 row_ror:8 row_mask:0xf bank_mask:0xf
	v_mov_b32_dpp v49, v36 row_ror:8 row_mask:0xf bank_mask:0xf
	v_mov_b32_dpp v50, v37 row_ror:8 row_mask:0xf bank_mask:0xf
	v_mov_b32_dpp v51, v38 row_ror:8 row_mask:0xf bank_mask:0xf
	v_mov_b32_dpp v52, v39 row_ror:8 row_mask:0xf bank_mask:0xf
	v_mov_b32_dpp v47, v34 row_ror:8 row_mask:0xf bank_mask:0xf
	v_mov_b32_dpp v48, v35 row_ror:8 row_mask:0xf bank_mask:0xf
	v_cndmask_b32_e64 v52, v52, v35, s[6:7]
	v_cndmask_b32_e64 v51, v51, v34, s[6:7]
	v_cndmask_b32_e64 v35, v50, v33, s[6:7]
	v_cndmask_b32_e64 v33, v49, v32, s[6:7]
	v_cndmask_b32_e64 v48, v39, v48, s[6:7]
	v_cndmask_b32_e64 v47, v38, v47, s[6:7]
	v_cndmask_b32_e64 v46, v37, v46, s[6:7]
	v_cndmask_b32_e64 v45, v36, v45, s[6:7]
	v_lshlrev_b32_e32 v32, 16, v33
	v_and_b32_e32 v33, 0xffff0000, v33
	v_lshlrev_b32_e32 v34, 16, v35
	v_and_b32_e32 v35, 0xffff0000, v35
	v_lshlrev_b32_e32 v36, 16, v51
	v_and_b32_e32 v37, 0xffff0000, v51
	v_lshlrev_b32_e32 v38, 16, v52
	v_and_b32_e32 v39, 0xffff0000, v52
	v_pk_fma_f32 v[30:31], v[30:31], v[44:45], v[34:35] op_sel_hi:[1,0,1]
	v_pk_fma_f32 v[28:29], v[28:29], v[44:45], v[32:33] op_sel_hi:[1,0,1]
	v_pk_fma_f32 v[26:27], v[26:27], v[44:45], v[38:39] op_sel_hi:[1,0,1]
	v_pk_fma_f32 v[24:25], v[24:25], v[44:45], v[36:37] op_sel_hi:[1,0,1]
	v_cvt_pk_bf16_f32 v32, v28, v29
	v_cvt_pk_bf16_f32 v33, v30, v31
	v_lshlrev_b32_e32 v28, 16, v47
	v_cvt_pk_bf16_f32 v34, v24, v25
	v_cvt_pk_bf16_f32 v35, v26, v27
	v_lshlrev_b32_e32 v24, 16, v45
	v_and_b32_e32 v25, 0xffff0000, v45
	v_lshlrev_b32_e32 v26, 16, v46
	v_and_b32_e32 v27, 0xffff0000, v46
	v_and_b32_e32 v29, 0xffff0000, v47
	v_lshlrev_b32_e32 v30, 16, v48
	v_and_b32_e32 v31, 0xffff0000, v48
	v_pk_fma_f32 v[22:23], v[22:23], v[44:45], v[26:27] op_sel_hi:[1,0,1]
	v_pk_fma_f32 v[20:21], v[20:21], v[44:45], v[24:25] op_sel_hi:[1,0,1]
	v_pk_fma_f32 v[18:19], v[18:19], v[44:45], v[30:31] op_sel_hi:[1,0,1]
	v_pk_fma_f32 v[16:17], v[16:17], v[44:45], v[28:29] op_sel_hi:[1,0,1]
	v_cvt_pk_bf16_f32 v20, v20, v21
	v_cvt_pk_bf16_f32 v21, v22, v23
	v_cvt_pk_bf16_f32 v22, v16, v17
	v_cvt_pk_bf16_f32 v23, v18, v19
	s_nop 0
	v_mov_b32_dpp v24, v32 row_ror:8 row_mask:0xf bank_mask:0xf
	v_mov_b32_dpp v25, v33 row_ror:8 row_mask:0xf bank_mask:0xf
	v_mov_b32_dpp v16, v20 row_ror:8 row_mask:0xf bank_mask:0xf
	v_mov_b32_dpp v17, v21 row_ror:8 row_mask:0xf bank_mask:0xf
	v_mov_b32_dpp v18, v22 row_ror:8 row_mask:0xf bank_mask:0xf
	v_mov_b32_dpp v19, v23 row_ror:8 row_mask:0xf bank_mask:0xf
	v_cndmask_b32_e64 v20, v20, v24, s[6:7]
	v_cndmask_b32_e64 v21, v21, v25, s[6:7]
	v_lshl_add_u64 v[24:25], s[8:9], 0, v[40:41]
	v_cndmask_b32_e64 v16, v16, v32, s[6:7]
	v_cndmask_b32_e64 v17, v17, v33, s[6:7]
	v_cndmask_b32_e64 v18, v18, v34, s[6:7]
	v_cndmask_b32_e64 v19, v19, v35, s[6:7]
	v_lshl_add_u64 v[24:25], v[24:25], 0, v[146:147]
	v_mov_b32_dpp v26, v34 row_ror:8 row_mask:0xf bank_mask:0xf
	v_mov_b32_dpp v27, v35 row_ror:8 row_mask:0xf bank_mask:0xf
	global_store_dwordx4 v[24:25], v[16:19], off
	v_cndmask_b32_e64 v22, v22, v26, s[6:7]
	v_cndmask_b32_e64 v23, v23, v27, s[6:7]
	v_lshl_add_u64 v[16:17], s[8:9], 0, v[42:43]
	v_lshl_add_u64 v[16:17], v[16:17], 0, v[146:147]
	global_store_dwordx4 v[16:17], v[20:23], off
	v_add_u32_e32 v16, 0xb0, v77
	v_ashrrev_i32_e32 v17, 31, v16
	v_lshlrev_b64 v[24:25], 12, v[16:17]
	v_lshl_add_u64 v[26:27], v[24:25], 0, s[36:37]
	s_waitcnt vmcnt(10)
; __device__ __forceinline__ unsigned cvt_pk_bf16(float lo, float hi) { unsigned r; asm volatile("v_cvt_pk_bf16_f32 %0, %1, %2" : "=v"(r) : "v"(lo), "v"(hi)); return r; }
; __device__ __forceinline__ float bflo(unsigned w) { return __uint_as_float(w << 16); }
; #define PG8_WAIT_V(n) asm volatile("s_waitcnt vmcnt(" #n ")" ::: "memory")
;     __device__ __forceinline__ void operator()(const f32x4 (&acc)[2][2][4][2], const Unit& u, int wr, int wc, int fr, int fq) const {
;     ...
;             for (int m = 0; m < 4; ++m) { const int row = row0 + ai * HALF + m * 16; const size_t off = (size_t)row * D + col0; float sq = 0.f; u32x4 w[2];
;                 const float sc = rsin ? __builtin_amdgcn_rcpf(rsin[row] * (1.f / D) + EPS) : 1.0f;
;                 u32x4 rr[2]; if (R) load_pair_lines(R, D, row, fr, col0, rr[0], rr[1]);
; #pragma unroll
;                 for (int bj = 0; bj < 2; ++bj) { f32x4 r0, r1;
;                     if (R) { const u32x4 rw = rr[bj]; r0 = (f32x4){bflo(rw.x), bfhi(rw.x), bflo(rw.y), bfhi(rw.y)}; r1 = (f32x4){bflo(rw.z), bfhi(rw.z), bflo(rw.w), bfhi(rw.w)}; }
;                     else { const float* rp = (row < 8192 ? src_p + off : src_s + (off - (size_t)8192 * D)) + 8 * bj; r0 = *(const f32x4*)rp; r1 = *(const f32x4*)(rp + 4); }
;                     const f32x4 o0 = r0 + acc[ai][bj][m][0] * sc, o1 = r1 + acc[ai][bj][m][1] * sc;
;                     sq += (o0[0] * o0[0] + o0[1] * o0[1]) + (o0[2] * o0[2] + o0[3] * o0[3]) + (o1[0] * o1[0] + o1[1] * o1[1]) + (o1[2] * o1[2] + o1[3] * o1[3]);
;                     w[bj].x = cvt_pk_bf16(o0[0], o0[1]); w[bj].y = cvt_pk_bf16(o0[2], o0[3]); w[bj].z = cvt_pk_bf16(o1[0], o1[1]); w[bj].w = cvt_pk_bf16(o1[2], o1[3]); }
;                 store_pair_lines(O, D, row, fr, col0, w[0], w[1]);
; template <class Epi>
; __device__ __forceinline__ void gemm_phase(LAS unsigned char* lds, const Gemm g, const StaticOrder& S, const Epi& E) {
;     ...
;         E(acc, cur, wr, wc, fr, fq);
;         if (!has_next) break;
; #pragma unroll
;         for (int a = 0; a < 2; ++a)
; #pragma unroll
;             for (int b = 0; b < 2; ++b)
; #pragma unroll
;                 for (int m = 0; m < 4; ++m)
; #pragma unroll
;                     for (int n = 0; n < 2; ++n) acc[a][b][m][n] = (f32x4){0.f, 0.f, 0.f, 0.f};
;         cur = nxt; cA = nA; cB = nB; ++ui;
;     }
;     PG8_WAIT_V(0);
;     if (wr == 0) PG8_BAR;
;     PG8_BAR;
	s_nop 0
	v_mov_b32_e32 v28, v205
	v_lshl_add_u64 v[16:17], s[16:17], 0, v[24:25]
	v_lshl_add_u64 v[20:21], s[16:17], 0, v[26:27]
	v_lshl_add_u64 v[16:17], v[16:17], 0, v[146:147]
	v_lshl_add_u64 v[20:21], v[20:21], 0, v[146:147]
	v_mov_b64_e32 v[16:17], v[216:217]
	v_mov_b64_e32 v[18:19], v[218:219]
	v_mov_b64_e32 v[20:21], v[220:221]
	v_mov_b64_e32 v[22:23], v[222:223]
	s_nop 1
	v_fmamk_f32 v28, v28, 0x3a000000, v159
	v_rcp_f32_e32 v28, v28
	v_mov_b32_dpp v29, v16 row_ror:8 row_mask:0xf bank_mask:0xf
	v_mov_b32_dpp v30, v17 row_ror:8 row_mask:0xf bank_mask:0xf
	v_mov_b32_dpp v33, v20 row_ror:8 row_mask:0xf bank_mask:0xf
	v_mov_b32_dpp v34, v21 row_ror:8 row_mask:0xf bank_mask:0xf
	v_mov_b32_dpp v35, v22 row_ror:8 row_mask:0xf bank_mask:0xf
	v_mov_b32_dpp v36, v23 row_ror:8 row_mask:0xf bank_mask:0xf
	v_mov_b32_dpp v31, v18 row_ror:8 row_mask:0xf bank_mask:0xf
	v_mov_b32_dpp v32, v19 row_ror:8 row_mask:0xf bank_mask:0xf
	v_cndmask_b32_e64 v36, v36, v19, s[6:7]
	v_cndmask_b32_e64 v35, v35, v18, s[6:7]
	v_cndmask_b32_e64 v19, v34, v17, s[6:7]
	v_cndmask_b32_e64 v17, v33, v16, s[6:7]
	v_cndmask_b32_e64 v32, v23, v32, s[6:7]
	v_cndmask_b32_e64 v31, v22, v31, s[6:7]
	v_cndmask_b32_e64 v30, v21, v30, s[6:7]
	v_cndmask_b32_e64 v29, v20, v29, s[6:7]
	v_lshlrev_b32_e32 v16, 16, v17
	v_and_b32_e32 v17, 0xffff0000, v17
	v_lshlrev_b32_e32 v18, 16, v19
	v_and_b32_e32 v19, 0xffff0000, v19
	v_lshlrev_b32_e32 v20, 16, v35
	v_and_b32_e32 v21, 0xffff0000, v35
	v_lshlrev_b32_e32 v22, 16, v36
	v_and_b32_e32 v23, 0xffff0000, v36
	v_pk_fma_f32 v[14:15], v[14:15], v[28:29], v[18:19] op_sel_hi:[1,0,1]
	v_pk_fma_f32 v[12:13], v[12:13], v[28:29], v[16:17] op_sel_hi:[1,0,1]
	v_pk_fma_f32 v[10:11], v[10:11], v[28:29], v[22:23] op_sel_hi:[1,0,1]
	v_pk_fma_f32 v[8:9], v[8:9], v[28:29], v[20:21] op_sel_hi:[1,0,1]
	v_cvt_pk_bf16_f32 v16, v12, v13
	v_cvt_pk_bf16_f32 v17, v14, v15
	v_lshlrev_b32_e32 v12, 16, v31
	v_cvt_pk_bf16_f32 v18, v8, v9
	v_cvt_pk_bf16_f32 v19, v10, v11
	v_lshlrev_b32_e32 v8, 16, v29
	v_and_b32_e32 v9, 0xffff0000, v29
	v_lshlrev_b32_e32 v10, 16, v30
	v_and_b32_e32 v11, 0xffff0000, v30
	v_and_b32_e32 v13, 0xffff0000, v31
	v_lshlrev_b32_e32 v14, 16, v32
	v_and_b32_e32 v15, 0xffff0000, v32
	v_pk_fma_f32 v[6:7], v[6:7], v[28:29], v[10:11] op_sel_hi:[1,0,1]
	v_pk_fma_f32 v[4:5], v[4:5], v[28:29], v[8:9] op_sel_hi:[1,0,1]
	v_pk_fma_f32 v[2:3], v[2:3], v[28:29], v[14:15] op_sel_hi:[1,0,1]
	v_pk_fma_f32 v[0:1], v[0:1], v[28:29], v[12:13] op_sel_hi:[1,0,1]
	v_cvt_pk_bf16_f32 v4, v4, v5
	v_cvt_pk_bf16_f32 v5, v6, v7
	v_cvt_pk_bf16_f32 v6, v0, v1
	v_cvt_pk_bf16_f32 v7, v2, v3
	s_nop 0
	v_mov_b32_dpp v8, v16 row_ror:8 row_mask:0xf bank_mask:0xf
	v_mov_b32_dpp v9, v17 row_ror:8 row_mask:0xf bank_mask:0xf
	v_mov_b32_dpp v0, v4 row_ror:8 row_mask:0xf bank_mask:0xf
	v_mov_b32_dpp v1, v5 row_ror:8 row_mask:0xf bank_mask:0xf
	v_mov_b32_dpp v2, v6 row_ror:8 row_mask:0xf bank_mask:0xf
	v_mov_b32_dpp v3, v7 row_ror:8 row_mask:0xf bank_mask:0xf
	v_cndmask_b32_e64 v4, v4, v8, s[6:7]
	v_cndmask_b32_e64 v5, v5, v9, s[6:7]
	v_lshl_add_u64 v[8:9], s[8:9], 0, v[24:25]
	v_cndmask_b32_e64 v0, v0, v16, s[6:7]
	v_cndmask_b32_e64 v1, v1, v17, s[6:7]
	v_cndmask_b32_e64 v2, v2, v18, s[6:7]
	v_cndmask_b32_e64 v3, v3, v19, s[6:7]
	v_lshl_add_u64 v[8:9], v[8:9], 0, v[146:147]
	v_mov_b32_dpp v10, v18 row_ror:8 row_mask:0xf bank_mask:0xf
	v_mov_b32_dpp v11, v19 row_ror:8 row_mask:0xf bank_mask:0xf
	global_store_dwordx4 v[8:9], v[0:3], off
	v_cndmask_b32_e64 v6, v6, v10, s[6:7]
	v_cndmask_b32_e64 v7, v7, v11, s[6:7]
	v_lshl_add_u64 v[0:1], s[8:9], 0, v[26:27]
	v_lshl_add_u64 v[0:1], v[0:1], 0, v[146:147]
	global_store_dwordx4 v[0:1], v[4:7], off
	s_cbranch_vccz .LBB0_798
	s_waitcnt vmcnt(0)
	s_cmpk_gt_u32 s56, 0xff
	s_cbranch_scc1 .LBB0_810
	s_barrier

; #define PG8_STAGE(bufoff, gbase, voff) do { _Pragma("unroll") for (int _i = 0; _i < 2; ++_i) \
;         __builtin_amdgcn_global_load_lds((const unsigned*)((const char*)(gbase) + (voff)[_i]), (LAS unsigned*)(lds + (bufoff) + ldsw + _i * 8192), 16, 0, 0); } while (0)
; #define PG8_LDA(dst, b, h) do { _Pragma("unroll") for (int m = 0; m < 4; ++m) _Pragma("unroll") for (int k = 0; k < 2; ++k) dst[m][k] = *(const LAS bf16x8*)(lds + PG8_SA(b, h) + aoff + m * 2048 + k * 1024); } while (0)
; #define PG8_LDB(dst, b, h) do { _Pragma("unroll") for (int n = 0; n < 2; ++n) _Pragma("unroll") for (int k = 0; k < 2; ++k) dst[n][k] = *(const LAS bf16x8*)(lds + PG8_SB(b, h) + boff + n * 2048 + k * 1024); } while (0)
; #define PG8_MMA(ai, bj, At, Bt) do { __builtin_amdgcn_s_setprio(1); _Pragma("unroll") for (int m = 0; m < 4; ++m) _Pragma("unroll") for (int n = 0; n < 2; ++n) _Pragma("unroll") for (int k = 0; k < 2; ++k) \
;         acc[ai][bj][m][n] = __builtin_amdgcn_mfma_f32_16x16x32_bf16(Bt[n][k], At[m][k], acc[ai][bj][m][n], 0, 0, 0); __builtin_amdgcn_s_setprio(0); } while (0)
; #define PG8_WAIT_V(n) asm volatile("s_waitcnt vmcnt(" #n ")" ::: "memory")
; #define PG8_WAIT_L(n) asm volatile("s_waitcnt lgkmcnt(" #n ")" ::: "memory")
; #define PG8_BAR __builtin_amdgcn_s_barrier()
; #define PG8_SCHED __builtin_amdgcn_sched_barrier(0)
; template <class Epi>
; __device__ __forceinline__ void gemm_phase(LAS unsigned char* lds, const Gemm g, const StaticOrder& S, const Epi& E) {
;     ...
;             PG8_LDB(B0, 0, 0); PG8_SCHED; PG8_LDA(At, 0, 0); PG8_STAGE(PG8_SA(1, 1), a1 + hstep, voffA);
;             PG8_WAIT_L(8); PG8_BAR; PG8_WAIT_L(0); PG8_MMA(0, 0, At, B0); PG8_BAR; PG8_SCHED;
;             PG8_LDB(B1, 0, 1); PG8_STAGE(PG8_SB(0, 0), b2, voffB0);
;             PG8_BAR; PG8_WAIT_L(0); PG8_MMA(0, 1, At, B1); PG8_BAR;
;             PG8_LDA(At, 0, 1); PG8_STAGE(PG8_SA(0, 0), a2, voffA);
;             PG8_BAR; PG8_WAIT_L(0); PG8_MMA(1, 0, At, B0); PG8_BAR; PG8_SCHED;
;             PG8_STAGE(PG8_SB(0, 1), b2, voffB1);
;             PG8_WAIT_V(6); PG8_BAR; PG8_MMA(1, 1, At, B1); PG8_BAR;
.LBB0_882:
	ds_read_b128 v[32:35], v177
	ds_read_b128 v[40:43], v177 offset:1024
	ds_read_b128 v[48:51], v177 offset:2048
	ds_read_b128 v[52:55], v177 offset:3072
	s_add_u32 s33, s60, 0xfff80080
	s_addc_u32 s62, s61, -1
	s_cmp_eq_u32 s86, 28
	s_cselect_b32 s63, s49, s62
	s_cselect_b32 s62, s57, s33
	s_cselect_b32 s65, s47, s85
	s_cselect_b32 s64, s83, s84
	v_lshl_add_u64 v[170:171], s[60:61], 0, v[156:157]
	s_add_i32 m0, s59, 0xc000
	ds_read_b128 v[162:165], v178
	ds_read_b128 v[166:169], v178 offset:1024
	ds_read_b128 v[182:185], v178 offset:2048
	ds_read_b128 v[186:189], v178 offset:3072
	ds_read_b128 v[190:193], v178 offset:4096
	ds_read_b128 v[194:197], v178 offset:5120
	ds_read_b128 v[198:201], v178 offset:6144
	ds_read_b128 v[204:207], v178 offset:7168
	global_load_lds_dwordx4 v[170:171], off
	v_lshl_add_u64 v[170:171], s[60:61], 0, v[158:159]
	s_add_i32 m0, s59, 0xe000
	s_nop 0
	global_load_lds_dwordx4 v[170:171], off
	s_waitcnt lgkmcnt(8)
	s_barrier
	s_waitcnt lgkmcnt(0)
	v_mfma_f32_16x16x32_bf16 v[140:143], v[32:35], v[162:165], v[140:143]
	v_mfma_f32_16x16x32_bf16 v[136:139], v[48:51], v[162:165], v[136:139]
	v_mfma_f32_16x16x32_bf16 v[124:127], v[32:35], v[182:185], v[124:127]
	v_mfma_f32_16x16x32_bf16 v[120:123], v[48:51], v[182:185], v[120:123]
	v_mfma_f32_16x16x32_bf16 v[108:111], v[32:35], v[190:193], v[108:111]
	v_mfma_f32_16x16x32_bf16 v[104:107], v[48:51], v[190:193], v[104:107]
	v_mfma_f32_16x16x32_bf16 v[92:95], v[32:35], v[198:201], v[92:95]
	v_mfma_f32_16x16x32_bf16 v[88:91], v[48:51], v[198:201], v[88:91]
	v_mfma_f32_16x16x32_bf16 v[140:143], v[40:43], v[166:169], v[140:143]
	v_mfma_f32_16x16x32_bf16 v[136:139], v[52:55], v[166:169], v[136:139]
	v_mfma_f32_16x16x32_bf16 v[124:127], v[40:43], v[186:189], v[124:127]
	v_mfma_f32_16x16x32_bf16 v[120:123], v[52:55], v[186:189], v[120:123]
	v_mfma_f32_16x16x32_bf16 v[108:111], v[40:43], v[194:197], v[108:111]
	v_mfma_f32_16x16x32_bf16 v[104:107], v[52:55], v[194:197], v[104:107]
	v_mfma_f32_16x16x32_bf16 v[92:95], v[40:43], v[204:207], v[92:95]
	v_mfma_f32_16x16x32_bf16 v[88:91], v[52:55], v[204:207], v[88:91]
	s_barrier
	s_add_i32 s33, s81, s69
	v_lshl_add_u64 v[170:171], s[64:65], 0, v[146:147]
	s_mov_b32 m0, s33
	ds_read_b128 v[208:211], v179
	ds_read_b128 v[212:215], v179 offset:1024
	ds_read_b128 v[216:219], v179 offset:2048
	ds_read_b128 v[220:223], v179 offset:3072
	global_load_lds_dwordx4 v[170:171], off
	v_lshl_add_u64 v[224:225], s[64:65], 0, v[152:153]
	s_add_i32 m0, s33, 0x2000
	s_nop 0
	global_load_lds_dwordx4 v[224:225], off
	s_waitcnt lgkmcnt(0)
	s_barrier
	s_waitcnt lgkmcnt(0)
	v_mfma_f32_16x16x32_bf16 v[132:135], v[208:211], v[162:165], v[132:135]
	v_mfma_f32_16x16x32_bf16 v[128:131], v[216:219], v[162:165], v[128:131]
	v_mfma_f32_16x16x32_bf16 v[116:119], v[208:211], v[182:185], v[116:119]
	v_mfma_f32_16x16x32_bf16 v[112:115], v[216:219], v[182:185], v[112:115]
	v_mfma_f32_16x16x32_bf16 v[100:103], v[208:211], v[190:193], v[100:103]
	v_mfma_f32_16x16x32_bf16 v[96:99], v[216:219], v[190:193], v[96:99]
	v_mfma_f32_16x16x32_bf16 v[84:87], v[208:211], v[198:201], v[84:87]
	v_mfma_f32_16x16x32_bf16 v[80:83], v[216:219], v[198:201], v[80:83]
	v_mfma_f32_16x16x32_bf16 v[132:135], v[212:215], v[166:169], v[132:135]
	v_mfma_f32_16x16x32_bf16 v[128:131], v[220:223], v[166:169], v[128:131]
	v_mfma_f32_16x16x32_bf16 v[116:119], v[212:215], v[186:189], v[116:119]
	v_mfma_f32_16x16x32_bf16 v[112:115], v[220:223], v[186:189], v[112:115]
	v_mfma_f32_16x16x32_bf16 v[100:103], v[212:215], v[194:197], v[100:103]
	v_mfma_f32_16x16x32_bf16 v[96:99], v[220:223], v[194:197], v[96:99]
	v_mfma_f32_16x16x32_bf16 v[84:87], v[212:215], v[204:207], v[84:87]
	v_mfma_f32_16x16x32_bf16 v[80:83], v[220:223], v[204:207], v[80:83]
	s_mov_b32 m0, s59
	v_lshl_add_u64 v[226:227], s[62:63], 0, v[144:145]
	s_barrier
	ds_read_b128 v[162:165], v178 offset:16384
	ds_read_b128 v[166:169], v178 offset:17408
	ds_read_b128 v[182:185], v178 offset:18432
	ds_read_b128 v[186:189], v178 offset:19456
	ds_read_b128 v[190:193], v178 offset:20480
	ds_read_b128 v[194:197], v178 offset:21504
	ds_read_b128 v[198:201], v178 offset:22528
	ds_read_b128 v[204:207], v178 offset:23552
	global_load_lds_dwordx4 v[226:227], off
	v_lshl_add_u64 v[228:229], s[62:63], 0, v[150:151]
	s_mov_b32 m0, s70
	s_nop 0
	global_load_lds_dwordx4 v[228:229], off
	s_add_i32 s33, s82, s69
	v_lshl_add_u64 v[230:231], s[64:65], 0, v[148:149]
	s_mov_b32 m0, s33
	v_lshl_add_u64 v[232:233], s[64:65], 0, v[154:155]
	global_load_lds_dwordx4 v[230:231], off
	s_add_i32 m0, s33, 0x2000
	s_nop 0
	global_load_lds_dwordx4 v[232:233], off
	s_waitcnt vmcnt(6)
	s_barrier
; #define PG8_STAGE(bufoff, gbase, voff) do { _Pragma("unroll") for (int _i = 0; _i < 2; ++_i) \
;         __builtin_amdgcn_global_load_lds((const unsigned*)((const char*)(gbase) + (voff)[_i]), (LAS unsigned*)(lds + (bufoff) + ldsw + _i * 8192), 16, 0, 0); } while (0)
; #define PG8_LDA(dst, b, h) do { _Pragma("unroll") for (int m = 0; m < 4; ++m) _Pragma("unroll") for (int k = 0; k < 2; ++k) dst[m][k] = *(const LAS bf16x8*)(lds + PG8_SA(b, h) + aoff + m * 2048 + k * 1024); } while (0)
; #define PG8_LDB(dst, b, h) do { _Pragma("unroll") for (int n = 0; n < 2; ++n) _Pragma("unroll") for (int k = 0; k < 2; ++k) dst[n][k] = *(const LAS bf16x8*)(lds + PG8_SB(b, h) + boff + n * 2048 + k * 1024); } while (0)
; #define PG8_MMA(ai, bj, At, Bt) do { __builtin_amdgcn_s_setprio(1); _Pragma("unroll") for (int m = 0; m < 4; ++m) _Pragma("unroll") for (int n = 0; n < 2; ++n) _Pragma("unroll") for (int k = 0; k < 2; ++k) \
;         acc[ai][bj][m][n] = __builtin_amdgcn_mfma_f32_16x16x32_bf16(Bt[n][k], At[m][k], acc[ai][bj][m][n], 0, 0, 0); __builtin_amdgcn_s_setprio(0); } while (0)
; #define PG8_WAIT_V(n) asm volatile("s_waitcnt vmcnt(" #n ")" ::: "memory")
; #define PG8_WAIT_L(n) asm volatile("s_waitcnt lgkmcnt(" #n ")" ::: "memory")
; #define PG8_BAR __builtin_amdgcn_s_barrier()
; #define PG8_SCHED __builtin_amdgcn_sched_barrier(0)
; template <class Epi>
; __device__ __forceinline__ void gemm_phase(LAS unsigned char* lds, const Gemm g, const StaticOrder& S, const Epi& E) {
;     ...
;             PG8_WAIT_V(6); PG8_BAR; PG8_MMA(1, 1, At, B1); PG8_BAR;
;             PG8_LDB(B0, 1, 0); PG8_SCHED; PG8_LDA(At, 1, 0); PG8_STAGE(PG8_SA(0, 1), a2 + hstep, voffA);
;             PG8_WAIT_L(8); PG8_BAR; PG8_WAIT_L(0); PG8_MMA(0, 0, At, B0); PG8_BAR; PG8_SCHED;
;             PG8_LDB(B1, 1, 1); PG8_STAGE(PG8_SB(1, 0), b3, voffB0);
;             PG8_BAR; PG8_WAIT_L(0); PG8_MMA(0, 1, At, B1); PG8_BAR;
;             PG8_LDA(At, 1, 1); PG8_STAGE(PG8_SA(1, 0), a3, voffA);
;             PG8_BAR; PG8_WAIT_L(0); PG8_MMA(1, 0, At, B0); PG8_BAR; PG8_SCHED;
	s_waitcnt lgkmcnt(0)
	v_mfma_f32_16x16x32_bf16 v[76:79], v[32:35], v[162:165], v[76:79]
	v_mfma_f32_16x16x32_bf16 v[72:75], v[48:51], v[162:165], v[72:75]
	v_mfma_f32_16x16x32_bf16 v[60:63], v[32:35], v[182:185], v[60:63]
	v_mfma_f32_16x16x32_bf16 v[56:59], v[48:51], v[182:185], v[56:59]
	v_mfma_f32_16x16x32_bf16 v[28:31], v[32:35], v[190:193], v[28:31]
	v_mfma_f32_16x16x32_bf16 v[24:27], v[48:51], v[190:193], v[24:27]
	v_mfma_f32_16x16x32_bf16 v[12:15], v[32:35], v[198:201], v[12:15]
	v_mfma_f32_16x16x32_bf16 v[8:11], v[48:51], v[198:201], v[8:11]
	v_mfma_f32_16x16x32_bf16 v[76:79], v[40:43], v[166:169], v[76:79]
	v_mfma_f32_16x16x32_bf16 v[72:75], v[52:55], v[166:169], v[72:75]
	v_mfma_f32_16x16x32_bf16 v[60:63], v[40:43], v[186:189], v[60:63]
	v_mfma_f32_16x16x32_bf16 v[56:59], v[52:55], v[186:189], v[56:59]
	v_mfma_f32_16x16x32_bf16 v[28:31], v[40:43], v[194:197], v[28:31]
	v_mfma_f32_16x16x32_bf16 v[24:27], v[52:55], v[194:197], v[24:27]
	v_mfma_f32_16x16x32_bf16 v[12:15], v[40:43], v[204:207], v[12:15]
	v_mfma_f32_16x16x32_bf16 v[8:11], v[52:55], v[204:207], v[8:11]
	v_mfma_f32_16x16x32_bf16 v[44:47], v[208:211], v[182:185], v[44:47]
	v_mfma_f32_16x16x32_bf16 v[36:39], v[216:219], v[182:185], v[36:39]
	v_mfma_f32_16x16x32_bf16 v[20:23], v[208:211], v[190:193], v[20:23]
	v_mfma_f32_16x16x32_bf16 v[16:19], v[216:219], v[190:193], v[16:19]
	v_mfma_f32_16x16x32_bf16 v[4:7], v[208:211], v[198:201], v[4:7]
	v_mfma_f32_16x16x32_bf16 v[0:3], v[216:219], v[198:201], v[0:3]
	v_mfma_f32_16x16x32_bf16 v[32:35], v[208:211], v[162:165], v[68:71]
	v_mfma_f32_16x16x32_bf16 v[40:43], v[216:219], v[162:165], v[64:67]
	v_mfma_f32_16x16x32_bf16 v[44:47], v[212:215], v[186:189], v[44:47]
	v_mfma_f32_16x16x32_bf16 v[36:39], v[220:223], v[186:189], v[36:39]
	v_mfma_f32_16x16x32_bf16 v[20:23], v[212:215], v[194:197], v[20:23]
	v_mfma_f32_16x16x32_bf16 v[16:19], v[220:223], v[194:197], v[16:19]
	v_mfma_f32_16x16x32_bf16 v[4:7], v[212:215], v[204:207], v[4:7]
	v_mfma_f32_16x16x32_bf16 v[0:3], v[220:223], v[204:207], v[0:3]
	v_mfma_f32_16x16x32_bf16 v[32:35], v[212:215], v[166:169], v[32:35]
	v_mfma_f32_16x16x32_bf16 v[40:43], v[220:223], v[166:169], v[40:43]
	s_add_i32 s33, 0, 0x18000
	v_add_u32_e32 v68, s33, v173
	s_barrier
	ds_read_b128 v[48:51], v68
	ds_read_b128 v[52:55], v68 offset:1024
	ds_read_b128 v[64:67], v68 offset:2048
	ds_read_b128 v[68:71], v68 offset:3072
	s_add_u32 s62, s62, 0x80000
	s_addc_u32 s63, s63, 0
	s_mov_b32 m0, s71
	v_lshl_add_u64 v[208:209], s[62:63], 0, v[144:145]
	ds_read_b128 v[162:165], v178 offset:32768
	ds_read_b128 v[166:169], v178 offset:33792
	ds_read_b128 v[182:185], v178 offset:34816
	ds_read_b128 v[186:189], v178 offset:35840
	ds_read_b128 v[190:193], v178 offset:36864
	ds_read_b128 v[194:197], v178 offset:37888
	ds_read_b128 v[198:201], v178 offset:38912
	ds_read_b128 v[204:207], v178 offset:39936
	global_load_lds_dwordx4 v[208:209], off
	v_lshl_add_u64 v[208:209], s[62:63], 0, v[150:151]
	s_mov_b32 m0, s72
	s_nop 0
	global_load_lds_dwordx4 v[208:209], off
	s_waitcnt lgkmcnt(8)
	s_barrier
	s_waitcnt lgkmcnt(0)
	v_mfma_f32_16x16x32_bf16 v[140:143], v[48:51], v[162:165], v[140:143]
	v_mfma_f32_16x16x32_bf16 v[136:139], v[64:67], v[162:165], v[136:139]
	v_mfma_f32_16x16x32_bf16 v[124:127], v[48:51], v[182:185], v[124:127]
	v_mfma_f32_16x16x32_bf16 v[120:123], v[64:67], v[182:185], v[120:123]
	v_mfma_f32_16x16x32_bf16 v[108:111], v[48:51], v[190:193], v[108:111]
	v_mfma_f32_16x16x32_bf16 v[104:107], v[64:67], v[190:193], v[104:107]
	v_mfma_f32_16x16x32_bf16 v[92:95], v[48:51], v[198:201], v[92:95]
	v_mfma_f32_16x16x32_bf16 v[88:91], v[64:67], v[198:201], v[88:91]
	v_mfma_f32_16x16x32_bf16 v[140:143], v[52:55], v[166:169], v[140:143]
	v_mfma_f32_16x16x32_bf16 v[136:139], v[68:71], v[166:169], v[136:139]
	v_mfma_f32_16x16x32_bf16 v[124:127], v[52:55], v[186:189], v[124:127]
	v_mfma_f32_16x16x32_bf16 v[120:123], v[68:71], v[186:189], v[120:123]
	v_mfma_f32_16x16x32_bf16 v[108:111], v[52:55], v[194:197], v[108:111]
	v_mfma_f32_16x16x32_bf16 v[104:107], v[68:71], v[194:197], v[104:107]
	v_mfma_f32_16x16x32_bf16 v[92:95], v[52:55], v[204:207], v[92:95]
	v_mfma_f32_16x16x32_bf16 v[88:91], v[68:71], v[204:207], v[88:91]
	s_barrier
	s_add_i32 s62, 0, 0x1c000
	s_add_i32 s33, s33, s69
	v_add_u32_e32 v181, s62, v173
	v_lshl_add_u64 v[170:171], v[170:171], 0, s[42:43]
	s_mov_b32 m0, s33
	ds_read_b128 v[208:211], v181
	ds_read_b128 v[212:215], v181 offset:1024
	ds_read_b128 v[216:219], v181 offset:2048
	ds_read_b128 v[220:223], v181 offset:3072
	global_load_lds_dwordx4 v[170:171], off
	v_lshl_add_u64 v[170:171], v[224:225], 0, s[42:43]
	s_add_i32 m0, s33, 0x2000
	s_nop 0
	global_load_lds_dwordx4 v[170:171], off
	s_waitcnt lgkmcnt(0)
	s_barrier
	s_waitcnt lgkmcnt(0)
	v_mfma_f32_16x16x32_bf16 v[132:135], v[208:211], v[162:165], v[132:135]
	v_mfma_f32_16x16x32_bf16 v[128:131], v[216:219], v[162:165], v[128:131]
	v_mfma_f32_16x16x32_bf16 v[116:119], v[208:211], v[182:185], v[116:119]
	v_mfma_f32_16x16x32_bf16 v[112:115], v[216:219], v[182:185], v[112:115]
	v_mfma_f32_16x16x32_bf16 v[100:103], v[208:211], v[190:193], v[100:103]
	v_mfma_f32_16x16x32_bf16 v[96:99], v[216:219], v[190:193], v[96:99]
	v_mfma_f32_16x16x32_bf16 v[84:87], v[208:211], v[198:201], v[84:87]
	v_mfma_f32_16x16x32_bf16 v[80:83], v[216:219], v[198:201], v[80:83]
	v_mfma_f32_16x16x32_bf16 v[132:135], v[212:215], v[166:169], v[132:135]
	v_mfma_f32_16x16x32_bf16 v[128:131], v[220:223], v[166:169], v[128:131]
	v_mfma_f32_16x16x32_bf16 v[116:119], v[212:215], v[186:189], v[116:119]
	v_mfma_f32_16x16x32_bf16 v[112:115], v[220:223], v[186:189], v[112:115]
	v_mfma_f32_16x16x32_bf16 v[100:103], v[212:215], v[194:197], v[100:103]
	v_mfma_f32_16x16x32_bf16 v[96:99], v[220:223], v[194:197], v[96:99]
	v_mfma_f32_16x16x32_bf16 v[84:87], v[212:215], v[204:207], v[84:87]
	v_mfma_f32_16x16x32_bf16 v[80:83], v[220:223], v[204:207], v[80:83]
	s_mov_b32 m0, s74
	v_lshl_add_u64 v[170:171], v[226:227], 0, s[42:43]
	s_barrier
; __device__ __forceinline__ float bflo(unsigned w) { return __uint_as_float(w << 16); }
; __device__ __forceinline__ float bfhi(unsigned w) { return __uint_as_float(w & 0xffff0000u); }
; #define PG8_LDA(dst, b, h) do { _Pragma("unroll") for (int m = 0; m < 4; ++m) _Pragma("unroll") for (int k = 0; k < 2; ++k) dst[m][k] = *(const LAS bf16x8*)(lds + PG8_SA(b, h) + aoff + m * 2048 + k * 1024); } while (0)
;     __device__ __forceinline__ void operator()(const f32x4 (&acc)[2][2][4][2], const Unit& u, int wr, int wc, int fr, int fq) const {
;         const int row0 = u.pm * BM + wr * 64 + fr, col0 = u.pn * BM + wc * 64 + 16 * fq;
;         f32x4 gv[2][2];
; #pragma unroll
;         for (int bj = 0; bj < 2; ++bj) { gv[bj][0] = *(const f32x4*)(g + col0 + 8 * bj); gv[bj][1] = *(const f32x4*)(g + col0 + 8 * bj + 4); }
; #pragma unroll
;         for (int ai = 0; ai < 2; ++ai)
; #pragma unroll
;             for (int m = 0; m < 4; ++m) { const int row = row0 + ai * HALF + m * 16; const size_t off = (size_t)row * D + col0; const float ri = __builtin_amdgcn_rsqf(sse[row] * (1.f / D) + EPS); float sq = 0.f; u32x4 w[2];
;                 u32x4 rr[2], ee[2]; load_pair_lines(R, D, row, fr, col0, rr[0], rr[1]); load_pair_lines(E, D, row, fr, col0, ee[0], ee[1]);
; #pragma unroll
;                 for (int bj = 0; bj < 2; ++bj) { const u32x4 rw = rr[bj], ew = ee[bj];
;                     const float r[8] = {bflo(rw.x), bfhi(rw.x), bflo(rw.y), bfhi(rw.y), bflo(rw.z), bfhi(rw.z), bflo(rw.w), bfhi(rw.w)};
;                     const float e[8] = {bflo(ew.x), bfhi(ew.x), bflo(ew.y), bfhi(ew.y), bflo(ew.z), bfhi(ew.z), bflo(ew.w), bfhi(ew.w)};
;                     float o[8];
; #pragma unroll
;                     for (int j = 0; j < 8; ++j) { const float a = acc[ai][bj][m][j >> 2][j & 3]; const float gg = gv[bj][j >> 2][j & 3];
;                         o[j] = r[j] + e[j] * ri * gg * __builtin_amdgcn_rcpf(1.f + __builtin_amdgcn_exp2f(-a * LOG2E)); }
; template <class Epi>
; __device__ __forceinline__ void gemm_phase(LAS unsigned char* lds, const Gemm g, const StaticOrder& S, const Epi& E) {
;     ...
;             PG8_LDA(At, 1, 1); PG8_STAGE(PG8_SA(1, 0), a3, voffA);
;             PG8_BAR; PG8_WAIT_L(0); PG8_MMA(1, 0, At, B0); PG8_BAR; PG8_SCHED;
;             PG8_STAGE(PG8_SB(1, 1), b3, voffB1);
;             PG8_WAIT_V(6); PG8_BAR; PG8_MMA(1, 1, At, B1); PG8_BAR;
;         }
	ds_read_b128 v[162:165], v178 offset:49152
	ds_read_b128 v[166:169], v178 offset:50176
	ds_read_b128 v[182:185], v178 offset:51200
	ds_read_b128 v[186:189], v178 offset:52224
	ds_read_b128 v[190:193], v178 offset:53248
	ds_read_b128 v[194:197], v178 offset:54272
	ds_read_b128 v[198:201], v178 offset:55296
	ds_read_b128 v[204:207], v178 offset:56320
	global_load_lds_dwordx4 v[170:171], off
	v_lshl_add_u64 v[170:171], v[228:229], 0, s[42:43]
	s_mov_b32 m0, s75
	s_nop 0
	global_load_lds_dwordx4 v[170:171], off
	s_add_i32 s33, s62, s69
	v_lshl_add_u64 v[250:251], v[230:231], 0, s[42:43]
	s_mov_b32 m0, s33
	s_nop 0
	global_load_lds_dwordx4 v[250:251], off
	v_lshl_add_u64 v[250:251], v[232:233], 0, s[42:43]
	s_add_i32 m0, s33, 0x2000
	s_nop 0
	global_load_lds_dwordx4 v[250:251], off
	s_waitcnt vmcnt(6)
	s_barrier
	s_waitcnt lgkmcnt(0)
	v_mfma_f32_16x16x32_bf16 v[76:79], v[48:51], v[162:165], v[76:79]
	v_mfma_f32_16x16x32_bf16 v[72:75], v[64:67], v[162:165], v[72:75]
	v_mfma_f32_16x16x32_bf16 v[60:63], v[48:51], v[182:185], v[60:63]
	v_mfma_f32_16x16x32_bf16 v[56:59], v[64:67], v[182:185], v[56:59]
	v_mfma_f32_16x16x32_bf16 v[28:31], v[48:51], v[190:193], v[28:31]
	v_mfma_f32_16x16x32_bf16 v[24:27], v[64:67], v[190:193], v[24:27]
	v_mfma_f32_16x16x32_bf16 v[12:15], v[48:51], v[198:201], v[12:15]
	v_mfma_f32_16x16x32_bf16 v[8:11], v[64:67], v[198:201], v[8:11]
	v_mfma_f32_16x16x32_bf16 v[76:79], v[52:55], v[166:169], v[76:79]
	v_mfma_f32_16x16x32_bf16 v[72:75], v[68:71], v[166:169], v[72:75]
	v_mfma_f32_16x16x32_bf16 v[60:63], v[52:55], v[186:189], v[60:63]
	v_mfma_f32_16x16x32_bf16 v[56:59], v[68:71], v[186:189], v[56:59]
	v_mfma_f32_16x16x32_bf16 v[28:31], v[52:55], v[194:197], v[28:31]
	v_mfma_f32_16x16x32_bf16 v[24:27], v[68:71], v[194:197], v[24:27]
	v_mfma_f32_16x16x32_bf16 v[12:15], v[52:55], v[204:207], v[12:15]
	v_mfma_f32_16x16x32_bf16 v[8:11], v[68:71], v[204:207], v[8:11]
	v_mfma_f32_16x16x32_bf16 v[32:35], v[208:211], v[162:165], v[32:35]
	v_mfma_f32_16x16x32_bf16 v[68:71], v[212:215], v[166:169], v[32:35]
	v_mfma_f32_16x16x32_bf16 v[32:35], v[216:219], v[162:165], v[40:43]
	v_mfma_f32_16x16x32_bf16 v[64:67], v[220:223], v[166:169], v[32:35]
	v_mfma_f32_16x16x32_bf16 v[32:35], v[208:211], v[182:185], v[44:47]
	v_mfma_f32_16x16x32_bf16 v[44:47], v[212:215], v[186:189], v[32:35]
	v_mfma_f32_16x16x32_bf16 v[32:35], v[216:219], v[182:185], v[36:39]
	v_mfma_f32_16x16x32_bf16 v[20:23], v[208:211], v[190:193], v[20:23]
	v_mfma_f32_16x16x32_bf16 v[16:19], v[216:219], v[190:193], v[16:19]
	v_mfma_f32_16x16x32_bf16 v[4:7], v[208:211], v[198:201], v[4:7]
	v_mfma_f32_16x16x32_bf16 v[0:3], v[216:219], v[198:201], v[0:3]
	v_mfma_f32_16x16x32_bf16 v[36:39], v[220:223], v[186:189], v[32:35]
	v_mfma_f32_16x16x32_bf16 v[20:23], v[212:215], v[194:197], v[20:23]
	v_mfma_f32_16x16x32_bf16 v[16:19], v[220:223], v[194:197], v[16:19]
	v_mfma_f32_16x16x32_bf16 v[4:7], v[212:215], v[204:207], v[4:7]
	v_mfma_f32_16x16x32_bf16 v[0:3], v[220:223], v[204:207], v[0:3]
	s_add_i32 s86, s86, 2
	s_add_u32 s60, s60, 0x100
	s_addc_u32 s61, s61, 0
	s_add_u32 s84, s84, 0x100
	s_addc_u32 s85, s85, 0
	s_cmp_gt_u32 s86, 29
	s_barrier
	s_cbranch_scc0 .LBB0_882
	s_lshl_b32 s33, s58, 8
	s_add_i32 s33, s33, s77
	v_lshl_or_b32 v32, s56, 8, v176
	v_or_b32_e32 v40, s33, v174
	v_or_b32_e32 v34, v32, v175
	v_ashrrev_i32_e32 v41, 31, v40
	v_ashrrev_i32_e32 v35, 31, v34
	v_lshlrev_b64 v[168:169], 12, v[40:41]
	v_lshl_add_u64 v[42:43], s[16:17], 0, v[168:169]
	v_lshlrev_b64 v[162:163], 1, v[34:35]
	v_lshl_add_u64 v[34:35], v[42:43], 0, v[162:163]
	global_load_dwordx4 v[182:185], v[34:35], off
	v_or_b32_e32 v34, 8, v40
	v_ashrrev_i32_e32 v35, 31, v34
	v_or_b32_e32 v164, s33, v172
	v_lshlrev_b64 v[170:171], 12, v[34:35]
	v_ashrrev_i32_e32 v165, 31, v164
	v_lshl_add_u64 v[34:35], s[16:17], 0, v[170:171]
	v_lshl_add_u64 v[166:167], v[164:165], 2, s[40:41]
	v_lshl_add_u64 v[34:35], v[34:35], 0, v[162:163]
	global_load_dword v181, v[166:167], off
	v_lshl_add_u64 v[40:41], s[38:39], 0, v[168:169]
	global_load_dwordx4 v[190:193], v[34:35], off
	v_lshl_add_u64 v[34:35], s[38:39], 0, v[170:171]
	v_lshl_add_u64 v[40:41], v[40:41], 0, v[162:163]
	v_lshl_add_u64 v[34:35], v[34:35], 0, v[162:163]
	global_load_dwordx4 v[186:189], v[40:41], off
	global_load_dwordx4 v[194:197], v[34:35], off
	v_ashrrev_i32_e32 v33, 31, v32
	v_lshl_add_u64 v[40:41], v[32:33], 2, s[10:11]
	global_load_dwordx4 v[52:55], v[40:41], off
	global_load_dwordx4 v[48:51], v[40:41], off offset:16
	global_load_dwordx4 v[32:35], v[40:41], off offset:48
	s_nop 0
	global_load_dwordx4 v[40:43], v[40:41], off offset:32
	v_or_b32_e32 v216, 16, v164
	v_ashrrev_i32_e32 v217, 31, v216
	v_lshl_add_u64 v[218:219], v[216:217], 2, s[40:41]
	global_load_dword v226, v[218:219], off
	v_sub_u32_e32 v218, v216, v172
	v_add_u32_e32 v218, v218, v174
	v_ashrrev_i32_e32 v219, 31, v218
	v_lshlrev_b64 v[218:219], 12, v[218:219]
	v_lshl_add_u64 v[220:221], s[16:17], 0, v[218:219]
	v_lshl_add_u64 v[220:221], v[220:221], 0, v[162:163]
	global_load_dwordx4 v[228:231], v[220:221], off
	v_lshl_add_u64 v[220:221], s[38:39], 0, v[218:219]
	v_lshl_add_u64 v[220:221], v[220:221], 0, v[162:163]
	global_load_dwordx4 v[232:235], v[220:221], off
	v_lshl_add_u64 v[220:221], v[218:219], 0, s[44:45]
	v_lshl_add_u64 v[224:225], s[38:39], 0, v[220:221]
	v_lshl_add_u64 v[222:223], s[16:17], 0, v[220:221]
	v_lshl_add_u64 v[224:225], v[224:225], 0, v[162:163]
	v_lshl_add_u64 v[222:223], v[222:223], 0, v[162:163]
	global_load_dwordx4 v[236:239], v[224:225], off
	global_load_dwordx4 v[240:243], v[222:223], off
	v_mul_f32_e32 v140, 0xbfb8aa3b, v140
	v_exp_f32_e32 v140, v140
	v_mul_f32_e32 v141, 0xbfb8aa3b, v141
	v_exp_f32_e32 v141, v141
	v_add_f32_e32 v140, 1.0, v140
	v_rcp_f32_e32 v140, v140
	v_add_f32_e32 v141, 1.0, v141
	v_rcp_f32_e32 v141, v141
	v_mul_f32_e32 v136, 0xbfb8aa3b, v136
	v_exp_f32_e32 v136, v136
	v_mul_f32_e32 v137, 0xbfb8aa3b, v137
	v_exp_f32_e32 v137, v137
	v_add_f32_e32 v136, 1.0, v136
	v_rcp_f32_e32 v136, v136
	v_add_f32_e32 v137, 1.0, v137
	v_mul_f32_e32 v132, 0xbfb8aa3b, v132
	v_rcp_f32_e32 v137, v137
	v_exp_f32_e32 v132, v132
	v_mul_f32_e32 v133, 0xbfb8aa3b, v133
	v_exp_f32_e32 v133, v133
	v_add_f32_e32 v132, 1.0, v132
	v_rcp_f32_e32 v132, v132
	v_add_f32_e32 v133, 1.0, v133
	v_rcp_f32_e32 v133, v133
	v_mul_f32_e32 v128, 0xbfb8aa3b, v128
	v_exp_f32_e32 v128, v128
	v_mul_f32_e32 v129, 0xbfb8aa3b, v129
	v_exp_f32_e32 v129, v129
	v_add_f32_e32 v128, 1.0, v128
	v_rcp_f32_e32 v128, v128
	v_add_f32_e32 v129, 1.0, v129
	v_rcp_f32_e32 v129, v129
	s_waitcnt vmcnt(5)
; __device__ __forceinline__ unsigned cvt_pk_bf16(float lo, float hi) { unsigned r; asm volatile("v_cvt_pk_bf16_f32 %0, %1, %2" : "=v"(r) : "v"(lo), "v"(hi)); return r; }
; __device__ __forceinline__ float bflo(unsigned w) { return __uint_as_float(w << 16); }
; __device__ __forceinline__ float bfhi(unsigned w) { return __uint_as_float(w & 0xffff0000u); }
;     __device__ __forceinline__ void operator()(const f32x4 (&acc)[2][2][4][2], const Unit& u, int wr, int wc, int fr, int fq) const {
;     ...
;             for (int m = 0; m < 4; ++m) { const int row = row0 + ai * HALF + m * 16; const size_t off = (size_t)row * D + col0; const float ri = __builtin_amdgcn_rsqf(sse[row] * (1.f / D) + EPS); float sq = 0.f; u32x4 w[2];
;                 u32x4 rr[2], ee[2]; load_pair_lines(R, D, row, fr, col0, rr[0], rr[1]); load_pair_lines(E, D, row, fr, col0, ee[0], ee[1]);
; #pragma unroll
;                 for (int bj = 0; bj < 2; ++bj) { const u32x4 rw = rr[bj], ew = ee[bj];
;                     const float r[8] = {bflo(rw.x), bfhi(rw.x), bflo(rw.y), bfhi(rw.y), bflo(rw.z), bfhi(rw.z), bflo(rw.w), bfhi(rw.w)};
;                     const float e[8] = {bflo(ew.x), bfhi(ew.x), bflo(ew.y), bfhi(ew.y), bflo(ew.z), bfhi(ew.z), bflo(ew.w), bfhi(ew.w)};
;                     float o[8];
; #pragma unroll
;                     for (int j = 0; j < 8; ++j) { const float a = acc[ai][bj][m][j >> 2][j & 3]; const float gg = gv[bj][j >> 2][j & 3];
;                         o[j] = r[j] + e[j] * ri * gg * __builtin_amdgcn_rcpf(1.f + __builtin_amdgcn_exp2f(-a * LOG2E)); }
;                     if (OUT) { *(f32x4*)(OUT + off + 8 * bj) = (f32x4){o[0], o[1], o[2], o[3]}; *(f32x4*)(OUT + off + 8 * bj + 4) = (f32x4){o[4], o[5], o[6], o[7]}; }
;                     else { sq += (o[0] * o[0] + o[1] * o[1]) + (o[2] * o[2] + o[3] * o[3]) + (o[4] * o[4] + o[5] * o[5]) + (o[6] * o[6] + o[7] * o[7]);
;                         w[bj].x = cvt_pk_bf16(o[0], o[1]); w[bj].y = cvt_pk_bf16(o[2], o[3]); w[bj].z = cvt_pk_bf16(o[4], o[5]); w[bj].w = cvt_pk_bf16(o[6], o[7]); } }
	v_mov_b32_dpp v198, v182 row_ror:8 row_mask:0xf bank_mask:0xf
	v_mov_b32_dpp v199, v183 row_ror:8 row_mask:0xf bank_mask:0xf
	v_mov_b32_dpp v200, v184 row_ror:8 row_mask:0xf bank_mask:0xf
	v_mov_b32_dpp v201, v185 row_ror:8 row_mask:0xf bank_mask:0xf
	v_fmamk_f32 v181, v181, 0x3a000000, v180
	v_rsq_f32_e32 v181, v181
	v_mov_b32_dpp v204, v190 row_ror:8 row_mask:0xf bank_mask:0xf
	v_cndmask_b32_e64 v182, v204, v182, s[6:7]
	v_cndmask_b32_e64 v190, v190, v198, s[6:7]
	v_lshlrev_b32_e32 v198, 16, v182
	v_mov_b32_dpp v208, v186 row_ror:8 row_mask:0xf bank_mask:0xf
	v_mov_b32_dpp v212, v194 row_ror:8 row_mask:0xf bank_mask:0xf
	v_cndmask_b32_e64 v186, v212, v186, s[6:7]
	v_lshlrev_b32_e32 v204, 16, v186
	v_mul_f32_e32 v204, v181, v204
	v_and_b32_e32 v186, 0xffff0000, v186
	v_mul_f32_e32 v204, v52, v204
	v_fmac_f32_e32 v198, v140, v204
	v_mul_f32_e32 v140, v181, v186
	v_and_b32_e32 v182, 0xffff0000, v182
	v_mul_f32_e32 v140, v53, v140
	v_fmac_f32_e32 v182, v141, v140
	v_mul_f32_e32 v140, 0xbfb8aa3b, v142
	v_exp_f32_e32 v140, v140
	v_mul_f32_e32 v142, 0xbfb8aa3b, v143
	v_exp_f32_e32 v142, v142
	v_mov_b32_dpp v213, v195 row_ror:8 row_mask:0xf bank_mask:0xf
	v_add_f32_e32 v140, 1.0, v140
	v_mov_b32_dpp v209, v187 row_ror:8 row_mask:0xf bank_mask:0xf
	v_mov_b32_dpp v205, v191 row_ror:8 row_mask:0xf bank_mask:0xf
	v_cndmask_b32_e64 v187, v213, v187, s[6:7]
	v_rcp_f32_e32 v140, v140
	v_cndmask_b32_e64 v183, v205, v183, s[6:7]
	v_lshlrev_b32_e32 v205, 16, v187
	v_add_f32_e32 v142, 1.0, v142
	v_mul_f32_e32 v141, v181, v205
	v_rcp_f32_e32 v142, v142
	v_cndmask_b32_e64 v191, v191, v199, s[6:7]
	v_mov_b32_dpp v214, v196 row_ror:8 row_mask:0xf bank_mask:0xf
	v_lshlrev_b32_e32 v199, 16, v183
	v_and_b32_e32 v187, 0xffff0000, v187
	v_mul_f32_e32 v141, v54, v141
	v_mov_b32_dpp v210, v188 row_ror:8 row_mask:0xf bank_mask:0xf
	v_mov_b32_dpp v206, v192 row_ror:8 row_mask:0xf bank_mask:0xf
	v_cndmask_b32_e64 v188, v214, v188, s[6:7]
	v_fmac_f32_e32 v199, v140, v141
	v_mul_f32_e32 v140, v181, v187
	v_cndmask_b32_e64 v184, v206, v184, s[6:7]
	v_and_b32_e32 v183, 0xffff0000, v183
	v_lshlrev_b32_e32 v206, 16, v188
	v_mul_f32_e32 v140, v55, v140
	v_fmac_f32_e32 v183, v142, v140
	v_mul_f32_e32 v140, v181, v206
	v_cndmask_b32_e64 v192, v192, v200, s[6:7]
	v_lshlrev_b32_e32 v200, 16, v184
	v_and_b32_e32 v188, 0xffff0000, v188
	v_mul_f32_e32 v140, v48, v140
	v_fmac_f32_e32 v200, v136, v140
	v_mul_f32_e32 v136, v181, v188
	v_and_b32_e32 v184, 0xffff0000, v184
	v_mul_f32_e32 v136, v49, v136
	v_fmac_f32_e32 v184, v137, v136
	v_mul_f32_e32 v136, 0xbfb8aa3b, v138
	v_cndmask_b32_e64 v194, v194, v208, s[6:7]
	v_exp_f32_e32 v136, v136
	v_mul_f32_e32 v138, 0xbfb8aa3b, v139
	v_lshlrev_b32_e32 v187, 16, v194
	v_exp_f32_e32 v138, v138
	v_mul_f32_e32 v187, v181, v187
	v_lshlrev_b32_e32 v141, 16, v190
	v_and_b32_e32 v188, 0xffff0000, v194
	v_mul_f32_e32 v187, v40, v187
	v_mov_b32_dpp v215, v197 row_ror:8 row_mask:0xf bank_mask:0xf
	v_add_f32_e32 v136, 1.0, v136
	v_fmac_f32_e32 v141, v132, v187
	v_mul_f32_e32 v132, v181, v188
	v_mov_b32_dpp v211, v189 row_ror:8 row_mask:0xf bank_mask:0xf
	v_mov_b32_dpp v207, v193 row_ror:8 row_mask:0xf bank_mask:0xf
	v_cndmask_b32_e64 v189, v215, v189, s[6:7]
	v_rcp_f32_e32 v136, v136
	v_and_b32_e32 v142, 0xffff0000, v190
	v_mul_f32_e32 v132, v41, v132
	v_cndmask_b32_e64 v185, v207, v185, s[6:7]
	v_lshlrev_b32_e32 v207, 16, v189
	v_add_f32_e32 v138, 1.0, v138
	v_fmac_f32_e32 v142, v133, v132
	v_mul_f32_e32 v132, 0xbfb8aa3b, v134
	v_mul_f32_e32 v137, v181, v207
	v_rcp_f32_e32 v138, v138
	v_exp_f32_e32 v132, v132
	v_cndmask_b32_e64 v193, v193, v201, s[6:7]
	v_lshlrev_b32_e32 v201, 16, v185
	v_and_b32_e32 v189, 0xffff0000, v189
	v_mul_f32_e32 v137, v50, v137
	v_mul_f32_e32 v134, 0xbfb8aa3b, v135
	v_fmac_f32_e32 v201, v136, v137
	v_mul_f32_e32 v136, v181, v189
	v_exp_f32_e32 v134, v134
	v_and_b32_e32 v185, 0xffff0000, v185
	v_mul_f32_e32 v136, v51, v136
	v_fmac_f32_e32 v185, v138, v136
	v_mul_f32_e32 v136, v182, v182
	v_mul_f32_e32 v137, v183, v183
	v_add_f32_e32 v132, 1.0, v132
	v_cndmask_b32_e64 v195, v195, v209, s[6:7]
	v_fmac_f32_e32 v136, v198, v198
	v_fmac_f32_e32 v137, v199, v199
	v_rcp_f32_e32 v132, v132
	v_add_f32_e32 v136, v136, v137
; __device__ __forceinline__ unsigned cvt_pk_bf16(float lo, float hi) { unsigned r; asm volatile("v_cvt_pk_bf16_f32 %0, %1, %2" : "=v"(r) : "v"(lo), "v"(hi)); return r; }
; __device__ __forceinline__ unsigned dpp_ror8(unsigned x) { return (unsigned)__builtin_amdgcn_update_dpp(0, (int)x, 0x128, 0xf, 0xf, false); }
; __device__ __forceinline__ void store_pair_lines(bf16_t* O, int ldc, int row, int fr, int col0, u32x4 wA, u32x4 wB) {
;     const u32x4 sA = {dpp_ror8(wA.x), dpp_ror8(wA.y), dpp_ror8(wA.z), dpp_ror8(wA.w)}, sB = {dpp_ror8(wB.x), dpp_ror8(wB.y), dpp_ror8(wB.z), dpp_ror8(wB.w)};
;     const bool lo = fr < 8;
;     const u32x4 o1 = lo ? wA : sB, o2 = lo ? sA : wB;
;     const int r1 = row - fr + (fr & 7), cb = col0 + (lo ? 0 : 8);
;     *(u32x4*)(O + (size_t)r1 * ldc + cb) = o1;
;     *(u32x4*)(O + (size_t)(r1 + 8) * ldc + cb) = o2;
; }
;     __device__ __forceinline__ void operator()(const f32x4 (&acc)[2][2][4][2], const Unit& u, int wr, int wc, int fr, int fq) const {
;     ...
;                     for (int j = 0; j < 8; ++j) { const float a = acc[ai][bj][m][j >> 2][j & 3]; const float gg = gv[bj][j >> 2][j & 3];
;                         o[j] = r[j] + e[j] * ri * gg * __builtin_amdgcn_rcpf(1.f + __builtin_amdgcn_exp2f(-a * LOG2E)); }
;                     if (OUT) { *(f32x4*)(OUT + off + 8 * bj) = (f32x4){o[0], o[1], o[2], o[3]}; *(f32x4*)(OUT + off + 8 * bj + 4) = (f32x4){o[4], o[5], o[6], o[7]}; }
;                     else { sq += (o[0] * o[0] + o[1] * o[1]) + (o[2] * o[2] + o[3] * o[3]) + (o[4] * o[4] + o[5] * o[5]) + (o[6] * o[6] + o[7] * o[7]);
;                         w[bj].x = cvt_pk_bf16(o[0], o[1]); w[bj].y = cvt_pk_bf16(o[2], o[3]); w[bj].z = cvt_pk_bf16(o[4], o[5]); w[bj].w = cvt_pk_bf16(o[6], o[7]); } }
;                 if (!OUT) { store_pair_lines(O, D, row, fr, col0, w[0], w[1]);
;                     sq += __shfl_xor(sq, 16); sq += __shfl_xor(sq, 32); if (fq == 0) unsafeAtomicAdd(ssout + row, sq); } }
	v_mul_f32_e32 v137, v184, v184
	v_lshlrev_b32_e32 v189, 16, v195
	v_add_f32_e32 v134, 1.0, v134
	v_fmac_f32_e32 v137, v200, v200
	v_mul_f32_e32 v133, v181, v189
	v_rcp_f32_e32 v134, v134
	v_add_f32_e32 v136, v137, v136
	v_mul_f32_e32 v137, v185, v185
	v_lshlrev_b32_e32 v143, 16, v191
	v_and_b32_e32 v190, 0xffff0000, v195
	v_mul_f32_e32 v133, v42, v133
	v_cndmask_b32_e64 v196, v196, v210, s[6:7]
	v_fmac_f32_e32 v137, v201, v201
	v_fmac_f32_e32 v143, v132, v133
	v_mul_f32_e32 v132, v181, v190
	v_add_f32_e32 v136, v137, v136
	v_cvt_pk_bf16_f32 v137, v198, v182
	v_and_b32_e32 v182, 0xffff0000, v191
	v_lshlrev_b32_e32 v191, 16, v196
	v_mul_f32_e32 v132, v43, v132
	v_fmac_f32_e32 v182, v134, v132
	v_mul_f32_e32 v132, v181, v191
	v_cvt_pk_bf16_f32 v138, v199, v183
	v_cvt_pk_bf16_f32 v139, v200, v184
	v_lshlrev_b32_e32 v183, 16, v192
	v_and_b32_e32 v184, 0xffff0000, v192
	v_and_b32_e32 v192, 0xffff0000, v196
	v_mul_f32_e32 v132, v32, v132
	v_fmac_f32_e32 v183, v128, v132
	v_mul_f32_e32 v128, v181, v192
	v_mul_f32_e32 v128, v33, v128
	v_fmac_f32_e32 v184, v129, v128
	v_mul_f32_e32 v128, 0xbfb8aa3b, v130
	v_exp_f32_e32 v128, v128
	v_mul_f32_e32 v130, 0xbfb8aa3b, v131
	v_exp_f32_e32 v130, v130
	v_cndmask_b32_e64 v197, v197, v211, s[6:7]
	v_add_f32_e32 v128, 1.0, v128
	v_rcp_f32_e32 v128, v128
	v_cvt_pk_bf16_f32 v140, v201, v185
	v_lshlrev_b32_e32 v185, 16, v193
	v_and_b32_e32 v186, 0xffff0000, v193
	v_lshlrev_b32_e32 v193, 16, v197
	v_add_f32_e32 v130, 1.0, v130
	v_mul_f32_e32 v129, v181, v193
	v_rcp_f32_e32 v130, v130
	v_and_b32_e32 v194, 0xffff0000, v197
	v_mul_f32_e32 v129, v34, v129
	v_fmac_f32_e32 v185, v128, v129
	v_mul_f32_e32 v128, v181, v194
	v_mul_f32_e32 v128, v35, v128
	v_fmac_f32_e32 v186, v130, v128
	v_mul_f32_e32 v128, v142, v142
	v_mul_f32_e32 v129, v182, v182
	v_fmac_f32_e32 v128, v141, v141
	v_fmac_f32_e32 v129, v143, v143
	v_add_f32_e32 v128, v128, v129
	v_mul_f32_e32 v129, v184, v184
	v_fmac_f32_e32 v129, v183, v183
	v_add_f32_e32 v128, v129, v128
	v_mul_f32_e32 v129, v186, v186
	v_fmac_f32_e32 v129, v185, v185
	v_add_f32_e32 v128, v129, v128
	v_add_f32_e32 v135, v128, v136
	v_cvt_pk_bf16_f32 v128, v141, v142
	v_cvt_pk_bf16_f32 v129, v143, v182
	v_mov_b32_dpp v143, v138 row_ror:8 row_mask:0xf bank_mask:0xf
	v_mov_b32_dpp v130, v128 row_ror:8 row_mask:0xf bank_mask:0xf
	v_mov_b32_dpp v134, v137 row_ror:8 row_mask:0xf bank_mask:0xf
	v_cndmask_b32_e64 v130, v130, v137, s[6:7]
	v_mov_b32_dpp v131, v129 row_ror:8 row_mask:0xf bank_mask:0xf
	v_cndmask_b32_e64 v137, v129, v143, s[6:7]
	v_and_b32_e32 v129, 64, v203
	v_cndmask_b32_e64 v136, v128, v134, s[6:7]
	v_xor_b32_e32 v128, 16, v203
	v_add_u32_e32 v143, 64, v129
	v_cmp_lt_i32_e32 vcc, v128, v143
	v_cvt_pk_bf16_f32 v141, v183, v184
	v_mov_b32_e32 v181, 0
	v_mov_b32_e32 v133, 0
	v_cndmask_b32_e32 v128, v203, v128, vcc
	v_lshlrev_b32_e32 v134, 2, v128
	ds_bpermute_b32 v183, v134, v135
	v_cvt_pk_bf16_f32 v142, v185, v186
	v_mov_b32_dpp v181, v139 row_ror:8 row_mask:0xf bank_mask:0xf
	v_mov_b32_e32 v182, 0
	v_mov_b32_dpp v133, v142 row_ror:8 row_mask:0xf bank_mask:0xf
	v_lshl_add_u64 v[128:129], s[36:37], 0, v[168:169]
	v_mov_b32_dpp v182, v140 row_ror:8 row_mask:0xf bank_mask:0xf
	v_mov_b32_dpp v132, v141 row_ror:8 row_mask:0xf bank_mask:0xf
	v_cndmask_b32_e64 v131, v131, v138, s[6:7]
	v_cndmask_b32_e64 v133, v133, v140, s[6:7]
	v_cndmask_b32_e64 v138, v141, v181, s[6:7]
	v_lshl_add_u64 v[140:141], v[128:129], 0, v[162:163]
	v_xor_b32_e32 v129, 32, v203
	v_cmp_lt_i32_e32 vcc, v129, v143
	s_waitcnt lgkmcnt(0)
	v_add_f32_e32 v128, v135, v183
	v_cndmask_b32_e64 v132, v132, v139, s[6:7]
	v_cndmask_b32_e32 v129, v203, v129, vcc
	v_lshlrev_b32_e32 v135, 2, v129
	ds_bpermute_b32 v129, v135, v128
	global_store_dwordx4 v[140:141], v[130:133], off
	v_cndmask_b32_e64 v139, v142, v182, s[6:7]
	s_nop 0
	v_lshl_add_u64 v[130:131], s[36:37], 0, v[170:171]
	v_lshl_add_u64 v[130:131], v[130:131], 0, v[162:163]
	global_store_dwordx4 v[130:131], v[136:139], off
	s_and_saveexec_b64 s[56:57], s[8:9]
	s_cbranch_execz .LBB0_885
	v_lshl_add_u64 v[130:131], v[164:165], 2, s[18:19]
	s_waitcnt lgkmcnt(0)
	v_add_f32_e32 v128, v128, v129
	global_atomic_add_f32 v[130:131], v128, off

; #define PG8_STAGE(bufoff, gbase, voff) do { _Pragma("unroll") for (int _i = 0; _i < 2; ++_i) \
;         __builtin_amdgcn_global_load_lds((const unsigned*)((const char*)(gbase) + (voff)[_i]), (LAS unsigned*)(lds + (bufoff) + ldsw + _i * 8192), 16, 0, 0); } while (0)
; #define PG8_LDA(dst, b, h) do { _Pragma("unroll") for (int m = 0; m < 4; ++m) _Pragma("unroll") for (int k = 0; k < 2; ++k) dst[m][k] = *(const LAS bf16x8*)(lds + PG8_SA(b, h) + aoff + m * 2048 + k * 1024); } while (0)
; #define PG8_LDB(dst, b, h) do { _Pragma("unroll") for (int n = 0; n < 2; ++n) _Pragma("unroll") for (int k = 0; k < 2; ++k) dst[n][k] = *(const LAS bf16x8*)(lds + PG8_SB(b, h) + boff + n * 2048 + k * 1024); } while (0)
; #define PG8_MMA(ai, bj, At, Bt) do { __builtin_amdgcn_s_setprio(1); _Pragma("unroll") for (int m = 0; m < 4; ++m) _Pragma("unroll") for (int n = 0; n < 2; ++n) _Pragma("unroll") for (int k = 0; k < 2; ++k) \
;         acc[ai][bj][m][n] = __builtin_amdgcn_mfma_f32_16x16x32_bf16(Bt[n][k], At[m][k], acc[ai][bj][m][n], 0, 0, 0); __builtin_amdgcn_s_setprio(0); } while (0)
; #define PG8_WAIT_V(n) asm volatile("s_waitcnt vmcnt(" #n ")" ::: "memory")
; #define PG8_WAIT_L(n) asm volatile("s_waitcnt lgkmcnt(" #n ")" ::: "memory")
; #define PG8_BAR __builtin_amdgcn_s_barrier()
; template <class Epi>
; __device__ __forceinline__ void gemm_phase(LAS unsigned char* lds, const Gemm g, const StaticOrder& S, const Epi& E) {
;     ...
;         for (int t = 0; t < nt; t += 2) {
;             const bool last = (t == nt - 2);
;             const char* a1 = cA + (size_t)(t + 1) * kstep;
;             const char* a2 = last ? nA : cA + (size_t)(t + 2) * kstep; const char* b2 = last ? nB : cB + (size_t)(t + 2) * kstep;
;             const char* a3 = a2 + kstep; const char* b3 = b2 + kstep;
;             PG8_LDB(B0, 0, 0); PG8_SCHED; PG8_LDA(At, 0, 0); PG8_STAGE(PG8_SA(1, 1), a1 + hstep, voffA);
;             PG8_WAIT_L(8); PG8_BAR; PG8_WAIT_L(0); PG8_MMA(0, 0, At, B0); PG8_BAR; PG8_SCHED;
;             PG8_LDB(B1, 0, 1); PG8_STAGE(PG8_SB(0, 0), b2, voffB0);
;             PG8_BAR; PG8_WAIT_L(0); PG8_MMA(0, 1, At, B1); PG8_BAR;
;             PG8_LDA(At, 0, 1); PG8_STAGE(PG8_SA(0, 0), a2, voffA);
;             PG8_BAR; PG8_WAIT_L(0); PG8_MMA(1, 0, At, B0); PG8_BAR; PG8_SCHED;
;             PG8_STAGE(PG8_SB(0, 1), b2, voffB1);
;             PG8_WAIT_V(6); PG8_BAR; PG8_MMA(1, 1, At, B1); PG8_BAR;
.LBB0_962:
	ds_read_b128 v[146:149], v158
	ds_read_b128 v[150:153], v158 offset:1024
	ds_read_b128 v[162:165], v158 offset:2048
	ds_read_b128 v[166:169], v158 offset:3072
	s_add_u32 s33, s46, 0xfff80080
	s_addc_u32 s48, s47, -1
	s_cmp_eq_u32 s77, 28
	s_cselect_b32 s49, s37, s48
	s_cselect_b32 s48, s72, s33
	s_cselect_b32 s51, s19, s75
	s_cselect_b32 s50, s73, s74
	v_lshl_add_u64 v[204:205], s[46:47], 0, v[140:141]
	s_add_i32 m0, s45, 0xc000
	ds_read_b128 v[170:173], v159
	ds_read_b128 v[174:177], v159 offset:1024
	ds_read_b128 v[178:181], v159 offset:2048
	ds_read_b128 v[182:185], v159 offset:3072
	ds_read_b128 v[186:189], v159 offset:4096
	ds_read_b128 v[190:193], v159 offset:5120
	ds_read_b128 v[194:197], v159 offset:6144
	ds_read_b128 v[198:201], v159 offset:7168
	global_load_lds_dwordx4 v[204:205], off
	v_lshl_add_u64 v[204:205], s[46:47], 0, v[142:143]
	s_add_i32 m0, s45, 0xe000
	s_nop 0
	global_load_lds_dwordx4 v[204:205], off
	s_waitcnt lgkmcnt(8)
	s_barrier
	s_waitcnt lgkmcnt(0)
	v_mfma_f32_16x16x32_bf16 v[124:127], v[146:149], v[170:173], v[124:127]
	v_mfma_f32_16x16x32_bf16 v[120:123], v[162:165], v[170:173], v[120:123]
	v_mfma_f32_16x16x32_bf16 v[108:111], v[146:149], v[178:181], v[108:111]
	v_mfma_f32_16x16x32_bf16 v[104:107], v[162:165], v[178:181], v[104:107]
	v_mfma_f32_16x16x32_bf16 v[92:95], v[146:149], v[186:189], v[92:95]
	v_mfma_f32_16x16x32_bf16 v[88:91], v[162:165], v[186:189], v[88:91]
	v_mfma_f32_16x16x32_bf16 v[76:79], v[146:149], v[194:197], v[76:79]
	v_mfma_f32_16x16x32_bf16 v[72:75], v[162:165], v[194:197], v[72:75]
	v_mfma_f32_16x16x32_bf16 v[124:127], v[150:153], v[174:177], v[124:127]
	v_mfma_f32_16x16x32_bf16 v[120:123], v[166:169], v[174:177], v[120:123]
	v_mfma_f32_16x16x32_bf16 v[108:111], v[150:153], v[182:185], v[108:111]
	v_mfma_f32_16x16x32_bf16 v[104:107], v[166:169], v[182:185], v[104:107]
	v_mfma_f32_16x16x32_bf16 v[92:95], v[150:153], v[190:193], v[92:95]
	v_mfma_f32_16x16x32_bf16 v[88:91], v[166:169], v[190:193], v[88:91]
	v_mfma_f32_16x16x32_bf16 v[76:79], v[150:153], v[198:201], v[76:79]
	v_mfma_f32_16x16x32_bf16 v[72:75], v[166:169], v[198:201], v[72:75]
	s_barrier
	s_add_i32 s33, s68, s57
	v_lshl_add_u64 v[220:221], s[50:51], 0, v[134:135]
	s_mov_b32 m0, s33
	ds_read_b128 v[204:207], v160
	ds_read_b128 v[208:211], v160 offset:1024
	ds_read_b128 v[212:215], v160 offset:2048
	ds_read_b128 v[216:219], v160 offset:3072
	global_load_lds_dwordx4 v[220:221], off
	v_lshl_add_u64 v[222:223], s[50:51], 0, v[128:129]
	s_add_i32 m0, s33, 0x2000
	s_nop 0
	global_load_lds_dwordx4 v[222:223], off
	s_waitcnt lgkmcnt(0)
	s_barrier
	s_waitcnt lgkmcnt(0)
	v_mfma_f32_16x16x32_bf16 v[116:119], v[204:207], v[170:173], v[116:119]
	v_mfma_f32_16x16x32_bf16 v[112:115], v[212:215], v[170:173], v[112:115]
	v_mfma_f32_16x16x32_bf16 v[100:103], v[204:207], v[178:181], v[100:103]
	v_mfma_f32_16x16x32_bf16 v[96:99], v[212:215], v[178:181], v[96:99]
	v_mfma_f32_16x16x32_bf16 v[84:87], v[204:207], v[186:189], v[84:87]
	v_mfma_f32_16x16x32_bf16 v[80:83], v[212:215], v[186:189], v[80:83]
	v_mfma_f32_16x16x32_bf16 v[68:71], v[204:207], v[194:197], v[68:71]
	v_mfma_f32_16x16x32_bf16 v[64:67], v[212:215], v[194:197], v[64:67]
	v_mfma_f32_16x16x32_bf16 v[116:119], v[208:211], v[174:177], v[116:119]
	v_mfma_f32_16x16x32_bf16 v[112:115], v[216:219], v[174:177], v[112:115]
	v_mfma_f32_16x16x32_bf16 v[100:103], v[208:211], v[182:185], v[100:103]
	v_mfma_f32_16x16x32_bf16 v[96:99], v[216:219], v[182:185], v[96:99]
	v_mfma_f32_16x16x32_bf16 v[84:87], v[208:211], v[190:193], v[84:87]
	v_mfma_f32_16x16x32_bf16 v[80:83], v[216:219], v[190:193], v[80:83]
	v_mfma_f32_16x16x32_bf16 v[68:71], v[208:211], v[198:201], v[68:71]
	v_mfma_f32_16x16x32_bf16 v[64:67], v[216:219], v[198:201], v[64:67]
	s_mov_b32 m0, s45
	v_lshl_add_u64 v[224:225], s[48:49], 0, v[138:139]
	s_barrier
	ds_read_b128 v[170:173], v159 offset:16384
	ds_read_b128 v[174:177], v159 offset:17408
	ds_read_b128 v[178:181], v159 offset:18432
	ds_read_b128 v[182:185], v159 offset:19456
	ds_read_b128 v[186:189], v159 offset:20480
	ds_read_b128 v[190:193], v159 offset:21504
	ds_read_b128 v[194:197], v159 offset:22528
	ds_read_b128 v[198:201], v159 offset:23552
	global_load_lds_dwordx4 v[224:225], off
	v_lshl_add_u64 v[226:227], s[48:49], 0, v[132:133]
	s_mov_b32 m0, s59
	s_nop 0
	global_load_lds_dwordx4 v[226:227], off
	s_add_i32 s33, s69, s57
	v_lshl_add_u64 v[228:229], s[50:51], 0, v[136:137]
	s_mov_b32 m0, s33
	v_lshl_add_u64 v[230:231], s[50:51], 0, v[130:131]
	global_load_lds_dwordx4 v[228:229], off
	s_add_i32 m0, s33, 0x2000
	s_nop 0
	global_load_lds_dwordx4 v[230:231], off
	s_waitcnt vmcnt(6)
	s_barrier
; #define PG8_STAGE(bufoff, gbase, voff) do { _Pragma("unroll") for (int _i = 0; _i < 2; ++_i) \
;         __builtin_amdgcn_global_load_lds((const unsigned*)((const char*)(gbase) + (voff)[_i]), (LAS unsigned*)(lds + (bufoff) + ldsw + _i * 8192), 16, 0, 0); } while (0)
; #define PG8_LDA(dst, b, h) do { _Pragma("unroll") for (int m = 0; m < 4; ++m) _Pragma("unroll") for (int k = 0; k < 2; ++k) dst[m][k] = *(const LAS bf16x8*)(lds + PG8_SA(b, h) + aoff + m * 2048 + k * 1024); } while (0)
; #define PG8_LDB(dst, b, h) do { _Pragma("unroll") for (int n = 0; n < 2; ++n) _Pragma("unroll") for (int k = 0; k < 2; ++k) dst[n][k] = *(const LAS bf16x8*)(lds + PG8_SB(b, h) + boff + n * 2048 + k * 1024); } while (0)
; #define PG8_MMA(ai, bj, At, Bt) do { __builtin_amdgcn_s_setprio(1); _Pragma("unroll") for (int m = 0; m < 4; ++m) _Pragma("unroll") for (int n = 0; n < 2; ++n) _Pragma("unroll") for (int k = 0; k < 2; ++k) \
;         acc[ai][bj][m][n] = __builtin_amdgcn_mfma_f32_16x16x32_bf16(Bt[n][k], At[m][k], acc[ai][bj][m][n], 0, 0, 0); __builtin_amdgcn_s_setprio(0); } while (0)
; #define PG8_WAIT_V(n) asm volatile("s_waitcnt vmcnt(" #n ")" ::: "memory")
; #define PG8_WAIT_L(n) asm volatile("s_waitcnt lgkmcnt(" #n ")" ::: "memory")
; #define PG8_BAR __builtin_amdgcn_s_barrier()
; #define PG8_SCHED __builtin_amdgcn_sched_barrier(0)
; template <class Epi>
; __device__ __forceinline__ void gemm_phase(LAS unsigned char* lds, const Gemm g, const StaticOrder& S, const Epi& E) {
;     ...
;             PG8_BAR; PG8_WAIT_L(0); PG8_MMA(1, 0, At, B0); PG8_BAR; PG8_SCHED;
;             PG8_STAGE(PG8_SB(0, 1), b2, voffB1);
;             PG8_WAIT_V(6); PG8_BAR; PG8_MMA(1, 1, At, B1); PG8_BAR;
;             PG8_LDB(B0, 1, 0); PG8_SCHED; PG8_LDA(At, 1, 0); PG8_STAGE(PG8_SA(0, 1), a2 + hstep, voffA);
;             PG8_WAIT_L(8); PG8_BAR; PG8_WAIT_L(0); PG8_MMA(0, 0, At, B0); PG8_BAR; PG8_SCHED;
;             PG8_LDB(B1, 1, 1); PG8_STAGE(PG8_SB(1, 0), b3, voffB0);
;             PG8_BAR; PG8_WAIT_L(0); PG8_MMA(0, 1, At, B1); PG8_BAR;
;             PG8_LDA(At, 1, 1); PG8_STAGE(PG8_SA(1, 0), a3, voffA);
;             PG8_BAR; PG8_WAIT_L(0); PG8_MMA(1, 0, At, B0); PG8_BAR; PG8_SCHED;
	s_waitcnt lgkmcnt(0)
	v_mfma_f32_16x16x32_bf16 v[60:63], v[146:149], v[170:173], v[60:63]
	v_mfma_f32_16x16x32_bf16 v[56:59], v[162:165], v[170:173], v[56:59]
	v_mfma_f32_16x16x32_bf16 v[44:47], v[146:149], v[178:181], v[44:47]
	v_mfma_f32_16x16x32_bf16 v[40:43], v[162:165], v[178:181], v[40:43]
	v_mfma_f32_16x16x32_bf16 v[28:31], v[146:149], v[186:189], v[28:31]
	v_mfma_f32_16x16x32_bf16 v[24:27], v[162:165], v[186:189], v[24:27]
	v_mfma_f32_16x16x32_bf16 v[12:15], v[146:149], v[194:197], v[12:15]
	v_mfma_f32_16x16x32_bf16 v[8:11], v[162:165], v[194:197], v[8:11]
	v_mfma_f32_16x16x32_bf16 v[60:63], v[150:153], v[174:177], v[60:63]
	v_mfma_f32_16x16x32_bf16 v[56:59], v[166:169], v[174:177], v[56:59]
	v_mfma_f32_16x16x32_bf16 v[44:47], v[150:153], v[182:185], v[44:47]
	v_mfma_f32_16x16x32_bf16 v[40:43], v[166:169], v[182:185], v[40:43]
	v_mfma_f32_16x16x32_bf16 v[28:31], v[150:153], v[190:193], v[28:31]
	v_mfma_f32_16x16x32_bf16 v[24:27], v[166:169], v[190:193], v[24:27]
	v_mfma_f32_16x16x32_bf16 v[12:15], v[150:153], v[198:201], v[12:15]
	v_mfma_f32_16x16x32_bf16 v[8:11], v[166:169], v[198:201], v[8:11]
	v_mfma_f32_16x16x32_bf16 v[52:55], v[204:207], v[170:173], v[52:55]
	v_mfma_f32_16x16x32_bf16 v[48:51], v[212:215], v[170:173], v[48:51]
	v_mfma_f32_16x16x32_bf16 v[36:39], v[204:207], v[178:181], v[36:39]
	v_mfma_f32_16x16x32_bf16 v[32:35], v[212:215], v[178:181], v[32:35]
	v_mfma_f32_16x16x32_bf16 v[20:23], v[204:207], v[186:189], v[20:23]
	v_mfma_f32_16x16x32_bf16 v[16:19], v[212:215], v[186:189], v[16:19]
	v_mfma_f32_16x16x32_bf16 v[4:7], v[204:207], v[194:197], v[4:7]
	v_mfma_f32_16x16x32_bf16 v[0:3], v[212:215], v[194:197], v[0:3]
	v_mfma_f32_16x16x32_bf16 v[52:55], v[208:211], v[174:177], v[52:55]
	v_mfma_f32_16x16x32_bf16 v[48:51], v[216:219], v[174:177], v[48:51]
	v_mfma_f32_16x16x32_bf16 v[36:39], v[208:211], v[182:185], v[36:39]
	v_mfma_f32_16x16x32_bf16 v[32:35], v[216:219], v[182:185], v[32:35]
	v_mfma_f32_16x16x32_bf16 v[20:23], v[208:211], v[190:193], v[20:23]
	v_mfma_f32_16x16x32_bf16 v[16:19], v[216:219], v[190:193], v[16:19]
	v_mfma_f32_16x16x32_bf16 v[4:7], v[208:211], v[198:201], v[4:7]
	v_mfma_f32_16x16x32_bf16 v[0:3], v[216:219], v[198:201], v[0:3]
	s_add_i32 s33, 0, 0x18000
	v_add_u32_e32 v166, s33, v155
	s_barrier
	ds_read_b128 v[146:149], v166
	ds_read_b128 v[150:153], v166 offset:1024
	ds_read_b128 v[162:165], v166 offset:2048
	ds_read_b128 v[166:169], v166 offset:3072
	s_add_u32 s48, s48, 0x80000
	s_addc_u32 s49, s49, 0
	s_mov_b32 m0, s60
	v_lshl_add_u64 v[204:205], s[48:49], 0, v[138:139]
	ds_read_b128 v[170:173], v159 offset:32768
	ds_read_b128 v[174:177], v159 offset:33792
	ds_read_b128 v[178:181], v159 offset:34816
	ds_read_b128 v[182:185], v159 offset:35840
	ds_read_b128 v[186:189], v159 offset:36864
	ds_read_b128 v[190:193], v159 offset:37888
	ds_read_b128 v[194:197], v159 offset:38912
	ds_read_b128 v[198:201], v159 offset:39936
	global_load_lds_dwordx4 v[204:205], off
	v_lshl_add_u64 v[204:205], s[48:49], 0, v[132:133]
	s_mov_b32 m0, s61
	s_nop 0
	global_load_lds_dwordx4 v[204:205], off
	s_waitcnt lgkmcnt(8)
	s_barrier
	s_waitcnt lgkmcnt(0)
	v_mfma_f32_16x16x32_bf16 v[124:127], v[146:149], v[170:173], v[124:127]
	v_mfma_f32_16x16x32_bf16 v[120:123], v[162:165], v[170:173], v[120:123]
	v_mfma_f32_16x16x32_bf16 v[108:111], v[146:149], v[178:181], v[108:111]
	v_mfma_f32_16x16x32_bf16 v[104:107], v[162:165], v[178:181], v[104:107]
	v_mfma_f32_16x16x32_bf16 v[92:95], v[146:149], v[186:189], v[92:95]
	v_mfma_f32_16x16x32_bf16 v[88:91], v[162:165], v[186:189], v[88:91]
	v_mfma_f32_16x16x32_bf16 v[76:79], v[146:149], v[194:197], v[76:79]
	v_mfma_f32_16x16x32_bf16 v[72:75], v[162:165], v[194:197], v[72:75]
	v_mfma_f32_16x16x32_bf16 v[124:127], v[150:153], v[174:177], v[124:127]
	v_mfma_f32_16x16x32_bf16 v[120:123], v[166:169], v[174:177], v[120:123]
	v_mfma_f32_16x16x32_bf16 v[108:111], v[150:153], v[182:185], v[108:111]
	v_mfma_f32_16x16x32_bf16 v[104:107], v[166:169], v[182:185], v[104:107]
	v_mfma_f32_16x16x32_bf16 v[92:95], v[150:153], v[190:193], v[92:95]
	v_mfma_f32_16x16x32_bf16 v[88:91], v[166:169], v[190:193], v[88:91]
	v_mfma_f32_16x16x32_bf16 v[76:79], v[150:153], v[198:201], v[76:79]
	v_mfma_f32_16x16x32_bf16 v[72:75], v[166:169], v[198:201], v[72:75]
	s_barrier
	s_add_i32 s48, 0, 0x1c000
	s_add_i32 s33, s33, s57
	v_add_u32_e32 v216, s48, v155
	v_lshl_add_u64 v[220:221], v[220:221], 0, s[16:17]
	s_mov_b32 m0, s33
	ds_read_b128 v[204:207], v216
	ds_read_b128 v[208:211], v216 offset:1024
	ds_read_b128 v[212:215], v216 offset:2048
	ds_read_b128 v[216:219], v216 offset:3072
	global_load_lds_dwordx4 v[220:221], off
	v_lshl_add_u64 v[220:221], v[222:223], 0, s[16:17]
	s_add_i32 m0, s33, 0x2000
	s_nop 0
	global_load_lds_dwordx4 v[220:221], off
	s_waitcnt lgkmcnt(0)
	s_barrier
	s_waitcnt lgkmcnt(0)
	v_mfma_f32_16x16x32_bf16 v[116:119], v[204:207], v[170:173], v[116:119]
	v_mfma_f32_16x16x32_bf16 v[112:115], v[212:215], v[170:173], v[112:115]
	v_mfma_f32_16x16x32_bf16 v[100:103], v[204:207], v[178:181], v[100:103]
	v_mfma_f32_16x16x32_bf16 v[96:99], v[212:215], v[178:181], v[96:99]
	v_mfma_f32_16x16x32_bf16 v[84:87], v[204:207], v[186:189], v[84:87]
	v_mfma_f32_16x16x32_bf16 v[80:83], v[212:215], v[186:189], v[80:83]
	v_mfma_f32_16x16x32_bf16 v[68:71], v[204:207], v[194:197], v[68:71]
	v_mfma_f32_16x16x32_bf16 v[64:67], v[212:215], v[194:197], v[64:67]
	v_mfma_f32_16x16x32_bf16 v[116:119], v[208:211], v[174:177], v[116:119]
	v_mfma_f32_16x16x32_bf16 v[112:115], v[216:219], v[174:177], v[112:115]
	v_mfma_f32_16x16x32_bf16 v[100:103], v[208:211], v[182:185], v[100:103]
	v_mfma_f32_16x16x32_bf16 v[96:99], v[216:219], v[182:185], v[96:99]
	v_mfma_f32_16x16x32_bf16 v[84:87], v[208:211], v[190:193], v[84:87]
	v_mfma_f32_16x16x32_bf16 v[80:83], v[216:219], v[190:193], v[80:83]
	v_mfma_f32_16x16x32_bf16 v[68:71], v[208:211], v[198:201], v[68:71]
	v_mfma_f32_16x16x32_bf16 v[64:67], v[216:219], v[198:201], v[64:67]
	s_mov_b32 m0, s63
	v_lshl_add_u64 v[220:221], v[224:225], 0, s[16:17]
	s_barrier
; #define PG8_STAGE(bufoff, gbase, voff) do { _Pragma("unroll") for (int _i = 0; _i < 2; ++_i) \
;         __builtin_amdgcn_global_load_lds((const unsigned*)((const char*)(gbase) + (voff)[_i]), (LAS unsigned*)(lds + (bufoff) + ldsw + _i * 8192), 16, 0, 0); } while (0)
; #define PG8_LDA(dst, b, h) do { _Pragma("unroll") for (int m = 0; m < 4; ++m) _Pragma("unroll") for (int k = 0; k < 2; ++k) dst[m][k] = *(const LAS bf16x8*)(lds + PG8_SA(b, h) + aoff + m * 2048 + k * 1024); } while (0)
; #define PG8_MMA(ai, bj, At, Bt) do { __builtin_amdgcn_s_setprio(1); _Pragma("unroll") for (int m = 0; m < 4; ++m) _Pragma("unroll") for (int n = 0; n < 2; ++n) _Pragma("unroll") for (int k = 0; k < 2; ++k) \
;         acc[ai][bj][m][n] = __builtin_amdgcn_mfma_f32_16x16x32_bf16(Bt[n][k], At[m][k], acc[ai][bj][m][n], 0, 0, 0); __builtin_amdgcn_s_setprio(0); } while (0)
; #define PG8_WAIT_V(n) asm volatile("s_waitcnt vmcnt(" #n ")" ::: "memory")
; #define PG8_WAIT_L(n) asm volatile("s_waitcnt lgkmcnt(" #n ")" ::: "memory")
; #define PG8_BAR __builtin_amdgcn_s_barrier()
; #define PG8_SCHED __builtin_amdgcn_sched_barrier(0)
;     __device__ __forceinline__ void operator()(const f32x4 (&acc)[2][2][4][2], const Unit& u, int wr, int wc, int fr, int fq) const {
;         const int row0 = u.pm * BM + wr * 64 + fr; const int col0 = u.pn * BM + wc * 64 + 16 * fq;
; #pragma unroll
;         for (int ai = 0; ai < 2; ++ai)
; #pragma unroll
;             for (int m = 0; m < 4; ++m) { const int row = row0 + ai * HALF + m * 16;
;                 const float rs = ssin ? __builtin_amdgcn_rsqf(ssin[row] * (1.f / D) + EPS) : 1.0f; float sq = 0.f; u32x4 w[2];
; template <class Epi>
; __device__ __forceinline__ void gemm_phase(LAS unsigned char* lds, const Gemm g, const StaticOrder& S, const Epi& E) {
;     ...
;             PG8_LDA(At, 1, 1); PG8_STAGE(PG8_SA(1, 0), a3, voffA);
;             PG8_BAR; PG8_WAIT_L(0); PG8_MMA(1, 0, At, B0); PG8_BAR; PG8_SCHED;
;             PG8_STAGE(PG8_SB(1, 1), b3, voffB1);
;             PG8_WAIT_V(6); PG8_BAR; PG8_MMA(1, 1, At, B1); PG8_BAR;
;         }
	ds_read_b128 v[170:173], v159 offset:49152
	ds_read_b128 v[174:177], v159 offset:50176
	ds_read_b128 v[178:181], v159 offset:51200
	ds_read_b128 v[182:185], v159 offset:52224
	ds_read_b128 v[186:189], v159 offset:53248
	ds_read_b128 v[190:193], v159 offset:54272
	ds_read_b128 v[194:197], v159 offset:55296
	ds_read_b128 v[198:201], v159 offset:56320
	global_load_lds_dwordx4 v[220:221], off
	v_lshl_add_u64 v[220:221], v[226:227], 0, s[16:17]
	s_mov_b32 m0, s64
	s_nop 0
	global_load_lds_dwordx4 v[220:221], off
	s_add_i32 s33, s48, s57
	v_lshl_add_u64 v[250:251], v[228:229], 0, s[16:17]
	s_mov_b32 m0, s33
	s_nop 0
	global_load_lds_dwordx4 v[250:251], off
	v_lshl_add_u64 v[250:251], v[230:231], 0, s[16:17]
	s_add_i32 m0, s33, 0x2000
	s_nop 0
	global_load_lds_dwordx4 v[250:251], off
	s_waitcnt vmcnt(6)
	s_barrier
	s_waitcnt lgkmcnt(0)
	v_mfma_f32_16x16x32_bf16 v[60:63], v[146:149], v[170:173], v[60:63]
	v_mfma_f32_16x16x32_bf16 v[56:59], v[162:165], v[170:173], v[56:59]
	v_mfma_f32_16x16x32_bf16 v[44:47], v[146:149], v[178:181], v[44:47]
	v_mfma_f32_16x16x32_bf16 v[40:43], v[162:165], v[178:181], v[40:43]
	v_mfma_f32_16x16x32_bf16 v[28:31], v[146:149], v[186:189], v[28:31]
	v_mfma_f32_16x16x32_bf16 v[24:27], v[162:165], v[186:189], v[24:27]
	v_mfma_f32_16x16x32_bf16 v[12:15], v[146:149], v[194:197], v[12:15]
	v_mfma_f32_16x16x32_bf16 v[8:11], v[162:165], v[194:197], v[8:11]
	v_mfma_f32_16x16x32_bf16 v[60:63], v[150:153], v[174:177], v[60:63]
	v_mfma_f32_16x16x32_bf16 v[56:59], v[166:169], v[174:177], v[56:59]
	v_mfma_f32_16x16x32_bf16 v[44:47], v[150:153], v[182:185], v[44:47]
	v_mfma_f32_16x16x32_bf16 v[40:43], v[166:169], v[182:185], v[40:43]
	v_mfma_f32_16x16x32_bf16 v[28:31], v[150:153], v[190:193], v[28:31]
	v_mfma_f32_16x16x32_bf16 v[24:27], v[166:169], v[190:193], v[24:27]
	v_mfma_f32_16x16x32_bf16 v[12:15], v[150:153], v[198:201], v[12:15]
	v_mfma_f32_16x16x32_bf16 v[8:11], v[166:169], v[198:201], v[8:11]
	v_mfma_f32_16x16x32_bf16 v[52:55], v[204:207], v[170:173], v[52:55]
	v_mfma_f32_16x16x32_bf16 v[48:51], v[212:215], v[170:173], v[48:51]
	v_mfma_f32_16x16x32_bf16 v[36:39], v[204:207], v[178:181], v[36:39]
	v_mfma_f32_16x16x32_bf16 v[32:35], v[212:215], v[178:181], v[32:35]
	v_mfma_f32_16x16x32_bf16 v[20:23], v[204:207], v[186:189], v[20:23]
	v_mfma_f32_16x16x32_bf16 v[16:19], v[212:215], v[186:189], v[16:19]
	v_mfma_f32_16x16x32_bf16 v[4:7], v[204:207], v[194:197], v[4:7]
	v_mfma_f32_16x16x32_bf16 v[0:3], v[212:215], v[194:197], v[0:3]
	v_mfma_f32_16x16x32_bf16 v[52:55], v[208:211], v[174:177], v[52:55]
	v_mfma_f32_16x16x32_bf16 v[48:51], v[216:219], v[174:177], v[48:51]
	v_mfma_f32_16x16x32_bf16 v[36:39], v[208:211], v[182:185], v[36:39]
	v_mfma_f32_16x16x32_bf16 v[32:35], v[216:219], v[182:185], v[32:35]
	v_mfma_f32_16x16x32_bf16 v[20:23], v[208:211], v[190:193], v[20:23]
	v_mfma_f32_16x16x32_bf16 v[16:19], v[216:219], v[190:193], v[16:19]
	v_mfma_f32_16x16x32_bf16 v[4:7], v[208:211], v[198:201], v[4:7]
	v_mfma_f32_16x16x32_bf16 v[0:3], v[216:219], v[198:201], v[0:3]
	s_add_i32 s77, s77, 2
	s_add_u32 s46, s46, 0x100
	s_addc_u32 s47, s47, 0
	s_add_u32 s74, s74, 0x100
	s_addc_u32 s75, s75, 0
	s_cmp_gt_u32 s77, 29
	s_barrier
	s_cbranch_scc0 .LBB0_962
	s_lshl_b32 s19, s44, 8
	s_add_i32 s19, s19, s65
	v_or_b32_e32 v152, s19, v154
	v_ashrrev_i32_e32 v153, 31, v152
	v_lshl_add_u64 v[150:151], v[152:153], 2, s[10:11]
	global_load_dword v153, v[150:151], off
	v_or_b32_e32 v180, 16, v152
	v_ashrrev_i32_e32 v181, 31, v180
	v_lshl_add_u64 v[182:183], v[180:181], 2, s[10:11]
	global_load_dword v179, v[182:183], off
	v_or_b32_e32 v180, 32, v152
	v_ashrrev_i32_e32 v181, 31, v180
	v_lshl_add_u64 v[182:183], v[180:181], 2, s[10:11]
	global_load_dword v184, v[182:183], off
	v_or_b32_e32 v180, 48, v152
	v_ashrrev_i32_e32 v181, 31, v180
	v_lshl_add_u64 v[182:183], v[180:181], 2, s[10:11]
	global_load_dword v185, v[182:183], off
	global_load_dword v186, v[150:151], off offset:512
	global_load_dword v187, v[150:151], off offset:576
	global_load_dword v188, v[150:151], off offset:640
	global_load_dword v189, v[150:151], off offset:704
	v_lshl_or_b32 v148, s71, 8, v157
	v_mov_b32_e32 v169, 0
	v_mov_b64_e32 v[146:147], s[8:9]
	v_ashrrev_i32_e32 v149, 31, v148
	v_or_b32_e32 v164, s19, v156
	v_lshlrev_b64 v[148:149], 1, v[148:149]
	v_mad_i64_i32 v[162:163], s[46:47], v164, s70, v[146:147]
	v_or_b32_e32 v165, 8, v164
	v_or_b32_e32 v164, 16, v152
	v_lshl_add_u64 v[162:163], v[162:163], 0, v[148:149]
	v_mad_i64_i32 v[166:167], s[46:47], v165, s70, v[146:147]
	v_ashrrev_i32_e32 v165, 31, v164
	v_lshl_add_u64 v[166:167], v[166:167], 0, v[148:149]
	v_lshl_add_u64 v[170:171], v[164:165], 2, s[10:11]
	s_and_b64 vcc, exec, s[40:41]
	s_mov_b32 s71, s18
	s_mov_b32 s44, s36
	s_mov_b64 s[48:49], s[42:43]
	s_waitcnt vmcnt(7)
; __device__ __forceinline__ unsigned cvt_pk_bf16(float lo, float hi) { unsigned r; asm volatile("v_cvt_pk_bf16_f32 %0, %1, %2" : "=v"(r) : "v"(lo), "v"(hi)); return r; }
; __device__ __forceinline__ unsigned dpp_ror8(unsigned x) { return (unsigned)__builtin_amdgcn_update_dpp(0, (int)x, 0x128, 0xf, 0xf, false); }
; __device__ __forceinline__ void store_pair_lines(bf16_t* O, int ldc, int row, int fr, int col0, u32x4 wA, u32x4 wB) {
;     const u32x4 sA = {dpp_ror8(wA.x), dpp_ror8(wA.y), dpp_ror8(wA.z), dpp_ror8(wA.w)}, sB = {dpp_ror8(wB.x), dpp_ror8(wB.y), dpp_ror8(wB.z), dpp_ror8(wB.w)};
;     const bool lo = fr < 8;
;     const u32x4 o1 = lo ? wA : sB, o2 = lo ? sA : wB;
;     const int r1 = row - fr + (fr & 7), cb = col0 + (lo ? 0 : 8);
;     *(u32x4*)(O + (size_t)r1 * ldc + cb) = o1;
;     *(u32x4*)(O + (size_t)(r1 + 8) * ldc + cb) = o2;
; }
;     __device__ __forceinline__ void operator()(const f32x4 (&acc)[2][2][4][2], const Unit& u, int wr, int wc, int fr, int fq) const {
;         const int row0 = u.pm * BM + wr * 64 + fr; const int col0 = u.pn * BM + wc * 64 + 16 * fq;
; #pragma unroll
;         for (int ai = 0; ai < 2; ++ai)
; #pragma unroll
;             for (int m = 0; m < 4; ++m) { const int row = row0 + ai * HALF + m * 16;
;                 const float rs = ssin ? __builtin_amdgcn_rsqf(ssin[row] * (1.f / D) + EPS) : 1.0f; float sq = 0.f; u32x4 w[2];
; #pragma unroll
;                 for (int bj = 0; bj < 2; ++bj) { f32x4 v0 = acc[ai][bj][m][0] * rs, v1 = acc[ai][bj][m][1] * rs;
;                     if (ACT == 1) {
; #pragma unroll
;                         for (int j = 0; j < 4; ++j) { const float a = fmaxf(v0[j], 0.f), b = fmaxf(v1[j], 0.f); v0[j] = a * a; v1[j] = b * b; } }
;                     sq += (v0[0] * v0[0] + v0[1] * v0[1]) + (v0[2] * v0[2] + v0[3] * v0[3]) + (v1[0] * v1[0] + v1[1] * v1[1]) + (v1[2] * v1[2] + v1[3] * v1[3]);
;                     w[bj].x = cvt_pk_bf16(v0[0], v0[1]); w[bj].y = cvt_pk_bf16(v0[2], v0[3]); w[bj].z = cvt_pk_bf16(v1[0], v1[1]); w[bj].w = cvt_pk_bf16(v1[2], v1[3]); }
;                 store_pair_lines(O, ldc, row, fr, col0, w[0], w[1]);
;                 if (ssout) { sq += __shfl_xor(sq, 16); sq += __shfl_xor(sq, 32); if (fq == 0) unsafeAtomicAdd(ssout + row, sq); } }
	v_fmamk_f32 v153, v153, 0x3a000000, v161
	v_rsq_f32_e32 v168, v153
	v_mov_b32_e32 v153, 0
	v_pk_mul_f32 v[124:125], v[124:125], v[168:169] op_sel_hi:[1,0]
	v_pk_mul_f32 v[120:121], v[120:121], v[168:169] op_sel_hi:[1,0]
	v_pk_mul_f32 v[118:119], v[118:119], v[168:169] op_sel_hi:[1,0]
	v_pk_mul_f32 v[116:117], v[116:117], v[168:169] op_sel_hi:[1,0]
	v_pk_mul_f32 v[126:127], v[126:127], v[168:169] op_sel_hi:[1,0]
	v_pk_mul_f32 v[122:123], v[122:123], v[168:169] op_sel_hi:[1,0]
	v_pk_mul_f32 v[114:115], v[114:115], v[168:169] op_sel_hi:[1,0]
	v_pk_mul_f32 v[112:113], v[112:113], v[168:169] op_sel_hi:[1,0]
	v_cvt_pk_bf16_f32 v124, v124, v125
	v_cvt_pk_bf16_f32 v125, v126, v127
	v_cvt_pk_bf16_f32 v120, v120, v121
	v_cvt_pk_bf16_f32 v121, v122, v123
	v_cvt_pk_bf16_f32 v116, v116, v117
	v_cvt_pk_bf16_f32 v117, v118, v119
	s_nop 0
	v_cvt_pk_bf16_f32 v118, v112, v113
	v_cvt_pk_bf16_f32 v119, v114, v115
	s_nop 0
	v_mov_b32_dpp v169, v124 row_ror:8 row_mask:0xf bank_mask:0xf
	v_mov_b32_dpp v172, v125 row_ror:8 row_mask:0xf bank_mask:0xf
	v_mov_b32_dpp v175, v116 row_ror:8 row_mask:0xf bank_mask:0xf
	v_mov_b32_dpp v176, v117 row_ror:8 row_mask:0xf bank_mask:0xf
	v_mov_b32_dpp v177, v118 row_ror:8 row_mask:0xf bank_mask:0xf
	v_mov_b32_dpp v178, v119 row_ror:8 row_mask:0xf bank_mask:0xf
	v_mov_b32_dpp v173, v120 row_ror:8 row_mask:0xf bank_mask:0xf
	v_mov_b32_dpp v174, v121 row_ror:8 row_mask:0xf bank_mask:0xf
	v_cndmask_b32_e64 v112, v175, v124, s[6:7]
	v_cndmask_b32_e64 v113, v176, v125, s[6:7]
	v_cndmask_b32_e64 v114, v177, v120, s[6:7]
	v_cndmask_b32_e64 v115, v178, v121, s[6:7]
	v_cndmask_b32_e64 v116, v116, v169, s[6:7]
	v_cndmask_b32_e64 v117, v117, v172, s[6:7]
	v_cndmask_b32_e64 v118, v118, v173, s[6:7]
	v_cndmask_b32_e64 v119, v119, v174, s[6:7]
	global_store_dwordx4 v[162:163], v[112:115], off
	global_store_dwordx4 v[166:167], v[116:119], off
	s_waitcnt vmcnt(8)
	s_nop 0
	v_mov_b32_e32 v118, v179
	s_nop 1
	v_or_b32_e32 v112, 32, v152
	v_mov_b32_e32 v119, 0
	v_sub_u32_e32 v114, v164, v154
	v_ashrrev_i32_e32 v113, 31, v112
	v_add_u32_e32 v120, v114, v156
	v_lshl_add_u64 v[114:115], v[112:113], 2, s[10:11]
	v_mad_i64_i32 v[116:117], s[46:47], v120, s70, v[146:147]
	v_add_u32_e32 v113, 8, v120
	v_lshl_add_u64 v[116:117], v[116:117], 0, v[148:149]
	v_mad_i64_i32 v[120:121], s[46:47], v113, s70, v[146:147]
	v_lshl_add_u64 v[120:121], v[120:121], 0, v[148:149]
	v_fmamk_f32 v118, v118, 0x3a000000, v161
	v_rsq_f32_e32 v118, v118
	s_nop 0
	v_pk_mul_f32 v[108:109], v[108:109], v[118:119] op_sel_hi:[1,0]
	v_pk_mul_f32 v[104:105], v[104:105], v[118:119] op_sel_hi:[1,0]
	v_pk_mul_f32 v[102:103], v[102:103], v[118:119] op_sel_hi:[1,0]
	v_pk_mul_f32 v[100:101], v[100:101], v[118:119] op_sel_hi:[1,0]
	v_pk_mul_f32 v[110:111], v[110:111], v[118:119] op_sel_hi:[1,0]
	v_pk_mul_f32 v[106:107], v[106:107], v[118:119] op_sel_hi:[1,0]
	v_pk_mul_f32 v[98:99], v[98:99], v[118:119] op_sel_hi:[1,0]
	v_pk_mul_f32 v[96:97], v[96:97], v[118:119] op_sel_hi:[1,0]
	v_cvt_pk_bf16_f32 v108, v108, v109
	v_cvt_pk_bf16_f32 v109, v110, v111
	v_cvt_pk_bf16_f32 v104, v104, v105
	v_cvt_pk_bf16_f32 v105, v106, v107
	v_cvt_pk_bf16_f32 v100, v100, v101
	v_cvt_pk_bf16_f32 v101, v102, v103
	s_nop 0
	v_cvt_pk_bf16_f32 v102, v96, v97
	v_cvt_pk_bf16_f32 v103, v98, v99
	s_nop 0
	v_mov_b32_dpp v119, v108 row_ror:8 row_mask:0xf bank_mask:0xf
	v_mov_b32_dpp v122, v109 row_ror:8 row_mask:0xf bank_mask:0xf
	v_mov_b32_dpp v125, v100 row_ror:8 row_mask:0xf bank_mask:0xf
	v_mov_b32_dpp v126, v101 row_ror:8 row_mask:0xf bank_mask:0xf
	v_mov_b32_dpp v127, v102 row_ror:8 row_mask:0xf bank_mask:0xf
	v_mov_b32_dpp v153, v103 row_ror:8 row_mask:0xf bank_mask:0xf
	v_mov_b32_dpp v123, v104 row_ror:8 row_mask:0xf bank_mask:0xf
	v_mov_b32_dpp v124, v105 row_ror:8 row_mask:0xf bank_mask:0xf
	v_cndmask_b32_e64 v96, v125, v108, s[6:7]
	v_cndmask_b32_e64 v97, v126, v109, s[6:7]
	v_cndmask_b32_e64 v98, v127, v104, s[6:7]
	v_cndmask_b32_e64 v99, v153, v105, s[6:7]
	v_cndmask_b32_e64 v100, v100, v119, s[6:7]
	v_cndmask_b32_e64 v101, v101, v122, s[6:7]
	v_cndmask_b32_e64 v102, v102, v123, s[6:7]
	v_cndmask_b32_e64 v103, v103, v124, s[6:7]
	global_store_dwordx4 v[116:117], v[96:99], off
	global_store_dwordx4 v[120:121], v[100:103], off
	s_waitcnt vmcnt(9)
	s_nop 0
	v_mov_b32_e32 v102, v184
	s_nop 1
	v_or_b32_e32 v96, 48, v152
	v_mov_b32_e32 v103, 0
	v_sub_u32_e32 v98, v112, v154
	v_ashrrev_i32_e32 v97, 31, v96
	v_add_u32_e32 v104, v98, v156
	v_lshl_add_u64 v[98:99], v[96:97], 2, s[10:11]
	v_mad_i64_i32 v[100:101], s[46:47], v104, s70, v[146:147]
	v_add_u32_e32 v97, 8, v104
	v_lshl_add_u64 v[100:101], v[100:101], 0, v[148:149]
	v_mad_i64_i32 v[104:105], s[46:47], v97, s70, v[146:147]
	v_lshl_add_u64 v[104:105], v[104:105], 0, v[148:149]
	v_fmamk_f32 v102, v102, 0x3a000000, v161
	v_rsq_f32_e32 v102, v102
	s_nop 0
	v_pk_mul_f32 v[92:93], v[92:93], v[102:103] op_sel_hi:[1,0]
	v_pk_mul_f32 v[88:89], v[88:89], v[102:103] op_sel_hi:[1,0]
	v_pk_mul_f32 v[86:87], v[86:87], v[102:103] op_sel_hi:[1,0]
	v_pk_mul_f32 v[84:85], v[84:85], v[102:103] op_sel_hi:[1,0]
	v_pk_mul_f32 v[94:95], v[94:95], v[102:103] op_sel_hi:[1,0]
	v_pk_mul_f32 v[90:91], v[90:91], v[102:103] op_sel_hi:[1,0]
	v_pk_mul_f32 v[82:83], v[82:83], v[102:103] op_sel_hi:[1,0]
	v_pk_mul_f32 v[80:81], v[80:81], v[102:103] op_sel_hi:[1,0]
	v_cvt_pk_bf16_f32 v92, v92, v93
	v_cvt_pk_bf16_f32 v93, v94, v95
	v_cvt_pk_bf16_f32 v88, v88, v89
	v_cvt_pk_bf16_f32 v89, v90, v91
	v_cvt_pk_bf16_f32 v84, v84, v85
	v_cvt_pk_bf16_f32 v85, v86, v87
	s_nop 0
	v_cvt_pk_bf16_f32 v86, v80, v81
	v_cvt_pk_bf16_f32 v87, v82, v83
	s_nop 0
	v_mov_b32_dpp v103, v92 row_ror:8 row_mask:0xf bank_mask:0xf
	v_mov_b32_dpp v106, v93 row_ror:8 row_mask:0xf bank_mask:0xf
	v_mov_b32_dpp v109, v84 row_ror:8 row_mask:0xf bank_mask:0xf
	v_mov_b32_dpp v110, v85 row_ror:8 row_mask:0xf bank_mask:0xf
	v_mov_b32_dpp v111, v86 row_ror:8 row_mask:0xf bank_mask:0xf
	v_mov_b32_dpp v113, v87 row_ror:8 row_mask:0xf bank_mask:0xf
	v_mov_b32_dpp v107, v88 row_ror:8 row_mask:0xf bank_mask:0xf
	v_mov_b32_dpp v108, v89 row_ror:8 row_mask:0xf bank_mask:0xf
	v_cndmask_b32_e64 v80, v109, v92, s[6:7]
	v_cndmask_b32_e64 v81, v110, v93, s[6:7]
	v_cndmask_b32_e64 v82, v111, v88, s[6:7]
	v_cndmask_b32_e64 v83, v113, v89, s[6:7]
	v_cndmask_b32_e64 v84, v84, v103, s[6:7]
	v_cndmask_b32_e64 v85, v85, v106, s[6:7]
	v_cndmask_b32_e64 v86, v86, v107, s[6:7]
	v_cndmask_b32_e64 v87, v87, v108, s[6:7]
	global_store_dwordx4 v[100:101], v[80:83], off
	global_store_dwordx4 v[104:105], v[84:87], off
	s_waitcnt vmcnt(10)
; __device__ __forceinline__ unsigned cvt_pk_bf16(float lo, float hi) { unsigned r; asm volatile("v_cvt_pk_bf16_f32 %0, %1, %2" : "=v"(r) : "v"(lo), "v"(hi)); return r; }
;     __device__ __forceinline__ void operator()(const f32x4 (&acc)[2][2][4][2], const Unit& u, int wr, int wc, int fr, int fq) const {
;     ...
;             for (int m = 0; m < 4; ++m) { const int row = row0 + ai * HALF + m * 16;
;                 const float rs = ssin ? __builtin_amdgcn_rsqf(ssin[row] * (1.f / D) + EPS) : 1.0f; float sq = 0.f; u32x4 w[2];
; #pragma unroll
;                 for (int bj = 0; bj < 2; ++bj) { f32x4 v0 = acc[ai][bj][m][0] * rs, v1 = acc[ai][bj][m][1] * rs;
;                     if (ACT == 1) {
; #pragma unroll
;                         for (int j = 0; j < 4; ++j) { const float a = fmaxf(v0[j], 0.f), b = fmaxf(v1[j], 0.f); v0[j] = a * a; v1[j] = b * b; } }
;                     sq += (v0[0] * v0[0] + v0[1] * v0[1]) + (v0[2] * v0[2] + v0[3] * v0[3]) + (v1[0] * v1[0] + v1[1] * v1[1]) + (v1[2] * v1[2] + v1[3] * v1[3]);
;                     w[bj].x = cvt_pk_bf16(v0[0], v0[1]); w[bj].y = cvt_pk_bf16(v0[2], v0[3]); w[bj].z = cvt_pk_bf16(v1[0], v1[1]); w[bj].w = cvt_pk_bf16(v1[2], v1[3]); }
;                 store_pair_lines(O, ldc, row, fr, col0, w[0], w[1]);
	s_nop 0
	v_mov_b32_e32 v82, v185
	s_nop 1
	v_mov_b32_e32 v83, 0
	v_sub_u32_e32 v80, v96, v154
	v_add_u32_e32 v84, v80, v156
	v_mad_i64_i32 v[80:81], s[46:47], v84, s70, v[146:147]
	v_add_u32_e32 v84, 8, v84
	v_lshl_add_u64 v[80:81], v[80:81], 0, v[148:149]
	v_mad_i64_i32 v[84:85], s[46:47], v84, s70, v[146:147]
	v_lshl_add_u64 v[84:85], v[84:85], 0, v[148:149]
	v_fmamk_f32 v82, v82, 0x3a000000, v161
	v_rsq_f32_e32 v82, v82
	s_nop 0
	v_pk_mul_f32 v[76:77], v[76:77], v[82:83] op_sel_hi:[1,0]
	v_pk_mul_f32 v[72:73], v[72:73], v[82:83] op_sel_hi:[1,0]
	v_pk_mul_f32 v[70:71], v[70:71], v[82:83] op_sel_hi:[1,0]
	v_pk_mul_f32 v[68:69], v[68:69], v[82:83] op_sel_hi:[1,0]
	v_pk_mul_f32 v[78:79], v[78:79], v[82:83] op_sel_hi:[1,0]
	v_pk_mul_f32 v[74:75], v[74:75], v[82:83] op_sel_hi:[1,0]
	v_pk_mul_f32 v[66:67], v[66:67], v[82:83] op_sel_hi:[1,0]
	v_pk_mul_f32 v[64:65], v[64:65], v[82:83] op_sel_hi:[1,0]
	v_cvt_pk_bf16_f32 v76, v76, v77
	v_cvt_pk_bf16_f32 v77, v78, v79
	v_cvt_pk_bf16_f32 v72, v72, v73
	v_cvt_pk_bf16_f32 v73, v74, v75
	v_cvt_pk_bf16_f32 v68, v68, v69
	v_cvt_pk_bf16_f32 v69, v70, v71
	s_nop 0
	v_cvt_pk_bf16_f32 v70, v64, v65
	v_cvt_pk_bf16_f32 v71, v66, v67
	s_nop 0
	v_mov_b32_dpp v83, v76 row_ror:8 row_mask:0xf bank_mask:0xf
	v_mov_b32_dpp v86, v77 row_ror:8 row_mask:0xf bank_mask:0xf
	v_mov_b32_dpp v89, v68 row_ror:8 row_mask:0xf bank_mask:0xf
	v_mov_b32_dpp v90, v69 row_ror:8 row_mask:0xf bank_mask:0xf
	v_mov_b32_dpp v91, v70 row_ror:8 row_mask:0xf bank_mask:0xf
	v_mov_b32_dpp v92, v71 row_ror:8 row_mask:0xf bank_mask:0xf
	v_mov_b32_dpp v87, v72 row_ror:8 row_mask:0xf bank_mask:0xf
	v_mov_b32_dpp v88, v73 row_ror:8 row_mask:0xf bank_mask:0xf
	v_cndmask_b32_e64 v64, v89, v76, s[6:7]
	v_cndmask_b32_e64 v65, v90, v77, s[6:7]
	v_cndmask_b32_e64 v66, v91, v72, s[6:7]
	v_cndmask_b32_e64 v67, v92, v73, s[6:7]
	v_cndmask_b32_e64 v68, v68, v83, s[6:7]
	v_cndmask_b32_e64 v69, v69, v86, s[6:7]
	v_cndmask_b32_e64 v70, v70, v87, s[6:7]
	v_cndmask_b32_e64 v71, v71, v88, s[6:7]
	global_store_dwordx4 v[80:81], v[64:67], off
	global_store_dwordx4 v[84:85], v[68:71], off
	s_waitcnt vmcnt(11)
	s_nop 0
	v_mov_b32_e32 v66, v186
	s_nop 1
	v_sub_u32_e32 v64, v152, v154
	v_mov_b32_e32 v67, 0
	v_add_u32_e32 v77, v64, v156
	v_add_u32_e32 v64, 0x80, v77
	v_add_u32_e32 v68, 0x88, v77
	v_mad_i64_i32 v[64:65], s[46:47], v64, s70, v[146:147]
	v_mad_i64_i32 v[68:69], s[46:47], v68, s70, v[146:147]
	v_lshl_add_u64 v[64:65], v[64:65], 0, v[148:149]
	v_lshl_add_u64 v[68:69], v[68:69], 0, v[148:149]
	v_fmamk_f32 v66, v66, 0x3a000000, v161
	v_rsq_f32_e32 v66, v66
	s_nop 0
	v_pk_mul_f32 v[60:61], v[60:61], v[66:67] op_sel_hi:[1,0]
	v_pk_mul_f32 v[56:57], v[56:57], v[66:67] op_sel_hi:[1,0]
	v_pk_mul_f32 v[54:55], v[54:55], v[66:67] op_sel_hi:[1,0]
	v_pk_mul_f32 v[52:53], v[52:53], v[66:67] op_sel_hi:[1,0]
	v_pk_mul_f32 v[62:63], v[62:63], v[66:67] op_sel_hi:[1,0]
	v_pk_mul_f32 v[58:59], v[58:59], v[66:67] op_sel_hi:[1,0]
	v_pk_mul_f32 v[50:51], v[50:51], v[66:67] op_sel_hi:[1,0]
	v_pk_mul_f32 v[48:49], v[48:49], v[66:67] op_sel_hi:[1,0]
	v_cvt_pk_bf16_f32 v60, v60, v61
	v_cvt_pk_bf16_f32 v61, v62, v63
	v_cvt_pk_bf16_f32 v56, v56, v57
	v_cvt_pk_bf16_f32 v57, v58, v59
	v_cvt_pk_bf16_f32 v52, v52, v53
	v_cvt_pk_bf16_f32 v53, v54, v55
	s_nop 0
	v_cvt_pk_bf16_f32 v54, v48, v49
	v_cvt_pk_bf16_f32 v55, v50, v51
	s_nop 0
	v_mov_b32_dpp v67, v60 row_ror:8 row_mask:0xf bank_mask:0xf
	v_mov_b32_dpp v70, v61 row_ror:8 row_mask:0xf bank_mask:0xf
	v_mov_b32_dpp v73, v52 row_ror:8 row_mask:0xf bank_mask:0xf
	v_mov_b32_dpp v74, v53 row_ror:8 row_mask:0xf bank_mask:0xf
	v_mov_b32_dpp v75, v54 row_ror:8 row_mask:0xf bank_mask:0xf
	v_mov_b32_dpp v76, v55 row_ror:8 row_mask:0xf bank_mask:0xf
	v_mov_b32_dpp v71, v56 row_ror:8 row_mask:0xf bank_mask:0xf
	v_mov_b32_dpp v72, v57 row_ror:8 row_mask:0xf bank_mask:0xf
	v_cndmask_b32_e64 v48, v73, v60, s[6:7]
	v_cndmask_b32_e64 v49, v74, v61, s[6:7]
	v_cndmask_b32_e64 v50, v75, v56, s[6:7]
	v_cndmask_b32_e64 v51, v76, v57, s[6:7]
	v_cndmask_b32_e64 v52, v52, v67, s[6:7]
	v_cndmask_b32_e64 v53, v53, v70, s[6:7]
	v_cndmask_b32_e64 v54, v54, v71, s[6:7]
	v_cndmask_b32_e64 v55, v55, v72, s[6:7]
	global_store_dwordx4 v[64:65], v[48:51], off
	global_store_dwordx4 v[68:69], v[52:55], off
	s_waitcnt vmcnt(12)
; __device__ __forceinline__ unsigned cvt_pk_bf16(float lo, float hi) { unsigned r; asm volatile("v_cvt_pk_bf16_f32 %0, %1, %2" : "=v"(r) : "v"(lo), "v"(hi)); return r; }
;     __device__ __forceinline__ void operator()(const f32x4 (&acc)[2][2][4][2], const Unit& u, int wr, int wc, int fr, int fq) const {
;     ...
;             for (int m = 0; m < 4; ++m) { const int row = row0 + ai * HALF + m * 16;
;                 const float rs = ssin ? __builtin_amdgcn_rsqf(ssin[row] * (1.f / D) + EPS) : 1.0f; float sq = 0.f; u32x4 w[2];
; #pragma unroll
;                 for (int bj = 0; bj < 2; ++bj) { f32x4 v0 = acc[ai][bj][m][0] * rs, v1 = acc[ai][bj][m][1] * rs;
;                     if (ACT == 1) {
; #pragma unroll
;                         for (int j = 0; j < 4; ++j) { const float a = fmaxf(v0[j], 0.f), b = fmaxf(v1[j], 0.f); v0[j] = a * a; v1[j] = b * b; } }
;                     sq += (v0[0] * v0[0] + v0[1] * v0[1]) + (v0[2] * v0[2] + v0[3] * v0[3]) + (v1[0] * v1[0] + v1[1] * v1[1]) + (v1[2] * v1[2] + v1[3] * v1[3]);
;                     w[bj].x = cvt_pk_bf16(v0[0], v0[1]); w[bj].y = cvt_pk_bf16(v0[2], v0[3]); w[bj].z = cvt_pk_bf16(v1[0], v1[1]); w[bj].w = cvt_pk_bf16(v1[2], v1[3]); }
;                 store_pair_lines(O, ldc, row, fr, col0, w[0], w[1]);
; template <class Epi>
; __device__ __forceinline__ void gemm_phase(LAS unsigned char* lds, const Gemm g, const StaticOrder& S, const Epi& E) {
;     ...
;         E(acc, cur, wr, wc, fr, fq);
;         if (!has_next) break;
	s_nop 0
	v_mov_b32_e32 v50, v187
	s_nop 1
	v_mov_b32_e32 v51, 0
	v_add_u32_e32 v48, 0x90, v77
	v_add_u32_e32 v52, 0x98, v77
	v_mad_i64_i32 v[48:49], s[46:47], v48, s70, v[146:147]
	v_mad_i64_i32 v[52:53], s[46:47], v52, s70, v[146:147]
	v_lshl_add_u64 v[48:49], v[48:49], 0, v[148:149]
	v_lshl_add_u64 v[52:53], v[52:53], 0, v[148:149]
	v_fmamk_f32 v50, v50, 0x3a000000, v161
	v_rsq_f32_e32 v50, v50
	s_nop 0
	v_pk_mul_f32 v[44:45], v[44:45], v[50:51] op_sel_hi:[1,0]
	v_pk_mul_f32 v[40:41], v[40:41], v[50:51] op_sel_hi:[1,0]
	v_pk_mul_f32 v[38:39], v[38:39], v[50:51] op_sel_hi:[1,0]
	v_pk_mul_f32 v[36:37], v[36:37], v[50:51] op_sel_hi:[1,0]
	v_pk_mul_f32 v[46:47], v[46:47], v[50:51] op_sel_hi:[1,0]
	v_pk_mul_f32 v[42:43], v[42:43], v[50:51] op_sel_hi:[1,0]
	v_pk_mul_f32 v[34:35], v[34:35], v[50:51] op_sel_hi:[1,0]
	v_pk_mul_f32 v[32:33], v[32:33], v[50:51] op_sel_hi:[1,0]
	v_cvt_pk_bf16_f32 v44, v44, v45
	v_cvt_pk_bf16_f32 v45, v46, v47
	v_cvt_pk_bf16_f32 v40, v40, v41
	v_cvt_pk_bf16_f32 v41, v42, v43
	v_cvt_pk_bf16_f32 v36, v36, v37
	v_cvt_pk_bf16_f32 v37, v38, v39
	s_nop 0
	v_cvt_pk_bf16_f32 v38, v32, v33
	v_cvt_pk_bf16_f32 v39, v34, v35
	s_nop 0
	v_mov_b32_dpp v51, v44 row_ror:8 row_mask:0xf bank_mask:0xf
	v_mov_b32_dpp v54, v45 row_ror:8 row_mask:0xf bank_mask:0xf
	v_mov_b32_dpp v57, v36 row_ror:8 row_mask:0xf bank_mask:0xf
	v_mov_b32_dpp v58, v37 row_ror:8 row_mask:0xf bank_mask:0xf
	v_mov_b32_dpp v59, v38 row_ror:8 row_mask:0xf bank_mask:0xf
	v_mov_b32_dpp v60, v39 row_ror:8 row_mask:0xf bank_mask:0xf
	v_mov_b32_dpp v55, v40 row_ror:8 row_mask:0xf bank_mask:0xf
	v_mov_b32_dpp v56, v41 row_ror:8 row_mask:0xf bank_mask:0xf
	v_cndmask_b32_e64 v32, v57, v44, s[6:7]
	v_cndmask_b32_e64 v33, v58, v45, s[6:7]
	v_cndmask_b32_e64 v34, v59, v40, s[6:7]
	v_cndmask_b32_e64 v35, v60, v41, s[6:7]
	v_cndmask_b32_e64 v36, v36, v51, s[6:7]
	v_cndmask_b32_e64 v37, v37, v54, s[6:7]
	v_cndmask_b32_e64 v38, v38, v55, s[6:7]
	v_cndmask_b32_e64 v39, v39, v56, s[6:7]
	global_store_dwordx4 v[48:49], v[32:35], off
	global_store_dwordx4 v[52:53], v[36:39], off
	s_waitcnt vmcnt(13)
	s_nop 0
	v_mov_b32_e32 v34, v188
	s_nop 1
	v_mov_b32_e32 v35, 0
	v_add_u32_e32 v32, 0xa0, v77
	v_add_u32_e32 v36, 0xa8, v77
	v_mad_i64_i32 v[32:33], s[46:47], v32, s70, v[146:147]
	v_mad_i64_i32 v[36:37], s[46:47], v36, s70, v[146:147]
	v_lshl_add_u64 v[32:33], v[32:33], 0, v[148:149]
	v_lshl_add_u64 v[36:37], v[36:37], 0, v[148:149]
	s_mov_b64 s[46:47], s[38:39]
	v_fmamk_f32 v34, v34, 0x3a000000, v161
	v_rsq_f32_e32 v34, v34
	s_nop 0
	v_pk_mul_f32 v[28:29], v[28:29], v[34:35] op_sel_hi:[1,0]
	v_pk_mul_f32 v[24:25], v[24:25], v[34:35] op_sel_hi:[1,0]
	v_pk_mul_f32 v[22:23], v[22:23], v[34:35] op_sel_hi:[1,0]
	v_pk_mul_f32 v[20:21], v[20:21], v[34:35] op_sel_hi:[1,0]
	v_pk_mul_f32 v[30:31], v[30:31], v[34:35] op_sel_hi:[1,0]
	v_pk_mul_f32 v[26:27], v[26:27], v[34:35] op_sel_hi:[1,0]
	v_pk_mul_f32 v[18:19], v[18:19], v[34:35] op_sel_hi:[1,0]
	v_pk_mul_f32 v[16:17], v[16:17], v[34:35] op_sel_hi:[1,0]
	v_cvt_pk_bf16_f32 v28, v28, v29
	v_cvt_pk_bf16_f32 v29, v30, v31
	v_cvt_pk_bf16_f32 v24, v24, v25
	v_cvt_pk_bf16_f32 v25, v26, v27
	v_cvt_pk_bf16_f32 v20, v20, v21
	v_cvt_pk_bf16_f32 v21, v22, v23
	s_nop 0
	v_cvt_pk_bf16_f32 v22, v16, v17
	v_cvt_pk_bf16_f32 v23, v18, v19
	s_nop 0
	v_mov_b32_dpp v35, v28 row_ror:8 row_mask:0xf bank_mask:0xf
	v_mov_b32_dpp v38, v29 row_ror:8 row_mask:0xf bank_mask:0xf
	v_mov_b32_dpp v41, v20 row_ror:8 row_mask:0xf bank_mask:0xf
	v_mov_b32_dpp v42, v21 row_ror:8 row_mask:0xf bank_mask:0xf
	v_mov_b32_dpp v43, v22 row_ror:8 row_mask:0xf bank_mask:0xf
	v_mov_b32_dpp v44, v23 row_ror:8 row_mask:0xf bank_mask:0xf
	v_mov_b32_dpp v39, v24 row_ror:8 row_mask:0xf bank_mask:0xf
	v_mov_b32_dpp v40, v25 row_ror:8 row_mask:0xf bank_mask:0xf
	v_cndmask_b32_e64 v16, v41, v28, s[6:7]
	v_cndmask_b32_e64 v17, v42, v29, s[6:7]
	v_cndmask_b32_e64 v18, v43, v24, s[6:7]
	v_cndmask_b32_e64 v19, v44, v25, s[6:7]
	v_cndmask_b32_e64 v20, v20, v35, s[6:7]
	v_cndmask_b32_e64 v21, v21, v38, s[6:7]
	v_cndmask_b32_e64 v22, v22, v39, s[6:7]
	v_cndmask_b32_e64 v23, v23, v40, s[6:7]
	global_store_dwordx4 v[32:33], v[16:19], off
	global_store_dwordx4 v[36:37], v[20:23], off
	s_waitcnt vmcnt(14)
	s_nop 0
	v_mov_b32_e32 v18, v189
	s_nop 1
	v_mov_b32_e32 v19, 0
	v_add_u32_e32 v16, 0xb0, v77
	v_add_u32_e32 v20, 0xb8, v77
	v_mad_i64_i32 v[16:17], s[38:39], v16, s70, v[146:147]
	v_mad_i64_i32 v[20:21], s[38:39], v20, s70, v[146:147]
	v_lshl_add_u64 v[16:17], v[16:17], 0, v[148:149]
	v_lshl_add_u64 v[20:21], v[20:21], 0, v[148:149]
	v_fmamk_f32 v18, v18, 0x3a000000, v161
	v_rsq_f32_e32 v18, v18
	s_nop 0
	v_pk_mul_f32 v[12:13], v[12:13], v[18:19] op_sel_hi:[1,0]
	v_pk_mul_f32 v[8:9], v[8:9], v[18:19] op_sel_hi:[1,0]
	v_pk_mul_f32 v[6:7], v[6:7], v[18:19] op_sel_hi:[1,0]
	v_pk_mul_f32 v[4:5], v[4:5], v[18:19] op_sel_hi:[1,0]
	v_pk_mul_f32 v[14:15], v[14:15], v[18:19] op_sel_hi:[1,0]
	v_pk_mul_f32 v[10:11], v[10:11], v[18:19] op_sel_hi:[1,0]
	v_pk_mul_f32 v[2:3], v[2:3], v[18:19] op_sel_hi:[1,0]
	v_pk_mul_f32 v[0:1], v[0:1], v[18:19] op_sel_hi:[1,0]
	v_cvt_pk_bf16_f32 v12, v12, v13
	v_cvt_pk_bf16_f32 v13, v14, v15
	v_cvt_pk_bf16_f32 v8, v8, v9
	v_cvt_pk_bf16_f32 v9, v10, v11
	v_cvt_pk_bf16_f32 v4, v4, v5
	v_cvt_pk_bf16_f32 v5, v6, v7
	s_nop 0
	v_cvt_pk_bf16_f32 v6, v0, v1
	v_cvt_pk_bf16_f32 v7, v2, v3
	s_nop 0
	v_mov_b32_dpp v19, v12 row_ror:8 row_mask:0xf bank_mask:0xf
	v_mov_b32_dpp v22, v13 row_ror:8 row_mask:0xf bank_mask:0xf
	v_mov_b32_dpp v25, v4 row_ror:8 row_mask:0xf bank_mask:0xf
	v_mov_b32_dpp v26, v5 row_ror:8 row_mask:0xf bank_mask:0xf
	v_mov_b32_dpp v27, v6 row_ror:8 row_mask:0xf bank_mask:0xf
	v_mov_b32_dpp v28, v7 row_ror:8 row_mask:0xf bank_mask:0xf
	v_mov_b32_dpp v23, v8 row_ror:8 row_mask:0xf bank_mask:0xf
	v_mov_b32_dpp v24, v9 row_ror:8 row_mask:0xf bank_mask:0xf
	v_cndmask_b32_e64 v0, v25, v12, s[6:7]
	v_cndmask_b32_e64 v1, v26, v13, s[6:7]
	v_cndmask_b32_e64 v2, v27, v8, s[6:7]
	v_cndmask_b32_e64 v3, v28, v9, s[6:7]
	v_cndmask_b32_e64 v4, v4, v19, s[6:7]
	v_cndmask_b32_e64 v5, v5, v22, s[6:7]
	v_cndmask_b32_e64 v6, v6, v23, s[6:7]
	v_cndmask_b32_e64 v7, v7, v24, s[6:7]
	global_store_dwordx4 v[16:17], v[0:3], off
	global_store_dwordx4 v[20:21], v[4:7], off
	s_cbranch_vccz .LBB0_958
	s_waitcnt vmcnt(0)
	s_cmpk_gt_u32 s52, 0xff
	s_cbranch_scc1 .LBB0_966
	s_barrier

; #define PG8_STAGE(bufoff, gbase, voff) do { _Pragma("unroll") for (int _i = 0; _i < 2; ++_i) \
;         __builtin_amdgcn_global_load_lds((const unsigned*)((const char*)(gbase) + (voff)[_i]), (LAS unsigned*)(lds + (bufoff) + ldsw + _i * 8192), 16, 0, 0); } while (0)
; #define PG8_LDA(dst, b, h) do { _Pragma("unroll") for (int m = 0; m < 4; ++m) _Pragma("unroll") for (int k = 0; k < 2; ++k) dst[m][k] = *(const LAS bf16x8*)(lds + PG8_SA(b, h) + aoff + m * 2048 + k * 1024); } while (0)
; #define PG8_LDB(dst, b, h) do { _Pragma("unroll") for (int n = 0; n < 2; ++n) _Pragma("unroll") for (int k = 0; k < 2; ++k) dst[n][k] = *(const LAS bf16x8*)(lds + PG8_SB(b, h) + boff + n * 2048 + k * 1024); } while (0)
; #define PG8_MMA(ai, bj, At, Bt) do { __builtin_amdgcn_s_setprio(1); _Pragma("unroll") for (int m = 0; m < 4; ++m) _Pragma("unroll") for (int n = 0; n < 2; ++n) _Pragma("unroll") for (int k = 0; k < 2; ++k) \
;         acc[ai][bj][m][n] = __builtin_amdgcn_mfma_f32_16x16x32_bf16(Bt[n][k], At[m][k], acc[ai][bj][m][n], 0, 0, 0); __builtin_amdgcn_s_setprio(0); } while (0)
; #define PG8_WAIT_V(n) asm volatile("s_waitcnt vmcnt(" #n ")" ::: "memory")
; #define PG8_WAIT_L(n) asm volatile("s_waitcnt lgkmcnt(" #n ")" ::: "memory")
; #define PG8_BAR __builtin_amdgcn_s_barrier()
; template <class Epi>
; __device__ __forceinline__ void gemm_phase(LAS unsigned char* lds, const Gemm g, const StaticOrder& S, const Epi& E) {
;     ...
;         for (int t = 0; t < nt; t += 2) {
;             const bool last = (t == nt - 2);
;             const char* a1 = cA + (size_t)(t + 1) * kstep;
;             const char* a2 = last ? nA : cA + (size_t)(t + 2) * kstep; const char* b2 = last ? nB : cB + (size_t)(t + 2) * kstep;
;             const char* a3 = a2 + kstep; const char* b3 = b2 + kstep;
;             PG8_LDB(B0, 0, 0); PG8_SCHED; PG8_LDA(At, 0, 0); PG8_STAGE(PG8_SA(1, 1), a1 + hstep, voffA);
;             PG8_WAIT_L(8); PG8_BAR; PG8_WAIT_L(0); PG8_MMA(0, 0, At, B0); PG8_BAR; PG8_SCHED;
;             PG8_LDB(B1, 0, 1); PG8_STAGE(PG8_SB(0, 0), b2, voffB0);
;             PG8_BAR; PG8_WAIT_L(0); PG8_MMA(0, 1, At, B1); PG8_BAR;
;             PG8_LDA(At, 0, 1); PG8_STAGE(PG8_SA(0, 0), a2, voffA);
;             PG8_BAR; PG8_WAIT_L(0); PG8_MMA(1, 0, At, B0); PG8_BAR; PG8_SCHED;
;             PG8_STAGE(PG8_SB(0, 1), b2, voffB1);
;             PG8_WAIT_V(6); PG8_BAR; PG8_MMA(1, 1, At, B1); PG8_BAR;
.LBB0_1245:
	ds_read_b128 v[146:149], v154
	ds_read_b128 v[158:161], v154 offset:1024
	ds_read_b128 v[162:165], v154 offset:2048
	ds_read_b128 v[166:169], v154 offset:3072
	s_add_u32 s33, s46, 0xfff80080
	s_addc_u32 s48, s47, -1
	s_cmp_eq_u32 s73, 28
	s_cselect_b32 s49, s35, s48
	s_cselect_b32 s48, s43, s33
	s_cselect_b32 s51, s31, s72
	s_cselect_b32 s50, s70, s71
	v_lshl_add_u64 v[204:205], s[46:47], 0, v[140:141]
	s_add_i32 m0, s45, 0xc000
	ds_read_b128 v[170:173], v155
	ds_read_b128 v[174:177], v155 offset:1024
	ds_read_b128 v[178:181], v155 offset:2048
	ds_read_b128 v[182:185], v155 offset:3072
	ds_read_b128 v[186:189], v155 offset:4096
	ds_read_b128 v[190:193], v155 offset:5120
	ds_read_b128 v[194:197], v155 offset:6144
	ds_read_b128 v[198:201], v155 offset:7168
	global_load_lds_dwordx4 v[204:205], off
	v_lshl_add_u64 v[204:205], s[46:47], 0, v[142:143]
	s_add_i32 m0, s45, 0xe000
	s_nop 0
	global_load_lds_dwordx4 v[204:205], off
	s_waitcnt lgkmcnt(8)
	s_barrier
	s_waitcnt lgkmcnt(0)
	v_mfma_f32_16x16x32_bf16 v[124:127], v[146:149], v[170:173], v[124:127]
	v_mfma_f32_16x16x32_bf16 v[120:123], v[162:165], v[170:173], v[120:123]
	v_mfma_f32_16x16x32_bf16 v[108:111], v[146:149], v[178:181], v[108:111]
	v_mfma_f32_16x16x32_bf16 v[104:107], v[162:165], v[178:181], v[104:107]
	v_mfma_f32_16x16x32_bf16 v[92:95], v[146:149], v[186:189], v[92:95]
	v_mfma_f32_16x16x32_bf16 v[88:91], v[162:165], v[186:189], v[88:91]
	v_mfma_f32_16x16x32_bf16 v[76:79], v[146:149], v[194:197], v[76:79]
	v_mfma_f32_16x16x32_bf16 v[72:75], v[162:165], v[194:197], v[72:75]
	v_mfma_f32_16x16x32_bf16 v[124:127], v[158:161], v[174:177], v[124:127]
	v_mfma_f32_16x16x32_bf16 v[120:123], v[166:169], v[174:177], v[120:123]
	v_mfma_f32_16x16x32_bf16 v[108:111], v[158:161], v[182:185], v[108:111]
	v_mfma_f32_16x16x32_bf16 v[104:107], v[166:169], v[182:185], v[104:107]
	v_mfma_f32_16x16x32_bf16 v[92:95], v[158:161], v[190:193], v[92:95]
	v_mfma_f32_16x16x32_bf16 v[88:91], v[166:169], v[190:193], v[88:91]
	v_mfma_f32_16x16x32_bf16 v[76:79], v[158:161], v[198:201], v[76:79]
	v_mfma_f32_16x16x32_bf16 v[72:75], v[166:169], v[198:201], v[72:75]
	s_barrier
	s_add_i32 s33, s68, s57
	v_lshl_add_u64 v[220:221], s[50:51], 0, v[130:131]
	s_mov_b32 m0, s33
	ds_read_b128 v[204:207], v156
	ds_read_b128 v[208:211], v156 offset:1024
	ds_read_b128 v[212:215], v156 offset:2048
	ds_read_b128 v[216:219], v156 offset:3072
	global_load_lds_dwordx4 v[220:221], off
	v_lshl_add_u64 v[222:223], s[50:51], 0, v[136:137]
	s_add_i32 m0, s33, 0x2000
	s_nop 0
	global_load_lds_dwordx4 v[222:223], off
	s_waitcnt lgkmcnt(0)
	s_barrier
	s_waitcnt lgkmcnt(0)
	v_mfma_f32_16x16x32_bf16 v[116:119], v[204:207], v[170:173], v[116:119]
	v_mfma_f32_16x16x32_bf16 v[112:115], v[212:215], v[170:173], v[112:115]
	v_mfma_f32_16x16x32_bf16 v[100:103], v[204:207], v[178:181], v[100:103]
	v_mfma_f32_16x16x32_bf16 v[96:99], v[212:215], v[178:181], v[96:99]
	v_mfma_f32_16x16x32_bf16 v[84:87], v[204:207], v[186:189], v[84:87]
	v_mfma_f32_16x16x32_bf16 v[80:83], v[212:215], v[186:189], v[80:83]
	v_mfma_f32_16x16x32_bf16 v[68:71], v[204:207], v[194:197], v[68:71]
	v_mfma_f32_16x16x32_bf16 v[64:67], v[212:215], v[194:197], v[64:67]
	v_mfma_f32_16x16x32_bf16 v[116:119], v[208:211], v[174:177], v[116:119]
	v_mfma_f32_16x16x32_bf16 v[112:115], v[216:219], v[174:177], v[112:115]
	v_mfma_f32_16x16x32_bf16 v[100:103], v[208:211], v[182:185], v[100:103]
	v_mfma_f32_16x16x32_bf16 v[96:99], v[216:219], v[182:185], v[96:99]
	v_mfma_f32_16x16x32_bf16 v[84:87], v[208:211], v[190:193], v[84:87]
	v_mfma_f32_16x16x32_bf16 v[80:83], v[216:219], v[190:193], v[80:83]
	v_mfma_f32_16x16x32_bf16 v[68:71], v[208:211], v[198:201], v[68:71]
	v_mfma_f32_16x16x32_bf16 v[64:67], v[216:219], v[198:201], v[64:67]
	s_mov_b32 m0, s45
	v_lshl_add_u64 v[224:225], s[48:49], 0, v[128:129]
	s_barrier
	ds_read_b128 v[170:173], v155 offset:16384
	ds_read_b128 v[174:177], v155 offset:17408
	ds_read_b128 v[178:181], v155 offset:18432
	ds_read_b128 v[182:185], v155 offset:19456
	ds_read_b128 v[186:189], v155 offset:20480
	ds_read_b128 v[190:193], v155 offset:21504
	ds_read_b128 v[194:197], v155 offset:22528
	ds_read_b128 v[198:201], v155 offset:23552
	global_load_lds_dwordx4 v[224:225], off
	v_lshl_add_u64 v[226:227], s[48:49], 0, v[134:135]
	s_mov_b32 m0, s58
	s_nop 0
	global_load_lds_dwordx4 v[226:227], off
	s_add_i32 s33, s69, s57
	v_lshl_add_u64 v[228:229], s[50:51], 0, v[132:133]
	s_mov_b32 m0, s33
	v_lshl_add_u64 v[230:231], s[50:51], 0, v[138:139]
	global_load_lds_dwordx4 v[228:229], off
	s_add_i32 m0, s33, 0x2000
	s_nop 0
	global_load_lds_dwordx4 v[230:231], off
	s_waitcnt vmcnt(6)
	s_barrier
; #define PG8_STAGE(bufoff, gbase, voff) do { _Pragma("unroll") for (int _i = 0; _i < 2; ++_i) \
;         __builtin_amdgcn_global_load_lds((const unsigned*)((const char*)(gbase) + (voff)[_i]), (LAS unsigned*)(lds + (bufoff) + ldsw + _i * 8192), 16, 0, 0); } while (0)
; #define PG8_LDA(dst, b, h) do { _Pragma("unroll") for (int m = 0; m < 4; ++m) _Pragma("unroll") for (int k = 0; k < 2; ++k) dst[m][k] = *(const LAS bf16x8*)(lds + PG8_SA(b, h) + aoff + m * 2048 + k * 1024); } while (0)
; #define PG8_LDB(dst, b, h) do { _Pragma("unroll") for (int n = 0; n < 2; ++n) _Pragma("unroll") for (int k = 0; k < 2; ++k) dst[n][k] = *(const LAS bf16x8*)(lds + PG8_SB(b, h) + boff + n * 2048 + k * 1024); } while (0)
; #define PG8_MMA(ai, bj, At, Bt) do { __builtin_amdgcn_s_setprio(1); _Pragma("unroll") for (int m = 0; m < 4; ++m) _Pragma("unroll") for (int n = 0; n < 2; ++n) _Pragma("unroll") for (int k = 0; k < 2; ++k) \
;         acc[ai][bj][m][n] = __builtin_amdgcn_mfma_f32_16x16x32_bf16(Bt[n][k], At[m][k], acc[ai][bj][m][n], 0, 0, 0); __builtin_amdgcn_s_setprio(0); } while (0)
; #define PG8_WAIT_V(n) asm volatile("s_waitcnt vmcnt(" #n ")" ::: "memory")
; #define PG8_WAIT_L(n) asm volatile("s_waitcnt lgkmcnt(" #n ")" ::: "memory")
; #define PG8_BAR __builtin_amdgcn_s_barrier()
; #define PG8_SCHED __builtin_amdgcn_sched_barrier(0)
; template <class Epi>
; __device__ __forceinline__ void gemm_phase(LAS unsigned char* lds, const Gemm g, const StaticOrder& S, const Epi& E) {
;     ...
;             PG8_BAR; PG8_WAIT_L(0); PG8_MMA(1, 0, At, B0); PG8_BAR; PG8_SCHED;
;             PG8_STAGE(PG8_SB(0, 1), b2, voffB1);
;             PG8_WAIT_V(6); PG8_BAR; PG8_MMA(1, 1, At, B1); PG8_BAR;
;             PG8_LDB(B0, 1, 0); PG8_SCHED; PG8_LDA(At, 1, 0); PG8_STAGE(PG8_SA(0, 1), a2 + hstep, voffA);
;             PG8_WAIT_L(8); PG8_BAR; PG8_WAIT_L(0); PG8_MMA(0, 0, At, B0); PG8_BAR; PG8_SCHED;
;             PG8_LDB(B1, 1, 1); PG8_STAGE(PG8_SB(1, 0), b3, voffB0);
;             PG8_BAR; PG8_WAIT_L(0); PG8_MMA(0, 1, At, B1); PG8_BAR;
;             PG8_LDA(At, 1, 1); PG8_STAGE(PG8_SA(1, 0), a3, voffA);
;             PG8_BAR; PG8_WAIT_L(0); PG8_MMA(1, 0, At, B0); PG8_BAR; PG8_SCHED;
	s_waitcnt lgkmcnt(0)
	v_mfma_f32_16x16x32_bf16 v[60:63], v[146:149], v[170:173], v[60:63]
	v_mfma_f32_16x16x32_bf16 v[56:59], v[162:165], v[170:173], v[56:59]
	v_mfma_f32_16x16x32_bf16 v[44:47], v[146:149], v[178:181], v[44:47]
	v_mfma_f32_16x16x32_bf16 v[40:43], v[162:165], v[178:181], v[40:43]
	v_mfma_f32_16x16x32_bf16 v[28:31], v[146:149], v[186:189], v[28:31]
	v_mfma_f32_16x16x32_bf16 v[24:27], v[162:165], v[186:189], v[24:27]
	v_mfma_f32_16x16x32_bf16 v[12:15], v[146:149], v[194:197], v[12:15]
	v_mfma_f32_16x16x32_bf16 v[8:11], v[162:165], v[194:197], v[8:11]
	v_mfma_f32_16x16x32_bf16 v[60:63], v[158:161], v[174:177], v[60:63]
	v_mfma_f32_16x16x32_bf16 v[56:59], v[166:169], v[174:177], v[56:59]
	v_mfma_f32_16x16x32_bf16 v[44:47], v[158:161], v[182:185], v[44:47]
	v_mfma_f32_16x16x32_bf16 v[40:43], v[166:169], v[182:185], v[40:43]
	v_mfma_f32_16x16x32_bf16 v[28:31], v[158:161], v[190:193], v[28:31]
	v_mfma_f32_16x16x32_bf16 v[24:27], v[166:169], v[190:193], v[24:27]
	v_mfma_f32_16x16x32_bf16 v[12:15], v[158:161], v[198:201], v[12:15]
	v_mfma_f32_16x16x32_bf16 v[8:11], v[166:169], v[198:201], v[8:11]
	v_mfma_f32_16x16x32_bf16 v[52:55], v[204:207], v[170:173], v[52:55]
	v_mfma_f32_16x16x32_bf16 v[48:51], v[212:215], v[170:173], v[48:51]
	v_mfma_f32_16x16x32_bf16 v[36:39], v[204:207], v[178:181], v[36:39]
	v_mfma_f32_16x16x32_bf16 v[32:35], v[212:215], v[178:181], v[32:35]
	v_mfma_f32_16x16x32_bf16 v[20:23], v[204:207], v[186:189], v[20:23]
	v_mfma_f32_16x16x32_bf16 v[16:19], v[212:215], v[186:189], v[16:19]
	v_mfma_f32_16x16x32_bf16 v[4:7], v[204:207], v[194:197], v[4:7]
	v_mfma_f32_16x16x32_bf16 v[0:3], v[212:215], v[194:197], v[0:3]
	v_mfma_f32_16x16x32_bf16 v[52:55], v[208:211], v[174:177], v[52:55]
	v_mfma_f32_16x16x32_bf16 v[48:51], v[216:219], v[174:177], v[48:51]
	v_mfma_f32_16x16x32_bf16 v[36:39], v[208:211], v[182:185], v[36:39]
	v_mfma_f32_16x16x32_bf16 v[32:35], v[216:219], v[182:185], v[32:35]
	v_mfma_f32_16x16x32_bf16 v[20:23], v[208:211], v[190:193], v[20:23]
	v_mfma_f32_16x16x32_bf16 v[16:19], v[216:219], v[190:193], v[16:19]
	v_mfma_f32_16x16x32_bf16 v[4:7], v[208:211], v[198:201], v[4:7]
	v_mfma_f32_16x16x32_bf16 v[0:3], v[216:219], v[198:201], v[0:3]
	s_add_i32 s33, 0, 0x18000
	v_add_u32_e32 v157, s33, v151
	s_barrier
	ds_read_b128 v[146:149], v157
	ds_read_b128 v[158:161], v157 offset:1024
	ds_read_b128 v[162:165], v157 offset:2048
	ds_read_b128 v[166:169], v157 offset:3072
	s_add_u32 s48, s48, 0x80000
	s_addc_u32 s49, s49, 0
	s_mov_b32 m0, s59
	v_lshl_add_u64 v[204:205], s[48:49], 0, v[128:129]
	ds_read_b128 v[170:173], v155 offset:32768
	ds_read_b128 v[174:177], v155 offset:33792
	ds_read_b128 v[178:181], v155 offset:34816
	ds_read_b128 v[182:185], v155 offset:35840
	ds_read_b128 v[186:189], v155 offset:36864
	ds_read_b128 v[190:193], v155 offset:37888
	ds_read_b128 v[194:197], v155 offset:38912
	ds_read_b128 v[198:201], v155 offset:39936
	global_load_lds_dwordx4 v[204:205], off
	v_lshl_add_u64 v[204:205], s[48:49], 0, v[134:135]
	s_mov_b32 m0, s60
	s_nop 0
	global_load_lds_dwordx4 v[204:205], off
	s_waitcnt lgkmcnt(8)
	s_barrier
	s_waitcnt lgkmcnt(0)
	v_mfma_f32_16x16x32_bf16 v[124:127], v[146:149], v[170:173], v[124:127]
	v_mfma_f32_16x16x32_bf16 v[120:123], v[162:165], v[170:173], v[120:123]
	v_mfma_f32_16x16x32_bf16 v[108:111], v[146:149], v[178:181], v[108:111]
	v_mfma_f32_16x16x32_bf16 v[104:107], v[162:165], v[178:181], v[104:107]
	v_mfma_f32_16x16x32_bf16 v[92:95], v[146:149], v[186:189], v[92:95]
	v_mfma_f32_16x16x32_bf16 v[88:91], v[162:165], v[186:189], v[88:91]
	v_mfma_f32_16x16x32_bf16 v[76:79], v[146:149], v[194:197], v[76:79]
	v_mfma_f32_16x16x32_bf16 v[72:75], v[162:165], v[194:197], v[72:75]
	v_mfma_f32_16x16x32_bf16 v[124:127], v[158:161], v[174:177], v[124:127]
	v_mfma_f32_16x16x32_bf16 v[120:123], v[166:169], v[174:177], v[120:123]
	v_mfma_f32_16x16x32_bf16 v[108:111], v[158:161], v[182:185], v[108:111]
	v_mfma_f32_16x16x32_bf16 v[104:107], v[166:169], v[182:185], v[104:107]
	v_mfma_f32_16x16x32_bf16 v[92:95], v[158:161], v[190:193], v[92:95]
	v_mfma_f32_16x16x32_bf16 v[88:91], v[166:169], v[190:193], v[88:91]
	v_mfma_f32_16x16x32_bf16 v[76:79], v[158:161], v[198:201], v[76:79]
	v_mfma_f32_16x16x32_bf16 v[72:75], v[166:169], v[198:201], v[72:75]
	s_barrier
	s_add_i32 s48, 0, 0x1c000
	s_add_i32 s33, s33, s57
	v_add_u32_e32 v157, s48, v151
	v_lshl_add_u64 v[220:221], v[220:221], 0, s[26:27]
	s_mov_b32 m0, s33
	ds_read_b128 v[204:207], v157
	ds_read_b128 v[208:211], v157 offset:1024
	ds_read_b128 v[212:215], v157 offset:2048
	ds_read_b128 v[216:219], v157 offset:3072
	global_load_lds_dwordx4 v[220:221], off
	v_lshl_add_u64 v[220:221], v[222:223], 0, s[26:27]
	s_add_i32 m0, s33, 0x2000
	s_nop 0
	global_load_lds_dwordx4 v[220:221], off
	s_waitcnt lgkmcnt(0)
	s_barrier
	s_waitcnt lgkmcnt(0)
	v_mfma_f32_16x16x32_bf16 v[116:119], v[204:207], v[170:173], v[116:119]
	v_mfma_f32_16x16x32_bf16 v[112:115], v[212:215], v[170:173], v[112:115]
	v_mfma_f32_16x16x32_bf16 v[100:103], v[204:207], v[178:181], v[100:103]
	v_mfma_f32_16x16x32_bf16 v[96:99], v[212:215], v[178:181], v[96:99]
	v_mfma_f32_16x16x32_bf16 v[84:87], v[204:207], v[186:189], v[84:87]
	v_mfma_f32_16x16x32_bf16 v[80:83], v[212:215], v[186:189], v[80:83]
	v_mfma_f32_16x16x32_bf16 v[68:71], v[204:207], v[194:197], v[68:71]
	v_mfma_f32_16x16x32_bf16 v[64:67], v[212:215], v[194:197], v[64:67]
	v_mfma_f32_16x16x32_bf16 v[116:119], v[208:211], v[174:177], v[116:119]
	v_mfma_f32_16x16x32_bf16 v[112:115], v[216:219], v[174:177], v[112:115]
	v_mfma_f32_16x16x32_bf16 v[100:103], v[208:211], v[182:185], v[100:103]
	v_mfma_f32_16x16x32_bf16 v[96:99], v[216:219], v[182:185], v[96:99]
	v_mfma_f32_16x16x32_bf16 v[84:87], v[208:211], v[190:193], v[84:87]
	v_mfma_f32_16x16x32_bf16 v[80:83], v[216:219], v[190:193], v[80:83]
	v_mfma_f32_16x16x32_bf16 v[68:71], v[208:211], v[198:201], v[68:71]
	v_mfma_f32_16x16x32_bf16 v[64:67], v[216:219], v[198:201], v[64:67]
	s_mov_b32 m0, s62
	v_lshl_add_u64 v[220:221], v[224:225], 0, s[26:27]
	s_barrier
; __device__ __forceinline__ unsigned dpp_ror8(unsigned x) { return (unsigned)__builtin_amdgcn_update_dpp(0, (int)x, 0x128, 0xf, 0xf, false); }
; #define PG8_STAGE(bufoff, gbase, voff) do { _Pragma("unroll") for (int _i = 0; _i < 2; ++_i) \
;         __builtin_amdgcn_global_load_lds((const unsigned*)((const char*)(gbase) + (voff)[_i]), (LAS unsigned*)(lds + (bufoff) + ldsw + _i * 8192), 16, 0, 0); } while (0)
; #define PG8_LDA(dst, b, h) do { _Pragma("unroll") for (int m = 0; m < 4; ++m) _Pragma("unroll") for (int k = 0; k < 2; ++k) dst[m][k] = *(const LAS bf16x8*)(lds + PG8_SA(b, h) + aoff + m * 2048 + k * 1024); } while (0)
; #define PG8_MMA(ai, bj, At, Bt) do { __builtin_amdgcn_s_setprio(1); _Pragma("unroll") for (int m = 0; m < 4; ++m) _Pragma("unroll") for (int n = 0; n < 2; ++n) _Pragma("unroll") for (int k = 0; k < 2; ++k) \
;         acc[ai][bj][m][n] = __builtin_amdgcn_mfma_f32_16x16x32_bf16(Bt[n][k], At[m][k], acc[ai][bj][m][n], 0, 0, 0); __builtin_amdgcn_s_setprio(0); } while (0)
; #define PG8_WAIT_V(n) asm volatile("s_waitcnt vmcnt(" #n ")" ::: "memory")
; #define PG8_WAIT_L(n) asm volatile("s_waitcnt lgkmcnt(" #n ")" ::: "memory")
; #define PG8_BAR __builtin_amdgcn_s_barrier()
; #define PG8_SCHED __builtin_amdgcn_sched_barrier(0)
;     const bool lo = fr < 8;
;     const int r1 = row - fr + (fr & 7), cb = col0 + (lo ? 0 : boff);
;     const u32x4 l1 = *(const u32x4*)(P + (size_t)r1 * ld + cb), l2 = *(const u32x4*)(P + (size_t)(r1 + 8) * ld + cb);
;     const u32x4 s1 = {dpp_ror8(l1.x), dpp_ror8(l1.y), dpp_ror8(l1.z), dpp_ror8(l1.w)}, s2 = {dpp_ror8(l2.x), dpp_ror8(l2.y), dpp_ror8(l2.z), dpp_ror8(l2.w)};
;     wA = lo ? l1 : s2; wB = lo ? s1 : l2;
; }
;     __device__ __forceinline__ void operator()(const f32x4 (&acc)[2][2][4][2], const Unit& u, int wr, int wc, int fr, int fq) const {
;     ...
;                 u32x4 rr[2]; if (R) load_pair_lines(R, D, row, fr, col0, rr[0], rr[1]);
; template <class Epi>
; __device__ __forceinline__ void gemm_phase(LAS unsigned char* lds, const Gemm g, const StaticOrder& S, const Epi& E) {
;     ...
;             PG8_LDA(At, 1, 1); PG8_STAGE(PG8_SA(1, 0), a3, voffA);
;             PG8_BAR; PG8_WAIT_L(0); PG8_MMA(1, 0, At, B0); PG8_BAR; PG8_SCHED;
;             PG8_STAGE(PG8_SB(1, 1), b3, voffB1);
;             PG8_WAIT_V(6); PG8_BAR; PG8_MMA(1, 1, At, B1); PG8_BAR;
;         }
	ds_read_b128 v[170:173], v155 offset:49152
	ds_read_b128 v[174:177], v155 offset:50176
	ds_read_b128 v[178:181], v155 offset:51200
	ds_read_b128 v[182:185], v155 offset:52224
	ds_read_b128 v[186:189], v155 offset:53248
	ds_read_b128 v[190:193], v155 offset:54272
	ds_read_b128 v[194:197], v155 offset:55296
	ds_read_b128 v[198:201], v155 offset:56320
	global_load_lds_dwordx4 v[220:221], off
	v_lshl_add_u64 v[220:221], v[226:227], 0, s[26:27]
	s_mov_b32 m0, s63
	s_nop 0
	global_load_lds_dwordx4 v[220:221], off
	s_add_i32 s33, s48, s57
	v_lshl_add_u64 v[250:251], v[228:229], 0, s[26:27]
	s_mov_b32 m0, s33
	s_nop 0
	global_load_lds_dwordx4 v[250:251], off
	v_lshl_add_u64 v[250:251], v[230:231], 0, s[26:27]
	s_add_i32 m0, s33, 0x2000
	s_nop 0
	global_load_lds_dwordx4 v[250:251], off
	s_waitcnt vmcnt(6)
	s_barrier
	s_waitcnt lgkmcnt(0)
	v_mfma_f32_16x16x32_bf16 v[60:63], v[146:149], v[170:173], v[60:63]
	v_mfma_f32_16x16x32_bf16 v[56:59], v[162:165], v[170:173], v[56:59]
	v_mfma_f32_16x16x32_bf16 v[44:47], v[146:149], v[178:181], v[44:47]
	v_mfma_f32_16x16x32_bf16 v[40:43], v[162:165], v[178:181], v[40:43]
	v_mfma_f32_16x16x32_bf16 v[28:31], v[146:149], v[186:189], v[28:31]
	v_mfma_f32_16x16x32_bf16 v[24:27], v[162:165], v[186:189], v[24:27]
	v_mfma_f32_16x16x32_bf16 v[12:15], v[146:149], v[194:197], v[12:15]
	v_mfma_f32_16x16x32_bf16 v[8:11], v[162:165], v[194:197], v[8:11]
	v_mfma_f32_16x16x32_bf16 v[60:63], v[158:161], v[174:177], v[60:63]
	v_mfma_f32_16x16x32_bf16 v[56:59], v[166:169], v[174:177], v[56:59]
	v_mfma_f32_16x16x32_bf16 v[44:47], v[158:161], v[182:185], v[44:47]
	v_mfma_f32_16x16x32_bf16 v[40:43], v[166:169], v[182:185], v[40:43]
	v_mfma_f32_16x16x32_bf16 v[28:31], v[158:161], v[190:193], v[28:31]
	v_mfma_f32_16x16x32_bf16 v[24:27], v[166:169], v[190:193], v[24:27]
	v_mfma_f32_16x16x32_bf16 v[12:15], v[158:161], v[198:201], v[12:15]
	v_mfma_f32_16x16x32_bf16 v[8:11], v[166:169], v[198:201], v[8:11]
	v_mfma_f32_16x16x32_bf16 v[52:55], v[204:207], v[170:173], v[52:55]
	v_mfma_f32_16x16x32_bf16 v[48:51], v[212:215], v[170:173], v[48:51]
	v_mfma_f32_16x16x32_bf16 v[36:39], v[204:207], v[178:181], v[36:39]
	v_mfma_f32_16x16x32_bf16 v[32:35], v[212:215], v[178:181], v[32:35]
	v_mfma_f32_16x16x32_bf16 v[20:23], v[204:207], v[186:189], v[20:23]
	v_mfma_f32_16x16x32_bf16 v[16:19], v[212:215], v[186:189], v[16:19]
	v_mfma_f32_16x16x32_bf16 v[4:7], v[204:207], v[194:197], v[4:7]
	v_mfma_f32_16x16x32_bf16 v[0:3], v[212:215], v[194:197], v[0:3]
	v_mfma_f32_16x16x32_bf16 v[52:55], v[208:211], v[174:177], v[52:55]
	v_mfma_f32_16x16x32_bf16 v[48:51], v[216:219], v[174:177], v[48:51]
	v_mfma_f32_16x16x32_bf16 v[36:39], v[208:211], v[182:185], v[36:39]
	v_mfma_f32_16x16x32_bf16 v[32:35], v[216:219], v[182:185], v[32:35]
	v_mfma_f32_16x16x32_bf16 v[20:23], v[208:211], v[190:193], v[20:23]
	v_mfma_f32_16x16x32_bf16 v[16:19], v[216:219], v[190:193], v[16:19]
	v_mfma_f32_16x16x32_bf16 v[4:7], v[208:211], v[198:201], v[4:7]
	v_mfma_f32_16x16x32_bf16 v[0:3], v[216:219], v[198:201], v[0:3]
	s_add_i32 s73, s73, 2
	s_add_u32 s46, s46, 0x100
	s_addc_u32 s47, s47, 0
	s_add_u32 s71, s71, 0x100
	s_addc_u32 s72, s72, 0
	s_cmp_gt_u32 s73, 29
	s_barrier
	s_cbranch_scc0 .LBB0_1245
	s_lshl_b32 s31, s44, 8
	s_add_i32 s31, s31, s64
	v_or_b32_e32 v148, s31, v152
	v_ashrrev_i32_e32 v149, 31, v148
	v_lshlrev_b64 v[166:167], 12, v[148:149]
	v_or_b32_e32 v148, 8, v148
	v_lshl_or_b32 v146, s42, 8, v153
	v_ashrrev_i32_e32 v149, 31, v148
	v_ashrrev_i32_e32 v147, 31, v146
	v_lshlrev_b64 v[168:169], 12, v[148:149]
	v_lshl_add_u64 v[158:159], s[10:11], 0, v[166:167]
	v_lshlrev_b64 v[146:147], 1, v[146:147]
	v_lshl_add_u64 v[148:149], s[10:11], 0, v[168:169]
	v_lshl_add_u64 v[158:159], v[158:159], 0, v[146:147]
	v_lshl_add_u64 v[148:149], v[148:149], 0, v[146:147]
	global_load_dwordx4 v[158:161], v[158:159], off
	global_load_dwordx4 v[162:165], v[148:149], off
	v_or_b32_e32 v194, s31, v150
	v_or_b32_e32 v184, 16, v194
	v_sub_u32_e32 v185, v184, v150
	v_add_u32_e32 v186, v185, v152
	v_ashrrev_i32_e32 v187, 31, v186
	v_lshlrev_b64 v[190:191], 12, v[186:187]
	v_lshl_add_u64 v[192:193], v[190:191], 0, s[28:29]
	v_lshl_add_u64 v[186:187], s[10:11], 0, v[190:191]
	v_lshl_add_u64 v[188:189], s[10:11], 0, v[192:193]
	v_lshl_add_u64 v[186:187], v[186:187], 0, v[146:147]
	v_lshl_add_u64 v[188:189], v[188:189], 0, v[146:147]
	global_load_dwordx4 v[196:199], v[186:187], off
	global_load_dwordx4 v[204:207], v[188:189], off
	v_or_b32_e32 v194, s31, v150
	v_or_b32_e32 v184, 32, v194
	v_sub_u32_e32 v185, v184, v150
	v_add_u32_e32 v186, v185, v152
	v_ashrrev_i32_e32 v187, 31, v186
	v_lshlrev_b64 v[190:191], 12, v[186:187]
	v_lshl_add_u64 v[192:193], v[190:191], 0, s[28:29]
	v_lshl_add_u64 v[186:187], s[10:11], 0, v[190:191]
	v_lshl_add_u64 v[188:189], s[10:11], 0, v[192:193]
	v_lshl_add_u64 v[186:187], v[186:187], 0, v[146:147]
	v_lshl_add_u64 v[188:189], v[188:189], 0, v[146:147]
	global_load_dwordx4 v[208:211], v[186:187], off
	global_load_dwordx4 v[212:215], v[188:189], off
	v_or_b32_e32 v194, s31, v150
	v_or_b32_e32 v184, 48, v194
	v_sub_u32_e32 v185, v184, v150
	v_add_u32_e32 v186, v185, v152
	v_ashrrev_i32_e32 v187, 31, v186
	v_lshlrev_b64 v[190:191], 12, v[186:187]
	v_lshl_add_u64 v[192:193], v[190:191], 0, s[28:29]
	v_lshl_add_u64 v[186:187], s[10:11], 0, v[190:191]
	v_lshl_add_u64 v[188:189], s[10:11], 0, v[192:193]
	v_lshl_add_u64 v[186:187], v[186:187], 0, v[146:147]
	v_lshl_add_u64 v[188:189], v[188:189], 0, v[146:147]
	global_load_dwordx4 v[216:219], v[186:187], off
	global_load_dwordx4 v[220:223], v[188:189], off
	v_or_b32_e32 v194, s31, v150
	v_add_u32_e32 v184, 0x80, v194
; __device__ __forceinline__ unsigned cvt_pk_bf16(float lo, float hi) { unsigned r; asm volatile("v_cvt_pk_bf16_f32 %0, %1, %2" : "=v"(r) : "v"(lo), "v"(hi)); return r; }
; __device__ __forceinline__ float bflo(unsigned w) { return __uint_as_float(w << 16); }
; __device__ __forceinline__ float bfhi(unsigned w) { return __uint_as_float(w & 0xffff0000u); }
; __device__ __forceinline__ unsigned dpp_ror8(unsigned x) { return (unsigned)__builtin_amdgcn_update_dpp(0, (int)x, 0x128, 0xf, 0xf, false); }
;     const bool lo = fr < 8;
;     const int r1 = row - fr + (fr & 7), cb = col0 + (lo ? 0 : boff);
;     const u32x4 l1 = *(const u32x4*)(P + (size_t)r1 * ld + cb), l2 = *(const u32x4*)(P + (size_t)(r1 + 8) * ld + cb);
;     const u32x4 s1 = {dpp_ror8(l1.x), dpp_ror8(l1.y), dpp_ror8(l1.z), dpp_ror8(l1.w)}, s2 = {dpp_ror8(l2.x), dpp_ror8(l2.y), dpp_ror8(l2.z), dpp_ror8(l2.w)};
;     wA = lo ? l1 : s2; wB = lo ? s1 : l2;
; }
;     __device__ __forceinline__ void operator()(const f32x4 (&acc)[2][2][4][2], const Unit& u, int wr, int wc, int fr, int fq) const {
;     ...
;                 u32x4 rr[2]; if (R) load_pair_lines(R, D, row, fr, col0, rr[0], rr[1]);
; #pragma unroll
;                 for (int bj = 0; bj < 2; ++bj) { f32x4 r0, r1;
;                     if (R) { const u32x4 rw = rr[bj]; r0 = (f32x4){bflo(rw.x), bfhi(rw.x), bflo(rw.y), bfhi(rw.y)}; r1 = (f32x4){bflo(rw.z), bfhi(rw.z), bflo(rw.w), bfhi(rw.w)}; }
;                     else { const float* rp = (row < 8192 ? src_p + off : src_s + (off - (size_t)8192 * D)) + 8 * bj; r0 = *(const f32x4*)rp; r1 = *(const f32x4*)(rp + 4); }
;                     const f32x4 o0 = r0 + acc[ai][bj][m][0] * sc, o1 = r1 + acc[ai][bj][m][1] * sc;
;                     sq += (o0[0] * o0[0] + o0[1] * o0[1]) + (o0[2] * o0[2] + o0[3] * o0[3]) + (o1[0] * o1[0] + o1[1] * o1[1]) + (o1[2] * o1[2] + o1[3] * o1[3]);
;                     w[bj].x = cvt_pk_bf16(o0[0], o0[1]); w[bj].y = cvt_pk_bf16(o0[2], o0[3]); w[bj].z = cvt_pk_bf16(o1[0], o1[1]); w[bj].w = cvt_pk_bf16(o1[2], o1[3]); }
;                 store_pair_lines(O, D, row, fr, col0, w[0], w[1]);
;                 if (ssout) { sq += __shfl_xor(sq, 16); sq += __shfl_xor(sq, 32); if (fq == 0) unsafeAtomicAdd(ssout + row, sq); } }
	v_sub_u32_e32 v185, v184, v150
	v_add_u32_e32 v186, v185, v152
	v_ashrrev_i32_e32 v187, 31, v186
	v_lshlrev_b64 v[190:191], 12, v[186:187]
	v_lshl_add_u64 v[192:193], v[190:191], 0, s[28:29]
	v_lshl_add_u64 v[186:187], s[10:11], 0, v[190:191]
	v_lshl_add_u64 v[188:189], s[10:11], 0, v[192:193]
	v_lshl_add_u64 v[186:187], v[186:187], 0, v[146:147]
	v_lshl_add_u64 v[188:189], v[188:189], 0, v[146:147]
	global_load_dwordx4 v[224:227], v[186:187], off
	global_load_dwordx4 v[228:231], v[188:189], off
	v_or_b32_e32 v194, s31, v150
	v_add_u32_e32 v184, 0x90, v194
	v_sub_u32_e32 v185, v184, v150
	v_add_u32_e32 v186, v185, v152
	v_ashrrev_i32_e32 v187, 31, v186
	v_lshlrev_b64 v[190:191], 12, v[186:187]
	v_lshl_add_u64 v[192:193], v[190:191], 0, s[28:29]
	v_lshl_add_u64 v[186:187], s[10:11], 0, v[190:191]
	v_lshl_add_u64 v[188:189], s[10:11], 0, v[192:193]
	v_lshl_add_u64 v[186:187], v[186:187], 0, v[146:147]
	v_lshl_add_u64 v[188:189], v[188:189], 0, v[146:147]
	global_load_dwordx4 v[232:235], v[186:187], off
	global_load_dwordx4 v[236:239], v[188:189], off
	v_or_b32_e32 v194, s31, v150
	v_add_u32_e32 v184, 0xa0, v194
	v_sub_u32_e32 v185, v184, v150
	v_add_u32_e32 v186, v185, v152
	v_ashrrev_i32_e32 v187, 31, v186
	v_lshlrev_b64 v[190:191], 12, v[186:187]
	v_lshl_add_u64 v[192:193], v[190:191], 0, s[28:29]
	v_lshl_add_u64 v[186:187], s[10:11], 0, v[190:191]
	v_lshl_add_u64 v[188:189], s[10:11], 0, v[192:193]
	v_lshl_add_u64 v[186:187], v[186:187], 0, v[146:147]
	v_lshl_add_u64 v[188:189], v[188:189], 0, v[146:147]
	global_load_dwordx4 v[240:243], v[186:187], off
	global_load_dwordx4 v[244:247], v[188:189], off
	v_or_b32_e32 v148, s31, v150
	s_waitcnt vmcnt(12)
	v_mov_b32_dpp v149, v158 row_ror:8 row_mask:0xf bank_mask:0xf
	v_mov_b32_dpp v157, v159 row_ror:8 row_mask:0xf bank_mask:0xf
	v_mov_b32_dpp v171, v161 row_ror:8 row_mask:0xf bank_mask:0xf
	v_mov_b32_dpp v172, v162 row_ror:8 row_mask:0xf bank_mask:0xf
	v_mov_b32_dpp v173, v163 row_ror:8 row_mask:0xf bank_mask:0xf
	v_mov_b32_dpp v170, v160 row_ror:8 row_mask:0xf bank_mask:0xf
	v_mov_b32_dpp v174, v164 row_ror:8 row_mask:0xf bank_mask:0xf
	v_mov_b32_dpp v175, v165 row_ror:8 row_mask:0xf bank_mask:0xf
	v_cndmask_b32_e64 v165, v165, v171, s[6:7]
	v_cndmask_b32_e64 v157, v163, v157, s[6:7]
	v_cndmask_b32_e64 v149, v162, v149, s[6:7]
	v_cndmask_b32_e64 v173, v173, v159, s[6:7]
	v_cndmask_b32_e64 v171, v172, v158, s[6:7]
	v_cndmask_b32_e64 v164, v164, v170, s[6:7]
	v_cndmask_b32_e64 v177, v175, v161, s[6:7]
	v_cndmask_b32_e64 v175, v174, v160, s[6:7]
	v_lshlrev_b32_e32 v158, 16, v149
	v_and_b32_e32 v159, 0xffff0000, v149
	v_lshlrev_b32_e32 v160, 16, v157
	v_and_b32_e32 v161, 0xffff0000, v157
	v_lshlrev_b32_e32 v170, 16, v171
	v_and_b32_e32 v171, 0xffff0000, v171
	v_lshlrev_b32_e32 v172, 16, v173
	v_and_b32_e32 v173, 0xffff0000, v173
	v_lshlrev_b32_e32 v174, 16, v175
	v_and_b32_e32 v175, 0xffff0000, v175
	v_pk_add_f32 v[160:161], v[118:119], v[160:161]
	v_pk_add_f32 v[158:159], v[116:117], v[158:159]
	v_pk_add_f32 v[116:117], v[126:127], v[172:173]
	v_pk_add_f32 v[118:119], v[124:125], v[170:171]
	v_lshlrev_b32_e32 v176, 16, v177
	v_and_b32_e32 v177, 0xffff0000, v177
	v_pk_add_f32 v[120:121], v[120:121], v[174:175]
	v_mul_f32_e32 v124, v119, v119
	v_mul_f32_e32 v125, v117, v117
	v_lshlrev_b32_e32 v162, 16, v164
	v_and_b32_e32 v163, 0xffff0000, v164
	v_lshlrev_b32_e32 v164, 16, v165
	v_and_b32_e32 v165, 0xffff0000, v165
	v_pk_add_f32 v[122:123], v[122:123], v[176:177]
	v_mul_f32_e32 v126, v121, v121
	v_fmac_f32_e32 v124, v118, v118
	v_fmac_f32_e32 v125, v116, v116
	v_pk_add_f32 v[114:115], v[114:115], v[164:165]
	v_mul_f32_e32 v127, v123, v123
	v_cvt_pk_bf16_f32 v119, v118, v119
	v_cvt_pk_bf16_f32 v117, v116, v117
	v_cvt_pk_bf16_f32 v121, v120, v121
	v_fmac_f32_e32 v126, v120, v120
	v_add_f32_e32 v116, v124, v125
	v_pk_add_f32 v[112:113], v[112:113], v[162:163]
	v_cvt_pk_bf16_f32 v123, v122, v123
	v_cvt_pk_bf16_f32 v149, v158, v159
	v_cvt_pk_bf16_f32 v157, v160, v161
	v_fmac_f32_e32 v127, v122, v122
	v_cvt_pk_bf16_f32 v162, v112, v113
	v_cvt_pk_bf16_f32 v163, v114, v115
	v_add_f32_e32 v116, v126, v116
	v_mov_b32_dpp v182, v149 row_ror:8 row_mask:0xf bank_mask:0xf
	v_mov_b32_dpp v120, v163 row_ror:8 row_mask:0xf bank_mask:0xf
	v_mul_f32_e32 v115, v115, v115
	v_mov_b32_dpp v178, v119 row_ror:8 row_mask:0xf bank_mask:0xf
	v_mov_b32_dpp v181, v123 row_ror:8 row_mask:0xf bank_mask:0xf
	v_add_f32_e32 v122, v127, v116
	v_cndmask_b32_e64 v116, v182, v119, s[6:7]
	v_cndmask_b32_e64 v119, v120, v123, s[6:7]
	v_fmac_f32_e32 v115, v114, v114
	v_mul_f32_e32 v114, v159, v159
	v_mul_f32_e32 v123, v161, v161
	v_fmac_f32_e32 v114, v158, v158
	v_fmac_f32_e32 v123, v160, v160
	v_mul_f32_e32 v113, v113, v113
	v_add_f32_e32 v114, v114, v123
	v_fmac_f32_e32 v113, v112, v112
	v_add_f32_e32 v112, v113, v114
	v_add_f32_e32 v112, v115, v112
	v_and_b32_e32 v113, 64, v203
	v_add_f32_e32 v115, v112, v122
	v_xor_b32_e32 v112, 16, v203
	v_add_u32_e32 v126, 64, v113
	v_cmp_lt_i32_e32 vcc, v112, v126
	v_mov_b32_e32 v118, 0
	v_mov_b32_dpp v183, v157 row_ror:8 row_mask:0xf bank_mask:0xf
	v_cndmask_b32_e32 v112, v203, v112, vcc
	v_lshlrev_b32_e32 v114, 2, v112
	ds_bpermute_b32 v127, v114, v115
	v_lshl_add_u64 v[112:113], s[16:17], 0, v[166:167]
	v_lshl_add_u64 v[124:125], v[112:113], 0, v[146:147]
	v_xor_b32_e32 v113, 32, v203
	v_cmp_lt_i32_e32 vcc, v113, v126
	s_waitcnt lgkmcnt(0)
	v_add_f32_e32 v112, v115, v127
	v_mov_b32_dpp v118, v162 row_ror:8 row_mask:0xf bank_mask:0xf
	v_cndmask_b32_e32 v113, v203, v113, vcc
	v_lshlrev_b32_e32 v115, 2, v113
	ds_bpermute_b32 v113, v115, v112
	v_mov_b32_dpp v179, v117 row_ror:8 row_mask:0xf bank_mask:0xf
	v_cndmask_b32_e64 v117, v183, v117, s[6:7]
	v_cndmask_b32_e64 v118, v118, v121, s[6:7]
	v_mov_b32_dpp v180, v121 row_ror:8 row_mask:0xf bank_mask:0xf
	global_store_dwordx4 v[124:125], v[116:119], off
	v_cndmask_b32_e64 v120, v149, v178, s[6:7]
	v_cndmask_b32_e64 v121, v157, v179, s[6:7]
	v_lshl_add_u64 v[116:117], s[16:17], 0, v[168:169]
	v_cndmask_b32_e64 v122, v162, v180, s[6:7]
	v_cndmask_b32_e64 v123, v163, v181, s[6:7]
	v_lshl_add_u64 v[116:117], v[116:117], 0, v[146:147]
	global_store_dwordx4 v[116:117], v[120:123], off
	s_and_saveexec_b64 s[42:43], s[8:9]
	s_cbranch_execz .LBB0_1248
	v_ashrrev_i32_e32 v149, 31, v148
	s_waitcnt lgkmcnt(0)
	v_add_f32_e32 v116, v112, v113
	v_lshl_add_u64 v[112:113], v[148:149], 2, s[18:19]
	global_atomic_add_f32 v[112:113], v116, off

; #define PG8_STAGE(bufoff, gbase, voff) do { _Pragma("unroll") for (int _i = 0; _i < 2; ++_i) \
;         __builtin_amdgcn_global_load_lds((const unsigned*)((const char*)(gbase) + (voff)[_i]), (LAS unsigned*)(lds + (bufoff) + ldsw + _i * 8192), 16, 0, 0); } while (0)
; #define PG8_LDA(dst, b, h) do { _Pragma("unroll") for (int m = 0; m < 4; ++m) _Pragma("unroll") for (int k = 0; k < 2; ++k) dst[m][k] = *(const LAS bf16x8*)(lds + PG8_SA(b, h) + aoff + m * 2048 + k * 1024); } while (0)
; #define PG8_LDB(dst, b, h) do { _Pragma("unroll") for (int n = 0; n < 2; ++n) _Pragma("unroll") for (int k = 0; k < 2; ++k) dst[n][k] = *(const LAS bf16x8*)(lds + PG8_SB(b, h) + boff + n * 2048 + k * 1024); } while (0)
; #define PG8_MMA(ai, bj, At, Bt) do { __builtin_amdgcn_s_setprio(1); _Pragma("unroll") for (int m = 0; m < 4; ++m) _Pragma("unroll") for (int n = 0; n < 2; ++n) _Pragma("unroll") for (int k = 0; k < 2; ++k) \
;         acc[ai][bj][m][n] = __builtin_amdgcn_mfma_f32_16x16x32_bf16(Bt[n][k], At[m][k], acc[ai][bj][m][n], 0, 0, 0); __builtin_amdgcn_s_setprio(0); } while (0)
; #define PG8_WAIT_V(n) asm volatile("s_waitcnt vmcnt(" #n ")" ::: "memory")
; #define PG8_WAIT_L(n) asm volatile("s_waitcnt lgkmcnt(" #n ")" ::: "memory")
; #define PG8_BAR __builtin_amdgcn_s_barrier()
; template <class Epi>
; __device__ __forceinline__ void gemm_phase(LAS unsigned char* lds, const Gemm g, const StaticOrder& S, const Epi& E) {
;     ...
;         for (int t = 0; t < nt; t += 2) {
;             const bool last = (t == nt - 2);
;             const char* a1 = cA + (size_t)(t + 1) * kstep;
;             const char* a2 = last ? nA : cA + (size_t)(t + 2) * kstep; const char* b2 = last ? nB : cB + (size_t)(t + 2) * kstep;
;             const char* a3 = a2 + kstep; const char* b3 = b2 + kstep;
;             PG8_LDB(B0, 0, 0); PG8_SCHED; PG8_LDA(At, 0, 0); PG8_STAGE(PG8_SA(1, 1), a1 + hstep, voffA);
;             PG8_WAIT_L(8); PG8_BAR; PG8_WAIT_L(0); PG8_MMA(0, 0, At, B0); PG8_BAR; PG8_SCHED;
;             PG8_LDB(B1, 0, 1); PG8_STAGE(PG8_SB(0, 0), b2, voffB0);
;             PG8_BAR; PG8_WAIT_L(0); PG8_MMA(0, 1, At, B1); PG8_BAR;
;             PG8_LDA(At, 0, 1); PG8_STAGE(PG8_SA(0, 0), a2, voffA);
;             PG8_BAR; PG8_WAIT_L(0); PG8_MMA(1, 0, At, B0); PG8_BAR; PG8_SCHED;
;             PG8_STAGE(PG8_SB(0, 1), b2, voffB1);
;             PG8_WAIT_V(6); PG8_BAR; PG8_MMA(1, 1, At, B1); PG8_BAR;
.LBB0_1365:
	ds_read_b128 v[160:163], v157
	ds_read_b128 v[164:167], v157 offset:1024
	ds_read_b128 v[168:171], v157 offset:2048
	ds_read_b128 v[172:175], v157 offset:3072
	s_add_u32 s33, s38, 0xfff80080
	s_addc_u32 s40, s39, -1
	s_cmp_eq_u32 s64, 28
	s_cselect_b32 s41, s27, s40
	s_cselect_b32 s40, s60, s33
	s_cselect_b32 s43, s19, s63
	s_cselect_b32 s42, s61, s62
	v_lshl_add_u64 v[200:201], s[38:39], 0, v[140:141]
	s_add_i32 m0, s37, 0xc000
	ds_read_b128 v[176:179], v158
	ds_read_b128 v[180:183], v158 offset:1024
	ds_read_b128 v[184:187], v158 offset:2048
	ds_read_b128 v[188:191], v158 offset:3072
	ds_read_b128 v[192:195], v158 offset:4096
	ds_read_b128 v[196:199], v158 offset:5120
	ds_read_b128 v[204:207], v158 offset:6144
	ds_read_b128 v[208:211], v158 offset:7168
	global_load_lds_dwordx4 v[200:201], off
	v_lshl_add_u64 v[200:201], s[38:39], 0, v[142:143]
	s_add_i32 m0, s37, 0xe000
	s_nop 0
	global_load_lds_dwordx4 v[200:201], off
	s_waitcnt lgkmcnt(8)
	s_barrier
	s_waitcnt lgkmcnt(0)
	v_mfma_f32_16x16x32_bf16 v[124:127], v[160:163], v[176:179], v[124:127]
	v_mfma_f32_16x16x32_bf16 v[120:123], v[168:171], v[176:179], v[120:123]
	v_mfma_f32_16x16x32_bf16 v[108:111], v[160:163], v[184:187], v[108:111]
	v_mfma_f32_16x16x32_bf16 v[104:107], v[168:171], v[184:187], v[104:107]
	v_mfma_f32_16x16x32_bf16 v[92:95], v[160:163], v[192:195], v[92:95]
	v_mfma_f32_16x16x32_bf16 v[88:91], v[168:171], v[192:195], v[88:91]
	v_mfma_f32_16x16x32_bf16 v[76:79], v[160:163], v[204:207], v[76:79]
	v_mfma_f32_16x16x32_bf16 v[72:75], v[168:171], v[204:207], v[72:75]
	v_mfma_f32_16x16x32_bf16 v[124:127], v[164:167], v[180:183], v[124:127]
	v_mfma_f32_16x16x32_bf16 v[120:123], v[172:175], v[180:183], v[120:123]
	v_mfma_f32_16x16x32_bf16 v[108:111], v[164:167], v[188:191], v[108:111]
	v_mfma_f32_16x16x32_bf16 v[104:107], v[172:175], v[188:191], v[104:107]
	v_mfma_f32_16x16x32_bf16 v[92:95], v[164:167], v[196:199], v[92:95]
	v_mfma_f32_16x16x32_bf16 v[88:91], v[172:175], v[196:199], v[88:91]
	v_mfma_f32_16x16x32_bf16 v[76:79], v[164:167], v[208:211], v[76:79]
	v_mfma_f32_16x16x32_bf16 v[72:75], v[172:175], v[208:211], v[72:75]
	s_barrier
	s_add_i32 s33, s56, s46
	v_lshl_add_u64 v[200:201], s[42:43], 0, v[130:131]
	s_mov_b32 m0, s33
	ds_read_b128 v[212:215], v159
	ds_read_b128 v[216:219], v159 offset:1024
	ds_read_b128 v[220:223], v159 offset:2048
	ds_read_b128 v[224:227], v159 offset:3072
	global_load_lds_dwordx4 v[200:201], off
	v_lshl_add_u64 v[228:229], s[42:43], 0, v[136:137]
	s_add_i32 m0, s33, 0x2000
	s_nop 0
	global_load_lds_dwordx4 v[228:229], off
	s_waitcnt lgkmcnt(0)
	s_barrier
	s_waitcnt lgkmcnt(0)
	v_mfma_f32_16x16x32_bf16 v[116:119], v[212:215], v[176:179], v[116:119]
	v_mfma_f32_16x16x32_bf16 v[112:115], v[220:223], v[176:179], v[112:115]
	v_mfma_f32_16x16x32_bf16 v[100:103], v[212:215], v[184:187], v[100:103]
	v_mfma_f32_16x16x32_bf16 v[96:99], v[220:223], v[184:187], v[96:99]
	v_mfma_f32_16x16x32_bf16 v[84:87], v[212:215], v[192:195], v[84:87]
	v_mfma_f32_16x16x32_bf16 v[80:83], v[220:223], v[192:195], v[80:83]
	v_mfma_f32_16x16x32_bf16 v[68:71], v[212:215], v[204:207], v[68:71]
	v_mfma_f32_16x16x32_bf16 v[64:67], v[220:223], v[204:207], v[64:67]
	v_mfma_f32_16x16x32_bf16 v[116:119], v[216:219], v[180:183], v[116:119]
	v_mfma_f32_16x16x32_bf16 v[112:115], v[224:227], v[180:183], v[112:115]
	v_mfma_f32_16x16x32_bf16 v[100:103], v[216:219], v[188:191], v[100:103]
	v_mfma_f32_16x16x32_bf16 v[96:99], v[224:227], v[188:191], v[96:99]
	v_mfma_f32_16x16x32_bf16 v[84:87], v[216:219], v[196:199], v[84:87]
	v_mfma_f32_16x16x32_bf16 v[80:83], v[224:227], v[196:199], v[80:83]
	v_mfma_f32_16x16x32_bf16 v[68:71], v[216:219], v[208:211], v[68:71]
	v_mfma_f32_16x16x32_bf16 v[64:67], v[224:227], v[208:211], v[64:67]
	s_mov_b32 m0, s37
	v_lshl_add_u64 v[230:231], s[40:41], 0, v[128:129]
	s_barrier
	ds_read_b128 v[176:179], v158 offset:16384
	ds_read_b128 v[180:183], v158 offset:17408
	ds_read_b128 v[184:187], v158 offset:18432
	ds_read_b128 v[188:191], v158 offset:19456
	ds_read_b128 v[192:195], v158 offset:20480
	ds_read_b128 v[196:199], v158 offset:21504
	ds_read_b128 v[204:207], v158 offset:22528
	ds_read_b128 v[208:211], v158 offset:23552
	global_load_lds_dwordx4 v[230:231], off
	v_lshl_add_u64 v[232:233], s[40:41], 0, v[134:135]
	s_mov_b32 m0, s47
	s_nop 0
	global_load_lds_dwordx4 v[232:233], off
	s_add_i32 s33, s57, s46
	v_lshl_add_u64 v[234:235], s[42:43], 0, v[132:133]
	s_mov_b32 m0, s33
	v_lshl_add_u64 v[236:237], s[42:43], 0, v[138:139]
	global_load_lds_dwordx4 v[234:235], off
	s_add_i32 m0, s33, 0x2000
	s_nop 0
	global_load_lds_dwordx4 v[236:237], off
	s_waitcnt vmcnt(6)
	s_barrier
; #define PG8_STAGE(bufoff, gbase, voff) do { _Pragma("unroll") for (int _i = 0; _i < 2; ++_i) \
;         __builtin_amdgcn_global_load_lds((const unsigned*)((const char*)(gbase) + (voff)[_i]), (LAS unsigned*)(lds + (bufoff) + ldsw + _i * 8192), 16, 0, 0); } while (0)
; #define PG8_LDA(dst, b, h) do { _Pragma("unroll") for (int m = 0; m < 4; ++m) _Pragma("unroll") for (int k = 0; k < 2; ++k) dst[m][k] = *(const LAS bf16x8*)(lds + PG8_SA(b, h) + aoff + m * 2048 + k * 1024); } while (0)
; #define PG8_LDB(dst, b, h) do { _Pragma("unroll") for (int n = 0; n < 2; ++n) _Pragma("unroll") for (int k = 0; k < 2; ++k) dst[n][k] = *(const LAS bf16x8*)(lds + PG8_SB(b, h) + boff + n * 2048 + k * 1024); } while (0)
; #define PG8_MMA(ai, bj, At, Bt) do { __builtin_amdgcn_s_setprio(1); _Pragma("unroll") for (int m = 0; m < 4; ++m) _Pragma("unroll") for (int n = 0; n < 2; ++n) _Pragma("unroll") for (int k = 0; k < 2; ++k) \
;         acc[ai][bj][m][n] = __builtin_amdgcn_mfma_f32_16x16x32_bf16(Bt[n][k], At[m][k], acc[ai][bj][m][n], 0, 0, 0); __builtin_amdgcn_s_setprio(0); } while (0)
; #define PG8_WAIT_V(n) asm volatile("s_waitcnt vmcnt(" #n ")" ::: "memory")
; #define PG8_WAIT_L(n) asm volatile("s_waitcnt lgkmcnt(" #n ")" ::: "memory")
; #define PG8_BAR __builtin_amdgcn_s_barrier()
; #define PG8_SCHED __builtin_amdgcn_sched_barrier(0)
; template <class Epi>
; __device__ __forceinline__ void gemm_phase(LAS unsigned char* lds, const Gemm g, const StaticOrder& S, const Epi& E) {
;     ...
;             PG8_BAR; PG8_WAIT_L(0); PG8_MMA(1, 0, At, B0); PG8_BAR; PG8_SCHED;
;             PG8_STAGE(PG8_SB(0, 1), b2, voffB1);
;             PG8_WAIT_V(6); PG8_BAR; PG8_MMA(1, 1, At, B1); PG8_BAR;
;             PG8_LDB(B0, 1, 0); PG8_SCHED; PG8_LDA(At, 1, 0); PG8_STAGE(PG8_SA(0, 1), a2 + hstep, voffA);
;             PG8_WAIT_L(8); PG8_BAR; PG8_WAIT_L(0); PG8_MMA(0, 0, At, B0); PG8_BAR; PG8_SCHED;
;             PG8_LDB(B1, 1, 1); PG8_STAGE(PG8_SB(1, 0), b3, voffB0);
;             PG8_BAR; PG8_WAIT_L(0); PG8_MMA(0, 1, At, B1); PG8_BAR;
;             PG8_LDA(At, 1, 1); PG8_STAGE(PG8_SA(1, 0), a3, voffA);
;             PG8_BAR; PG8_WAIT_L(0); PG8_MMA(1, 0, At, B0); PG8_BAR; PG8_SCHED;
	s_waitcnt lgkmcnt(0)
	v_mfma_f32_16x16x32_bf16 v[60:63], v[160:163], v[176:179], v[60:63]
	v_mfma_f32_16x16x32_bf16 v[56:59], v[168:171], v[176:179], v[56:59]
	v_mfma_f32_16x16x32_bf16 v[44:47], v[160:163], v[184:187], v[44:47]
	v_mfma_f32_16x16x32_bf16 v[40:43], v[168:171], v[184:187], v[40:43]
	v_mfma_f32_16x16x32_bf16 v[28:31], v[160:163], v[192:195], v[28:31]
	v_mfma_f32_16x16x32_bf16 v[24:27], v[168:171], v[192:195], v[24:27]
	v_mfma_f32_16x16x32_bf16 v[12:15], v[160:163], v[204:207], v[12:15]
	v_mfma_f32_16x16x32_bf16 v[8:11], v[168:171], v[204:207], v[8:11]
	v_mfma_f32_16x16x32_bf16 v[60:63], v[164:167], v[180:183], v[60:63]
	v_mfma_f32_16x16x32_bf16 v[56:59], v[172:175], v[180:183], v[56:59]
	v_mfma_f32_16x16x32_bf16 v[44:47], v[164:167], v[188:191], v[44:47]
	v_mfma_f32_16x16x32_bf16 v[40:43], v[172:175], v[188:191], v[40:43]
	v_mfma_f32_16x16x32_bf16 v[28:31], v[164:167], v[196:199], v[28:31]
	v_mfma_f32_16x16x32_bf16 v[24:27], v[172:175], v[196:199], v[24:27]
	v_mfma_f32_16x16x32_bf16 v[12:15], v[164:167], v[208:211], v[12:15]
	v_mfma_f32_16x16x32_bf16 v[8:11], v[172:175], v[208:211], v[8:11]
	v_mfma_f32_16x16x32_bf16 v[52:55], v[212:215], v[176:179], v[52:55]
	v_mfma_f32_16x16x32_bf16 v[48:51], v[220:223], v[176:179], v[48:51]
	v_mfma_f32_16x16x32_bf16 v[36:39], v[212:215], v[184:187], v[36:39]
	v_mfma_f32_16x16x32_bf16 v[32:35], v[220:223], v[184:187], v[32:35]
	v_mfma_f32_16x16x32_bf16 v[20:23], v[212:215], v[192:195], v[20:23]
	v_mfma_f32_16x16x32_bf16 v[16:19], v[220:223], v[192:195], v[16:19]
	v_mfma_f32_16x16x32_bf16 v[4:7], v[212:215], v[204:207], v[4:7]
	v_mfma_f32_16x16x32_bf16 v[0:3], v[220:223], v[204:207], v[0:3]
	v_mfma_f32_16x16x32_bf16 v[52:55], v[216:219], v[180:183], v[52:55]
	v_mfma_f32_16x16x32_bf16 v[48:51], v[224:227], v[180:183], v[48:51]
	v_mfma_f32_16x16x32_bf16 v[36:39], v[216:219], v[188:191], v[36:39]
	v_mfma_f32_16x16x32_bf16 v[32:35], v[224:227], v[188:191], v[32:35]
	v_mfma_f32_16x16x32_bf16 v[20:23], v[216:219], v[196:199], v[20:23]
	v_mfma_f32_16x16x32_bf16 v[16:19], v[224:227], v[196:199], v[16:19]
	v_mfma_f32_16x16x32_bf16 v[4:7], v[216:219], v[208:211], v[4:7]
	v_mfma_f32_16x16x32_bf16 v[0:3], v[224:227], v[208:211], v[0:3]
	s_add_i32 s33, 0, 0x18000
	v_add_u32_e32 v172, s33, v147
	s_barrier
	ds_read_b128 v[160:163], v172
	ds_read_b128 v[164:167], v172 offset:1024
	ds_read_b128 v[168:171], v172 offset:2048
	ds_read_b128 v[172:175], v172 offset:3072
	s_add_u32 s40, s40, 0x80000
	s_addc_u32 s41, s41, 0
	s_mov_b32 m0, s48
	v_lshl_add_u64 v[212:213], s[40:41], 0, v[128:129]
	ds_read_b128 v[176:179], v158 offset:32768
	ds_read_b128 v[180:183], v158 offset:33792
	ds_read_b128 v[184:187], v158 offset:34816
	ds_read_b128 v[188:191], v158 offset:35840
	ds_read_b128 v[192:195], v158 offset:36864
	ds_read_b128 v[196:199], v158 offset:37888
	ds_read_b128 v[204:207], v158 offset:38912
	ds_read_b128 v[208:211], v158 offset:39936
	global_load_lds_dwordx4 v[212:213], off
	v_lshl_add_u64 v[212:213], s[40:41], 0, v[134:135]
	s_mov_b32 m0, s49
	s_nop 0
	global_load_lds_dwordx4 v[212:213], off
	s_waitcnt lgkmcnt(8)
	s_barrier
	s_waitcnt lgkmcnt(0)
	v_mfma_f32_16x16x32_bf16 v[124:127], v[160:163], v[176:179], v[124:127]
	v_mfma_f32_16x16x32_bf16 v[120:123], v[168:171], v[176:179], v[120:123]
	v_mfma_f32_16x16x32_bf16 v[108:111], v[160:163], v[184:187], v[108:111]
	v_mfma_f32_16x16x32_bf16 v[104:107], v[168:171], v[184:187], v[104:107]
	v_mfma_f32_16x16x32_bf16 v[92:95], v[160:163], v[192:195], v[92:95]
	v_mfma_f32_16x16x32_bf16 v[88:91], v[168:171], v[192:195], v[88:91]
	v_mfma_f32_16x16x32_bf16 v[76:79], v[160:163], v[204:207], v[76:79]
	v_mfma_f32_16x16x32_bf16 v[72:75], v[168:171], v[204:207], v[72:75]
	v_mfma_f32_16x16x32_bf16 v[124:127], v[164:167], v[180:183], v[124:127]
	v_mfma_f32_16x16x32_bf16 v[120:123], v[172:175], v[180:183], v[120:123]
	v_mfma_f32_16x16x32_bf16 v[108:111], v[164:167], v[188:191], v[108:111]
	v_mfma_f32_16x16x32_bf16 v[104:107], v[172:175], v[188:191], v[104:107]
	v_mfma_f32_16x16x32_bf16 v[92:95], v[164:167], v[196:199], v[92:95]
	v_mfma_f32_16x16x32_bf16 v[88:91], v[172:175], v[196:199], v[88:91]
	v_mfma_f32_16x16x32_bf16 v[76:79], v[164:167], v[208:211], v[76:79]
	v_mfma_f32_16x16x32_bf16 v[72:75], v[172:175], v[208:211], v[72:75]
	s_barrier
	s_add_i32 s40, 0, 0x1c000
	s_add_i32 s33, s33, s46
	v_add_u32_e32 v203, s40, v147
	v_lshl_add_u64 v[200:201], v[200:201], 0, s[16:17]
	s_mov_b32 m0, s33
	ds_read_b128 v[212:215], v203
	ds_read_b128 v[216:219], v203 offset:1024
	ds_read_b128 v[220:223], v203 offset:2048
	ds_read_b128 v[224:227], v203 offset:3072
	global_load_lds_dwordx4 v[200:201], off
	v_lshl_add_u64 v[200:201], v[228:229], 0, s[16:17]
	s_add_i32 m0, s33, 0x2000
	s_nop 0
	global_load_lds_dwordx4 v[200:201], off
	s_waitcnt lgkmcnt(0)
	s_barrier
	s_waitcnt lgkmcnt(0)
	v_mfma_f32_16x16x32_bf16 v[116:119], v[212:215], v[176:179], v[116:119]
	v_mfma_f32_16x16x32_bf16 v[112:115], v[220:223], v[176:179], v[112:115]
	v_mfma_f32_16x16x32_bf16 v[100:103], v[212:215], v[184:187], v[100:103]
	v_mfma_f32_16x16x32_bf16 v[96:99], v[220:223], v[184:187], v[96:99]
	v_mfma_f32_16x16x32_bf16 v[84:87], v[212:215], v[192:195], v[84:87]
	v_mfma_f32_16x16x32_bf16 v[80:83], v[220:223], v[192:195], v[80:83]
	v_mfma_f32_16x16x32_bf16 v[68:71], v[212:215], v[204:207], v[68:71]
	v_mfma_f32_16x16x32_bf16 v[64:67], v[220:223], v[204:207], v[64:67]
	v_mfma_f32_16x16x32_bf16 v[116:119], v[216:219], v[180:183], v[116:119]
	v_mfma_f32_16x16x32_bf16 v[112:115], v[224:227], v[180:183], v[112:115]
	v_mfma_f32_16x16x32_bf16 v[100:103], v[216:219], v[188:191], v[100:103]
	v_mfma_f32_16x16x32_bf16 v[96:99], v[224:227], v[188:191], v[96:99]
	v_mfma_f32_16x16x32_bf16 v[84:87], v[216:219], v[196:199], v[84:87]
	v_mfma_f32_16x16x32_bf16 v[80:83], v[224:227], v[196:199], v[80:83]
	v_mfma_f32_16x16x32_bf16 v[68:71], v[216:219], v[208:211], v[68:71]
	v_mfma_f32_16x16x32_bf16 v[64:67], v[224:227], v[208:211], v[64:67]
	s_mov_b32 m0, s51
	v_lshl_add_u64 v[200:201], v[230:231], 0, s[16:17]
	s_barrier
; __device__ __forceinline__ unsigned cvt_pk_bf16(float lo, float hi) { unsigned r; asm volatile("v_cvt_pk_bf16_f32 %0, %1, %2" : "=v"(r) : "v"(lo), "v"(hi)); return r; }
; #define PG8_STAGE(bufoff, gbase, voff) do { _Pragma("unroll") for (int _i = 0; _i < 2; ++_i) \
;         __builtin_amdgcn_global_load_lds((const unsigned*)((const char*)(gbase) + (voff)[_i]), (LAS unsigned*)(lds + (bufoff) + ldsw + _i * 8192), 16, 0, 0); } while (0)
; #define PG8_LDA(dst, b, h) do { _Pragma("unroll") for (int m = 0; m < 4; ++m) _Pragma("unroll") for (int k = 0; k < 2; ++k) dst[m][k] = *(const LAS bf16x8*)(lds + PG8_SA(b, h) + aoff + m * 2048 + k * 1024); } while (0)
; #define PG8_MMA(ai, bj, At, Bt) do { __builtin_amdgcn_s_setprio(1); _Pragma("unroll") for (int m = 0; m < 4; ++m) _Pragma("unroll") for (int n = 0; n < 2; ++n) _Pragma("unroll") for (int k = 0; k < 2; ++k) \
;         acc[ai][bj][m][n] = __builtin_amdgcn_mfma_f32_16x16x32_bf16(Bt[n][k], At[m][k], acc[ai][bj][m][n], 0, 0, 0); __builtin_amdgcn_s_setprio(0); } while (0)
; #define PG8_WAIT_V(n) asm volatile("s_waitcnt vmcnt(" #n ")" ::: "memory")
; #define PG8_WAIT_L(n) asm volatile("s_waitcnt lgkmcnt(" #n ")" ::: "memory")
;     __device__ __forceinline__ void operator()(const f32x4 (&acc)[2][2][4][2], const Unit& u, int wr, int wc, int fr, int fq) const {
;     ...
;                     if (ACT == 1) {
; #pragma unroll
;                         for (int j = 0; j < 4; ++j) { const float a = fmaxf(v0[j], 0.f), b = fmaxf(v1[j], 0.f); v0[j] = a * a; v1[j] = b * b; } }
;                     sq += (v0[0] * v0[0] + v0[1] * v0[1]) + (v0[2] * v0[2] + v0[3] * v0[3]) + (v1[0] * v1[0] + v1[1] * v1[1]) + (v1[2] * v1[2] + v1[3] * v1[3]);
;                     w[bj].x = cvt_pk_bf16(v0[0], v0[1]); w[bj].y = cvt_pk_bf16(v0[2], v0[3]); w[bj].z = cvt_pk_bf16(v1[0], v1[1]); w[bj].w = cvt_pk_bf16(v1[2], v1[3]); }
;                 store_pair_lines(O, ldc, row, fr, col0, w[0], w[1]);
; template <class Epi>
; __device__ __forceinline__ void gemm_phase(LAS unsigned char* lds, const Gemm g, const StaticOrder& S, const Epi& E) {
;     ...
;             PG8_LDA(At, 1, 1); PG8_STAGE(PG8_SA(1, 0), a3, voffA);
;             PG8_BAR; PG8_WAIT_L(0); PG8_MMA(1, 0, At, B0); PG8_BAR; PG8_SCHED;
;             PG8_STAGE(PG8_SB(1, 1), b3, voffB1);
;             PG8_WAIT_V(6); PG8_BAR; PG8_MMA(1, 1, At, B1); PG8_BAR;
;         }
	ds_read_b128 v[176:179], v158 offset:49152
	ds_read_b128 v[180:183], v158 offset:50176
	ds_read_b128 v[184:187], v158 offset:51200
	ds_read_b128 v[188:191], v158 offset:52224
	ds_read_b128 v[192:195], v158 offset:53248
	ds_read_b128 v[196:199], v158 offset:54272
	ds_read_b128 v[204:207], v158 offset:55296
	ds_read_b128 v[208:211], v158 offset:56320
	global_load_lds_dwordx4 v[200:201], off
	v_lshl_add_u64 v[200:201], v[232:233], 0, s[16:17]
	s_mov_b32 m0, s52
	s_nop 0
	global_load_lds_dwordx4 v[200:201], off
	s_add_i32 s33, s40, s46
	v_lshl_add_u64 v[250:251], v[234:235], 0, s[16:17]
	s_mov_b32 m0, s33
	s_nop 0
	global_load_lds_dwordx4 v[250:251], off
	v_lshl_add_u64 v[250:251], v[236:237], 0, s[16:17]
	s_add_i32 m0, s33, 0x2000
	s_nop 0
	global_load_lds_dwordx4 v[250:251], off
	s_waitcnt vmcnt(6)
	s_barrier
	s_waitcnt lgkmcnt(0)
	v_mfma_f32_16x16x32_bf16 v[60:63], v[160:163], v[176:179], v[60:63]
	v_mfma_f32_16x16x32_bf16 v[56:59], v[168:171], v[176:179], v[56:59]
	v_mfma_f32_16x16x32_bf16 v[44:47], v[160:163], v[184:187], v[44:47]
	v_mfma_f32_16x16x32_bf16 v[40:43], v[168:171], v[184:187], v[40:43]
	v_mfma_f32_16x16x32_bf16 v[28:31], v[160:163], v[192:195], v[28:31]
	v_mfma_f32_16x16x32_bf16 v[24:27], v[168:171], v[192:195], v[24:27]
	v_mfma_f32_16x16x32_bf16 v[12:15], v[160:163], v[204:207], v[12:15]
	v_mfma_f32_16x16x32_bf16 v[8:11], v[168:171], v[204:207], v[8:11]
	v_mfma_f32_16x16x32_bf16 v[60:63], v[164:167], v[180:183], v[60:63]
	v_mfma_f32_16x16x32_bf16 v[56:59], v[172:175], v[180:183], v[56:59]
	v_mfma_f32_16x16x32_bf16 v[44:47], v[164:167], v[188:191], v[44:47]
	v_mfma_f32_16x16x32_bf16 v[40:43], v[172:175], v[188:191], v[40:43]
	v_mfma_f32_16x16x32_bf16 v[28:31], v[164:167], v[196:199], v[28:31]
	v_mfma_f32_16x16x32_bf16 v[24:27], v[172:175], v[196:199], v[24:27]
	v_mfma_f32_16x16x32_bf16 v[12:15], v[164:167], v[208:211], v[12:15]
	v_mfma_f32_16x16x32_bf16 v[8:11], v[172:175], v[208:211], v[8:11]
	v_mfma_f32_16x16x32_bf16 v[52:55], v[212:215], v[176:179], v[52:55]
	v_mfma_f32_16x16x32_bf16 v[48:51], v[220:223], v[176:179], v[48:51]
	v_mfma_f32_16x16x32_bf16 v[36:39], v[212:215], v[184:187], v[36:39]
	v_mfma_f32_16x16x32_bf16 v[32:35], v[220:223], v[184:187], v[32:35]
	v_mfma_f32_16x16x32_bf16 v[20:23], v[212:215], v[192:195], v[20:23]
	v_mfma_f32_16x16x32_bf16 v[16:19], v[220:223], v[192:195], v[16:19]
	v_mfma_f32_16x16x32_bf16 v[4:7], v[212:215], v[204:207], v[4:7]
	v_mfma_f32_16x16x32_bf16 v[0:3], v[220:223], v[204:207], v[0:3]
	v_mfma_f32_16x16x32_bf16 v[52:55], v[216:219], v[180:183], v[52:55]
	v_mfma_f32_16x16x32_bf16 v[48:51], v[224:227], v[180:183], v[48:51]
	v_mfma_f32_16x16x32_bf16 v[36:39], v[216:219], v[188:191], v[36:39]
	v_mfma_f32_16x16x32_bf16 v[32:35], v[224:227], v[188:191], v[32:35]
	v_mfma_f32_16x16x32_bf16 v[20:23], v[216:219], v[196:199], v[20:23]
	v_mfma_f32_16x16x32_bf16 v[16:19], v[224:227], v[196:199], v[16:19]
	v_mfma_f32_16x16x32_bf16 v[4:7], v[216:219], v[208:211], v[4:7]
	v_mfma_f32_16x16x32_bf16 v[0:3], v[224:227], v[208:211], v[0:3]
	s_add_i32 s64, s64, 2
	s_add_u32 s38, s38, 0x100
	s_addc_u32 s39, s39, 0
	s_add_u32 s62, s62, 0x100
	s_addc_u32 s63, s63, 0
	s_cmp_gt_u32 s64, 29
	s_barrier
	s_cbranch_scc0 .LBB0_1365
	v_max_f32_e32 v124, 0, v124
	v_max_f32_e32 v120, 0, v120
	v_max_f32_e32 v125, 0, v125
	v_max_f32_e32 v121, 0, v121
	v_max_f32_e32 v122, 0, v122
	v_max_f32_e32 v118, 0, v118
	v_max_f32_e32 v119, 0, v119
	v_mul_f32_e32 v124, v124, v124
	v_mul_f32_e32 v120, v120, v120
	v_mul_f32_e32 v125, v125, v125
	v_mul_f32_e32 v121, v121, v121
	v_max_f32_e32 v126, 0, v126
	v_mul_f32_e32 v122, v122, v122
	v_max_f32_e32 v127, 0, v127
	v_max_f32_e32 v123, 0, v123
	v_max_f32_e32 v116, 0, v116
	v_max_f32_e32 v112, 0, v112
	v_max_f32_e32 v117, 0, v117
	v_max_f32_e32 v113, 0, v113
	v_max_f32_e32 v114, 0, v114
	v_mul_f32_e32 v118, v118, v118
	v_mul_f32_e32 v119, v119, v119
	s_lshl_b32 s19, s36, 8
	v_mul_f32_e32 v126, v126, v126
	v_mul_f32_e32 v127, v127, v127
	v_mul_f32_e32 v123, v123, v123
	v_cvt_pk_bf16_f32 v124, v124, v125
	v_cvt_pk_bf16_f32 v125, v126, v127
	v_cvt_pk_bf16_f32 v120, v120, v121
	v_cvt_pk_bf16_f32 v121, v122, v123
	v_mul_f32_e32 v116, v116, v116
	v_mul_f32_e32 v112, v112, v112
	v_mul_f32_e32 v117, v117, v117
	v_mul_f32_e32 v113, v113, v113
	v_mul_f32_e32 v114, v114, v114
	v_max_f32_e32 v115, 0, v115
	v_cvt_pk_bf16_f32 v122, v116, v117
	v_cvt_pk_bf16_f32 v119, v118, v119
	s_add_i32 s19, s19, s53
	v_mul_f32_e32 v115, v115, v115
	v_cvt_pk_bf16_f32 v112, v112, v113
	v_cvt_pk_bf16_f32 v113, v114, v115
	v_mov_b32_dpp v118, v124 row_ror:8 row_mask:0xf bank_mask:0xf
	v_mov_b32_dpp v123, v125 row_ror:8 row_mask:0xf bank_mask:0xf
	v_mov_b32_dpp v114, v122 row_ror:8 row_mask:0xf bank_mask:0xf
	v_cndmask_b32_e64 v118, v122, v118, s[6:7]
	v_or_b32_e32 v122, s19, v148
	v_lshl_or_b32 v162, s59, 8, v156
	v_mov_b32_dpp v126, v120 row_ror:8 row_mask:0xf bank_mask:0xf
	v_mov_b32_dpp v127, v121 row_ror:8 row_mask:0xf bank_mask:0xf
	v_mov_b32_dpp v115, v119 row_ror:8 row_mask:0xf bank_mask:0xf
	v_mov_b32_dpp v116, v112 row_ror:8 row_mask:0xf bank_mask:0xf
	v_mov_b32_dpp v117, v113 row_ror:8 row_mask:0xf bank_mask:0xf
	v_cndmask_b32_e64 v119, v119, v123, s[6:7]
	v_ashrrev_i32_e32 v123, 31, v122
	v_ashrrev_i32_e32 v163, 31, v162
	v_cndmask_b32_e64 v116, v116, v120, s[6:7]
	v_cndmask_b32_e64 v117, v117, v121, s[6:7]
	v_cndmask_b32_e64 v120, v112, v126, s[6:7]
	v_cndmask_b32_e64 v121, v113, v127, s[6:7]
	v_lshlrev_b64 v[112:113], 14, v[122:123]
	v_cndmask_b32_e64 v114, v114, v124, s[6:7]
	v_cndmask_b32_e64 v115, v115, v125, s[6:7]
	v_lshl_add_u64 v[124:125], s[12:13], 0, v[112:113]
	v_lshlrev_b64 v[112:113], 1, v[162:163]
; __device__ __forceinline__ unsigned cvt_pk_bf16(float lo, float hi) { unsigned r; asm volatile("v_cvt_pk_bf16_f32 %0, %1, %2" : "=v"(r) : "v"(lo), "v"(hi)); return r; }
;     __device__ __forceinline__ void operator()(const f32x4 (&acc)[2][2][4][2], const Unit& u, int wr, int wc, int fr, int fq) const {
;     ...
;         for (int ai = 0; ai < 2; ++ai)
; #pragma unroll
;             for (int m = 0; m < 4; ++m) { const int row = row0 + ai * HALF + m * 16;
;                 const float rs = ssin ? __builtin_amdgcn_rsqf(ssin[row] * (1.f / D) + EPS) : 1.0f; float sq = 0.f; u32x4 w[2];
; #pragma unroll
;                 for (int bj = 0; bj < 2; ++bj) { f32x4 v0 = acc[ai][bj][m][0] * rs, v1 = acc[ai][bj][m][1] * rs;
;                     if (ACT == 1) {
; #pragma unroll
;                         for (int j = 0; j < 4; ++j) { const float a = fmaxf(v0[j], 0.f), b = fmaxf(v1[j], 0.f); v0[j] = a * a; v1[j] = b * b; } }
;                     sq += (v0[0] * v0[0] + v0[1] * v0[1]) + (v0[2] * v0[2] + v0[3] * v0[3]) + (v1[0] * v1[0] + v1[1] * v1[1]) + (v1[2] * v1[2] + v1[3] * v1[3]);
;                     w[bj].x = cvt_pk_bf16(v0[0], v0[1]); w[bj].y = cvt_pk_bf16(v0[2], v0[3]); w[bj].z = cvt_pk_bf16(v1[0], v1[1]); w[bj].w = cvt_pk_bf16(v1[2], v1[3]); }
;                 store_pair_lines(O, ldc, row, fr, col0, w[0], w[1]);
	v_lshl_add_u64 v[124:125], v[124:125], 0, v[112:113]
	global_store_dwordx4 v[124:125], v[114:117], off
	v_max_f32_e32 v108, v108, v108
	v_max_f32_e32 v104, v104, v104
	v_or_b32_e32 v114, 8, v122
	v_ashrrev_i32_e32 v115, 31, v114
	v_lshlrev_b64 v[114:115], 14, v[114:115]
	v_lshl_add_u64 v[114:115], s[12:13], 0, v[114:115]
	v_max_f32_e32 v108, 0, v108
	v_max_f32_e32 v104, 0, v104
	v_max_f32_e32 v109, 0, v109
	v_max_f32_e32 v105, 0, v105
	v_max_f32_e32 v100, 0, v100
	v_max_f32_e32 v101, 0, v101
	v_max_f32_e32 v102, 0, v102
	v_max_f32_e32 v98, 0, v98
	v_max_f32_e32 v103, 0, v103
	v_lshl_add_u64 v[114:115], v[114:115], 0, v[112:113]
	v_mul_f32_e32 v108, v108, v108
	v_mul_f32_e32 v104, v104, v104
	v_mul_f32_e32 v109, v109, v109
	v_mul_f32_e32 v105, v105, v105
	v_max_f32_e32 v110, 0, v110
	v_max_f32_e32 v106, 0, v106
	v_max_f32_e32 v111, 0, v111
	v_max_f32_e32 v107, 0, v107
	v_max_f32_e32 v96, 0, v96
	v_mul_f32_e32 v100, v100, v100
	v_max_f32_e32 v97, 0, v97
	v_mul_f32_e32 v101, v101, v101
	v_mul_f32_e32 v102, v102, v102
	v_mul_f32_e32 v98, v98, v98
	v_max_f32_e32 v99, 0, v99
	v_mul_f32_e32 v103, v103, v103
	global_store_dwordx4 v[114:115], v[118:121], off
	v_mul_f32_e32 v110, v110, v110
	v_mul_f32_e32 v106, v106, v106
	v_mul_f32_e32 v111, v111, v111
	v_mul_f32_e32 v107, v107, v107
	v_cvt_pk_bf16_f32 v108, v108, v109
	v_cvt_pk_bf16_f32 v109, v110, v111
	v_cvt_pk_bf16_f32 v104, v104, v105
	v_cvt_pk_bf16_f32 v105, v106, v107
	v_mul_f32_e32 v96, v96, v96
	v_mul_f32_e32 v97, v97, v97
	v_mul_f32_e32 v99, v99, v99
	v_cvt_pk_bf16_f32 v100, v100, v101
	v_cvt_pk_bf16_f32 v101, v102, v103
	v_cvt_pk_bf16_f32 v102, v96, v97
	v_cvt_pk_bf16_f32 v103, v98, v99
	v_or_b32_e32 v160, s19, v146
	v_mov_b32_dpp v98, v102 row_ror:8 row_mask:0xf bank_mask:0xf
	v_mov_b32_dpp v110, v104 row_ror:8 row_mask:0xf bank_mask:0xf
	v_mov_b32_dpp v99, v103 row_ror:8 row_mask:0xf bank_mask:0xf
	v_cndmask_b32_e64 v98, v98, v104, s[6:7]
	v_add_u32_e32 v104, v149, v160
	v_mov_b32_dpp v111, v105 row_ror:8 row_mask:0xf bank_mask:0xf
	v_cndmask_b32_e64 v99, v99, v105, s[6:7]
	v_ashrrev_i32_e32 v105, 31, v104
	v_lshlrev_b64 v[104:105], 14, v[104:105]
	v_mov_b32_dpp v96, v100 row_ror:8 row_mask:0xf bank_mask:0xf
	v_mov_b32_dpp v97, v101 row_ror:8 row_mask:0xf bank_mask:0xf
	v_lshl_add_u64 v[104:105], s[12:13], 0, v[104:105]
	v_cndmask_b32_e64 v96, v96, v108, s[6:7]
	v_cndmask_b32_e64 v97, v97, v109, s[6:7]
	v_lshl_add_u64 v[104:105], v[104:105], 0, v[112:113]
	v_mov_b32_dpp v106, v108 row_ror:8 row_mask:0xf bank_mask:0xf
	v_mov_b32_dpp v107, v109 row_ror:8 row_mask:0xf bank_mask:0xf
	global_store_dwordx4 v[104:105], v[96:99], off
	v_max_f32_e32 v92, 0, v92
	v_max_f32_e32 v88, 0, v88
	v_add_co_u32_e32 v96, vcc, s58, v104
	v_max_f32_e32 v93, 0, v93
	v_max_f32_e32 v89, 0, v89
	v_max_f32_e32 v84, 0, v84
	v_max_f32_e32 v85, 0, v85
	v_max_f32_e32 v86, 0, v86
	v_max_f32_e32 v82, 0, v82
	v_max_f32_e32 v87, 0, v87
	v_cndmask_b32_e64 v100, v100, v106, s[6:7]
	v_cndmask_b32_e64 v101, v101, v107, s[6:7]
	v_cndmask_b32_e64 v102, v102, v110, s[6:7]
	v_cndmask_b32_e64 v103, v103, v111, s[6:7]
	v_addc_co_u32_e32 v97, vcc, 0, v105, vcc
	v_mul_f32_e32 v92, v92, v92
	v_mul_f32_e32 v88, v88, v88
	v_mul_f32_e32 v93, v93, v93
	v_mul_f32_e32 v89, v89, v89
	v_max_f32_e32 v94, 0, v94
	v_max_f32_e32 v90, 0, v90
	v_max_f32_e32 v95, 0, v95
	v_max_f32_e32 v91, 0, v91
	v_max_f32_e32 v80, 0, v80
	v_mul_f32_e32 v84, v84, v84
	v_max_f32_e32 v81, 0, v81
	v_mul_f32_e32 v85, v85, v85
	v_mul_f32_e32 v86, v86, v86
	v_mul_f32_e32 v82, v82, v82
	v_max_f32_e32 v83, 0, v83
	v_mul_f32_e32 v87, v87, v87
	global_store_dwordx4 v[96:97], v[100:103], off
	v_mul_f32_e32 v94, v94, v94
	v_mul_f32_e32 v90, v90, v90
	v_mul_f32_e32 v95, v95, v95
	v_mul_f32_e32 v91, v91, v91
	v_cvt_pk_bf16_f32 v92, v92, v93
	v_cvt_pk_bf16_f32 v93, v94, v95
	v_cvt_pk_bf16_f32 v88, v88, v89
	v_cvt_pk_bf16_f32 v89, v90, v91
	v_mul_f32_e32 v80, v80, v80
	v_mul_f32_e32 v81, v81, v81
	v_mul_f32_e32 v83, v83, v83
	v_cvt_pk_bf16_f32 v84, v84, v85
	v_cvt_pk_bf16_f32 v85, v86, v87
	v_cvt_pk_bf16_f32 v86, v80, v81
	v_cvt_pk_bf16_f32 v87, v82, v83
	v_mov_b32_e32 v82, 0
	v_mov_b32_dpp v82, v86 row_ror:8 row_mask:0xf bank_mask:0xf
	v_mov_b32_dpp v94, v88 row_ror:8 row_mask:0xf bank_mask:0xf
	v_mov_b32_dpp v83, v87 row_ror:8 row_mask:0xf bank_mask:0xf
	v_cndmask_b32_e64 v82, v82, v88, s[6:7]
	v_add_u32_e32 v88, v150, v160
	v_mov_b32_dpp v95, v89 row_ror:8 row_mask:0xf bank_mask:0xf
	v_cndmask_b32_e64 v83, v83, v89, s[6:7]
	v_ashrrev_i32_e32 v89, 31, v88
	v_lshlrev_b64 v[88:89], 14, v[88:89]
	v_mov_b32_dpp v80, v84 row_ror:8 row_mask:0xf bank_mask:0xf
	v_mov_b32_dpp v81, v85 row_ror:8 row_mask:0xf bank_mask:0xf
	v_lshl_add_u64 v[88:89], s[12:13], 0, v[88:89]
	v_cndmask_b32_e64 v80, v80, v92, s[6:7]
	v_cndmask_b32_e64 v81, v81, v93, s[6:7]
	v_lshl_add_u64 v[88:89], v[88:89], 0, v[112:113]
	v_mov_b32_dpp v90, v92 row_ror:8 row_mask:0xf bank_mask:0xf
	v_mov_b32_dpp v91, v93 row_ror:8 row_mask:0xf bank_mask:0xf
	global_store_dwordx4 v[88:89], v[80:83], off
	v_max_f32_e32 v76, 0, v76
	v_max_f32_e32 v72, 0, v72
	v_add_co_u32_e32 v80, vcc, s58, v88
	v_max_f32_e32 v77, 0, v77
	v_max_f32_e32 v73, 0, v73
	v_max_f32_e32 v68, 0, v68
	v_max_f32_e32 v69, 0, v69
	v_max_f32_e32 v70, 0, v70
	v_max_f32_e32 v66, 0, v66
	v_max_f32_e32 v71, 0, v71
	v_cndmask_b32_e64 v84, v84, v90, s[6:7]
	v_cndmask_b32_e64 v85, v85, v91, s[6:7]
	v_cndmask_b32_e64 v86, v86, v94, s[6:7]
	v_cndmask_b32_e64 v87, v87, v95, s[6:7]
	v_addc_co_u32_e32 v81, vcc, 0, v89, vcc
	v_mul_f32_e32 v76, v76, v76
	v_mul_f32_e32 v72, v72, v72
	v_mul_f32_e32 v77, v77, v77
	v_mul_f32_e32 v73, v73, v73
	v_max_f32_e32 v78, 0, v78
; __device__ __forceinline__ unsigned cvt_pk_bf16(float lo, float hi) { unsigned r; asm volatile("v_cvt_pk_bf16_f32 %0, %1, %2" : "=v"(r) : "v"(lo), "v"(hi)); return r; }
;     __device__ __forceinline__ void operator()(const f32x4 (&acc)[2][2][4][2], const Unit& u, int wr, int wc, int fr, int fq) const {
;     ...
;         for (int ai = 0; ai < 2; ++ai)
; #pragma unroll
;             for (int m = 0; m < 4; ++m) { const int row = row0 + ai * HALF + m * 16;
;                 const float rs = ssin ? __builtin_amdgcn_rsqf(ssin[row] * (1.f / D) + EPS) : 1.0f; float sq = 0.f; u32x4 w[2];
; #pragma unroll
;                 for (int bj = 0; bj < 2; ++bj) { f32x4 v0 = acc[ai][bj][m][0] * rs, v1 = acc[ai][bj][m][1] * rs;
;                     if (ACT == 1) {
; #pragma unroll
;                         for (int j = 0; j < 4; ++j) { const float a = fmaxf(v0[j], 0.f), b = fmaxf(v1[j], 0.f); v0[j] = a * a; v1[j] = b * b; } }
;                     sq += (v0[0] * v0[0] + v0[1] * v0[1]) + (v0[2] * v0[2] + v0[3] * v0[3]) + (v1[0] * v1[0] + v1[1] * v1[1]) + (v1[2] * v1[2] + v1[3] * v1[3]);
;                     w[bj].x = cvt_pk_bf16(v0[0], v0[1]); w[bj].y = cvt_pk_bf16(v0[2], v0[3]); w[bj].z = cvt_pk_bf16(v1[0], v1[1]); w[bj].w = cvt_pk_bf16(v1[2], v1[3]); }
;                 store_pair_lines(O, ldc, row, fr, col0, w[0], w[1]);
	v_max_f32_e32 v74, 0, v74
	v_max_f32_e32 v79, 0, v79
	v_max_f32_e32 v75, 0, v75
	v_max_f32_e32 v64, 0, v64
	v_mul_f32_e32 v68, v68, v68
	v_max_f32_e32 v65, 0, v65
	v_mul_f32_e32 v69, v69, v69
	v_mul_f32_e32 v70, v70, v70
	v_mul_f32_e32 v66, v66, v66
	v_max_f32_e32 v67, 0, v67
	v_mul_f32_e32 v71, v71, v71
	global_store_dwordx4 v[80:81], v[84:87], off
	v_mul_f32_e32 v78, v78, v78
	v_mul_f32_e32 v74, v74, v74
	v_mul_f32_e32 v79, v79, v79
	v_mul_f32_e32 v75, v75, v75
	v_cvt_pk_bf16_f32 v76, v76, v77
	v_cvt_pk_bf16_f32 v77, v78, v79
	v_cvt_pk_bf16_f32 v72, v72, v73
	v_cvt_pk_bf16_f32 v73, v74, v75
	v_mul_f32_e32 v64, v64, v64
	v_mul_f32_e32 v65, v65, v65
	v_mul_f32_e32 v67, v67, v67
	v_cvt_pk_bf16_f32 v68, v68, v69
	v_cvt_pk_bf16_f32 v69, v70, v71
	v_cvt_pk_bf16_f32 v70, v64, v65
	v_cvt_pk_bf16_f32 v71, v66, v67
	v_mov_b32_e32 v66, 0
	v_mov_b32_dpp v66, v70 row_ror:8 row_mask:0xf bank_mask:0xf
	v_mov_b32_dpp v78, v72 row_ror:8 row_mask:0xf bank_mask:0xf
	v_mov_b32_dpp v67, v71 row_ror:8 row_mask:0xf bank_mask:0xf
	v_cndmask_b32_e64 v66, v66, v72, s[6:7]
	v_add_u32_e32 v72, v151, v160
	v_mov_b32_dpp v79, v73 row_ror:8 row_mask:0xf bank_mask:0xf
	v_cndmask_b32_e64 v67, v67, v73, s[6:7]
	v_ashrrev_i32_e32 v73, 31, v72
	v_lshlrev_b64 v[72:73], 14, v[72:73]
	v_mov_b32_dpp v64, v68 row_ror:8 row_mask:0xf bank_mask:0xf
	v_mov_b32_dpp v65, v69 row_ror:8 row_mask:0xf bank_mask:0xf
	v_lshl_add_u64 v[72:73], s[12:13], 0, v[72:73]
	v_cndmask_b32_e64 v64, v64, v76, s[6:7]
	v_cndmask_b32_e64 v65, v65, v77, s[6:7]
	v_lshl_add_u64 v[72:73], v[72:73], 0, v[112:113]
	v_mov_b32_dpp v74, v76 row_ror:8 row_mask:0xf bank_mask:0xf
	v_mov_b32_dpp v75, v77 row_ror:8 row_mask:0xf bank_mask:0xf
	global_store_dwordx4 v[72:73], v[64:67], off
	v_max_f32_e32 v60, 0, v60
	v_max_f32_e32 v56, 0, v56
	v_add_co_u32_e32 v64, vcc, s58, v72
	v_max_f32_e32 v61, 0, v61
	v_max_f32_e32 v57, 0, v57
	v_max_f32_e32 v52, 0, v52
	v_max_f32_e32 v53, 0, v53
	v_max_f32_e32 v54, 0, v54
	v_max_f32_e32 v50, 0, v50
	v_max_f32_e32 v55, 0, v55
	v_cndmask_b32_e64 v68, v68, v74, s[6:7]
	v_cndmask_b32_e64 v69, v69, v75, s[6:7]
	v_cndmask_b32_e64 v70, v70, v78, s[6:7]
	v_cndmask_b32_e64 v71, v71, v79, s[6:7]
	v_addc_co_u32_e32 v65, vcc, 0, v73, vcc
	v_mul_f32_e32 v60, v60, v60
	v_mul_f32_e32 v56, v56, v56
	v_mul_f32_e32 v61, v61, v61
	v_mul_f32_e32 v57, v57, v57
	v_max_f32_e32 v62, 0, v62
	v_max_f32_e32 v58, 0, v58
	v_max_f32_e32 v63, 0, v63
	v_max_f32_e32 v59, 0, v59
	v_max_f32_e32 v48, 0, v48
	v_mul_f32_e32 v52, v52, v52
	v_max_f32_e32 v49, 0, v49
	v_mul_f32_e32 v53, v53, v53
	v_mul_f32_e32 v54, v54, v54
	v_mul_f32_e32 v50, v50, v50
	v_max_f32_e32 v51, 0, v51
	v_mul_f32_e32 v55, v55, v55
	global_store_dwordx4 v[64:65], v[68:71], off
	v_mul_f32_e32 v62, v62, v62
	v_mul_f32_e32 v58, v58, v58
	v_mul_f32_e32 v63, v63, v63
	v_mul_f32_e32 v59, v59, v59
	v_cvt_pk_bf16_f32 v60, v60, v61
	v_cvt_pk_bf16_f32 v61, v62, v63
	v_cvt_pk_bf16_f32 v56, v56, v57
	v_cvt_pk_bf16_f32 v57, v58, v59
	v_mul_f32_e32 v48, v48, v48
	v_mul_f32_e32 v49, v49, v49
	v_mul_f32_e32 v51, v51, v51
	v_cvt_pk_bf16_f32 v52, v52, v53
	v_cvt_pk_bf16_f32 v53, v54, v55
	v_cvt_pk_bf16_f32 v54, v48, v49
	v_cvt_pk_bf16_f32 v55, v50, v51
	v_mov_b32_e32 v50, 0
	v_mov_b32_dpp v50, v54 row_ror:8 row_mask:0xf bank_mask:0xf
	v_mov_b32_dpp v62, v56 row_ror:8 row_mask:0xf bank_mask:0xf
	v_mov_b32_dpp v51, v55 row_ror:8 row_mask:0xf bank_mask:0xf
	v_cndmask_b32_e64 v50, v50, v56, s[6:7]
	v_add_u32_e32 v56, v152, v160
	v_mov_b32_dpp v63, v57 row_ror:8 row_mask:0xf bank_mask:0xf
	v_cndmask_b32_e64 v51, v51, v57, s[6:7]
	v_ashrrev_i32_e32 v57, 31, v56
	v_lshlrev_b64 v[56:57], 14, v[56:57]
	v_mov_b32_dpp v48, v52 row_ror:8 row_mask:0xf bank_mask:0xf
	v_mov_b32_dpp v49, v53 row_ror:8 row_mask:0xf bank_mask:0xf
	v_lshl_add_u64 v[56:57], s[12:13], 0, v[56:57]
	v_cndmask_b32_e64 v48, v48, v60, s[6:7]
	v_cndmask_b32_e64 v49, v49, v61, s[6:7]
	v_lshl_add_u64 v[56:57], v[56:57], 0, v[112:113]
	v_mov_b32_dpp v58, v60 row_ror:8 row_mask:0xf bank_mask:0xf
	v_mov_b32_dpp v59, v61 row_ror:8 row_mask:0xf bank_mask:0xf
	global_store_dwordx4 v[56:57], v[48:51], off
	v_max_f32_e32 v44, 0, v44
	v_max_f32_e32 v40, 0, v40
	v_add_co_u32_e32 v48, vcc, s58, v56
	v_max_f32_e32 v45, 0, v45
	v_max_f32_e32 v41, 0, v41
	v_max_f32_e32 v36, 0, v36
	v_max_f32_e32 v37, 0, v37
	v_max_f32_e32 v38, 0, v38
	v_max_f32_e32 v34, 0, v34
	v_max_f32_e32 v39, 0, v39
	v_cndmask_b32_e64 v52, v52, v58, s[6:7]
	v_cndmask_b32_e64 v53, v53, v59, s[6:7]
	v_cndmask_b32_e64 v54, v54, v62, s[6:7]
	v_cndmask_b32_e64 v55, v55, v63, s[6:7]
	v_addc_co_u32_e32 v49, vcc, 0, v57, vcc
	v_mul_f32_e32 v44, v44, v44
	v_mul_f32_e32 v40, v40, v40
	v_mul_f32_e32 v45, v45, v45
	v_mul_f32_e32 v41, v41, v41
	v_max_f32_e32 v46, 0, v46
	v_max_f32_e32 v42, 0, v42
	v_max_f32_e32 v47, 0, v47
	v_max_f32_e32 v43, 0, v43
	v_max_f32_e32 v32, 0, v32
	v_mul_f32_e32 v36, v36, v36
	v_max_f32_e32 v33, 0, v33
	v_mul_f32_e32 v37, v37, v37
	v_mul_f32_e32 v38, v38, v38
	v_mul_f32_e32 v34, v34, v34
	v_max_f32_e32 v35, 0, v35
	v_mul_f32_e32 v39, v39, v39
	global_store_dwordx4 v[48:49], v[52:55], off
	v_mul_f32_e32 v46, v46, v46
	v_mul_f32_e32 v42, v42, v42
	v_mul_f32_e32 v47, v47, v47
	v_mul_f32_e32 v43, v43, v43
	v_cvt_pk_bf16_f32 v44, v44, v45
	v_cvt_pk_bf16_f32 v45, v46, v47
	v_cvt_pk_bf16_f32 v40, v40, v41
	v_cvt_pk_bf16_f32 v41, v42, v43
	v_mul_f32_e32 v32, v32, v32
	v_mul_f32_e32 v33, v33, v33
	v_mul_f32_e32 v35, v35, v35
	v_cvt_pk_bf16_f32 v36, v36, v37
	v_cvt_pk_bf16_f32 v37, v38, v39
	v_cvt_pk_bf16_f32 v38, v32, v33
	v_cvt_pk_bf16_f32 v39, v34, v35
	v_mov_b32_e32 v34, 0
	v_mov_b32_dpp v34, v38 row_ror:8 row_mask:0xf bank_mask:0xf
; __device__ __forceinline__ unsigned cvt_pk_bf16(float lo, float hi) { unsigned r; asm volatile("v_cvt_pk_bf16_f32 %0, %1, %2" : "=v"(r) : "v"(lo), "v"(hi)); return r; }
;     __device__ __forceinline__ void operator()(const f32x4 (&acc)[2][2][4][2], const Unit& u, int wr, int wc, int fr, int fq) const {
;     ...
;         for (int ai = 0; ai < 2; ++ai)
; #pragma unroll
;             for (int m = 0; m < 4; ++m) { const int row = row0 + ai * HALF + m * 16;
;                 const float rs = ssin ? __builtin_amdgcn_rsqf(ssin[row] * (1.f / D) + EPS) : 1.0f; float sq = 0.f; u32x4 w[2];
; #pragma unroll
;                 for (int bj = 0; bj < 2; ++bj) { f32x4 v0 = acc[ai][bj][m][0] * rs, v1 = acc[ai][bj][m][1] * rs;
;                     if (ACT == 1) {
; #pragma unroll
;                         for (int j = 0; j < 4; ++j) { const float a = fmaxf(v0[j], 0.f), b = fmaxf(v1[j], 0.f); v0[j] = a * a; v1[j] = b * b; } }
;                     sq += (v0[0] * v0[0] + v0[1] * v0[1]) + (v0[2] * v0[2] + v0[3] * v0[3]) + (v1[0] * v1[0] + v1[1] * v1[1]) + (v1[2] * v1[2] + v1[3] * v1[3]);
;                     w[bj].x = cvt_pk_bf16(v0[0], v0[1]); w[bj].y = cvt_pk_bf16(v0[2], v0[3]); w[bj].z = cvt_pk_bf16(v1[0], v1[1]); w[bj].w = cvt_pk_bf16(v1[2], v1[3]); }
;                 store_pair_lines(O, ldc, row, fr, col0, w[0], w[1]);
; template <class Epi>
; __device__ __forceinline__ void gemm_phase(LAS unsigned char* lds, const Gemm g, const StaticOrder& S, const Epi& E) {
;     ...
;         E(acc, cur, wr, wc, fr, fq);
;         if (!has_next) break;
	v_mov_b32_dpp v46, v40 row_ror:8 row_mask:0xf bank_mask:0xf
	v_mov_b32_dpp v35, v39 row_ror:8 row_mask:0xf bank_mask:0xf
	v_cndmask_b32_e64 v34, v34, v40, s[6:7]
	v_add_u32_e32 v40, v153, v160
	v_mov_b32_dpp v47, v41 row_ror:8 row_mask:0xf bank_mask:0xf
	v_cndmask_b32_e64 v35, v35, v41, s[6:7]
	v_ashrrev_i32_e32 v41, 31, v40
	v_lshlrev_b64 v[40:41], 14, v[40:41]
	v_mov_b32_dpp v32, v36 row_ror:8 row_mask:0xf bank_mask:0xf
	v_mov_b32_dpp v33, v37 row_ror:8 row_mask:0xf bank_mask:0xf
	v_lshl_add_u64 v[40:41], s[12:13], 0, v[40:41]
	v_cndmask_b32_e64 v32, v32, v44, s[6:7]
	v_cndmask_b32_e64 v33, v33, v45, s[6:7]
	v_lshl_add_u64 v[40:41], v[40:41], 0, v[112:113]
	v_mov_b32_dpp v42, v44 row_ror:8 row_mask:0xf bank_mask:0xf
	v_mov_b32_dpp v43, v45 row_ror:8 row_mask:0xf bank_mask:0xf
	global_store_dwordx4 v[40:41], v[32:35], off
	v_max_f32_e32 v28, 0, v28
	v_max_f32_e32 v24, 0, v24
	v_add_co_u32_e32 v32, vcc, s58, v40
	v_max_f32_e32 v29, 0, v29
	v_max_f32_e32 v25, 0, v25
	v_max_f32_e32 v20, 0, v20
	v_max_f32_e32 v21, 0, v21
	v_max_f32_e32 v22, 0, v22
	v_max_f32_e32 v18, 0, v18
	v_max_f32_e32 v23, 0, v23
	v_cndmask_b32_e64 v36, v36, v42, s[6:7]
	v_cndmask_b32_e64 v37, v37, v43, s[6:7]
	v_cndmask_b32_e64 v38, v38, v46, s[6:7]
	v_cndmask_b32_e64 v39, v39, v47, s[6:7]
	v_addc_co_u32_e32 v33, vcc, 0, v41, vcc
	v_mul_f32_e32 v28, v28, v28
	v_mul_f32_e32 v24, v24, v24
	v_mul_f32_e32 v29, v29, v29
	v_mul_f32_e32 v25, v25, v25
	v_max_f32_e32 v30, 0, v30
	v_max_f32_e32 v26, 0, v26
	v_max_f32_e32 v31, 0, v31
	v_max_f32_e32 v27, 0, v27
	v_max_f32_e32 v16, 0, v16
	v_mul_f32_e32 v20, v20, v20
	v_max_f32_e32 v17, 0, v17
	v_mul_f32_e32 v21, v21, v21
	v_mul_f32_e32 v22, v22, v22
	v_mul_f32_e32 v18, v18, v18
	v_max_f32_e32 v19, 0, v19
	v_mul_f32_e32 v23, v23, v23
	global_store_dwordx4 v[32:33], v[36:39], off
	v_mul_f32_e32 v30, v30, v30
	v_mul_f32_e32 v26, v26, v26
	v_mul_f32_e32 v31, v31, v31
	v_mul_f32_e32 v27, v27, v27
	v_cvt_pk_bf16_f32 v28, v28, v29
	v_cvt_pk_bf16_f32 v29, v30, v31
	v_cvt_pk_bf16_f32 v24, v24, v25
	v_cvt_pk_bf16_f32 v25, v26, v27
	v_mul_f32_e32 v16, v16, v16
	v_mul_f32_e32 v17, v17, v17
	v_mul_f32_e32 v19, v19, v19
	v_cvt_pk_bf16_f32 v20, v20, v21
	v_cvt_pk_bf16_f32 v21, v22, v23
	v_cvt_pk_bf16_f32 v22, v16, v17
	v_cvt_pk_bf16_f32 v23, v18, v19
	v_mov_b32_e32 v18, 0
	v_mov_b32_dpp v18, v22 row_ror:8 row_mask:0xf bank_mask:0xf
	v_mov_b32_dpp v30, v24 row_ror:8 row_mask:0xf bank_mask:0xf
	v_mov_b32_dpp v19, v23 row_ror:8 row_mask:0xf bank_mask:0xf
	v_cndmask_b32_e64 v18, v18, v24, s[6:7]
	v_add_u32_e32 v24, v154, v160
	v_mov_b32_dpp v31, v25 row_ror:8 row_mask:0xf bank_mask:0xf
	v_cndmask_b32_e64 v19, v19, v25, s[6:7]
	v_ashrrev_i32_e32 v25, 31, v24
	v_lshlrev_b64 v[24:25], 14, v[24:25]
	v_mov_b32_dpp v16, v20 row_ror:8 row_mask:0xf bank_mask:0xf
	v_mov_b32_dpp v17, v21 row_ror:8 row_mask:0xf bank_mask:0xf
	v_lshl_add_u64 v[24:25], s[12:13], 0, v[24:25]
	v_cndmask_b32_e64 v16, v16, v28, s[6:7]
	v_cndmask_b32_e64 v17, v17, v29, s[6:7]
	v_lshl_add_u64 v[24:25], v[24:25], 0, v[112:113]
	v_mov_b32_dpp v26, v28 row_ror:8 row_mask:0xf bank_mask:0xf
	v_mov_b32_dpp v27, v29 row_ror:8 row_mask:0xf bank_mask:0xf
	global_store_dwordx4 v[24:25], v[16:19], off
	v_max_f32_e32 v12, 0, v12
	v_max_f32_e32 v8, 0, v8
	v_add_co_u32_e32 v16, vcc, s58, v24
	v_max_f32_e32 v13, 0, v13
	v_max_f32_e32 v9, 0, v9
	v_max_f32_e32 v4, 0, v4
	v_max_f32_e32 v5, 0, v5
	v_max_f32_e32 v6, 0, v6
	v_max_f32_e32 v2, 0, v2
	v_max_f32_e32 v7, 0, v7
	v_cndmask_b32_e64 v20, v20, v26, s[6:7]
	v_cndmask_b32_e64 v21, v21, v27, s[6:7]
	v_cndmask_b32_e64 v22, v22, v30, s[6:7]
	v_cndmask_b32_e64 v23, v23, v31, s[6:7]
	v_addc_co_u32_e32 v17, vcc, 0, v25, vcc
	v_mul_f32_e32 v12, v12, v12
	v_mul_f32_e32 v8, v8, v8
	v_mul_f32_e32 v13, v13, v13
	v_mul_f32_e32 v9, v9, v9
	v_max_f32_e32 v14, 0, v14
	v_max_f32_e32 v10, 0, v10
	v_max_f32_e32 v15, 0, v15
	v_max_f32_e32 v11, 0, v11
	v_max_f32_e32 v0, 0, v0
	v_mul_f32_e32 v4, v4, v4
	v_max_f32_e32 v1, 0, v1
	v_mul_f32_e32 v5, v5, v5
	v_mul_f32_e32 v6, v6, v6
	v_mul_f32_e32 v2, v2, v2
	v_max_f32_e32 v3, 0, v3
	v_mul_f32_e32 v7, v7, v7
	global_store_dwordx4 v[16:17], v[20:23], off
	v_mul_f32_e32 v14, v14, v14
	v_mul_f32_e32 v10, v10, v10
	v_mul_f32_e32 v15, v15, v15
	v_mul_f32_e32 v11, v11, v11
	v_cvt_pk_bf16_f32 v12, v12, v13
	v_cvt_pk_bf16_f32 v13, v14, v15
	v_cvt_pk_bf16_f32 v8, v8, v9
	v_cvt_pk_bf16_f32 v9, v10, v11
	v_mul_f32_e32 v0, v0, v0
	v_mul_f32_e32 v1, v1, v1
	v_mul_f32_e32 v3, v3, v3
	v_cvt_pk_bf16_f32 v4, v4, v5
	v_cvt_pk_bf16_f32 v5, v6, v7
	v_cvt_pk_bf16_f32 v6, v0, v1
	v_cvt_pk_bf16_f32 v7, v2, v3
	v_mov_b32_e32 v2, 0
	v_mov_b32_dpp v2, v6 row_ror:8 row_mask:0xf bank_mask:0xf
	v_mov_b32_dpp v14, v8 row_ror:8 row_mask:0xf bank_mask:0xf
	v_mov_b32_dpp v3, v7 row_ror:8 row_mask:0xf bank_mask:0xf
	v_cndmask_b32_e64 v2, v2, v8, s[6:7]
	v_add_u32_e32 v8, v155, v160
	v_mov_b32_dpp v15, v9 row_ror:8 row_mask:0xf bank_mask:0xf
	v_cndmask_b32_e64 v3, v3, v9, s[6:7]
	v_ashrrev_i32_e32 v9, 31, v8
	v_lshlrev_b64 v[8:9], 14, v[8:9]
	v_mov_b32_dpp v0, v4 row_ror:8 row_mask:0xf bank_mask:0xf
	v_mov_b32_dpp v1, v5 row_ror:8 row_mask:0xf bank_mask:0xf
	v_lshl_add_u64 v[8:9], s[12:13], 0, v[8:9]
	v_cndmask_b32_e64 v0, v0, v12, s[6:7]
	v_cndmask_b32_e64 v1, v1, v13, s[6:7]
	v_lshl_add_u64 v[8:9], v[8:9], 0, v[112:113]
	global_store_dwordx4 v[8:9], v[0:3], off
	v_mov_b32_dpp v10, v12 row_ror:8 row_mask:0xf bank_mask:0xf
	v_mov_b32_dpp v11, v13 row_ror:8 row_mask:0xf bank_mask:0xf
	v_add_co_u32_e32 v0, vcc, 0x20000, v8
	v_cndmask_b32_e64 v4, v4, v10, s[6:7]
	s_nop 0
	v_addc_co_u32_e32 v1, vcc, 0, v9, vcc
	v_cndmask_b32_e64 v5, v5, v11, s[6:7]
	v_cndmask_b32_e64 v6, v6, v14, s[6:7]
	v_cndmask_b32_e64 v7, v7, v15, s[6:7]
	s_and_b64 vcc, exec, s[30:31]
	s_mov_b32 s59, s18
	s_mov_b32 s36, s26
	s_mov_b64 s[40:41], s[34:35]
	s_mov_b64 s[38:39], s[28:29]
	global_store_dwordx4 v[0:1], v[4:7], off
	s_cbranch_vccz .LBB0_1357
	s_waitcnt vmcnt(0)
	s_cmpk_gt_u32 s44, 0xff
	s_cbranch_scc1 .LBB0_1369
	s_barrier

; #define PG8_STAGE(bufoff, gbase, voff) do { _Pragma("unroll") for (int _i = 0; _i < 2; ++_i) \
;         __builtin_amdgcn_global_load_lds((const unsigned*)((const char*)(gbase) + (voff)[_i]), (LAS unsigned*)(lds + (bufoff) + ldsw + _i * 8192), 16, 0, 0); } while (0)
; #define PG8_LDA(dst, b, h) do { _Pragma("unroll") for (int m = 0; m < 4; ++m) _Pragma("unroll") for (int k = 0; k < 2; ++k) dst[m][k] = *(const LAS bf16x8*)(lds + PG8_SA(b, h) + aoff + m * 2048 + k * 1024); } while (0)
; #define PG8_LDB(dst, b, h) do { _Pragma("unroll") for (int n = 0; n < 2; ++n) _Pragma("unroll") for (int k = 0; k < 2; ++k) dst[n][k] = *(const LAS bf16x8*)(lds + PG8_SB(b, h) + boff + n * 2048 + k * 1024); } while (0)
; #define PG8_MMA(ai, bj, At, Bt) do { __builtin_amdgcn_s_setprio(1); _Pragma("unroll") for (int m = 0; m < 4; ++m) _Pragma("unroll") for (int n = 0; n < 2; ++n) _Pragma("unroll") for (int k = 0; k < 2; ++k) \
;         acc[ai][bj][m][n] = __builtin_amdgcn_mfma_f32_16x16x32_bf16(Bt[n][k], At[m][k], acc[ai][bj][m][n], 0, 0, 0); __builtin_amdgcn_s_setprio(0); } while (0)
; #define PG8_WAIT_V(n) asm volatile("s_waitcnt vmcnt(" #n ")" ::: "memory")
; #define PG8_WAIT_L(n) asm volatile("s_waitcnt lgkmcnt(" #n ")" ::: "memory")
; #define PG8_BAR __builtin_amdgcn_s_barrier()
; template <class Epi>
; __device__ __forceinline__ void gemm_phase(LAS unsigned char* lds, const Gemm g, const StaticOrder& S, const Epi& E) {
;     ...
;         for (int t = 0; t < nt; t += 2) {
;             const bool last = (t == nt - 2);
;             const char* a1 = cA + (size_t)(t + 1) * kstep;
;             const char* a2 = last ? nA : cA + (size_t)(t + 2) * kstep; const char* b2 = last ? nB : cB + (size_t)(t + 2) * kstep;
;             const char* a3 = a2 + kstep; const char* b3 = b2 + kstep;
;             PG8_LDB(B0, 0, 0); PG8_SCHED; PG8_LDA(At, 0, 0); PG8_STAGE(PG8_SA(1, 1), a1 + hstep, voffA);
;             PG8_WAIT_L(8); PG8_BAR; PG8_WAIT_L(0); PG8_MMA(0, 0, At, B0); PG8_BAR; PG8_SCHED;
;             PG8_LDB(B1, 0, 1); PG8_STAGE(PG8_SB(0, 0), b2, voffB0);
;             PG8_BAR; PG8_WAIT_L(0); PG8_MMA(0, 1, At, B1); PG8_BAR;
;             PG8_LDA(At, 0, 1); PG8_STAGE(PG8_SA(0, 0), a2, voffA);
;             PG8_BAR; PG8_WAIT_L(0); PG8_MMA(1, 0, At, B0); PG8_BAR; PG8_SCHED;
;             PG8_STAGE(PG8_SB(0, 1), b2, voffB1);
;             PG8_WAIT_V(6); PG8_BAR; PG8_MMA(1, 1, At, B1); PG8_BAR;
.LBB0_1443:
	ds_read_b128 v[128:131], v179
	ds_read_b128 v[132:135], v179 offset:1024
	ds_read_b128 v[154:157], v179 offset:2048
	ds_read_b128 v[158:161], v179 offset:3072
	s_add_u32 s33, s42, 0xffe00080
	s_addc_u32 s44, s43, -1
	s_cmpk_eq_i32 s74, 0x7c
	s_cselect_b32 s45, s9, s44
	s_cselect_b32 s44, s11, s33
	s_cselect_b32 s47, s31, s73
	s_cselect_b32 s46, s35, s72
	v_lshl_add_u64 v[200:201], s[42:43], 0, v[148:149]
	s_add_i32 m0, s54, 0xc000
	ds_read_b128 v[162:165], v180
	ds_read_b128 v[166:169], v180 offset:1024
	ds_read_b128 v[170:173], v180 offset:2048
	ds_read_b128 v[184:187], v180 offset:3072
	ds_read_b128 v[188:191], v180 offset:4096
	ds_read_b128 v[192:195], v180 offset:5120
	ds_read_b128 v[196:199], v180 offset:6144
	ds_read_b128 v[204:207], v180 offset:7168
	global_load_lds_dwordx4 v[200:201], off
	v_lshl_add_u64 v[200:201], s[42:43], 0, v[150:151]
	s_add_i32 m0, s54, 0xe000
	s_nop 0
	global_load_lds_dwordx4 v[200:201], off
	s_waitcnt lgkmcnt(8)
	s_barrier
	s_waitcnt lgkmcnt(0)
	v_mfma_f32_16x16x32_bf16 v[124:127], v[128:131], v[162:165], v[124:127]
	v_mfma_f32_16x16x32_bf16 v[120:123], v[154:157], v[162:165], v[120:123]
	v_mfma_f32_16x16x32_bf16 v[108:111], v[128:131], v[170:173], v[108:111]
	v_mfma_f32_16x16x32_bf16 v[104:107], v[154:157], v[170:173], v[104:107]
	v_mfma_f32_16x16x32_bf16 v[92:95], v[128:131], v[188:191], v[92:95]
	v_mfma_f32_16x16x32_bf16 v[88:91], v[154:157], v[188:191], v[88:91]
	v_mfma_f32_16x16x32_bf16 v[76:79], v[128:131], v[196:199], v[76:79]
	v_mfma_f32_16x16x32_bf16 v[72:75], v[154:157], v[196:199], v[72:75]
	v_mfma_f32_16x16x32_bf16 v[124:127], v[132:135], v[166:169], v[124:127]
	v_mfma_f32_16x16x32_bf16 v[120:123], v[158:161], v[166:169], v[120:123]
	v_mfma_f32_16x16x32_bf16 v[108:111], v[132:135], v[184:187], v[108:111]
	v_mfma_f32_16x16x32_bf16 v[104:107], v[158:161], v[184:187], v[104:107]
	v_mfma_f32_16x16x32_bf16 v[92:95], v[132:135], v[192:195], v[92:95]
	v_mfma_f32_16x16x32_bf16 v[88:91], v[158:161], v[192:195], v[88:91]
	v_mfma_f32_16x16x32_bf16 v[76:79], v[132:135], v[204:207], v[76:79]
	v_mfma_f32_16x16x32_bf16 v[72:75], v[158:161], v[204:207], v[72:75]
	s_barrier
	s_add_i32 s33, s66, s53
	v_lshl_add_u64 v[200:201], s[46:47], 0, v[138:139]
	s_mov_b32 m0, s33
	ds_read_b128 v[208:211], v181
	ds_read_b128 v[212:215], v181 offset:1024
	ds_read_b128 v[216:219], v181 offset:2048
	ds_read_b128 v[220:223], v181 offset:3072
	global_load_lds_dwordx4 v[200:201], off
	v_lshl_add_u64 v[224:225], s[46:47], 0, v[144:145]
	s_add_i32 m0, s33, 0x2000
	s_nop 0
	global_load_lds_dwordx4 v[224:225], off
	s_waitcnt lgkmcnt(0)
	s_barrier
	s_waitcnt lgkmcnt(0)
	v_mfma_f32_16x16x32_bf16 v[116:119], v[208:211], v[162:165], v[116:119]
	v_mfma_f32_16x16x32_bf16 v[112:115], v[216:219], v[162:165], v[112:115]
	v_mfma_f32_16x16x32_bf16 v[100:103], v[208:211], v[170:173], v[100:103]
	v_mfma_f32_16x16x32_bf16 v[96:99], v[216:219], v[170:173], v[96:99]
	v_mfma_f32_16x16x32_bf16 v[84:87], v[208:211], v[188:191], v[84:87]
	v_mfma_f32_16x16x32_bf16 v[80:83], v[216:219], v[188:191], v[80:83]
	v_mfma_f32_16x16x32_bf16 v[68:71], v[208:211], v[196:199], v[68:71]
	v_mfma_f32_16x16x32_bf16 v[64:67], v[216:219], v[196:199], v[64:67]
	v_mfma_f32_16x16x32_bf16 v[116:119], v[212:215], v[166:169], v[116:119]
	v_mfma_f32_16x16x32_bf16 v[112:115], v[220:223], v[166:169], v[112:115]
	v_mfma_f32_16x16x32_bf16 v[100:103], v[212:215], v[184:187], v[100:103]
	v_mfma_f32_16x16x32_bf16 v[96:99], v[220:223], v[184:187], v[96:99]
	v_mfma_f32_16x16x32_bf16 v[84:87], v[212:215], v[192:195], v[84:87]
	v_mfma_f32_16x16x32_bf16 v[80:83], v[220:223], v[192:195], v[80:83]
	v_mfma_f32_16x16x32_bf16 v[68:71], v[212:215], v[204:207], v[68:71]
	v_mfma_f32_16x16x32_bf16 v[64:67], v[220:223], v[204:207], v[64:67]
	s_mov_b32 m0, s54
	v_lshl_add_u64 v[226:227], s[44:45], 0, v[136:137]
	s_barrier
	ds_read_b128 v[162:165], v180 offset:16384
	ds_read_b128 v[166:169], v180 offset:17408
	ds_read_b128 v[170:173], v180 offset:18432
	ds_read_b128 v[184:187], v180 offset:19456
	ds_read_b128 v[188:191], v180 offset:20480
	ds_read_b128 v[192:195], v180 offset:21504
	ds_read_b128 v[196:199], v180 offset:22528
	ds_read_b128 v[204:207], v180 offset:23552
	global_load_lds_dwordx4 v[226:227], off
	v_lshl_add_u64 v[228:229], s[44:45], 0, v[142:143]
	s_mov_b32 m0, s55
	s_nop 0
	global_load_lds_dwordx4 v[228:229], off
	s_add_i32 s33, s67, s53
	v_lshl_add_u64 v[230:231], s[46:47], 0, v[140:141]
	s_mov_b32 m0, s33
	v_lshl_add_u64 v[232:233], s[46:47], 0, v[146:147]
	global_load_lds_dwordx4 v[230:231], off
	s_add_i32 m0, s33, 0x2000
	s_nop 0
	global_load_lds_dwordx4 v[232:233], off
	s_waitcnt vmcnt(6)
	s_barrier
; #define PG8_STAGE(bufoff, gbase, voff) do { _Pragma("unroll") for (int _i = 0; _i < 2; ++_i) \
;         __builtin_amdgcn_global_load_lds((const unsigned*)((const char*)(gbase) + (voff)[_i]), (LAS unsigned*)(lds + (bufoff) + ldsw + _i * 8192), 16, 0, 0); } while (0)
; #define PG8_LDA(dst, b, h) do { _Pragma("unroll") for (int m = 0; m < 4; ++m) _Pragma("unroll") for (int k = 0; k < 2; ++k) dst[m][k] = *(const LAS bf16x8*)(lds + PG8_SA(b, h) + aoff + m * 2048 + k * 1024); } while (0)
; #define PG8_LDB(dst, b, h) do { _Pragma("unroll") for (int n = 0; n < 2; ++n) _Pragma("unroll") for (int k = 0; k < 2; ++k) dst[n][k] = *(const LAS bf16x8*)(lds + PG8_SB(b, h) + boff + n * 2048 + k * 1024); } while (0)
; #define PG8_MMA(ai, bj, At, Bt) do { __builtin_amdgcn_s_setprio(1); _Pragma("unroll") for (int m = 0; m < 4; ++m) _Pragma("unroll") for (int n = 0; n < 2; ++n) _Pragma("unroll") for (int k = 0; k < 2; ++k) \
;         acc[ai][bj][m][n] = __builtin_amdgcn_mfma_f32_16x16x32_bf16(Bt[n][k], At[m][k], acc[ai][bj][m][n], 0, 0, 0); __builtin_amdgcn_s_setprio(0); } while (0)
; #define PG8_WAIT_V(n) asm volatile("s_waitcnt vmcnt(" #n ")" ::: "memory")
; #define PG8_WAIT_L(n) asm volatile("s_waitcnt lgkmcnt(" #n ")" ::: "memory")
; #define PG8_BAR __builtin_amdgcn_s_barrier()
; #define PG8_SCHED __builtin_amdgcn_sched_barrier(0)
; template <class Epi>
; __device__ __forceinline__ void gemm_phase(LAS unsigned char* lds, const Gemm g, const StaticOrder& S, const Epi& E) {
;     ...
;             PG8_BAR; PG8_WAIT_L(0); PG8_MMA(1, 0, At, B0); PG8_BAR; PG8_SCHED;
;             PG8_STAGE(PG8_SB(0, 1), b2, voffB1);
;             PG8_WAIT_V(6); PG8_BAR; PG8_MMA(1, 1, At, B1); PG8_BAR;
;             PG8_LDB(B0, 1, 0); PG8_SCHED; PG8_LDA(At, 1, 0); PG8_STAGE(PG8_SA(0, 1), a2 + hstep, voffA);
;             PG8_WAIT_L(8); PG8_BAR; PG8_WAIT_L(0); PG8_MMA(0, 0, At, B0); PG8_BAR; PG8_SCHED;
;             PG8_LDB(B1, 1, 1); PG8_STAGE(PG8_SB(1, 0), b3, voffB0);
;             PG8_BAR; PG8_WAIT_L(0); PG8_MMA(0, 1, At, B1); PG8_BAR;
;             PG8_LDA(At, 1, 1); PG8_STAGE(PG8_SA(1, 0), a3, voffA);
;             PG8_BAR; PG8_WAIT_L(0); PG8_MMA(1, 0, At, B0); PG8_BAR; PG8_SCHED;
	s_waitcnt lgkmcnt(0)
	v_mfma_f32_16x16x32_bf16 v[60:63], v[128:131], v[162:165], v[60:63]
	v_mfma_f32_16x16x32_bf16 v[56:59], v[154:157], v[162:165], v[56:59]
	v_mfma_f32_16x16x32_bf16 v[44:47], v[128:131], v[170:173], v[44:47]
	v_mfma_f32_16x16x32_bf16 v[40:43], v[154:157], v[170:173], v[40:43]
	v_mfma_f32_16x16x32_bf16 v[28:31], v[128:131], v[188:191], v[28:31]
	v_mfma_f32_16x16x32_bf16 v[24:27], v[154:157], v[188:191], v[24:27]
	v_mfma_f32_16x16x32_bf16 v[12:15], v[128:131], v[196:199], v[12:15]
	v_mfma_f32_16x16x32_bf16 v[8:11], v[154:157], v[196:199], v[8:11]
	v_mfma_f32_16x16x32_bf16 v[60:63], v[132:135], v[166:169], v[60:63]
	v_mfma_f32_16x16x32_bf16 v[56:59], v[158:161], v[166:169], v[56:59]
	v_mfma_f32_16x16x32_bf16 v[44:47], v[132:135], v[184:187], v[44:47]
	v_mfma_f32_16x16x32_bf16 v[40:43], v[158:161], v[184:187], v[40:43]
	v_mfma_f32_16x16x32_bf16 v[28:31], v[132:135], v[192:195], v[28:31]
	v_mfma_f32_16x16x32_bf16 v[24:27], v[158:161], v[192:195], v[24:27]
	v_mfma_f32_16x16x32_bf16 v[12:15], v[132:135], v[204:207], v[12:15]
	v_mfma_f32_16x16x32_bf16 v[8:11], v[158:161], v[204:207], v[8:11]
	v_mfma_f32_16x16x32_bf16 v[52:55], v[208:211], v[162:165], v[52:55]
	v_mfma_f32_16x16x32_bf16 v[48:51], v[216:219], v[162:165], v[48:51]
	v_mfma_f32_16x16x32_bf16 v[36:39], v[208:211], v[170:173], v[36:39]
	v_mfma_f32_16x16x32_bf16 v[32:35], v[216:219], v[170:173], v[32:35]
	v_mfma_f32_16x16x32_bf16 v[20:23], v[208:211], v[188:191], v[20:23]
	v_mfma_f32_16x16x32_bf16 v[16:19], v[216:219], v[188:191], v[16:19]
	v_mfma_f32_16x16x32_bf16 v[4:7], v[208:211], v[196:199], v[4:7]
	v_mfma_f32_16x16x32_bf16 v[0:3], v[216:219], v[196:199], v[0:3]
	v_mfma_f32_16x16x32_bf16 v[52:55], v[212:215], v[166:169], v[52:55]
	v_mfma_f32_16x16x32_bf16 v[48:51], v[220:223], v[166:169], v[48:51]
	v_mfma_f32_16x16x32_bf16 v[36:39], v[212:215], v[184:187], v[36:39]
	v_mfma_f32_16x16x32_bf16 v[32:35], v[220:223], v[184:187], v[32:35]
	v_mfma_f32_16x16x32_bf16 v[20:23], v[212:215], v[192:195], v[20:23]
	v_mfma_f32_16x16x32_bf16 v[16:19], v[220:223], v[192:195], v[16:19]
	v_mfma_f32_16x16x32_bf16 v[4:7], v[212:215], v[204:207], v[4:7]
	v_mfma_f32_16x16x32_bf16 v[0:3], v[220:223], v[204:207], v[0:3]
	s_add_i32 s33, 0, 0x18000
	v_add_u32_e32 v158, s33, v175
	s_barrier
	ds_read_b128 v[128:131], v158
	ds_read_b128 v[132:135], v158 offset:1024
	ds_read_b128 v[154:157], v158 offset:2048
	ds_read_b128 v[158:161], v158 offset:3072
	s_add_u32 s44, s44, 0x200000
	s_addc_u32 s45, s45, 0
	s_mov_b32 m0, s56
	v_lshl_add_u64 v[208:209], s[44:45], 0, v[136:137]
	ds_read_b128 v[162:165], v180 offset:32768
	ds_read_b128 v[166:169], v180 offset:33792
	ds_read_b128 v[170:173], v180 offset:34816
	ds_read_b128 v[184:187], v180 offset:35840
	ds_read_b128 v[188:191], v180 offset:36864
	ds_read_b128 v[192:195], v180 offset:37888
	ds_read_b128 v[196:199], v180 offset:38912
	ds_read_b128 v[204:207], v180 offset:39936
	global_load_lds_dwordx4 v[208:209], off
	v_lshl_add_u64 v[208:209], s[44:45], 0, v[142:143]
	s_mov_b32 m0, s57
	s_nop 0
	global_load_lds_dwordx4 v[208:209], off
	s_waitcnt lgkmcnt(8)
	s_barrier
	s_waitcnt lgkmcnt(0)
	v_mfma_f32_16x16x32_bf16 v[124:127], v[128:131], v[162:165], v[124:127]
	v_mfma_f32_16x16x32_bf16 v[120:123], v[154:157], v[162:165], v[120:123]
	v_mfma_f32_16x16x32_bf16 v[108:111], v[128:131], v[170:173], v[108:111]
	v_mfma_f32_16x16x32_bf16 v[104:107], v[154:157], v[170:173], v[104:107]
	v_mfma_f32_16x16x32_bf16 v[92:95], v[128:131], v[188:191], v[92:95]
	v_mfma_f32_16x16x32_bf16 v[88:91], v[154:157], v[188:191], v[88:91]
	v_mfma_f32_16x16x32_bf16 v[76:79], v[128:131], v[196:199], v[76:79]
	v_mfma_f32_16x16x32_bf16 v[72:75], v[154:157], v[196:199], v[72:75]
	v_mfma_f32_16x16x32_bf16 v[124:127], v[132:135], v[166:169], v[124:127]
	v_mfma_f32_16x16x32_bf16 v[120:123], v[158:161], v[166:169], v[120:123]
	v_mfma_f32_16x16x32_bf16 v[108:111], v[132:135], v[184:187], v[108:111]
	v_mfma_f32_16x16x32_bf16 v[104:107], v[158:161], v[184:187], v[104:107]
	v_mfma_f32_16x16x32_bf16 v[92:95], v[132:135], v[192:195], v[92:95]
	v_mfma_f32_16x16x32_bf16 v[88:91], v[158:161], v[192:195], v[88:91]
	v_mfma_f32_16x16x32_bf16 v[76:79], v[132:135], v[204:207], v[76:79]
	v_mfma_f32_16x16x32_bf16 v[72:75], v[158:161], v[204:207], v[72:75]
	s_barrier
	s_add_i32 s44, 0, 0x1c000
	s_add_i32 s33, s33, s53
	v_add_u32_e32 v203, s44, v175
	v_lshl_add_u64 v[200:201], v[200:201], 0, s[26:27]
	s_mov_b32 m0, s33
	ds_read_b128 v[208:211], v203
	ds_read_b128 v[212:215], v203 offset:1024
	ds_read_b128 v[216:219], v203 offset:2048
	ds_read_b128 v[220:223], v203 offset:3072
	global_load_lds_dwordx4 v[200:201], off
	v_lshl_add_u64 v[200:201], v[224:225], 0, s[26:27]
	s_add_i32 m0, s33, 0x2000
	s_nop 0
	global_load_lds_dwordx4 v[200:201], off
	s_waitcnt lgkmcnt(0)
	s_barrier
	s_waitcnt lgkmcnt(0)
	v_mfma_f32_16x16x32_bf16 v[116:119], v[208:211], v[162:165], v[116:119]
	v_mfma_f32_16x16x32_bf16 v[112:115], v[216:219], v[162:165], v[112:115]
	v_mfma_f32_16x16x32_bf16 v[100:103], v[208:211], v[170:173], v[100:103]
	v_mfma_f32_16x16x32_bf16 v[96:99], v[216:219], v[170:173], v[96:99]
	v_mfma_f32_16x16x32_bf16 v[84:87], v[208:211], v[188:191], v[84:87]
	v_mfma_f32_16x16x32_bf16 v[80:83], v[216:219], v[188:191], v[80:83]
	v_mfma_f32_16x16x32_bf16 v[68:71], v[208:211], v[196:199], v[68:71]
	v_mfma_f32_16x16x32_bf16 v[64:67], v[216:219], v[196:199], v[64:67]
	v_mfma_f32_16x16x32_bf16 v[116:119], v[212:215], v[166:169], v[116:119]
	v_mfma_f32_16x16x32_bf16 v[112:115], v[220:223], v[166:169], v[112:115]
	v_mfma_f32_16x16x32_bf16 v[100:103], v[212:215], v[184:187], v[100:103]
	v_mfma_f32_16x16x32_bf16 v[96:99], v[220:223], v[184:187], v[96:99]
	v_mfma_f32_16x16x32_bf16 v[84:87], v[212:215], v[192:195], v[84:87]
	v_mfma_f32_16x16x32_bf16 v[80:83], v[220:223], v[192:195], v[80:83]
	v_mfma_f32_16x16x32_bf16 v[68:71], v[212:215], v[204:207], v[68:71]
	v_mfma_f32_16x16x32_bf16 v[64:67], v[220:223], v[204:207], v[64:67]
	s_mov_b32 m0, s60
	v_lshl_add_u64 v[200:201], v[226:227], 0, s[26:27]
	s_barrier
; #define PG8_STAGE(bufoff, gbase, voff) do { _Pragma("unroll") for (int _i = 0; _i < 2; ++_i) \
;         __builtin_amdgcn_global_load_lds((const unsigned*)((const char*)(gbase) + (voff)[_i]), (LAS unsigned*)(lds + (bufoff) + ldsw + _i * 8192), 16, 0, 0); } while (0)
; #define PG8_LDA(dst, b, h) do { _Pragma("unroll") for (int m = 0; m < 4; ++m) _Pragma("unroll") for (int k = 0; k < 2; ++k) dst[m][k] = *(const LAS bf16x8*)(lds + PG8_SA(b, h) + aoff + m * 2048 + k * 1024); } while (0)
; #define PG8_MMA(ai, bj, At, Bt) do { __builtin_amdgcn_s_setprio(1); _Pragma("unroll") for (int m = 0; m < 4; ++m) _Pragma("unroll") for (int n = 0; n < 2; ++n) _Pragma("unroll") for (int k = 0; k < 2; ++k) \
;         acc[ai][bj][m][n] = __builtin_amdgcn_mfma_f32_16x16x32_bf16(Bt[n][k], At[m][k], acc[ai][bj][m][n], 0, 0, 0); __builtin_amdgcn_s_setprio(0); } while (0)
; #define PG8_WAIT_V(n) asm volatile("s_waitcnt vmcnt(" #n ")" ::: "memory")
; #define PG8_WAIT_L(n) asm volatile("s_waitcnt lgkmcnt(" #n ")" ::: "memory")
; #define PG8_BAR __builtin_amdgcn_s_barrier()
; #define PG8_SCHED __builtin_amdgcn_sched_barrier(0)
;     __device__ __forceinline__ void operator()(const f32x4 (&acc)[2][2][4][2], const Unit& u, int wr, int wc, int fr, int fq) const {
;     ...
;             for (int m = 0; m < 4; ++m) { const int row = row0 + ai * HALF + m * 16; const size_t off = (size_t)row * D + col0; float sq = 0.f; u32x4 w[2];
;                 const float sc = rsin ? __builtin_amdgcn_rcpf(rsin[row] * (1.f / D) + EPS) : 1.0f;
;                 u32x4 rr[2]; if (R) load_pair_lines(R, D, row, fr, col0, rr[0], rr[1]);
; template <class Epi>
; __device__ __forceinline__ void gemm_phase(LAS unsigned char* lds, const Gemm g, const StaticOrder& S, const Epi& E) {
;     ...
;             PG8_LDA(At, 1, 1); PG8_STAGE(PG8_SA(1, 0), a3, voffA);
;             PG8_BAR; PG8_WAIT_L(0); PG8_MMA(1, 0, At, B0); PG8_BAR; PG8_SCHED;
;             PG8_STAGE(PG8_SB(1, 1), b3, voffB1);
;             PG8_WAIT_V(6); PG8_BAR; PG8_MMA(1, 1, At, B1); PG8_BAR;
;         }
	ds_read_b128 v[162:165], v180 offset:49152
	ds_read_b128 v[166:169], v180 offset:50176
	ds_read_b128 v[170:173], v180 offset:51200
	ds_read_b128 v[184:187], v180 offset:52224
	ds_read_b128 v[188:191], v180 offset:53248
	ds_read_b128 v[192:195], v180 offset:54272
	ds_read_b128 v[196:199], v180 offset:55296
	ds_read_b128 v[204:207], v180 offset:56320
	global_load_lds_dwordx4 v[200:201], off
	v_lshl_add_u64 v[200:201], v[228:229], 0, s[26:27]
	s_mov_b32 m0, s61
	s_nop 0
	global_load_lds_dwordx4 v[200:201], off
	s_add_i32 s33, s44, s53
	v_lshl_add_u64 v[250:251], v[230:231], 0, s[26:27]
	s_mov_b32 m0, s33
	s_nop 0
	global_load_lds_dwordx4 v[250:251], off
	v_lshl_add_u64 v[250:251], v[232:233], 0, s[26:27]
	s_add_i32 m0, s33, 0x2000
	s_nop 0
	global_load_lds_dwordx4 v[250:251], off
	s_waitcnt vmcnt(6)
	s_barrier
	s_waitcnt lgkmcnt(0)
	v_mfma_f32_16x16x32_bf16 v[60:63], v[128:131], v[162:165], v[60:63]
	v_mfma_f32_16x16x32_bf16 v[56:59], v[154:157], v[162:165], v[56:59]
	v_mfma_f32_16x16x32_bf16 v[44:47], v[128:131], v[170:173], v[44:47]
	v_mfma_f32_16x16x32_bf16 v[40:43], v[154:157], v[170:173], v[40:43]
	v_mfma_f32_16x16x32_bf16 v[28:31], v[128:131], v[188:191], v[28:31]
	v_mfma_f32_16x16x32_bf16 v[24:27], v[154:157], v[188:191], v[24:27]
	v_mfma_f32_16x16x32_bf16 v[12:15], v[128:131], v[196:199], v[12:15]
	v_mfma_f32_16x16x32_bf16 v[8:11], v[154:157], v[196:199], v[8:11]
	v_mfma_f32_16x16x32_bf16 v[60:63], v[132:135], v[166:169], v[60:63]
	v_mfma_f32_16x16x32_bf16 v[56:59], v[158:161], v[166:169], v[56:59]
	v_mfma_f32_16x16x32_bf16 v[44:47], v[132:135], v[184:187], v[44:47]
	v_mfma_f32_16x16x32_bf16 v[40:43], v[158:161], v[184:187], v[40:43]
	v_mfma_f32_16x16x32_bf16 v[28:31], v[132:135], v[192:195], v[28:31]
	v_mfma_f32_16x16x32_bf16 v[24:27], v[158:161], v[192:195], v[24:27]
	v_mfma_f32_16x16x32_bf16 v[12:15], v[132:135], v[204:207], v[12:15]
	v_mfma_f32_16x16x32_bf16 v[8:11], v[158:161], v[204:207], v[8:11]
	v_mfma_f32_16x16x32_bf16 v[52:55], v[208:211], v[162:165], v[52:55]
	v_mfma_f32_16x16x32_bf16 v[48:51], v[216:219], v[162:165], v[48:51]
	v_mfma_f32_16x16x32_bf16 v[36:39], v[208:211], v[170:173], v[36:39]
	v_mfma_f32_16x16x32_bf16 v[32:35], v[216:219], v[170:173], v[32:35]
	v_mfma_f32_16x16x32_bf16 v[20:23], v[208:211], v[188:191], v[20:23]
	v_mfma_f32_16x16x32_bf16 v[16:19], v[216:219], v[188:191], v[16:19]
	v_mfma_f32_16x16x32_bf16 v[4:7], v[208:211], v[196:199], v[4:7]
	v_mfma_f32_16x16x32_bf16 v[0:3], v[216:219], v[196:199], v[0:3]
	v_mfma_f32_16x16x32_bf16 v[52:55], v[212:215], v[166:169], v[52:55]
	v_mfma_f32_16x16x32_bf16 v[48:51], v[220:223], v[166:169], v[48:51]
	v_mfma_f32_16x16x32_bf16 v[36:39], v[212:215], v[184:187], v[36:39]
	v_mfma_f32_16x16x32_bf16 v[32:35], v[220:223], v[184:187], v[32:35]
	v_mfma_f32_16x16x32_bf16 v[20:23], v[212:215], v[192:195], v[20:23]
	v_mfma_f32_16x16x32_bf16 v[16:19], v[220:223], v[192:195], v[16:19]
	v_mfma_f32_16x16x32_bf16 v[4:7], v[212:215], v[204:207], v[4:7]
	v_mfma_f32_16x16x32_bf16 v[0:3], v[220:223], v[204:207], v[0:3]
	s_add_i32 s74, s74, 2
	s_add_u32 s42, s42, 0x100
	s_addc_u32 s43, s43, 0
	s_add_u32 s72, s72, 0x100
	s_addc_u32 s73, s73, 0
	s_cmpk_gt_u32 s74, 0x7d
	s_barrier
	s_cbranch_scc0 .LBB0_1443
	s_lshl_b32 s9, s10, 8
	s_add_i32 s10, s9, s62
	v_or_b32_e32 v158, s10, v174
	v_ashrrev_i32_e32 v159, 31, v158
	v_lshl_add_u64 v[160:161], v[158:159], 2, s[18:19]
	global_load_dword v168, v[160:161], off
	v_lshl_or_b32 v156, s8, 8, v178
	v_or_b32_e32 v154, v156, v177
	v_ashrrev_i32_e32 v155, 31, v154
	v_cndmask_b32_e64 v128, 0, 1, s[28:29]
	v_or_b32_e32 v166, s10, v176
	v_cmp_ne_u32_e64 s[8:9], 1, v128
	s_andn2_b64 vcc, exec, s[28:29]
	v_lshlrev_b64 v[162:163], 1, v[154:155]
	v_ashrrev_i32_e32 v167, 31, v166
	v_or_b32_e32 v164, 8, v166
	s_cbranch_vccnz .LBB0_1447
	v_ashrrev_i32_e32 v165, 31, v164
	v_lshlrev_b64 v[128:129], 12, v[166:167]
	v_lshlrev_b64 v[132:133], 12, v[164:165]
	v_lshl_add_u64 v[128:129], s[16:17], 0, v[128:129]
	v_lshl_add_u64 v[132:133], s[16:17], 0, v[132:133]
	v_lshl_add_u64 v[128:129], v[128:129], 0, v[162:163]
	v_lshl_add_u64 v[132:133], v[132:133], 0, v[162:163]
	global_load_dwordx4 v[128:131], v[128:129], off
	global_load_dwordx4 v[132:135], v[132:133], off
	s_waitcnt vmcnt(0)
	v_mov_b32_dpp v157, v128 row_ror:8 row_mask:0xf bank_mask:0xf
	v_mov_b32_dpp v165, v129 row_ror:8 row_mask:0xf bank_mask:0xf
	v_mov_b32_dpp v169, v130 row_ror:8 row_mask:0xf bank_mask:0xf
	v_mov_b32_dpp v170, v131 row_ror:8 row_mask:0xf bank_mask:0xf
	v_mov_b32_dpp v171, v132 row_ror:8 row_mask:0xf bank_mask:0xf
	v_mov_b32_dpp v172, v133 row_ror:8 row_mask:0xf bank_mask:0xf
	v_mov_b32_dpp v173, v134 row_ror:8 row_mask:0xf bank_mask:0xf
	v_mov_b32_dpp v187, v135 row_ror:8 row_mask:0xf bank_mask:0xf
	v_cndmask_b32_e64 v184, v132, v157, s[6:7]
	v_cndmask_b32_e64 v185, v133, v165, s[6:7]
	v_cndmask_b32_e64 v186, v134, v169, s[6:7]
	v_cndmask_b32_e64 v188, v171, v128, s[6:7]
	v_cndmask_b32_e64 v189, v172, v129, s[6:7]
	v_cndmask_b32_e64 v190, v173, v130, s[6:7]
	v_cndmask_b32_e64 v191, v187, v131, s[6:7]
	v_cndmask_b32_e64 v187, v135, v170, s[6:7]
	s_and_b64 vcc, exec, s[8:9]
	v_cmp_gt_i32_e64 s[10:11], s58, v158
	s_cbranch_vccnz .LBB0_1448

; #define PG8_STAGE(bufoff, gbase, voff) do { _Pragma("unroll") for (int _i = 0; _i < 2; ++_i) \
;         __builtin_amdgcn_global_load_lds((const unsigned*)((const char*)(gbase) + (voff)[_i]), (LAS unsigned*)(lds + (bufoff) + ldsw + _i * 8192), 16, 0, 0); } while (0)
; #define PG8_LDA(dst, b, h) do { _Pragma("unroll") for (int m = 0; m < 4; ++m) _Pragma("unroll") for (int k = 0; k < 2; ++k) dst[m][k] = *(const LAS bf16x8*)(lds + PG8_SA(b, h) + aoff + m * 2048 + k * 1024); } while (0)
; #define PG8_LDB(dst, b, h) do { _Pragma("unroll") for (int n = 0; n < 2; ++n) _Pragma("unroll") for (int k = 0; k < 2; ++k) dst[n][k] = *(const LAS bf16x8*)(lds + PG8_SB(b, h) + boff + n * 2048 + k * 1024); } while (0)
; #define PG8_MMA(ai, bj, At, Bt) do { __builtin_amdgcn_s_setprio(1); _Pragma("unroll") for (int m = 0; m < 4; ++m) _Pragma("unroll") for (int n = 0; n < 2; ++n) _Pragma("unroll") for (int k = 0; k < 2; ++k) \
;         acc[ai][bj][m][n] = __builtin_amdgcn_mfma_f32_16x16x32_bf16(Bt[n][k], At[m][k], acc[ai][bj][m][n], 0, 0, 0); __builtin_amdgcn_s_setprio(0); } while (0)
; #define PG8_WAIT_V(n) asm volatile("s_waitcnt vmcnt(" #n ")" ::: "memory")
; #define PG8_WAIT_L(n) asm volatile("s_waitcnt lgkmcnt(" #n ")" ::: "memory")
; #define PG8_BAR __builtin_amdgcn_s_barrier()
; template <class Epi>
; __device__ __forceinline__ void gemm_phase(LAS unsigned char* lds, const Gemm g, const StaticOrder& S, const Epi& E) {
;     ...
;         for (int t = 0; t < nt; t += 2) {
;             const bool last = (t == nt - 2);
;             const char* a1 = cA + (size_t)(t + 1) * kstep;
;             const char* a2 = last ? nA : cA + (size_t)(t + 2) * kstep; const char* b2 = last ? nB : cB + (size_t)(t + 2) * kstep;
;             const char* a3 = a2 + kstep; const char* b3 = b2 + kstep;
;             PG8_LDB(B0, 0, 0); PG8_SCHED; PG8_LDA(At, 0, 0); PG8_STAGE(PG8_SA(1, 1), a1 + hstep, voffA);
;             PG8_WAIT_L(8); PG8_BAR; PG8_WAIT_L(0); PG8_MMA(0, 0, At, B0); PG8_BAR; PG8_SCHED;
;             PG8_LDB(B1, 0, 1); PG8_STAGE(PG8_SB(0, 0), b2, voffB0);
;             PG8_BAR; PG8_WAIT_L(0); PG8_MMA(0, 1, At, B1); PG8_BAR;
;             PG8_LDA(At, 0, 1); PG8_STAGE(PG8_SA(0, 0), a2, voffA);
;             PG8_BAR; PG8_WAIT_L(0); PG8_MMA(1, 0, At, B0); PG8_BAR; PG8_SCHED;
;             PG8_STAGE(PG8_SB(0, 1), b2, voffB1);
;             PG8_WAIT_V(6); PG8_BAR; PG8_MMA(1, 1, At, B1); PG8_BAR;
.LBB0_1603:
	ds_read_b128 v[40:43], v179
	ds_read_b128 v[44:47], v179 offset:1024
	ds_read_b128 v[56:59], v179 offset:2048
	ds_read_b128 v[60:63], v179 offset:3072
	s_add_u32 s36, s34, 0xfff80080
	s_addc_u32 s37, s35, -1
	s_cmp_eq_u32 s58, 28
	s_cselect_b32 s37, s23, s37
	s_cselect_b32 s36, s54, s36
	s_cselect_b32 s39, s19, s57
	s_cselect_b32 s38, s55, s56
	v_lshl_add_u64 v[172:173], s[34:35], 0, v[158:159]
	s_add_i32 m0, s31, 0xc000
	ds_read_b128 v[164:167], v180
	ds_read_b128 v[168:171], v180 offset:1024
	ds_read_b128 v[184:187], v180 offset:2048
	ds_read_b128 v[188:191], v180 offset:3072
	ds_read_b128 v[192:195], v180 offset:4096
	ds_read_b128 v[196:199], v180 offset:5120
	ds_read_b128 v[200:203], v180 offset:6144
	ds_read_b128 v[204:207], v180 offset:7168
	global_load_lds_dwordx4 v[172:173], off
	v_lshl_add_u64 v[172:173], s[34:35], 0, v[160:161]
	s_add_i32 m0, s31, 0xe000
	s_nop 0
	global_load_lds_dwordx4 v[172:173], off
	s_waitcnt lgkmcnt(8)
	s_barrier
	s_waitcnt lgkmcnt(0)
	v_mfma_f32_16x16x32_bf16 v[140:143], v[40:43], v[164:167], v[140:143]
	v_mfma_f32_16x16x32_bf16 v[136:139], v[56:59], v[164:167], v[136:139]
	v_mfma_f32_16x16x32_bf16 v[124:127], v[40:43], v[184:187], v[124:127]
	v_mfma_f32_16x16x32_bf16 v[120:123], v[56:59], v[184:187], v[120:123]
	v_mfma_f32_16x16x32_bf16 v[108:111], v[40:43], v[192:195], v[108:111]
	v_mfma_f32_16x16x32_bf16 v[104:107], v[56:59], v[192:195], v[104:107]
	v_mfma_f32_16x16x32_bf16 v[92:95], v[40:43], v[200:203], v[92:95]
	v_mfma_f32_16x16x32_bf16 v[88:91], v[56:59], v[200:203], v[88:91]
	v_mfma_f32_16x16x32_bf16 v[140:143], v[44:47], v[168:171], v[140:143]
	v_mfma_f32_16x16x32_bf16 v[136:139], v[60:63], v[168:171], v[136:139]
	v_mfma_f32_16x16x32_bf16 v[124:127], v[44:47], v[188:191], v[124:127]
	v_mfma_f32_16x16x32_bf16 v[120:123], v[60:63], v[188:191], v[120:123]
	v_mfma_f32_16x16x32_bf16 v[108:111], v[44:47], v[196:199], v[108:111]
	v_mfma_f32_16x16x32_bf16 v[104:107], v[60:63], v[196:199], v[104:107]
	v_mfma_f32_16x16x32_bf16 v[92:95], v[44:47], v[204:207], v[92:95]
	v_mfma_f32_16x16x32_bf16 v[88:91], v[60:63], v[204:207], v[88:91]
	s_barrier
	s_add_i32 s59, s51, s41
	v_lshl_add_u64 v[172:173], s[38:39], 0, v[146:147]
	s_mov_b32 m0, s59
	ds_read_b128 v[208:211], v181
	ds_read_b128 v[212:215], v181 offset:1024
	ds_read_b128 v[216:219], v181 offset:2048
	ds_read_b128 v[220:223], v181 offset:3072
	global_load_lds_dwordx4 v[172:173], off
	v_lshl_add_u64 v[224:225], s[38:39], 0, v[152:153]
	s_add_i32 m0, s59, 0x2000
	s_nop 0
	global_load_lds_dwordx4 v[224:225], off
	s_waitcnt lgkmcnt(0)
	s_barrier
	s_waitcnt lgkmcnt(0)
	v_mfma_f32_16x16x32_bf16 v[132:135], v[208:211], v[164:167], v[132:135]
	v_mfma_f32_16x16x32_bf16 v[128:131], v[216:219], v[164:167], v[128:131]
	v_mfma_f32_16x16x32_bf16 v[116:119], v[208:211], v[184:187], v[116:119]
	v_mfma_f32_16x16x32_bf16 v[112:115], v[216:219], v[184:187], v[112:115]
	v_mfma_f32_16x16x32_bf16 v[100:103], v[208:211], v[192:195], v[100:103]
	v_mfma_f32_16x16x32_bf16 v[96:99], v[216:219], v[192:195], v[96:99]
	v_mfma_f32_16x16x32_bf16 v[84:87], v[208:211], v[200:203], v[84:87]
	v_mfma_f32_16x16x32_bf16 v[80:83], v[216:219], v[200:203], v[80:83]
	v_mfma_f32_16x16x32_bf16 v[132:135], v[212:215], v[168:171], v[132:135]
	v_mfma_f32_16x16x32_bf16 v[128:131], v[220:223], v[168:171], v[128:131]
	v_mfma_f32_16x16x32_bf16 v[116:119], v[212:215], v[188:191], v[116:119]
	v_mfma_f32_16x16x32_bf16 v[112:115], v[220:223], v[188:191], v[112:115]
	v_mfma_f32_16x16x32_bf16 v[100:103], v[212:215], v[196:199], v[100:103]
	v_mfma_f32_16x16x32_bf16 v[96:99], v[220:223], v[196:199], v[96:99]
	v_mfma_f32_16x16x32_bf16 v[84:87], v[212:215], v[204:207], v[84:87]
	v_mfma_f32_16x16x32_bf16 v[80:83], v[220:223], v[204:207], v[80:83]
	s_mov_b32 m0, s31
	v_lshl_add_u64 v[226:227], s[36:37], 0, v[144:145]
	s_barrier
	ds_read_b128 v[164:167], v180 offset:16384
	ds_read_b128 v[168:171], v180 offset:17408
	ds_read_b128 v[184:187], v180 offset:18432
	ds_read_b128 v[188:191], v180 offset:19456
	ds_read_b128 v[192:195], v180 offset:20480
	ds_read_b128 v[196:199], v180 offset:21504
	ds_read_b128 v[200:203], v180 offset:22528
	ds_read_b128 v[204:207], v180 offset:23552
	global_load_lds_dwordx4 v[226:227], off
	v_lshl_add_u64 v[228:229], s[36:37], 0, v[150:151]
	s_mov_b32 m0, s42
	s_nop 0
	global_load_lds_dwordx4 v[228:229], off
	s_add_i32 s59, s52, s41
	v_lshl_add_u64 v[230:231], s[38:39], 0, v[148:149]
	s_mov_b32 m0, s59
	v_lshl_add_u64 v[232:233], s[38:39], 0, v[154:155]
	global_load_lds_dwordx4 v[230:231], off
	s_add_i32 m0, s59, 0x2000
	s_nop 0
	global_load_lds_dwordx4 v[232:233], off
	s_waitcnt vmcnt(6)
	s_barrier
; #define PG8_STAGE(bufoff, gbase, voff) do { _Pragma("unroll") for (int _i = 0; _i < 2; ++_i) \
;         __builtin_amdgcn_global_load_lds((const unsigned*)((const char*)(gbase) + (voff)[_i]), (LAS unsigned*)(lds + (bufoff) + ldsw + _i * 8192), 16, 0, 0); } while (0)
; #define PG8_LDA(dst, b, h) do { _Pragma("unroll") for (int m = 0; m < 4; ++m) _Pragma("unroll") for (int k = 0; k < 2; ++k) dst[m][k] = *(const LAS bf16x8*)(lds + PG8_SA(b, h) + aoff + m * 2048 + k * 1024); } while (0)
; #define PG8_LDB(dst, b, h) do { _Pragma("unroll") for (int n = 0; n < 2; ++n) _Pragma("unroll") for (int k = 0; k < 2; ++k) dst[n][k] = *(const LAS bf16x8*)(lds + PG8_SB(b, h) + boff + n * 2048 + k * 1024); } while (0)
; #define PG8_MMA(ai, bj, At, Bt) do { __builtin_amdgcn_s_setprio(1); _Pragma("unroll") for (int m = 0; m < 4; ++m) _Pragma("unroll") for (int n = 0; n < 2; ++n) _Pragma("unroll") for (int k = 0; k < 2; ++k) \
;         acc[ai][bj][m][n] = __builtin_amdgcn_mfma_f32_16x16x32_bf16(Bt[n][k], At[m][k], acc[ai][bj][m][n], 0, 0, 0); __builtin_amdgcn_s_setprio(0); } while (0)
; #define PG8_WAIT_V(n) asm volatile("s_waitcnt vmcnt(" #n ")" ::: "memory")
; #define PG8_WAIT_L(n) asm volatile("s_waitcnt lgkmcnt(" #n ")" ::: "memory")
; #define PG8_BAR __builtin_amdgcn_s_barrier()
; #define PG8_SCHED __builtin_amdgcn_sched_barrier(0)
; template <class Epi>
; __device__ __forceinline__ void gemm_phase(LAS unsigned char* lds, const Gemm g, const StaticOrder& S, const Epi& E) {
;     ...
;             PG8_BAR; PG8_WAIT_L(0); PG8_MMA(1, 0, At, B0); PG8_BAR; PG8_SCHED;
;             PG8_STAGE(PG8_SB(0, 1), b2, voffB1);
;             PG8_WAIT_V(6); PG8_BAR; PG8_MMA(1, 1, At, B1); PG8_BAR;
;             PG8_LDB(B0, 1, 0); PG8_SCHED; PG8_LDA(At, 1, 0); PG8_STAGE(PG8_SA(0, 1), a2 + hstep, voffA);
;             PG8_WAIT_L(8); PG8_BAR; PG8_WAIT_L(0); PG8_MMA(0, 0, At, B0); PG8_BAR; PG8_SCHED;
;             PG8_LDB(B1, 1, 1); PG8_STAGE(PG8_SB(1, 0), b3, voffB0);
;             PG8_BAR; PG8_WAIT_L(0); PG8_MMA(0, 1, At, B1); PG8_BAR;
;             PG8_LDA(At, 1, 1); PG8_STAGE(PG8_SA(1, 0), a3, voffA);
;             PG8_BAR; PG8_WAIT_L(0); PG8_MMA(1, 0, At, B0); PG8_BAR; PG8_SCHED;
	s_waitcnt lgkmcnt(0)
	v_mfma_f32_16x16x32_bf16 v[76:79], v[40:43], v[164:167], v[76:79]
	v_mfma_f32_16x16x32_bf16 v[72:75], v[56:59], v[164:167], v[72:75]
	v_mfma_f32_16x16x32_bf16 v[52:55], v[40:43], v[184:187], v[52:55]
	v_mfma_f32_16x16x32_bf16 v[48:51], v[56:59], v[184:187], v[48:51]
	v_mfma_f32_16x16x32_bf16 v[28:31], v[40:43], v[192:195], v[28:31]
	v_mfma_f32_16x16x32_bf16 v[24:27], v[56:59], v[192:195], v[24:27]
	v_mfma_f32_16x16x32_bf16 v[12:15], v[40:43], v[200:203], v[12:15]
	v_mfma_f32_16x16x32_bf16 v[8:11], v[56:59], v[200:203], v[8:11]
	v_mfma_f32_16x16x32_bf16 v[76:79], v[44:47], v[168:171], v[76:79]
	v_mfma_f32_16x16x32_bf16 v[72:75], v[60:63], v[168:171], v[72:75]
	v_mfma_f32_16x16x32_bf16 v[52:55], v[44:47], v[188:191], v[52:55]
	v_mfma_f32_16x16x32_bf16 v[48:51], v[60:63], v[188:191], v[48:51]
	v_mfma_f32_16x16x32_bf16 v[28:31], v[44:47], v[196:199], v[28:31]
	v_mfma_f32_16x16x32_bf16 v[24:27], v[60:63], v[196:199], v[24:27]
	v_mfma_f32_16x16x32_bf16 v[12:15], v[44:47], v[204:207], v[12:15]
	v_mfma_f32_16x16x32_bf16 v[8:11], v[60:63], v[204:207], v[8:11]
	v_mfma_f32_16x16x32_bf16 v[36:39], v[208:211], v[184:187], v[36:39]
	v_mfma_f32_16x16x32_bf16 v[32:35], v[216:219], v[184:187], v[32:35]
	v_mfma_f32_16x16x32_bf16 v[20:23], v[208:211], v[192:195], v[20:23]
	v_mfma_f32_16x16x32_bf16 v[16:19], v[216:219], v[192:195], v[16:19]
	v_mfma_f32_16x16x32_bf16 v[4:7], v[208:211], v[200:203], v[4:7]
	v_mfma_f32_16x16x32_bf16 v[0:3], v[216:219], v[200:203], v[0:3]
	v_mfma_f32_16x16x32_bf16 v[40:43], v[208:211], v[164:167], v[68:71]
	v_mfma_f32_16x16x32_bf16 v[44:47], v[216:219], v[164:167], v[64:67]
	v_mfma_f32_16x16x32_bf16 v[36:39], v[212:215], v[188:191], v[36:39]
	v_mfma_f32_16x16x32_bf16 v[32:35], v[220:223], v[188:191], v[32:35]
	v_mfma_f32_16x16x32_bf16 v[20:23], v[212:215], v[196:199], v[20:23]
	v_mfma_f32_16x16x32_bf16 v[16:19], v[220:223], v[196:199], v[16:19]
	v_mfma_f32_16x16x32_bf16 v[4:7], v[212:215], v[204:207], v[4:7]
	v_mfma_f32_16x16x32_bf16 v[0:3], v[220:223], v[204:207], v[0:3]
	v_mfma_f32_16x16x32_bf16 v[40:43], v[212:215], v[168:171], v[40:43]
	v_mfma_f32_16x16x32_bf16 v[44:47], v[220:223], v[168:171], v[44:47]
	s_add_i32 s38, 0, 0x18000
	v_add_u32_e32 v68, s38, v175
	s_barrier
	ds_read_b128 v[56:59], v68
	ds_read_b128 v[60:63], v68 offset:1024
	ds_read_b128 v[64:67], v68 offset:2048
	ds_read_b128 v[68:71], v68 offset:3072
	s_add_u32 s36, s36, 0x80000
	s_addc_u32 s37, s37, 0
	s_mov_b32 m0, s43
	v_lshl_add_u64 v[208:209], s[36:37], 0, v[144:145]
	ds_read_b128 v[164:167], v180 offset:32768
	ds_read_b128 v[168:171], v180 offset:33792
	ds_read_b128 v[184:187], v180 offset:34816
	ds_read_b128 v[188:191], v180 offset:35840
	ds_read_b128 v[192:195], v180 offset:36864
	ds_read_b128 v[196:199], v180 offset:37888
	ds_read_b128 v[200:203], v180 offset:38912
	ds_read_b128 v[204:207], v180 offset:39936
	global_load_lds_dwordx4 v[208:209], off
	v_lshl_add_u64 v[208:209], s[36:37], 0, v[150:151]
	s_mov_b32 m0, s44
	s_nop 0
	global_load_lds_dwordx4 v[208:209], off
	s_waitcnt lgkmcnt(8)
	s_barrier
	s_waitcnt lgkmcnt(0)
	v_mfma_f32_16x16x32_bf16 v[140:143], v[56:59], v[164:167], v[140:143]
	v_mfma_f32_16x16x32_bf16 v[136:139], v[64:67], v[164:167], v[136:139]
	v_mfma_f32_16x16x32_bf16 v[124:127], v[56:59], v[184:187], v[124:127]
	v_mfma_f32_16x16x32_bf16 v[120:123], v[64:67], v[184:187], v[120:123]
	v_mfma_f32_16x16x32_bf16 v[108:111], v[56:59], v[192:195], v[108:111]
	v_mfma_f32_16x16x32_bf16 v[104:107], v[64:67], v[192:195], v[104:107]
	v_mfma_f32_16x16x32_bf16 v[92:95], v[56:59], v[200:203], v[92:95]
	v_mfma_f32_16x16x32_bf16 v[88:91], v[64:67], v[200:203], v[88:91]
	v_mfma_f32_16x16x32_bf16 v[140:143], v[60:63], v[168:171], v[140:143]
	v_mfma_f32_16x16x32_bf16 v[136:139], v[68:71], v[168:171], v[136:139]
	v_mfma_f32_16x16x32_bf16 v[124:127], v[60:63], v[188:191], v[124:127]
	v_mfma_f32_16x16x32_bf16 v[120:123], v[68:71], v[188:191], v[120:123]
	v_mfma_f32_16x16x32_bf16 v[108:111], v[60:63], v[196:199], v[108:111]
	v_mfma_f32_16x16x32_bf16 v[104:107], v[68:71], v[196:199], v[104:107]
	v_mfma_f32_16x16x32_bf16 v[92:95], v[60:63], v[204:207], v[92:95]
	v_mfma_f32_16x16x32_bf16 v[88:91], v[68:71], v[204:207], v[88:91]
	s_barrier
	s_add_i32 s36, 0, 0x1c000
	s_add_i32 s37, s38, s41
	v_add_u32_e32 v183, s36, v175
	v_lshl_add_u64 v[172:173], v[172:173], 0, s[14:15]
	s_mov_b32 m0, s37
	ds_read_b128 v[208:211], v183
	ds_read_b128 v[212:215], v183 offset:1024
	ds_read_b128 v[216:219], v183 offset:2048
	ds_read_b128 v[220:223], v183 offset:3072
	global_load_lds_dwordx4 v[172:173], off
	v_lshl_add_u64 v[172:173], v[224:225], 0, s[14:15]
	s_add_i32 m0, s37, 0x2000
	s_nop 0
	global_load_lds_dwordx4 v[172:173], off
	s_waitcnt lgkmcnt(0)
	s_barrier
	s_waitcnt lgkmcnt(0)
	v_mfma_f32_16x16x32_bf16 v[132:135], v[208:211], v[164:167], v[132:135]
	v_mfma_f32_16x16x32_bf16 v[128:131], v[216:219], v[164:167], v[128:131]
	v_mfma_f32_16x16x32_bf16 v[116:119], v[208:211], v[184:187], v[116:119]
	v_mfma_f32_16x16x32_bf16 v[112:115], v[216:219], v[184:187], v[112:115]
	v_mfma_f32_16x16x32_bf16 v[100:103], v[208:211], v[192:195], v[100:103]
	v_mfma_f32_16x16x32_bf16 v[96:99], v[216:219], v[192:195], v[96:99]
	v_mfma_f32_16x16x32_bf16 v[84:87], v[208:211], v[200:203], v[84:87]
	v_mfma_f32_16x16x32_bf16 v[80:83], v[216:219], v[200:203], v[80:83]
	v_mfma_f32_16x16x32_bf16 v[132:135], v[212:215], v[168:171], v[132:135]
	v_mfma_f32_16x16x32_bf16 v[128:131], v[220:223], v[168:171], v[128:131]
	v_mfma_f32_16x16x32_bf16 v[116:119], v[212:215], v[188:191], v[116:119]
	v_mfma_f32_16x16x32_bf16 v[112:115], v[220:223], v[188:191], v[112:115]
	v_mfma_f32_16x16x32_bf16 v[100:103], v[212:215], v[196:199], v[100:103]
	v_mfma_f32_16x16x32_bf16 v[96:99], v[220:223], v[196:199], v[96:99]
	v_mfma_f32_16x16x32_bf16 v[84:87], v[212:215], v[204:207], v[84:87]
	v_mfma_f32_16x16x32_bf16 v[80:83], v[220:223], v[204:207], v[80:83]
	s_mov_b32 m0, s47
	v_lshl_add_u64 v[172:173], v[226:227], 0, s[14:15]
	s_barrier
; #define PG8_STAGE(bufoff, gbase, voff) do { _Pragma("unroll") for (int _i = 0; _i < 2; ++_i) \
;         __builtin_amdgcn_global_load_lds((const unsigned*)((const char*)(gbase) + (voff)[_i]), (LAS unsigned*)(lds + (bufoff) + ldsw + _i * 8192), 16, 0, 0); } while (0)
; #define PG8_LDA(dst, b, h) do { _Pragma("unroll") for (int m = 0; m < 4; ++m) _Pragma("unroll") for (int k = 0; k < 2; ++k) dst[m][k] = *(const LAS bf16x8*)(lds + PG8_SA(b, h) + aoff + m * 2048 + k * 1024); } while (0)
; #define PG8_LDB(dst, b, h) do { _Pragma("unroll") for (int n = 0; n < 2; ++n) _Pragma("unroll") for (int k = 0; k < 2; ++k) dst[n][k] = *(const LAS bf16x8*)(lds + PG8_SB(b, h) + boff + n * 2048 + k * 1024); } while (0)
;     __device__ __forceinline__ void operator()(const f32x4 (&acc)[2][2][4][2], const Unit& u, int wr, int wc, int fr, int fq) const {
;         const int row0 = u.pm * BM + wr * 64 + fr, col0 = u.pn * BM + wc * 64 + 8 * fq;
;         f32x4 gv[2][2];
; #pragma unroll
;         for (int bj = 0; bj < 2; ++bj) { gv[bj][0] = *(const f32x4*)(g + col0 + 32 * bj); gv[bj][1] = *(const f32x4*)(g + col0 + 32 * bj + 4); }
;         const bool lo = fr < 8;
; #pragma unroll
;         for (int ai = 0; ai < 2; ++ai)
; #pragma unroll
;             for (int m = 0; m < 4; ++m) { const int row = row0 + ai * HALF + m * 16; const float ri = __builtin_amdgcn_rsqf(sse[row] * (1.f / D) + EPS);
;                 u32x4 rr[2], ee[2]; load_pair_lines(R, D, row, fr, col0, rr[0], rr[1], 32); load_pair_lines(E, D, row, fr, col0, ee[0], ee[1], 32);
; template <class Epi>
; __device__ __forceinline__ void gemm_phase(LAS unsigned char* lds, const Gemm g, const StaticOrder& S, const Epi& E) {
;     ...
;             PG8_WAIT_V(6); PG8_BAR; PG8_MMA(1, 1, At, B1); PG8_BAR;
;             PG8_LDB(B0, 1, 0); PG8_SCHED; PG8_LDA(At, 1, 0); PG8_STAGE(PG8_SA(0, 1), a2 + hstep, voffA);
;             PG8_WAIT_L(8); PG8_BAR; PG8_WAIT_L(0); PG8_MMA(0, 0, At, B0); PG8_BAR; PG8_SCHED;
;             PG8_LDB(B1, 1, 1); PG8_STAGE(PG8_SB(1, 0), b3, voffB0);
;             PG8_BAR; PG8_WAIT_L(0); PG8_MMA(0, 1, At, B1); PG8_BAR;
;             PG8_LDA(At, 1, 1); PG8_STAGE(PG8_SA(1, 0), a3, voffA);
;             PG8_BAR; PG8_WAIT_L(0); PG8_MMA(1, 0, At, B0); PG8_BAR; PG8_SCHED;
;             PG8_STAGE(PG8_SB(1, 1), b3, voffB1);
;             PG8_WAIT_V(6); PG8_BAR; PG8_MMA(1, 1, At, B1); PG8_BAR;
	ds_read_b128 v[164:167], v180 offset:49152
	ds_read_b128 v[168:171], v180 offset:50176
	ds_read_b128 v[184:187], v180 offset:51200
	ds_read_b128 v[188:191], v180 offset:52224
	ds_read_b128 v[192:195], v180 offset:53248
	ds_read_b128 v[196:199], v180 offset:54272
	ds_read_b128 v[200:203], v180 offset:55296
	ds_read_b128 v[204:207], v180 offset:56320
	global_load_lds_dwordx4 v[172:173], off
	v_lshl_add_u64 v[172:173], v[228:229], 0, s[14:15]
	s_mov_b32 m0, s48
	s_nop 0
	global_load_lds_dwordx4 v[172:173], off
	s_add_i32 s36, s36, s41
	v_lshl_add_u64 v[250:251], v[230:231], 0, s[14:15]
	s_mov_b32 m0, s36
	s_nop 0
	global_load_lds_dwordx4 v[250:251], off
	v_lshl_add_u64 v[250:251], v[232:233], 0, s[14:15]
	s_add_i32 m0, s36, 0x2000
	s_nop 0
	global_load_lds_dwordx4 v[250:251], off
	s_waitcnt vmcnt(6)
	s_barrier
	s_waitcnt lgkmcnt(0)
	v_mfma_f32_16x16x32_bf16 v[76:79], v[56:59], v[164:167], v[76:79]
	v_mfma_f32_16x16x32_bf16 v[72:75], v[64:67], v[164:167], v[72:75]
	v_mfma_f32_16x16x32_bf16 v[52:55], v[56:59], v[184:187], v[52:55]
	v_mfma_f32_16x16x32_bf16 v[48:51], v[64:67], v[184:187], v[48:51]
	v_mfma_f32_16x16x32_bf16 v[28:31], v[56:59], v[192:195], v[28:31]
	v_mfma_f32_16x16x32_bf16 v[24:27], v[64:67], v[192:195], v[24:27]
	v_mfma_f32_16x16x32_bf16 v[12:15], v[56:59], v[200:203], v[12:15]
	v_mfma_f32_16x16x32_bf16 v[8:11], v[64:67], v[200:203], v[8:11]
	v_mfma_f32_16x16x32_bf16 v[76:79], v[60:63], v[168:171], v[76:79]
	v_mfma_f32_16x16x32_bf16 v[72:75], v[68:71], v[168:171], v[72:75]
	v_mfma_f32_16x16x32_bf16 v[52:55], v[60:63], v[188:191], v[52:55]
	v_mfma_f32_16x16x32_bf16 v[48:51], v[68:71], v[188:191], v[48:51]
	v_mfma_f32_16x16x32_bf16 v[28:31], v[60:63], v[196:199], v[28:31]
	v_mfma_f32_16x16x32_bf16 v[24:27], v[68:71], v[196:199], v[24:27]
	v_mfma_f32_16x16x32_bf16 v[12:15], v[60:63], v[204:207], v[12:15]
	v_mfma_f32_16x16x32_bf16 v[8:11], v[68:71], v[204:207], v[8:11]
	v_mfma_f32_16x16x32_bf16 v[40:43], v[208:211], v[164:167], v[40:43]
	v_mfma_f32_16x16x32_bf16 v[68:71], v[212:215], v[168:171], v[40:43]
	v_mfma_f32_16x16x32_bf16 v[40:43], v[216:219], v[164:167], v[44:47]
	v_mfma_f32_16x16x32_bf16 v[36:39], v[208:211], v[184:187], v[36:39]
	v_mfma_f32_16x16x32_bf16 v[32:35], v[216:219], v[184:187], v[32:35]
	v_mfma_f32_16x16x32_bf16 v[20:23], v[208:211], v[192:195], v[20:23]
	v_mfma_f32_16x16x32_bf16 v[16:19], v[216:219], v[192:195], v[16:19]
	v_mfma_f32_16x16x32_bf16 v[4:7], v[208:211], v[200:203], v[4:7]
	v_mfma_f32_16x16x32_bf16 v[0:3], v[216:219], v[200:203], v[0:3]
	v_mfma_f32_16x16x32_bf16 v[64:67], v[220:223], v[168:171], v[40:43]
	v_mfma_f32_16x16x32_bf16 v[36:39], v[212:215], v[188:191], v[36:39]
	v_mfma_f32_16x16x32_bf16 v[32:35], v[220:223], v[188:191], v[32:35]
	v_mfma_f32_16x16x32_bf16 v[20:23], v[212:215], v[196:199], v[20:23]
	v_mfma_f32_16x16x32_bf16 v[16:19], v[220:223], v[196:199], v[16:19]
	v_mfma_f32_16x16x32_bf16 v[4:7], v[212:215], v[204:207], v[4:7]
	v_mfma_f32_16x16x32_bf16 v[0:3], v[220:223], v[204:207], v[0:3]
	s_add_i32 s58, s58, 2
	s_add_u32 s34, s34, 0x100
	s_addc_u32 s35, s35, 0
	s_add_u32 s56, s56, 0x100
	s_addc_u32 s57, s57, 0
	s_cmp_gt_u32 s58, 29
	s_barrier
	s_cbranch_scc0 .LBB0_1603
	s_lshl_b32 s19, s30, 8
	s_add_i32 s19, s19, s49
	v_lshl_or_b32 v40, s53, 8, v178
	v_or_b32_e32 v172, s19, v176
	v_or_b32_e32 v42, v40, v177
	v_ashrrev_i32_e32 v173, 31, v172
	v_or_b32_e32 v170, s19, v174
	v_ashrrev_i32_e32 v43, 31, v42
	v_lshlrev_b64 v[44:45], 12, v[172:173]
	v_ashrrev_i32_e32 v171, 31, v170
	v_lshl_add_u64 v[46:47], s[8:9], 0, v[44:45]
	v_lshlrev_b64 v[164:165], 1, v[42:43]
	v_lshl_add_u64 v[168:169], v[170:171], 2, s[6:7]
	v_lshl_add_u64 v[42:43], v[46:47], 0, v[164:165]
	global_load_dword v171, v[168:169], off
	global_load_dwordx4 v[184:187], v[42:43], off
	v_or_b32_e32 v42, 8, v172
	v_ashrrev_i32_e32 v43, 31, v42
	v_lshlrev_b64 v[42:43], 12, v[42:43]
	v_lshl_add_u64 v[46:47], s[8:9], 0, v[42:43]
	v_lshl_add_u64 v[44:45], s[10:11], 0, v[44:45]
	v_lshl_add_u64 v[42:43], s[10:11], 0, v[42:43]
	v_lshl_add_u64 v[46:47], v[46:47], 0, v[164:165]
	v_lshl_add_u64 v[44:45], v[44:45], 0, v[164:165]
	v_lshl_add_u64 v[42:43], v[42:43], 0, v[164:165]
	global_load_dwordx4 v[188:191], v[46:47], off
	global_load_dwordx4 v[192:195], v[44:45], off
	global_load_dwordx4 v[196:199], v[42:43], off
	v_ashrrev_i32_e32 v41, 31, v40
	v_lshlrev_b64 v[166:167], 2, v[40:41]
	v_lshl_add_u64 v[44:45], s[12:13], 0, v[166:167]
	global_load_dwordx4 v[56:59], v[44:45], off
	global_load_dwordx4 v[60:63], v[44:45], off offset:16
	v_mul_f32_e32 v40, 0xbfb8aa3b, v140
	v_exp_f32_e32 v215, v40
	global_load_dwordx4 v[40:43], v[44:45], off offset:128
	s_nop 0
	global_load_dwordx4 v[44:47], v[44:45], off offset:144
	v_or_b32_e32 v216, 16, v170
	v_ashrrev_i32_e32 v217, 31, v216
	v_lshl_add_u64 v[218:219], v[216:217], 2, s[6:7]
	v_sub_u32_e32 v216, v216, v174
	v_add_u32_e32 v222, v216, v176
	v_ashrrev_i32_e32 v223, 31, v222
	v_lshlrev_b64 v[216:217], 12, v[222:223]
	v_lshl_add_u64 v[224:225], v[216:217], 0, s[16:17]
	global_load_dword v228, v[218:219], off
	v_lshl_add_u64 v[218:219], s[8:9], 0, v[216:217]
	v_lshl_add_u64 v[220:221], s[8:9], 0, v[224:225]
	v_lshl_add_u64 v[216:217], s[10:11], 0, v[216:217]
	v_lshl_add_u64 v[218:219], v[218:219], 0, v[164:165]
	v_lshl_add_u64 v[220:221], v[220:221], 0, v[164:165]
	v_lshl_add_u64 v[216:217], v[216:217], 0, v[164:165]
	global_load_dwordx4 v[232:235], v[218:219], off
	global_load_dwordx4 v[236:239], v[220:221], off
	global_load_dwordx4 v[240:243], v[216:217], off
	v_lshl_add_u64 v[216:217], s[10:11], 0, v[224:225]
	v_lshl_add_u64 v[216:217], v[216:217], 0, v[164:165]
	global_load_dwordx4 v[244:247], v[216:217], off
; __device__ __forceinline__ float bflo(unsigned w) { return __uint_as_float(w << 16); }
; __device__ __forceinline__ float bfhi(unsigned w) { return __uint_as_float(w & 0xffff0000u); }
;     __device__ __forceinline__ void operator()(const f32x4 (&acc)[2][2][4][2], const Unit& u, int wr, int wc, int fr, int fq) const {
;     ...
;             for (int m = 0; m < 4; ++m) { const int row = row0 + ai * HALF + m * 16; const float ri = __builtin_amdgcn_rsqf(sse[row] * (1.f / D) + EPS);
;                 u32x4 rr[2], ee[2]; load_pair_lines(R, D, row, fr, col0, rr[0], rr[1], 32); load_pair_lines(E, D, row, fr, col0, ee[0], ee[1], 32);
;                 float* orow = OUT + (size_t)(row - fr + (fr & 7)) * D + col0 + (lo ? 0 : 4);
; #pragma unroll
;                 for (int bj = 0; bj < 2; ++bj) { const u32x4 rw = rr[bj], ew = ee[bj];
;                     const float r[8] = {bflo(rw.x), bfhi(rw.x), bflo(rw.y), bfhi(rw.y), bflo(rw.z), bfhi(rw.z), bflo(rw.w), bfhi(rw.w)};
;                     const float e[8] = {bflo(ew.x), bfhi(ew.x), bflo(ew.y), bfhi(ew.y), bflo(ew.z), bfhi(ew.z), bflo(ew.w), bfhi(ew.w)};
;                     float o[8];
; #pragma unroll
;                     for (int j = 0; j < 8; ++j) { const float a = acc[ai][bj][m][j >> 2][j & 3]; const float gg = gv[bj][j >> 2][j & 3];
;                         o[j] = r[j] + e[j] * ri * gg * __builtin_amdgcn_rcpf(1.f + __builtin_amdgcn_exp2f(-a * LOG2E)); }
	v_mul_f32_e32 v141, 0xbfb8aa3b, v141
	v_mul_f32_e32 v136, 0xbfb8aa3b, v136
	v_mul_f32_e32 v137, 0xbfb8aa3b, v137
	v_exp_f32_e32 v141, v141
	v_mul_f32_e32 v142, 0xbfb8aa3b, v142
	v_exp_f32_e32 v136, v136
	v_exp_f32_e32 v137, v137
	v_exp_f32_e32 v142, v142
	v_mul_f32_e32 v143, 0xbfb8aa3b, v143
	v_exp_f32_e32 v143, v143
	v_add_f32_e32 v141, 1.0, v141
	v_add_f32_e32 v136, 1.0, v136
	v_add_f32_e32 v137, 1.0, v137
	v_rcp_f32_e32 v136, v136
	v_rcp_f32_e32 v137, v137
	v_mul_f32_e32 v138, 0xbfb8aa3b, v138
	v_mul_f32_e32 v139, 0xbfb8aa3b, v139
	v_exp_f32_e32 v138, v138
	v_exp_f32_e32 v139, v139
	v_add_f32_e32 v138, 1.0, v138
	v_add_f32_e32 v139, 1.0, v139
	v_rcp_f32_e32 v138, v138
	v_rcp_f32_e32 v139, v139
	v_mul_f32_e32 v128, 0xbfb8aa3b, v128
	v_mul_f32_e32 v129, 0xbfb8aa3b, v129
	v_exp_f32_e32 v128, v128
	v_exp_f32_e32 v129, v129
	v_mul_f32_e32 v132, 0xbfb8aa3b, v132
	v_mul_f32_e32 v133, 0xbfb8aa3b, v133
	v_exp_f32_e32 v132, v132
	v_exp_f32_e32 v133, v133
	v_lshlrev_b64 v[172:173], 13, v[172:173]
	v_add_f32_e32 v128, 1.0, v128
	v_add_f32_e32 v129, 1.0, v129
	v_lshl_add_u64 v[172:173], s[4:5], 0, v[172:173]
	v_rcp_f32_e32 v128, v128
	v_mul_f32_e32 v130, 0xbfb8aa3b, v130
	v_mul_f32_e32 v131, 0xbfb8aa3b, v131
	v_rcp_f32_e32 v129, v129
	v_lshl_add_u64 v[172:173], v[172:173], 0, v[166:167]
	v_exp_f32_e32 v130, v130
	v_exp_f32_e32 v131, v131
	v_lshl_add_u64 v[172:173], v[172:173], 0, v[156:157]
	s_waitcnt vmcnt(5)
	v_fmamk_f32 v140, v171, 0x3a000000, v182
	v_rsq_f32_e32 v140, v140
	v_mov_b32_dpp v200, v185 row_ror:8 row_mask:0xf bank_mask:0xf
	v_mov_b32_dpp v183, v184 row_ror:8 row_mask:0xf bank_mask:0xf
	v_mov_b32_dpp v201, v186 row_ror:8 row_mask:0xf bank_mask:0xf
	v_mov_b32_dpp v202, v187 row_ror:8 row_mask:0xf bank_mask:0xf
	v_add_f32_e32 v132, 1.0, v132
	v_add_f32_e32 v133, 1.0, v133
	v_rcp_f32_e32 v132, v132
	v_mul_f32_e32 v134, 0xbfb8aa3b, v134
	v_mul_f32_e32 v135, 0xbfb8aa3b, v135
	v_mov_b32_dpp v204, v189 row_ror:8 row_mask:0xf bank_mask:0xf
	v_cndmask_b32_e64 v171, v189, v200, s[0:1]
	v_mov_b32_dpp v213, v198 row_ror:8 row_mask:0xf bank_mask:0xf
	v_cndmask_b32_e64 v200, v204, v185, s[0:1]
	v_cndmask_b32_e64 v189, v213, v194, s[0:1]
	v_rcp_f32_e32 v185, v141
	v_add_f32_e32 v141, 1.0, v142
	v_mov_b32_dpp v203, v188 row_ror:8 row_mask:0xf bank_mask:0xf
	v_mov_b32_dpp v205, v190 row_ror:8 row_mask:0xf bank_mask:0xf
	v_mov_b32_dpp v206, v191 row_ror:8 row_mask:0xf bank_mask:0xf
	v_cndmask_b32_e64 v183, v188, v183, s[0:1]
	v_rcp_f32_e32 v142, v141
	v_add_f32_e32 v141, 1.0, v143
	v_lshlrev_b32_e32 v188, 16, v189
	v_and_b32_e32 v189, 0xffff0000, v189
	v_cndmask_b32_e64 v190, v190, v201, s[0:1]
	v_cndmask_b32_e64 v201, v206, v187, s[0:1]
	v_cndmask_b32_e64 v187, v205, v186, s[0:1]
	v_pk_mul_f32 v[188:189], v[140:141], v[188:189] op_sel_hi:[0,1]
	v_cndmask_b32_e64 v191, v191, v202, s[0:1]
	v_mov_b32_dpp v211, v196 row_ror:8 row_mask:0xf bank_mask:0xf
	v_cndmask_b32_e64 v202, v203, v184, s[0:1]
	v_add_f32_e32 v184, 1.0, v215
	v_lshlrev_b32_e32 v186, 16, v187
	v_and_b32_e32 v187, 0xffff0000, v187
	v_pk_mul_f32 v[188:189], v[60:61], v[188:189]
	v_mov_b32_dpp v207, v192 row_ror:8 row_mask:0xf bank_mask:0xf
	v_cndmask_b32_e64 v192, v211, v192, s[0:1]
	v_rcp_f32_e32 v184, v184
	v_rcp_f32_e32 v143, v141
	v_pk_fma_f32 v[188:189], v[136:137], v[188:189], v[186:187]
	v_mov_b32_e32 v141, v157
	v_lshlrev_b32_e32 v186, 16, v192
	v_and_b32_e32 v187, 0xffff0000, v192
	v_mov_b32_dpp v141, v188 row_ror:8 row_mask:0xf bank_mask:0xf
	v_mov_b32_dpp v214, v199 row_ror:8 row_mask:0xf bank_mask:0xf
	v_pk_mul_f32 v[186:187], v[140:141], v[186:187] op_sel_hi:[0,1]
	v_mov_b32_dpp v210, v195 row_ror:8 row_mask:0xf bank_mask:0xf
	v_cndmask_b32_e64 v195, v214, v195, s[0:1]
	v_lshlrev_b32_e32 v136, 16, v202
	v_and_b32_e32 v137, 0xffff0000, v202
	v_pk_mul_f32 v[186:187], v[56:57], v[186:187]
	v_mov_b32_dpp v212, v197 row_ror:8 row_mask:0xf bank_mask:0xf
	v_pk_fma_f32 v[136:137], v[184:185], v[186:187], v[136:137]
	v_lshlrev_b32_e32 v186, 16, v195
	v_and_b32_e32 v187, 0xffff0000, v195
	v_pk_mul_f32 v[186:187], v[140:141], v[186:187] op_sel_hi:[0,1]
	v_mov_b32_dpp v208, v193 row_ror:8 row_mask:0xf bank_mask:0xf
	v_cndmask_b32_e64 v193, v212, v193, s[0:1]
	v_lshlrev_b32_e32 v184, 16, v201
	v_and_b32_e32 v185, 0xffff0000, v201
	v_pk_mul_f32 v[186:187], v[62:63], v[186:187]
	v_mov_b32_dpp v209, v194 row_ror:8 row_mask:0xf bank_mask:0xf
	v_pk_fma_f32 v[184:185], v[138:139], v[186:187], v[184:185]
	v_lshlrev_b32_e32 v186, 16, v193
	v_and_b32_e32 v187, 0xffff0000, v193
	v_pk_mul_f32 v[186:187], v[140:141], v[186:187] op_sel_hi:[0,1]
	v_lshlrev_b32_e32 v138, 16, v200
	v_and_b32_e32 v139, 0xffff0000, v200
	v_pk_mul_f32 v[186:187], v[58:59], v[186:187]
	v_cndmask_b32_e64 v194, v197, v208, s[0:1]
	v_pk_fma_f32 v[138:139], v[142:143], v[186:187], v[138:139]
	v_mov_b32_e32 v142, v157
	v_mov_b32_e32 v143, v157
	v_cndmask_b32_e64 v197, v199, v210, s[0:1]
	v_cndmask_b32_e64 v198, v198, v209, s[0:1]
	v_mov_b32_e32 v199, v157
	v_mov_b32_e32 v195, v157
	v_mov_b32_e32 v201, v157
	v_mov_b32_dpp v142, v138 row_ror:8 row_mask:0xf bank_mask:0xf
	v_mov_b32_dpp v143, v139 row_ror:8 row_mask:0xf bank_mask:0xf
	v_mov_b32_dpp v199, v189 row_ror:8 row_mask:0xf bank_mask:0xf
	v_mov_b32_e32 v192, v157
	v_mov_b32_e32 v202, v157
	v_mov_b32_dpp v195, v184 row_ror:8 row_mask:0xf bank_mask:0xf
	v_mov_b32_dpp v201, v185 row_ror:8 row_mask:0xf bank_mask:0xf
	v_cndmask_b32_e64 v187, v185, v143, s[0:1]
	v_cndmask_b32_e64 v186, v184, v142, s[0:1]
	v_lshlrev_b32_e32 v142, 16, v198
	v_and_b32_e32 v143, 0xffff0000, v198
	v_mov_b32_dpp v192, v136 row_ror:8 row_mask:0xf bank_mask:0xf
	v_mov_b32_dpp v202, v137 row_ror:8 row_mask:0xf bank_mask:0xf
; __device__ __forceinline__ float bflo(unsigned w) { return __uint_as_float(w << 16); }
; __device__ __forceinline__ float bfhi(unsigned w) { return __uint_as_float(w & 0xffff0000u); }
; __device__ __forceinline__ unsigned dpp_ror8(unsigned x) { return (unsigned)__builtin_amdgcn_update_dpp(0, (int)x, 0x128, 0xf, 0xf, false); }
;     __device__ __forceinline__ void operator()(const f32x4 (&acc)[2][2][4][2], const Unit& u, int wr, int wc, int fr, int fq) const {
;     ...
;             for (int m = 0; m < 4; ++m) { const int row = row0 + ai * HALF + m * 16; const float ri = __builtin_amdgcn_rsqf(sse[row] * (1.f / D) + EPS);
;                 u32x4 rr[2], ee[2]; load_pair_lines(R, D, row, fr, col0, rr[0], rr[1], 32); load_pair_lines(E, D, row, fr, col0, ee[0], ee[1], 32);
;                 float* orow = OUT + (size_t)(row - fr + (fr & 7)) * D + col0 + (lo ? 0 : 4);
; #pragma unroll
;                 for (int bj = 0; bj < 2; ++bj) { const u32x4 rw = rr[bj], ew = ee[bj];
;                     const float r[8] = {bflo(rw.x), bfhi(rw.x), bflo(rw.y), bfhi(rw.y), bflo(rw.z), bfhi(rw.z), bflo(rw.w), bfhi(rw.w)};
;                     const float e[8] = {bflo(ew.x), bfhi(ew.x), bflo(ew.y), bfhi(ew.y), bflo(ew.z), bfhi(ew.z), bflo(ew.w), bfhi(ew.w)};
;                     float o[8];
; #pragma unroll
;                     for (int j = 0; j < 8; ++j) { const float a = acc[ai][bj][m][j >> 2][j & 3]; const float gg = gv[bj][j >> 2][j & 3];
;                         o[j] = r[j] + e[j] * ri * gg * __builtin_amdgcn_rcpf(1.f + __builtin_amdgcn_exp2f(-a * LOG2E)); }
;                     f32x4 o1, o2;
; #pragma unroll
;                     for (int j = 0; j < 4; ++j) { const unsigned a = __float_as_uint(o[j]), b = __float_as_uint(o[4 + j]); const unsigned sa = dpp_ror8(a), sb = dpp_ror8(b);
;                         o1[j] = __uint_as_float(lo ? a : sb); o2[j] = __uint_as_float(lo ? sa : b); }
;                     *(f32x4*)(orow + 32 * bj) = o1; *(f32x4*)(orow + (size_t)8 * D + 32 * bj) = o2; } }
	v_cndmask_b32_e64 v139, v201, v139, s[0:1]
	v_cndmask_b32_e64 v138, v195, v138, s[0:1]
	v_cndmask_b32_e64 v137, v199, v137, s[0:1]
	v_cndmask_b32_e64 v136, v141, v136, s[0:1]
	v_pk_mul_f32 v[142:143], v[140:141], v[142:143] op_sel_hi:[0,1]
	v_cndmask_b32_e64 v196, v196, v207, s[0:1]
	global_store_dwordx4 v[172:173], v[136:139], off
	v_rcp_f32_e32 v133, v133
	v_pk_mul_f32 v[142:143], v[44:45], v[142:143]
	v_lshlrev_b32_e32 v138, 16, v190
	v_and_b32_e32 v139, 0xffff0000, v190
	v_exp_f32_e32 v134, v134
	v_exp_f32_e32 v135, v135
	v_pk_fma_f32 v[138:139], v[128:129], v[142:143], v[138:139]
	v_lshlrev_b32_e32 v142, 16, v196
	v_and_b32_e32 v143, 0xffff0000, v196
	v_add_f32_e32 v130, 1.0, v130
	v_add_f32_e32 v131, 1.0, v131
	v_pk_mul_f32 v[142:143], v[140:141], v[142:143] op_sel_hi:[0,1]
	v_rcp_f32_e32 v130, v130
	v_rcp_f32_e32 v131, v131
	v_lshlrev_b32_e32 v128, 16, v183
	v_and_b32_e32 v129, 0xffff0000, v183
	v_pk_mul_f32 v[142:143], v[40:41], v[142:143]
	v_add_f32_e32 v134, 1.0, v134
	v_pk_fma_f32 v[128:129], v[132:133], v[142:143], v[128:129]
	v_lshlrev_b32_e32 v142, 16, v197
	v_and_b32_e32 v143, 0xffff0000, v197
	v_add_f32_e32 v135, 1.0, v135
	v_pk_mul_f32 v[142:143], v[140:141], v[142:143] op_sel_hi:[0,1]
	v_rcp_f32_e32 v134, v134
	v_rcp_f32_e32 v135, v135
	v_lshlrev_b32_e32 v132, 16, v191
	v_and_b32_e32 v133, 0xffff0000, v191
	v_pk_mul_f32 v[142:143], v[46:47], v[142:143]
	v_add_co_u32_e32 v136, vcc, s45, v172
	v_pk_fma_f32 v[132:133], v[130:131], v[142:143], v[132:133]
	v_lshlrev_b32_e32 v142, 16, v194
	v_and_b32_e32 v143, 0xffff0000, v194
	v_cndmask_b32_e64 v185, v189, v202, s[0:1]
	v_cndmask_b32_e64 v184, v188, v192, s[0:1]
	v_addc_co_u32_e32 v137, vcc, 0, v173, vcc
	v_pk_mul_f32 v[140:141], v[140:141], v[142:143] op_sel_hi:[0,1]
	global_store_dwordx4 v[136:137], v[184:187], off
	v_mov_b32_e32 v188, v157
	v_lshlrev_b32_e32 v130, 16, v171
	v_mov_b32_e32 v184, v157
	v_mov_b32_e32 v185, v157
	v_mov_b32_e32 v187, v157
	v_and_b32_e32 v131, 0xffff0000, v171
	v_pk_mul_f32 v[140:141], v[42:43], v[140:141]
	v_mov_b32_dpp v184, v138 row_ror:8 row_mask:0xf bank_mask:0xf
	v_mov_b32_dpp v185, v139 row_ror:8 row_mask:0xf bank_mask:0xf
	v_mov_b32_e32 v183, v157
	v_mov_b32_e32 v186, v157
	v_mov_b32_dpp v187, v132 row_ror:8 row_mask:0xf bank_mask:0xf
	v_mov_b32_dpp v188, v133 row_ror:8 row_mask:0xf bank_mask:0xf
	v_pk_fma_f32 v[130:131], v[134:135], v[140:141], v[130:131]
	v_mov_b32_e32 v134, v157
	v_mov_b32_e32 v135, v157
	v_mov_b32_dpp v183, v128 row_ror:8 row_mask:0xf bank_mask:0xf
	v_mov_b32_dpp v186, v129 row_ror:8 row_mask:0xf bank_mask:0xf
	v_mov_b32_dpp v134, v130 row_ror:8 row_mask:0xf bank_mask:0xf
	v_mov_b32_dpp v135, v131 row_ror:8 row_mask:0xf bank_mask:0xf
	v_cndmask_b32_e64 v131, v188, v131, s[0:1]
	v_cndmask_b32_e64 v130, v187, v130, s[0:1]
	v_cndmask_b32_e64 v129, v185, v129, s[0:1]
	v_cndmask_b32_e64 v128, v184, v128, s[0:1]
	v_cndmask_b32_e64 v135, v133, v135, s[0:1]
	v_cndmask_b32_e64 v134, v132, v134, s[0:1]
	v_cndmask_b32_e64 v133, v139, v186, s[0:1]
	v_cndmask_b32_e64 v132, v138, v183, s[0:1]
	global_store_dwordx4 v[172:173], v[128:131], off offset:128
	global_store_dwordx4 v[136:137], v[132:135], off offset:128
	v_mov_b32_e32 v183, v157
	v_or_b32_e32 v128, 16, v170
	v_ashrrev_i32_e32 v129, 31, v128
	v_lshl_add_u64 v[130:131], v[128:129], 2, s[6:7]
	v_sub_u32_e32 v128, v128, v174
	v_add_u32_e32 v142, v128, v176
	v_ashrrev_i32_e32 v143, 31, v142
	v_lshlrev_b64 v[128:129], 12, v[142:143]
	v_lshl_add_u64 v[172:173], v[128:129], 0, s[16:17]
	s_waitcnt vmcnt(4)
	s_nop 0
	v_mov_b32_e32 v171, v228
	v_lshl_add_u64 v[130:131], s[8:9], 0, v[128:129]
	v_lshl_add_u64 v[134:135], s[8:9], 0, v[172:173]
	v_lshl_add_u64 v[128:129], s[10:11], 0, v[128:129]
	v_lshl_add_u64 v[130:131], v[130:131], 0, v[164:165]
	v_lshl_add_u64 v[134:135], v[134:135], 0, v[164:165]
	v_lshl_add_u64 v[128:129], v[128:129], 0, v[164:165]
	v_mov_b64_e32 v[130:131], v[232:233]
	v_mov_b64_e32 v[132:133], v[234:235]
	v_mov_b32_e32 v189, v157
	v_mov_b64_e32 v[134:135], v[236:237]
	v_mov_b64_e32 v[136:137], v[238:239]
	v_mov_b32_e32 v190, v157
	v_mov_b64_e32 v[138:139], v[240:241]
	v_mov_b64_e32 v[140:141], v[242:243]
	v_lshl_add_u64 v[128:129], s[10:11], 0, v[172:173]
	v_lshl_add_u64 v[128:129], v[128:129], 0, v[164:165]
	v_mov_b64_e32 v[184:185], v[244:245]
	v_mov_b64_e32 v[186:187], v[246:247]
	s_nop 1
	v_or_b32_e32 v216, 32, v170
	v_ashrrev_i32_e32 v217, 31, v216
	v_lshl_add_u64 v[218:219], v[216:217], 2, s[6:7]
	v_sub_u32_e32 v216, v216, v174
	v_add_u32_e32 v224, v216, v176
	v_ashrrev_i32_e32 v225, 31, v224
	v_lshlrev_b64 v[216:217], 12, v[224:225]
	v_lshl_add_u64 v[222:223], v[216:217], 0, s[16:17]
	v_lshl_add_u64 v[220:221], s[8:9], 0, v[222:223]
	global_load_dword v228, v[218:219], off
	v_lshl_add_u64 v[218:219], s[8:9], 0, v[216:217]
	v_lshl_add_u64 v[220:221], v[220:221], 0, v[164:165]
	v_lshl_add_u64 v[216:217], s[10:11], 0, v[216:217]
	v_lshl_add_u64 v[218:219], v[218:219], 0, v[164:165]
	global_load_dwordx4 v[232:235], v[220:221], off
	v_lshl_add_u64 v[216:217], v[216:217], 0, v[164:165]
	global_load_dwordx4 v[236:239], v[218:219], off
	global_load_dwordx4 v[240:243], v[216:217], off
	v_lshl_add_u64 v[216:217], s[10:11], 0, v[222:223]
	v_lshl_add_u64 v[216:217], v[216:217], 0, v[164:165]
	global_load_dwordx4 v[244:247], v[216:217], off
	v_mov_b32_e32 v173, v157
	v_mov_b32_e32 v129, v157
	v_mov_b32_e32 v172, v157
	v_mov_b32_e32 v188, v157
	v_mul_f32_e32 v120, 0xbfb8aa3b, v120
	v_mul_f32_e32 v121, 0xbfb8aa3b, v121
	v_mul_f32_e32 v124, 0xbfb8aa3b, v124
	v_exp_f32_e32 v120, v120
	v_exp_f32_e32 v121, v121
	v_mul_f32_e32 v122, 0xbfb8aa3b, v122
	v_mul_f32_e32 v123, 0xbfb8aa3b, v123
; __device__ __forceinline__ float bflo(unsigned w) { return __uint_as_float(w << 16); }
; __device__ __forceinline__ float bfhi(unsigned w) { return __uint_as_float(w & 0xffff0000u); }
; __device__ __forceinline__ unsigned dpp_ror8(unsigned x) { return (unsigned)__builtin_amdgcn_update_dpp(0, (int)x, 0x128, 0xf, 0xf, false); }
;     __device__ __forceinline__ void operator()(const f32x4 (&acc)[2][2][4][2], const Unit& u, int wr, int wc, int fr, int fq) const {
;     ...
;             for (int m = 0; m < 4; ++m) { const int row = row0 + ai * HALF + m * 16; const float ri = __builtin_amdgcn_rsqf(sse[row] * (1.f / D) + EPS);
;                 u32x4 rr[2], ee[2]; load_pair_lines(R, D, row, fr, col0, rr[0], rr[1], 32); load_pair_lines(E, D, row, fr, col0, ee[0], ee[1], 32);
;                 float* orow = OUT + (size_t)(row - fr + (fr & 7)) * D + col0 + (lo ? 0 : 4);
; #pragma unroll
;                 for (int bj = 0; bj < 2; ++bj) { const u32x4 rw = rr[bj], ew = ee[bj];
;                     const float r[8] = {bflo(rw.x), bfhi(rw.x), bflo(rw.y), bfhi(rw.y), bflo(rw.z), bfhi(rw.z), bflo(rw.w), bfhi(rw.w)};
;                     const float e[8] = {bflo(ew.x), bfhi(ew.x), bflo(ew.y), bfhi(ew.y), bflo(ew.z), bfhi(ew.z), bflo(ew.w), bfhi(ew.w)};
;                     float o[8];
; #pragma unroll
;                     for (int j = 0; j < 8; ++j) { const float a = acc[ai][bj][m][j >> 2][j & 3]; const float gg = gv[bj][j >> 2][j & 3];
;                         o[j] = r[j] + e[j] * ri * gg * __builtin_amdgcn_rcpf(1.f + __builtin_amdgcn_exp2f(-a * LOG2E)); }
;                     f32x4 o1, o2;
; #pragma unroll
;                     for (int j = 0; j < 4; ++j) { const unsigned a = __float_as_uint(o[j]), b = __float_as_uint(o[4 + j]); const unsigned sa = dpp_ror8(a), sb = dpp_ror8(b);
;                         o1[j] = __uint_as_float(lo ? a : sb); o2[j] = __uint_as_float(lo ? sa : b); }
;                     *(f32x4*)(orow + 32 * bj) = o1; *(f32x4*)(orow + (size_t)8 * D + 32 * bj) = o2; } }
	v_add_f32_e32 v120, 1.0, v120
	v_add_f32_e32 v121, 1.0, v121
	v_rcp_f32_e32 v120, v120
	v_rcp_f32_e32 v121, v121
	v_exp_f32_e32 v122, v122
	v_exp_f32_e32 v123, v123
	v_mul_f32_e32 v126, 0xbfb8aa3b, v126
	v_mul_f32_e32 v127, 0xbfb8aa3b, v127
	v_exp_f32_e32 v126, v126
	v_exp_f32_e32 v127, v127
	v_add_f32_e32 v122, 1.0, v122
	v_add_f32_e32 v123, 1.0, v123
	v_rcp_f32_e32 v122, v122
	v_rcp_f32_e32 v123, v123
	v_add_f32_e32 v126, 1.0, v126
	v_add_f32_e32 v127, 1.0, v127
	v_mul_f32_e32 v112, 0xbfb8aa3b, v112
	v_mul_f32_e32 v113, 0xbfb8aa3b, v113
	v_rcp_f32_e32 v126, v126
	v_rcp_f32_e32 v127, v127
	v_exp_f32_e32 v112, v112
	v_exp_f32_e32 v113, v113
	v_mul_f32_e32 v116, 0xbfb8aa3b, v116
	v_mul_f32_e32 v117, 0xbfb8aa3b, v117
	v_exp_f32_e32 v116, v116
	v_exp_f32_e32 v117, v117
	v_add_f32_e32 v112, 1.0, v112
	v_add_f32_e32 v113, 1.0, v113
	v_rcp_f32_e32 v112, v112
	v_rcp_f32_e32 v113, v113
	v_mul_f32_e32 v114, 0xbfb8aa3b, v114
	v_mul_f32_e32 v115, 0xbfb8aa3b, v115
	v_add_f32_e32 v116, 1.0, v116
	v_add_f32_e32 v117, 1.0, v117
	v_exp_f32_e32 v114, v114
	v_exp_f32_e32 v115, v115
	v_rcp_f32_e32 v116, v116
	v_rcp_f32_e32 v117, v117
	v_mul_f32_e32 v118, 0xbfb8aa3b, v118
	v_mul_f32_e32 v119, 0xbfb8aa3b, v119
	v_exp_f32_e32 v118, v118
	v_exp_f32_e32 v119, v119
	v_add_f32_e32 v114, 1.0, v114
	v_add_f32_e32 v115, 1.0, v115
	v_rcp_f32_e32 v114, v114
	v_rcp_f32_e32 v115, v115
	v_add_f32_e32 v118, 1.0, v118
	v_add_f32_e32 v119, 1.0, v119
	v_rcp_f32_e32 v118, v118
	v_rcp_f32_e32 v119, v119
	v_mul_f32_e32 v104, 0xbfb8aa3b, v104
	v_mul_f32_e32 v105, 0xbfb8aa3b, v105
	v_mul_f32_e32 v108, 0xbfb8aa3b, v108
	v_exp_f32_e32 v104, v104
	v_fmamk_f32 v128, v171, 0x3a000000, v182
	v_mov_b32_e32 v171, v157
	v_rsq_f32_e32 v128, v128
	v_exp_f32_e32 v105, v105
	v_add_f32_e32 v104, 1.0, v104
	v_rcp_f32_e32 v104, v104
	v_mul_f32_e32 v106, 0xbfb8aa3b, v106
	v_mov_b32_dpp v171, v131 row_ror:8 row_mask:0xf bank_mask:0xf
	v_mov_b32_dpp v173, v133 row_ror:8 row_mask:0xf bank_mask:0xf
	v_mov_b32_dpp v183, v134 row_ror:8 row_mask:0xf bank_mask:0xf
	v_mov_b32_dpp v189, v136 row_ror:8 row_mask:0xf bank_mask:0xf
	v_mov_b32_dpp v190, v137 row_ror:8 row_mask:0xf bank_mask:0xf
	v_mov_b32_dpp v129, v130 row_ror:8 row_mask:0xf bank_mask:0xf
	v_mov_b32_dpp v172, v132 row_ror:8 row_mask:0xf bank_mask:0xf
	v_mov_b32_dpp v188, v135 row_ror:8 row_mask:0xf bank_mask:0xf
	v_cndmask_b32_e64 v190, v190, v133, s[0:1]
	v_cndmask_b32_e64 v183, v183, v130, s[0:1]
	v_cndmask_b32_e64 v133, v189, v132, s[0:1]
	v_cndmask_b32_e64 v171, v135, v171, s[0:1]
	v_cndmask_b32_e64 v137, v137, v173, s[0:1]
	v_mov_b32_e32 v130, v157
	v_mov_b32_e32 v132, v157
	v_mov_b32_e32 v135, v157
	v_mov_b32_e32 v173, v157
	v_cndmask_b32_e64 v129, v134, v129, s[0:1]
	v_cndmask_b32_e64 v136, v136, v172, s[0:1]
	v_mov_b32_dpp v130, v138 row_ror:8 row_mask:0xf bank_mask:0xf
	v_mov_b32_dpp v132, v140 row_ror:8 row_mask:0xf bank_mask:0xf
	v_mov_b32_e32 v134, v157
	v_mov_b32_dpp v135, v184 row_ror:8 row_mask:0xf bank_mask:0xf
	v_mov_b32_e32 v172, v157
	v_mov_b32_dpp v173, v186 row_ror:8 row_mask:0xf bank_mask:0xf
	v_cndmask_b32_e64 v188, v188, v131, s[0:1]
	v_mov_b32_e32 v131, v157
	v_mov_b32_dpp v134, v141 row_ror:8 row_mask:0xf bank_mask:0xf
	v_mov_b32_dpp v172, v185 row_ror:8 row_mask:0xf bank_mask:0xf
	v_cndmask_b32_e64 v138, v135, v138, s[0:1]
	v_cndmask_b32_e64 v135, v173, v140, s[0:1]
	v_cndmask_b32_e64 v173, v184, v130, s[0:1]
	v_cndmask_b32_e64 v184, v186, v132, s[0:1]
	v_exp_f32_e32 v132, v124
	v_mul_f32_e32 v124, 0xbfb8aa3b, v125
	v_mov_b32_dpp v131, v139 row_ror:8 row_mask:0xf bank_mask:0xf
	v_cndmask_b32_e64 v139, v172, v139, s[0:1]
	v_cndmask_b32_e64 v172, v187, v134, s[0:1]
	v_exp_f32_e32 v134, v124
	v_cndmask_b32_e64 v140, v185, v131, s[0:1]
	v_lshlrev_b64 v[130:131], 13, v[142:143]
	v_lshl_add_u64 v[130:131], s[4:5], 0, v[130:131]
	v_lshl_add_u64 v[130:131], v[130:131], 0, v[166:167]
	v_lshl_add_u64 v[124:125], v[130:131], 0, v[156:157]
	v_add_f32_e32 v131, 1.0, v134
	v_lshlrev_b32_e32 v134, 16, v135
	v_and_b32_e32 v135, 0xffff0000, v135
	v_add_f32_e32 v130, 1.0, v132
	v_pk_mul_f32 v[134:135], v[128:129], v[134:135] op_sel_hi:[0,1]
	v_rcp_f32_e32 v130, v130
	v_rcp_f32_e32 v131, v131
	v_lshlrev_b32_e32 v132, 16, v133
	v_and_b32_e32 v133, 0xffff0000, v133
	v_pk_mul_f32 v[134:135], v[60:61], v[134:135]
	v_mov_b32_e32 v189, v157
	v_pk_fma_f32 v[134:135], v[120:121], v[134:135], v[132:133]
	v_lshlrev_b32_e32 v132, 16, v138
	v_and_b32_e32 v133, 0xffff0000, v138
	v_mov_b32_dpp v189, v187 row_ror:8 row_mask:0xf bank_mask:0xf
	v_pk_mul_f32 v[132:133], v[128:129], v[132:133] op_sel_hi:[0,1]
	v_cndmask_b32_e64 v141, v189, v141, s[0:1]
	v_lshlrev_b32_e32 v120, 16, v183
	v_and_b32_e32 v121, 0xffff0000, v183
	v_pk_mul_f32 v[132:133], v[56:57], v[132:133]
	v_mov_b32_e32 v142, v157
	v_pk_fma_f32 v[120:121], v[130:131], v[132:133], v[120:121]
	v_lshlrev_b32_e32 v132, 16, v141
	v_and_b32_e32 v133, 0xffff0000, v141
	v_pk_mul_f32 v[132:133], v[128:129], v[132:133] op_sel_hi:[0,1]
	v_lshlrev_b32_e32 v130, 16, v190
	v_and_b32_e32 v131, 0xffff0000, v190
	v_pk_mul_f32 v[132:133], v[62:63], v[132:133]
	v_mov_b32_e32 v143, v157
	v_pk_fma_f32 v[130:131], v[122:123], v[132:133], v[130:131]
	v_lshlrev_b32_e32 v132, 16, v139
	v_and_b32_e32 v133, 0xffff0000, v139
	v_pk_mul_f32 v[132:133], v[128:129], v[132:133] op_sel_hi:[0,1]
	v_lshlrev_b32_e32 v122, 16, v188
	v_and_b32_e32 v123, 0xffff0000, v188
	v_pk_mul_f32 v[132:133], v[58:59], v[132:133]
	v_mov_b32_e32 v141, v157
	v_pk_fma_f32 v[122:123], v[126:127], v[132:133], v[122:123]
	v_mov_b32_e32 v126, v157
	v_mov_b32_e32 v127, v157
	v_mov_b32_e32 v185, v157
	v_mov_b32_dpp v126, v122 row_ror:8 row_mask:0xf bank_mask:0xf
; __device__ __forceinline__ float bflo(unsigned w) { return __uint_as_float(w << 16); }
; __device__ __forceinline__ float bfhi(unsigned w) { return __uint_as_float(w & 0xffff0000u); }
; __device__ __forceinline__ unsigned dpp_ror8(unsigned x) { return (unsigned)__builtin_amdgcn_update_dpp(0, (int)x, 0x128, 0xf, 0xf, false); }
;     __device__ __forceinline__ void operator()(const f32x4 (&acc)[2][2][4][2], const Unit& u, int wr, int wc, int fr, int fq) const {
;     ...
;             for (int m = 0; m < 4; ++m) { const int row = row0 + ai * HALF + m * 16; const float ri = __builtin_amdgcn_rsqf(sse[row] * (1.f / D) + EPS);
;                 u32x4 rr[2], ee[2]; load_pair_lines(R, D, row, fr, col0, rr[0], rr[1], 32); load_pair_lines(E, D, row, fr, col0, ee[0], ee[1], 32);
;                 float* orow = OUT + (size_t)(row - fr + (fr & 7)) * D + col0 + (lo ? 0 : 4);
; #pragma unroll
;                 for (int bj = 0; bj < 2; ++bj) { const u32x4 rw = rr[bj], ew = ee[bj];
;                     const float r[8] = {bflo(rw.x), bfhi(rw.x), bflo(rw.y), bfhi(rw.y), bflo(rw.z), bfhi(rw.z), bflo(rw.w), bfhi(rw.w)};
;                     const float e[8] = {bflo(ew.x), bfhi(ew.x), bflo(ew.y), bfhi(ew.y), bflo(ew.z), bfhi(ew.z), bflo(ew.w), bfhi(ew.w)};
;                     float o[8];
; #pragma unroll
;                     for (int j = 0; j < 8; ++j) { const float a = acc[ai][bj][m][j >> 2][j & 3]; const float gg = gv[bj][j >> 2][j & 3];
;                         o[j] = r[j] + e[j] * ri * gg * __builtin_amdgcn_rcpf(1.f + __builtin_amdgcn_exp2f(-a * LOG2E)); }
;                     f32x4 o1, o2;
; #pragma unroll
;                     for (int j = 0; j < 4; ++j) { const unsigned a = __float_as_uint(o[j]), b = __float_as_uint(o[4 + j]); const unsigned sa = dpp_ror8(a), sb = dpp_ror8(b);
;                         o1[j] = __uint_as_float(lo ? a : sb); o2[j] = __uint_as_float(lo ? sa : b); }
;                     *(f32x4*)(orow + 32 * bj) = o1; *(f32x4*)(orow + (size_t)8 * D + 32 * bj) = o2; } }
	v_mov_b32_dpp v127, v123 row_ror:8 row_mask:0xf bank_mask:0xf
	v_mov_b32_dpp v142, v134 row_ror:8 row_mask:0xf bank_mask:0xf
	v_mov_b32_dpp v143, v135 row_ror:8 row_mask:0xf bank_mask:0xf
	v_mov_b32_e32 v138, v157
	v_mov_b32_e32 v183, v157
	v_mov_b32_dpp v141, v130 row_ror:8 row_mask:0xf bank_mask:0xf
	v_mov_b32_dpp v185, v131 row_ror:8 row_mask:0xf bank_mask:0xf
	v_cndmask_b32_e64 v133, v131, v127, s[0:1]
	v_cndmask_b32_e64 v132, v130, v126, s[0:1]
	v_lshlrev_b32_e32 v126, 16, v184
	v_and_b32_e32 v127, 0xffff0000, v184
	v_mov_b32_dpp v138, v120 row_ror:8 row_mask:0xf bank_mask:0xf
	v_mov_b32_dpp v183, v121 row_ror:8 row_mask:0xf bank_mask:0xf
	v_cndmask_b32_e64 v123, v185, v123, s[0:1]
	v_cndmask_b32_e64 v122, v141, v122, s[0:1]
	v_cndmask_b32_e64 v121, v143, v121, s[0:1]
	v_cndmask_b32_e64 v120, v142, v120, s[0:1]
	v_pk_mul_f32 v[126:127], v[128:129], v[126:127] op_sel_hi:[0,1]
	global_store_dwordx4 v[124:125], v[120:123], off
	v_pk_mul_f32 v[126:127], v[44:45], v[126:127]
	v_cndmask_b32_e64 v131, v135, v183, s[0:1]
	v_lshlrev_b32_e32 v122, 16, v136
	v_and_b32_e32 v123, 0xffff0000, v136
	v_pk_fma_f32 v[122:123], v[112:113], v[126:127], v[122:123]
	v_lshlrev_b32_e32 v126, 16, v173
	v_and_b32_e32 v127, 0xffff0000, v173
	v_pk_mul_f32 v[126:127], v[128:129], v[126:127] op_sel_hi:[0,1]
	v_lshlrev_b32_e32 v112, 16, v129
	v_and_b32_e32 v113, 0xffff0000, v129
	v_pk_mul_f32 v[126:127], v[40:41], v[126:127]
	v_mov_b32_e32 v129, v157
	v_pk_fma_f32 v[112:113], v[116:117], v[126:127], v[112:113]
	v_lshlrev_b32_e32 v126, 16, v172
	v_and_b32_e32 v127, 0xffff0000, v172
	v_mov_b32_dpp v129, v112 row_ror:8 row_mask:0xf bank_mask:0xf
	v_pk_mul_f32 v[126:127], v[128:129], v[126:127] op_sel_hi:[0,1]
	v_lshlrev_b32_e32 v116, 16, v137
	v_and_b32_e32 v117, 0xffff0000, v137
	v_pk_mul_f32 v[126:127], v[46:47], v[126:127]
	v_add_co_u32_e32 v120, vcc, s45, v124
	v_pk_fma_f32 v[116:117], v[114:115], v[126:127], v[116:117]
	v_lshlrev_b32_e32 v126, 16, v140
	v_and_b32_e32 v127, 0xffff0000, v140
	v_cndmask_b32_e64 v130, v134, v138, s[0:1]
	v_addc_co_u32_e32 v121, vcc, 0, v125, vcc
	v_pk_mul_f32 v[126:127], v[128:129], v[126:127] op_sel_hi:[0,1]
	global_store_dwordx4 v[120:121], v[130:133], off
	v_mov_b32_e32 v134, v157
	v_lshlrev_b32_e32 v114, 16, v171
	v_mov_b32_e32 v130, v157
	v_mov_b32_e32 v131, v157
	v_mov_b32_e32 v133, v157
	v_and_b32_e32 v115, 0xffff0000, v171
	v_pk_mul_f32 v[126:127], v[42:43], v[126:127]
	v_mov_b32_dpp v130, v122 row_ror:8 row_mask:0xf bank_mask:0xf
	v_mov_b32_dpp v131, v123 row_ror:8 row_mask:0xf bank_mask:0xf
	v_mov_b32_e32 v132, v157
	v_mov_b32_dpp v133, v116 row_ror:8 row_mask:0xf bank_mask:0xf
	v_mov_b32_dpp v134, v117 row_ror:8 row_mask:0xf bank_mask:0xf
	v_pk_fma_f32 v[114:115], v[118:119], v[126:127], v[114:115]
	v_mov_b32_e32 v118, v157
	v_mov_b32_e32 v119, v157
	v_mov_b32_dpp v132, v113 row_ror:8 row_mask:0xf bank_mask:0xf
	v_mov_b32_dpp v118, v114 row_ror:8 row_mask:0xf bank_mask:0xf
	v_mov_b32_dpp v119, v115 row_ror:8 row_mask:0xf bank_mask:0xf
	v_cndmask_b32_e64 v115, v134, v115, s[0:1]
	v_cndmask_b32_e64 v114, v133, v114, s[0:1]
	v_cndmask_b32_e64 v113, v131, v113, s[0:1]
	v_cndmask_b32_e64 v112, v130, v112, s[0:1]
	v_cndmask_b32_e64 v119, v117, v119, s[0:1]
	v_cndmask_b32_e64 v118, v116, v118, s[0:1]
	v_cndmask_b32_e64 v117, v123, v132, s[0:1]
	v_cndmask_b32_e64 v116, v122, v129, s[0:1]
	global_store_dwordx4 v[124:125], v[112:115], off offset:128
	global_store_dwordx4 v[120:121], v[116:119], off offset:128
	v_mov_b32_e32 v137, v157
	v_or_b32_e32 v112, 32, v170
	v_ashrrev_i32_e32 v113, 31, v112
	v_lshl_add_u64 v[114:115], v[112:113], 2, s[6:7]
	v_sub_u32_e32 v112, v112, v174
	v_add_u32_e32 v130, v112, v176
	v_ashrrev_i32_e32 v131, 31, v130
	v_lshlrev_b64 v[112:113], 12, v[130:131]
	v_lshl_add_u64 v[126:127], v[112:113], 0, s[16:17]
	v_lshl_add_u64 v[118:119], s[8:9], 0, v[126:127]
	s_waitcnt vmcnt(4)
	s_nop 0
	v_mov_b32_e32 v132, v228
	v_lshl_add_u64 v[114:115], s[8:9], 0, v[112:113]
	v_lshl_add_u64 v[118:119], v[118:119], 0, v[164:165]
	v_lshl_add_u64 v[112:113], s[10:11], 0, v[112:113]
	v_lshl_add_u64 v[114:115], v[114:115], 0, v[164:165]
	v_mov_b64_e32 v[118:119], v[232:233]
	v_mov_b64_e32 v[120:121], v[234:235]
	v_lshl_add_u64 v[112:113], v[112:113], 0, v[164:165]
	v_mov_b64_e32 v[114:115], v[236:237]
	v_mov_b64_e32 v[116:117], v[238:239]
	v_mov_b32_e32 v138, v157
	v_mov_b64_e32 v[122:123], v[240:241]
	v_mov_b64_e32 v[124:125], v[242:243]
	v_lshl_add_u64 v[112:113], s[10:11], 0, v[126:127]
	v_lshl_add_u64 v[112:113], v[112:113], 0, v[164:165]
	v_mov_b64_e32 v[126:127], v[244:245]
	v_mov_b64_e32 v[128:129], v[246:247]
	s_nop 1
	v_or_b32_e32 v216, 48, v170
	v_ashrrev_i32_e32 v217, 31, v216
	v_lshl_add_u64 v[218:219], v[216:217], 2, s[6:7]
	v_sub_u32_e32 v216, v216, v174
	v_add_u32_e32 v224, v216, v176
	v_ashrrev_i32_e32 v225, 31, v224
	v_lshlrev_b64 v[216:217], 12, v[224:225]
	v_lshl_add_u64 v[222:223], v[216:217], 0, s[16:17]
	v_lshl_add_u64 v[220:221], s[8:9], 0, v[222:223]
	global_load_dword v228, v[218:219], off
	v_lshl_add_u64 v[218:219], s[8:9], 0, v[216:217]
	v_lshl_add_u64 v[220:221], v[220:221], 0, v[164:165]
	v_lshl_add_u64 v[216:217], s[10:11], 0, v[216:217]
	v_lshl_add_u64 v[218:219], v[218:219], 0, v[164:165]
	global_load_dwordx4 v[232:235], v[220:221], off
	v_lshl_add_u64 v[216:217], v[216:217], 0, v[164:165]
	global_load_dwordx4 v[236:239], v[218:219], off
	global_load_dwordx4 v[240:243], v[216:217], off
	v_lshl_add_u64 v[216:217], s[10:11], 0, v[222:223]
	v_lshl_add_u64 v[216:217], v[216:217], 0, v[164:165]
	global_load_dwordx4 v[244:247], v[216:217], off
	v_mov_b32_e32 v113, v157
	v_mov_b32_e32 v133, v157
; __device__ __forceinline__ float bflo(unsigned w) { return __uint_as_float(w << 16); }
; __device__ __forceinline__ float bfhi(unsigned w) { return __uint_as_float(w & 0xffff0000u); }
; __device__ __forceinline__ unsigned dpp_ror8(unsigned x) { return (unsigned)__builtin_amdgcn_update_dpp(0, (int)x, 0x128, 0xf, 0xf, false); }
;     __device__ __forceinline__ void operator()(const f32x4 (&acc)[2][2][4][2], const Unit& u, int wr, int wc, int fr, int fq) const {
;     ...
;             for (int m = 0; m < 4; ++m) { const int row = row0 + ai * HALF + m * 16; const float ri = __builtin_amdgcn_rsqf(sse[row] * (1.f / D) + EPS);
;                 u32x4 rr[2], ee[2]; load_pair_lines(R, D, row, fr, col0, rr[0], rr[1], 32); load_pair_lines(E, D, row, fr, col0, ee[0], ee[1], 32);
;                 float* orow = OUT + (size_t)(row - fr + (fr & 7)) * D + col0 + (lo ? 0 : 4);
; #pragma unroll
;                 for (int bj = 0; bj < 2; ++bj) { const u32x4 rw = rr[bj], ew = ee[bj];
;                     const float r[8] = {bflo(rw.x), bfhi(rw.x), bflo(rw.y), bfhi(rw.y), bflo(rw.z), bfhi(rw.z), bflo(rw.w), bfhi(rw.w)};
;                     const float e[8] = {bflo(ew.x), bfhi(ew.x), bflo(ew.y), bfhi(ew.y), bflo(ew.z), bfhi(ew.z), bflo(ew.w), bfhi(ew.w)};
;                     float o[8];
; #pragma unroll
;                     for (int j = 0; j < 8; ++j) { const float a = acc[ai][bj][m][j >> 2][j & 3]; const float gg = gv[bj][j >> 2][j & 3];
;                         o[j] = r[j] + e[j] * ri * gg * __builtin_amdgcn_rcpf(1.f + __builtin_amdgcn_exp2f(-a * LOG2E)); }
;                     f32x4 o1, o2;
; #pragma unroll
;                     for (int j = 0; j < 4; ++j) { const unsigned a = __float_as_uint(o[j]), b = __float_as_uint(o[4 + j]); const unsigned sa = dpp_ror8(a), sb = dpp_ror8(b);
;                         o1[j] = __uint_as_float(lo ? a : sb); o2[j] = __uint_as_float(lo ? sa : b); }
;                     *(f32x4*)(orow + 32 * bj) = o1; *(f32x4*)(orow + (size_t)8 * D + 32 * bj) = o2; } }
	v_mov_b32_e32 v134, v157
	v_mov_b32_e32 v136, v157
	v_mov_b32_e32 v135, v157
	v_add_f32_e32 v105, 1.0, v105
	v_mul_f32_e32 v107, 0xbfb8aa3b, v107
	v_rcp_f32_e32 v105, v105
	v_exp_f32_e32 v106, v106
	v_exp_f32_e32 v107, v107
	v_mul_f32_e32 v110, 0xbfb8aa3b, v110
	v_mul_f32_e32 v111, 0xbfb8aa3b, v111
	v_exp_f32_e32 v110, v110
	v_exp_f32_e32 v111, v111
	v_add_f32_e32 v106, 1.0, v106
	v_add_f32_e32 v107, 1.0, v107
	v_rcp_f32_e32 v106, v106
	v_rcp_f32_e32 v107, v107
	v_add_f32_e32 v110, 1.0, v110
	v_add_f32_e32 v111, 1.0, v111
	v_mul_f32_e32 v96, 0xbfb8aa3b, v96
	v_mul_f32_e32 v97, 0xbfb8aa3b, v97
	v_rcp_f32_e32 v110, v110
	v_rcp_f32_e32 v111, v111
	v_exp_f32_e32 v96, v96
	v_exp_f32_e32 v97, v97
	v_mul_f32_e32 v100, 0xbfb8aa3b, v100
	v_mul_f32_e32 v101, 0xbfb8aa3b, v101
	v_exp_f32_e32 v100, v100
	v_exp_f32_e32 v101, v101
	v_add_f32_e32 v96, 1.0, v96
	v_add_f32_e32 v97, 1.0, v97
	v_rcp_f32_e32 v96, v96
	v_rcp_f32_e32 v97, v97
	v_mul_f32_e32 v98, 0xbfb8aa3b, v98
	v_mul_f32_e32 v99, 0xbfb8aa3b, v99
	v_add_f32_e32 v100, 1.0, v100
	v_add_f32_e32 v101, 1.0, v101
	v_exp_f32_e32 v98, v98
	v_exp_f32_e32 v99, v99
	v_rcp_f32_e32 v100, v100
	v_rcp_f32_e32 v101, v101
	v_mul_f32_e32 v102, 0xbfb8aa3b, v102
	v_mul_f32_e32 v103, 0xbfb8aa3b, v103
	v_exp_f32_e32 v102, v102
	v_exp_f32_e32 v103, v103
	v_add_f32_e32 v98, 1.0, v98
	v_add_f32_e32 v99, 1.0, v99
	v_rcp_f32_e32 v98, v98
	v_rcp_f32_e32 v99, v99
	v_add_f32_e32 v102, 1.0, v102
	v_add_f32_e32 v103, 1.0, v103
	v_rcp_f32_e32 v102, v102
	v_rcp_f32_e32 v103, v103
	v_mul_f32_e32 v88, 0xbfb8aa3b, v88
	v_mul_f32_e32 v89, 0xbfb8aa3b, v89
	v_mul_f32_e32 v92, 0xbfb8aa3b, v92
	v_exp_f32_e32 v88, v88
	v_exp_f32_e32 v89, v89
	v_mul_f32_e32 v90, 0xbfb8aa3b, v90
	v_mul_f32_e32 v91, 0xbfb8aa3b, v91
	v_add_f32_e32 v88, 1.0, v88
	v_add_f32_e32 v89, 1.0, v89
	v_rcp_f32_e32 v88, v88
	v_rcp_f32_e32 v89, v89
	v_exp_f32_e32 v90, v90
	v_exp_f32_e32 v91, v91
	v_fmamk_f32 v112, v132, 0x3a000000, v182
	v_mov_b32_e32 v132, v157
	v_rsq_f32_e32 v112, v112
	v_mul_f32_e32 v94, 0xbfb8aa3b, v94
	v_mul_f32_e32 v95, 0xbfb8aa3b, v95
	v_mov_b32_dpp v137, v120 row_ror:8 row_mask:0xf bank_mask:0xf
	v_mov_b32_dpp v138, v121 row_ror:8 row_mask:0xf bank_mask:0xf
	v_mov_b32_dpp v113, v114 row_ror:8 row_mask:0xf bank_mask:0xf
	v_mov_b32_dpp v132, v115 row_ror:8 row_mask:0xf bank_mask:0xf
	v_mov_b32_dpp v133, v116 row_ror:8 row_mask:0xf bank_mask:0xf
	v_mov_b32_dpp v134, v117 row_ror:8 row_mask:0xf bank_mask:0xf
	v_mov_b32_dpp v136, v119 row_ror:8 row_mask:0xf bank_mask:0xf
	v_cndmask_b32_e64 v138, v138, v117, s[0:1]
	v_cndmask_b32_e64 v117, v137, v116, s[0:1]
	v_mov_b32_e32 v116, v157
	v_mov_b32_dpp v135, v118 row_ror:8 row_mask:0xf bank_mask:0xf
	v_cndmask_b32_e64 v136, v136, v115, s[0:1]
	v_cndmask_b32_e64 v132, v119, v132, s[0:1]
	v_cndmask_b32_e64 v121, v121, v134, s[0:1]
	v_cndmask_b32_e64 v113, v118, v113, s[0:1]
	v_mov_b32_e32 v115, v157
	v_mov_b32_dpp v116, v124 row_ror:8 row_mask:0xf bank_mask:0xf
	v_mov_b32_e32 v118, v157
	v_mov_b32_e32 v119, v157
	v_mov_b32_e32 v134, v157
	v_cndmask_b32_e64 v135, v135, v114, s[0:1]
	v_cndmask_b32_e64 v120, v120, v133, s[0:1]
	v_mov_b32_e32 v114, v157
	v_mov_b32_dpp v115, v123 row_ror:8 row_mask:0xf bank_mask:0xf
	v_mov_b32_dpp v118, v125 row_ror:8 row_mask:0xf bank_mask:0xf
	v_mov_b32_dpp v119, v126 row_ror:8 row_mask:0xf bank_mask:0xf
	v_mov_b32_e32 v133, v157
	v_mov_b32_dpp v134, v128 row_ror:8 row_mask:0xf bank_mask:0xf
	v_cndmask_b32_e64 v128, v128, v116, s[0:1]
	v_exp_f32_e32 v116, v108
	v_mul_f32_e32 v108, 0xbfb8aa3b, v109
	v_mov_b32_dpp v114, v122 row_ror:8 row_mask:0xf bank_mask:0xf
	v_mov_b32_dpp v133, v127 row_ror:8 row_mask:0xf bank_mask:0xf
	v_cndmask_b32_e64 v122, v119, v122, s[0:1]
	v_cndmask_b32_e64 v119, v134, v124, s[0:1]
	v_cndmask_b32_e64 v124, v127, v115, s[0:1]
	v_cndmask_b32_e64 v127, v129, v118, s[0:1]
	v_exp_f32_e32 v118, v108
	v_cndmask_b32_e64 v126, v126, v114, s[0:1]
	v_lshlrev_b64 v[114:115], 13, v[130:131]
	v_lshl_add_u64 v[114:115], s[4:5], 0, v[114:115]
	v_lshl_add_u64 v[114:115], v[114:115], 0, v[166:167]
	v_lshl_add_u64 v[108:109], v[114:115], 0, v[156:157]
	v_add_f32_e32 v115, 1.0, v118
	v_lshlrev_b32_e32 v118, 16, v119
	v_and_b32_e32 v119, 0xffff0000, v119
	v_add_f32_e32 v114, 1.0, v116
	v_pk_mul_f32 v[118:119], v[112:113], v[118:119] op_sel_hi:[0,1]
	v_rcp_f32_e32 v114, v114
	v_rcp_f32_e32 v115, v115
	v_lshlrev_b32_e32 v116, 16, v117
	v_and_b32_e32 v117, 0xffff0000, v117
	v_pk_mul_f32 v[118:119], v[60:61], v[118:119]
	v_mov_b32_e32 v137, v157
	v_pk_fma_f32 v[118:119], v[104:105], v[118:119], v[116:117]
	v_lshlrev_b32_e32 v116, 16, v122
	v_and_b32_e32 v117, 0xffff0000, v122
	v_mov_b32_dpp v137, v129 row_ror:8 row_mask:0xf bank_mask:0xf
	v_pk_mul_f32 v[116:117], v[112:113], v[116:117] op_sel_hi:[0,1]
	v_cndmask_b32_e64 v125, v137, v125, s[0:1]
	v_lshlrev_b32_e32 v104, 16, v135
	v_and_b32_e32 v105, 0xffff0000, v135
	v_pk_mul_f32 v[116:117], v[56:57], v[116:117]
	v_cndmask_b32_e64 v123, v133, v123, s[0:1]
	v_pk_fma_f32 v[104:105], v[114:115], v[116:117], v[104:105]
	v_lshlrev_b32_e32 v116, 16, v125
	v_and_b32_e32 v117, 0xffff0000, v125
	v_pk_mul_f32 v[116:117], v[112:113], v[116:117] op_sel_hi:[0,1]
	v_lshlrev_b32_e32 v114, 16, v138
	v_and_b32_e32 v115, 0xffff0000, v138
	v_pk_mul_f32 v[116:117], v[62:63], v[116:117]
	v_mov_b32_e32 v129, v157
	v_pk_fma_f32 v[114:115], v[106:107], v[116:117], v[114:115]
	v_lshlrev_b32_e32 v116, 16, v123
	v_and_b32_e32 v117, 0xffff0000, v123
	v_pk_mul_f32 v[116:117], v[112:113], v[116:117] op_sel_hi:[0,1]
	v_lshlrev_b32_e32 v106, 16, v136
	v_and_b32_e32 v107, 0xffff0000, v136
	v_pk_mul_f32 v[116:117], v[58:59], v[116:117]
	v_mov_b32_e32 v130, v157
; __device__ __forceinline__ float bflo(unsigned w) { return __uint_as_float(w << 16); }
; __device__ __forceinline__ float bfhi(unsigned w) { return __uint_as_float(w & 0xffff0000u); }
; __device__ __forceinline__ unsigned dpp_ror8(unsigned x) { return (unsigned)__builtin_amdgcn_update_dpp(0, (int)x, 0x128, 0xf, 0xf, false); }
;     __device__ __forceinline__ void operator()(const f32x4 (&acc)[2][2][4][2], const Unit& u, int wr, int wc, int fr, int fq) const {
;     ...
;             for (int m = 0; m < 4; ++m) { const int row = row0 + ai * HALF + m * 16; const float ri = __builtin_amdgcn_rsqf(sse[row] * (1.f / D) + EPS);
;                 u32x4 rr[2], ee[2]; load_pair_lines(R, D, row, fr, col0, rr[0], rr[1], 32); load_pair_lines(E, D, row, fr, col0, ee[0], ee[1], 32);
;                 float* orow = OUT + (size_t)(row - fr + (fr & 7)) * D + col0 + (lo ? 0 : 4);
; #pragma unroll
;                 for (int bj = 0; bj < 2; ++bj) { const u32x4 rw = rr[bj], ew = ee[bj];
;                     const float r[8] = {bflo(rw.x), bfhi(rw.x), bflo(rw.y), bfhi(rw.y), bflo(rw.z), bfhi(rw.z), bflo(rw.w), bfhi(rw.w)};
;                     const float e[8] = {bflo(ew.x), bfhi(ew.x), bflo(ew.y), bfhi(ew.y), bflo(ew.z), bfhi(ew.z), bflo(ew.w), bfhi(ew.w)};
;                     float o[8];
; #pragma unroll
;                     for (int j = 0; j < 8; ++j) { const float a = acc[ai][bj][m][j >> 2][j & 3]; const float gg = gv[bj][j >> 2][j & 3];
;                         o[j] = r[j] + e[j] * ri * gg * __builtin_amdgcn_rcpf(1.f + __builtin_amdgcn_exp2f(-a * LOG2E)); }
;                     f32x4 o1, o2;
; #pragma unroll
;                     for (int j = 0; j < 4; ++j) { const unsigned a = __float_as_uint(o[j]), b = __float_as_uint(o[4 + j]); const unsigned sa = dpp_ror8(a), sb = dpp_ror8(b);
;                         o1[j] = __uint_as_float(lo ? a : sb); o2[j] = __uint_as_float(lo ? sa : b); }
;                     *(f32x4*)(orow + 32 * bj) = o1; *(f32x4*)(orow + (size_t)8 * D + 32 * bj) = o2; } }
	v_pk_fma_f32 v[106:107], v[110:111], v[116:117], v[106:107]
	v_mov_b32_e32 v110, v157
	v_mov_b32_e32 v111, v157
	v_mov_b32_e32 v125, v157
	v_mov_b32_e32 v133, v157
	v_mov_b32_dpp v110, v106 row_ror:8 row_mask:0xf bank_mask:0xf
	v_mov_b32_dpp v111, v107 row_ror:8 row_mask:0xf bank_mask:0xf
	v_mov_b32_dpp v129, v118 row_ror:8 row_mask:0xf bank_mask:0xf
	v_mov_b32_dpp v130, v119 row_ror:8 row_mask:0xf bank_mask:0xf
	v_mov_b32_e32 v122, v157
	v_mov_b32_e32 v131, v157
	v_mov_b32_dpp v125, v114 row_ror:8 row_mask:0xf bank_mask:0xf
	v_mov_b32_dpp v133, v115 row_ror:8 row_mask:0xf bank_mask:0xf
	v_cndmask_b32_e64 v117, v115, v111, s[0:1]
	v_cndmask_b32_e64 v116, v114, v110, s[0:1]
	v_lshlrev_b32_e32 v110, 16, v128
	v_and_b32_e32 v111, 0xffff0000, v128
	v_mov_b32_dpp v122, v104 row_ror:8 row_mask:0xf bank_mask:0xf
	v_mov_b32_dpp v131, v105 row_ror:8 row_mask:0xf bank_mask:0xf
	v_cndmask_b32_e64 v107, v133, v107, s[0:1]
	v_cndmask_b32_e64 v106, v125, v106, s[0:1]
	v_cndmask_b32_e64 v105, v130, v105, s[0:1]
	v_cndmask_b32_e64 v104, v129, v104, s[0:1]
	v_pk_mul_f32 v[110:111], v[112:113], v[110:111] op_sel_hi:[0,1]
	global_store_dwordx4 v[108:109], v[104:107], off
	v_pk_mul_f32 v[110:111], v[44:45], v[110:111]
	v_cndmask_b32_e64 v115, v119, v131, s[0:1]
	v_lshlrev_b32_e32 v106, 16, v120
	v_and_b32_e32 v107, 0xffff0000, v120
	v_pk_fma_f32 v[106:107], v[96:97], v[110:111], v[106:107]
	v_lshlrev_b32_e32 v110, 16, v126
	v_and_b32_e32 v111, 0xffff0000, v126
	v_pk_mul_f32 v[110:111], v[112:113], v[110:111] op_sel_hi:[0,1]
	v_lshlrev_b32_e32 v96, 16, v113
	v_and_b32_e32 v97, 0xffff0000, v113
	v_pk_mul_f32 v[110:111], v[40:41], v[110:111]
	v_mov_b32_e32 v113, v157
	v_pk_fma_f32 v[96:97], v[100:101], v[110:111], v[96:97]
	v_lshlrev_b32_e32 v110, 16, v127
	v_and_b32_e32 v111, 0xffff0000, v127
	v_mov_b32_dpp v113, v96 row_ror:8 row_mask:0xf bank_mask:0xf
	v_pk_mul_f32 v[110:111], v[112:113], v[110:111] op_sel_hi:[0,1]
	v_lshlrev_b32_e32 v100, 16, v121
	v_and_b32_e32 v101, 0xffff0000, v121
	v_pk_mul_f32 v[110:111], v[46:47], v[110:111]
	v_add_co_u32_e32 v104, vcc, s45, v108
	v_pk_fma_f32 v[100:101], v[98:99], v[110:111], v[100:101]
	v_lshlrev_b32_e32 v110, 16, v124
	v_and_b32_e32 v111, 0xffff0000, v124
	v_cndmask_b32_e64 v114, v118, v122, s[0:1]
	v_addc_co_u32_e32 v105, vcc, 0, v109, vcc
	v_pk_mul_f32 v[110:111], v[112:113], v[110:111] op_sel_hi:[0,1]
	global_store_dwordx4 v[104:105], v[114:117], off
	v_mov_b32_e32 v118, v157
	v_lshlrev_b32_e32 v98, 16, v132
	v_mov_b32_e32 v114, v157
	v_mov_b32_e32 v115, v157
	v_mov_b32_e32 v117, v157
	v_and_b32_e32 v99, 0xffff0000, v132
	v_pk_mul_f32 v[110:111], v[42:43], v[110:111]
	v_mov_b32_dpp v114, v106 row_ror:8 row_mask:0xf bank_mask:0xf
	v_mov_b32_dpp v115, v107 row_ror:8 row_mask:0xf bank_mask:0xf
	v_mov_b32_e32 v116, v157
	v_mov_b32_dpp v117, v100 row_ror:8 row_mask:0xf bank_mask:0xf
	v_mov_b32_dpp v118, v101 row_ror:8 row_mask:0xf bank_mask:0xf
	v_pk_fma_f32 v[98:99], v[102:103], v[110:111], v[98:99]
	v_mov_b32_e32 v102, v157
	v_mov_b32_e32 v103, v157
	v_mov_b32_dpp v116, v97 row_ror:8 row_mask:0xf bank_mask:0xf
	v_mov_b32_dpp v102, v98 row_ror:8 row_mask:0xf bank_mask:0xf
	v_mov_b32_dpp v103, v99 row_ror:8 row_mask:0xf bank_mask:0xf
	v_cndmask_b32_e64 v99, v118, v99, s[0:1]
	v_cndmask_b32_e64 v98, v117, v98, s[0:1]
	v_cndmask_b32_e64 v97, v115, v97, s[0:1]
	v_cndmask_b32_e64 v96, v114, v96, s[0:1]
	v_cndmask_b32_e64 v103, v101, v103, s[0:1]
	v_cndmask_b32_e64 v102, v100, v102, s[0:1]
	v_cndmask_b32_e64 v101, v107, v116, s[0:1]
	v_cndmask_b32_e64 v100, v106, v113, s[0:1]
	global_store_dwordx4 v[108:109], v[96:99], off offset:128
	global_store_dwordx4 v[104:105], v[100:103], off offset:128
	v_mov_b32_e32 v121, v157
	v_or_b32_e32 v96, 48, v170
	v_ashrrev_i32_e32 v97, 31, v96
	v_lshl_add_u64 v[98:99], v[96:97], 2, s[6:7]
	v_sub_u32_e32 v96, v96, v174
	v_add_u32_e32 v114, v96, v176
	v_ashrrev_i32_e32 v115, 31, v114
	v_lshlrev_b64 v[96:97], 12, v[114:115]
	v_lshl_add_u64 v[110:111], v[96:97], 0, s[16:17]
	v_lshl_add_u64 v[102:103], s[8:9], 0, v[110:111]
	s_waitcnt vmcnt(4)
	s_nop 0
	v_mov_b32_e32 v116, v228
	v_lshl_add_u64 v[98:99], s[8:9], 0, v[96:97]
	v_lshl_add_u64 v[102:103], v[102:103], 0, v[164:165]
	v_lshl_add_u64 v[96:97], s[10:11], 0, v[96:97]
	v_lshl_add_u64 v[98:99], v[98:99], 0, v[164:165]
	v_mov_b64_e32 v[102:103], v[232:233]
	v_mov_b64_e32 v[104:105], v[234:235]
	v_lshl_add_u64 v[96:97], v[96:97], 0, v[164:165]
	v_mov_b64_e32 v[98:99], v[236:237]
	v_mov_b64_e32 v[100:101], v[238:239]
	v_mov_b32_e32 v122, v157
	v_mov_b64_e32 v[106:107], v[240:241]
	v_mov_b64_e32 v[108:109], v[242:243]
	v_lshl_add_u64 v[96:97], s[10:11], 0, v[110:111]
	v_lshl_add_u64 v[96:97], v[96:97], 0, v[164:165]
	v_mov_b64_e32 v[110:111], v[244:245]
	v_mov_b64_e32 v[112:113], v[246:247]
	s_nop 1
	global_load_dword v228, v[168:169], off offset:512
	v_sub_u32_e32 v217, v170, v174
	v_add_u32_e32 v217, v217, v176
	v_add_u32_e32 v226, 0x80, v217
	v_ashrrev_i32_e32 v227, 31, v226
	v_lshlrev_b64 v[222:223], 12, v[226:227]
	v_lshl_add_u64 v[224:225], v[222:223], 0, s[16:17]
	v_lshl_add_u64 v[218:219], s[8:9], 0, v[222:223]
	v_lshl_add_u64 v[220:221], s[8:9], 0, v[224:225]
	v_lshl_add_u64 v[218:219], v[218:219], 0, v[164:165]
	v_lshl_add_u64 v[220:221], v[220:221], 0, v[164:165]
	global_load_dwordx4 v[232:235], v[218:219], off
	v_lshl_add_u64 v[222:223], s[10:11], 0, v[222:223]
	global_load_dwordx4 v[236:239], v[220:221], off
	v_lshl_add_u64 v[222:223], v[222:223], 0, v[164:165]
	v_lshl_add_u64 v[224:225], s[10:11], 0, v[224:225]
	global_load_dwordx4 v[240:243], v[222:223], off
	v_lshl_add_u64 v[224:225], v[224:225], 0, v[164:165]
; __device__ __forceinline__ float bflo(unsigned w) { return __uint_as_float(w << 16); }
; __device__ __forceinline__ float bfhi(unsigned w) { return __uint_as_float(w & 0xffff0000u); }
; __device__ __forceinline__ unsigned dpp_ror8(unsigned x) { return (unsigned)__builtin_amdgcn_update_dpp(0, (int)x, 0x128, 0xf, 0xf, false); }
;     __device__ __forceinline__ void operator()(const f32x4 (&acc)[2][2][4][2], const Unit& u, int wr, int wc, int fr, int fq) const {
;     ...
;             for (int m = 0; m < 4; ++m) { const int row = row0 + ai * HALF + m * 16; const float ri = __builtin_amdgcn_rsqf(sse[row] * (1.f / D) + EPS);
;                 u32x4 rr[2], ee[2]; load_pair_lines(R, D, row, fr, col0, rr[0], rr[1], 32); load_pair_lines(E, D, row, fr, col0, ee[0], ee[1], 32);
;                 float* orow = OUT + (size_t)(row - fr + (fr & 7)) * D + col0 + (lo ? 0 : 4);
; #pragma unroll
;                 for (int bj = 0; bj < 2; ++bj) { const u32x4 rw = rr[bj], ew = ee[bj];
;                     const float r[8] = {bflo(rw.x), bfhi(rw.x), bflo(rw.y), bfhi(rw.y), bflo(rw.z), bfhi(rw.z), bflo(rw.w), bfhi(rw.w)};
;                     const float e[8] = {bflo(ew.x), bfhi(ew.x), bflo(ew.y), bfhi(ew.y), bflo(ew.z), bfhi(ew.z), bflo(ew.w), bfhi(ew.w)};
;                     float o[8];
; #pragma unroll
;                     for (int j = 0; j < 8; ++j) { const float a = acc[ai][bj][m][j >> 2][j & 3]; const float gg = gv[bj][j >> 2][j & 3];
;                         o[j] = r[j] + e[j] * ri * gg * __builtin_amdgcn_rcpf(1.f + __builtin_amdgcn_exp2f(-a * LOG2E)); }
;                     f32x4 o1, o2;
; #pragma unroll
;                     for (int j = 0; j < 4; ++j) { const unsigned a = __float_as_uint(o[j]), b = __float_as_uint(o[4 + j]); const unsigned sa = dpp_ror8(a), sb = dpp_ror8(b);
;                         o1[j] = __uint_as_float(lo ? a : sb); o2[j] = __uint_as_float(lo ? sa : b); }
;                     *(f32x4*)(orow + 32 * bj) = o1; *(f32x4*)(orow + (size_t)8 * D + 32 * bj) = o2; } }
	global_load_dwordx4 v[244:247], v[224:225], off
	v_mov_b32_e32 v97, v157
	v_mov_b32_e32 v117, v157
	v_mov_b32_e32 v118, v157
	v_mov_b32_e32 v120, v157
	v_mov_b32_e32 v119, v157
	v_exp_f32_e32 v94, v94
	v_exp_f32_e32 v95, v95
	v_add_f32_e32 v90, 1.0, v90
	v_add_f32_e32 v91, 1.0, v91
	v_rcp_f32_e32 v90, v90
	v_rcp_f32_e32 v91, v91
	v_add_f32_e32 v94, 1.0, v94
	v_add_f32_e32 v95, 1.0, v95
	v_mul_f32_e32 v80, 0xbfb8aa3b, v80
	v_mul_f32_e32 v81, 0xbfb8aa3b, v81
	v_rcp_f32_e32 v94, v94
	v_rcp_f32_e32 v95, v95
	v_exp_f32_e32 v80, v80
	v_exp_f32_e32 v81, v81
	v_mul_f32_e32 v84, 0xbfb8aa3b, v84
	v_mul_f32_e32 v85, 0xbfb8aa3b, v85
	v_exp_f32_e32 v84, v84
	v_exp_f32_e32 v85, v85
	v_add_f32_e32 v80, 1.0, v80
	v_add_f32_e32 v81, 1.0, v81
	v_rcp_f32_e32 v80, v80
	v_rcp_f32_e32 v81, v81
	v_mul_f32_e32 v82, 0xbfb8aa3b, v82
	v_mul_f32_e32 v83, 0xbfb8aa3b, v83
	v_add_f32_e32 v84, 1.0, v84
	v_add_f32_e32 v85, 1.0, v85
	v_exp_f32_e32 v82, v82
	v_exp_f32_e32 v83, v83
	v_rcp_f32_e32 v84, v84
	v_rcp_f32_e32 v85, v85
	v_mul_f32_e32 v86, 0xbfb8aa3b, v86
	v_mul_f32_e32 v87, 0xbfb8aa3b, v87
	v_exp_f32_e32 v86, v86
	v_exp_f32_e32 v87, v87
	v_add_f32_e32 v82, 1.0, v82
	v_add_f32_e32 v83, 1.0, v83
	v_rcp_f32_e32 v82, v82
	v_rcp_f32_e32 v83, v83
	v_add_f32_e32 v86, 1.0, v86
	v_add_f32_e32 v87, 1.0, v87
	v_rcp_f32_e32 v86, v86
	v_rcp_f32_e32 v87, v87
	v_mul_f32_e32 v72, 0xbfb8aa3b, v72
	v_mul_f32_e32 v73, 0xbfb8aa3b, v73
	v_mul_f32_e32 v76, 0xbfb8aa3b, v76
	v_exp_f32_e32 v72, v72
	v_exp_f32_e32 v73, v73
	v_mul_f32_e32 v74, 0xbfb8aa3b, v74
	v_mul_f32_e32 v75, 0xbfb8aa3b, v75
	v_add_f32_e32 v72, 1.0, v72
	v_add_f32_e32 v73, 1.0, v73
	v_rcp_f32_e32 v72, v72
	v_rcp_f32_e32 v73, v73
	v_exp_f32_e32 v74, v74
	v_exp_f32_e32 v75, v75
	v_mul_f32_e32 v78, 0xbfb8aa3b, v78
	v_mul_f32_e32 v79, 0xbfb8aa3b, v79
	v_exp_f32_e32 v78, v78
	v_exp_f32_e32 v79, v79
	v_add_f32_e32 v74, 1.0, v74
	v_add_f32_e32 v75, 1.0, v75
	v_rcp_f32_e32 v74, v74
	v_fmamk_f32 v96, v116, 0x3a000000, v182
	v_mov_b32_e32 v116, v157
	v_rsq_f32_e32 v96, v96
	v_rcp_f32_e32 v75, v75
	v_add_f32_e32 v78, 1.0, v78
	v_mov_b32_dpp v121, v104 row_ror:8 row_mask:0xf bank_mask:0xf
	v_mov_b32_dpp v122, v105 row_ror:8 row_mask:0xf bank_mask:0xf
	v_mov_b32_dpp v97, v98 row_ror:8 row_mask:0xf bank_mask:0xf
	v_mov_b32_dpp v116, v99 row_ror:8 row_mask:0xf bank_mask:0xf
	v_mov_b32_dpp v117, v100 row_ror:8 row_mask:0xf bank_mask:0xf
	v_mov_b32_dpp v118, v101 row_ror:8 row_mask:0xf bank_mask:0xf
	v_mov_b32_dpp v120, v103 row_ror:8 row_mask:0xf bank_mask:0xf
	v_cndmask_b32_e64 v122, v122, v101, s[0:1]
	v_cndmask_b32_e64 v101, v121, v100, s[0:1]
	v_mov_b32_e32 v100, v157
	v_mov_b32_dpp v119, v102 row_ror:8 row_mask:0xf bank_mask:0xf
	v_cndmask_b32_e64 v120, v120, v99, s[0:1]
	v_cndmask_b32_e64 v116, v103, v116, s[0:1]
	v_cndmask_b32_e64 v105, v105, v118, s[0:1]
	v_cndmask_b32_e64 v97, v102, v97, s[0:1]
	v_mov_b32_e32 v99, v157
	v_mov_b32_dpp v100, v108 row_ror:8 row_mask:0xf bank_mask:0xf
	v_mov_b32_e32 v102, v157
	v_mov_b32_e32 v103, v157
	v_mov_b32_e32 v118, v157
	v_cndmask_b32_e64 v119, v119, v98, s[0:1]
	v_cndmask_b32_e64 v104, v104, v117, s[0:1]
	v_mov_b32_e32 v98, v157
	v_mov_b32_dpp v99, v107 row_ror:8 row_mask:0xf bank_mask:0xf
	v_mov_b32_dpp v102, v109 row_ror:8 row_mask:0xf bank_mask:0xf
	v_mov_b32_dpp v103, v110 row_ror:8 row_mask:0xf bank_mask:0xf
	v_mov_b32_e32 v117, v157
	v_mov_b32_dpp v118, v112 row_ror:8 row_mask:0xf bank_mask:0xf
	v_cndmask_b32_e64 v112, v112, v100, s[0:1]
	v_exp_f32_e32 v100, v92
	v_mul_f32_e32 v92, 0xbfb8aa3b, v93
	v_mov_b32_dpp v98, v106 row_ror:8 row_mask:0xf bank_mask:0xf
	v_mov_b32_dpp v117, v111 row_ror:8 row_mask:0xf bank_mask:0xf
	v_cndmask_b32_e64 v106, v103, v106, s[0:1]
	v_cndmask_b32_e64 v103, v118, v108, s[0:1]
	v_cndmask_b32_e64 v108, v111, v99, s[0:1]
	v_cndmask_b32_e64 v111, v113, v102, s[0:1]
	v_exp_f32_e32 v102, v92
	v_cndmask_b32_e64 v110, v110, v98, s[0:1]
	v_lshlrev_b64 v[98:99], 13, v[114:115]
	v_lshl_add_u64 v[98:99], s[4:5], 0, v[98:99]
	v_lshl_add_u64 v[98:99], v[98:99], 0, v[166:167]
	v_lshl_add_u64 v[92:93], v[98:99], 0, v[156:157]
	v_add_f32_e32 v99, 1.0, v102
	v_lshlrev_b32_e32 v102, 16, v103
	v_and_b32_e32 v103, 0xffff0000, v103
	v_add_f32_e32 v98, 1.0, v100
	v_pk_mul_f32 v[102:103], v[96:97], v[102:103] op_sel_hi:[0,1]
	v_rcp_f32_e32 v98, v98
	v_rcp_f32_e32 v99, v99
	v_lshlrev_b32_e32 v100, 16, v101
	v_and_b32_e32 v101, 0xffff0000, v101
	v_pk_mul_f32 v[102:103], v[60:61], v[102:103]
	v_mov_b32_e32 v121, v157
	v_pk_fma_f32 v[102:103], v[88:89], v[102:103], v[100:101]
	v_lshlrev_b32_e32 v100, 16, v106
	v_and_b32_e32 v101, 0xffff0000, v106
	v_mov_b32_dpp v121, v113 row_ror:8 row_mask:0xf bank_mask:0xf
	v_pk_mul_f32 v[100:101], v[96:97], v[100:101] op_sel_hi:[0,1]
	v_cndmask_b32_e64 v109, v121, v109, s[0:1]
	v_lshlrev_b32_e32 v88, 16, v119
	v_and_b32_e32 v89, 0xffff0000, v119
	v_pk_mul_f32 v[100:101], v[56:57], v[100:101]
	v_cndmask_b32_e64 v107, v117, v107, s[0:1]
	v_pk_fma_f32 v[88:89], v[98:99], v[100:101], v[88:89]
	v_lshlrev_b32_e32 v100, 16, v109
	v_and_b32_e32 v101, 0xffff0000, v109
	v_pk_mul_f32 v[100:101], v[96:97], v[100:101] op_sel_hi:[0,1]
	v_lshlrev_b32_e32 v98, 16, v122
	v_and_b32_e32 v99, 0xffff0000, v122
	v_pk_mul_f32 v[100:101], v[62:63], v[100:101]
	v_mov_b32_e32 v113, v157
	v_pk_fma_f32 v[98:99], v[90:91], v[100:101], v[98:99]
	v_lshlrev_b32_e32 v100, 16, v107
	v_and_b32_e32 v101, 0xffff0000, v107
	v_pk_mul_f32 v[100:101], v[96:97], v[100:101] op_sel_hi:[0,1]
	v_lshlrev_b32_e32 v90, 16, v120
	v_and_b32_e32 v91, 0xffff0000, v120
	v_pk_mul_f32 v[100:101], v[58:59], v[100:101]
	v_mov_b32_e32 v114, v157
	v_pk_fma_f32 v[90:91], v[94:95], v[100:101], v[90:91]
; __device__ __forceinline__ float bflo(unsigned w) { return __uint_as_float(w << 16); }
; __device__ __forceinline__ float bfhi(unsigned w) { return __uint_as_float(w & 0xffff0000u); }
; __device__ __forceinline__ unsigned dpp_ror8(unsigned x) { return (unsigned)__builtin_amdgcn_update_dpp(0, (int)x, 0x128, 0xf, 0xf, false); }
;     __device__ __forceinline__ void operator()(const f32x4 (&acc)[2][2][4][2], const Unit& u, int wr, int wc, int fr, int fq) const {
;     ...
;             for (int m = 0; m < 4; ++m) { const int row = row0 + ai * HALF + m * 16; const float ri = __builtin_amdgcn_rsqf(sse[row] * (1.f / D) + EPS);
;                 u32x4 rr[2], ee[2]; load_pair_lines(R, D, row, fr, col0, rr[0], rr[1], 32); load_pair_lines(E, D, row, fr, col0, ee[0], ee[1], 32);
;                 float* orow = OUT + (size_t)(row - fr + (fr & 7)) * D + col0 + (lo ? 0 : 4);
; #pragma unroll
;                 for (int bj = 0; bj < 2; ++bj) { const u32x4 rw = rr[bj], ew = ee[bj];
;                     const float r[8] = {bflo(rw.x), bfhi(rw.x), bflo(rw.y), bfhi(rw.y), bflo(rw.z), bfhi(rw.z), bflo(rw.w), bfhi(rw.w)};
;                     const float e[8] = {bflo(ew.x), bfhi(ew.x), bflo(ew.y), bfhi(ew.y), bflo(ew.z), bfhi(ew.z), bflo(ew.w), bfhi(ew.w)};
;                     float o[8];
; #pragma unroll
;                     for (int j = 0; j < 8; ++j) { const float a = acc[ai][bj][m][j >> 2][j & 3]; const float gg = gv[bj][j >> 2][j & 3];
;                         o[j] = r[j] + e[j] * ri * gg * __builtin_amdgcn_rcpf(1.f + __builtin_amdgcn_exp2f(-a * LOG2E)); }
;                     f32x4 o1, o2;
; #pragma unroll
;                     for (int j = 0; j < 4; ++j) { const unsigned a = __float_as_uint(o[j]), b = __float_as_uint(o[4 + j]); const unsigned sa = dpp_ror8(a), sb = dpp_ror8(b);
;                         o1[j] = __uint_as_float(lo ? a : sb); o2[j] = __uint_as_float(lo ? sa : b); }
;                     *(f32x4*)(orow + 32 * bj) = o1; *(f32x4*)(orow + (size_t)8 * D + 32 * bj) = o2; } }
	v_mov_b32_e32 v94, v157
	v_mov_b32_e32 v95, v157
	v_mov_b32_e32 v109, v157
	v_mov_b32_e32 v117, v157
	v_mov_b32_dpp v94, v90 row_ror:8 row_mask:0xf bank_mask:0xf
	v_mov_b32_dpp v95, v91 row_ror:8 row_mask:0xf bank_mask:0xf
	v_mov_b32_dpp v113, v102 row_ror:8 row_mask:0xf bank_mask:0xf
	v_mov_b32_dpp v114, v103 row_ror:8 row_mask:0xf bank_mask:0xf
	v_mov_b32_e32 v106, v157
	v_mov_b32_e32 v115, v157
	v_mov_b32_dpp v109, v98 row_ror:8 row_mask:0xf bank_mask:0xf
	v_mov_b32_dpp v117, v99 row_ror:8 row_mask:0xf bank_mask:0xf
	v_cndmask_b32_e64 v101, v99, v95, s[0:1]
	v_cndmask_b32_e64 v100, v98, v94, s[0:1]
	v_lshlrev_b32_e32 v94, 16, v112
	v_and_b32_e32 v95, 0xffff0000, v112
	v_mov_b32_dpp v106, v88 row_ror:8 row_mask:0xf bank_mask:0xf
	v_mov_b32_dpp v115, v89 row_ror:8 row_mask:0xf bank_mask:0xf
	v_cndmask_b32_e64 v91, v117, v91, s[0:1]
	v_cndmask_b32_e64 v90, v109, v90, s[0:1]
	v_cndmask_b32_e64 v89, v114, v89, s[0:1]
	v_cndmask_b32_e64 v88, v113, v88, s[0:1]
	v_pk_mul_f32 v[94:95], v[96:97], v[94:95] op_sel_hi:[0,1]
	global_store_dwordx4 v[92:93], v[88:91], off
	v_pk_mul_f32 v[94:95], v[44:45], v[94:95]
	v_cndmask_b32_e64 v99, v103, v115, s[0:1]
	v_lshlrev_b32_e32 v90, 16, v104
	v_and_b32_e32 v91, 0xffff0000, v104
	v_pk_fma_f32 v[90:91], v[80:81], v[94:95], v[90:91]
	v_lshlrev_b32_e32 v94, 16, v110
	v_and_b32_e32 v95, 0xffff0000, v110
	v_pk_mul_f32 v[94:95], v[96:97], v[94:95] op_sel_hi:[0,1]
	v_lshlrev_b32_e32 v80, 16, v97
	v_and_b32_e32 v81, 0xffff0000, v97
	v_pk_mul_f32 v[94:95], v[40:41], v[94:95]
	v_mov_b32_e32 v97, v157
	v_pk_fma_f32 v[80:81], v[84:85], v[94:95], v[80:81]
	v_lshlrev_b32_e32 v94, 16, v111
	v_and_b32_e32 v95, 0xffff0000, v111
	v_mov_b32_dpp v97, v80 row_ror:8 row_mask:0xf bank_mask:0xf
	v_pk_mul_f32 v[94:95], v[96:97], v[94:95] op_sel_hi:[0,1]
	v_lshlrev_b32_e32 v84, 16, v105
	v_and_b32_e32 v85, 0xffff0000, v105
	v_pk_mul_f32 v[94:95], v[46:47], v[94:95]
	v_add_co_u32_e32 v88, vcc, s45, v92
	v_pk_fma_f32 v[84:85], v[82:83], v[94:95], v[84:85]
	v_lshlrev_b32_e32 v94, 16, v108
	v_and_b32_e32 v95, 0xffff0000, v108
	v_cndmask_b32_e64 v98, v102, v106, s[0:1]
	v_addc_co_u32_e32 v89, vcc, 0, v93, vcc
	v_pk_mul_f32 v[94:95], v[96:97], v[94:95] op_sel_hi:[0,1]
	global_store_dwordx4 v[88:89], v[98:101], off
	v_mov_b32_e32 v102, v157
	v_lshlrev_b32_e32 v82, 16, v116
	v_mov_b32_e32 v98, v157
	v_mov_b32_e32 v99, v157
	v_mov_b32_e32 v101, v157
	v_and_b32_e32 v83, 0xffff0000, v116
	v_pk_mul_f32 v[94:95], v[42:43], v[94:95]
	v_mov_b32_dpp v98, v90 row_ror:8 row_mask:0xf bank_mask:0xf
	v_mov_b32_dpp v99, v91 row_ror:8 row_mask:0xf bank_mask:0xf
	v_mov_b32_e32 v100, v157
	v_mov_b32_dpp v101, v84 row_ror:8 row_mask:0xf bank_mask:0xf
	v_mov_b32_dpp v102, v85 row_ror:8 row_mask:0xf bank_mask:0xf
	v_pk_fma_f32 v[82:83], v[86:87], v[94:95], v[82:83]
	v_mov_b32_e32 v86, v157
	v_mov_b32_e32 v87, v157
	v_mov_b32_dpp v100, v81 row_ror:8 row_mask:0xf bank_mask:0xf
	v_mov_b32_dpp v86, v82 row_ror:8 row_mask:0xf bank_mask:0xf
	v_mov_b32_dpp v87, v83 row_ror:8 row_mask:0xf bank_mask:0xf
	v_cndmask_b32_e64 v83, v102, v83, s[0:1]
	v_cndmask_b32_e64 v82, v101, v82, s[0:1]
	v_cndmask_b32_e64 v81, v99, v81, s[0:1]
	v_cndmask_b32_e64 v80, v98, v80, s[0:1]
	v_cndmask_b32_e64 v87, v85, v87, s[0:1]
	v_cndmask_b32_e64 v86, v84, v86, s[0:1]
	v_cndmask_b32_e64 v85, v91, v100, s[0:1]
	v_cndmask_b32_e64 v84, v90, v97, s[0:1]
	global_store_dwordx4 v[92:93], v[80:83], off offset:128
	global_store_dwordx4 v[88:89], v[84:87], off offset:128
	s_waitcnt vmcnt(4)
	s_nop 0
	v_mov_b32_e32 v80, v228
	v_sub_u32_e32 v81, v170, v174
	v_add_u32_e32 v81, v81, v176
	v_add_u32_e32 v98, 0x80, v81
	v_ashrrev_i32_e32 v99, 31, v98
	v_lshlrev_b64 v[90:91], 12, v[98:99]
	v_lshl_add_u64 v[94:95], v[90:91], 0, s[16:17]
	v_lshl_add_u64 v[82:83], s[8:9], 0, v[90:91]
	v_lshl_add_u64 v[86:87], s[8:9], 0, v[94:95]
	v_lshl_add_u64 v[82:83], v[82:83], 0, v[164:165]
	v_lshl_add_u64 v[86:87], v[86:87], 0, v[164:165]
	v_mov_b64_e32 v[82:83], v[232:233]
	v_mov_b64_e32 v[84:85], v[234:235]
	v_lshl_add_u64 v[90:91], s[10:11], 0, v[90:91]
	v_mov_b64_e32 v[86:87], v[236:237]
	v_mov_b64_e32 v[88:89], v[238:239]
	v_lshl_add_u64 v[90:91], v[90:91], 0, v[164:165]
	v_lshl_add_u64 v[94:95], s[10:11], 0, v[94:95]
	v_mov_b64_e32 v[90:91], v[240:241]
	v_mov_b64_e32 v[92:93], v[242:243]
	v_lshl_add_u64 v[94:95], v[94:95], 0, v[164:165]
	v_mov_b64_e32 v[94:95], v[244:245]
	v_mov_b64_e32 v[96:97], v[246:247]
	s_nop 1
	v_add_u32_e32 v222, 0x90, v81
	v_ashrrev_i32_e32 v223, 31, v222
	global_load_dword v228, v[168:169], off offset:576
	v_lshlrev_b64 v[216:217], 12, v[222:223]
	v_lshl_add_u64 v[224:225], v[216:217], 0, s[16:17]
	v_lshl_add_u64 v[220:221], s[8:9], 0, v[224:225]
	v_lshl_add_u64 v[218:219], s[8:9], 0, v[216:217]
	v_lshl_add_u64 v[220:221], v[220:221], 0, v[164:165]
	v_lshl_add_u64 v[216:217], s[10:11], 0, v[216:217]
	v_lshl_add_u64 v[218:219], v[218:219], 0, v[164:165]
	global_load_dwordx4 v[232:235], v[220:221], off
	v_lshl_add_u64 v[216:217], v[216:217], 0, v[164:165]
	global_load_dwordx4 v[236:239], v[218:219], off
	global_load_dwordx4 v[240:243], v[216:217], off
	v_lshl_add_u64 v[216:217], s[10:11], 0, v[224:225]
	v_lshl_add_u64 v[216:217], v[216:217], 0, v[164:165]
	global_load_dwordx4 v[244:247], v[216:217], off
	v_mov_b32_e32 v106, v157
	v_mov_b32_e32 v107, v157
	v_mov_b32_e32 v100, v157
	v_mov_b32_e32 v101, v157
	v_mov_b32_e32 v102, v157
	v_mov_b32_e32 v103, v157
	v_mov_b32_e32 v105, v157
	v_mov_b32_e32 v104, v157
	v_add_f32_e32 v79, 1.0, v79
	v_mul_f32_e32 v64, 0xbfb8aa3b, v64
	v_mul_f32_e32 v65, 0xbfb8aa3b, v65
	v_rcp_f32_e32 v78, v78
	v_rcp_f32_e32 v79, v79
	v_exp_f32_e32 v64, v64
; __device__ __forceinline__ float bflo(unsigned w) { return __uint_as_float(w << 16); }
; __device__ __forceinline__ float bfhi(unsigned w) { return __uint_as_float(w & 0xffff0000u); }
; __device__ __forceinline__ unsigned dpp_ror8(unsigned x) { return (unsigned)__builtin_amdgcn_update_dpp(0, (int)x, 0x128, 0xf, 0xf, false); }
;     __device__ __forceinline__ void operator()(const f32x4 (&acc)[2][2][4][2], const Unit& u, int wr, int wc, int fr, int fq) const {
;     ...
;             for (int m = 0; m < 4; ++m) { const int row = row0 + ai * HALF + m * 16; const float ri = __builtin_amdgcn_rsqf(sse[row] * (1.f / D) + EPS);
;                 u32x4 rr[2], ee[2]; load_pair_lines(R, D, row, fr, col0, rr[0], rr[1], 32); load_pair_lines(E, D, row, fr, col0, ee[0], ee[1], 32);
;                 float* orow = OUT + (size_t)(row - fr + (fr & 7)) * D + col0 + (lo ? 0 : 4);
; #pragma unroll
;                 for (int bj = 0; bj < 2; ++bj) { const u32x4 rw = rr[bj], ew = ee[bj];
;                     const float r[8] = {bflo(rw.x), bfhi(rw.x), bflo(rw.y), bfhi(rw.y), bflo(rw.z), bfhi(rw.z), bflo(rw.w), bfhi(rw.w)};
;                     const float e[8] = {bflo(ew.x), bfhi(ew.x), bflo(ew.y), bfhi(ew.y), bflo(ew.z), bfhi(ew.z), bflo(ew.w), bfhi(ew.w)};
;                     float o[8];
; #pragma unroll
;                     for (int j = 0; j < 8; ++j) { const float a = acc[ai][bj][m][j >> 2][j & 3]; const float gg = gv[bj][j >> 2][j & 3];
;                         o[j] = r[j] + e[j] * ri * gg * __builtin_amdgcn_rcpf(1.f + __builtin_amdgcn_exp2f(-a * LOG2E)); }
;                     f32x4 o1, o2;
; #pragma unroll
;                     for (int j = 0; j < 4; ++j) { const unsigned a = __float_as_uint(o[j]), b = __float_as_uint(o[4 + j]); const unsigned sa = dpp_ror8(a), sb = dpp_ror8(b);
;                         o1[j] = __uint_as_float(lo ? a : sb); o2[j] = __uint_as_float(lo ? sa : b); }
;                     *(f32x4*)(orow + 32 * bj) = o1; *(f32x4*)(orow + (size_t)8 * D + 32 * bj) = o2; } }
	v_exp_f32_e32 v65, v65
	v_mul_f32_e32 v68, 0xbfb8aa3b, v68
	v_mul_f32_e32 v69, 0xbfb8aa3b, v69
	v_exp_f32_e32 v68, v68
	v_exp_f32_e32 v69, v69
	v_add_f32_e32 v64, 1.0, v64
	v_add_f32_e32 v65, 1.0, v65
	v_rcp_f32_e32 v64, v64
	v_mul_f32_e32 v66, 0xbfb8aa3b, v66
	v_mul_f32_e32 v67, 0xbfb8aa3b, v67
	v_rcp_f32_e32 v65, v65
	v_exp_f32_e32 v66, v66
	v_exp_f32_e32 v67, v67
	v_add_f32_e32 v68, 1.0, v68
	v_add_f32_e32 v69, 1.0, v69
	v_rcp_f32_e32 v68, v68
	v_mul_f32_e32 v70, 0xbfb8aa3b, v70
	v_mul_f32_e32 v71, 0xbfb8aa3b, v71
	v_rcp_f32_e32 v69, v69
	v_exp_f32_e32 v70, v70
	v_exp_f32_e32 v71, v71
	v_add_f32_e32 v66, 1.0, v66
	v_add_f32_e32 v67, 1.0, v67
	v_rcp_f32_e32 v66, v66
	v_rcp_f32_e32 v67, v67
	v_add_f32_e32 v70, 1.0, v70
	v_add_f32_e32 v71, 1.0, v71
	v_rcp_f32_e32 v70, v70
	v_rcp_f32_e32 v71, v71
	v_mul_f32_e32 v48, 0xbfb8aa3b, v48
	v_mul_f32_e32 v49, 0xbfb8aa3b, v49
	v_mul_f32_e32 v52, 0xbfb8aa3b, v52
	v_exp_f32_e32 v48, v48
	v_exp_f32_e32 v49, v49
	v_mul_f32_e32 v50, 0xbfb8aa3b, v50
	v_mul_f32_e32 v51, 0xbfb8aa3b, v51
	v_add_f32_e32 v48, 1.0, v48
	v_add_f32_e32 v49, 1.0, v49
	v_rcp_f32_e32 v48, v48
	v_rcp_f32_e32 v49, v49
	v_exp_f32_e32 v50, v50
	v_exp_f32_e32 v51, v51
	v_mul_f32_e32 v54, 0xbfb8aa3b, v54
	v_mul_f32_e32 v55, 0xbfb8aa3b, v55
	v_exp_f32_e32 v54, v54
	v_exp_f32_e32 v55, v55
	v_add_f32_e32 v50, 1.0, v50
	v_fmamk_f32 v80, v80, 0x3a000000, v182
	v_rsq_f32_e32 v80, v80
	v_add_f32_e32 v51, 1.0, v51
	v_rcp_f32_e32 v50, v50
	v_rcp_f32_e32 v51, v51
	v_add_f32_e32 v54, 1.0, v54
	v_add_f32_e32 v55, 1.0, v55
	v_mul_f32_e32 v32, 0xbfb8aa3b, v32
	v_mul_f32_e32 v33, 0xbfb8aa3b, v33
	v_rcp_f32_e32 v54, v54
	v_rcp_f32_e32 v55, v55
	v_mov_b32_dpp v100, v82 row_ror:8 row_mask:0xf bank_mask:0xf
	v_mov_b32_dpp v101, v83 row_ror:8 row_mask:0xf bank_mask:0xf
	v_mov_b32_dpp v106, v88 row_ror:8 row_mask:0xf bank_mask:0xf
	v_mov_b32_dpp v107, v89 row_ror:8 row_mask:0xf bank_mask:0xf
	v_mov_b32_dpp v102, v84 row_ror:8 row_mask:0xf bank_mask:0xf
	v_mov_b32_dpp v103, v85 row_ror:8 row_mask:0xf bank_mask:0xf
	v_mov_b32_dpp v105, v87 row_ror:8 row_mask:0xf bank_mask:0xf
	v_cndmask_b32_e64 v107, v107, v85, s[0:1]
	v_cndmask_b32_e64 v85, v106, v84, s[0:1]
	v_mov_b32_e32 v84, v157
	v_mov_b32_dpp v104, v86 row_ror:8 row_mask:0xf bank_mask:0xf
	v_cndmask_b32_e64 v105, v105, v83, s[0:1]
	v_cndmask_b32_e64 v101, v87, v101, s[0:1]
	v_cndmask_b32_e64 v89, v89, v103, s[0:1]
	v_cndmask_b32_e64 v100, v86, v100, s[0:1]
	v_mov_b32_e32 v83, v157
	v_mov_b32_dpp v84, v92 row_ror:8 row_mask:0xf bank_mask:0xf
	v_mov_b32_e32 v86, v157
	v_mov_b32_e32 v87, v157
	v_mov_b32_e32 v103, v157
	v_cndmask_b32_e64 v104, v104, v82, s[0:1]
	v_cndmask_b32_e64 v88, v88, v102, s[0:1]
	v_mov_b32_e32 v82, v157
	v_mov_b32_dpp v83, v91 row_ror:8 row_mask:0xf bank_mask:0xf
	v_mov_b32_dpp v86, v93 row_ror:8 row_mask:0xf bank_mask:0xf
	v_mov_b32_dpp v87, v94 row_ror:8 row_mask:0xf bank_mask:0xf
	v_mov_b32_e32 v102, v157
	v_mov_b32_dpp v103, v96 row_ror:8 row_mask:0xf bank_mask:0xf
	v_cndmask_b32_e64 v96, v96, v84, s[0:1]
	v_exp_f32_e32 v84, v76
	v_mul_f32_e32 v76, 0xbfb8aa3b, v77
	v_mov_b32_dpp v82, v90 row_ror:8 row_mask:0xf bank_mask:0xf
	v_mov_b32_dpp v102, v95 row_ror:8 row_mask:0xf bank_mask:0xf
	v_cndmask_b32_e64 v90, v87, v90, s[0:1]
	v_cndmask_b32_e64 v87, v103, v92, s[0:1]
	v_cndmask_b32_e64 v92, v95, v83, s[0:1]
	v_cndmask_b32_e64 v95, v97, v86, s[0:1]
	v_exp_f32_e32 v86, v76
	v_cndmask_b32_e64 v94, v94, v82, s[0:1]
	v_lshlrev_b64 v[82:83], 13, v[98:99]
	v_lshl_add_u64 v[82:83], s[4:5], 0, v[82:83]
	v_lshl_add_u64 v[82:83], v[82:83], 0, v[166:167]
	v_lshl_add_u64 v[76:77], v[82:83], 0, v[156:157]
	v_add_f32_e32 v83, 1.0, v86
	v_lshlrev_b32_e32 v86, 16, v87
	v_and_b32_e32 v87, 0xffff0000, v87
	v_add_f32_e32 v82, 1.0, v84
	v_pk_mul_f32 v[86:87], v[80:81], v[86:87] op_sel_hi:[0,1]
	v_rcp_f32_e32 v82, v82
	v_rcp_f32_e32 v83, v83
	v_lshlrev_b32_e32 v84, 16, v85
	v_and_b32_e32 v85, 0xffff0000, v85
	v_pk_mul_f32 v[86:87], v[60:61], v[86:87]
	v_mov_b32_e32 v106, v157
	v_pk_fma_f32 v[86:87], v[72:73], v[86:87], v[84:85]
	v_lshlrev_b32_e32 v84, 16, v90
	v_and_b32_e32 v85, 0xffff0000, v90
	v_mov_b32_dpp v106, v97 row_ror:8 row_mask:0xf bank_mask:0xf
	v_pk_mul_f32 v[84:85], v[80:81], v[84:85] op_sel_hi:[0,1]
	v_cndmask_b32_e64 v93, v106, v93, s[0:1]
	v_lshlrev_b32_e32 v72, 16, v104
	v_and_b32_e32 v73, 0xffff0000, v104
	v_pk_mul_f32 v[84:85], v[56:57], v[84:85]
	v_cndmask_b32_e64 v91, v102, v91, s[0:1]
	v_pk_fma_f32 v[72:73], v[82:83], v[84:85], v[72:73]
	v_lshlrev_b32_e32 v84, 16, v93
	v_and_b32_e32 v85, 0xffff0000, v93
	v_pk_mul_f32 v[84:85], v[80:81], v[84:85] op_sel_hi:[0,1]
	v_lshlrev_b32_e32 v82, 16, v107
	v_and_b32_e32 v83, 0xffff0000, v107
	v_pk_mul_f32 v[84:85], v[62:63], v[84:85]
	v_mov_b32_e32 v97, v157
	v_pk_fma_f32 v[82:83], v[74:75], v[84:85], v[82:83]
	v_lshlrev_b32_e32 v84, 16, v91
	v_and_b32_e32 v85, 0xffff0000, v91
	v_pk_mul_f32 v[84:85], v[80:81], v[84:85] op_sel_hi:[0,1]
	v_lshlrev_b32_e32 v74, 16, v105
	v_and_b32_e32 v75, 0xffff0000, v105
	v_pk_mul_f32 v[84:85], v[58:59], v[84:85]
	v_mov_b32_e32 v98, v157
	v_pk_fma_f32 v[74:75], v[78:79], v[84:85], v[74:75]
	v_mov_b32_e32 v78, v157
	v_mov_b32_e32 v79, v157
	v_mov_b32_e32 v93, v157
	v_mov_b32_e32 v102, v157
	v_mov_b32_dpp v78, v74 row_ror:8 row_mask:0xf bank_mask:0xf
	v_mov_b32_dpp v79, v75 row_ror:8 row_mask:0xf bank_mask:0xf
	v_mov_b32_dpp v97, v86 row_ror:8 row_mask:0xf bank_mask:0xf
	v_mov_b32_dpp v98, v87 row_ror:8 row_mask:0xf bank_mask:0xf
	v_mov_b32_e32 v90, v157
	v_mov_b32_e32 v99, v157
	v_mov_b32_dpp v93, v82 row_ror:8 row_mask:0xf bank_mask:0xf
	v_mov_b32_dpp v102, v83 row_ror:8 row_mask:0xf bank_mask:0xf
; __device__ __forceinline__ float bflo(unsigned w) { return __uint_as_float(w << 16); }
; __device__ __forceinline__ float bfhi(unsigned w) { return __uint_as_float(w & 0xffff0000u); }
; __device__ __forceinline__ unsigned dpp_ror8(unsigned x) { return (unsigned)__builtin_amdgcn_update_dpp(0, (int)x, 0x128, 0xf, 0xf, false); }
;     __device__ __forceinline__ void operator()(const f32x4 (&acc)[2][2][4][2], const Unit& u, int wr, int wc, int fr, int fq) const {
;     ...
;             for (int m = 0; m < 4; ++m) { const int row = row0 + ai * HALF + m * 16; const float ri = __builtin_amdgcn_rsqf(sse[row] * (1.f / D) + EPS);
;                 u32x4 rr[2], ee[2]; load_pair_lines(R, D, row, fr, col0, rr[0], rr[1], 32); load_pair_lines(E, D, row, fr, col0, ee[0], ee[1], 32);
;                 float* orow = OUT + (size_t)(row - fr + (fr & 7)) * D + col0 + (lo ? 0 : 4);
; #pragma unroll
;                 for (int bj = 0; bj < 2; ++bj) { const u32x4 rw = rr[bj], ew = ee[bj];
;                     const float r[8] = {bflo(rw.x), bfhi(rw.x), bflo(rw.y), bfhi(rw.y), bflo(rw.z), bfhi(rw.z), bflo(rw.w), bfhi(rw.w)};
;                     const float e[8] = {bflo(ew.x), bfhi(ew.x), bflo(ew.y), bfhi(ew.y), bflo(ew.z), bfhi(ew.z), bflo(ew.w), bfhi(ew.w)};
;                     float o[8];
; #pragma unroll
;                     for (int j = 0; j < 8; ++j) { const float a = acc[ai][bj][m][j >> 2][j & 3]; const float gg = gv[bj][j >> 2][j & 3];
;                         o[j] = r[j] + e[j] * ri * gg * __builtin_amdgcn_rcpf(1.f + __builtin_amdgcn_exp2f(-a * LOG2E)); }
;                     f32x4 o1, o2;
; #pragma unroll
;                     for (int j = 0; j < 4; ++j) { const unsigned a = __float_as_uint(o[j]), b = __float_as_uint(o[4 + j]); const unsigned sa = dpp_ror8(a), sb = dpp_ror8(b);
;                         o1[j] = __uint_as_float(lo ? a : sb); o2[j] = __uint_as_float(lo ? sa : b); }
;                     *(f32x4*)(orow + 32 * bj) = o1; *(f32x4*)(orow + (size_t)8 * D + 32 * bj) = o2; } }
	v_cndmask_b32_e64 v85, v83, v79, s[0:1]
	v_cndmask_b32_e64 v84, v82, v78, s[0:1]
	v_lshlrev_b32_e32 v78, 16, v96
	v_and_b32_e32 v79, 0xffff0000, v96
	v_mov_b32_dpp v90, v72 row_ror:8 row_mask:0xf bank_mask:0xf
	v_mov_b32_dpp v99, v73 row_ror:8 row_mask:0xf bank_mask:0xf
	v_cndmask_b32_e64 v75, v102, v75, s[0:1]
	v_cndmask_b32_e64 v74, v93, v74, s[0:1]
	v_cndmask_b32_e64 v73, v98, v73, s[0:1]
	v_cndmask_b32_e64 v72, v97, v72, s[0:1]
	v_pk_mul_f32 v[78:79], v[80:81], v[78:79] op_sel_hi:[0,1]
	global_store_dwordx4 v[76:77], v[72:75], off
	v_pk_mul_f32 v[78:79], v[44:45], v[78:79]
	v_cndmask_b32_e64 v83, v87, v99, s[0:1]
	v_lshlrev_b32_e32 v74, 16, v88
	v_and_b32_e32 v75, 0xffff0000, v88
	v_pk_fma_f32 v[74:75], v[64:65], v[78:79], v[74:75]
	v_lshlrev_b32_e32 v78, 16, v94
	v_and_b32_e32 v79, 0xffff0000, v94
	v_pk_mul_f32 v[78:79], v[80:81], v[78:79] op_sel_hi:[0,1]
	v_lshlrev_b32_e32 v64, 16, v100
	v_and_b32_e32 v65, 0xffff0000, v100
	v_pk_mul_f32 v[78:79], v[40:41], v[78:79]
	v_add_co_u32_e32 v72, vcc, s45, v76
	v_pk_fma_f32 v[64:65], v[68:69], v[78:79], v[64:65]
	v_lshlrev_b32_e32 v78, 16, v95
	v_and_b32_e32 v79, 0xffff0000, v95
	v_pk_mul_f32 v[78:79], v[80:81], v[78:79] op_sel_hi:[0,1]
	v_lshlrev_b32_e32 v68, 16, v89
	v_and_b32_e32 v69, 0xffff0000, v89
	v_pk_mul_f32 v[78:79], v[46:47], v[78:79]
	v_cndmask_b32_e64 v82, v86, v90, s[0:1]
	v_pk_fma_f32 v[68:69], v[66:67], v[78:79], v[68:69]
	v_lshlrev_b32_e32 v78, 16, v92
	v_and_b32_e32 v79, 0xffff0000, v92
	v_addc_co_u32_e32 v73, vcc, 0, v77, vcc
	v_pk_mul_f32 v[78:79], v[80:81], v[78:79] op_sel_hi:[0,1]
	global_store_dwordx4 v[72:73], v[82:85], off
	v_mov_b32_e32 v86, v157
	v_mov_b32_e32 v87, v157
	v_mov_b32_e32 v82, v157
	v_mov_b32_e32 v83, v157
	v_lshlrev_b32_e32 v66, 16, v101
	v_and_b32_e32 v67, 0xffff0000, v101
	v_pk_mul_f32 v[78:79], v[42:43], v[78:79]
	v_mov_b32_dpp v82, v74 row_ror:8 row_mask:0xf bank_mask:0xf
	v_mov_b32_dpp v83, v75 row_ror:8 row_mask:0xf bank_mask:0xf
	v_mov_b32_e32 v84, v157
	v_mov_b32_e32 v85, v157
	v_mov_b32_dpp v86, v68 row_ror:8 row_mask:0xf bank_mask:0xf
	v_mov_b32_dpp v87, v69 row_ror:8 row_mask:0xf bank_mask:0xf
	v_pk_fma_f32 v[66:67], v[70:71], v[78:79], v[66:67]
	v_mov_b32_e32 v70, v157
	v_mov_b32_e32 v71, v157
	v_add_u32_e32 v78, 0x90, v81
	v_mov_b32_dpp v84, v64 row_ror:8 row_mask:0xf bank_mask:0xf
	v_mov_b32_dpp v85, v65 row_ror:8 row_mask:0xf bank_mask:0xf
	v_mov_b32_dpp v70, v66 row_ror:8 row_mask:0xf bank_mask:0xf
	v_mov_b32_dpp v71, v67 row_ror:8 row_mask:0xf bank_mask:0xf
	v_cndmask_b32_e64 v67, v87, v67, s[0:1]
	v_cndmask_b32_e64 v66, v86, v66, s[0:1]
	v_cndmask_b32_e64 v65, v83, v65, s[0:1]
	v_cndmask_b32_e64 v64, v82, v64, s[0:1]
	v_ashrrev_i32_e32 v79, 31, v78
	v_cndmask_b32_e64 v71, v69, v71, s[0:1]
	v_cndmask_b32_e64 v70, v68, v70, s[0:1]
	v_cndmask_b32_e64 v69, v75, v85, s[0:1]
	v_cndmask_b32_e64 v68, v74, v84, s[0:1]
	global_store_dwordx4 v[76:77], v[64:67], off offset:128
	global_store_dwordx4 v[72:73], v[68:71], off offset:128
	s_waitcnt vmcnt(4)
	s_nop 0
	v_mov_b32_e32 v80, v228
	v_lshlrev_b64 v[64:65], 12, v[78:79]
	v_lshl_add_u64 v[82:83], v[64:65], 0, s[16:17]
	v_lshl_add_u64 v[70:71], s[8:9], 0, v[82:83]
	v_lshl_add_u64 v[66:67], s[8:9], 0, v[64:65]
	v_lshl_add_u64 v[70:71], v[70:71], 0, v[164:165]
	v_lshl_add_u64 v[64:65], s[10:11], 0, v[64:65]
	v_lshl_add_u64 v[66:67], v[66:67], 0, v[164:165]
	v_mov_b64_e32 v[70:71], v[232:233]
	v_mov_b64_e32 v[72:73], v[234:235]
	v_lshl_add_u64 v[64:65], v[64:65], 0, v[164:165]
	v_mov_b64_e32 v[66:67], v[236:237]
	v_mov_b64_e32 v[68:69], v[238:239]
	v_mov_b32_e32 v90, v157
	v_mov_b64_e32 v[74:75], v[240:241]
	v_mov_b64_e32 v[76:77], v[242:243]
	v_lshl_add_u64 v[64:65], s[10:11], 0, v[82:83]
	v_lshl_add_u64 v[64:65], v[64:65], 0, v[164:165]
	v_mov_b64_e32 v[82:83], v[244:245]
	v_mov_b64_e32 v[84:85], v[246:247]
	s_nop 1
	global_load_dword v228, v[168:169], off offset:640
	v_add_u32_e32 v220, 0xa0, v81
	v_ashrrev_i32_e32 v221, 31, v220
	v_lshlrev_b64 v[216:217], 12, v[220:221]
	v_lshl_add_u64 v[224:225], v[216:217], 0, s[16:17]
	v_lshl_add_u64 v[222:223], s[8:9], 0, v[224:225]
	v_lshl_add_u64 v[218:219], s[8:9], 0, v[216:217]
	v_lshl_add_u64 v[222:223], v[222:223], 0, v[164:165]
	v_lshl_add_u64 v[216:217], s[10:11], 0, v[216:217]
	v_lshl_add_u64 v[218:219], v[218:219], 0, v[164:165]
	global_load_dwordx4 v[232:235], v[222:223], off
	v_lshl_add_u64 v[216:217], v[216:217], 0, v[164:165]
	global_load_dwordx4 v[236:239], v[218:219], off
	global_load_dwordx4 v[240:243], v[216:217], off
	v_lshl_add_u64 v[216:217], s[10:11], 0, v[224:225]
	v_lshl_add_u64 v[216:217], v[216:217], 0, v[164:165]
	global_load_dwordx4 v[244:247], v[216:217], off
	v_mov_b32_e32 v91, v157
	v_mov_b32_e32 v65, v157
	v_mov_b32_e32 v86, v157
	v_mov_b32_e32 v87, v157
	v_mov_b32_e32 v89, v157
	v_mov_b32_e32 v88, v157
	v_exp_f32_e32 v32, v32
	v_exp_f32_e32 v33, v33
	v_mul_f32_e32 v36, 0xbfb8aa3b, v36
	v_mul_f32_e32 v37, 0xbfb8aa3b, v37
	v_exp_f32_e32 v36, v36
	v_exp_f32_e32 v37, v37
	v_add_f32_e32 v32, 1.0, v32
	v_add_f32_e32 v33, 1.0, v33
	v_rcp_f32_e32 v32, v32
	v_rcp_f32_e32 v33, v33
	v_mul_f32_e32 v34, 0xbfb8aa3b, v34
	v_mul_f32_e32 v35, 0xbfb8aa3b, v35
	v_add_f32_e32 v36, 1.0, v36
	v_add_f32_e32 v37, 1.0, v37
	v_exp_f32_e32 v34, v34
	v_exp_f32_e32 v35, v35
	v_rcp_f32_e32 v36, v36
	v_rcp_f32_e32 v37, v37
	v_mul_f32_e32 v38, 0xbfb8aa3b, v38
	v_mul_f32_e32 v39, 0xbfb8aa3b, v39
	v_exp_f32_e32 v38, v38
	v_exp_f32_e32 v39, v39
	v_add_f32_e32 v34, 1.0, v34
	v_add_f32_e32 v35, 1.0, v35
	v_rcp_f32_e32 v34, v34
	v_rcp_f32_e32 v35, v35
	v_add_f32_e32 v38, 1.0, v38
	v_add_f32_e32 v39, 1.0, v39
	v_rcp_f32_e32 v38, v38
	v_rcp_f32_e32 v39, v39
; __device__ __forceinline__ float bflo(unsigned w) { return __uint_as_float(w << 16); }
; __device__ __forceinline__ float bfhi(unsigned w) { return __uint_as_float(w & 0xffff0000u); }
; __device__ __forceinline__ unsigned dpp_ror8(unsigned x) { return (unsigned)__builtin_amdgcn_update_dpp(0, (int)x, 0x128, 0xf, 0xf, false); }
;     __device__ __forceinline__ void operator()(const f32x4 (&acc)[2][2][4][2], const Unit& u, int wr, int wc, int fr, int fq) const {
;     ...
;             for (int m = 0; m < 4; ++m) { const int row = row0 + ai * HALF + m * 16; const float ri = __builtin_amdgcn_rsqf(sse[row] * (1.f / D) + EPS);
;                 u32x4 rr[2], ee[2]; load_pair_lines(R, D, row, fr, col0, rr[0], rr[1], 32); load_pair_lines(E, D, row, fr, col0, ee[0], ee[1], 32);
;                 float* orow = OUT + (size_t)(row - fr + (fr & 7)) * D + col0 + (lo ? 0 : 4);
; #pragma unroll
;                 for (int bj = 0; bj < 2; ++bj) { const u32x4 rw = rr[bj], ew = ee[bj];
;                     const float r[8] = {bflo(rw.x), bfhi(rw.x), bflo(rw.y), bfhi(rw.y), bflo(rw.z), bfhi(rw.z), bflo(rw.w), bfhi(rw.w)};
;                     const float e[8] = {bflo(ew.x), bfhi(ew.x), bflo(ew.y), bfhi(ew.y), bflo(ew.z), bfhi(ew.z), bflo(ew.w), bfhi(ew.w)};
;                     float o[8];
; #pragma unroll
;                     for (int j = 0; j < 8; ++j) { const float a = acc[ai][bj][m][j >> 2][j & 3]; const float gg = gv[bj][j >> 2][j & 3];
;                         o[j] = r[j] + e[j] * ri * gg * __builtin_amdgcn_rcpf(1.f + __builtin_amdgcn_exp2f(-a * LOG2E)); }
;                     f32x4 o1, o2;
; #pragma unroll
;                     for (int j = 0; j < 4; ++j) { const unsigned a = __float_as_uint(o[j]), b = __float_as_uint(o[4 + j]); const unsigned sa = dpp_ror8(a), sb = dpp_ror8(b);
;                         o1[j] = __uint_as_float(lo ? a : sb); o2[j] = __uint_as_float(lo ? sa : b); }
;                     *(f32x4*)(orow + 32 * bj) = o1; *(f32x4*)(orow + (size_t)8 * D + 32 * bj) = o2; } }
	v_mul_f32_e32 v24, 0xbfb8aa3b, v24
	v_mul_f32_e32 v25, 0xbfb8aa3b, v25
	v_mul_f32_e32 v28, 0xbfb8aa3b, v28
	v_exp_f32_e32 v24, v24
	v_exp_f32_e32 v25, v25
	v_mul_f32_e32 v26, 0xbfb8aa3b, v26
	v_mul_f32_e32 v27, 0xbfb8aa3b, v27
	v_add_f32_e32 v24, 1.0, v24
	v_add_f32_e32 v25, 1.0, v25
	v_rcp_f32_e32 v24, v24
	v_rcp_f32_e32 v25, v25
	v_exp_f32_e32 v26, v26
	v_exp_f32_e32 v27, v27
	v_mul_f32_e32 v30, 0xbfb8aa3b, v30
	v_mul_f32_e32 v31, 0xbfb8aa3b, v31
	v_exp_f32_e32 v30, v30
	v_exp_f32_e32 v31, v31
	v_add_f32_e32 v26, 1.0, v26
	v_add_f32_e32 v27, 1.0, v27
	v_rcp_f32_e32 v26, v26
	v_rcp_f32_e32 v27, v27
	v_add_f32_e32 v30, 1.0, v30
	v_add_f32_e32 v31, 1.0, v31
	v_mul_f32_e32 v16, 0xbfb8aa3b, v16
	v_mul_f32_e32 v17, 0xbfb8aa3b, v17
	v_rcp_f32_e32 v30, v30
	v_rcp_f32_e32 v31, v31
	v_exp_f32_e32 v16, v16
	v_fmamk_f32 v64, v80, 0x3a000000, v182
	v_mov_b32_e32 v80, v157
	v_rsq_f32_e32 v64, v64
	v_exp_f32_e32 v17, v17
	v_mul_f32_e32 v20, 0xbfb8aa3b, v20
	v_mul_f32_e32 v21, 0xbfb8aa3b, v21
	v_exp_f32_e32 v20, v20
	v_exp_f32_e32 v21, v21
	v_mov_b32_dpp v90, v72 row_ror:8 row_mask:0xf bank_mask:0xf
	v_mov_b32_dpp v91, v73 row_ror:8 row_mask:0xf bank_mask:0xf
	v_mov_b32_dpp v65, v66 row_ror:8 row_mask:0xf bank_mask:0xf
	v_mov_b32_dpp v80, v67 row_ror:8 row_mask:0xf bank_mask:0xf
	v_mov_b32_dpp v86, v68 row_ror:8 row_mask:0xf bank_mask:0xf
	v_mov_b32_dpp v87, v69 row_ror:8 row_mask:0xf bank_mask:0xf
	v_mov_b32_dpp v89, v71 row_ror:8 row_mask:0xf bank_mask:0xf
	v_cndmask_b32_e64 v91, v91, v69, s[0:1]
	v_cndmask_b32_e64 v69, v90, v68, s[0:1]
	v_mov_b32_e32 v68, v157
	v_mov_b32_dpp v88, v70 row_ror:8 row_mask:0xf bank_mask:0xf
	v_cndmask_b32_e64 v89, v89, v67, s[0:1]
	v_cndmask_b32_e64 v80, v71, v80, s[0:1]
	v_cndmask_b32_e64 v73, v73, v87, s[0:1]
	v_cndmask_b32_e64 v65, v70, v65, s[0:1]
	v_mov_b32_e32 v67, v157
	v_mov_b32_dpp v68, v76 row_ror:8 row_mask:0xf bank_mask:0xf
	v_mov_b32_e32 v70, v157
	v_mov_b32_e32 v71, v157
	v_mov_b32_e32 v87, v157
	v_cndmask_b32_e64 v88, v88, v66, s[0:1]
	v_cndmask_b32_e64 v72, v72, v86, s[0:1]
	v_mov_b32_e32 v66, v157
	v_mov_b32_dpp v67, v75 row_ror:8 row_mask:0xf bank_mask:0xf
	v_mov_b32_dpp v70, v77 row_ror:8 row_mask:0xf bank_mask:0xf
	v_mov_b32_dpp v71, v82 row_ror:8 row_mask:0xf bank_mask:0xf
	v_mov_b32_e32 v86, v157
	v_mov_b32_dpp v87, v84 row_ror:8 row_mask:0xf bank_mask:0xf
	v_cndmask_b32_e64 v84, v84, v68, s[0:1]
	v_exp_f32_e32 v68, v52
	v_mul_f32_e32 v52, 0xbfb8aa3b, v53
	v_mov_b32_dpp v66, v74 row_ror:8 row_mask:0xf bank_mask:0xf
	v_mov_b32_dpp v86, v83 row_ror:8 row_mask:0xf bank_mask:0xf
	v_cndmask_b32_e64 v74, v71, v74, s[0:1]
	v_cndmask_b32_e64 v71, v87, v76, s[0:1]
	v_cndmask_b32_e64 v76, v83, v67, s[0:1]
	v_cndmask_b32_e64 v83, v85, v70, s[0:1]
	v_exp_f32_e32 v70, v52
	v_cndmask_b32_e64 v82, v82, v66, s[0:1]
	v_lshlrev_b64 v[66:67], 13, v[78:79]
	v_lshl_add_u64 v[66:67], s[4:5], 0, v[66:67]
	v_lshl_add_u64 v[66:67], v[66:67], 0, v[166:167]
	v_lshl_add_u64 v[52:53], v[66:67], 0, v[156:157]
	v_add_f32_e32 v67, 1.0, v70
	v_lshlrev_b32_e32 v70, 16, v71
	v_and_b32_e32 v71, 0xffff0000, v71
	v_add_f32_e32 v66, 1.0, v68
	v_pk_mul_f32 v[70:71], v[64:65], v[70:71] op_sel_hi:[0,1]
	v_rcp_f32_e32 v66, v66
	v_rcp_f32_e32 v67, v67
	v_lshlrev_b32_e32 v68, 16, v69
	v_and_b32_e32 v69, 0xffff0000, v69
	v_pk_mul_f32 v[70:71], v[60:61], v[70:71]
	v_mov_b32_e32 v90, v157
	v_pk_fma_f32 v[70:71], v[48:49], v[70:71], v[68:69]
	v_lshlrev_b32_e32 v68, 16, v74
	v_and_b32_e32 v69, 0xffff0000, v74
	v_mov_b32_dpp v90, v85 row_ror:8 row_mask:0xf bank_mask:0xf
	v_pk_mul_f32 v[68:69], v[64:65], v[68:69] op_sel_hi:[0,1]
	v_cndmask_b32_e64 v77, v90, v77, s[0:1]
	v_lshlrev_b32_e32 v48, 16, v88
	v_and_b32_e32 v49, 0xffff0000, v88
	v_pk_mul_f32 v[68:69], v[56:57], v[68:69]
	v_cndmask_b32_e64 v75, v86, v75, s[0:1]
	v_pk_fma_f32 v[48:49], v[66:67], v[68:69], v[48:49]
	v_lshlrev_b32_e32 v68, 16, v77
	v_and_b32_e32 v69, 0xffff0000, v77
	v_pk_mul_f32 v[68:69], v[64:65], v[68:69] op_sel_hi:[0,1]
	v_lshlrev_b32_e32 v66, 16, v91
	v_and_b32_e32 v67, 0xffff0000, v91
	v_pk_mul_f32 v[68:69], v[62:63], v[68:69]
	v_mov_b32_e32 v78, v157
	v_pk_fma_f32 v[66:67], v[50:51], v[68:69], v[66:67]
	v_lshlrev_b32_e32 v68, 16, v75
	v_and_b32_e32 v69, 0xffff0000, v75
	v_pk_mul_f32 v[68:69], v[64:65], v[68:69] op_sel_hi:[0,1]
	v_lshlrev_b32_e32 v50, 16, v89
	v_and_b32_e32 v51, 0xffff0000, v89
	v_pk_mul_f32 v[68:69], v[58:59], v[68:69]
	v_mov_b32_e32 v79, v157
	v_pk_fma_f32 v[50:51], v[54:55], v[68:69], v[50:51]
	v_mov_b32_e32 v54, v157
	v_mov_b32_e32 v55, v157
	v_mov_b32_e32 v77, v157
	v_mov_b32_e32 v86, v157
	v_mov_b32_dpp v54, v50 row_ror:8 row_mask:0xf bank_mask:0xf
	v_mov_b32_dpp v55, v51 row_ror:8 row_mask:0xf bank_mask:0xf
	v_mov_b32_dpp v78, v70 row_ror:8 row_mask:0xf bank_mask:0xf
	v_mov_b32_dpp v79, v71 row_ror:8 row_mask:0xf bank_mask:0xf
	v_mov_b32_e32 v74, v157
	v_mov_b32_e32 v85, v157
	v_mov_b32_dpp v77, v66 row_ror:8 row_mask:0xf bank_mask:0xf
	v_mov_b32_dpp v86, v67 row_ror:8 row_mask:0xf bank_mask:0xf
	v_cndmask_b32_e64 v69, v67, v55, s[0:1]
	v_cndmask_b32_e64 v68, v66, v54, s[0:1]
	v_lshlrev_b32_e32 v54, 16, v84
	v_and_b32_e32 v55, 0xffff0000, v84
	v_mov_b32_dpp v74, v48 row_ror:8 row_mask:0xf bank_mask:0xf
	v_mov_b32_dpp v85, v49 row_ror:8 row_mask:0xf bank_mask:0xf
	v_cndmask_b32_e64 v51, v86, v51, s[0:1]
	v_cndmask_b32_e64 v50, v77, v50, s[0:1]
	v_cndmask_b32_e64 v49, v79, v49, s[0:1]
	v_cndmask_b32_e64 v48, v78, v48, s[0:1]
	v_pk_mul_f32 v[54:55], v[64:65], v[54:55] op_sel_hi:[0,1]
	global_store_dwordx4 v[52:53], v[48:51], off
	v_pk_mul_f32 v[54:55], v[44:45], v[54:55]
	v_cndmask_b32_e64 v67, v71, v85, s[0:1]
	v_lshlrev_b32_e32 v50, 16, v72
; __device__ __forceinline__ float bflo(unsigned w) { return __uint_as_float(w << 16); }
; __device__ __forceinline__ float bfhi(unsigned w) { return __uint_as_float(w & 0xffff0000u); }
; __device__ __forceinline__ unsigned dpp_ror8(unsigned x) { return (unsigned)__builtin_amdgcn_update_dpp(0, (int)x, 0x128, 0xf, 0xf, false); }
;     __device__ __forceinline__ void operator()(const f32x4 (&acc)[2][2][4][2], const Unit& u, int wr, int wc, int fr, int fq) const {
;     ...
;             for (int m = 0; m < 4; ++m) { const int row = row0 + ai * HALF + m * 16; const float ri = __builtin_amdgcn_rsqf(sse[row] * (1.f / D) + EPS);
;                 u32x4 rr[2], ee[2]; load_pair_lines(R, D, row, fr, col0, rr[0], rr[1], 32); load_pair_lines(E, D, row, fr, col0, ee[0], ee[1], 32);
;                 float* orow = OUT + (size_t)(row - fr + (fr & 7)) * D + col0 + (lo ? 0 : 4);
; #pragma unroll
;                 for (int bj = 0; bj < 2; ++bj) { const u32x4 rw = rr[bj], ew = ee[bj];
;                     const float r[8] = {bflo(rw.x), bfhi(rw.x), bflo(rw.y), bfhi(rw.y), bflo(rw.z), bfhi(rw.z), bflo(rw.w), bfhi(rw.w)};
;                     const float e[8] = {bflo(ew.x), bfhi(ew.x), bflo(ew.y), bfhi(ew.y), bflo(ew.z), bfhi(ew.z), bflo(ew.w), bfhi(ew.w)};
;                     float o[8];
; #pragma unroll
;                     for (int j = 0; j < 8; ++j) { const float a = acc[ai][bj][m][j >> 2][j & 3]; const float gg = gv[bj][j >> 2][j & 3];
;                         o[j] = r[j] + e[j] * ri * gg * __builtin_amdgcn_rcpf(1.f + __builtin_amdgcn_exp2f(-a * LOG2E)); }
;                     f32x4 o1, o2;
; #pragma unroll
;                     for (int j = 0; j < 4; ++j) { const unsigned a = __float_as_uint(o[j]), b = __float_as_uint(o[4 + j]); const unsigned sa = dpp_ror8(a), sb = dpp_ror8(b);
;                         o1[j] = __uint_as_float(lo ? a : sb); o2[j] = __uint_as_float(lo ? sa : b); }
;                     *(f32x4*)(orow + 32 * bj) = o1; *(f32x4*)(orow + (size_t)8 * D + 32 * bj) = o2; } }
	v_and_b32_e32 v51, 0xffff0000, v72
	v_pk_fma_f32 v[50:51], v[32:33], v[54:55], v[50:51]
	v_lshlrev_b32_e32 v54, 16, v82
	v_and_b32_e32 v55, 0xffff0000, v82
	v_pk_mul_f32 v[54:55], v[64:65], v[54:55] op_sel_hi:[0,1]
	v_lshlrev_b32_e32 v32, 16, v65
	v_and_b32_e32 v33, 0xffff0000, v65
	v_pk_mul_f32 v[54:55], v[40:41], v[54:55]
	v_mov_b32_e32 v65, v157
	v_pk_fma_f32 v[32:33], v[36:37], v[54:55], v[32:33]
	v_lshlrev_b32_e32 v54, 16, v83
	v_and_b32_e32 v55, 0xffff0000, v83
	v_mov_b32_dpp v65, v32 row_ror:8 row_mask:0xf bank_mask:0xf
	v_pk_mul_f32 v[54:55], v[64:65], v[54:55] op_sel_hi:[0,1]
	v_lshlrev_b32_e32 v36, 16, v73
	v_and_b32_e32 v37, 0xffff0000, v73
	v_pk_mul_f32 v[54:55], v[46:47], v[54:55]
	v_add_co_u32_e32 v48, vcc, s45, v52
	v_pk_fma_f32 v[36:37], v[34:35], v[54:55], v[36:37]
	v_lshlrev_b32_e32 v54, 16, v76
	v_and_b32_e32 v55, 0xffff0000, v76
	v_pk_mul_f32 v[54:55], v[64:65], v[54:55] op_sel_hi:[0,1]
	v_cndmask_b32_e64 v66, v70, v74, s[0:1]
	v_addc_co_u32_e32 v49, vcc, 0, v53, vcc
	v_lshlrev_b32_e32 v34, 16, v80
	v_and_b32_e32 v35, 0xffff0000, v80
	v_pk_mul_f32 v[54:55], v[42:43], v[54:55]
	global_store_dwordx4 v[48:49], v[66:69], off
	v_mov_b32_e32 v70, v157
	v_pk_fma_f32 v[34:35], v[38:39], v[54:55], v[34:35]
	v_mov_b32_e32 v66, v157
	v_mov_b32_e32 v67, v157
	v_mov_b32_e32 v69, v157
	v_mov_b32_e32 v38, v157
	v_mov_b32_dpp v66, v50 row_ror:8 row_mask:0xf bank_mask:0xf
	v_mov_b32_dpp v67, v51 row_ror:8 row_mask:0xf bank_mask:0xf
	v_mov_b32_e32 v68, v157
	v_mov_b32_dpp v69, v36 row_ror:8 row_mask:0xf bank_mask:0xf
	v_mov_b32_dpp v70, v37 row_ror:8 row_mask:0xf bank_mask:0xf
	v_mov_b32_dpp v38, v34 row_ror:8 row_mask:0xf bank_mask:0xf
	v_mov_b32_e32 v39, v157
	v_mov_b32_dpp v68, v33 row_ror:8 row_mask:0xf bank_mask:0xf
	v_cndmask_b32_e64 v34, v69, v34, s[0:1]
	v_mov_b32_dpp v39, v35 row_ror:8 row_mask:0xf bank_mask:0xf
	v_cndmask_b32_e64 v35, v70, v35, s[0:1]
	v_cndmask_b32_e64 v33, v67, v33, s[0:1]
	v_cndmask_b32_e64 v32, v66, v32, s[0:1]
	v_cndmask_b32_e64 v38, v36, v38, s[0:1]
	v_cndmask_b32_e64 v39, v37, v39, s[0:1]
	v_cndmask_b32_e64 v37, v51, v68, s[0:1]
	v_cndmask_b32_e64 v36, v50, v65, s[0:1]
	global_store_dwordx4 v[52:53], v[32:35], off offset:128
	global_store_dwordx4 v[48:49], v[36:39], off offset:128
	s_waitcnt vmcnt(4)
	s_nop 0
	v_mov_b32_e32 v68, v228
	v_mov_b32_e32 v73, v157
	v_add_u32_e32 v38, 0xa0, v81
	v_ashrrev_i32_e32 v39, 31, v38
	v_lshlrev_b64 v[32:33], 12, v[38:39]
	v_lshl_add_u64 v[64:65], v[32:33], 0, s[16:17]
	v_lshl_add_u64 v[48:49], s[8:9], 0, v[64:65]
	v_lshl_add_u64 v[34:35], s[8:9], 0, v[32:33]
	v_lshl_add_u64 v[48:49], v[48:49], 0, v[164:165]
	v_lshl_add_u64 v[32:33], s[10:11], 0, v[32:33]
	v_lshl_add_u64 v[34:35], v[34:35], 0, v[164:165]
	v_mov_b64_e32 v[48:49], v[232:233]
	v_mov_b64_e32 v[50:51], v[234:235]
	v_lshl_add_u64 v[32:33], v[32:33], 0, v[164:165]
	v_mov_b64_e32 v[34:35], v[236:237]
	v_mov_b64_e32 v[36:37], v[238:239]
	v_mov_b32_e32 v74, v157
	v_mov_b64_e32 v[52:53], v[240:241]
	v_mov_b64_e32 v[54:55], v[242:243]
	v_lshl_add_u64 v[32:33], s[10:11], 0, v[64:65]
	v_lshl_add_u64 v[32:33], v[32:33], 0, v[164:165]
	v_mov_b64_e32 v[64:65], v[244:245]
	v_mov_b64_e32 v[66:67], v[246:247]
	s_nop 1
	v_add_u32_e32 v224, 0xb0, v81
	v_ashrrev_i32_e32 v225, 31, v224
	global_load_dword v228, v[168:169], off offset:704
	v_lshlrev_b64 v[216:217], 12, v[224:225]
	v_lshl_add_u64 v[222:223], v[216:217], 0, s[16:17]
	v_lshl_add_u64 v[220:221], s[8:9], 0, v[222:223]
	v_lshl_add_u64 v[218:219], s[8:9], 0, v[216:217]
	v_lshl_add_u64 v[220:221], v[220:221], 0, v[164:165]
	v_lshl_add_u64 v[216:217], s[10:11], 0, v[216:217]
	v_lshl_add_u64 v[218:219], v[218:219], 0, v[164:165]
	global_load_dwordx4 v[232:235], v[220:221], off
	v_lshl_add_u64 v[216:217], v[216:217], 0, v[164:165]
	global_load_dwordx4 v[236:239], v[218:219], off
	global_load_dwordx4 v[240:243], v[216:217], off
	v_lshl_add_u64 v[216:217], s[10:11], 0, v[222:223]
	v_lshl_add_u64 v[216:217], v[216:217], 0, v[164:165]
	global_load_dwordx4 v[244:247], v[216:217], off
	v_mov_b32_e32 v69, v157
	v_mov_b32_e32 v70, v157
	v_mov_b32_e32 v71, v157
	v_mov_b32_e32 v72, v157
	v_mov_b32_e32 v33, v157
	v_add_f32_e32 v16, 1.0, v16
	v_add_f32_e32 v17, 1.0, v17
	v_rcp_f32_e32 v16, v16
	v_rcp_f32_e32 v17, v17
	v_mul_f32_e32 v18, 0xbfb8aa3b, v18
	v_mul_f32_e32 v19, 0xbfb8aa3b, v19
	v_add_f32_e32 v20, 1.0, v20
	v_add_f32_e32 v21, 1.0, v21
	v_exp_f32_e32 v18, v18
	v_exp_f32_e32 v19, v19
	v_rcp_f32_e32 v20, v20
	v_rcp_f32_e32 v21, v21
	v_mul_f32_e32 v22, 0xbfb8aa3b, v22
	v_mul_f32_e32 v23, 0xbfb8aa3b, v23
	v_exp_f32_e32 v22, v22
	v_exp_f32_e32 v23, v23
	v_add_f32_e32 v18, 1.0, v18
	v_add_f32_e32 v19, 1.0, v19
	v_rcp_f32_e32 v18, v18
	v_rcp_f32_e32 v19, v19
	v_add_f32_e32 v22, 1.0, v22
	v_add_f32_e32 v23, 1.0, v23
	v_rcp_f32_e32 v22, v22
	v_rcp_f32_e32 v23, v23
	v_mul_f32_e32 v8, 0xbfb8aa3b, v8
	v_mul_f32_e32 v9, 0xbfb8aa3b, v9
	v_mul_f32_e32 v12, 0xbfb8aa3b, v12
	v_exp_f32_e32 v8, v8
	v_exp_f32_e32 v9, v9
	v_mul_f32_e32 v10, 0xbfb8aa3b, v10
	v_mul_f32_e32 v11, 0xbfb8aa3b, v11
	v_add_f32_e32 v8, 1.0, v8
	v_add_f32_e32 v9, 1.0, v9
	v_rcp_f32_e32 v8, v8
	v_rcp_f32_e32 v9, v9
	v_exp_f32_e32 v10, v10
	v_exp_f32_e32 v11, v11
	v_mul_f32_e32 v14, 0xbfb8aa3b, v14
	v_mul_f32_e32 v15, 0xbfb8aa3b, v15
	v_exp_f32_e32 v14, v14
	v_exp_f32_e32 v15, v15
	v_add_f32_e32 v10, 1.0, v10
	v_add_f32_e32 v11, 1.0, v11
	v_rcp_f32_e32 v10, v10
	v_rcp_f32_e32 v11, v11
	v_add_f32_e32 v14, 1.0, v14
	v_add_f32_e32 v15, 1.0, v15
	v_mul_f32_e32 v0, 0xbfb8aa3b, v0
	v_mul_f32_e32 v1, 0xbfb8aa3b, v1
	v_rcp_f32_e32 v14, v14
	v_rcp_f32_e32 v15, v15
	v_exp_f32_e32 v0, v0
	v_exp_f32_e32 v1, v1
	v_mul_f32_e32 v4, 0xbfb8aa3b, v4
; __device__ __forceinline__ float bflo(unsigned w) { return __uint_as_float(w << 16); }
; __device__ __forceinline__ float bfhi(unsigned w) { return __uint_as_float(w & 0xffff0000u); }
; __device__ __forceinline__ unsigned dpp_ror8(unsigned x) { return (unsigned)__builtin_amdgcn_update_dpp(0, (int)x, 0x128, 0xf, 0xf, false); }
;     __device__ __forceinline__ void operator()(const f32x4 (&acc)[2][2][4][2], const Unit& u, int wr, int wc, int fr, int fq) const {
;     ...
;             for (int m = 0; m < 4; ++m) { const int row = row0 + ai * HALF + m * 16; const float ri = __builtin_amdgcn_rsqf(sse[row] * (1.f / D) + EPS);
;                 u32x4 rr[2], ee[2]; load_pair_lines(R, D, row, fr, col0, rr[0], rr[1], 32); load_pair_lines(E, D, row, fr, col0, ee[0], ee[1], 32);
;                 float* orow = OUT + (size_t)(row - fr + (fr & 7)) * D + col0 + (lo ? 0 : 4);
; #pragma unroll
;                 for (int bj = 0; bj < 2; ++bj) { const u32x4 rw = rr[bj], ew = ee[bj];
;                     const float r[8] = {bflo(rw.x), bfhi(rw.x), bflo(rw.y), bfhi(rw.y), bflo(rw.z), bfhi(rw.z), bflo(rw.w), bfhi(rw.w)};
;                     const float e[8] = {bflo(ew.x), bfhi(ew.x), bflo(ew.y), bfhi(ew.y), bflo(ew.z), bfhi(ew.z), bflo(ew.w), bfhi(ew.w)};
;                     float o[8];
; #pragma unroll
;                     for (int j = 0; j < 8; ++j) { const float a = acc[ai][bj][m][j >> 2][j & 3]; const float gg = gv[bj][j >> 2][j & 3];
;                         o[j] = r[j] + e[j] * ri * gg * __builtin_amdgcn_rcpf(1.f + __builtin_amdgcn_exp2f(-a * LOG2E)); }
;                     f32x4 o1, o2;
; #pragma unroll
;                     for (int j = 0; j < 4; ++j) { const unsigned a = __float_as_uint(o[j]), b = __float_as_uint(o[4 + j]); const unsigned sa = dpp_ror8(a), sb = dpp_ror8(b);
;                         o1[j] = __uint_as_float(lo ? a : sb); o2[j] = __uint_as_float(lo ? sa : b); }
;                     *(f32x4*)(orow + 32 * bj) = o1; *(f32x4*)(orow + (size_t)8 * D + 32 * bj) = o2; } }
	v_mul_f32_e32 v5, 0xbfb8aa3b, v5
	v_exp_f32_e32 v4, v4
	v_fmamk_f32 v32, v68, 0x3a000000, v182
	v_mov_b32_e32 v68, v157
	v_rsq_f32_e32 v32, v32
	v_exp_f32_e32 v5, v5
	v_add_f32_e32 v0, 1.0, v0
	v_add_f32_e32 v1, 1.0, v1
	v_rcp_f32_e32 v0, v0
	v_rcp_f32_e32 v1, v1
	v_mul_f32_e32 v2, 0xbfb8aa3b, v2
	v_mul_f32_e32 v3, 0xbfb8aa3b, v3
	v_add_f32_e32 v4, 1.0, v4
	v_mov_b32_dpp v73, v50 row_ror:8 row_mask:0xf bank_mask:0xf
	v_mov_b32_dpp v74, v51 row_ror:8 row_mask:0xf bank_mask:0xf
	v_mov_b32_dpp v69, v36 row_ror:8 row_mask:0xf bank_mask:0xf
	v_mov_b32_dpp v70, v37 row_ror:8 row_mask:0xf bank_mask:0xf
	v_mov_b32_dpp v71, v48 row_ror:8 row_mask:0xf bank_mask:0xf
	v_mov_b32_dpp v72, v49 row_ror:8 row_mask:0xf bank_mask:0xf
	v_cndmask_b32_e64 v74, v74, v37, s[0:1]
	v_cndmask_b32_e64 v37, v73, v36, s[0:1]
	v_mov_b32_e32 v36, v157
	v_mov_b32_dpp v33, v34 row_ror:8 row_mask:0xf bank_mask:0xf
	v_mov_b32_dpp v68, v35 row_ror:8 row_mask:0xf bank_mask:0xf
	v_cndmask_b32_e64 v72, v72, v35, s[0:1]
	v_cndmask_b32_e64 v71, v71, v34, s[0:1]
	v_cndmask_b32_e64 v51, v51, v70, s[0:1]
	v_mov_b32_e32 v34, v157
	v_mov_b32_e32 v35, v157
	v_mov_b32_dpp v36, v54 row_ror:8 row_mask:0xf bank_mask:0xf
	v_mov_b32_e32 v70, v157
	v_cndmask_b32_e64 v49, v49, v68, s[0:1]
	v_cndmask_b32_e64 v33, v48, v33, s[0:1]
	v_cndmask_b32_e64 v48, v50, v69, s[0:1]
	v_mov_b32_dpp v34, v52 row_ror:8 row_mask:0xf bank_mask:0xf
	v_mov_b32_dpp v35, v53 row_ror:8 row_mask:0xf bank_mask:0xf
	v_mov_b32_e32 v68, v157
	v_mov_b32_e32 v69, v157
	v_mov_b32_dpp v70, v66 row_ror:8 row_mask:0xf bank_mask:0xf
	v_cndmask_b32_e64 v66, v66, v36, s[0:1]
	v_exp_f32_e32 v36, v28
	v_mul_f32_e32 v28, 0xbfb8aa3b, v29
	v_mov_b32_dpp v68, v64 row_ror:8 row_mask:0xf bank_mask:0xf
	v_mov_b32_dpp v69, v65 row_ror:8 row_mask:0xf bank_mask:0xf
	v_cndmask_b32_e64 v65, v65, v35, s[0:1]
	v_cndmask_b32_e64 v64, v64, v34, s[0:1]
	v_lshlrev_b64 v[34:35], 13, v[38:39]
	v_exp_f32_e32 v38, v28
	v_lshl_add_u64 v[34:35], s[4:5], 0, v[34:35]
	v_cndmask_b32_e64 v54, v70, v54, s[0:1]
	v_lshl_add_u64 v[34:35], v[34:35], 0, v[166:167]
	v_lshl_add_u64 v[28:29], v[34:35], 0, v[156:157]
	v_add_f32_e32 v35, 1.0, v38
	v_lshlrev_b32_e32 v38, 16, v54
	v_and_b32_e32 v39, 0xffff0000, v54
	v_add_f32_e32 v34, 1.0, v36
	v_pk_mul_f32 v[38:39], v[32:33], v[38:39] op_sel_hi:[0,1]
	v_cndmask_b32_e64 v52, v68, v52, s[0:1]
	v_rcp_f32_e32 v34, v34
	v_rcp_f32_e32 v35, v35
	v_lshlrev_b32_e32 v36, 16, v37
	v_and_b32_e32 v37, 0xffff0000, v37
	v_pk_mul_f32 v[38:39], v[60:61], v[38:39]
	v_mov_b32_e32 v73, v157
	v_pk_fma_f32 v[38:39], v[24:25], v[38:39], v[36:37]
	v_lshlrev_b32_e32 v36, 16, v52
	v_and_b32_e32 v37, 0xffff0000, v52
	v_mov_b32_e32 v50, v157
	v_mov_b32_dpp v73, v67 row_ror:8 row_mask:0xf bank_mask:0xf
	v_pk_mul_f32 v[36:37], v[32:33], v[36:37] op_sel_hi:[0,1]
	v_mov_b32_dpp v50, v55 row_ror:8 row_mask:0xf bank_mask:0xf
	v_cndmask_b32_e64 v55, v73, v55, s[0:1]
	v_lshlrev_b32_e32 v24, 16, v71
	v_and_b32_e32 v25, 0xffff0000, v71
	v_pk_mul_f32 v[36:37], v[56:57], v[36:37]
	v_cndmask_b32_e64 v53, v69, v53, s[0:1]
	v_pk_fma_f32 v[24:25], v[34:35], v[36:37], v[24:25]
	v_lshlrev_b32_e32 v36, 16, v55
	v_and_b32_e32 v37, 0xffff0000, v55
	v_pk_mul_f32 v[36:37], v[32:33], v[36:37] op_sel_hi:[0,1]
	v_lshlrev_b32_e32 v34, 16, v74
	v_and_b32_e32 v35, 0xffff0000, v74
	v_pk_mul_f32 v[36:37], v[62:63], v[36:37]
	v_cndmask_b32_e64 v50, v67, v50, s[0:1]
	v_pk_fma_f32 v[34:35], v[26:27], v[36:37], v[34:35]
	v_lshlrev_b32_e32 v36, 16, v53
	v_and_b32_e32 v37, 0xffff0000, v53
	v_pk_mul_f32 v[36:37], v[32:33], v[36:37] op_sel_hi:[0,1]
	v_lshlrev_b32_e32 v26, 16, v72
	v_and_b32_e32 v27, 0xffff0000, v72
	v_pk_mul_f32 v[36:37], v[58:59], v[36:37]
	v_mov_b32_e32 v54, v157
	v_pk_fma_f32 v[26:27], v[30:31], v[36:37], v[26:27]
	v_mov_b32_e32 v30, v157
	v_mov_b32_e32 v31, v157
	v_mov_b32_e32 v67, v157
	v_mov_b32_e32 v55, v157
	v_mov_b32_e32 v69, v157
	v_mov_b32_dpp v30, v26 row_ror:8 row_mask:0xf bank_mask:0xf
	v_mov_b32_dpp v31, v27 row_ror:8 row_mask:0xf bank_mask:0xf
	v_mov_b32_dpp v54, v38 row_ror:8 row_mask:0xf bank_mask:0xf
	v_mov_b32_dpp v67, v39 row_ror:8 row_mask:0xf bank_mask:0xf
	v_mov_b32_e32 v52, v157
	v_mov_b32_e32 v68, v157
	v_mov_b32_dpp v55, v34 row_ror:8 row_mask:0xf bank_mask:0xf
	v_mov_b32_dpp v69, v35 row_ror:8 row_mask:0xf bank_mask:0xf
	v_cndmask_b32_e64 v37, v35, v31, s[0:1]
	v_cndmask_b32_e64 v36, v34, v30, s[0:1]
	v_lshlrev_b32_e32 v30, 16, v66
	v_and_b32_e32 v31, 0xffff0000, v66
	v_mov_b32_dpp v52, v24 row_ror:8 row_mask:0xf bank_mask:0xf
	v_mov_b32_dpp v68, v25 row_ror:8 row_mask:0xf bank_mask:0xf
	v_cndmask_b32_e64 v27, v69, v27, s[0:1]
	v_cndmask_b32_e64 v26, v55, v26, s[0:1]
	v_cndmask_b32_e64 v25, v67, v25, s[0:1]
	v_cndmask_b32_e64 v24, v54, v24, s[0:1]
	v_pk_mul_f32 v[30:31], v[32:33], v[30:31] op_sel_hi:[0,1]
	global_store_dwordx4 v[28:29], v[24:27], off
	v_pk_mul_f32 v[30:31], v[44:45], v[30:31]
	v_cndmask_b32_e64 v35, v39, v68, s[0:1]
	v_lshlrev_b32_e32 v26, 16, v48
	v_and_b32_e32 v27, 0xffff0000, v48
	v_pk_fma_f32 v[26:27], v[16:17], v[30:31], v[26:27]
	v_lshlrev_b32_e32 v30, 16, v64
	v_and_b32_e32 v31, 0xffff0000, v64
	v_pk_mul_f32 v[30:31], v[32:33], v[30:31] op_sel_hi:[0,1]
	v_lshlrev_b32_e32 v16, 16, v33
	v_and_b32_e32 v17, 0xffff0000, v33
	v_pk_mul_f32 v[30:31], v[40:41], v[30:31]
	v_mov_b32_e32 v33, v157
	v_pk_fma_f32 v[16:17], v[20:21], v[30:31], v[16:17]
	v_lshlrev_b32_e32 v30, 16, v50
	v_and_b32_e32 v31, 0xffff0000, v50
	v_mov_b32_dpp v33, v16 row_ror:8 row_mask:0xf bank_mask:0xf
	v_pk_mul_f32 v[30:31], v[32:33], v[30:31] op_sel_hi:[0,1]
	v_add_co_u32_e32 v24, vcc, s45, v28
	v_lshlrev_b32_e32 v20, 16, v51
	v_and_b32_e32 v21, 0xffff0000, v51
; __device__ __forceinline__ float bflo(unsigned w) { return __uint_as_float(w << 16); }
; __device__ __forceinline__ float bfhi(unsigned w) { return __uint_as_float(w & 0xffff0000u); }
; __device__ __forceinline__ unsigned dpp_ror8(unsigned x) { return (unsigned)__builtin_amdgcn_update_dpp(0, (int)x, 0x128, 0xf, 0xf, false); }
;     __device__ __forceinline__ void operator()(const f32x4 (&acc)[2][2][4][2], const Unit& u, int wr, int wc, int fr, int fq) const {
;     ...
;             for (int m = 0; m < 4; ++m) { const int row = row0 + ai * HALF + m * 16; const float ri = __builtin_amdgcn_rsqf(sse[row] * (1.f / D) + EPS);
;                 u32x4 rr[2], ee[2]; load_pair_lines(R, D, row, fr, col0, rr[0], rr[1], 32); load_pair_lines(E, D, row, fr, col0, ee[0], ee[1], 32);
;                 float* orow = OUT + (size_t)(row - fr + (fr & 7)) * D + col0 + (lo ? 0 : 4);
; #pragma unroll
;                 for (int bj = 0; bj < 2; ++bj) { const u32x4 rw = rr[bj], ew = ee[bj];
;                     const float r[8] = {bflo(rw.x), bfhi(rw.x), bflo(rw.y), bfhi(rw.y), bflo(rw.z), bfhi(rw.z), bflo(rw.w), bfhi(rw.w)};
;                     const float e[8] = {bflo(ew.x), bfhi(ew.x), bflo(ew.y), bfhi(ew.y), bflo(ew.z), bfhi(ew.z), bflo(ew.w), bfhi(ew.w)};
;                     float o[8];
; #pragma unroll
;                     for (int j = 0; j < 8; ++j) { const float a = acc[ai][bj][m][j >> 2][j & 3]; const float gg = gv[bj][j >> 2][j & 3];
;                         o[j] = r[j] + e[j] * ri * gg * __builtin_amdgcn_rcpf(1.f + __builtin_amdgcn_exp2f(-a * LOG2E)); }
;                     f32x4 o1, o2;
; #pragma unroll
;                     for (int j = 0; j < 4; ++j) { const unsigned a = __float_as_uint(o[j]), b = __float_as_uint(o[4 + j]); const unsigned sa = dpp_ror8(a), sb = dpp_ror8(b);
;                         o1[j] = __uint_as_float(lo ? a : sb); o2[j] = __uint_as_float(lo ? sa : b); }
;                     *(f32x4*)(orow + 32 * bj) = o1; *(f32x4*)(orow + (size_t)8 * D + 32 * bj) = o2; } }
; template <class Epi>
; __device__ __forceinline__ void gemm_phase(LAS unsigned char* lds, const Gemm g, const StaticOrder& S, const Epi& E) {
;     ...
;         cur = nxt; cA = nA; cB = nB; ++ui;
	v_pk_mul_f32 v[30:31], v[46:47], v[30:31]
	v_cndmask_b32_e64 v34, v38, v52, s[0:1]
	v_addc_co_u32_e32 v25, vcc, 0, v29, vcc
	v_pk_fma_f32 v[20:21], v[18:19], v[30:31], v[20:21]
	v_lshlrev_b32_e32 v30, 16, v65
	v_and_b32_e32 v31, 0xffff0000, v65
	global_store_dwordx4 v[24:25], v[34:37], off
	v_pk_mul_f32 v[30:31], v[32:33], v[30:31] op_sel_hi:[0,1]
	v_mov_b32_e32 v38, v157
	v_mov_b32_e32 v34, v157
	v_mov_b32_e32 v35, v157
	v_mov_b32_e32 v37, v157
	v_mov_b32_dpp v34, v26 row_ror:8 row_mask:0xf bank_mask:0xf
	v_lshlrev_b32_e32 v18, 16, v49
	v_and_b32_e32 v19, 0xffff0000, v49
	v_pk_mul_f32 v[30:31], v[42:43], v[30:31]
	v_mov_b32_dpp v35, v27 row_ror:8 row_mask:0xf bank_mask:0xf
	v_mov_b32_e32 v36, v157
	v_mov_b32_dpp v37, v20 row_ror:8 row_mask:0xf bank_mask:0xf
	v_mov_b32_dpp v38, v21 row_ror:8 row_mask:0xf bank_mask:0xf
	v_pk_fma_f32 v[18:19], v[22:23], v[30:31], v[18:19]
	v_mov_b32_e32 v22, v157
	v_mov_b32_e32 v23, v157
	v_cndmask_b32_e64 v16, v34, v16, s[0:1]
	v_add_u32_e32 v34, 0xb0, v81
	v_mov_b32_dpp v36, v17 row_ror:8 row_mask:0xf bank_mask:0xf
	v_mov_b32_dpp v22, v18 row_ror:8 row_mask:0xf bank_mask:0xf
	v_mov_b32_dpp v23, v19 row_ror:8 row_mask:0xf bank_mask:0xf
	v_cndmask_b32_e64 v19, v38, v19, s[0:1]
	v_cndmask_b32_e64 v18, v37, v18, s[0:1]
	v_cndmask_b32_e64 v17, v35, v17, s[0:1]
	v_ashrrev_i32_e32 v35, 31, v34
	v_cndmask_b32_e64 v23, v21, v23, s[0:1]
	v_cndmask_b32_e64 v22, v20, v22, s[0:1]
	v_cndmask_b32_e64 v21, v27, v36, s[0:1]
	v_cndmask_b32_e64 v20, v26, v33, s[0:1]
	global_store_dwordx4 v[28:29], v[16:19], off offset:128
	global_store_dwordx4 v[24:25], v[20:23], off offset:128
	s_waitcnt vmcnt(4)
	s_nop 0
	v_mov_b32_e32 v36, v228
	v_lshlrev_b64 v[16:17], 12, v[34:35]
	v_lshl_add_u64 v[30:31], v[16:17], 0, s[16:17]
	v_lshl_add_u64 v[22:23], s[8:9], 0, v[30:31]
	v_lshl_add_u64 v[18:19], s[8:9], 0, v[16:17]
	v_lshl_add_u64 v[22:23], v[22:23], 0, v[164:165]
	v_lshl_add_u64 v[16:17], s[10:11], 0, v[16:17]
	v_lshl_add_u64 v[18:19], v[18:19], 0, v[164:165]
	v_mov_b64_e32 v[22:23], v[232:233]
	v_mov_b64_e32 v[24:25], v[234:235]
	v_lshl_add_u64 v[16:17], v[16:17], 0, v[164:165]
	v_mov_b64_e32 v[18:19], v[236:237]
	v_mov_b64_e32 v[20:21], v[238:239]
	v_mov_b32_e32 v49, v157
	v_mov_b64_e32 v[26:27], v[240:241]
	v_mov_b64_e32 v[28:29], v[242:243]
	v_lshl_add_u64 v[16:17], s[10:11], 0, v[30:31]
	v_lshl_add_u64 v[16:17], v[16:17], 0, v[164:165]
	v_mov_b64_e32 v[30:31], v[244:245]
	v_mov_b64_e32 v[32:33], v[246:247]
	s_nop 1
	v_mov_b32_e32 v50, v157
	v_mov_b32_e32 v17, v157
	v_mov_b32_e32 v37, v157
	v_mov_b32_e32 v38, v157
	v_mov_b32_e32 v48, v157
	v_mov_b32_e32 v39, v157
	v_add_f32_e32 v5, 1.0, v5
	v_exp_f32_e32 v2, v2
	v_exp_f32_e32 v3, v3
	v_rcp_f32_e32 v4, v4
	v_rcp_f32_e32 v5, v5
	v_mul_f32_e32 v6, 0xbfb8aa3b, v6
	v_mul_f32_e32 v7, 0xbfb8aa3b, v7
	v_exp_f32_e32 v6, v6
	v_exp_f32_e32 v7, v7
	v_add_f32_e32 v2, 1.0, v2
	v_add_f32_e32 v3, 1.0, v3
	v_rcp_f32_e32 v2, v2
	v_rcp_f32_e32 v3, v3
	v_add_f32_e32 v6, 1.0, v6
	v_add_f32_e32 v7, 1.0, v7
	v_rcp_f32_e32 v6, v6
	v_rcp_f32_e32 v7, v7
	s_mov_b32 s53, s18
	s_mov_b32 s30, s22
	s_mov_b64 s[36:37], s[28:29]
	s_mov_b64 s[34:35], s[24:25]
	v_fmamk_f32 v16, v36, 0x3a000000, v182
	v_mov_b32_e32 v36, v157
	v_rsq_f32_e32 v16, v16
	v_mov_b32_dpp v49, v24 row_ror:8 row_mask:0xf bank_mask:0xf
	v_mov_b32_dpp v50, v25 row_ror:8 row_mask:0xf bank_mask:0xf
	v_mov_b32_dpp v17, v18 row_ror:8 row_mask:0xf bank_mask:0xf
	v_mov_b32_dpp v36, v19 row_ror:8 row_mask:0xf bank_mask:0xf
	v_mov_b32_dpp v37, v20 row_ror:8 row_mask:0xf bank_mask:0xf
	v_mov_b32_dpp v38, v21 row_ror:8 row_mask:0xf bank_mask:0xf
	v_mov_b32_dpp v48, v23 row_ror:8 row_mask:0xf bank_mask:0xf
	v_cndmask_b32_e64 v50, v50, v21, s[0:1]
	v_cndmask_b32_e64 v21, v49, v20, s[0:1]
	v_mov_b32_e32 v20, v157
	v_mov_b32_dpp v39, v22 row_ror:8 row_mask:0xf bank_mask:0xf
	v_cndmask_b32_e64 v48, v48, v19, s[0:1]
	v_cndmask_b32_e64 v36, v23, v36, s[0:1]
	v_cndmask_b32_e64 v25, v25, v38, s[0:1]
	v_cndmask_b32_e64 v17, v22, v17, s[0:1]
	v_mov_b32_e32 v19, v157
	v_mov_b32_dpp v20, v28 row_ror:8 row_mask:0xf bank_mask:0xf
	v_mov_b32_e32 v22, v157
	v_mov_b32_e32 v23, v157
	v_mov_b32_e32 v38, v157
	v_cndmask_b32_e64 v39, v39, v18, s[0:1]
	v_cndmask_b32_e64 v24, v24, v37, s[0:1]
	v_mov_b32_e32 v18, v157
	v_mov_b32_dpp v19, v27 row_ror:8 row_mask:0xf bank_mask:0xf
	v_mov_b32_dpp v22, v29 row_ror:8 row_mask:0xf bank_mask:0xf
	v_mov_b32_dpp v23, v30 row_ror:8 row_mask:0xf bank_mask:0xf
	v_mov_b32_e32 v37, v157
	v_mov_b32_dpp v38, v32 row_ror:8 row_mask:0xf bank_mask:0xf
	v_cndmask_b32_e64 v32, v32, v20, s[0:1]
	v_exp_f32_e32 v20, v12
	v_mul_f32_e32 v12, 0xbfb8aa3b, v13
	v_mov_b32_dpp v18, v26 row_ror:8 row_mask:0xf bank_mask:0xf
	v_mov_b32_dpp v37, v31 row_ror:8 row_mask:0xf bank_mask:0xf
	v_cndmask_b32_e64 v26, v23, v26, s[0:1]
	v_cndmask_b32_e64 v23, v38, v28, s[0:1]
	v_cndmask_b32_e64 v28, v31, v19, s[0:1]
	v_cndmask_b32_e64 v31, v33, v22, s[0:1]
	v_exp_f32_e32 v22, v12
	v_cndmask_b32_e64 v30, v30, v18, s[0:1]
	v_lshlrev_b64 v[18:19], 13, v[34:35]
	v_lshl_add_u64 v[18:19], s[4:5], 0, v[18:19]
; __device__ __forceinline__ unsigned dpp_ror8(unsigned x) { return (unsigned)__builtin_amdgcn_update_dpp(0, (int)x, 0x128, 0xf, 0xf, false); }
; #define PG8_WAIT_V(n) asm volatile("s_waitcnt vmcnt(" #n ")" ::: "memory")
; #define PG8_BAR __builtin_amdgcn_s_barrier()
;     __device__ __forceinline__ void operator()(const f32x4 (&acc)[2][2][4][2], const Unit& u, int wr, int wc, int fr, int fq) const {
;     ...
;                     for (int j = 0; j < 8; ++j) { const float a = acc[ai][bj][m][j >> 2][j & 3]; const float gg = gv[bj][j >> 2][j & 3];
;                         o[j] = r[j] + e[j] * ri * gg * __builtin_amdgcn_rcpf(1.f + __builtin_amdgcn_exp2f(-a * LOG2E)); }
;                     f32x4 o1, o2;
; #pragma unroll
;                     for (int j = 0; j < 4; ++j) { const unsigned a = __float_as_uint(o[j]), b = __float_as_uint(o[4 + j]); const unsigned sa = dpp_ror8(a), sb = dpp_ror8(b);
;                         o1[j] = __uint_as_float(lo ? a : sb); o2[j] = __uint_as_float(lo ? sa : b); }
;                     *(f32x4*)(orow + 32 * bj) = o1; *(f32x4*)(orow + (size_t)8 * D + 32 * bj) = o2; } }
; template <class Epi>
; __device__ __forceinline__ void gemm_phase(LAS unsigned char* lds, const Gemm g, const StaticOrder& S, const Epi& E) {
;     ...
;         if (!has_next) break;
; #pragma unroll
;         for (int a = 0; a < 2; ++a)
; #pragma unroll
;             for (int b = 0; b < 2; ++b)
; #pragma unroll
;                 for (int m = 0; m < 4; ++m)
; #pragma unroll
;                     for (int n = 0; n < 2; ++n) acc[a][b][m][n] = (f32x4){0.f, 0.f, 0.f, 0.f};
;         cur = nxt; cA = nA; cB = nB; ++ui;
;     }
;     PG8_WAIT_V(0);
;     if (wr == 0) PG8_BAR;
;     PG8_BAR;
	v_lshl_add_u64 v[18:19], v[18:19], 0, v[166:167]
	v_lshl_add_u64 v[12:13], v[18:19], 0, v[156:157]
	v_add_f32_e32 v19, 1.0, v22
	v_lshlrev_b32_e32 v22, 16, v23
	v_and_b32_e32 v23, 0xffff0000, v23
	v_add_f32_e32 v18, 1.0, v20
	v_pk_mul_f32 v[22:23], v[16:17], v[22:23] op_sel_hi:[0,1]
	v_rcp_f32_e32 v18, v18
	v_rcp_f32_e32 v19, v19
	v_lshlrev_b32_e32 v20, 16, v21
	v_and_b32_e32 v21, 0xffff0000, v21
	v_pk_mul_f32 v[22:23], v[60:61], v[22:23]
	v_mov_b32_e32 v49, v157
	v_pk_fma_f32 v[22:23], v[8:9], v[22:23], v[20:21]
	v_lshlrev_b32_e32 v20, 16, v26
	v_and_b32_e32 v21, 0xffff0000, v26
	v_mov_b32_dpp v49, v33 row_ror:8 row_mask:0xf bank_mask:0xf
	v_pk_mul_f32 v[20:21], v[16:17], v[20:21] op_sel_hi:[0,1]
	v_cndmask_b32_e64 v29, v49, v29, s[0:1]
	v_lshlrev_b32_e32 v8, 16, v39
	v_and_b32_e32 v9, 0xffff0000, v39
	v_pk_mul_f32 v[20:21], v[56:57], v[20:21]
	v_cndmask_b32_e64 v27, v37, v27, s[0:1]
	v_pk_fma_f32 v[8:9], v[18:19], v[20:21], v[8:9]
	v_lshlrev_b32_e32 v20, 16, v29
	v_and_b32_e32 v21, 0xffff0000, v29
	v_pk_mul_f32 v[20:21], v[16:17], v[20:21] op_sel_hi:[0,1]
	v_lshlrev_b32_e32 v18, 16, v50
	v_and_b32_e32 v19, 0xffff0000, v50
	v_pk_mul_f32 v[20:21], v[62:63], v[20:21]
	v_mov_b32_e32 v33, v157
	v_pk_fma_f32 v[18:19], v[10:11], v[20:21], v[18:19]
	v_lshlrev_b32_e32 v20, 16, v27
	v_and_b32_e32 v21, 0xffff0000, v27
	v_pk_mul_f32 v[20:21], v[16:17], v[20:21] op_sel_hi:[0,1]
	v_lshlrev_b32_e32 v10, 16, v48
	v_and_b32_e32 v11, 0xffff0000, v48
	v_pk_mul_f32 v[20:21], v[58:59], v[20:21]
	v_mov_b32_e32 v34, v157
	v_pk_fma_f32 v[10:11], v[14:15], v[20:21], v[10:11]
	v_mov_b32_e32 v14, v157
	v_mov_b32_e32 v15, v157
	v_mov_b32_e32 v29, v157
	v_mov_b32_e32 v37, v157
	v_mov_b32_dpp v14, v10 row_ror:8 row_mask:0xf bank_mask:0xf
	v_mov_b32_dpp v15, v11 row_ror:8 row_mask:0xf bank_mask:0xf
	v_mov_b32_dpp v33, v22 row_ror:8 row_mask:0xf bank_mask:0xf
	v_mov_b32_dpp v34, v23 row_ror:8 row_mask:0xf bank_mask:0xf
	v_mov_b32_e32 v26, v157
	v_mov_b32_e32 v35, v157
	v_mov_b32_dpp v29, v18 row_ror:8 row_mask:0xf bank_mask:0xf
	v_mov_b32_dpp v37, v19 row_ror:8 row_mask:0xf bank_mask:0xf
	v_cndmask_b32_e64 v21, v19, v15, s[0:1]
	v_cndmask_b32_e64 v20, v18, v14, s[0:1]
	v_lshlrev_b32_e32 v14, 16, v32
	v_and_b32_e32 v15, 0xffff0000, v32
	v_mov_b32_dpp v26, v8 row_ror:8 row_mask:0xf bank_mask:0xf
	v_mov_b32_dpp v35, v9 row_ror:8 row_mask:0xf bank_mask:0xf
	v_cndmask_b32_e64 v11, v37, v11, s[0:1]
	v_cndmask_b32_e64 v10, v29, v10, s[0:1]
	v_cndmask_b32_e64 v9, v34, v9, s[0:1]
	v_cndmask_b32_e64 v8, v33, v8, s[0:1]
	v_pk_mul_f32 v[14:15], v[16:17], v[14:15] op_sel_hi:[0,1]
	global_store_dwordx4 v[12:13], v[8:11], off
	v_pk_mul_f32 v[14:15], v[44:45], v[14:15]
	v_cndmask_b32_e64 v19, v23, v35, s[0:1]
	v_lshlrev_b32_e32 v10, 16, v24
	v_and_b32_e32 v11, 0xffff0000, v24
	v_pk_fma_f32 v[10:11], v[0:1], v[14:15], v[10:11]
	v_lshlrev_b32_e32 v14, 16, v30
	v_and_b32_e32 v15, 0xffff0000, v30
	v_pk_mul_f32 v[14:15], v[16:17], v[14:15] op_sel_hi:[0,1]
	v_lshlrev_b32_e32 v0, 16, v17
	v_and_b32_e32 v1, 0xffff0000, v17
	v_pk_mul_f32 v[14:15], v[40:41], v[14:15]
	v_mov_b32_e32 v17, v157
	v_pk_fma_f32 v[0:1], v[4:5], v[14:15], v[0:1]
	v_lshlrev_b32_e32 v14, 16, v31
	v_and_b32_e32 v15, 0xffff0000, v31
	v_mov_b32_dpp v17, v0 row_ror:8 row_mask:0xf bank_mask:0xf
	v_pk_mul_f32 v[14:15], v[16:17], v[14:15] op_sel_hi:[0,1]
	v_lshlrev_b32_e32 v4, 16, v25
	v_and_b32_e32 v5, 0xffff0000, v25
	v_pk_mul_f32 v[14:15], v[46:47], v[14:15]
	v_add_co_u32_e32 v8, vcc, s45, v12
	v_pk_fma_f32 v[4:5], v[2:3], v[14:15], v[4:5]
	v_lshlrev_b32_e32 v14, 16, v28
	v_and_b32_e32 v15, 0xffff0000, v28
	v_cndmask_b32_e64 v18, v22, v26, s[0:1]
	v_addc_co_u32_e32 v9, vcc, 0, v13, vcc
	v_pk_mul_f32 v[14:15], v[16:17], v[14:15] op_sel_hi:[0,1]
	global_store_dwordx4 v[8:9], v[18:21], off
	v_mov_b32_e32 v22, v157
	v_lshlrev_b32_e32 v2, 16, v36
	v_mov_b32_e32 v18, v157
	v_mov_b32_e32 v19, v157
	v_mov_b32_e32 v21, v157
	v_and_b32_e32 v3, 0xffff0000, v36
	v_pk_mul_f32 v[14:15], v[42:43], v[14:15]
	v_mov_b32_dpp v18, v10 row_ror:8 row_mask:0xf bank_mask:0xf
	v_mov_b32_dpp v19, v11 row_ror:8 row_mask:0xf bank_mask:0xf
	v_mov_b32_e32 v20, v157
	v_mov_b32_dpp v21, v4 row_ror:8 row_mask:0xf bank_mask:0xf
	v_mov_b32_dpp v22, v5 row_ror:8 row_mask:0xf bank_mask:0xf
	v_pk_fma_f32 v[2:3], v[6:7], v[14:15], v[2:3]
	v_mov_b32_e32 v6, v157
	v_mov_b32_e32 v7, v157
	v_mov_b32_dpp v20, v1 row_ror:8 row_mask:0xf bank_mask:0xf
	v_mov_b32_dpp v6, v2 row_ror:8 row_mask:0xf bank_mask:0xf
	v_mov_b32_dpp v7, v3 row_ror:8 row_mask:0xf bank_mask:0xf
	v_cndmask_b32_e64 v3, v22, v3, s[0:1]
	v_cndmask_b32_e64 v2, v21, v2, s[0:1]
	v_cndmask_b32_e64 v1, v19, v1, s[0:1]
	v_cndmask_b32_e64 v0, v18, v0, s[0:1]
	s_and_b64 vcc, exec, s[26:27]
	v_cndmask_b32_e64 v7, v5, v7, s[0:1]
	v_cndmask_b32_e64 v6, v4, v6, s[0:1]
	v_cndmask_b32_e64 v5, v11, v20, s[0:1]
	v_cndmask_b32_e64 v4, v10, v17, s[0:1]
	global_store_dwordx4 v[12:13], v[0:3], off offset:128
	global_store_dwordx4 v[8:9], v[4:7], off offset:128
	s_cbranch_vccz .LBB0_1595
	s_waitcnt vmcnt(0)
	s_cmpk_gt_u32 s3, 0xff
	s_cbranch_scc1 .LBB0_1607
	s_barrier
